# v-phase code placed 8 bytes later (placement trial)
# baseline (speedup 1.0000x reference)
; __device__ __forceinline__ void peer_v_tokens(int j, const LAS unsigned short* EL, const LAS unsigned char* AL  , const LAS float* ASC  , const LAS int* SAL  , ...
;     asm volatile("" : "+v"(lane));
;     const int BUF[3] = {vslot(3 * wave), vslot(3 * wave + 1), vslot(3 * wave + 2)};
;     const int g = lane >> 3, j8 = lane & 7, s16 = lane & 15, grp = lane >> 4;
;     *(LAS unsigned long long*)(ldsb + BUF[0] + 8 * s16) = 0xFEDCBA9876543210ull;
;     CFENCE();
;     const v2i cal = TR4(ldsb + BUF[0] + 8 * s16);
;     const int pc = cal.x & 15;
;     asm volatile("s_waitcnt lgkmcnt(0)" ::: "memory");
;     const unsigned cx0 = 16u * (unsigned)(j8 ^ (g >> 1)), cx1 = 16u * (unsigned)(j8 ^ (4 + (g >> 1)));
;     const int fr = (4 * (s16 >> 3) + ((s16 & 7) >> 1)) & 7;
;     int roff[4];
; #pragma unroll
;     for (int r = 0; r < 4; ++r) roff[r] = 128 * s16 + 16 * ((((grp >> 1) + 2 * r)) ^ fr) + 8 * (grp & 1);
;     ...
; #pragma unroll 1
;     for (int it = 0; it < 8; ++it) {
;         const int tl = it * 8 + wave, t = j * 64 + tl;
;         unsigned E[8];
;         { const LAS v4u* ep = (const LAS v4u*)(EL + tl * 128 + 16 * g); const v4u e0 = ep[0], e1 = ep[1];
;           E[0] = e0.x; E[1] = e0.y; E[2] = e0.z; E[3] = e0.w; E[4] = e1.x; E[5] = e1.y; E[6] = e1.z; E[7] = e1.w; }
;         uint2 hv[4]; float4 gv[4];
;         { unsigned ho = (unsigned)t * (D / 4) + (unsigned)lane; asm volatile("" : "+v"(ho)); const uint2* hp = (const uint2*)HB + ho; const float4* gp = (const float4*)fng + lane;
; #pragma unroll
;           for (int jq = 0; jq < 4; ++jq) { hv[jq] = hp[64 * jq]; gv[jq] = gp[64 * jq]; } }
;         VDMA(0, 0); VDMA(1, 1);
; #pragma unroll
;         for (int m = 0; m < 2; ++m) {
;             const int idx = lane + 64 * m, tau = idx >> 4, sr = idx & 15, k = 16 * (sr & 7) + 2 * tau + (sr >> 3);
;             const int aq = (int)*(const LAS signed char*)(AL + tl * 128 + k); const int tq = aq + 8;
;             const unsigned lo = (((unsigned)tq & 15u) ^ 8u) * 0x11111111u, hi = ((unsigned)(tq >> 4) & 15u) * 0x11111111u;
;             typedef unsigned u2v __attribute__((ext_vector_type(2)));
;             u2v l2; l2.x = lo; l2.y = lo; u2v h2; h2.x = hi; h2.y = hi;
;             *(LAS u2v*)(ATL + 8 * idx) = l2; *(LAS u2v*)(ATL + 1024 + 8 * idx) = h2;
;         }
;         const float asc = ASC[tl]; const int sa = SAL[tl];
;         CFENCE();
.LBB0_691:
	s_or_b64 exec, exec, s[10:11]
	v_mov_b32_e32 v18, v1
	s_waitcnt lgkmcnt(0)
	s_barrier
	v_readlane_b32 s70, v235, 50
	v_and_b32_e32 v19, 15, v18
	v_lshlrev_b32_e32 v58, 3, v19
	v_add_u32_e32 v20, s60, v58
	ds_write_b64 v20, v[84:85]
	v_lshrrev_b32_e32 v23, 1, v18
	v_ashrrev_i32_e32 v24, 5, v18
	v_and_b32_e32 v25, 8, v23
	ds_read_b64_tr_b4 v[20:21], v20
	v_lshl_or_b32 v19, v19, 7, v25
	v_bitop3_b32 v25, v23, v24, 7 bitop3:0x6c
	v_lshl_add_u32 v59, v25, 4, v19
	v_add_u32_e32 v25, 2, v24
	v_bitop3_b32 v25, v25, v23, 7 bitop3:0x78
	v_lshl_add_u32 v60, v25, 4, v19
	v_add_u32_e32 v25, 4, v24
	v_add_u32_e32 v24, 6, v24
	s_waitcnt lgkmcnt(0)
	v_ashrrev_i32_e32 v21, 4, v18
	v_bitop3_b32 v25, v25, v23, 7 bitop3:0x78
	v_bitop3_b32 v23, v24, v23, 7 bitop3:0x78
	v_bitop3_b32 v22, v18, v21, 7 bitop3:0x6c
	v_add_u32_e32 v21, 4, v21
	v_lshl_add_u32 v61, v25, 4, v19
	v_lshl_add_u32 v62, v23, 4, v19
	v_and_b32_e32 v19, 15, v20
	v_bitop3_b32 v21, v21, v18, 7 bitop3:0x78
	v_lshlrev_b32_e32 v63, 4, v22
	v_lshlrev_b32_e32 v22, 1, v19
	v_ashrrev_i32_e32 v19, 31, v18
	v_lshlrev_b32_e32 v64, 4, v21
	v_lshlrev_b64 v[20:21], 4, v[18:19]
	v_and_b32_e32 v25, 0x7ffffff0, v18
	v_lshl_add_u64 v[34:35], s[86:87], 0, v[20:21]
	v_lshlrev_b32_e32 v19, 4, v18
	v_lshlrev_b32_e32 v25, 1, v25
	v_lshl_add_u64 v[36:37], s[88:89], 0, v[20:21]
	v_add_u32_e32 v21, 64, v18
	s_waitcnt lgkmcnt(0)
	v_and_b32_e32 v19, 0x70, v19
	v_add3_u32 v65, s58, v22, v25
	v_ashrrev_i32_e32 v20, 3, v18
	v_ashrrev_i32_e32 v22, 3, v21
	v_lshrrev_b32_e32 v23, 3, v18
	v_bfe_u32 v24, v18, 3, 1
	v_and_b32_e32 v20, -2, v20
	v_and_b32_e32 v22, -2, v22
	v_lshlrev_b32_e32 v21, 3, v21
	v_add_u32_e32 v19, s72, v19
	v_lshlrev_b32_e32 v66, 3, v18
	v_add_u32_e32 v67, 0x200000, v63
	v_add_u32_e32 v68, 0x200000, v64
	v_add_u32_e32 v69, 0x400000, v63
	v_add_u32_e32 v70, 0x400000, v64
	v_add_u32_e32 v71, 0x600000, v63
	v_add_u32_e32 v72, 0x600000, v64
	v_add3_u32 v73, v19, v22, v24
	v_add3_u32 v74, v19, v20, v24
	v_lshl_add_u32 v75, v23, 5, s65
	v_add_u32_e32 v76, s73, v18
	s_mov_b32 s12, 0
	v_add_u32_e32 v77, s59, v21
	s_mov_b32 s13, s67
	v_readlane_b32 s71, v235, 51
	s_nop 0
	s_nop 0
	s_mov_b32 s76, s60
	s_add_i32 s77, s60, 0x800
	s_mov_b32 s78, s61
	s_add_i32 s79, s61, 0x800
	s_mov_b32 s98, s62
	s_add_i32 s99, s62, 0x800
	v_add_u32_e32 v159, s59, v66
	v_add_u32_e32 v160, s59, v58
	v_add_u32_e32 v154, s58, v66
	v_add_u32_e32 v227, 0x12000, v75
	v_lshlrev_b32_e32 v138, 1, v66
	v_add_u32_e32 v155, 0x11200, v138
	v_add_u32_e32 v156, 0x27400, v138
	global_load_dwordx4 v[210:213], v[34:35], off
	global_load_dwordx4 v[214:217], v[34:35], off offset:1024
	global_load_dwordx4 v[218:221], v[34:35], off offset:2048
	global_load_dwordx4 v[222:225], v[34:35], off offset:3072
	ds_read_b128 v[18:21], v227
	ds_read_b128 v[22:25], v227 offset:16
	v_mov_b32_e32 v138, v74
	ds_read_u8 v139, v138
	v_mov_b32_e32 v141, v73
	ds_read_u8 v140, v141
	v_mov_b32_e32 v150, v63
	v_mov_b32_e32 v151, v64
	s_waitcnt lgkmcnt(0)
	v_and_b32_e32 v78, 0xffff, v18
	v_lshrrev_b32_e32 v79, 16, v18
	v_lshl_add_u32 v78, v78, 7, v150
	v_lshl_add_u32 v79, v79, 7, v151
	s_mov_b32 m0, s76
	s_add_i32 s43, s76, 0x400
	global_load_lds_dwordx4 v78, s[50:51]
	s_mov_b32 m0, s43
	s_nop 0
	global_load_lds_dwordx4 v79, s[50:51]
	v_and_b32_e32 v78, 0xffff, v19
	v_lshrrev_b32_e32 v79, 16, v19
	v_lshl_add_u32 v78, v78, 7, v150
	v_lshl_add_u32 v79, v79, 7, v151
	s_mov_b32 m0, s77
	s_add_i32 s43, s77, 0x400
	global_load_lds_dwordx4 v78, s[50:51]
	s_mov_b32 m0, s43
	s_nop 0
	global_load_lds_dwordx4 v79, s[50:51]
	v_and_b32_e32 v78, 0xffff, v20
	v_lshrrev_b32_e32 v79, 16, v20
	v_lshl_add_u32 v78, v78, 7, v150
	v_lshl_add_u32 v79, v79, 7, v151
	s_mov_b32 m0, s78
	s_add_i32 s43, s78, 0x400
	global_load_lds_dwordx4 v78, s[50:51]
	s_mov_b32 m0, s43
	s_nop 0
	global_load_lds_dwordx4 v79, s[50:51]
	v_and_b32_e32 v78, 0xffff, v21
	v_lshrrev_b32_e32 v79, 16, v21
	v_lshl_add_u32 v78, v78, 7, v150
	v_lshl_add_u32 v79, v79, 7, v151
	s_mov_b32 m0, s79
	s_add_i32 s43, s79, 0x400
	global_load_lds_dwordx4 v78, s[50:51]
	s_mov_b32 m0, s43
	s_nop 0
	global_load_lds_dwordx4 v79, s[50:51]
	v_and_b32_e32 v78, 0xffff, v22
	v_lshrrev_b32_e32 v79, 16, v22
	v_lshl_add_u32 v78, v78, 7, v150
	v_lshl_add_u32 v79, v79, 7, v151
	s_mov_b32 m0, s98
	s_add_i32 s43, s98, 0x400
	global_load_lds_dwordx4 v78, s[50:51]
	s_mov_b32 m0, s43
	s_nop 0
	global_load_lds_dwordx4 v79, s[50:51]
	v_add_u32_e32 v143, 8, v139
	v_and_b32_e32 v142, 15, v143
	v_xor_b32_e32 v142, 8, v142
	v_bfe_u32 v144, v143, 4, 4
	v_mul_lo_u32 v142, v142, s92
	v_mul_lo_u32 v144, v144, s92
	v_mov_b32_e32 v143, v142
	v_mov_b32_e32 v145, v144
	ds_write2st64_b64 v159, v[142:143], v[144:145] offset1:2
	s_waitcnt vmcnt(10)
	ds_write_b128 v155, v[210:213]
	ds_write_b128 v155, v[214:217] offset:1024
	ds_write_b128 v156, v[218:221]
	ds_write_b128 v156, v[222:225] offset:1024
	s_waitcnt vmcnt(8)
	v_add_u32_e32 v54, s76, v59
	v_add_u32_e32 v55, s76, v60
	v_add_u32_e32 v56, s76, v61
	v_add_u32_e32 v57, s76, v62
	ds_read_b64_tr_b4 v[46:47], v160
	ds_read_b64_tr_b4 v[48:49], v160 offset:1024
	ds_read_b64_tr_b4 v[122:123], v54
	ds_read_b64_tr_b4 v[124:125], v55
	ds_read_b64_tr_b4 v[126:127], v56
	ds_read_b64_tr_b4 v[128:129], v57
	v_add_u32_e32 v147, 8, v140
	v_and_b32_e32 v146, 15, v147
	v_xor_b32_e32 v146, 8, v146
	v_bfe_u32 v148, v147, 4, 4
	v_mul_lo_u32 v146, v146, s92
	v_mul_lo_u32 v148, v148, s92
	v_mov_b32_e32 v147, v146
	v_mov_b32_e32 v149, v148
	ds_write2st64_b64 v77, v[146:147], v[148:149] offset1:2
	v_add_u32_e32 v138, 0x400, v74
	ds_read_u8 v139, v138
	v_add_u32_e32 v141, 0x400, v73
	ds_read_u8 v140, v141
	s_mov_b32 s43, s67
	v_mov_b32_e32 v138, s43
	ds_read2st64_b32 v[228:229], v138 offset1:1
	ds_read_b128 v[26:29], v227 offset:2048
	ds_read_b128 v[30:33], v227 offset:2064
	v_mov_b32_e32 v38, 0
	v_mov_b32_e32 v39, 0
	v_mov_b32_e32 v40, 0
	v_mov_b32_e32 v41, 0
	v_mov_b32_e32 v42, 0
	v_mov_b32_e32 v43, 0
	v_mov_b32_e32 v44, 0
	v_mov_b32_e32 v45, 0
	v_and_b32_e32 v78, 0xffff, v23
	v_lshrrev_b32_e32 v79, 16, v23
	v_lshl_add_u32 v78, v78, 7, v150
	v_lshl_add_u32 v79, v79, 7, v151
	s_mov_b32 m0, s99
	s_add_i32 s43, s99, 0x400
	global_load_lds_dwordx4 v78, s[50:51]
	s_mov_b32 m0, s43
	s_nop 0
	global_load_lds_dwordx4 v79, s[50:51]
	s_waitcnt vmcnt(8)
; #define TR4(p_) __builtin_amdgcn_ds_read_tr4_b64_v2i32((LAS v2i*)(p_))
; #define VDMA(st_, k_) do { _Pragma("unroll") for (int i_ = 0; i_ < 4; ++i_) { \
;         const unsigned off_ = (unsigned)((st_) >> 2) * (16384u * 128u) + (PE_ID(E, 4 * ((st_) & 3) + i_) << 7) + ((i_ & 1) ? cx1 : cx0); \
;         __builtin_amdgcn_global_load_lds((const unsigned*)(V4 + off_), (LAS unsigned*)(ldsb + BUF[k_] + 1024 * i_), 16, 0, 0); } } while (0)
; __device__ __forceinline__ void peer_v_tokens(int j, const LAS unsigned short* EL, const LAS unsigned char* AL  , const LAS float* ASC  , const LAS int* SAL  , ...
;     ...
;         for (int st = 0; st < 16; ++st) {
;             const int p = st >> 2, q = st & 3;
;             if (st < 14) VDMA(st + 2, (st + 2) % 3);
;             if (st < 14) asm volatile("s_waitcnt vmcnt(8)" ::: "memory");
;             else if (st == 14) asm volatile("s_waitcnt vmcnt(4)" ::: "memory");
;             else asm volatile("s_waitcnt vmcnt(0)" ::: "memory");
;             if (q == 0) {
; #pragma unroll
;                 for (int r = 0; r < 4; ++r) { accH[r] = 0; accL[r] = 0; } }
; #pragma unroll
;             for (int tp = 0; tp < 2; ++tp) {
;                 const v2i ao = TR4(ATL + (2 * q + tp) * 128 + 8 * s16), ah = TR4(ATL + 1024 + (2 * q + tp) * 128 + 8 * s16);
; #pragma unroll
;                 for (int r = 0; r < 4; ++r) {
;                     const v2i d = TR4(ldsb + BUF[st % 3] + 2048 * tp + roff[r]);
;                     accH[r] = __builtin_amdgcn_sdot8(d.x, ah.x, accH[r], false); accH[r] = __builtin_amdgcn_sdot8(d.y, ah.y, accH[r], false);
;                     accL[r] = __builtin_amdgcn_sdot8(d.x, ao.x, accL[r], false); accL[r] = __builtin_amdgcn_sdot8(d.y, ao.y, accL[r], false);
;                 }
;             }
	v_add_u32_e32 v54, s77, v59
	v_add_u32_e32 v55, s77, v60
	v_add_u32_e32 v56, s77, v61
	v_add_u32_e32 v57, s77, v62
	ds_read_b64_tr_b4 v[50:51], v160 offset:128
	ds_read_b64_tr_b4 v[52:53], v160 offset:1152
	ds_read_b64_tr_b4 v[130:131], v54
	ds_read_b64_tr_b4 v[132:133], v55
	ds_read_b64_tr_b4 v[134:135], v56
	ds_read_b64_tr_b4 v[136:137], v57
	s_waitcnt lgkmcnt(12)
	v_dot8c_i32_i4_e32 v38, v122, v48
	v_dot8c_i32_i4_e32 v39, v122, v46
	v_dot8c_i32_i4_e32 v40, v124, v48
	v_dot8c_i32_i4_e32 v41, v124, v46
	v_dot8c_i32_i4_e32 v42, v126, v48
	v_dot8c_i32_i4_e32 v43, v126, v46
	v_dot8c_i32_i4_e32 v44, v128, v48
	v_dot8c_i32_i4_e32 v45, v128, v46
	v_dot8c_i32_i4_e32 v38, v123, v49
	v_dot8c_i32_i4_e32 v39, v123, v47
	v_dot8c_i32_i4_e32 v40, v125, v49
	v_dot8c_i32_i4_e32 v41, v125, v47
	v_dot8c_i32_i4_e32 v42, v127, v49
	v_dot8c_i32_i4_e32 v43, v127, v47
	v_dot8c_i32_i4_e32 v44, v129, v49
	v_dot8c_i32_i4_e32 v45, v129, v47
	v_and_b32_e32 v78, 0xffff, v24
	v_lshrrev_b32_e32 v79, 16, v24
	v_lshl_add_u32 v78, v78, 7, v150
	v_lshl_add_u32 v79, v79, 7, v151
	s_mov_b32 m0, s76
	s_add_i32 s43, s76, 0x400
	global_load_lds_dwordx4 v78, s[50:51]
	s_mov_b32 m0, s43
	s_nop 0
	global_load_lds_dwordx4 v79, s[50:51]
	s_waitcnt vmcnt(8)
	v_add_u32_e32 v54, s78, v59
	v_add_u32_e32 v55, s78, v60
	v_add_u32_e32 v56, s78, v61
	v_add_u32_e32 v57, s78, v62
	ds_read_b64_tr_b4 v[46:47], v160 offset:256
	ds_read_b64_tr_b4 v[48:49], v160 offset:1280
	ds_read_b64_tr_b4 v[122:123], v54
	ds_read_b64_tr_b4 v[124:125], v55
	ds_read_b64_tr_b4 v[126:127], v56
	ds_read_b64_tr_b4 v[128:129], v57
	s_waitcnt lgkmcnt(6)
	v_dot8c_i32_i4_e32 v38, v130, v52
	v_dot8c_i32_i4_e32 v39, v130, v50
	v_dot8c_i32_i4_e32 v40, v132, v52
	v_dot8c_i32_i4_e32 v41, v132, v50
	v_dot8c_i32_i4_e32 v42, v134, v52
	v_dot8c_i32_i4_e32 v43, v134, v50
	v_dot8c_i32_i4_e32 v44, v136, v52
	v_dot8c_i32_i4_e32 v45, v136, v50
	v_dot8c_i32_i4_e32 v38, v131, v53
	v_dot8c_i32_i4_e32 v39, v131, v51
	v_dot8c_i32_i4_e32 v40, v133, v53
	v_dot8c_i32_i4_e32 v41, v133, v51
	v_dot8c_i32_i4_e32 v42, v135, v53
	v_dot8c_i32_i4_e32 v43, v135, v51
	v_dot8c_i32_i4_e32 v44, v137, v53
	v_dot8c_i32_i4_e32 v45, v137, v51
	v_and_b32_e32 v78, 0xffff, v25
	v_lshrrev_b32_e32 v79, 16, v25
	v_lshl_add_u32 v78, v78, 7, v150
	v_lshl_add_u32 v79, v79, 7, v151
	s_mov_b32 m0, s77
	s_add_i32 s43, s77, 0x400
	global_load_lds_dwordx4 v78, s[50:51]
	s_mov_b32 m0, s43
	s_nop 0
	global_load_lds_dwordx4 v79, s[50:51]
	s_waitcnt vmcnt(8)
	v_add_u32_e32 v54, s79, v59
	v_add_u32_e32 v55, s79, v60
	v_add_u32_e32 v56, s79, v61
	v_add_u32_e32 v57, s79, v62
	ds_read_b64_tr_b4 v[50:51], v160 offset:384
	ds_read_b64_tr_b4 v[52:53], v160 offset:1408
	ds_read_b64_tr_b4 v[130:131], v54
	ds_read_b64_tr_b4 v[132:133], v55
	ds_read_b64_tr_b4 v[134:135], v56
	ds_read_b64_tr_b4 v[136:137], v57
	s_waitcnt lgkmcnt(6)
	v_dot8c_i32_i4_e32 v38, v122, v48
	v_dot8c_i32_i4_e32 v39, v122, v46
	v_dot8c_i32_i4_e32 v40, v124, v48
	v_dot8c_i32_i4_e32 v41, v124, v46
	v_dot8c_i32_i4_e32 v42, v126, v48
	v_dot8c_i32_i4_e32 v43, v126, v46
	v_dot8c_i32_i4_e32 v44, v128, v48
	v_dot8c_i32_i4_e32 v45, v128, v46
	v_dot8c_i32_i4_e32 v38, v123, v49
	v_dot8c_i32_i4_e32 v39, v123, v47
	v_dot8c_i32_i4_e32 v40, v125, v49
	v_dot8c_i32_i4_e32 v41, v125, v47
	v_dot8c_i32_i4_e32 v42, v127, v49
	v_dot8c_i32_i4_e32 v43, v127, v47
	v_dot8c_i32_i4_e32 v44, v129, v49
	v_dot8c_i32_i4_e32 v45, v129, v47
	s_waitcnt lgkmcnt(15)
	v_and_b32_e32 v78, 0xffff, v26
	v_lshrrev_b32_e32 v79, 16, v26
	v_lshl_add_u32 v78, v78, 7, v150
	v_lshl_add_u32 v79, v79, 7, v151
	s_mov_b32 m0, s78
	s_add_i32 s43, s78, 0x400
	global_load_lds_dwordx4 v78, s[50:51]
	s_mov_b32 m0, s43
	s_nop 0
	global_load_lds_dwordx4 v79, s[50:51]
	s_waitcnt vmcnt(8)
	v_add_u32_e32 v54, s98, v59
	v_add_u32_e32 v55, s98, v60
	v_add_u32_e32 v56, s98, v61
	v_add_u32_e32 v57, s98, v62
	ds_read_b64_tr_b4 v[46:47], v160 offset:512
	ds_read_b64_tr_b4 v[48:49], v160 offset:1536
	ds_read_b64_tr_b4 v[122:123], v54
	ds_read_b64_tr_b4 v[124:125], v55
	ds_read_b64_tr_b4 v[126:127], v56
	ds_read_b64_tr_b4 v[128:129], v57
	s_waitcnt lgkmcnt(6)
	v_dot8c_i32_i4_e32 v38, v130, v52
	v_dot8c_i32_i4_e32 v39, v130, v50
	v_dot8c_i32_i4_e32 v40, v132, v52
	v_dot8c_i32_i4_e32 v41, v132, v50
	v_dot8c_i32_i4_e32 v42, v134, v52
	v_dot8c_i32_i4_e32 v43, v134, v50
	v_dot8c_i32_i4_e32 v44, v136, v52
	v_dot8c_i32_i4_e32 v45, v136, v50
	v_dot8c_i32_i4_e32 v38, v131, v53
	v_dot8c_i32_i4_e32 v39, v131, v51
	v_dot8c_i32_i4_e32 v40, v133, v53
	v_dot8c_i32_i4_e32 v41, v133, v51
	v_dot8c_i32_i4_e32 v42, v135, v53
	v_dot8c_i32_i4_e32 v43, v135, v51
	v_dot8c_i32_i4_e32 v44, v137, v53
	v_dot8c_i32_i4_e32 v45, v137, v51
	v_and_b32_e32 v78, 0xffff, v27
	v_lshrrev_b32_e32 v79, 16, v27
	v_lshl_add_u32 v78, v78, 7, v150
	v_lshl_add_u32 v79, v79, 7, v151
	s_mov_b32 m0, s79
	s_add_i32 s43, s79, 0x400
	global_load_lds_dwordx4 v78, s[50:51]
	s_mov_b32 m0, s43
	s_nop 0
	global_load_lds_dwordx4 v79, s[50:51]
	s_waitcnt vmcnt(8)
	v_add_u32_e32 v54, s99, v59
	v_add_u32_e32 v55, s99, v60
	v_add_u32_e32 v56, s99, v61
	v_add_u32_e32 v57, s99, v62
	ds_read_b64_tr_b4 v[50:51], v160 offset:640
	ds_read_b64_tr_b4 v[52:53], v160 offset:1664
	ds_read_b64_tr_b4 v[130:131], v54
	ds_read_b64_tr_b4 v[132:133], v55
	ds_read_b64_tr_b4 v[134:135], v56
	ds_read_b64_tr_b4 v[136:137], v57
	s_waitcnt lgkmcnt(6)
	v_dot8c_i32_i4_e32 v38, v122, v48
	v_dot8c_i32_i4_e32 v39, v122, v46
	v_dot8c_i32_i4_e32 v40, v124, v48
	v_dot8c_i32_i4_e32 v41, v124, v46
	v_dot8c_i32_i4_e32 v42, v126, v48
	v_dot8c_i32_i4_e32 v43, v126, v46
	v_dot8c_i32_i4_e32 v44, v128, v48
	v_dot8c_i32_i4_e32 v45, v128, v46
	v_dot8c_i32_i4_e32 v38, v123, v49
	v_dot8c_i32_i4_e32 v39, v123, v47
	v_dot8c_i32_i4_e32 v40, v125, v49
	v_dot8c_i32_i4_e32 v41, v125, v47
	v_dot8c_i32_i4_e32 v42, v127, v49
	v_dot8c_i32_i4_e32 v43, v127, v47
	v_dot8c_i32_i4_e32 v44, v129, v49
	v_dot8c_i32_i4_e32 v45, v129, v47
	s_waitcnt lgkmcnt(15)
; #define LAS __attribute__((address_space(3)))
; __device__ __forceinline__ bf16 f2bf(float f) { return (bf16)f2bfu(f); }
; #define TR4(p_) __builtin_amdgcn_ds_read_tr4_b64_v2i32((LAS v2i*)(p_))
; __device__ __forceinline__ void peer_v_tokens(int j, const LAS unsigned short* EL, const LAS unsigned char* AL  , const LAS float* ASC  , const LAS int* SAL  , ...
;     ...
;             const unsigned lo = (((unsigned)tq & 15u) ^ 8u) * 0x11111111u, hi = ((unsigned)(tq >> 4) & 15u) * 0x11111111u;
;             typedef unsigned u2v __attribute__((ext_vector_type(2)));
;             u2v l2; l2.x = lo; l2.y = lo; u2v h2; h2.x = hi; h2.y = hi;
;             *(LAS u2v*)(ATL + 8 * idx) = l2; *(LAS u2v*)(ATL + 1024 + 8 * idx) = h2;
;     ...
;         for (int st = 0; st < 16; ++st) {
;             const int p = st >> 2, q = st & 3;
;             if (st < 14) VDMA(st + 2, (st + 2) % 3);
;             if (st < 14) asm volatile("s_waitcnt vmcnt(8)" ::: "memory");
;             else if (st == 14) asm volatile("s_waitcnt vmcnt(4)" ::: "memory");
;             else asm volatile("s_waitcnt vmcnt(0)" ::: "memory");
;             if (q == 0) {
; #pragma unroll
;                 for (int r = 0; r < 4; ++r) { accH[r] = 0; accL[r] = 0; } }
; #pragma unroll
;             for (int tp = 0; tp < 2; ++tp) {
;                 const v2i ao = TR4(ATL + (2 * q + tp) * 128 + 8 * s16), ah = TR4(ATL + 1024 + (2 * q + tp) * 128 + 8 * s16);
; #pragma unroll
;                 for (int r = 0; r < 4; ++r) {
;                     const v2i d = TR4(ldsb + BUF[st % 3] + 2048 * tp + roff[r]);
;                     accH[r] = __builtin_amdgcn_sdot8(d.x, ah.x, accH[r], false); accH[r] = __builtin_amdgcn_sdot8(d.y, ah.y, accH[r], false);
;                     accL[r] = __builtin_amdgcn_sdot8(d.x, ao.x, accL[r], false); accL[r] = __builtin_amdgcn_sdot8(d.y, ao.y, accL[r], false);
;                 }
;             }
;             asm volatile("s_waitcnt lgkmcnt(0)" ::: "memory");
;             if (q == 3) {
; #pragma unroll
;                 for (int r = 0; r < 4; ++r) STASH[256 * p + 16 * (grp + 4 * r) + pc] = f2bf(asc * (float)(2 * ((accH[r] << 4) + accL[r]) + sa));
;             }
	v_add_u32_e32 v143, 8, v139
	v_and_b32_e32 v142, 15, v143
	v_xor_b32_e32 v142, 8, v142
	v_bfe_u32 v144, v143, 4, 4
	v_mul_lo_u32 v142, v142, s92
	v_mul_lo_u32 v144, v144, s92
	v_mov_b32_e32 v143, v142
	v_mov_b32_e32 v145, v144
	ds_write2st64_b64 v159, v[142:143], v[144:145] offset1:2
	v_and_b32_e32 v78, 0xffff, v28
	v_lshrrev_b32_e32 v79, 16, v28
	v_lshl_add_u32 v78, v78, 7, v150
	v_lshl_add_u32 v79, v79, 7, v151
	s_mov_b32 m0, s98
	s_add_i32 s43, s98, 0x400
	global_load_lds_dwordx4 v78, s[50:51]
	s_mov_b32 m0, s43
	s_nop 0
	global_load_lds_dwordx4 v79, s[50:51]
	s_waitcnt vmcnt(8)
	v_add_u32_e32 v54, s76, v59
	v_add_u32_e32 v55, s76, v60
	v_add_u32_e32 v56, s76, v61
	v_add_u32_e32 v57, s76, v62
	ds_read_b64_tr_b4 v[46:47], v160 offset:768
	ds_read_b64_tr_b4 v[48:49], v160 offset:1792
	ds_read_b64_tr_b4 v[122:123], v54
	ds_read_b64_tr_b4 v[124:125], v55
	ds_read_b64_tr_b4 v[126:127], v56
	ds_read_b64_tr_b4 v[128:129], v57
	s_waitcnt lgkmcnt(7)
	v_dot8c_i32_i4_e32 v38, v130, v52
	v_dot8c_i32_i4_e32 v39, v130, v50
	v_dot8c_i32_i4_e32 v40, v132, v52
	v_dot8c_i32_i4_e32 v41, v132, v50
	v_dot8c_i32_i4_e32 v42, v134, v52
	v_dot8c_i32_i4_e32 v43, v134, v50
	v_dot8c_i32_i4_e32 v44, v136, v52
	v_dot8c_i32_i4_e32 v45, v136, v50
	v_dot8c_i32_i4_e32 v38, v131, v53
	v_dot8c_i32_i4_e32 v39, v131, v51
	v_dot8c_i32_i4_e32 v40, v133, v53
	v_dot8c_i32_i4_e32 v41, v133, v51
	v_dot8c_i32_i4_e32 v42, v135, v53
	v_dot8c_i32_i4_e32 v43, v135, v51
	v_dot8c_i32_i4_e32 v44, v137, v53
	v_dot8c_i32_i4_e32 v45, v137, v51
	v_and_b32_e32 v78, 0xffff, v29
	v_lshrrev_b32_e32 v79, 16, v29
	v_lshl_add_u32 v78, v78, 7, v150
	v_lshl_add_u32 v79, v79, 7, v151
	s_mov_b32 m0, s99
	s_add_i32 s43, s99, 0x400
	global_load_lds_dwordx4 v78, s[50:51]
	s_mov_b32 m0, s43
	s_nop 0
	global_load_lds_dwordx4 v79, s[50:51]
	s_waitcnt vmcnt(8)
	v_add_u32_e32 v54, s77, v59
	v_add_u32_e32 v55, s77, v60
	v_add_u32_e32 v56, s77, v61
	v_add_u32_e32 v57, s77, v62
	ds_read_b64_tr_b4 v[50:51], v160 offset:896
	ds_read_b64_tr_b4 v[52:53], v160 offset:1920
	ds_read_b64_tr_b4 v[130:131], v54
	ds_read_b64_tr_b4 v[132:133], v55
	ds_read_b64_tr_b4 v[134:135], v56
	ds_read_b64_tr_b4 v[136:137], v57
	s_waitcnt lgkmcnt(6)
	v_dot8c_i32_i4_e32 v38, v122, v48
	v_dot8c_i32_i4_e32 v39, v122, v46
	v_dot8c_i32_i4_e32 v40, v124, v48
	v_dot8c_i32_i4_e32 v41, v124, v46
	v_dot8c_i32_i4_e32 v42, v126, v48
	v_dot8c_i32_i4_e32 v43, v126, v46
	v_dot8c_i32_i4_e32 v44, v128, v48
	v_dot8c_i32_i4_e32 v45, v128, v46
	v_dot8c_i32_i4_e32 v38, v123, v49
	v_dot8c_i32_i4_e32 v39, v123, v47
	v_dot8c_i32_i4_e32 v40, v125, v49
	v_dot8c_i32_i4_e32 v41, v125, v47
	v_dot8c_i32_i4_e32 v42, v127, v49
	v_dot8c_i32_i4_e32 v43, v127, v47
	v_dot8c_i32_i4_e32 v44, v129, v49
	v_dot8c_i32_i4_e32 v45, v129, v47
	v_and_b32_e32 v78, 0xffff, v30
	v_lshrrev_b32_e32 v79, 16, v30
	v_lshl_add_u32 v78, v78, 7, v150
	v_lshl_add_u32 v79, v79, 7, v151
	s_mov_b32 m0, s76
	s_add_i32 s43, s76, 0x400
	global_load_lds_dwordx4 v78, s[50:51]
	s_mov_b32 m0, s43
	s_nop 0
	global_load_lds_dwordx4 v79, s[50:51]
	s_waitcnt vmcnt(8)
	v_add_u32_e32 v54, s78, v59
	v_add_u32_e32 v55, s78, v60
	v_add_u32_e32 v56, s78, v61
	v_add_u32_e32 v57, s78, v62
	ds_read_b64_tr_b4 v[46:47], v160
	ds_read_b64_tr_b4 v[48:49], v160 offset:1024
	ds_read_b64_tr_b4 v[122:123], v54
	ds_read_b64_tr_b4 v[124:125], v55
	ds_read_b64_tr_b4 v[126:127], v56
	ds_read_b64_tr_b4 v[128:129], v57
	s_waitcnt lgkmcnt(6)
	v_dot8c_i32_i4_e32 v38, v130, v52
	v_dot8c_i32_i4_e32 v39, v130, v50
	v_dot8c_i32_i4_e32 v40, v132, v52
	v_dot8c_i32_i4_e32 v41, v132, v50
	v_dot8c_i32_i4_e32 v42, v134, v52
	v_dot8c_i32_i4_e32 v43, v134, v50
	v_dot8c_i32_i4_e32 v44, v136, v52
	v_dot8c_i32_i4_e32 v45, v136, v50
	v_dot8c_i32_i4_e32 v38, v131, v53
	v_dot8c_i32_i4_e32 v39, v131, v51
	v_dot8c_i32_i4_e32 v40, v133, v53
	v_dot8c_i32_i4_e32 v41, v133, v51
	v_dot8c_i32_i4_e32 v42, v135, v53
	v_dot8c_i32_i4_e32 v43, v135, v51
	v_dot8c_i32_i4_e32 v44, v137, v53
	v_dot8c_i32_i4_e32 v45, v137, v51
	s_nop 3
	s_waitcnt lgkmcnt(15)
	v_lshlrev_b32_e32 v38, 5, v38
	v_lshlrev_b32_e32 v39, 1, v39
	v_add3_u32 v38, v39, v229, v38
	v_cvt_f32_i32_e32 v38, v38
	v_mul_f32_e32 v38, v228, v38
	v_lshlrev_b32_e32 v40, 5, v40
	v_lshlrev_b32_e32 v41, 1, v41
	v_add3_u32 v40, v41, v229, v40
	v_cvt_f32_i32_e32 v40, v40
	v_mul_f32_e32 v40, v228, v40
	v_lshlrev_b32_e32 v42, 5, v42
	v_lshlrev_b32_e32 v43, 1, v43
	v_add3_u32 v42, v43, v229, v42
	v_cvt_f32_i32_e32 v42, v42
	v_mul_f32_e32 v42, v228, v42
	v_lshlrev_b32_e32 v44, 5, v44
	v_lshlrev_b32_e32 v45, 1, v45
	v_add3_u32 v44, v45, v229, v44
	v_cvt_f32_i32_e32 v44, v44
	v_mul_f32_e32 v44, v228, v44
	v_cvt_pk_bf16_f32 v162, v38, v40
	v_cvt_pk_bf16_f32 v163, v42, v44
	v_add_u32_e32 v147, 8, v140
	v_and_b32_e32 v146, 15, v147
	v_xor_b32_e32 v146, 8, v146
	v_bfe_u32 v148, v147, 4, 4
	v_mul_lo_u32 v146, v146, s92
	v_mul_lo_u32 v148, v148, s92
	v_mov_b32_e32 v147, v146
	v_mov_b32_e32 v149, v148
	ds_write2st64_b64 v77, v[146:147], v[148:149] offset1:2
	v_mov_b32_e32 v138, v74
	ds_read_u8 v139, v138
	v_mov_b32_e32 v141, v73
	ds_read_u8 v140, v141
	s_add_i32 s43, s67, 32
	v_mov_b32_e32 v138, s43
	ds_read2st64_b32 v[228:229], v138 offset1:1
	ds_read_b128 v[18:21], v227
	ds_read_b128 v[22:25], v227 offset:16
	v_add_u32_e32 v152, 0x200000, v63
	v_add_u32_e32 v153, 0x200000, v64
	v_mov_b32_e32 v38, 0
	v_mov_b32_e32 v39, 0
	v_mov_b32_e32 v40, 0
	v_mov_b32_e32 v41, 0
	v_mov_b32_e32 v42, 0
	v_mov_b32_e32 v43, 0
	v_mov_b32_e32 v44, 0
	v_mov_b32_e32 v45, 0
	v_and_b32_e32 v78, 0xffff, v31
	v_lshrrev_b32_e32 v79, 16, v31
	v_lshl_add_u32 v78, v78, 7, v150
	v_lshl_add_u32 v79, v79, 7, v151
	s_mov_b32 m0, s77
	s_add_i32 s43, s77, 0x400
	global_load_lds_dwordx4 v78, s[50:51]
	s_mov_b32 m0, s43
	s_nop 0
	global_load_lds_dwordx4 v79, s[50:51]
	s_waitcnt vmcnt(8)
; #define TR4(p_) __builtin_amdgcn_ds_read_tr4_b64_v2i32((LAS v2i*)(p_))
; #define VDMA(st_, k_) do { _Pragma("unroll") for (int i_ = 0; i_ < 4; ++i_) { \
;         const unsigned off_ = (unsigned)((st_) >> 2) * (16384u * 128u) + (PE_ID(E, 4 * ((st_) & 3) + i_) << 7) + ((i_ & 1) ? cx1 : cx0); \
;         __builtin_amdgcn_global_load_lds((const unsigned*)(V4 + off_), (LAS unsigned*)(ldsb + BUF[k_] + 1024 * i_), 16, 0, 0); } } while (0)
; __device__ __forceinline__ void peer_v_tokens(int j, const LAS unsigned short* EL, const LAS unsigned char* AL  , const LAS float* ASC  , const LAS int* SAL  , ...
;     ...
;         for (int st = 0; st < 16; ++st) {
;             const int p = st >> 2, q = st & 3;
;             if (st < 14) VDMA(st + 2, (st + 2) % 3);
;             if (st < 14) asm volatile("s_waitcnt vmcnt(8)" ::: "memory");
;             else if (st == 14) asm volatile("s_waitcnt vmcnt(4)" ::: "memory");
;             else asm volatile("s_waitcnt vmcnt(0)" ::: "memory");
;             if (q == 0) {
; #pragma unroll
;                 for (int r = 0; r < 4; ++r) { accH[r] = 0; accL[r] = 0; } }
; #pragma unroll
;             for (int tp = 0; tp < 2; ++tp) {
;                 const v2i ao = TR4(ATL + (2 * q + tp) * 128 + 8 * s16), ah = TR4(ATL + 1024 + (2 * q + tp) * 128 + 8 * s16);
; #pragma unroll
;                 for (int r = 0; r < 4; ++r) {
;                     const v2i d = TR4(ldsb + BUF[st % 3] + 2048 * tp + roff[r]);
;                     accH[r] = __builtin_amdgcn_sdot8(d.x, ah.x, accH[r], false); accH[r] = __builtin_amdgcn_sdot8(d.y, ah.y, accH[r], false);
;                     accL[r] = __builtin_amdgcn_sdot8(d.x, ao.x, accL[r], false); accL[r] = __builtin_amdgcn_sdot8(d.y, ao.y, accL[r], false);
;                 }
;             }
	v_add_u32_e32 v54, s79, v59
	v_add_u32_e32 v55, s79, v60
	v_add_u32_e32 v56, s79, v61
	v_add_u32_e32 v57, s79, v62
	ds_read_b64_tr_b4 v[50:51], v160 offset:128
	ds_read_b64_tr_b4 v[52:53], v160 offset:1152
	ds_read_b64_tr_b4 v[130:131], v54
	ds_read_b64_tr_b4 v[132:133], v55
	ds_read_b64_tr_b4 v[134:135], v56
	ds_read_b64_tr_b4 v[136:137], v57
	s_waitcnt lgkmcnt(12)
	v_dot8c_i32_i4_e32 v38, v122, v48
	v_dot8c_i32_i4_e32 v39, v122, v46
	v_dot8c_i32_i4_e32 v40, v124, v48
	v_dot8c_i32_i4_e32 v41, v124, v46
	v_dot8c_i32_i4_e32 v42, v126, v48
	v_dot8c_i32_i4_e32 v43, v126, v46
	v_dot8c_i32_i4_e32 v44, v128, v48
	v_dot8c_i32_i4_e32 v45, v128, v46
	v_dot8c_i32_i4_e32 v38, v123, v49
	v_dot8c_i32_i4_e32 v39, v123, v47
	v_dot8c_i32_i4_e32 v40, v125, v49
	v_dot8c_i32_i4_e32 v41, v125, v47
	v_dot8c_i32_i4_e32 v42, v127, v49
	v_dot8c_i32_i4_e32 v43, v127, v47
	v_dot8c_i32_i4_e32 v44, v129, v49
	v_dot8c_i32_i4_e32 v45, v129, v47
	v_and_b32_e32 v78, 0xffff, v32
	v_lshrrev_b32_e32 v79, 16, v32
	v_lshl_add_u32 v78, v78, 7, v150
	v_lshl_add_u32 v79, v79, 7, v151
	s_mov_b32 m0, s78
	s_add_i32 s43, s78, 0x400
	global_load_lds_dwordx4 v78, s[50:51]
	s_mov_b32 m0, s43
	s_nop 0
	global_load_lds_dwordx4 v79, s[50:51]
	s_waitcnt vmcnt(8)
	v_add_u32_e32 v54, s98, v59
	v_add_u32_e32 v55, s98, v60
	v_add_u32_e32 v56, s98, v61
	v_add_u32_e32 v57, s98, v62
	ds_read_b64_tr_b4 v[46:47], v160 offset:256
	ds_read_b64_tr_b4 v[48:49], v160 offset:1280
	ds_read_b64_tr_b4 v[122:123], v54
	ds_read_b64_tr_b4 v[124:125], v55
	ds_read_b64_tr_b4 v[126:127], v56
	ds_read_b64_tr_b4 v[128:129], v57
	s_waitcnt lgkmcnt(6)
	v_dot8c_i32_i4_e32 v38, v130, v52
	v_dot8c_i32_i4_e32 v39, v130, v50
	v_dot8c_i32_i4_e32 v40, v132, v52
	v_dot8c_i32_i4_e32 v41, v132, v50
	v_dot8c_i32_i4_e32 v42, v134, v52
	v_dot8c_i32_i4_e32 v43, v134, v50
	v_dot8c_i32_i4_e32 v44, v136, v52
	v_dot8c_i32_i4_e32 v45, v136, v50
	v_dot8c_i32_i4_e32 v38, v131, v53
	v_dot8c_i32_i4_e32 v39, v131, v51
	v_dot8c_i32_i4_e32 v40, v133, v53
	v_dot8c_i32_i4_e32 v41, v133, v51
	v_dot8c_i32_i4_e32 v42, v135, v53
	v_dot8c_i32_i4_e32 v43, v135, v51
	v_dot8c_i32_i4_e32 v44, v137, v53
	v_dot8c_i32_i4_e32 v45, v137, v51
	v_and_b32_e32 v78, 0xffff, v33
	v_lshrrev_b32_e32 v79, 16, v33
	v_lshl_add_u32 v78, v78, 7, v150
	v_lshl_add_u32 v79, v79, 7, v151
	s_mov_b32 m0, s79
	s_add_i32 s43, s79, 0x400
	global_load_lds_dwordx4 v78, s[50:51]
	s_mov_b32 m0, s43
	s_nop 0
	global_load_lds_dwordx4 v79, s[50:51]
	s_waitcnt vmcnt(8)
	v_add_u32_e32 v54, s99, v59
	v_add_u32_e32 v55, s99, v60
	v_add_u32_e32 v56, s99, v61
	v_add_u32_e32 v57, s99, v62
	ds_read_b64_tr_b4 v[50:51], v160 offset:384
	ds_read_b64_tr_b4 v[52:53], v160 offset:1408
	ds_read_b64_tr_b4 v[130:131], v54
	ds_read_b64_tr_b4 v[132:133], v55
	ds_read_b64_tr_b4 v[134:135], v56
	ds_read_b64_tr_b4 v[136:137], v57
	s_waitcnt lgkmcnt(6)
	v_dot8c_i32_i4_e32 v38, v122, v48
	v_dot8c_i32_i4_e32 v39, v122, v46
	v_dot8c_i32_i4_e32 v40, v124, v48
	v_dot8c_i32_i4_e32 v41, v124, v46
	v_dot8c_i32_i4_e32 v42, v126, v48
	v_dot8c_i32_i4_e32 v43, v126, v46
	v_dot8c_i32_i4_e32 v44, v128, v48
	v_dot8c_i32_i4_e32 v45, v128, v46
	v_dot8c_i32_i4_e32 v38, v123, v49
	v_dot8c_i32_i4_e32 v39, v123, v47
	v_dot8c_i32_i4_e32 v40, v125, v49
	v_dot8c_i32_i4_e32 v41, v125, v47
	v_dot8c_i32_i4_e32 v42, v127, v49
	v_dot8c_i32_i4_e32 v43, v127, v47
	v_dot8c_i32_i4_e32 v44, v129, v49
	v_dot8c_i32_i4_e32 v45, v129, v47
	s_waitcnt lgkmcnt(15)
	v_and_b32_e32 v78, 0xffff, v18
	v_lshrrev_b32_e32 v79, 16, v18
	v_lshl_add_u32 v78, v78, 7, v152
	v_lshl_add_u32 v79, v79, 7, v153
	s_mov_b32 m0, s98
	s_add_i32 s43, s98, 0x400
	global_load_lds_dwordx4 v78, s[50:51]
	s_mov_b32 m0, s43
	s_nop 0
	global_load_lds_dwordx4 v79, s[50:51]
	s_waitcnt vmcnt(8)
	v_add_u32_e32 v54, s76, v59
	v_add_u32_e32 v55, s76, v60
	v_add_u32_e32 v56, s76, v61
	v_add_u32_e32 v57, s76, v62
	ds_read_b64_tr_b4 v[46:47], v160 offset:512
	ds_read_b64_tr_b4 v[48:49], v160 offset:1536
	ds_read_b64_tr_b4 v[122:123], v54
	ds_read_b64_tr_b4 v[124:125], v55
	ds_read_b64_tr_b4 v[126:127], v56
	ds_read_b64_tr_b4 v[128:129], v57
	s_waitcnt lgkmcnt(6)
	v_dot8c_i32_i4_e32 v38, v130, v52
	v_dot8c_i32_i4_e32 v39, v130, v50
	v_dot8c_i32_i4_e32 v40, v132, v52
	v_dot8c_i32_i4_e32 v41, v132, v50
	v_dot8c_i32_i4_e32 v42, v134, v52
	v_dot8c_i32_i4_e32 v43, v134, v50
	v_dot8c_i32_i4_e32 v44, v136, v52
	v_dot8c_i32_i4_e32 v45, v136, v50
	v_dot8c_i32_i4_e32 v38, v131, v53
	v_dot8c_i32_i4_e32 v39, v131, v51
	v_dot8c_i32_i4_e32 v40, v133, v53
	v_dot8c_i32_i4_e32 v41, v133, v51
	v_dot8c_i32_i4_e32 v42, v135, v53
	v_dot8c_i32_i4_e32 v43, v135, v51
	v_dot8c_i32_i4_e32 v44, v137, v53
	v_dot8c_i32_i4_e32 v45, v137, v51
	v_and_b32_e32 v78, 0xffff, v19
	v_lshrrev_b32_e32 v79, 16, v19
	v_lshl_add_u32 v78, v78, 7, v152
	v_lshl_add_u32 v79, v79, 7, v153
	s_mov_b32 m0, s99
	s_add_i32 s43, s99, 0x400
	global_load_lds_dwordx4 v78, s[50:51]
	s_mov_b32 m0, s43
	s_nop 0
	global_load_lds_dwordx4 v79, s[50:51]
	s_waitcnt vmcnt(8)
	v_add_u32_e32 v54, s77, v59
	v_add_u32_e32 v55, s77, v60
	v_add_u32_e32 v56, s77, v61
	v_add_u32_e32 v57, s77, v62
	ds_read_b64_tr_b4 v[50:51], v160 offset:640
	ds_read_b64_tr_b4 v[52:53], v160 offset:1664
	ds_read_b64_tr_b4 v[130:131], v54
	ds_read_b64_tr_b4 v[132:133], v55
	ds_read_b64_tr_b4 v[134:135], v56
	ds_read_b64_tr_b4 v[136:137], v57
	s_waitcnt lgkmcnt(6)
	v_dot8c_i32_i4_e32 v38, v122, v48
	v_dot8c_i32_i4_e32 v39, v122, v46
	v_dot8c_i32_i4_e32 v40, v124, v48
	v_dot8c_i32_i4_e32 v41, v124, v46
	v_dot8c_i32_i4_e32 v42, v126, v48
	v_dot8c_i32_i4_e32 v43, v126, v46
	v_dot8c_i32_i4_e32 v44, v128, v48
	v_dot8c_i32_i4_e32 v45, v128, v46
	v_dot8c_i32_i4_e32 v38, v123, v49
	v_dot8c_i32_i4_e32 v39, v123, v47
	v_dot8c_i32_i4_e32 v40, v125, v49
	v_dot8c_i32_i4_e32 v41, v125, v47
	v_dot8c_i32_i4_e32 v42, v127, v49
	v_dot8c_i32_i4_e32 v43, v127, v47
	v_dot8c_i32_i4_e32 v44, v129, v49
	v_dot8c_i32_i4_e32 v45, v129, v47
	s_waitcnt lgkmcnt(15)
; #define LAS __attribute__((address_space(3)))
; __device__ __forceinline__ bf16 f2bf(float f) { return (bf16)f2bfu(f); }
; #define TR4(p_) __builtin_amdgcn_ds_read_tr4_b64_v2i32((LAS v2i*)(p_))
; __device__ __forceinline__ void peer_v_tokens(int j, const LAS unsigned short* EL, const LAS unsigned char* AL  , const LAS float* ASC  , const LAS int* SAL  , ...
;     ...
;             const unsigned lo = (((unsigned)tq & 15u) ^ 8u) * 0x11111111u, hi = ((unsigned)(tq >> 4) & 15u) * 0x11111111u;
;             typedef unsigned u2v __attribute__((ext_vector_type(2)));
;             u2v l2; l2.x = lo; l2.y = lo; u2v h2; h2.x = hi; h2.y = hi;
;             *(LAS u2v*)(ATL + 8 * idx) = l2; *(LAS u2v*)(ATL + 1024 + 8 * idx) = h2;
;     ...
;         for (int st = 0; st < 16; ++st) {
;             const int p = st >> 2, q = st & 3;
;             if (st < 14) VDMA(st + 2, (st + 2) % 3);
;             if (st < 14) asm volatile("s_waitcnt vmcnt(8)" ::: "memory");
;             else if (st == 14) asm volatile("s_waitcnt vmcnt(4)" ::: "memory");
;             else asm volatile("s_waitcnt vmcnt(0)" ::: "memory");
;             if (q == 0) {
; #pragma unroll
;                 for (int r = 0; r < 4; ++r) { accH[r] = 0; accL[r] = 0; } }
; #pragma unroll
;             for (int tp = 0; tp < 2; ++tp) {
;                 const v2i ao = TR4(ATL + (2 * q + tp) * 128 + 8 * s16), ah = TR4(ATL + 1024 + (2 * q + tp) * 128 + 8 * s16);
; #pragma unroll
;                 for (int r = 0; r < 4; ++r) {
;                     const v2i d = TR4(ldsb + BUF[st % 3] + 2048 * tp + roff[r]);
;                     accH[r] = __builtin_amdgcn_sdot8(d.x, ah.x, accH[r], false); accH[r] = __builtin_amdgcn_sdot8(d.y, ah.y, accH[r], false);
;                     accL[r] = __builtin_amdgcn_sdot8(d.x, ao.x, accL[r], false); accL[r] = __builtin_amdgcn_sdot8(d.y, ao.y, accL[r], false);
;                 }
;             }
;             asm volatile("s_waitcnt lgkmcnt(0)" ::: "memory");
;             if (q == 3) {
; #pragma unroll
;                 for (int r = 0; r < 4; ++r) STASH[256 * p + 16 * (grp + 4 * r) + pc] = f2bf(asc * (float)(2 * ((accH[r] << 4) + accL[r]) + sa));
;             }
	v_add_u32_e32 v143, 8, v139
	v_and_b32_e32 v142, 15, v143
	v_xor_b32_e32 v142, 8, v142
	v_bfe_u32 v144, v143, 4, 4
	v_mul_lo_u32 v142, v142, s92
	v_mul_lo_u32 v144, v144, s92
	v_mov_b32_e32 v143, v142
	v_mov_b32_e32 v145, v144
	ds_write2st64_b64 v159, v[142:143], v[144:145] offset1:2
	v_and_b32_e32 v78, 0xffff, v20
	v_lshrrev_b32_e32 v79, 16, v20
	v_lshl_add_u32 v78, v78, 7, v152
	v_lshl_add_u32 v79, v79, 7, v153
	s_mov_b32 m0, s76
	s_add_i32 s43, s76, 0x400
	global_load_lds_dwordx4 v78, s[50:51]
	s_mov_b32 m0, s43
	s_nop 0
	global_load_lds_dwordx4 v79, s[50:51]
	s_waitcnt vmcnt(8)
	v_add_u32_e32 v54, s78, v59
	v_add_u32_e32 v55, s78, v60
	v_add_u32_e32 v56, s78, v61
	v_add_u32_e32 v57, s78, v62
	ds_read_b64_tr_b4 v[46:47], v160 offset:768
	ds_read_b64_tr_b4 v[48:49], v160 offset:1792
	ds_read_b64_tr_b4 v[122:123], v54
	ds_read_b64_tr_b4 v[124:125], v55
	ds_read_b64_tr_b4 v[126:127], v56
	ds_read_b64_tr_b4 v[128:129], v57
	s_waitcnt lgkmcnt(7)
	v_dot8c_i32_i4_e32 v38, v130, v52
	v_dot8c_i32_i4_e32 v39, v130, v50
	v_dot8c_i32_i4_e32 v40, v132, v52
	v_dot8c_i32_i4_e32 v41, v132, v50
	v_dot8c_i32_i4_e32 v42, v134, v52
	v_dot8c_i32_i4_e32 v43, v134, v50
	v_dot8c_i32_i4_e32 v44, v136, v52
	v_dot8c_i32_i4_e32 v45, v136, v50
	v_dot8c_i32_i4_e32 v38, v131, v53
	v_dot8c_i32_i4_e32 v39, v131, v51
	v_dot8c_i32_i4_e32 v40, v133, v53
	v_dot8c_i32_i4_e32 v41, v133, v51
	v_dot8c_i32_i4_e32 v42, v135, v53
	v_dot8c_i32_i4_e32 v43, v135, v51
	v_dot8c_i32_i4_e32 v44, v137, v53
	v_dot8c_i32_i4_e32 v45, v137, v51
	v_and_b32_e32 v78, 0xffff, v21
	v_lshrrev_b32_e32 v79, 16, v21
	v_lshl_add_u32 v78, v78, 7, v152
	v_lshl_add_u32 v79, v79, 7, v153
	s_mov_b32 m0, s77
	s_add_i32 s43, s77, 0x400
	global_load_lds_dwordx4 v78, s[50:51]
	s_mov_b32 m0, s43
	s_nop 0
	global_load_lds_dwordx4 v79, s[50:51]
	s_waitcnt vmcnt(8)
	v_add_u32_e32 v54, s79, v59
	v_add_u32_e32 v55, s79, v60
	v_add_u32_e32 v56, s79, v61
	v_add_u32_e32 v57, s79, v62
	ds_read_b64_tr_b4 v[50:51], v160 offset:896
	ds_read_b64_tr_b4 v[52:53], v160 offset:1920
	ds_read_b64_tr_b4 v[130:131], v54
	ds_read_b64_tr_b4 v[132:133], v55
	ds_read_b64_tr_b4 v[134:135], v56
	ds_read_b64_tr_b4 v[136:137], v57
	s_waitcnt lgkmcnt(6)
	v_dot8c_i32_i4_e32 v38, v122, v48
	v_dot8c_i32_i4_e32 v39, v122, v46
	v_dot8c_i32_i4_e32 v40, v124, v48
	v_dot8c_i32_i4_e32 v41, v124, v46
	v_dot8c_i32_i4_e32 v42, v126, v48
	v_dot8c_i32_i4_e32 v43, v126, v46
	v_dot8c_i32_i4_e32 v44, v128, v48
	v_dot8c_i32_i4_e32 v45, v128, v46
	v_dot8c_i32_i4_e32 v38, v123, v49
	v_dot8c_i32_i4_e32 v39, v123, v47
	v_dot8c_i32_i4_e32 v40, v125, v49
	v_dot8c_i32_i4_e32 v41, v125, v47
	v_dot8c_i32_i4_e32 v42, v127, v49
	v_dot8c_i32_i4_e32 v43, v127, v47
	v_dot8c_i32_i4_e32 v44, v129, v49
	v_dot8c_i32_i4_e32 v45, v129, v47
	v_and_b32_e32 v78, 0xffff, v22
	v_lshrrev_b32_e32 v79, 16, v22
	v_lshl_add_u32 v78, v78, 7, v152
	v_lshl_add_u32 v79, v79, 7, v153
	s_mov_b32 m0, s78
	s_add_i32 s43, s78, 0x400
	global_load_lds_dwordx4 v78, s[50:51]
	s_mov_b32 m0, s43
	s_nop 0
	global_load_lds_dwordx4 v79, s[50:51]
	s_waitcnt vmcnt(8)
	v_add_u32_e32 v54, s98, v59
	v_add_u32_e32 v55, s98, v60
	v_add_u32_e32 v56, s98, v61
	v_add_u32_e32 v57, s98, v62
	ds_read_b64_tr_b4 v[46:47], v160
	ds_read_b64_tr_b4 v[48:49], v160 offset:1024
	ds_read_b64_tr_b4 v[122:123], v54
	ds_read_b64_tr_b4 v[124:125], v55
	ds_read_b64_tr_b4 v[126:127], v56
	ds_read_b64_tr_b4 v[128:129], v57
	s_waitcnt lgkmcnt(6)
	v_dot8c_i32_i4_e32 v38, v130, v52
	v_dot8c_i32_i4_e32 v39, v130, v50
	v_dot8c_i32_i4_e32 v40, v132, v52
	v_dot8c_i32_i4_e32 v41, v132, v50
	v_dot8c_i32_i4_e32 v42, v134, v52
	v_dot8c_i32_i4_e32 v43, v134, v50
	v_dot8c_i32_i4_e32 v44, v136, v52
	v_dot8c_i32_i4_e32 v45, v136, v50
	v_dot8c_i32_i4_e32 v38, v131, v53
	v_dot8c_i32_i4_e32 v39, v131, v51
	v_dot8c_i32_i4_e32 v40, v133, v53
	v_dot8c_i32_i4_e32 v41, v133, v51
	v_dot8c_i32_i4_e32 v42, v135, v53
	v_dot8c_i32_i4_e32 v43, v135, v51
	v_dot8c_i32_i4_e32 v44, v137, v53
	v_dot8c_i32_i4_e32 v45, v137, v51
	s_nop 3
	s_waitcnt lgkmcnt(15)
	v_lshlrev_b32_e32 v38, 5, v38
	v_lshlrev_b32_e32 v39, 1, v39
	v_add3_u32 v38, v39, v229, v38
	v_cvt_f32_i32_e32 v38, v38
	v_mul_f32_e32 v38, v228, v38
	v_lshlrev_b32_e32 v40, 5, v40
	v_lshlrev_b32_e32 v41, 1, v41
	v_add3_u32 v40, v41, v229, v40
	v_cvt_f32_i32_e32 v40, v40
	v_mul_f32_e32 v40, v228, v40
	v_lshlrev_b32_e32 v42, 5, v42
	v_lshlrev_b32_e32 v43, 1, v43
	v_add3_u32 v42, v43, v229, v42
	v_cvt_f32_i32_e32 v42, v42
	v_mul_f32_e32 v42, v228, v42
	v_lshlrev_b32_e32 v44, 5, v44
	v_lshlrev_b32_e32 v45, 1, v45
	v_add3_u32 v44, v45, v229, v44
	v_cvt_f32_i32_e32 v44, v44
	v_mul_f32_e32 v44, v228, v44
	v_cvt_pk_bf16_f32 v170, v38, v40
	v_cvt_pk_bf16_f32 v171, v42, v44
	v_add_u32_e32 v147, 8, v140
	v_and_b32_e32 v146, 15, v147
	v_xor_b32_e32 v146, 8, v146
	v_bfe_u32 v148, v147, 4, 4
	v_mul_lo_u32 v146, v146, s92
	v_mul_lo_u32 v148, v148, s92
	v_mov_b32_e32 v147, v146
	v_mov_b32_e32 v149, v148
	ds_write2st64_b64 v77, v[146:147], v[148:149] offset1:2
	v_add_u32_e32 v138, 0x400, v74
	ds_read_u8 v139, v138
	v_add_u32_e32 v141, 0x400, v73
	ds_read_u8 v140, v141
	s_mov_b32 s43, s67
	v_mov_b32_e32 v138, s43
	ds_read2st64_b32 v[228:229], v138 offset1:1
	ds_read_b128 v[26:29], v227 offset:2048
	ds_read_b128 v[30:33], v227 offset:2064
	v_mov_b32_e32 v38, 0
	v_mov_b32_e32 v39, 0
	v_mov_b32_e32 v40, 0
	v_mov_b32_e32 v41, 0
	v_mov_b32_e32 v42, 0
	v_mov_b32_e32 v43, 0
	v_mov_b32_e32 v44, 0
	v_mov_b32_e32 v45, 0
	v_and_b32_e32 v78, 0xffff, v23
	v_lshrrev_b32_e32 v79, 16, v23
	v_lshl_add_u32 v78, v78, 7, v152
	v_lshl_add_u32 v79, v79, 7, v153
	s_mov_b32 m0, s79
	s_add_i32 s43, s79, 0x400
	global_load_lds_dwordx4 v78, s[50:51]
	s_mov_b32 m0, s43
	s_nop 0
	global_load_lds_dwordx4 v79, s[50:51]
	s_waitcnt vmcnt(8)
; #define TR4(p_) __builtin_amdgcn_ds_read_tr4_b64_v2i32((LAS v2i*)(p_))
; #define VDMA(st_, k_) do { _Pragma("unroll") for (int i_ = 0; i_ < 4; ++i_) { \
;         const unsigned off_ = (unsigned)((st_) >> 2) * (16384u * 128u) + (PE_ID(E, 4 * ((st_) & 3) + i_) << 7) + ((i_ & 1) ? cx1 : cx0); \
;         __builtin_amdgcn_global_load_lds((const unsigned*)(V4 + off_), (LAS unsigned*)(ldsb + BUF[k_] + 1024 * i_), 16, 0, 0); } } while (0)
; __device__ __forceinline__ void peer_v_tokens(int j, const LAS unsigned short* EL, const LAS unsigned char* AL  , const LAS float* ASC  , const LAS int* SAL  , ...
;     ...
;         for (int st = 0; st < 16; ++st) {
;             const int p = st >> 2, q = st & 3;
;             if (st < 14) VDMA(st + 2, (st + 2) % 3);
;             if (st < 14) asm volatile("s_waitcnt vmcnt(8)" ::: "memory");
;             else if (st == 14) asm volatile("s_waitcnt vmcnt(4)" ::: "memory");
;             else asm volatile("s_waitcnt vmcnt(0)" ::: "memory");
;             if (q == 0) {
; #pragma unroll
;                 for (int r = 0; r < 4; ++r) { accH[r] = 0; accL[r] = 0; } }
; #pragma unroll
;             for (int tp = 0; tp < 2; ++tp) {
;                 const v2i ao = TR4(ATL + (2 * q + tp) * 128 + 8 * s16), ah = TR4(ATL + 1024 + (2 * q + tp) * 128 + 8 * s16);
; #pragma unroll
;                 for (int r = 0; r < 4; ++r) {
;                     const v2i d = TR4(ldsb + BUF[st % 3] + 2048 * tp + roff[r]);
;                     accH[r] = __builtin_amdgcn_sdot8(d.x, ah.x, accH[r], false); accH[r] = __builtin_amdgcn_sdot8(d.y, ah.y, accH[r], false);
;                     accL[r] = __builtin_amdgcn_sdot8(d.x, ao.x, accL[r], false); accL[r] = __builtin_amdgcn_sdot8(d.y, ao.y, accL[r], false);
;                 }
;             }
	v_add_u32_e32 v54, s99, v59
	v_add_u32_e32 v55, s99, v60
	v_add_u32_e32 v56, s99, v61
	v_add_u32_e32 v57, s99, v62
	ds_read_b64_tr_b4 v[50:51], v160 offset:128
	ds_read_b64_tr_b4 v[52:53], v160 offset:1152
	ds_read_b64_tr_b4 v[130:131], v54
	ds_read_b64_tr_b4 v[132:133], v55
	ds_read_b64_tr_b4 v[134:135], v56
	ds_read_b64_tr_b4 v[136:137], v57
	s_waitcnt lgkmcnt(12)
	v_dot8c_i32_i4_e32 v38, v122, v48
	v_dot8c_i32_i4_e32 v39, v122, v46
	v_dot8c_i32_i4_e32 v40, v124, v48
	v_dot8c_i32_i4_e32 v41, v124, v46
	v_dot8c_i32_i4_e32 v42, v126, v48
	v_dot8c_i32_i4_e32 v43, v126, v46
	v_dot8c_i32_i4_e32 v44, v128, v48
	v_dot8c_i32_i4_e32 v45, v128, v46
	v_dot8c_i32_i4_e32 v38, v123, v49
	v_dot8c_i32_i4_e32 v39, v123, v47
	v_dot8c_i32_i4_e32 v40, v125, v49
	v_dot8c_i32_i4_e32 v41, v125, v47
	v_dot8c_i32_i4_e32 v42, v127, v49
	v_dot8c_i32_i4_e32 v43, v127, v47
	v_dot8c_i32_i4_e32 v44, v129, v49
	v_dot8c_i32_i4_e32 v45, v129, v47
	v_and_b32_e32 v78, 0xffff, v24
	v_lshrrev_b32_e32 v79, 16, v24
	v_lshl_add_u32 v78, v78, 7, v152
	v_lshl_add_u32 v79, v79, 7, v153
	s_mov_b32 m0, s98
	s_add_i32 s43, s98, 0x400
	global_load_lds_dwordx4 v78, s[50:51]
	s_mov_b32 m0, s43
	s_nop 0
	global_load_lds_dwordx4 v79, s[50:51]
	s_waitcnt vmcnt(8)
	v_add_u32_e32 v54, s76, v59
	v_add_u32_e32 v55, s76, v60
	v_add_u32_e32 v56, s76, v61
	v_add_u32_e32 v57, s76, v62
	ds_read_b64_tr_b4 v[46:47], v160 offset:256
	ds_read_b64_tr_b4 v[48:49], v160 offset:1280
	ds_read_b64_tr_b4 v[122:123], v54
	ds_read_b64_tr_b4 v[124:125], v55
	ds_read_b64_tr_b4 v[126:127], v56
	ds_read_b64_tr_b4 v[128:129], v57
	s_waitcnt lgkmcnt(6)
	v_dot8c_i32_i4_e32 v38, v130, v52
	v_dot8c_i32_i4_e32 v39, v130, v50
	v_dot8c_i32_i4_e32 v40, v132, v52
	v_dot8c_i32_i4_e32 v41, v132, v50
	v_dot8c_i32_i4_e32 v42, v134, v52
	v_dot8c_i32_i4_e32 v43, v134, v50
	v_dot8c_i32_i4_e32 v44, v136, v52
	v_dot8c_i32_i4_e32 v45, v136, v50
	v_dot8c_i32_i4_e32 v38, v131, v53
	v_dot8c_i32_i4_e32 v39, v131, v51
	v_dot8c_i32_i4_e32 v40, v133, v53
	v_dot8c_i32_i4_e32 v41, v133, v51
	v_dot8c_i32_i4_e32 v42, v135, v53
	v_dot8c_i32_i4_e32 v43, v135, v51
	v_dot8c_i32_i4_e32 v44, v137, v53
	v_dot8c_i32_i4_e32 v45, v137, v51
	v_and_b32_e32 v78, 0xffff, v25
	v_lshrrev_b32_e32 v79, 16, v25
	v_lshl_add_u32 v78, v78, 7, v152
	v_lshl_add_u32 v79, v79, 7, v153
	s_mov_b32 m0, s99
	s_add_i32 s43, s99, 0x400
	global_load_lds_dwordx4 v78, s[50:51]
	s_mov_b32 m0, s43
	s_nop 0
	global_load_lds_dwordx4 v79, s[50:51]
	s_waitcnt vmcnt(8)
	v_add_u32_e32 v54, s77, v59
	v_add_u32_e32 v55, s77, v60
	v_add_u32_e32 v56, s77, v61
	v_add_u32_e32 v57, s77, v62
	ds_read_b64_tr_b4 v[50:51], v160 offset:384
	ds_read_b64_tr_b4 v[52:53], v160 offset:1408
	ds_read_b64_tr_b4 v[130:131], v54
	ds_read_b64_tr_b4 v[132:133], v55
	ds_read_b64_tr_b4 v[134:135], v56
	ds_read_b64_tr_b4 v[136:137], v57
	s_waitcnt lgkmcnt(6)
	v_dot8c_i32_i4_e32 v38, v122, v48
	v_dot8c_i32_i4_e32 v39, v122, v46
	v_dot8c_i32_i4_e32 v40, v124, v48
	v_dot8c_i32_i4_e32 v41, v124, v46
	v_dot8c_i32_i4_e32 v42, v126, v48
	v_dot8c_i32_i4_e32 v43, v126, v46
	v_dot8c_i32_i4_e32 v44, v128, v48
	v_dot8c_i32_i4_e32 v45, v128, v46
	v_dot8c_i32_i4_e32 v38, v123, v49
	v_dot8c_i32_i4_e32 v39, v123, v47
	v_dot8c_i32_i4_e32 v40, v125, v49
	v_dot8c_i32_i4_e32 v41, v125, v47
	v_dot8c_i32_i4_e32 v42, v127, v49
	v_dot8c_i32_i4_e32 v43, v127, v47
	v_dot8c_i32_i4_e32 v44, v129, v49
	v_dot8c_i32_i4_e32 v45, v129, v47
	s_waitcnt lgkmcnt(15)
	v_and_b32_e32 v78, 0xffff, v26
	v_lshrrev_b32_e32 v79, 16, v26
	v_lshl_add_u32 v78, v78, 7, v152
	v_lshl_add_u32 v79, v79, 7, v153
	s_mov_b32 m0, s76
	s_add_i32 s43, s76, 0x400
	global_load_lds_dwordx4 v78, s[50:51]
	s_mov_b32 m0, s43
	s_nop 0
	global_load_lds_dwordx4 v79, s[50:51]
	s_waitcnt vmcnt(8)
	v_add_u32_e32 v54, s78, v59
	v_add_u32_e32 v55, s78, v60
	v_add_u32_e32 v56, s78, v61
	v_add_u32_e32 v57, s78, v62
	ds_read_b64_tr_b4 v[46:47], v160 offset:512
	ds_read_b64_tr_b4 v[48:49], v160 offset:1536
	ds_read_b64_tr_b4 v[122:123], v54
	ds_read_b64_tr_b4 v[124:125], v55
	ds_read_b64_tr_b4 v[126:127], v56
	ds_read_b64_tr_b4 v[128:129], v57
	s_waitcnt lgkmcnt(6)
	v_dot8c_i32_i4_e32 v38, v130, v52
	v_dot8c_i32_i4_e32 v39, v130, v50
	v_dot8c_i32_i4_e32 v40, v132, v52
	v_dot8c_i32_i4_e32 v41, v132, v50
	v_dot8c_i32_i4_e32 v42, v134, v52
	v_dot8c_i32_i4_e32 v43, v134, v50
	v_dot8c_i32_i4_e32 v44, v136, v52
	v_dot8c_i32_i4_e32 v45, v136, v50
	v_dot8c_i32_i4_e32 v38, v131, v53
	v_dot8c_i32_i4_e32 v39, v131, v51
	v_dot8c_i32_i4_e32 v40, v133, v53
	v_dot8c_i32_i4_e32 v41, v133, v51
	v_dot8c_i32_i4_e32 v42, v135, v53
	v_dot8c_i32_i4_e32 v43, v135, v51
	v_dot8c_i32_i4_e32 v44, v137, v53
	v_dot8c_i32_i4_e32 v45, v137, v51
	v_and_b32_e32 v78, 0xffff, v27
	v_lshrrev_b32_e32 v79, 16, v27
	v_lshl_add_u32 v78, v78, 7, v152
	v_lshl_add_u32 v79, v79, 7, v153
	s_mov_b32 m0, s77
	s_add_i32 s43, s77, 0x400
	global_load_lds_dwordx4 v78, s[50:51]
	s_mov_b32 m0, s43
	s_nop 0
	global_load_lds_dwordx4 v79, s[50:51]
	s_waitcnt vmcnt(8)
	v_add_u32_e32 v54, s79, v59
	v_add_u32_e32 v55, s79, v60
	v_add_u32_e32 v56, s79, v61
	v_add_u32_e32 v57, s79, v62
	ds_read_b64_tr_b4 v[50:51], v160 offset:640
	ds_read_b64_tr_b4 v[52:53], v160 offset:1664
	ds_read_b64_tr_b4 v[130:131], v54
	ds_read_b64_tr_b4 v[132:133], v55
	ds_read_b64_tr_b4 v[134:135], v56
	ds_read_b64_tr_b4 v[136:137], v57
	s_waitcnt lgkmcnt(6)
	v_dot8c_i32_i4_e32 v38, v122, v48
	v_dot8c_i32_i4_e32 v39, v122, v46
	v_dot8c_i32_i4_e32 v40, v124, v48
	v_dot8c_i32_i4_e32 v41, v124, v46
	v_dot8c_i32_i4_e32 v42, v126, v48
	v_dot8c_i32_i4_e32 v43, v126, v46
	v_dot8c_i32_i4_e32 v44, v128, v48
	v_dot8c_i32_i4_e32 v45, v128, v46
	v_dot8c_i32_i4_e32 v38, v123, v49
	v_dot8c_i32_i4_e32 v39, v123, v47
	v_dot8c_i32_i4_e32 v40, v125, v49
	v_dot8c_i32_i4_e32 v41, v125, v47
	v_dot8c_i32_i4_e32 v42, v127, v49
	v_dot8c_i32_i4_e32 v43, v127, v47
	v_dot8c_i32_i4_e32 v44, v129, v49
	v_dot8c_i32_i4_e32 v45, v129, v47
	s_waitcnt lgkmcnt(15)
; #define LAS __attribute__((address_space(3)))
; __device__ __forceinline__ bf16 f2bf(float f) { return (bf16)f2bfu(f); }
; #define TR4(p_) __builtin_amdgcn_ds_read_tr4_b64_v2i32((LAS v2i*)(p_))
; __device__ __forceinline__ void peer_v_tokens(int j, const LAS unsigned short* EL, const LAS unsigned char* AL  , const LAS float* ASC  , const LAS int* SAL  , ...
;     ...
;             const unsigned lo = (((unsigned)tq & 15u) ^ 8u) * 0x11111111u, hi = ((unsigned)(tq >> 4) & 15u) * 0x11111111u;
;             typedef unsigned u2v __attribute__((ext_vector_type(2)));
;             u2v l2; l2.x = lo; l2.y = lo; u2v h2; h2.x = hi; h2.y = hi;
;             *(LAS u2v*)(ATL + 8 * idx) = l2; *(LAS u2v*)(ATL + 1024 + 8 * idx) = h2;
;     ...
;         for (int st = 0; st < 16; ++st) {
;             const int p = st >> 2, q = st & 3;
;             if (st < 14) VDMA(st + 2, (st + 2) % 3);
;             if (st < 14) asm volatile("s_waitcnt vmcnt(8)" ::: "memory");
;             else if (st == 14) asm volatile("s_waitcnt vmcnt(4)" ::: "memory");
;             else asm volatile("s_waitcnt vmcnt(0)" ::: "memory");
;             if (q == 0) {
; #pragma unroll
;                 for (int r = 0; r < 4; ++r) { accH[r] = 0; accL[r] = 0; } }
; #pragma unroll
;             for (int tp = 0; tp < 2; ++tp) {
;                 const v2i ao = TR4(ATL + (2 * q + tp) * 128 + 8 * s16), ah = TR4(ATL + 1024 + (2 * q + tp) * 128 + 8 * s16);
; #pragma unroll
;                 for (int r = 0; r < 4; ++r) {
;                     const v2i d = TR4(ldsb + BUF[st % 3] + 2048 * tp + roff[r]);
;                     accH[r] = __builtin_amdgcn_sdot8(d.x, ah.x, accH[r], false); accH[r] = __builtin_amdgcn_sdot8(d.y, ah.y, accH[r], false);
;                     accL[r] = __builtin_amdgcn_sdot8(d.x, ao.x, accL[r], false); accL[r] = __builtin_amdgcn_sdot8(d.y, ao.y, accL[r], false);
;                 }
;             }
;             asm volatile("s_waitcnt lgkmcnt(0)" ::: "memory");
;             if (q == 3) {
; #pragma unroll
;                 for (int r = 0; r < 4; ++r) STASH[256 * p + 16 * (grp + 4 * r) + pc] = f2bf(asc * (float)(2 * ((accH[r] << 4) + accL[r]) + sa));
;             }
	v_add_u32_e32 v143, 8, v139
	v_and_b32_e32 v142, 15, v143
	v_xor_b32_e32 v142, 8, v142
	v_bfe_u32 v144, v143, 4, 4
	v_mul_lo_u32 v142, v142, s92
	v_mul_lo_u32 v144, v144, s92
	v_mov_b32_e32 v143, v142
	v_mov_b32_e32 v145, v144
	ds_write2st64_b64 v159, v[142:143], v[144:145] offset1:2
	v_and_b32_e32 v78, 0xffff, v28
	v_lshrrev_b32_e32 v79, 16, v28
	v_lshl_add_u32 v78, v78, 7, v152
	v_lshl_add_u32 v79, v79, 7, v153
	s_mov_b32 m0, s78
	s_add_i32 s43, s78, 0x400
	global_load_lds_dwordx4 v78, s[50:51]
	s_mov_b32 m0, s43
	s_nop 0
	global_load_lds_dwordx4 v79, s[50:51]
	s_waitcnt vmcnt(8)
	v_add_u32_e32 v54, s98, v59
	v_add_u32_e32 v55, s98, v60
	v_add_u32_e32 v56, s98, v61
	v_add_u32_e32 v57, s98, v62
	ds_read_b64_tr_b4 v[46:47], v160 offset:768
	ds_read_b64_tr_b4 v[48:49], v160 offset:1792
	ds_read_b64_tr_b4 v[122:123], v54
	ds_read_b64_tr_b4 v[124:125], v55
	ds_read_b64_tr_b4 v[126:127], v56
	ds_read_b64_tr_b4 v[128:129], v57
	s_waitcnt lgkmcnt(7)
	v_dot8c_i32_i4_e32 v38, v130, v52
	v_dot8c_i32_i4_e32 v39, v130, v50
	v_dot8c_i32_i4_e32 v40, v132, v52
	v_dot8c_i32_i4_e32 v41, v132, v50
	v_dot8c_i32_i4_e32 v42, v134, v52
	v_dot8c_i32_i4_e32 v43, v134, v50
	v_dot8c_i32_i4_e32 v44, v136, v52
	v_dot8c_i32_i4_e32 v45, v136, v50
	v_dot8c_i32_i4_e32 v38, v131, v53
	v_dot8c_i32_i4_e32 v39, v131, v51
	v_dot8c_i32_i4_e32 v40, v133, v53
	v_dot8c_i32_i4_e32 v41, v133, v51
	v_dot8c_i32_i4_e32 v42, v135, v53
	v_dot8c_i32_i4_e32 v43, v135, v51
	v_dot8c_i32_i4_e32 v44, v137, v53
	v_dot8c_i32_i4_e32 v45, v137, v51
	v_and_b32_e32 v78, 0xffff, v29
	v_lshrrev_b32_e32 v79, 16, v29
	v_lshl_add_u32 v78, v78, 7, v152
	v_lshl_add_u32 v79, v79, 7, v153
	s_mov_b32 m0, s79
	s_add_i32 s43, s79, 0x400
	global_load_lds_dwordx4 v78, s[50:51]
	s_mov_b32 m0, s43
	s_nop 0
	global_load_lds_dwordx4 v79, s[50:51]
	s_waitcnt vmcnt(8)
	v_add_u32_e32 v54, s99, v59
	v_add_u32_e32 v55, s99, v60
	v_add_u32_e32 v56, s99, v61
	v_add_u32_e32 v57, s99, v62
	ds_read_b64_tr_b4 v[50:51], v160 offset:896
	ds_read_b64_tr_b4 v[52:53], v160 offset:1920
	ds_read_b64_tr_b4 v[130:131], v54
	ds_read_b64_tr_b4 v[132:133], v55
	ds_read_b64_tr_b4 v[134:135], v56
	ds_read_b64_tr_b4 v[136:137], v57
	s_waitcnt lgkmcnt(6)
	v_dot8c_i32_i4_e32 v38, v122, v48
	v_dot8c_i32_i4_e32 v39, v122, v46
	v_dot8c_i32_i4_e32 v40, v124, v48
	v_dot8c_i32_i4_e32 v41, v124, v46
	v_dot8c_i32_i4_e32 v42, v126, v48
	v_dot8c_i32_i4_e32 v43, v126, v46
	v_dot8c_i32_i4_e32 v44, v128, v48
	v_dot8c_i32_i4_e32 v45, v128, v46
	v_dot8c_i32_i4_e32 v38, v123, v49
	v_dot8c_i32_i4_e32 v39, v123, v47
	v_dot8c_i32_i4_e32 v40, v125, v49
	v_dot8c_i32_i4_e32 v41, v125, v47
	v_dot8c_i32_i4_e32 v42, v127, v49
	v_dot8c_i32_i4_e32 v43, v127, v47
	v_dot8c_i32_i4_e32 v44, v129, v49
	v_dot8c_i32_i4_e32 v45, v129, v47
	v_and_b32_e32 v78, 0xffff, v30
	v_lshrrev_b32_e32 v79, 16, v30
	v_lshl_add_u32 v78, v78, 7, v152
	v_lshl_add_u32 v79, v79, 7, v153
	s_mov_b32 m0, s98
	s_add_i32 s43, s98, 0x400
	global_load_lds_dwordx4 v78, s[50:51]
	s_mov_b32 m0, s43
	s_nop 0
	global_load_lds_dwordx4 v79, s[50:51]
	s_waitcnt vmcnt(8)
	v_add_u32_e32 v54, s76, v59
	v_add_u32_e32 v55, s76, v60
	v_add_u32_e32 v56, s76, v61
	v_add_u32_e32 v57, s76, v62
	ds_read_b64_tr_b4 v[46:47], v160
	ds_read_b64_tr_b4 v[48:49], v160 offset:1024
	ds_read_b64_tr_b4 v[122:123], v54
	ds_read_b64_tr_b4 v[124:125], v55
	ds_read_b64_tr_b4 v[126:127], v56
	ds_read_b64_tr_b4 v[128:129], v57
	s_waitcnt lgkmcnt(6)
	v_dot8c_i32_i4_e32 v38, v130, v52
	v_dot8c_i32_i4_e32 v39, v130, v50
	v_dot8c_i32_i4_e32 v40, v132, v52
	v_dot8c_i32_i4_e32 v41, v132, v50
	v_dot8c_i32_i4_e32 v42, v134, v52
	v_dot8c_i32_i4_e32 v43, v134, v50
	v_dot8c_i32_i4_e32 v44, v136, v52
	v_dot8c_i32_i4_e32 v45, v136, v50
	v_dot8c_i32_i4_e32 v38, v131, v53
	v_dot8c_i32_i4_e32 v39, v131, v51
	v_dot8c_i32_i4_e32 v40, v133, v53
	v_dot8c_i32_i4_e32 v41, v133, v51
	v_dot8c_i32_i4_e32 v42, v135, v53
	v_dot8c_i32_i4_e32 v43, v135, v51
	v_dot8c_i32_i4_e32 v44, v137, v53
	v_dot8c_i32_i4_e32 v45, v137, v51
	s_nop 3
	s_waitcnt lgkmcnt(15)
	v_lshlrev_b32_e32 v38, 5, v38
	v_lshlrev_b32_e32 v39, 1, v39
	v_add3_u32 v38, v39, v229, v38
	v_cvt_f32_i32_e32 v38, v38
	v_mul_f32_e32 v38, v228, v38
	v_lshlrev_b32_e32 v40, 5, v40
	v_lshlrev_b32_e32 v41, 1, v41
	v_add3_u32 v40, v41, v229, v40
	v_cvt_f32_i32_e32 v40, v40
	v_mul_f32_e32 v40, v228, v40
	v_lshlrev_b32_e32 v42, 5, v42
	v_lshlrev_b32_e32 v43, 1, v43
	v_add3_u32 v42, v43, v229, v42
	v_cvt_f32_i32_e32 v42, v42
	v_mul_f32_e32 v42, v228, v42
	v_lshlrev_b32_e32 v44, 5, v44
	v_lshlrev_b32_e32 v45, 1, v45
	v_add3_u32 v44, v45, v229, v44
	v_cvt_f32_i32_e32 v44, v44
	v_mul_f32_e32 v44, v228, v44
	v_cvt_pk_bf16_f32 v164, v38, v40
	v_cvt_pk_bf16_f32 v165, v42, v44
	v_add_u32_e32 v147, 8, v140
	v_and_b32_e32 v146, 15, v147
	v_xor_b32_e32 v146, 8, v146
	v_bfe_u32 v148, v147, 4, 4
	v_mul_lo_u32 v146, v146, s92
	v_mul_lo_u32 v148, v148, s92
	v_mov_b32_e32 v147, v146
	v_mov_b32_e32 v149, v148
	ds_write2st64_b64 v77, v[146:147], v[148:149] offset1:2
	v_mov_b32_e32 v138, v74
	ds_read_u8 v139, v138
	v_mov_b32_e32 v141, v73
	ds_read_u8 v140, v141
	s_add_i32 s43, s67, 32
	v_mov_b32_e32 v138, s43
	ds_read2st64_b32 v[228:229], v138 offset1:1
	ds_read_b128 v[18:21], v227
	ds_read_b128 v[22:25], v227 offset:16
	v_add_u32_e32 v150, 0x400000, v63
	v_add_u32_e32 v151, 0x400000, v64
	v_mov_b32_e32 v38, 0
	v_mov_b32_e32 v39, 0
	v_mov_b32_e32 v40, 0
	v_mov_b32_e32 v41, 0
	v_mov_b32_e32 v42, 0
	v_mov_b32_e32 v43, 0
	v_mov_b32_e32 v44, 0
	v_mov_b32_e32 v45, 0
	v_and_b32_e32 v78, 0xffff, v31
	v_lshrrev_b32_e32 v79, 16, v31
	v_lshl_add_u32 v78, v78, 7, v152
	v_lshl_add_u32 v79, v79, 7, v153
	s_mov_b32 m0, s99
	s_add_i32 s43, s99, 0x400
	global_load_lds_dwordx4 v78, s[50:51]
	s_mov_b32 m0, s43
	s_nop 0
	global_load_lds_dwordx4 v79, s[50:51]
	s_waitcnt vmcnt(8)
; #define TR4(p_) __builtin_amdgcn_ds_read_tr4_b64_v2i32((LAS v2i*)(p_))
; #define VDMA(st_, k_) do { _Pragma("unroll") for (int i_ = 0; i_ < 4; ++i_) { \
;         const unsigned off_ = (unsigned)((st_) >> 2) * (16384u * 128u) + (PE_ID(E, 4 * ((st_) & 3) + i_) << 7) + ((i_ & 1) ? cx1 : cx0); \
;         __builtin_amdgcn_global_load_lds((const unsigned*)(V4 + off_), (LAS unsigned*)(ldsb + BUF[k_] + 1024 * i_), 16, 0, 0); } } while (0)
; __device__ __forceinline__ void peer_v_tokens(int j, const LAS unsigned short* EL, const LAS unsigned char* AL  , const LAS float* ASC  , const LAS int* SAL  , ...
;     ...
;         for (int st = 0; st < 16; ++st) {
;             const int p = st >> 2, q = st & 3;
;             if (st < 14) VDMA(st + 2, (st + 2) % 3);
;             if (st < 14) asm volatile("s_waitcnt vmcnt(8)" ::: "memory");
;             else if (st == 14) asm volatile("s_waitcnt vmcnt(4)" ::: "memory");
;             else asm volatile("s_waitcnt vmcnt(0)" ::: "memory");
;             if (q == 0) {
; #pragma unroll
;                 for (int r = 0; r < 4; ++r) { accH[r] = 0; accL[r] = 0; } }
; #pragma unroll
;             for (int tp = 0; tp < 2; ++tp) {
;                 const v2i ao = TR4(ATL + (2 * q + tp) * 128 + 8 * s16), ah = TR4(ATL + 1024 + (2 * q + tp) * 128 + 8 * s16);
; #pragma unroll
;                 for (int r = 0; r < 4; ++r) {
;                     const v2i d = TR4(ldsb + BUF[st % 3] + 2048 * tp + roff[r]);
;                     accH[r] = __builtin_amdgcn_sdot8(d.x, ah.x, accH[r], false); accH[r] = __builtin_amdgcn_sdot8(d.y, ah.y, accH[r], false);
;                     accL[r] = __builtin_amdgcn_sdot8(d.x, ao.x, accL[r], false); accL[r] = __builtin_amdgcn_sdot8(d.y, ao.y, accL[r], false);
;                 }
;             }
	v_add_u32_e32 v54, s77, v59
	v_add_u32_e32 v55, s77, v60
	v_add_u32_e32 v56, s77, v61
	v_add_u32_e32 v57, s77, v62
	ds_read_b64_tr_b4 v[50:51], v160 offset:128
	ds_read_b64_tr_b4 v[52:53], v160 offset:1152
	ds_read_b64_tr_b4 v[130:131], v54
	ds_read_b64_tr_b4 v[132:133], v55
	ds_read_b64_tr_b4 v[134:135], v56
	ds_read_b64_tr_b4 v[136:137], v57
	s_waitcnt lgkmcnt(12)
	v_dot8c_i32_i4_e32 v38, v122, v48
	v_dot8c_i32_i4_e32 v39, v122, v46
	v_dot8c_i32_i4_e32 v40, v124, v48
	v_dot8c_i32_i4_e32 v41, v124, v46
	v_dot8c_i32_i4_e32 v42, v126, v48
	v_dot8c_i32_i4_e32 v43, v126, v46
	v_dot8c_i32_i4_e32 v44, v128, v48
	v_dot8c_i32_i4_e32 v45, v128, v46
	v_dot8c_i32_i4_e32 v38, v123, v49
	v_dot8c_i32_i4_e32 v39, v123, v47
	v_dot8c_i32_i4_e32 v40, v125, v49
	v_dot8c_i32_i4_e32 v41, v125, v47
	v_dot8c_i32_i4_e32 v42, v127, v49
	v_dot8c_i32_i4_e32 v43, v127, v47
	v_dot8c_i32_i4_e32 v44, v129, v49
	v_dot8c_i32_i4_e32 v45, v129, v47
	v_and_b32_e32 v78, 0xffff, v32
	v_lshrrev_b32_e32 v79, 16, v32
	v_lshl_add_u32 v78, v78, 7, v152
	v_lshl_add_u32 v79, v79, 7, v153
	s_mov_b32 m0, s76
	s_add_i32 s43, s76, 0x400
	global_load_lds_dwordx4 v78, s[50:51]
	s_mov_b32 m0, s43
	s_nop 0
	global_load_lds_dwordx4 v79, s[50:51]
	s_waitcnt vmcnt(8)
	v_add_u32_e32 v54, s78, v59
	v_add_u32_e32 v55, s78, v60
	v_add_u32_e32 v56, s78, v61
	v_add_u32_e32 v57, s78, v62
	ds_read_b64_tr_b4 v[46:47], v160 offset:256
	ds_read_b64_tr_b4 v[48:49], v160 offset:1280
	ds_read_b64_tr_b4 v[122:123], v54
	ds_read_b64_tr_b4 v[124:125], v55
	ds_read_b64_tr_b4 v[126:127], v56
	ds_read_b64_tr_b4 v[128:129], v57
	s_waitcnt lgkmcnt(6)
	v_dot8c_i32_i4_e32 v38, v130, v52
	v_dot8c_i32_i4_e32 v39, v130, v50
	v_dot8c_i32_i4_e32 v40, v132, v52
	v_dot8c_i32_i4_e32 v41, v132, v50
	v_dot8c_i32_i4_e32 v42, v134, v52
	v_dot8c_i32_i4_e32 v43, v134, v50
	v_dot8c_i32_i4_e32 v44, v136, v52
	v_dot8c_i32_i4_e32 v45, v136, v50
	v_dot8c_i32_i4_e32 v38, v131, v53
	v_dot8c_i32_i4_e32 v39, v131, v51
	v_dot8c_i32_i4_e32 v40, v133, v53
	v_dot8c_i32_i4_e32 v41, v133, v51
	v_dot8c_i32_i4_e32 v42, v135, v53
	v_dot8c_i32_i4_e32 v43, v135, v51
	v_dot8c_i32_i4_e32 v44, v137, v53
	v_dot8c_i32_i4_e32 v45, v137, v51
	v_and_b32_e32 v78, 0xffff, v33
	v_lshrrev_b32_e32 v79, 16, v33
	v_lshl_add_u32 v78, v78, 7, v152
	v_lshl_add_u32 v79, v79, 7, v153
	s_mov_b32 m0, s77
	s_add_i32 s43, s77, 0x400
	global_load_lds_dwordx4 v78, s[50:51]
	s_mov_b32 m0, s43
	s_nop 0
	global_load_lds_dwordx4 v79, s[50:51]
	s_waitcnt vmcnt(8)
	v_add_u32_e32 v54, s79, v59
	v_add_u32_e32 v55, s79, v60
	v_add_u32_e32 v56, s79, v61
	v_add_u32_e32 v57, s79, v62
	ds_read_b64_tr_b4 v[50:51], v160 offset:384
	ds_read_b64_tr_b4 v[52:53], v160 offset:1408
	ds_read_b64_tr_b4 v[130:131], v54
	ds_read_b64_tr_b4 v[132:133], v55
	ds_read_b64_tr_b4 v[134:135], v56
	ds_read_b64_tr_b4 v[136:137], v57
	s_waitcnt lgkmcnt(6)
	v_dot8c_i32_i4_e32 v38, v122, v48
	v_dot8c_i32_i4_e32 v39, v122, v46
	v_dot8c_i32_i4_e32 v40, v124, v48
	v_dot8c_i32_i4_e32 v41, v124, v46
	v_dot8c_i32_i4_e32 v42, v126, v48
	v_dot8c_i32_i4_e32 v43, v126, v46
	v_dot8c_i32_i4_e32 v44, v128, v48
	v_dot8c_i32_i4_e32 v45, v128, v46
	v_dot8c_i32_i4_e32 v38, v123, v49
	v_dot8c_i32_i4_e32 v39, v123, v47
	v_dot8c_i32_i4_e32 v40, v125, v49
	v_dot8c_i32_i4_e32 v41, v125, v47
	v_dot8c_i32_i4_e32 v42, v127, v49
	v_dot8c_i32_i4_e32 v43, v127, v47
	v_dot8c_i32_i4_e32 v44, v129, v49
	v_dot8c_i32_i4_e32 v45, v129, v47
	s_waitcnt lgkmcnt(15)
	v_and_b32_e32 v78, 0xffff, v18
	v_lshrrev_b32_e32 v79, 16, v18
	v_lshl_add_u32 v78, v78, 7, v150
	v_lshl_add_u32 v79, v79, 7, v151
	s_mov_b32 m0, s78
	s_add_i32 s43, s78, 0x400
	global_load_lds_dwordx4 v78, s[50:51]
	s_mov_b32 m0, s43
	s_nop 0
	global_load_lds_dwordx4 v79, s[50:51]
	s_waitcnt vmcnt(8)
	v_add_u32_e32 v54, s98, v59
	v_add_u32_e32 v55, s98, v60
	v_add_u32_e32 v56, s98, v61
	v_add_u32_e32 v57, s98, v62
	ds_read_b64_tr_b4 v[46:47], v160 offset:512
	ds_read_b64_tr_b4 v[48:49], v160 offset:1536
	ds_read_b64_tr_b4 v[122:123], v54
	ds_read_b64_tr_b4 v[124:125], v55
	ds_read_b64_tr_b4 v[126:127], v56
	ds_read_b64_tr_b4 v[128:129], v57
	s_waitcnt lgkmcnt(6)
	v_dot8c_i32_i4_e32 v38, v130, v52
	v_dot8c_i32_i4_e32 v39, v130, v50
	v_dot8c_i32_i4_e32 v40, v132, v52
	v_dot8c_i32_i4_e32 v41, v132, v50
	v_dot8c_i32_i4_e32 v42, v134, v52
	v_dot8c_i32_i4_e32 v43, v134, v50
	v_dot8c_i32_i4_e32 v44, v136, v52
	v_dot8c_i32_i4_e32 v45, v136, v50
	v_dot8c_i32_i4_e32 v38, v131, v53
	v_dot8c_i32_i4_e32 v39, v131, v51
	v_dot8c_i32_i4_e32 v40, v133, v53
	v_dot8c_i32_i4_e32 v41, v133, v51
	v_dot8c_i32_i4_e32 v42, v135, v53
	v_dot8c_i32_i4_e32 v43, v135, v51
	v_dot8c_i32_i4_e32 v44, v137, v53
	v_dot8c_i32_i4_e32 v45, v137, v51
	v_and_b32_e32 v78, 0xffff, v19
	v_lshrrev_b32_e32 v79, 16, v19
	v_lshl_add_u32 v78, v78, 7, v150
	v_lshl_add_u32 v79, v79, 7, v151
	s_mov_b32 m0, s79
	s_add_i32 s43, s79, 0x400
	global_load_lds_dwordx4 v78, s[50:51]
	s_mov_b32 m0, s43
	s_nop 0
	global_load_lds_dwordx4 v79, s[50:51]
	s_waitcnt vmcnt(8)
	v_add_u32_e32 v54, s99, v59
	v_add_u32_e32 v55, s99, v60
	v_add_u32_e32 v56, s99, v61
	v_add_u32_e32 v57, s99, v62
	ds_read_b64_tr_b4 v[50:51], v160 offset:640
	ds_read_b64_tr_b4 v[52:53], v160 offset:1664
	ds_read_b64_tr_b4 v[130:131], v54
	ds_read_b64_tr_b4 v[132:133], v55
	ds_read_b64_tr_b4 v[134:135], v56
	ds_read_b64_tr_b4 v[136:137], v57
	s_waitcnt lgkmcnt(6)
	v_dot8c_i32_i4_e32 v38, v122, v48
	v_dot8c_i32_i4_e32 v39, v122, v46
	v_dot8c_i32_i4_e32 v40, v124, v48
	v_dot8c_i32_i4_e32 v41, v124, v46
	v_dot8c_i32_i4_e32 v42, v126, v48
	v_dot8c_i32_i4_e32 v43, v126, v46
	v_dot8c_i32_i4_e32 v44, v128, v48
	v_dot8c_i32_i4_e32 v45, v128, v46
	v_dot8c_i32_i4_e32 v38, v123, v49
	v_dot8c_i32_i4_e32 v39, v123, v47
	v_dot8c_i32_i4_e32 v40, v125, v49
	v_dot8c_i32_i4_e32 v41, v125, v47
	v_dot8c_i32_i4_e32 v42, v127, v49
	v_dot8c_i32_i4_e32 v43, v127, v47
	v_dot8c_i32_i4_e32 v44, v129, v49
	v_dot8c_i32_i4_e32 v45, v129, v47
	s_waitcnt lgkmcnt(15)
; #define LAS __attribute__((address_space(3)))
; __device__ __forceinline__ bf16 f2bf(float f) { return (bf16)f2bfu(f); }
; #define TR4(p_) __builtin_amdgcn_ds_read_tr4_b64_v2i32((LAS v2i*)(p_))
; __device__ __forceinline__ void peer_v_tokens(int j, const LAS unsigned short* EL, const LAS unsigned char* AL  , const LAS float* ASC  , const LAS int* SAL  , ...
;     ...
;             const unsigned lo = (((unsigned)tq & 15u) ^ 8u) * 0x11111111u, hi = ((unsigned)(tq >> 4) & 15u) * 0x11111111u;
;             typedef unsigned u2v __attribute__((ext_vector_type(2)));
;             u2v l2; l2.x = lo; l2.y = lo; u2v h2; h2.x = hi; h2.y = hi;
;             *(LAS u2v*)(ATL + 8 * idx) = l2; *(LAS u2v*)(ATL + 1024 + 8 * idx) = h2;
;     ...
;         for (int st = 0; st < 16; ++st) {
;             const int p = st >> 2, q = st & 3;
;             if (st < 14) VDMA(st + 2, (st + 2) % 3);
;             if (st < 14) asm volatile("s_waitcnt vmcnt(8)" ::: "memory");
;             else if (st == 14) asm volatile("s_waitcnt vmcnt(4)" ::: "memory");
;             else asm volatile("s_waitcnt vmcnt(0)" ::: "memory");
;             if (q == 0) {
; #pragma unroll
;                 for (int r = 0; r < 4; ++r) { accH[r] = 0; accL[r] = 0; } }
; #pragma unroll
;             for (int tp = 0; tp < 2; ++tp) {
;                 const v2i ao = TR4(ATL + (2 * q + tp) * 128 + 8 * s16), ah = TR4(ATL + 1024 + (2 * q + tp) * 128 + 8 * s16);
; #pragma unroll
;                 for (int r = 0; r < 4; ++r) {
;                     const v2i d = TR4(ldsb + BUF[st % 3] + 2048 * tp + roff[r]);
;                     accH[r] = __builtin_amdgcn_sdot8(d.x, ah.x, accH[r], false); accH[r] = __builtin_amdgcn_sdot8(d.y, ah.y, accH[r], false);
;                     accL[r] = __builtin_amdgcn_sdot8(d.x, ao.x, accL[r], false); accL[r] = __builtin_amdgcn_sdot8(d.y, ao.y, accL[r], false);
;                 }
;             }
;             asm volatile("s_waitcnt lgkmcnt(0)" ::: "memory");
;             if (q == 3) {
; #pragma unroll
;                 for (int r = 0; r < 4; ++r) STASH[256 * p + 16 * (grp + 4 * r) + pc] = f2bf(asc * (float)(2 * ((accH[r] << 4) + accL[r]) + sa));
;             }
	v_add_u32_e32 v143, 8, v139
	v_and_b32_e32 v142, 15, v143
	v_xor_b32_e32 v142, 8, v142
	v_bfe_u32 v144, v143, 4, 4
	v_mul_lo_u32 v142, v142, s92
	v_mul_lo_u32 v144, v144, s92
	v_mov_b32_e32 v143, v142
	v_mov_b32_e32 v145, v144
	ds_write2st64_b64 v159, v[142:143], v[144:145] offset1:2
	v_and_b32_e32 v78, 0xffff, v20
	v_lshrrev_b32_e32 v79, 16, v20
	v_lshl_add_u32 v78, v78, 7, v150
	v_lshl_add_u32 v79, v79, 7, v151
	s_mov_b32 m0, s98
	s_add_i32 s43, s98, 0x400
	global_load_lds_dwordx4 v78, s[50:51]
	s_mov_b32 m0, s43
	s_nop 0
	global_load_lds_dwordx4 v79, s[50:51]
	s_waitcnt vmcnt(8)
	v_add_u32_e32 v54, s76, v59
	v_add_u32_e32 v55, s76, v60
	v_add_u32_e32 v56, s76, v61
	v_add_u32_e32 v57, s76, v62
	ds_read_b64_tr_b4 v[46:47], v160 offset:768
	ds_read_b64_tr_b4 v[48:49], v160 offset:1792
	ds_read_b64_tr_b4 v[122:123], v54
	ds_read_b64_tr_b4 v[124:125], v55
	ds_read_b64_tr_b4 v[126:127], v56
	ds_read_b64_tr_b4 v[128:129], v57
	s_waitcnt lgkmcnt(7)
	v_dot8c_i32_i4_e32 v38, v130, v52
	v_dot8c_i32_i4_e32 v39, v130, v50
	v_dot8c_i32_i4_e32 v40, v132, v52
	v_dot8c_i32_i4_e32 v41, v132, v50
	v_dot8c_i32_i4_e32 v42, v134, v52
	v_dot8c_i32_i4_e32 v43, v134, v50
	v_dot8c_i32_i4_e32 v44, v136, v52
	v_dot8c_i32_i4_e32 v45, v136, v50
	v_dot8c_i32_i4_e32 v38, v131, v53
	v_dot8c_i32_i4_e32 v39, v131, v51
	v_dot8c_i32_i4_e32 v40, v133, v53
	v_dot8c_i32_i4_e32 v41, v133, v51
	v_dot8c_i32_i4_e32 v42, v135, v53
	v_dot8c_i32_i4_e32 v43, v135, v51
	v_dot8c_i32_i4_e32 v44, v137, v53
	v_dot8c_i32_i4_e32 v45, v137, v51
	v_and_b32_e32 v78, 0xffff, v21
	v_lshrrev_b32_e32 v79, 16, v21
	v_lshl_add_u32 v78, v78, 7, v150
	v_lshl_add_u32 v79, v79, 7, v151
	s_mov_b32 m0, s99
	s_add_i32 s43, s99, 0x400
	global_load_lds_dwordx4 v78, s[50:51]
	s_mov_b32 m0, s43
	s_nop 0
	global_load_lds_dwordx4 v79, s[50:51]
	s_waitcnt vmcnt(8)
	v_add_u32_e32 v54, s77, v59
	v_add_u32_e32 v55, s77, v60
	v_add_u32_e32 v56, s77, v61
	v_add_u32_e32 v57, s77, v62
	ds_read_b64_tr_b4 v[50:51], v160 offset:896
	ds_read_b64_tr_b4 v[52:53], v160 offset:1920
	ds_read_b64_tr_b4 v[130:131], v54
	ds_read_b64_tr_b4 v[132:133], v55
	ds_read_b64_tr_b4 v[134:135], v56
	ds_read_b64_tr_b4 v[136:137], v57
	s_waitcnt lgkmcnt(6)
	v_dot8c_i32_i4_e32 v38, v122, v48
	v_dot8c_i32_i4_e32 v39, v122, v46
	v_dot8c_i32_i4_e32 v40, v124, v48
	v_dot8c_i32_i4_e32 v41, v124, v46
	v_dot8c_i32_i4_e32 v42, v126, v48
	v_dot8c_i32_i4_e32 v43, v126, v46
	v_dot8c_i32_i4_e32 v44, v128, v48
	v_dot8c_i32_i4_e32 v45, v128, v46
	v_dot8c_i32_i4_e32 v38, v123, v49
	v_dot8c_i32_i4_e32 v39, v123, v47
	v_dot8c_i32_i4_e32 v40, v125, v49
	v_dot8c_i32_i4_e32 v41, v125, v47
	v_dot8c_i32_i4_e32 v42, v127, v49
	v_dot8c_i32_i4_e32 v43, v127, v47
	v_dot8c_i32_i4_e32 v44, v129, v49
	v_dot8c_i32_i4_e32 v45, v129, v47
	v_and_b32_e32 v78, 0xffff, v22
	v_lshrrev_b32_e32 v79, 16, v22
	v_lshl_add_u32 v78, v78, 7, v150
	v_lshl_add_u32 v79, v79, 7, v151
	s_mov_b32 m0, s76
	s_add_i32 s43, s76, 0x400
	global_load_lds_dwordx4 v78, s[50:51]
	s_mov_b32 m0, s43
	s_nop 0
	global_load_lds_dwordx4 v79, s[50:51]
	s_waitcnt vmcnt(8)
	v_add_u32_e32 v54, s78, v59
	v_add_u32_e32 v55, s78, v60
	v_add_u32_e32 v56, s78, v61
	v_add_u32_e32 v57, s78, v62
	ds_read_b64_tr_b4 v[46:47], v160
	ds_read_b64_tr_b4 v[48:49], v160 offset:1024
	ds_read_b64_tr_b4 v[122:123], v54
	ds_read_b64_tr_b4 v[124:125], v55
	ds_read_b64_tr_b4 v[126:127], v56
	ds_read_b64_tr_b4 v[128:129], v57
	s_waitcnt lgkmcnt(6)
	v_dot8c_i32_i4_e32 v38, v130, v52
	v_dot8c_i32_i4_e32 v39, v130, v50
	v_dot8c_i32_i4_e32 v40, v132, v52
	v_dot8c_i32_i4_e32 v41, v132, v50
	v_dot8c_i32_i4_e32 v42, v134, v52
	v_dot8c_i32_i4_e32 v43, v134, v50
	v_dot8c_i32_i4_e32 v44, v136, v52
	v_dot8c_i32_i4_e32 v45, v136, v50
	v_dot8c_i32_i4_e32 v38, v131, v53
	v_dot8c_i32_i4_e32 v39, v131, v51
	v_dot8c_i32_i4_e32 v40, v133, v53
	v_dot8c_i32_i4_e32 v41, v133, v51
	v_dot8c_i32_i4_e32 v42, v135, v53
	v_dot8c_i32_i4_e32 v43, v135, v51
	v_dot8c_i32_i4_e32 v44, v137, v53
	v_dot8c_i32_i4_e32 v45, v137, v51
	s_nop 3
	s_waitcnt lgkmcnt(15)
	v_lshlrev_b32_e32 v38, 5, v38
	v_lshlrev_b32_e32 v39, 1, v39
	v_add3_u32 v38, v39, v229, v38
	v_cvt_f32_i32_e32 v38, v38
	v_mul_f32_e32 v38, v228, v38
	v_lshlrev_b32_e32 v40, 5, v40
	v_lshlrev_b32_e32 v41, 1, v41
	v_add3_u32 v40, v41, v229, v40
	v_cvt_f32_i32_e32 v40, v40
	v_mul_f32_e32 v40, v228, v40
	v_lshlrev_b32_e32 v42, 5, v42
	v_lshlrev_b32_e32 v43, 1, v43
	v_add3_u32 v42, v43, v229, v42
	v_cvt_f32_i32_e32 v42, v42
	v_mul_f32_e32 v42, v228, v42
	v_lshlrev_b32_e32 v44, 5, v44
	v_lshlrev_b32_e32 v45, 1, v45
	v_add3_u32 v44, v45, v229, v44
	v_cvt_f32_i32_e32 v44, v44
	v_mul_f32_e32 v44, v228, v44
	v_cvt_pk_bf16_f32 v172, v38, v40
	v_cvt_pk_bf16_f32 v173, v42, v44
	v_add_u32_e32 v147, 8, v140
	v_and_b32_e32 v146, 15, v147
	v_xor_b32_e32 v146, 8, v146
	v_bfe_u32 v148, v147, 4, 4
	v_mul_lo_u32 v146, v146, s92
	v_mul_lo_u32 v148, v148, s92
	v_mov_b32_e32 v147, v146
	v_mov_b32_e32 v149, v148
	ds_write2st64_b64 v77, v[146:147], v[148:149] offset1:2
	v_add_u32_e32 v138, 0x400, v74
	ds_read_u8 v139, v138
	v_add_u32_e32 v141, 0x400, v73
	ds_read_u8 v140, v141
	s_mov_b32 s43, s67
	v_mov_b32_e32 v138, s43
	ds_read2st64_b32 v[228:229], v138 offset1:1
	ds_read_b128 v[26:29], v227 offset:2048
	ds_read_b128 v[30:33], v227 offset:2064
	v_mov_b32_e32 v38, 0
	v_mov_b32_e32 v39, 0
	v_mov_b32_e32 v40, 0
	v_mov_b32_e32 v41, 0
	v_mov_b32_e32 v42, 0
	v_mov_b32_e32 v43, 0
	v_mov_b32_e32 v44, 0
	v_mov_b32_e32 v45, 0
	v_and_b32_e32 v78, 0xffff, v23
	v_lshrrev_b32_e32 v79, 16, v23
	v_lshl_add_u32 v78, v78, 7, v150
	v_lshl_add_u32 v79, v79, 7, v151
	s_mov_b32 m0, s77
	s_add_i32 s43, s77, 0x400
	global_load_lds_dwordx4 v78, s[50:51]
	s_mov_b32 m0, s43
	s_nop 0
	global_load_lds_dwordx4 v79, s[50:51]
	s_waitcnt vmcnt(8)
; #define TR4(p_) __builtin_amdgcn_ds_read_tr4_b64_v2i32((LAS v2i*)(p_))
; #define VDMA(st_, k_) do { _Pragma("unroll") for (int i_ = 0; i_ < 4; ++i_) { \
;         const unsigned off_ = (unsigned)((st_) >> 2) * (16384u * 128u) + (PE_ID(E, 4 * ((st_) & 3) + i_) << 7) + ((i_ & 1) ? cx1 : cx0); \
;         __builtin_amdgcn_global_load_lds((const unsigned*)(V4 + off_), (LAS unsigned*)(ldsb + BUF[k_] + 1024 * i_), 16, 0, 0); } } while (0)
; __device__ __forceinline__ void peer_v_tokens(int j, const LAS unsigned short* EL, const LAS unsigned char* AL  , const LAS float* ASC  , const LAS int* SAL  , ...
;     ...
;         for (int st = 0; st < 16; ++st) {
;             const int p = st >> 2, q = st & 3;
;             if (st < 14) VDMA(st + 2, (st + 2) % 3);
;             if (st < 14) asm volatile("s_waitcnt vmcnt(8)" ::: "memory");
;             else if (st == 14) asm volatile("s_waitcnt vmcnt(4)" ::: "memory");
;             else asm volatile("s_waitcnt vmcnt(0)" ::: "memory");
;             if (q == 0) {
; #pragma unroll
;                 for (int r = 0; r < 4; ++r) { accH[r] = 0; accL[r] = 0; } }
; #pragma unroll
;             for (int tp = 0; tp < 2; ++tp) {
;                 const v2i ao = TR4(ATL + (2 * q + tp) * 128 + 8 * s16), ah = TR4(ATL + 1024 + (2 * q + tp) * 128 + 8 * s16);
; #pragma unroll
;                 for (int r = 0; r < 4; ++r) {
;                     const v2i d = TR4(ldsb + BUF[st % 3] + 2048 * tp + roff[r]);
;                     accH[r] = __builtin_amdgcn_sdot8(d.x, ah.x, accH[r], false); accH[r] = __builtin_amdgcn_sdot8(d.y, ah.y, accH[r], false);
;                     accL[r] = __builtin_amdgcn_sdot8(d.x, ao.x, accL[r], false); accL[r] = __builtin_amdgcn_sdot8(d.y, ao.y, accL[r], false);
;                 }
;             }
	v_add_u32_e32 v54, s79, v59
	v_add_u32_e32 v55, s79, v60
	v_add_u32_e32 v56, s79, v61
	v_add_u32_e32 v57, s79, v62
	ds_read_b64_tr_b4 v[50:51], v160 offset:128
	ds_read_b64_tr_b4 v[52:53], v160 offset:1152
	ds_read_b64_tr_b4 v[130:131], v54
	ds_read_b64_tr_b4 v[132:133], v55
	ds_read_b64_tr_b4 v[134:135], v56
	ds_read_b64_tr_b4 v[136:137], v57
	s_waitcnt lgkmcnt(12)
	v_dot8c_i32_i4_e32 v38, v122, v48
	v_dot8c_i32_i4_e32 v39, v122, v46
	v_dot8c_i32_i4_e32 v40, v124, v48
	v_dot8c_i32_i4_e32 v41, v124, v46
	v_dot8c_i32_i4_e32 v42, v126, v48
	v_dot8c_i32_i4_e32 v43, v126, v46
	v_dot8c_i32_i4_e32 v44, v128, v48
	v_dot8c_i32_i4_e32 v45, v128, v46
	v_dot8c_i32_i4_e32 v38, v123, v49
	v_dot8c_i32_i4_e32 v39, v123, v47
	v_dot8c_i32_i4_e32 v40, v125, v49
	v_dot8c_i32_i4_e32 v41, v125, v47
	v_dot8c_i32_i4_e32 v42, v127, v49
	v_dot8c_i32_i4_e32 v43, v127, v47
	v_dot8c_i32_i4_e32 v44, v129, v49
	v_dot8c_i32_i4_e32 v45, v129, v47
	v_and_b32_e32 v78, 0xffff, v24
	v_lshrrev_b32_e32 v79, 16, v24
	v_lshl_add_u32 v78, v78, 7, v150
	v_lshl_add_u32 v79, v79, 7, v151
	s_mov_b32 m0, s78
	s_add_i32 s43, s78, 0x400
	global_load_lds_dwordx4 v78, s[50:51]
	s_mov_b32 m0, s43
	s_nop 0
	global_load_lds_dwordx4 v79, s[50:51]
	s_waitcnt vmcnt(8)
	v_add_u32_e32 v54, s98, v59
	v_add_u32_e32 v55, s98, v60
	v_add_u32_e32 v56, s98, v61
	v_add_u32_e32 v57, s98, v62
	ds_read_b64_tr_b4 v[46:47], v160 offset:256
	ds_read_b64_tr_b4 v[48:49], v160 offset:1280
	ds_read_b64_tr_b4 v[122:123], v54
	ds_read_b64_tr_b4 v[124:125], v55
	ds_read_b64_tr_b4 v[126:127], v56
	ds_read_b64_tr_b4 v[128:129], v57
	s_waitcnt lgkmcnt(6)
	v_dot8c_i32_i4_e32 v38, v130, v52
	v_dot8c_i32_i4_e32 v39, v130, v50
	v_dot8c_i32_i4_e32 v40, v132, v52
	v_dot8c_i32_i4_e32 v41, v132, v50
	v_dot8c_i32_i4_e32 v42, v134, v52
	v_dot8c_i32_i4_e32 v43, v134, v50
	v_dot8c_i32_i4_e32 v44, v136, v52
	v_dot8c_i32_i4_e32 v45, v136, v50
	v_dot8c_i32_i4_e32 v38, v131, v53
	v_dot8c_i32_i4_e32 v39, v131, v51
	v_dot8c_i32_i4_e32 v40, v133, v53
	v_dot8c_i32_i4_e32 v41, v133, v51
	v_dot8c_i32_i4_e32 v42, v135, v53
	v_dot8c_i32_i4_e32 v43, v135, v51
	v_dot8c_i32_i4_e32 v44, v137, v53
	v_dot8c_i32_i4_e32 v45, v137, v51
	v_and_b32_e32 v78, 0xffff, v25
	v_lshrrev_b32_e32 v79, 16, v25
	v_lshl_add_u32 v78, v78, 7, v150
	v_lshl_add_u32 v79, v79, 7, v151
	s_mov_b32 m0, s79
	s_add_i32 s43, s79, 0x400
	global_load_lds_dwordx4 v78, s[50:51]
	s_mov_b32 m0, s43
	s_nop 0
	global_load_lds_dwordx4 v79, s[50:51]
	s_waitcnt vmcnt(8)
	v_add_u32_e32 v54, s99, v59
	v_add_u32_e32 v55, s99, v60
	v_add_u32_e32 v56, s99, v61
	v_add_u32_e32 v57, s99, v62
	ds_read_b64_tr_b4 v[50:51], v160 offset:384
	ds_read_b64_tr_b4 v[52:53], v160 offset:1408
	ds_read_b64_tr_b4 v[130:131], v54
	ds_read_b64_tr_b4 v[132:133], v55
	ds_read_b64_tr_b4 v[134:135], v56
	ds_read_b64_tr_b4 v[136:137], v57
	s_waitcnt lgkmcnt(6)
	v_dot8c_i32_i4_e32 v38, v122, v48
	v_dot8c_i32_i4_e32 v39, v122, v46
	v_dot8c_i32_i4_e32 v40, v124, v48
	v_dot8c_i32_i4_e32 v41, v124, v46
	v_dot8c_i32_i4_e32 v42, v126, v48
	v_dot8c_i32_i4_e32 v43, v126, v46
	v_dot8c_i32_i4_e32 v44, v128, v48
	v_dot8c_i32_i4_e32 v45, v128, v46
	v_dot8c_i32_i4_e32 v38, v123, v49
	v_dot8c_i32_i4_e32 v39, v123, v47
	v_dot8c_i32_i4_e32 v40, v125, v49
	v_dot8c_i32_i4_e32 v41, v125, v47
	v_dot8c_i32_i4_e32 v42, v127, v49
	v_dot8c_i32_i4_e32 v43, v127, v47
	v_dot8c_i32_i4_e32 v44, v129, v49
	v_dot8c_i32_i4_e32 v45, v129, v47
	s_waitcnt lgkmcnt(15)
	v_and_b32_e32 v78, 0xffff, v26
	v_lshrrev_b32_e32 v79, 16, v26
	v_lshl_add_u32 v78, v78, 7, v150
	v_lshl_add_u32 v79, v79, 7, v151
	s_mov_b32 m0, s98
	s_add_i32 s43, s98, 0x400
	global_load_lds_dwordx4 v78, s[50:51]
	s_mov_b32 m0, s43
	s_nop 0
	global_load_lds_dwordx4 v79, s[50:51]
	s_waitcnt vmcnt(8)
	v_add_u32_e32 v54, s76, v59
	v_add_u32_e32 v55, s76, v60
	v_add_u32_e32 v56, s76, v61
	v_add_u32_e32 v57, s76, v62
	ds_read_b64_tr_b4 v[46:47], v160 offset:512
	ds_read_b64_tr_b4 v[48:49], v160 offset:1536
	ds_read_b64_tr_b4 v[122:123], v54
	ds_read_b64_tr_b4 v[124:125], v55
	ds_read_b64_tr_b4 v[126:127], v56
	ds_read_b64_tr_b4 v[128:129], v57
	s_waitcnt lgkmcnt(6)
	v_dot8c_i32_i4_e32 v38, v130, v52
	v_dot8c_i32_i4_e32 v39, v130, v50
	v_dot8c_i32_i4_e32 v40, v132, v52
	v_dot8c_i32_i4_e32 v41, v132, v50
	v_dot8c_i32_i4_e32 v42, v134, v52
	v_dot8c_i32_i4_e32 v43, v134, v50
	v_dot8c_i32_i4_e32 v44, v136, v52
	v_dot8c_i32_i4_e32 v45, v136, v50
	v_dot8c_i32_i4_e32 v38, v131, v53
	v_dot8c_i32_i4_e32 v39, v131, v51
	v_dot8c_i32_i4_e32 v40, v133, v53
	v_dot8c_i32_i4_e32 v41, v133, v51
	v_dot8c_i32_i4_e32 v42, v135, v53
	v_dot8c_i32_i4_e32 v43, v135, v51
	v_dot8c_i32_i4_e32 v44, v137, v53
	v_dot8c_i32_i4_e32 v45, v137, v51
	v_and_b32_e32 v78, 0xffff, v27
	v_lshrrev_b32_e32 v79, 16, v27
	v_lshl_add_u32 v78, v78, 7, v150
	v_lshl_add_u32 v79, v79, 7, v151
	s_mov_b32 m0, s99
	s_add_i32 s43, s99, 0x400
	global_load_lds_dwordx4 v78, s[50:51]
	s_mov_b32 m0, s43
	s_nop 0
	global_load_lds_dwordx4 v79, s[50:51]
	s_waitcnt vmcnt(8)
	v_add_u32_e32 v54, s77, v59
	v_add_u32_e32 v55, s77, v60
	v_add_u32_e32 v56, s77, v61
	v_add_u32_e32 v57, s77, v62
	ds_read_b64_tr_b4 v[50:51], v160 offset:640
	ds_read_b64_tr_b4 v[52:53], v160 offset:1664
	ds_read_b64_tr_b4 v[130:131], v54
	ds_read_b64_tr_b4 v[132:133], v55
	ds_read_b64_tr_b4 v[134:135], v56
	ds_read_b64_tr_b4 v[136:137], v57
	s_waitcnt lgkmcnt(6)
	v_dot8c_i32_i4_e32 v38, v122, v48
	v_dot8c_i32_i4_e32 v39, v122, v46
	v_dot8c_i32_i4_e32 v40, v124, v48
	v_dot8c_i32_i4_e32 v41, v124, v46
	v_dot8c_i32_i4_e32 v42, v126, v48
	v_dot8c_i32_i4_e32 v43, v126, v46
	v_dot8c_i32_i4_e32 v44, v128, v48
	v_dot8c_i32_i4_e32 v45, v128, v46
	v_dot8c_i32_i4_e32 v38, v123, v49
	v_dot8c_i32_i4_e32 v39, v123, v47
	v_dot8c_i32_i4_e32 v40, v125, v49
	v_dot8c_i32_i4_e32 v41, v125, v47
	v_dot8c_i32_i4_e32 v42, v127, v49
	v_dot8c_i32_i4_e32 v43, v127, v47
	v_dot8c_i32_i4_e32 v44, v129, v49
	v_dot8c_i32_i4_e32 v45, v129, v47
	s_waitcnt lgkmcnt(15)
; #define LAS __attribute__((address_space(3)))
; __device__ __forceinline__ bf16 f2bf(float f) { return (bf16)f2bfu(f); }
; #define TR4(p_) __builtin_amdgcn_ds_read_tr4_b64_v2i32((LAS v2i*)(p_))
; __device__ __forceinline__ void peer_v_tokens(int j, const LAS unsigned short* EL, const LAS unsigned char* AL  , const LAS float* ASC  , const LAS int* SAL  , ...
;     ...
;             const unsigned lo = (((unsigned)tq & 15u) ^ 8u) * 0x11111111u, hi = ((unsigned)(tq >> 4) & 15u) * 0x11111111u;
;             typedef unsigned u2v __attribute__((ext_vector_type(2)));
;             u2v l2; l2.x = lo; l2.y = lo; u2v h2; h2.x = hi; h2.y = hi;
;             *(LAS u2v*)(ATL + 8 * idx) = l2; *(LAS u2v*)(ATL + 1024 + 8 * idx) = h2;
;     ...
;         for (int st = 0; st < 16; ++st) {
;             const int p = st >> 2, q = st & 3;
;             if (st < 14) VDMA(st + 2, (st + 2) % 3);
;             if (st < 14) asm volatile("s_waitcnt vmcnt(8)" ::: "memory");
;             else if (st == 14) asm volatile("s_waitcnt vmcnt(4)" ::: "memory");
;             else asm volatile("s_waitcnt vmcnt(0)" ::: "memory");
;             if (q == 0) {
; #pragma unroll
;                 for (int r = 0; r < 4; ++r) { accH[r] = 0; accL[r] = 0; } }
; #pragma unroll
;             for (int tp = 0; tp < 2; ++tp) {
;                 const v2i ao = TR4(ATL + (2 * q + tp) * 128 + 8 * s16), ah = TR4(ATL + 1024 + (2 * q + tp) * 128 + 8 * s16);
; #pragma unroll
;                 for (int r = 0; r < 4; ++r) {
;                     const v2i d = TR4(ldsb + BUF[st % 3] + 2048 * tp + roff[r]);
;                     accH[r] = __builtin_amdgcn_sdot8(d.x, ah.x, accH[r], false); accH[r] = __builtin_amdgcn_sdot8(d.y, ah.y, accH[r], false);
;                     accL[r] = __builtin_amdgcn_sdot8(d.x, ao.x, accL[r], false); accL[r] = __builtin_amdgcn_sdot8(d.y, ao.y, accL[r], false);
;                 }
;             }
;             asm volatile("s_waitcnt lgkmcnt(0)" ::: "memory");
;             if (q == 3) {
; #pragma unroll
;                 for (int r = 0; r < 4; ++r) STASH[256 * p + 16 * (grp + 4 * r) + pc] = f2bf(asc * (float)(2 * ((accH[r] << 4) + accL[r]) + sa));
;             }
	v_add_u32_e32 v143, 8, v139
	v_and_b32_e32 v142, 15, v143
	v_xor_b32_e32 v142, 8, v142
	v_bfe_u32 v144, v143, 4, 4
	v_mul_lo_u32 v142, v142, s92
	v_mul_lo_u32 v144, v144, s92
	v_mov_b32_e32 v143, v142
	v_mov_b32_e32 v145, v144
	ds_write2st64_b64 v159, v[142:143], v[144:145] offset1:2
	v_and_b32_e32 v78, 0xffff, v28
	v_lshrrev_b32_e32 v79, 16, v28
	v_lshl_add_u32 v78, v78, 7, v150
	v_lshl_add_u32 v79, v79, 7, v151
	s_mov_b32 m0, s76
	s_add_i32 s43, s76, 0x400
	global_load_lds_dwordx4 v78, s[50:51]
	s_mov_b32 m0, s43
	s_nop 0
	global_load_lds_dwordx4 v79, s[50:51]
	s_waitcnt vmcnt(8)
	v_add_u32_e32 v54, s78, v59
	v_add_u32_e32 v55, s78, v60
	v_add_u32_e32 v56, s78, v61
	v_add_u32_e32 v57, s78, v62
	ds_read_b64_tr_b4 v[46:47], v160 offset:768
	ds_read_b64_tr_b4 v[48:49], v160 offset:1792
	ds_read_b64_tr_b4 v[122:123], v54
	ds_read_b64_tr_b4 v[124:125], v55
	ds_read_b64_tr_b4 v[126:127], v56
	ds_read_b64_tr_b4 v[128:129], v57
	s_waitcnt lgkmcnt(7)
	v_dot8c_i32_i4_e32 v38, v130, v52
	v_dot8c_i32_i4_e32 v39, v130, v50
	v_dot8c_i32_i4_e32 v40, v132, v52
	v_dot8c_i32_i4_e32 v41, v132, v50
	v_dot8c_i32_i4_e32 v42, v134, v52
	v_dot8c_i32_i4_e32 v43, v134, v50
	v_dot8c_i32_i4_e32 v44, v136, v52
	v_dot8c_i32_i4_e32 v45, v136, v50
	v_dot8c_i32_i4_e32 v38, v131, v53
	v_dot8c_i32_i4_e32 v39, v131, v51
	v_dot8c_i32_i4_e32 v40, v133, v53
	v_dot8c_i32_i4_e32 v41, v133, v51
	v_dot8c_i32_i4_e32 v42, v135, v53
	v_dot8c_i32_i4_e32 v43, v135, v51
	v_dot8c_i32_i4_e32 v44, v137, v53
	v_dot8c_i32_i4_e32 v45, v137, v51
	v_and_b32_e32 v78, 0xffff, v29
	v_lshrrev_b32_e32 v79, 16, v29
	v_lshl_add_u32 v78, v78, 7, v150
	v_lshl_add_u32 v79, v79, 7, v151
	s_mov_b32 m0, s77
	s_add_i32 s43, s77, 0x400
	global_load_lds_dwordx4 v78, s[50:51]
	s_mov_b32 m0, s43
	s_nop 0
	global_load_lds_dwordx4 v79, s[50:51]
	s_waitcnt vmcnt(8)
	v_add_u32_e32 v54, s79, v59
	v_add_u32_e32 v55, s79, v60
	v_add_u32_e32 v56, s79, v61
	v_add_u32_e32 v57, s79, v62
	ds_read_b64_tr_b4 v[50:51], v160 offset:896
	ds_read_b64_tr_b4 v[52:53], v160 offset:1920
	ds_read_b64_tr_b4 v[130:131], v54
	ds_read_b64_tr_b4 v[132:133], v55
	ds_read_b64_tr_b4 v[134:135], v56
	ds_read_b64_tr_b4 v[136:137], v57
	s_waitcnt lgkmcnt(6)
	v_dot8c_i32_i4_e32 v38, v122, v48
	v_dot8c_i32_i4_e32 v39, v122, v46
	v_dot8c_i32_i4_e32 v40, v124, v48
	v_dot8c_i32_i4_e32 v41, v124, v46
	v_dot8c_i32_i4_e32 v42, v126, v48
	v_dot8c_i32_i4_e32 v43, v126, v46
	v_dot8c_i32_i4_e32 v44, v128, v48
	v_dot8c_i32_i4_e32 v45, v128, v46
	v_dot8c_i32_i4_e32 v38, v123, v49
	v_dot8c_i32_i4_e32 v39, v123, v47
	v_dot8c_i32_i4_e32 v40, v125, v49
	v_dot8c_i32_i4_e32 v41, v125, v47
	v_dot8c_i32_i4_e32 v42, v127, v49
	v_dot8c_i32_i4_e32 v43, v127, v47
	v_dot8c_i32_i4_e32 v44, v129, v49
	v_dot8c_i32_i4_e32 v45, v129, v47
	v_and_b32_e32 v78, 0xffff, v30
	v_lshrrev_b32_e32 v79, 16, v30
	v_lshl_add_u32 v78, v78, 7, v150
	v_lshl_add_u32 v79, v79, 7, v151
	s_mov_b32 m0, s78
	s_add_i32 s43, s78, 0x400
	global_load_lds_dwordx4 v78, s[50:51]
	s_mov_b32 m0, s43
	s_nop 0
	global_load_lds_dwordx4 v79, s[50:51]
	s_waitcnt vmcnt(8)
	v_add_u32_e32 v54, s98, v59
	v_add_u32_e32 v55, s98, v60
	v_add_u32_e32 v56, s98, v61
	v_add_u32_e32 v57, s98, v62
	ds_read_b64_tr_b4 v[46:47], v160
	ds_read_b64_tr_b4 v[48:49], v160 offset:1024
	ds_read_b64_tr_b4 v[122:123], v54
	ds_read_b64_tr_b4 v[124:125], v55
	ds_read_b64_tr_b4 v[126:127], v56
	ds_read_b64_tr_b4 v[128:129], v57
	s_waitcnt lgkmcnt(6)
	v_dot8c_i32_i4_e32 v38, v130, v52
	v_dot8c_i32_i4_e32 v39, v130, v50
	v_dot8c_i32_i4_e32 v40, v132, v52
	v_dot8c_i32_i4_e32 v41, v132, v50
	v_dot8c_i32_i4_e32 v42, v134, v52
	v_dot8c_i32_i4_e32 v43, v134, v50
	v_dot8c_i32_i4_e32 v44, v136, v52
	v_dot8c_i32_i4_e32 v45, v136, v50
	v_dot8c_i32_i4_e32 v38, v131, v53
	v_dot8c_i32_i4_e32 v39, v131, v51
	v_dot8c_i32_i4_e32 v40, v133, v53
	v_dot8c_i32_i4_e32 v41, v133, v51
	v_dot8c_i32_i4_e32 v42, v135, v53
	v_dot8c_i32_i4_e32 v43, v135, v51
	v_dot8c_i32_i4_e32 v44, v137, v53
	v_dot8c_i32_i4_e32 v45, v137, v51
	s_nop 3
	s_waitcnt lgkmcnt(15)
	v_lshlrev_b32_e32 v38, 5, v38
	v_lshlrev_b32_e32 v39, 1, v39
	v_add3_u32 v38, v39, v229, v38
	v_cvt_f32_i32_e32 v38, v38
	v_mul_f32_e32 v38, v228, v38
	v_lshlrev_b32_e32 v40, 5, v40
	v_lshlrev_b32_e32 v41, 1, v41
	v_add3_u32 v40, v41, v229, v40
	v_cvt_f32_i32_e32 v40, v40
	v_mul_f32_e32 v40, v228, v40
	v_lshlrev_b32_e32 v42, 5, v42
	v_lshlrev_b32_e32 v43, 1, v43
	v_add3_u32 v42, v43, v229, v42
	v_cvt_f32_i32_e32 v42, v42
	v_mul_f32_e32 v42, v228, v42
	v_lshlrev_b32_e32 v44, 5, v44
	v_lshlrev_b32_e32 v45, 1, v45
	v_add3_u32 v44, v45, v229, v44
	v_cvt_f32_i32_e32 v44, v44
	v_mul_f32_e32 v44, v228, v44
	v_cvt_pk_bf16_f32 v166, v38, v40
	v_cvt_pk_bf16_f32 v167, v42, v44
	v_add_u32_e32 v147, 8, v140
	v_and_b32_e32 v146, 15, v147
	v_xor_b32_e32 v146, 8, v146
	v_bfe_u32 v148, v147, 4, 4
	v_mul_lo_u32 v146, v146, s92
	v_mul_lo_u32 v148, v148, s92
	v_mov_b32_e32 v147, v146
	v_mov_b32_e32 v149, v148
	ds_write2st64_b64 v77, v[146:147], v[148:149] offset1:2
	v_mov_b32_e32 v138, v74
	ds_read_u8 v139, v138
	v_mov_b32_e32 v141, v73
	ds_read_u8 v140, v141
	s_add_i32 s43, s67, 32
	v_mov_b32_e32 v138, s43
	ds_read2st64_b32 v[228:229], v138 offset1:1
	ds_read_b128 v[18:21], v227
	ds_read_b128 v[22:25], v227 offset:16
	v_add_u32_e32 v152, 0x600000, v63
	v_add_u32_e32 v153, 0x600000, v64
	v_mov_b32_e32 v38, 0
	v_mov_b32_e32 v39, 0
	v_mov_b32_e32 v40, 0
	v_mov_b32_e32 v41, 0
	v_mov_b32_e32 v42, 0
	v_mov_b32_e32 v43, 0
	v_mov_b32_e32 v44, 0
	v_mov_b32_e32 v45, 0
	v_and_b32_e32 v78, 0xffff, v31
	v_lshrrev_b32_e32 v79, 16, v31
	v_lshl_add_u32 v78, v78, 7, v150
	v_lshl_add_u32 v79, v79, 7, v151
	s_mov_b32 m0, s79
	s_add_i32 s43, s79, 0x400
	global_load_lds_dwordx4 v78, s[50:51]
	s_mov_b32 m0, s43
	s_nop 0
	global_load_lds_dwordx4 v79, s[50:51]
	s_waitcnt vmcnt(8)
; #define TR4(p_) __builtin_amdgcn_ds_read_tr4_b64_v2i32((LAS v2i*)(p_))
; #define VDMA(st_, k_) do { _Pragma("unroll") for (int i_ = 0; i_ < 4; ++i_) { \
;         const unsigned off_ = (unsigned)((st_) >> 2) * (16384u * 128u) + (PE_ID(E, 4 * ((st_) & 3) + i_) << 7) + ((i_ & 1) ? cx1 : cx0); \
;         __builtin_amdgcn_global_load_lds((const unsigned*)(V4 + off_), (LAS unsigned*)(ldsb + BUF[k_] + 1024 * i_), 16, 0, 0); } } while (0)
; __device__ __forceinline__ void peer_v_tokens(int j, const LAS unsigned short* EL, const LAS unsigned char* AL  , const LAS float* ASC  , const LAS int* SAL  , ...
;     ...
;         for (int st = 0; st < 16; ++st) {
;             const int p = st >> 2, q = st & 3;
;             if (st < 14) VDMA(st + 2, (st + 2) % 3);
;             if (st < 14) asm volatile("s_waitcnt vmcnt(8)" ::: "memory");
;             else if (st == 14) asm volatile("s_waitcnt vmcnt(4)" ::: "memory");
;             else asm volatile("s_waitcnt vmcnt(0)" ::: "memory");
;             if (q == 0) {
; #pragma unroll
;                 for (int r = 0; r < 4; ++r) { accH[r] = 0; accL[r] = 0; } }
; #pragma unroll
;             for (int tp = 0; tp < 2; ++tp) {
;                 const v2i ao = TR4(ATL + (2 * q + tp) * 128 + 8 * s16), ah = TR4(ATL + 1024 + (2 * q + tp) * 128 + 8 * s16);
; #pragma unroll
;                 for (int r = 0; r < 4; ++r) {
;                     const v2i d = TR4(ldsb + BUF[st % 3] + 2048 * tp + roff[r]);
;                     accH[r] = __builtin_amdgcn_sdot8(d.x, ah.x, accH[r], false); accH[r] = __builtin_amdgcn_sdot8(d.y, ah.y, accH[r], false);
;                     accL[r] = __builtin_amdgcn_sdot8(d.x, ao.x, accL[r], false); accL[r] = __builtin_amdgcn_sdot8(d.y, ao.y, accL[r], false);
;                 }
;             }
	v_add_u32_e32 v54, s99, v59
	v_add_u32_e32 v55, s99, v60
	v_add_u32_e32 v56, s99, v61
	v_add_u32_e32 v57, s99, v62
	ds_read_b64_tr_b4 v[50:51], v160 offset:128
	ds_read_b64_tr_b4 v[52:53], v160 offset:1152
	ds_read_b64_tr_b4 v[130:131], v54
	ds_read_b64_tr_b4 v[132:133], v55
	ds_read_b64_tr_b4 v[134:135], v56
	ds_read_b64_tr_b4 v[136:137], v57
	s_waitcnt lgkmcnt(12)
	v_dot8c_i32_i4_e32 v38, v122, v48
	v_dot8c_i32_i4_e32 v39, v122, v46
	v_dot8c_i32_i4_e32 v40, v124, v48
	v_dot8c_i32_i4_e32 v41, v124, v46
	v_dot8c_i32_i4_e32 v42, v126, v48
	v_dot8c_i32_i4_e32 v43, v126, v46
	v_dot8c_i32_i4_e32 v44, v128, v48
	v_dot8c_i32_i4_e32 v45, v128, v46
	v_dot8c_i32_i4_e32 v38, v123, v49
	v_dot8c_i32_i4_e32 v39, v123, v47
	v_dot8c_i32_i4_e32 v40, v125, v49
	v_dot8c_i32_i4_e32 v41, v125, v47
	v_dot8c_i32_i4_e32 v42, v127, v49
	v_dot8c_i32_i4_e32 v43, v127, v47
	v_dot8c_i32_i4_e32 v44, v129, v49
	v_dot8c_i32_i4_e32 v45, v129, v47
	v_and_b32_e32 v78, 0xffff, v32
	v_lshrrev_b32_e32 v79, 16, v32
	v_lshl_add_u32 v78, v78, 7, v150
	v_lshl_add_u32 v79, v79, 7, v151
	s_mov_b32 m0, s98
	s_add_i32 s43, s98, 0x400
	global_load_lds_dwordx4 v78, s[50:51]
	s_mov_b32 m0, s43
	s_nop 0
	global_load_lds_dwordx4 v79, s[50:51]
	s_waitcnt vmcnt(8)
	v_add_u32_e32 v54, s76, v59
	v_add_u32_e32 v55, s76, v60
	v_add_u32_e32 v56, s76, v61
	v_add_u32_e32 v57, s76, v62
	ds_read_b64_tr_b4 v[46:47], v160 offset:256
	ds_read_b64_tr_b4 v[48:49], v160 offset:1280
	ds_read_b64_tr_b4 v[122:123], v54
	ds_read_b64_tr_b4 v[124:125], v55
	ds_read_b64_tr_b4 v[126:127], v56
	ds_read_b64_tr_b4 v[128:129], v57
	s_waitcnt lgkmcnt(6)
	v_dot8c_i32_i4_e32 v38, v130, v52
	v_dot8c_i32_i4_e32 v39, v130, v50
	v_dot8c_i32_i4_e32 v40, v132, v52
	v_dot8c_i32_i4_e32 v41, v132, v50
	v_dot8c_i32_i4_e32 v42, v134, v52
	v_dot8c_i32_i4_e32 v43, v134, v50
	v_dot8c_i32_i4_e32 v44, v136, v52
	v_dot8c_i32_i4_e32 v45, v136, v50
	v_dot8c_i32_i4_e32 v38, v131, v53
	v_dot8c_i32_i4_e32 v39, v131, v51
	v_dot8c_i32_i4_e32 v40, v133, v53
	v_dot8c_i32_i4_e32 v41, v133, v51
	v_dot8c_i32_i4_e32 v42, v135, v53
	v_dot8c_i32_i4_e32 v43, v135, v51
	v_dot8c_i32_i4_e32 v44, v137, v53
	v_dot8c_i32_i4_e32 v45, v137, v51
	v_and_b32_e32 v78, 0xffff, v33
	v_lshrrev_b32_e32 v79, 16, v33
	v_lshl_add_u32 v78, v78, 7, v150
	v_lshl_add_u32 v79, v79, 7, v151
	s_mov_b32 m0, s99
	s_add_i32 s43, s99, 0x400
	global_load_lds_dwordx4 v78, s[50:51]
	s_mov_b32 m0, s43
	s_nop 0
	global_load_lds_dwordx4 v79, s[50:51]
	s_waitcnt vmcnt(8)
	v_add_u32_e32 v54, s77, v59
	v_add_u32_e32 v55, s77, v60
	v_add_u32_e32 v56, s77, v61
	v_add_u32_e32 v57, s77, v62
	ds_read_b64_tr_b4 v[50:51], v160 offset:384
	ds_read_b64_tr_b4 v[52:53], v160 offset:1408
	ds_read_b64_tr_b4 v[130:131], v54
	ds_read_b64_tr_b4 v[132:133], v55
	ds_read_b64_tr_b4 v[134:135], v56
	ds_read_b64_tr_b4 v[136:137], v57
	s_waitcnt lgkmcnt(6)
	v_dot8c_i32_i4_e32 v38, v122, v48
	v_dot8c_i32_i4_e32 v39, v122, v46
	v_dot8c_i32_i4_e32 v40, v124, v48
	v_dot8c_i32_i4_e32 v41, v124, v46
	v_dot8c_i32_i4_e32 v42, v126, v48
	v_dot8c_i32_i4_e32 v43, v126, v46
	v_dot8c_i32_i4_e32 v44, v128, v48
	v_dot8c_i32_i4_e32 v45, v128, v46
	v_dot8c_i32_i4_e32 v38, v123, v49
	v_dot8c_i32_i4_e32 v39, v123, v47
	v_dot8c_i32_i4_e32 v40, v125, v49
	v_dot8c_i32_i4_e32 v41, v125, v47
	v_dot8c_i32_i4_e32 v42, v127, v49
	v_dot8c_i32_i4_e32 v43, v127, v47
	v_dot8c_i32_i4_e32 v44, v129, v49
	v_dot8c_i32_i4_e32 v45, v129, v47
	s_waitcnt lgkmcnt(15)
	v_and_b32_e32 v78, 0xffff, v18
	v_lshrrev_b32_e32 v79, 16, v18
	v_lshl_add_u32 v78, v78, 7, v152
	v_lshl_add_u32 v79, v79, 7, v153
	s_mov_b32 m0, s76
	s_add_i32 s43, s76, 0x400
	global_load_lds_dwordx4 v78, s[50:51]
	s_mov_b32 m0, s43
	s_nop 0
	global_load_lds_dwordx4 v79, s[50:51]
	s_waitcnt vmcnt(8)
	v_add_u32_e32 v54, s78, v59
	v_add_u32_e32 v55, s78, v60
	v_add_u32_e32 v56, s78, v61
	v_add_u32_e32 v57, s78, v62
	ds_read_b64_tr_b4 v[46:47], v160 offset:512
	ds_read_b64_tr_b4 v[48:49], v160 offset:1536
	ds_read_b64_tr_b4 v[122:123], v54
	ds_read_b64_tr_b4 v[124:125], v55
	ds_read_b64_tr_b4 v[126:127], v56
	ds_read_b64_tr_b4 v[128:129], v57
	s_waitcnt lgkmcnt(6)
	v_dot8c_i32_i4_e32 v38, v130, v52
	v_dot8c_i32_i4_e32 v39, v130, v50
	v_dot8c_i32_i4_e32 v40, v132, v52
	v_dot8c_i32_i4_e32 v41, v132, v50
	v_dot8c_i32_i4_e32 v42, v134, v52
	v_dot8c_i32_i4_e32 v43, v134, v50
	v_dot8c_i32_i4_e32 v44, v136, v52
	v_dot8c_i32_i4_e32 v45, v136, v50
	v_dot8c_i32_i4_e32 v38, v131, v53
	v_dot8c_i32_i4_e32 v39, v131, v51
	v_dot8c_i32_i4_e32 v40, v133, v53
	v_dot8c_i32_i4_e32 v41, v133, v51
	v_dot8c_i32_i4_e32 v42, v135, v53
	v_dot8c_i32_i4_e32 v43, v135, v51
	v_dot8c_i32_i4_e32 v44, v137, v53
	v_dot8c_i32_i4_e32 v45, v137, v51
	v_and_b32_e32 v78, 0xffff, v19
	v_lshrrev_b32_e32 v79, 16, v19
	v_lshl_add_u32 v78, v78, 7, v152
	v_lshl_add_u32 v79, v79, 7, v153
	s_mov_b32 m0, s77
	s_add_i32 s43, s77, 0x400
	global_load_lds_dwordx4 v78, s[50:51]
	s_mov_b32 m0, s43
	s_nop 0
	global_load_lds_dwordx4 v79, s[50:51]
	s_waitcnt vmcnt(8)
	v_add_u32_e32 v54, s79, v59
	v_add_u32_e32 v55, s79, v60
	v_add_u32_e32 v56, s79, v61
	v_add_u32_e32 v57, s79, v62
	ds_read_b64_tr_b4 v[50:51], v160 offset:640
	ds_read_b64_tr_b4 v[52:53], v160 offset:1664
	ds_read_b64_tr_b4 v[130:131], v54
	ds_read_b64_tr_b4 v[132:133], v55
	ds_read_b64_tr_b4 v[134:135], v56
	ds_read_b64_tr_b4 v[136:137], v57
	s_waitcnt lgkmcnt(6)
	v_dot8c_i32_i4_e32 v38, v122, v48
	v_dot8c_i32_i4_e32 v39, v122, v46
	v_dot8c_i32_i4_e32 v40, v124, v48
	v_dot8c_i32_i4_e32 v41, v124, v46
	v_dot8c_i32_i4_e32 v42, v126, v48
	v_dot8c_i32_i4_e32 v43, v126, v46
	v_dot8c_i32_i4_e32 v44, v128, v48
	v_dot8c_i32_i4_e32 v45, v128, v46
	v_dot8c_i32_i4_e32 v38, v123, v49
	v_dot8c_i32_i4_e32 v39, v123, v47
	v_dot8c_i32_i4_e32 v40, v125, v49
	v_dot8c_i32_i4_e32 v41, v125, v47
	v_dot8c_i32_i4_e32 v42, v127, v49
	v_dot8c_i32_i4_e32 v43, v127, v47
	v_dot8c_i32_i4_e32 v44, v129, v49
	v_dot8c_i32_i4_e32 v45, v129, v47
	s_waitcnt lgkmcnt(15)
; #define LAS __attribute__((address_space(3)))
; __device__ __forceinline__ bf16 f2bf(float f) { return (bf16)f2bfu(f); }
; #define TR4(p_) __builtin_amdgcn_ds_read_tr4_b64_v2i32((LAS v2i*)(p_))
; __device__ __forceinline__ void peer_v_tokens(int j, const LAS unsigned short* EL, const LAS unsigned char* AL  , const LAS float* ASC  , const LAS int* SAL  , ...
;     ...
;             const unsigned lo = (((unsigned)tq & 15u) ^ 8u) * 0x11111111u, hi = ((unsigned)(tq >> 4) & 15u) * 0x11111111u;
;             typedef unsigned u2v __attribute__((ext_vector_type(2)));
;             u2v l2; l2.x = lo; l2.y = lo; u2v h2; h2.x = hi; h2.y = hi;
;             *(LAS u2v*)(ATL + 8 * idx) = l2; *(LAS u2v*)(ATL + 1024 + 8 * idx) = h2;
;     ...
;         for (int st = 0; st < 16; ++st) {
;             const int p = st >> 2, q = st & 3;
;             if (st < 14) VDMA(st + 2, (st + 2) % 3);
;             if (st < 14) asm volatile("s_waitcnt vmcnt(8)" ::: "memory");
;             else if (st == 14) asm volatile("s_waitcnt vmcnt(4)" ::: "memory");
;             else asm volatile("s_waitcnt vmcnt(0)" ::: "memory");
;             if (q == 0) {
; #pragma unroll
;                 for (int r = 0; r < 4; ++r) { accH[r] = 0; accL[r] = 0; } }
; #pragma unroll
;             for (int tp = 0; tp < 2; ++tp) {
;                 const v2i ao = TR4(ATL + (2 * q + tp) * 128 + 8 * s16), ah = TR4(ATL + 1024 + (2 * q + tp) * 128 + 8 * s16);
; #pragma unroll
;                 for (int r = 0; r < 4; ++r) {
;                     const v2i d = TR4(ldsb + BUF[st % 3] + 2048 * tp + roff[r]);
;                     accH[r] = __builtin_amdgcn_sdot8(d.x, ah.x, accH[r], false); accH[r] = __builtin_amdgcn_sdot8(d.y, ah.y, accH[r], false);
;                     accL[r] = __builtin_amdgcn_sdot8(d.x, ao.x, accL[r], false); accL[r] = __builtin_amdgcn_sdot8(d.y, ao.y, accL[r], false);
;                 }
;             }
;             asm volatile("s_waitcnt lgkmcnt(0)" ::: "memory");
;             if (q == 3) {
; #pragma unroll
;                 for (int r = 0; r < 4; ++r) STASH[256 * p + 16 * (grp + 4 * r) + pc] = f2bf(asc * (float)(2 * ((accH[r] << 4) + accL[r]) + sa));
;             }
	v_add_u32_e32 v143, 8, v139
	v_and_b32_e32 v142, 15, v143
	v_xor_b32_e32 v142, 8, v142
	v_bfe_u32 v144, v143, 4, 4
	v_mul_lo_u32 v142, v142, s92
	v_mul_lo_u32 v144, v144, s92
	v_mov_b32_e32 v143, v142
	v_mov_b32_e32 v145, v144
	ds_write2st64_b64 v159, v[142:143], v[144:145] offset1:2
	v_and_b32_e32 v78, 0xffff, v20
	v_lshrrev_b32_e32 v79, 16, v20
	v_lshl_add_u32 v78, v78, 7, v152
	v_lshl_add_u32 v79, v79, 7, v153
	s_mov_b32 m0, s78
	s_add_i32 s43, s78, 0x400
	global_load_lds_dwordx4 v78, s[50:51]
	s_mov_b32 m0, s43
	s_nop 0
	global_load_lds_dwordx4 v79, s[50:51]
	s_waitcnt vmcnt(8)
	v_add_u32_e32 v54, s98, v59
	v_add_u32_e32 v55, s98, v60
	v_add_u32_e32 v56, s98, v61
	v_add_u32_e32 v57, s98, v62
	ds_read_b64_tr_b4 v[46:47], v160 offset:768
	ds_read_b64_tr_b4 v[48:49], v160 offset:1792
	ds_read_b64_tr_b4 v[122:123], v54
	ds_read_b64_tr_b4 v[124:125], v55
	ds_read_b64_tr_b4 v[126:127], v56
	ds_read_b64_tr_b4 v[128:129], v57
	s_waitcnt lgkmcnt(7)
	v_dot8c_i32_i4_e32 v38, v130, v52
	v_dot8c_i32_i4_e32 v39, v130, v50
	v_dot8c_i32_i4_e32 v40, v132, v52
	v_dot8c_i32_i4_e32 v41, v132, v50
	v_dot8c_i32_i4_e32 v42, v134, v52
	v_dot8c_i32_i4_e32 v43, v134, v50
	v_dot8c_i32_i4_e32 v44, v136, v52
	v_dot8c_i32_i4_e32 v45, v136, v50
	v_dot8c_i32_i4_e32 v38, v131, v53
	v_dot8c_i32_i4_e32 v39, v131, v51
	v_dot8c_i32_i4_e32 v40, v133, v53
	v_dot8c_i32_i4_e32 v41, v133, v51
	v_dot8c_i32_i4_e32 v42, v135, v53
	v_dot8c_i32_i4_e32 v43, v135, v51
	v_dot8c_i32_i4_e32 v44, v137, v53
	v_dot8c_i32_i4_e32 v45, v137, v51
	v_and_b32_e32 v78, 0xffff, v21
	v_lshrrev_b32_e32 v79, 16, v21
	v_lshl_add_u32 v78, v78, 7, v152
	v_lshl_add_u32 v79, v79, 7, v153
	s_mov_b32 m0, s79
	s_add_i32 s43, s79, 0x400
	global_load_lds_dwordx4 v78, s[50:51]
	s_mov_b32 m0, s43
	s_nop 0
	global_load_lds_dwordx4 v79, s[50:51]
	s_waitcnt vmcnt(8)
	v_add_u32_e32 v54, s99, v59
	v_add_u32_e32 v55, s99, v60
	v_add_u32_e32 v56, s99, v61
	v_add_u32_e32 v57, s99, v62
	ds_read_b64_tr_b4 v[50:51], v160 offset:896
	ds_read_b64_tr_b4 v[52:53], v160 offset:1920
	ds_read_b64_tr_b4 v[130:131], v54
	ds_read_b64_tr_b4 v[132:133], v55
	ds_read_b64_tr_b4 v[134:135], v56
	ds_read_b64_tr_b4 v[136:137], v57
	s_waitcnt lgkmcnt(6)
	v_dot8c_i32_i4_e32 v38, v122, v48
	v_dot8c_i32_i4_e32 v39, v122, v46
	v_dot8c_i32_i4_e32 v40, v124, v48
	v_dot8c_i32_i4_e32 v41, v124, v46
	v_dot8c_i32_i4_e32 v42, v126, v48
	v_dot8c_i32_i4_e32 v43, v126, v46
	v_dot8c_i32_i4_e32 v44, v128, v48
	v_dot8c_i32_i4_e32 v45, v128, v46
	v_dot8c_i32_i4_e32 v38, v123, v49
	v_dot8c_i32_i4_e32 v39, v123, v47
	v_dot8c_i32_i4_e32 v40, v125, v49
	v_dot8c_i32_i4_e32 v41, v125, v47
	v_dot8c_i32_i4_e32 v42, v127, v49
	v_dot8c_i32_i4_e32 v43, v127, v47
	v_dot8c_i32_i4_e32 v44, v129, v49
	v_dot8c_i32_i4_e32 v45, v129, v47
	v_and_b32_e32 v78, 0xffff, v22
	v_lshrrev_b32_e32 v79, 16, v22
	v_lshl_add_u32 v78, v78, 7, v152
	v_lshl_add_u32 v79, v79, 7, v153
	s_mov_b32 m0, s98
	s_add_i32 s43, s98, 0x400
	global_load_lds_dwordx4 v78, s[50:51]
	s_mov_b32 m0, s43
	s_nop 0
	global_load_lds_dwordx4 v79, s[50:51]
	s_waitcnt vmcnt(8)
	v_add_u32_e32 v54, s76, v59
	v_add_u32_e32 v55, s76, v60
	v_add_u32_e32 v56, s76, v61
	v_add_u32_e32 v57, s76, v62
	ds_read_b64_tr_b4 v[46:47], v160
	ds_read_b64_tr_b4 v[48:49], v160 offset:1024
	ds_read_b64_tr_b4 v[122:123], v54
	ds_read_b64_tr_b4 v[124:125], v55
	ds_read_b64_tr_b4 v[126:127], v56
	ds_read_b64_tr_b4 v[128:129], v57
	s_waitcnt lgkmcnt(6)
	v_dot8c_i32_i4_e32 v38, v130, v52
	v_dot8c_i32_i4_e32 v39, v130, v50
	v_dot8c_i32_i4_e32 v40, v132, v52
	v_dot8c_i32_i4_e32 v41, v132, v50
	v_dot8c_i32_i4_e32 v42, v134, v52
	v_dot8c_i32_i4_e32 v43, v134, v50
	v_dot8c_i32_i4_e32 v44, v136, v52
	v_dot8c_i32_i4_e32 v45, v136, v50
	v_dot8c_i32_i4_e32 v38, v131, v53
	v_dot8c_i32_i4_e32 v39, v131, v51
	v_dot8c_i32_i4_e32 v40, v133, v53
	v_dot8c_i32_i4_e32 v41, v133, v51
	v_dot8c_i32_i4_e32 v42, v135, v53
	v_dot8c_i32_i4_e32 v43, v135, v51
	v_dot8c_i32_i4_e32 v44, v137, v53
	v_dot8c_i32_i4_e32 v45, v137, v51
	s_nop 3
	s_waitcnt lgkmcnt(15)
	v_lshlrev_b32_e32 v38, 5, v38
	v_lshlrev_b32_e32 v39, 1, v39
	v_add3_u32 v38, v39, v229, v38
	v_cvt_f32_i32_e32 v38, v38
	v_mul_f32_e32 v38, v228, v38
	v_lshlrev_b32_e32 v40, 5, v40
	v_lshlrev_b32_e32 v41, 1, v41
	v_add3_u32 v40, v41, v229, v40
	v_cvt_f32_i32_e32 v40, v40
	v_mul_f32_e32 v40, v228, v40
	v_lshlrev_b32_e32 v42, 5, v42
	v_lshlrev_b32_e32 v43, 1, v43
	v_add3_u32 v42, v43, v229, v42
	v_cvt_f32_i32_e32 v42, v42
	v_mul_f32_e32 v42, v228, v42
	v_lshlrev_b32_e32 v44, 5, v44
	v_lshlrev_b32_e32 v45, 1, v45
	v_add3_u32 v44, v45, v229, v44
	v_cvt_f32_i32_e32 v44, v44
	v_mul_f32_e32 v44, v228, v44
	v_cvt_pk_bf16_f32 v174, v38, v40
	v_cvt_pk_bf16_f32 v175, v42, v44
	v_add_u32_e32 v147, 8, v140
	v_and_b32_e32 v146, 15, v147
	v_xor_b32_e32 v146, 8, v146
	v_bfe_u32 v148, v147, 4, 4
	v_mul_lo_u32 v146, v146, s92
	v_mul_lo_u32 v148, v148, s92
	v_mov_b32_e32 v147, v146
	v_mov_b32_e32 v149, v148
	ds_write2st64_b64 v77, v[146:147], v[148:149] offset1:2
	v_add_u32_e32 v138, 0x400, v74
	ds_read_u8 v139, v138
	v_add_u32_e32 v141, 0x400, v73
	ds_read_u8 v140, v141
	s_mov_b32 s43, s67
	v_mov_b32_e32 v138, s43
	ds_read2st64_b32 v[228:229], v138 offset1:1
	ds_read_b128 v[26:29], v227 offset:2048
	ds_read_b128 v[30:33], v227 offset:2064
	v_mov_b32_e32 v38, 0
	v_mov_b32_e32 v39, 0
	v_mov_b32_e32 v40, 0
	v_mov_b32_e32 v41, 0
	v_mov_b32_e32 v42, 0
	v_mov_b32_e32 v43, 0
	v_mov_b32_e32 v44, 0
	v_mov_b32_e32 v45, 0
	v_and_b32_e32 v78, 0xffff, v23
	v_lshrrev_b32_e32 v79, 16, v23
	v_lshl_add_u32 v78, v78, 7, v152
	v_lshl_add_u32 v79, v79, 7, v153
	s_mov_b32 m0, s99
	s_add_i32 s43, s99, 0x400
	global_load_lds_dwordx4 v78, s[50:51]
	s_mov_b32 m0, s43
	s_nop 0
	global_load_lds_dwordx4 v79, s[50:51]
	s_waitcnt vmcnt(8)
; #define TR4(p_) __builtin_amdgcn_ds_read_tr4_b64_v2i32((LAS v2i*)(p_))
; #define VDMA(st_, k_) do { _Pragma("unroll") for (int i_ = 0; i_ < 4; ++i_) { \
;         const unsigned off_ = (unsigned)((st_) >> 2) * (16384u * 128u) + (PE_ID(E, 4 * ((st_) & 3) + i_) << 7) + ((i_ & 1) ? cx1 : cx0); \
;         __builtin_amdgcn_global_load_lds((const unsigned*)(V4 + off_), (LAS unsigned*)(ldsb + BUF[k_] + 1024 * i_), 16, 0, 0); } } while (0)
; __device__ __forceinline__ void peer_v_tokens(int j, const LAS unsigned short* EL, const LAS unsigned char* AL  , const LAS float* ASC  , const LAS int* SAL  , ...
;     ...
;         for (int st = 0; st < 16; ++st) {
;             const int p = st >> 2, q = st & 3;
;             if (st < 14) VDMA(st + 2, (st + 2) % 3);
;             if (st < 14) asm volatile("s_waitcnt vmcnt(8)" ::: "memory");
;             else if (st == 14) asm volatile("s_waitcnt vmcnt(4)" ::: "memory");
;             else asm volatile("s_waitcnt vmcnt(0)" ::: "memory");
;             if (q == 0) {
; #pragma unroll
;                 for (int r = 0; r < 4; ++r) { accH[r] = 0; accL[r] = 0; } }
; #pragma unroll
;             for (int tp = 0; tp < 2; ++tp) {
;                 const v2i ao = TR4(ATL + (2 * q + tp) * 128 + 8 * s16), ah = TR4(ATL + 1024 + (2 * q + tp) * 128 + 8 * s16);
; #pragma unroll
;                 for (int r = 0; r < 4; ++r) {
;                     const v2i d = TR4(ldsb + BUF[st % 3] + 2048 * tp + roff[r]);
;                     accH[r] = __builtin_amdgcn_sdot8(d.x, ah.x, accH[r], false); accH[r] = __builtin_amdgcn_sdot8(d.y, ah.y, accH[r], false);
;                     accL[r] = __builtin_amdgcn_sdot8(d.x, ao.x, accL[r], false); accL[r] = __builtin_amdgcn_sdot8(d.y, ao.y, accL[r], false);
;                 }
;             }
	v_add_u32_e32 v54, s77, v59
	v_add_u32_e32 v55, s77, v60
	v_add_u32_e32 v56, s77, v61
	v_add_u32_e32 v57, s77, v62
	ds_read_b64_tr_b4 v[50:51], v160 offset:128
	ds_read_b64_tr_b4 v[52:53], v160 offset:1152
	ds_read_b64_tr_b4 v[130:131], v54
	ds_read_b64_tr_b4 v[132:133], v55
	ds_read_b64_tr_b4 v[134:135], v56
	ds_read_b64_tr_b4 v[136:137], v57
	s_waitcnt lgkmcnt(12)
	v_dot8c_i32_i4_e32 v38, v122, v48
	v_dot8c_i32_i4_e32 v39, v122, v46
	v_dot8c_i32_i4_e32 v40, v124, v48
	v_dot8c_i32_i4_e32 v41, v124, v46
	v_dot8c_i32_i4_e32 v42, v126, v48
	v_dot8c_i32_i4_e32 v43, v126, v46
	v_dot8c_i32_i4_e32 v44, v128, v48
	v_dot8c_i32_i4_e32 v45, v128, v46
	v_dot8c_i32_i4_e32 v38, v123, v49
	v_dot8c_i32_i4_e32 v39, v123, v47
	v_dot8c_i32_i4_e32 v40, v125, v49
	v_dot8c_i32_i4_e32 v41, v125, v47
	v_dot8c_i32_i4_e32 v42, v127, v49
	v_dot8c_i32_i4_e32 v43, v127, v47
	v_dot8c_i32_i4_e32 v44, v129, v49
	v_dot8c_i32_i4_e32 v45, v129, v47
	v_and_b32_e32 v78, 0xffff, v24
	v_lshrrev_b32_e32 v79, 16, v24
	v_lshl_add_u32 v78, v78, 7, v152
	v_lshl_add_u32 v79, v79, 7, v153
	s_mov_b32 m0, s76
	s_add_i32 s43, s76, 0x400
	global_load_lds_dwordx4 v78, s[50:51]
	s_mov_b32 m0, s43
	s_nop 0
	global_load_lds_dwordx4 v79, s[50:51]
	s_waitcnt vmcnt(8)
	v_add_u32_e32 v54, s78, v59
	v_add_u32_e32 v55, s78, v60
	v_add_u32_e32 v56, s78, v61
	v_add_u32_e32 v57, s78, v62
	ds_read_b64_tr_b4 v[46:47], v160 offset:256
	ds_read_b64_tr_b4 v[48:49], v160 offset:1280
	ds_read_b64_tr_b4 v[122:123], v54
	ds_read_b64_tr_b4 v[124:125], v55
	ds_read_b64_tr_b4 v[126:127], v56
	ds_read_b64_tr_b4 v[128:129], v57
	s_waitcnt lgkmcnt(6)
	v_dot8c_i32_i4_e32 v38, v130, v52
	v_dot8c_i32_i4_e32 v39, v130, v50
	v_dot8c_i32_i4_e32 v40, v132, v52
	v_dot8c_i32_i4_e32 v41, v132, v50
	v_dot8c_i32_i4_e32 v42, v134, v52
	v_dot8c_i32_i4_e32 v43, v134, v50
	v_dot8c_i32_i4_e32 v44, v136, v52
	v_dot8c_i32_i4_e32 v45, v136, v50
	v_dot8c_i32_i4_e32 v38, v131, v53
	v_dot8c_i32_i4_e32 v39, v131, v51
	v_dot8c_i32_i4_e32 v40, v133, v53
	v_dot8c_i32_i4_e32 v41, v133, v51
	v_dot8c_i32_i4_e32 v42, v135, v53
	v_dot8c_i32_i4_e32 v43, v135, v51
	v_dot8c_i32_i4_e32 v44, v137, v53
	v_dot8c_i32_i4_e32 v45, v137, v51
	v_and_b32_e32 v78, 0xffff, v25
	v_lshrrev_b32_e32 v79, 16, v25
	v_lshl_add_u32 v78, v78, 7, v152
	v_lshl_add_u32 v79, v79, 7, v153
	s_mov_b32 m0, s77
	s_add_i32 s43, s77, 0x400
	global_load_lds_dwordx4 v78, s[50:51]
	s_mov_b32 m0, s43
	s_nop 0
	global_load_lds_dwordx4 v79, s[50:51]
	s_waitcnt vmcnt(8)
	v_add_u32_e32 v54, s79, v59
	v_add_u32_e32 v55, s79, v60
	v_add_u32_e32 v56, s79, v61
	v_add_u32_e32 v57, s79, v62
	ds_read_b64_tr_b4 v[50:51], v160 offset:384
	ds_read_b64_tr_b4 v[52:53], v160 offset:1408
	ds_read_b64_tr_b4 v[130:131], v54
	ds_read_b64_tr_b4 v[132:133], v55
	ds_read_b64_tr_b4 v[134:135], v56
	ds_read_b64_tr_b4 v[136:137], v57
	s_waitcnt lgkmcnt(6)
	v_dot8c_i32_i4_e32 v38, v122, v48
	v_dot8c_i32_i4_e32 v39, v122, v46
	v_dot8c_i32_i4_e32 v40, v124, v48
	v_dot8c_i32_i4_e32 v41, v124, v46
	v_dot8c_i32_i4_e32 v42, v126, v48
	v_dot8c_i32_i4_e32 v43, v126, v46
	v_dot8c_i32_i4_e32 v44, v128, v48
	v_dot8c_i32_i4_e32 v45, v128, v46
	v_dot8c_i32_i4_e32 v38, v123, v49
	v_dot8c_i32_i4_e32 v39, v123, v47
	v_dot8c_i32_i4_e32 v40, v125, v49
	v_dot8c_i32_i4_e32 v41, v125, v47
	v_dot8c_i32_i4_e32 v42, v127, v49
	v_dot8c_i32_i4_e32 v43, v127, v47
	v_dot8c_i32_i4_e32 v44, v129, v49
	v_dot8c_i32_i4_e32 v45, v129, v47
	s_waitcnt lgkmcnt(15)
	v_and_b32_e32 v78, 0xffff, v26
	v_lshrrev_b32_e32 v79, 16, v26
	v_lshl_add_u32 v78, v78, 7, v152
	v_lshl_add_u32 v79, v79, 7, v153
	s_mov_b32 m0, s78
	s_add_i32 s43, s78, 0x400
	global_load_lds_dwordx4 v78, s[50:51]
	s_mov_b32 m0, s43
	s_nop 0
	global_load_lds_dwordx4 v79, s[50:51]
	s_waitcnt vmcnt(8)
	v_add_u32_e32 v54, s98, v59
	v_add_u32_e32 v55, s98, v60
	v_add_u32_e32 v56, s98, v61
	v_add_u32_e32 v57, s98, v62
	ds_read_b64_tr_b4 v[46:47], v160 offset:512
	ds_read_b64_tr_b4 v[48:49], v160 offset:1536
	ds_read_b64_tr_b4 v[122:123], v54
	ds_read_b64_tr_b4 v[124:125], v55
	ds_read_b64_tr_b4 v[126:127], v56
	ds_read_b64_tr_b4 v[128:129], v57
	s_waitcnt lgkmcnt(6)
	v_dot8c_i32_i4_e32 v38, v130, v52
	v_dot8c_i32_i4_e32 v39, v130, v50
	v_dot8c_i32_i4_e32 v40, v132, v52
	v_dot8c_i32_i4_e32 v41, v132, v50
	v_dot8c_i32_i4_e32 v42, v134, v52
	v_dot8c_i32_i4_e32 v43, v134, v50
	v_dot8c_i32_i4_e32 v44, v136, v52
	v_dot8c_i32_i4_e32 v45, v136, v50
	v_dot8c_i32_i4_e32 v38, v131, v53
	v_dot8c_i32_i4_e32 v39, v131, v51
	v_dot8c_i32_i4_e32 v40, v133, v53
	v_dot8c_i32_i4_e32 v41, v133, v51
	v_dot8c_i32_i4_e32 v42, v135, v53
	v_dot8c_i32_i4_e32 v43, v135, v51
	v_dot8c_i32_i4_e32 v44, v137, v53
	v_dot8c_i32_i4_e32 v45, v137, v51
	v_and_b32_e32 v78, 0xffff, v27
	v_lshrrev_b32_e32 v79, 16, v27
	v_lshl_add_u32 v78, v78, 7, v152
	v_lshl_add_u32 v79, v79, 7, v153
	s_mov_b32 m0, s79
	s_add_i32 s43, s79, 0x400
	global_load_lds_dwordx4 v78, s[50:51]
	s_mov_b32 m0, s43
	s_nop 0
	global_load_lds_dwordx4 v79, s[50:51]
	s_waitcnt vmcnt(8)
	v_add_u32_e32 v54, s99, v59
	v_add_u32_e32 v55, s99, v60
	v_add_u32_e32 v56, s99, v61
	v_add_u32_e32 v57, s99, v62
	ds_read_b64_tr_b4 v[50:51], v160 offset:640
	ds_read_b64_tr_b4 v[52:53], v160 offset:1664
	ds_read_b64_tr_b4 v[130:131], v54
	ds_read_b64_tr_b4 v[132:133], v55
	ds_read_b64_tr_b4 v[134:135], v56
	ds_read_b64_tr_b4 v[136:137], v57
	s_waitcnt lgkmcnt(6)
	v_dot8c_i32_i4_e32 v38, v122, v48
	v_dot8c_i32_i4_e32 v39, v122, v46
	v_dot8c_i32_i4_e32 v40, v124, v48
	v_dot8c_i32_i4_e32 v41, v124, v46
	v_dot8c_i32_i4_e32 v42, v126, v48
	v_dot8c_i32_i4_e32 v43, v126, v46
	v_dot8c_i32_i4_e32 v44, v128, v48
	v_dot8c_i32_i4_e32 v45, v128, v46
	v_dot8c_i32_i4_e32 v38, v123, v49
	v_dot8c_i32_i4_e32 v39, v123, v47
	v_dot8c_i32_i4_e32 v40, v125, v49
	v_dot8c_i32_i4_e32 v41, v125, v47
	v_dot8c_i32_i4_e32 v42, v127, v49
	v_dot8c_i32_i4_e32 v43, v127, v47
	v_dot8c_i32_i4_e32 v44, v129, v49
	v_dot8c_i32_i4_e32 v45, v129, v47
	s_waitcnt lgkmcnt(15)
; __device__ __forceinline__ bf16 f2bf(float f) { return (bf16)f2bfu(f); }
; #define TR4(p_) __builtin_amdgcn_ds_read_tr4_b64_v2i32((LAS v2i*)(p_))
; __device__ __forceinline__ void peer_v_tokens(int j, const LAS unsigned short* EL, const LAS unsigned char* AL  , const LAS float* ASC  , const LAS int* SAL  , ...
;     ...
;         uint2 hv[4]; float4 gv[4];
;         { unsigned ho = (unsigned)t * (D / 4) + (unsigned)lane; asm volatile("" : "+v"(ho)); const uint2* hp = (const uint2*)HB + ho; const float4* gp = (const float4*)fng + lane;
; #pragma unroll
;           for (int jq = 0; jq < 4; ++jq) { hv[jq] = hp[64 * jq]; gv[jq] = gp[64 * jq]; } }
;     ...
;         for (int st = 0; st < 16; ++st) {
;             const int p = st >> 2, q = st & 3;
;             if (st < 14) VDMA(st + 2, (st + 2) % 3);
;             if (st < 14) asm volatile("s_waitcnt vmcnt(8)" ::: "memory");
;             else if (st == 14) asm volatile("s_waitcnt vmcnt(4)" ::: "memory");
;             else asm volatile("s_waitcnt vmcnt(0)" ::: "memory");
;             if (q == 0) {
; #pragma unroll
;                 for (int r = 0; r < 4; ++r) { accH[r] = 0; accL[r] = 0; } }
; #pragma unroll
;             for (int tp = 0; tp < 2; ++tp) {
;                 const v2i ao = TR4(ATL + (2 * q + tp) * 128 + 8 * s16), ah = TR4(ATL + 1024 + (2 * q + tp) * 128 + 8 * s16);
; #pragma unroll
;                 for (int r = 0; r < 4; ++r) {
;                     const v2i d = TR4(ldsb + BUF[st % 3] + 2048 * tp + roff[r]);
;                     accH[r] = __builtin_amdgcn_sdot8(d.x, ah.x, accH[r], false); accH[r] = __builtin_amdgcn_sdot8(d.y, ah.y, accH[r], false);
;                     accL[r] = __builtin_amdgcn_sdot8(d.x, ao.x, accL[r], false); accL[r] = __builtin_amdgcn_sdot8(d.y, ao.y, accL[r], false);
;                 }
;             }
;             asm volatile("s_waitcnt lgkmcnt(0)" ::: "memory");
;             if (q == 3) {
; #pragma unroll
;                 for (int r = 0; r < 4; ++r) STASH[256 * p + 16 * (grp + 4 * r) + pc] = f2bf(asc * (float)(2 * ((accH[r] << 4) + accL[r]) + sa));
;             }
	v_add_u32_e32 v143, 8, v139
	v_and_b32_e32 v142, 15, v143
	v_xor_b32_e32 v142, 8, v142
	v_bfe_u32 v144, v143, 4, 4
	v_mul_lo_u32 v142, v142, s92
	v_mul_lo_u32 v144, v144, s92
	v_mov_b32_e32 v143, v142
	v_mov_b32_e32 v145, v144
	ds_write2st64_b64 v159, v[142:143], v[144:145] offset1:2
	v_and_b32_e32 v78, 0xffff, v28
	v_lshrrev_b32_e32 v79, 16, v28
	v_lshl_add_u32 v78, v78, 7, v152
	v_lshl_add_u32 v79, v79, 7, v153
	s_mov_b32 m0, s98
	s_add_i32 s43, s98, 0x400
	global_load_lds_dwordx4 v78, s[50:51]
	s_mov_b32 m0, s43
	s_nop 0
	global_load_lds_dwordx4 v79, s[50:51]
	s_waitcnt vmcnt(8)
	v_add_u32_e32 v54, s76, v59
	v_add_u32_e32 v55, s76, v60
	v_add_u32_e32 v56, s76, v61
	v_add_u32_e32 v57, s76, v62
	ds_read_b64_tr_b4 v[46:47], v160 offset:768
	ds_read_b64_tr_b4 v[48:49], v160 offset:1792
	ds_read_b64_tr_b4 v[122:123], v54
	ds_read_b64_tr_b4 v[124:125], v55
	ds_read_b64_tr_b4 v[126:127], v56
	ds_read_b64_tr_b4 v[128:129], v57
	s_waitcnt lgkmcnt(7)
	v_dot8c_i32_i4_e32 v38, v130, v52
	v_dot8c_i32_i4_e32 v39, v130, v50
	v_dot8c_i32_i4_e32 v40, v132, v52
	v_dot8c_i32_i4_e32 v41, v132, v50
	v_dot8c_i32_i4_e32 v42, v134, v52
	v_dot8c_i32_i4_e32 v43, v134, v50
	v_dot8c_i32_i4_e32 v44, v136, v52
	v_dot8c_i32_i4_e32 v45, v136, v50
	v_dot8c_i32_i4_e32 v38, v131, v53
	v_dot8c_i32_i4_e32 v39, v131, v51
	v_dot8c_i32_i4_e32 v40, v133, v53
	v_dot8c_i32_i4_e32 v41, v133, v51
	v_dot8c_i32_i4_e32 v42, v135, v53
	v_dot8c_i32_i4_e32 v43, v135, v51
	v_dot8c_i32_i4_e32 v44, v137, v53
	v_dot8c_i32_i4_e32 v45, v137, v51
	v_and_b32_e32 v78, 0xffff, v29
	v_lshrrev_b32_e32 v79, 16, v29
	v_lshl_add_u32 v78, v78, 7, v152
	v_lshl_add_u32 v79, v79, 7, v153
	s_mov_b32 m0, s99
	s_add_i32 s43, s99, 0x400
	global_load_lds_dwordx4 v78, s[50:51]
	s_mov_b32 m0, s43
	s_nop 0
	global_load_lds_dwordx4 v79, s[50:51]
	s_waitcnt vmcnt(8)
	v_add_u32_e32 v54, s77, v59
	v_add_u32_e32 v55, s77, v60
	v_add_u32_e32 v56, s77, v61
	v_add_u32_e32 v57, s77, v62
	ds_read_b64_tr_b4 v[50:51], v160 offset:896
	ds_read_b64_tr_b4 v[52:53], v160 offset:1920
	ds_read_b64_tr_b4 v[130:131], v54
	ds_read_b64_tr_b4 v[132:133], v55
	ds_read_b64_tr_b4 v[134:135], v56
	ds_read_b64_tr_b4 v[136:137], v57
	s_waitcnt lgkmcnt(6)
	v_dot8c_i32_i4_e32 v38, v122, v48
	v_dot8c_i32_i4_e32 v39, v122, v46
	v_dot8c_i32_i4_e32 v40, v124, v48
	v_dot8c_i32_i4_e32 v41, v124, v46
	v_dot8c_i32_i4_e32 v42, v126, v48
	v_dot8c_i32_i4_e32 v43, v126, v46
	v_dot8c_i32_i4_e32 v44, v128, v48
	v_dot8c_i32_i4_e32 v45, v128, v46
	v_dot8c_i32_i4_e32 v38, v123, v49
	v_dot8c_i32_i4_e32 v39, v123, v47
	v_dot8c_i32_i4_e32 v40, v125, v49
	v_dot8c_i32_i4_e32 v41, v125, v47
	v_dot8c_i32_i4_e32 v42, v127, v49
	v_dot8c_i32_i4_e32 v43, v127, v47
	v_dot8c_i32_i4_e32 v44, v129, v49
	v_dot8c_i32_i4_e32 v45, v129, v47
	v_and_b32_e32 v78, 0xffff, v30
	v_lshrrev_b32_e32 v79, 16, v30
	v_lshl_add_u32 v78, v78, 7, v152
	v_lshl_add_u32 v79, v79, 7, v153
	s_mov_b32 m0, s76
	s_add_i32 s43, s76, 0x400
	global_load_lds_dwordx4 v78, s[50:51]
	s_mov_b32 m0, s43
	s_nop 0
	global_load_lds_dwordx4 v79, s[50:51]
	s_waitcnt vmcnt(8)
	v_add_u32_e32 v54, s78, v59
	v_add_u32_e32 v55, s78, v60
	v_add_u32_e32 v56, s78, v61
	v_add_u32_e32 v57, s78, v62
	ds_read_b64_tr_b4 v[46:47], v160
	ds_read_b64_tr_b4 v[48:49], v160 offset:1024
	ds_read_b64_tr_b4 v[122:123], v54
	ds_read_b64_tr_b4 v[124:125], v55
	ds_read_b64_tr_b4 v[126:127], v56
	ds_read_b64_tr_b4 v[128:129], v57
	s_waitcnt lgkmcnt(6)
	v_dot8c_i32_i4_e32 v38, v130, v52
	v_dot8c_i32_i4_e32 v39, v130, v50
	v_dot8c_i32_i4_e32 v40, v132, v52
	v_dot8c_i32_i4_e32 v41, v132, v50
	v_dot8c_i32_i4_e32 v42, v134, v52
	v_dot8c_i32_i4_e32 v43, v134, v50
	v_dot8c_i32_i4_e32 v44, v136, v52
	v_dot8c_i32_i4_e32 v45, v136, v50
	v_dot8c_i32_i4_e32 v38, v131, v53
	v_dot8c_i32_i4_e32 v39, v131, v51
	v_dot8c_i32_i4_e32 v40, v133, v53
	v_dot8c_i32_i4_e32 v41, v133, v51
	v_dot8c_i32_i4_e32 v42, v135, v53
	v_dot8c_i32_i4_e32 v43, v135, v51
	v_dot8c_i32_i4_e32 v44, v137, v53
	v_dot8c_i32_i4_e32 v45, v137, v51
	s_nop 3
	s_waitcnt lgkmcnt(15)
	v_lshlrev_b32_e32 v38, 5, v38
	v_lshlrev_b32_e32 v39, 1, v39
	v_add3_u32 v38, v39, v229, v38
	v_cvt_f32_i32_e32 v38, v38
	v_mul_f32_e32 v38, v228, v38
	v_lshlrev_b32_e32 v40, 5, v40
	v_lshlrev_b32_e32 v41, 1, v41
	v_add3_u32 v40, v41, v229, v40
	v_cvt_f32_i32_e32 v40, v40
	v_mul_f32_e32 v40, v228, v40
	v_lshlrev_b32_e32 v42, 5, v42
	v_lshlrev_b32_e32 v43, 1, v43
	v_add3_u32 v42, v43, v229, v42
	v_cvt_f32_i32_e32 v42, v42
	v_mul_f32_e32 v42, v228, v42
	v_lshlrev_b32_e32 v44, 5, v44
	v_lshlrev_b32_e32 v45, 1, v45
	v_add3_u32 v44, v45, v229, v44
	v_cvt_f32_i32_e32 v44, v44
	v_mul_f32_e32 v44, v228, v44
	v_cvt_pk_bf16_f32 v168, v38, v40
	v_cvt_pk_bf16_f32 v169, v42, v44
	s_add_i32 s43, s40, 0
	s_lshl_b32 s43, s43, 11
	v_add_u32_e32 v138, s43, v66
	global_load_dwordx2 v[194:195], v138, s[70:71]
	global_load_dwordx2 v[196:197], v138, s[70:71] offset:512
	global_load_dwordx2 v[198:199], v138, s[70:71] offset:1024
	global_load_dwordx2 v[200:201], v138, s[70:71] offset:1536
	v_add_u32_e32 v147, 8, v140
	v_and_b32_e32 v146, 15, v147
	v_xor_b32_e32 v146, 8, v146
	v_bfe_u32 v148, v147, 4, 4
	v_mul_lo_u32 v146, v146, s92
	v_mul_lo_u32 v148, v148, s92
	v_mov_b32_e32 v147, v146
	v_mov_b32_e32 v149, v148
	ds_write2st64_b64 v77, v[146:147], v[148:149] offset1:2
	v_add_u32_e32 v138, 0x800, v74
	ds_read_u8 v139, v138
	v_add_u32_e32 v141, 0x800, v73
	ds_read_u8 v140, v141
	s_add_i32 s43, s67, 32
	v_mov_b32_e32 v138, s43
	ds_read2st64_b32 v[228:229], v138 offset1:1
	ds_read_b128 v[18:21], v227 offset:4096
	ds_read_b128 v[22:25], v227 offset:4112
	v_mov_b32_e32 v150, v63
	v_mov_b32_e32 v151, v64
	v_mov_b32_e32 v38, 0
	v_mov_b32_e32 v39, 0
	v_mov_b32_e32 v40, 0
	v_mov_b32_e32 v41, 0
	v_mov_b32_e32 v42, 0
	v_mov_b32_e32 v43, 0
	v_mov_b32_e32 v44, 0
	v_mov_b32_e32 v45, 0
	v_and_b32_e32 v78, 0xffff, v31
	v_lshrrev_b32_e32 v79, 16, v31
	v_lshl_add_u32 v78, v78, 7, v152
	v_lshl_add_u32 v79, v79, 7, v153
	s_mov_b32 m0, s77
	s_add_i32 s43, s77, 0x400
	global_load_lds_dwordx4 v78, s[50:51]
	s_mov_b32 m0, s43
	s_nop 0
	global_load_lds_dwordx4 v79, s[50:51]
	s_waitcnt vmcnt(12)
; #define TR4(p_) __builtin_amdgcn_ds_read_tr4_b64_v2i32((LAS v2i*)(p_))
; #define VDMA(st_, k_) do { _Pragma("unroll") for (int i_ = 0; i_ < 4; ++i_) { \
;         const unsigned off_ = (unsigned)((st_) >> 2) * (16384u * 128u) + (PE_ID(E, 4 * ((st_) & 3) + i_) << 7) + ((i_ & 1) ? cx1 : cx0); \
;         __builtin_amdgcn_global_load_lds((const unsigned*)(V4 + off_), (LAS unsigned*)(ldsb + BUF[k_] + 1024 * i_), 16, 0, 0); } } while (0)
; __device__ __forceinline__ void peer_v_tokens(int j, const LAS unsigned short* EL, const LAS unsigned char* AL  , const LAS float* ASC  , const LAS int* SAL  , ...
;     ...
;         for (int st = 0; st < 16; ++st) {
;             const int p = st >> 2, q = st & 3;
;             if (st < 14) VDMA(st + 2, (st + 2) % 3);
;             if (st < 14) asm volatile("s_waitcnt vmcnt(8)" ::: "memory");
;             else if (st == 14) asm volatile("s_waitcnt vmcnt(4)" ::: "memory");
;             else asm volatile("s_waitcnt vmcnt(0)" ::: "memory");
;             if (q == 0) {
; #pragma unroll
;                 for (int r = 0; r < 4; ++r) { accH[r] = 0; accL[r] = 0; } }
; #pragma unroll
;             for (int tp = 0; tp < 2; ++tp) {
;                 const v2i ao = TR4(ATL + (2 * q + tp) * 128 + 8 * s16), ah = TR4(ATL + 1024 + (2 * q + tp) * 128 + 8 * s16);
; #pragma unroll
;                 for (int r = 0; r < 4; ++r) {
;                     const v2i d = TR4(ldsb + BUF[st % 3] + 2048 * tp + roff[r]);
;                     accH[r] = __builtin_amdgcn_sdot8(d.x, ah.x, accH[r], false); accH[r] = __builtin_amdgcn_sdot8(d.y, ah.y, accH[r], false);
;                     accL[r] = __builtin_amdgcn_sdot8(d.x, ao.x, accL[r], false); accL[r] = __builtin_amdgcn_sdot8(d.y, ao.y, accL[r], false);
;                 }
;             }
	v_add_u32_e32 v54, s79, v59
	v_add_u32_e32 v55, s79, v60
	v_add_u32_e32 v56, s79, v61
	v_add_u32_e32 v57, s79, v62
	ds_read_b64_tr_b4 v[50:51], v160 offset:128
	ds_read_b64_tr_b4 v[52:53], v160 offset:1152
	ds_read_b64_tr_b4 v[130:131], v54
	ds_read_b64_tr_b4 v[132:133], v55
	ds_read_b64_tr_b4 v[134:135], v56
	ds_read_b64_tr_b4 v[136:137], v57
	s_waitcnt lgkmcnt(12)
	v_dot8c_i32_i4_e32 v38, v122, v48
	v_dot8c_i32_i4_e32 v39, v122, v46
	v_dot8c_i32_i4_e32 v40, v124, v48
	v_dot8c_i32_i4_e32 v41, v124, v46
	v_dot8c_i32_i4_e32 v42, v126, v48
	v_dot8c_i32_i4_e32 v43, v126, v46
	v_dot8c_i32_i4_e32 v44, v128, v48
	v_dot8c_i32_i4_e32 v45, v128, v46
	v_dot8c_i32_i4_e32 v38, v123, v49
	v_dot8c_i32_i4_e32 v39, v123, v47
	v_dot8c_i32_i4_e32 v40, v125, v49
	v_dot8c_i32_i4_e32 v41, v125, v47
	v_dot8c_i32_i4_e32 v42, v127, v49
	v_dot8c_i32_i4_e32 v43, v127, v47
	v_dot8c_i32_i4_e32 v44, v129, v49
	v_dot8c_i32_i4_e32 v45, v129, v47
	v_and_b32_e32 v78, 0xffff, v32
	v_lshrrev_b32_e32 v79, 16, v32
	v_lshl_add_u32 v78, v78, 7, v152
	v_lshl_add_u32 v79, v79, 7, v153
	s_mov_b32 m0, s78
	s_add_i32 s43, s78, 0x400
	global_load_lds_dwordx4 v78, s[50:51]
	s_mov_b32 m0, s43
	s_nop 0
	global_load_lds_dwordx4 v79, s[50:51]
	s_waitcnt vmcnt(12)
	v_add_u32_e32 v54, s98, v59
	v_add_u32_e32 v55, s98, v60
	v_add_u32_e32 v56, s98, v61
	v_add_u32_e32 v57, s98, v62
	ds_read_b64_tr_b4 v[46:47], v160 offset:256
	ds_read_b64_tr_b4 v[48:49], v160 offset:1280
	ds_read_b64_tr_b4 v[122:123], v54
	ds_read_b64_tr_b4 v[124:125], v55
	ds_read_b64_tr_b4 v[126:127], v56
	ds_read_b64_tr_b4 v[128:129], v57
	s_waitcnt lgkmcnt(6)
	v_dot8c_i32_i4_e32 v38, v130, v52
	v_dot8c_i32_i4_e32 v39, v130, v50
	v_dot8c_i32_i4_e32 v40, v132, v52
	v_dot8c_i32_i4_e32 v41, v132, v50
	v_dot8c_i32_i4_e32 v42, v134, v52
	v_dot8c_i32_i4_e32 v43, v134, v50
	v_dot8c_i32_i4_e32 v44, v136, v52
	v_dot8c_i32_i4_e32 v45, v136, v50
	v_dot8c_i32_i4_e32 v38, v131, v53
	v_dot8c_i32_i4_e32 v39, v131, v51
	v_dot8c_i32_i4_e32 v40, v133, v53
	v_dot8c_i32_i4_e32 v41, v133, v51
	v_dot8c_i32_i4_e32 v42, v135, v53
	v_dot8c_i32_i4_e32 v43, v135, v51
	v_dot8c_i32_i4_e32 v44, v137, v53
	v_dot8c_i32_i4_e32 v45, v137, v51
	v_and_b32_e32 v78, 0xffff, v33
	v_lshrrev_b32_e32 v79, 16, v33
	v_lshl_add_u32 v78, v78, 7, v152
	v_lshl_add_u32 v79, v79, 7, v153
	s_mov_b32 m0, s79
	s_add_i32 s43, s79, 0x400
	global_load_lds_dwordx4 v78, s[50:51]
	s_mov_b32 m0, s43
	s_nop 0
	global_load_lds_dwordx4 v79, s[50:51]
	s_waitcnt vmcnt(12)
	v_add_u32_e32 v54, s99, v59
	v_add_u32_e32 v55, s99, v60
	v_add_u32_e32 v56, s99, v61
	v_add_u32_e32 v57, s99, v62
	ds_read_b64_tr_b4 v[50:51], v160 offset:384
	ds_read_b64_tr_b4 v[52:53], v160 offset:1408
	ds_read_b64_tr_b4 v[130:131], v54
	ds_read_b64_tr_b4 v[132:133], v55
	ds_read_b64_tr_b4 v[134:135], v56
	ds_read_b64_tr_b4 v[136:137], v57
	s_waitcnt lgkmcnt(6)
	v_dot8c_i32_i4_e32 v38, v122, v48
	v_dot8c_i32_i4_e32 v39, v122, v46
	v_dot8c_i32_i4_e32 v40, v124, v48
	v_dot8c_i32_i4_e32 v41, v124, v46
	v_dot8c_i32_i4_e32 v42, v126, v48
	v_dot8c_i32_i4_e32 v43, v126, v46
	v_dot8c_i32_i4_e32 v44, v128, v48
	v_dot8c_i32_i4_e32 v45, v128, v46
	v_dot8c_i32_i4_e32 v38, v123, v49
	v_dot8c_i32_i4_e32 v39, v123, v47
	v_dot8c_i32_i4_e32 v40, v125, v49
	v_dot8c_i32_i4_e32 v41, v125, v47
	v_dot8c_i32_i4_e32 v42, v127, v49
	v_dot8c_i32_i4_e32 v43, v127, v47
	v_dot8c_i32_i4_e32 v44, v129, v49
	v_dot8c_i32_i4_e32 v45, v129, v47
	s_waitcnt lgkmcnt(15)
	v_and_b32_e32 v78, 0xffff, v18
	v_lshrrev_b32_e32 v79, 16, v18
	v_lshl_add_u32 v78, v78, 7, v150
	v_lshl_add_u32 v79, v79, 7, v151
	s_mov_b32 m0, s98
	s_add_i32 s43, s98, 0x400
	global_load_lds_dwordx4 v78, s[50:51]
	s_mov_b32 m0, s43
	s_nop 0
	global_load_lds_dwordx4 v79, s[50:51]
	s_waitcnt vmcnt(12)
	v_add_u32_e32 v54, s76, v59
	v_add_u32_e32 v55, s76, v60
	v_add_u32_e32 v56, s76, v61
	v_add_u32_e32 v57, s76, v62
	ds_read_b64_tr_b4 v[46:47], v160 offset:512
	ds_read_b64_tr_b4 v[48:49], v160 offset:1536
	ds_read_b64_tr_b4 v[122:123], v54
	ds_read_b64_tr_b4 v[124:125], v55
	ds_read_b64_tr_b4 v[126:127], v56
	ds_read_b64_tr_b4 v[128:129], v57
	s_waitcnt lgkmcnt(6)
	v_dot8c_i32_i4_e32 v38, v130, v52
	v_dot8c_i32_i4_e32 v39, v130, v50
	v_dot8c_i32_i4_e32 v40, v132, v52
	v_dot8c_i32_i4_e32 v41, v132, v50
	v_dot8c_i32_i4_e32 v42, v134, v52
	v_dot8c_i32_i4_e32 v43, v134, v50
	v_dot8c_i32_i4_e32 v44, v136, v52
	v_dot8c_i32_i4_e32 v45, v136, v50
	v_dot8c_i32_i4_e32 v38, v131, v53
	v_dot8c_i32_i4_e32 v39, v131, v51
	v_dot8c_i32_i4_e32 v40, v133, v53
	v_dot8c_i32_i4_e32 v41, v133, v51
	v_dot8c_i32_i4_e32 v42, v135, v53
	v_dot8c_i32_i4_e32 v43, v135, v51
	v_dot8c_i32_i4_e32 v44, v137, v53
	v_dot8c_i32_i4_e32 v45, v137, v51
	v_and_b32_e32 v78, 0xffff, v19
	v_lshrrev_b32_e32 v79, 16, v19
	v_lshl_add_u32 v78, v78, 7, v150
	v_lshl_add_u32 v79, v79, 7, v151
	s_mov_b32 m0, s99
	s_add_i32 s43, s99, 0x400
	global_load_lds_dwordx4 v78, s[50:51]
	s_mov_b32 m0, s43
	s_nop 0
	global_load_lds_dwordx4 v79, s[50:51]
	s_waitcnt vmcnt(8)
	v_add_u32_e32 v54, s77, v59
	v_add_u32_e32 v55, s77, v60
	v_add_u32_e32 v56, s77, v61
	v_add_u32_e32 v57, s77, v62
	ds_read_b64_tr_b4 v[50:51], v160 offset:640
	ds_read_b64_tr_b4 v[52:53], v160 offset:1664
	ds_read_b64_tr_b4 v[130:131], v54
	ds_read_b64_tr_b4 v[132:133], v55
	ds_read_b64_tr_b4 v[134:135], v56
	ds_read_b64_tr_b4 v[136:137], v57
	s_waitcnt lgkmcnt(6)
	v_dot8c_i32_i4_e32 v38, v122, v48
	v_dot8c_i32_i4_e32 v39, v122, v46
	v_dot8c_i32_i4_e32 v40, v124, v48
	v_dot8c_i32_i4_e32 v41, v124, v46
	v_dot8c_i32_i4_e32 v42, v126, v48
	v_dot8c_i32_i4_e32 v43, v126, v46
	v_dot8c_i32_i4_e32 v44, v128, v48
	v_dot8c_i32_i4_e32 v45, v128, v46
	v_dot8c_i32_i4_e32 v38, v123, v49
	v_dot8c_i32_i4_e32 v39, v123, v47
	v_dot8c_i32_i4_e32 v40, v125, v49
	v_dot8c_i32_i4_e32 v41, v125, v47
	v_dot8c_i32_i4_e32 v42, v127, v49
	v_dot8c_i32_i4_e32 v43, v127, v47
	v_dot8c_i32_i4_e32 v44, v129, v49
	v_dot8c_i32_i4_e32 v45, v129, v47
	s_waitcnt lgkmcnt(15)
; #define LAS __attribute__((address_space(3)))
; __device__ __forceinline__ bf16 f2bf(float f) { return (bf16)f2bfu(f); }
; #define TR4(p_) __builtin_amdgcn_ds_read_tr4_b64_v2i32((LAS v2i*)(p_))
; __device__ __forceinline__ void peer_v_tokens(int j, const LAS unsigned short* EL, const LAS unsigned char* AL  , const LAS float* ASC  , const LAS int* SAL  , ...
;     ...
;             const unsigned lo = (((unsigned)tq & 15u) ^ 8u) * 0x11111111u, hi = ((unsigned)(tq >> 4) & 15u) * 0x11111111u;
;             typedef unsigned u2v __attribute__((ext_vector_type(2)));
;             u2v l2; l2.x = lo; l2.y = lo; u2v h2; h2.x = hi; h2.y = hi;
;             *(LAS u2v*)(ATL + 8 * idx) = l2; *(LAS u2v*)(ATL + 1024 + 8 * idx) = h2;
;     ...
;         for (int st = 0; st < 16; ++st) {
;             const int p = st >> 2, q = st & 3;
;             if (st < 14) VDMA(st + 2, (st + 2) % 3);
;             if (st < 14) asm volatile("s_waitcnt vmcnt(8)" ::: "memory");
;             else if (st == 14) asm volatile("s_waitcnt vmcnt(4)" ::: "memory");
;             else asm volatile("s_waitcnt vmcnt(0)" ::: "memory");
;             if (q == 0) {
; #pragma unroll
;                 for (int r = 0; r < 4; ++r) { accH[r] = 0; accL[r] = 0; } }
; #pragma unroll
;             for (int tp = 0; tp < 2; ++tp) {
;                 const v2i ao = TR4(ATL + (2 * q + tp) * 128 + 8 * s16), ah = TR4(ATL + 1024 + (2 * q + tp) * 128 + 8 * s16);
; #pragma unroll
;                 for (int r = 0; r < 4; ++r) {
;                     const v2i d = TR4(ldsb + BUF[st % 3] + 2048 * tp + roff[r]);
;                     accH[r] = __builtin_amdgcn_sdot8(d.x, ah.x, accH[r], false); accH[r] = __builtin_amdgcn_sdot8(d.y, ah.y, accH[r], false);
;                     accL[r] = __builtin_amdgcn_sdot8(d.x, ao.x, accL[r], false); accL[r] = __builtin_amdgcn_sdot8(d.y, ao.y, accL[r], false);
;                 }
;             }
;             asm volatile("s_waitcnt lgkmcnt(0)" ::: "memory");
;             if (q == 3) {
; #pragma unroll
;                 for (int r = 0; r < 4; ++r) STASH[256 * p + 16 * (grp + 4 * r) + pc] = f2bf(asc * (float)(2 * ((accH[r] << 4) + accL[r]) + sa));
;             }
	v_add_u32_e32 v143, 8, v139
	v_and_b32_e32 v142, 15, v143
	v_xor_b32_e32 v142, 8, v142
	v_bfe_u32 v144, v143, 4, 4
	v_mul_lo_u32 v142, v142, s92
	v_mul_lo_u32 v144, v144, s92
	v_mov_b32_e32 v143, v142
	v_mov_b32_e32 v145, v144
	ds_write2st64_b64 v159, v[142:143], v[144:145] offset1:2
	v_and_b32_e32 v78, 0xffff, v20
	v_lshrrev_b32_e32 v79, 16, v20
	v_lshl_add_u32 v78, v78, 7, v150
	v_lshl_add_u32 v79, v79, 7, v151
	s_mov_b32 m0, s76
	s_add_i32 s43, s76, 0x400
	global_load_lds_dwordx4 v78, s[50:51]
	s_mov_b32 m0, s43
	s_nop 0
	global_load_lds_dwordx4 v79, s[50:51]
	s_waitcnt vmcnt(8)
	v_add_u32_e32 v54, s78, v59
	v_add_u32_e32 v55, s78, v60
	v_add_u32_e32 v56, s78, v61
	v_add_u32_e32 v57, s78, v62
	ds_read_b64_tr_b4 v[46:47], v160 offset:768
	ds_read_b64_tr_b4 v[48:49], v160 offset:1792
	ds_read_b64_tr_b4 v[122:123], v54
	ds_read_b64_tr_b4 v[124:125], v55
	ds_read_b64_tr_b4 v[126:127], v56
	ds_read_b64_tr_b4 v[128:129], v57
	s_waitcnt lgkmcnt(7)
	v_dot8c_i32_i4_e32 v38, v130, v52
	v_dot8c_i32_i4_e32 v39, v130, v50
	v_dot8c_i32_i4_e32 v40, v132, v52
	v_dot8c_i32_i4_e32 v41, v132, v50
	v_dot8c_i32_i4_e32 v42, v134, v52
	v_dot8c_i32_i4_e32 v43, v134, v50
	v_dot8c_i32_i4_e32 v44, v136, v52
	v_dot8c_i32_i4_e32 v45, v136, v50
	v_dot8c_i32_i4_e32 v38, v131, v53
	v_dot8c_i32_i4_e32 v39, v131, v51
	v_dot8c_i32_i4_e32 v40, v133, v53
	v_dot8c_i32_i4_e32 v41, v133, v51
	v_dot8c_i32_i4_e32 v42, v135, v53
	v_dot8c_i32_i4_e32 v43, v135, v51
	v_dot8c_i32_i4_e32 v44, v137, v53
	v_dot8c_i32_i4_e32 v45, v137, v51
	v_and_b32_e32 v78, 0xffff, v21
	v_lshrrev_b32_e32 v79, 16, v21
	v_lshl_add_u32 v78, v78, 7, v150
	v_lshl_add_u32 v79, v79, 7, v151
	s_mov_b32 m0, s77
	s_add_i32 s43, s77, 0x400
	global_load_lds_dwordx4 v78, s[50:51]
	s_mov_b32 m0, s43
	s_nop 0
	global_load_lds_dwordx4 v79, s[50:51]
	s_waitcnt vmcnt(8)
	v_add_u32_e32 v54, s79, v59
	v_add_u32_e32 v55, s79, v60
	v_add_u32_e32 v56, s79, v61
	v_add_u32_e32 v57, s79, v62
	ds_read_b64_tr_b4 v[50:51], v160 offset:896
	ds_read_b64_tr_b4 v[52:53], v160 offset:1920
	ds_read_b64_tr_b4 v[130:131], v54
	ds_read_b64_tr_b4 v[132:133], v55
	ds_read_b64_tr_b4 v[134:135], v56
	ds_read_b64_tr_b4 v[136:137], v57
	s_waitcnt lgkmcnt(6)
	v_dot8c_i32_i4_e32 v38, v122, v48
	v_dot8c_i32_i4_e32 v39, v122, v46
	v_dot8c_i32_i4_e32 v40, v124, v48
	v_dot8c_i32_i4_e32 v41, v124, v46
	v_dot8c_i32_i4_e32 v42, v126, v48
	v_dot8c_i32_i4_e32 v43, v126, v46
	v_dot8c_i32_i4_e32 v44, v128, v48
	v_dot8c_i32_i4_e32 v45, v128, v46
	v_dot8c_i32_i4_e32 v38, v123, v49
	v_dot8c_i32_i4_e32 v39, v123, v47
	v_dot8c_i32_i4_e32 v40, v125, v49
	v_dot8c_i32_i4_e32 v41, v125, v47
	v_dot8c_i32_i4_e32 v42, v127, v49
	v_dot8c_i32_i4_e32 v43, v127, v47
	v_dot8c_i32_i4_e32 v44, v129, v49
	v_dot8c_i32_i4_e32 v45, v129, v47
	v_and_b32_e32 v78, 0xffff, v22
	v_lshrrev_b32_e32 v79, 16, v22
	v_lshl_add_u32 v78, v78, 7, v150
	v_lshl_add_u32 v79, v79, 7, v151
	s_mov_b32 m0, s78
	s_add_i32 s43, s78, 0x400
	global_load_lds_dwordx4 v78, s[50:51]
	s_mov_b32 m0, s43
	s_nop 0
	global_load_lds_dwordx4 v79, s[50:51]
	s_waitcnt vmcnt(8)
	v_add_u32_e32 v54, s98, v59
	v_add_u32_e32 v55, s98, v60
	v_add_u32_e32 v56, s98, v61
	v_add_u32_e32 v57, s98, v62
	ds_read_b64_tr_b4 v[46:47], v160
	ds_read_b64_tr_b4 v[48:49], v160 offset:1024
	ds_read_b64_tr_b4 v[122:123], v54
	ds_read_b64_tr_b4 v[124:125], v55
	ds_read_b64_tr_b4 v[126:127], v56
	ds_read_b64_tr_b4 v[128:129], v57
	s_waitcnt lgkmcnt(6)
	v_dot8c_i32_i4_e32 v38, v130, v52
	v_dot8c_i32_i4_e32 v39, v130, v50
	v_dot8c_i32_i4_e32 v40, v132, v52
	v_dot8c_i32_i4_e32 v41, v132, v50
	v_dot8c_i32_i4_e32 v42, v134, v52
	v_dot8c_i32_i4_e32 v43, v134, v50
	v_dot8c_i32_i4_e32 v44, v136, v52
	v_dot8c_i32_i4_e32 v45, v136, v50
	v_dot8c_i32_i4_e32 v38, v131, v53
	v_dot8c_i32_i4_e32 v39, v131, v51
	v_dot8c_i32_i4_e32 v40, v133, v53
	v_dot8c_i32_i4_e32 v41, v133, v51
	v_dot8c_i32_i4_e32 v42, v135, v53
	v_dot8c_i32_i4_e32 v43, v135, v51
	v_dot8c_i32_i4_e32 v44, v137, v53
	v_dot8c_i32_i4_e32 v45, v137, v51
	s_nop 3
	s_waitcnt lgkmcnt(15)
	v_lshlrev_b32_e32 v38, 5, v38
	v_lshlrev_b32_e32 v39, 1, v39
	v_add3_u32 v38, v39, v229, v38
	v_cvt_f32_i32_e32 v38, v38
	v_mul_f32_e32 v38, v228, v38
	v_lshlrev_b32_e32 v40, 5, v40
	v_lshlrev_b32_e32 v41, 1, v41
	v_add3_u32 v40, v41, v229, v40
	v_cvt_f32_i32_e32 v40, v40
	v_mul_f32_e32 v40, v228, v40
	v_lshlrev_b32_e32 v42, 5, v42
	v_lshlrev_b32_e32 v43, 1, v43
	v_add3_u32 v42, v43, v229, v42
	v_cvt_f32_i32_e32 v42, v42
	v_mul_f32_e32 v42, v228, v42
	v_lshlrev_b32_e32 v44, 5, v44
	v_lshlrev_b32_e32 v45, 1, v45
	v_add3_u32 v44, v45, v229, v44
	v_cvt_f32_i32_e32 v44, v44
	v_mul_f32_e32 v44, v228, v44
	v_cvt_pk_bf16_f32 v176, v38, v40
	v_cvt_pk_bf16_f32 v177, v42, v44
	v_add_u32_e32 v147, 8, v140
	v_and_b32_e32 v146, 15, v147
	v_xor_b32_e32 v146, 8, v146
	v_bfe_u32 v148, v147, 4, 4
	v_mul_lo_u32 v146, v146, s92
	v_mul_lo_u32 v148, v148, s92
	v_mov_b32_e32 v147, v146
	v_mov_b32_e32 v149, v148
	ds_write2st64_b64 v77, v[146:147], v[148:149] offset1:2
	v_add_u32_e32 v138, 0xc00, v74
	ds_read_u8 v139, v138
	v_add_u32_e32 v141, 0xc00, v73
	ds_read_u8 v140, v141
	s_add_i32 s43, s67, 64
	v_mov_b32_e32 v138, s43
	ds_read2st64_b32 v[228:229], v138 offset1:1
	ds_read_b128 v[26:29], v227 offset:6144
	ds_read_b128 v[30:33], v227 offset:6160
	v_mov_b32_e32 v38, 0
	v_mov_b32_e32 v39, 0
	v_mov_b32_e32 v40, 0
	v_mov_b32_e32 v41, 0
	v_mov_b32_e32 v42, 0
	v_mov_b32_e32 v43, 0
	v_mov_b32_e32 v44, 0
	v_mov_b32_e32 v45, 0
	v_and_b32_e32 v78, 0xffff, v23
	v_lshrrev_b32_e32 v79, 16, v23
	v_lshl_add_u32 v78, v78, 7, v150
	v_lshl_add_u32 v79, v79, 7, v151
	s_mov_b32 m0, s79
	s_add_i32 s43, s79, 0x400
	global_load_lds_dwordx4 v78, s[50:51]
	s_mov_b32 m0, s43
	s_nop 0
	global_load_lds_dwordx4 v79, s[50:51]
	s_waitcnt vmcnt(8)
; #define LAS __attribute__((address_space(3)))
; __device__ __forceinline__ bf16 f2bf(float f) { return (bf16)f2bfu(f); }
; #define TR4(p_) __builtin_amdgcn_ds_read_tr4_b64_v2i32((LAS v2i*)(p_))
; __device__ __forceinline__ void peer_v_tokens(int j, const LAS unsigned short* EL, const LAS unsigned char* AL  , const LAS float* ASC  , const LAS int* SAL  , ...
;     ...
;             for (int tp = 0; tp < 2; ++tp) {
;                 const v2i ao = TR4(ATL + (2 * q + tp) * 128 + 8 * s16), ah = TR4(ATL + 1024 + (2 * q + tp) * 128 + 8 * s16);
; #pragma unroll
;                 for (int r = 0; r < 4; ++r) {
;                     const v2i d = TR4(ldsb + BUF[st % 3] + 2048 * tp + roff[r]);
;                     accH[r] = __builtin_amdgcn_sdot8(d.x, ah.x, accH[r], false); accH[r] = __builtin_amdgcn_sdot8(d.y, ah.y, accH[r], false);
;                     accL[r] = __builtin_amdgcn_sdot8(d.x, ao.x, accL[r], false); accL[r] = __builtin_amdgcn_sdot8(d.y, ao.y, accL[r], false);
;                 }
;             }
;     ...
;                 for (int r = 0; r < 4; ++r) STASH[256 * p + 16 * (grp + 4 * r) + pc] = f2bf(asc * (float)(2 * ((accH[r] << 4) + accL[r]) + sa));
;     ...
;             for (int jq = 0; jq < 4; ++jq) { typedef unsigned u2v __attribute__((ext_vector_type(2))); const u2v pw = *(const LAS u2v*)(STASH + 4 * lane + 256 * jq); const uint2 hw = hv[jq];
	v_add_u32_e32 v54, s99, v59
	v_add_u32_e32 v55, s99, v60
	v_add_u32_e32 v56, s99, v61
	v_add_u32_e32 v57, s99, v62
	ds_read_b64_tr_b4 v[50:51], v160 offset:128
	ds_read_b64_tr_b4 v[52:53], v160 offset:1152
	ds_read_b64_tr_b4 v[130:131], v54
	ds_read_b64_tr_b4 v[132:133], v55
	ds_read_b64_tr_b4 v[134:135], v56
	ds_read_b64_tr_b4 v[136:137], v57
	s_waitcnt lgkmcnt(12)
	v_dot8c_i32_i4_e32 v38, v122, v48
	v_dot8c_i32_i4_e32 v39, v122, v46
	v_dot8c_i32_i4_e32 v40, v124, v48
	v_dot8c_i32_i4_e32 v41, v124, v46
	v_dot8c_i32_i4_e32 v42, v126, v48
	v_dot8c_i32_i4_e32 v43, v126, v46
	v_dot8c_i32_i4_e32 v44, v128, v48
	v_dot8c_i32_i4_e32 v45, v128, v46
	v_dot8c_i32_i4_e32 v38, v123, v49
	v_dot8c_i32_i4_e32 v39, v123, v47
	v_dot8c_i32_i4_e32 v40, v125, v49
	v_dot8c_i32_i4_e32 v41, v125, v47
	v_dot8c_i32_i4_e32 v42, v127, v49
	v_dot8c_i32_i4_e32 v43, v127, v47
	v_dot8c_i32_i4_e32 v44, v129, v49
	v_dot8c_i32_i4_e32 v45, v129, v47
	v_and_b32_e32 v78, 0xffff, v24
	v_lshrrev_b32_e32 v79, 16, v24
	v_lshl_add_u32 v78, v78, 7, v150
	v_lshl_add_u32 v79, v79, 7, v151
	s_mov_b32 m0, s98
	s_add_i32 s43, s98, 0x400
	global_load_lds_dwordx4 v78, s[50:51]
	s_mov_b32 m0, s43
	s_nop 0
	global_load_lds_dwordx4 v79, s[50:51]
	s_waitcnt vmcnt(8)
	v_add_u32_e32 v54, s76, v59
	v_add_u32_e32 v55, s76, v60
	v_add_u32_e32 v56, s76, v61
	v_add_u32_e32 v57, s76, v62
	ds_read_b64_tr_b4 v[46:47], v160 offset:256
	ds_read_b64_tr_b4 v[48:49], v160 offset:1280
	ds_read_b64_tr_b4 v[122:123], v54
	ds_read_b64_tr_b4 v[124:125], v55
	ds_read_b64_tr_b4 v[126:127], v56
	ds_read_b64_tr_b4 v[128:129], v57
	s_waitcnt lgkmcnt(6)
	v_dot8c_i32_i4_e32 v38, v130, v52
	v_dot8c_i32_i4_e32 v39, v130, v50
	v_dot8c_i32_i4_e32 v40, v132, v52
	v_dot8c_i32_i4_e32 v41, v132, v50
	v_dot8c_i32_i4_e32 v42, v134, v52
	v_dot8c_i32_i4_e32 v43, v134, v50
	v_dot8c_i32_i4_e32 v44, v136, v52
	v_dot8c_i32_i4_e32 v45, v136, v50
	v_dot8c_i32_i4_e32 v38, v131, v53
	v_dot8c_i32_i4_e32 v39, v131, v51
	v_dot8c_i32_i4_e32 v40, v133, v53
	v_dot8c_i32_i4_e32 v41, v133, v51
	v_dot8c_i32_i4_e32 v42, v135, v53
	v_dot8c_i32_i4_e32 v43, v135, v51
	v_dot8c_i32_i4_e32 v44, v137, v53
	v_dot8c_i32_i4_e32 v45, v137, v51
	ds_write_b16 v65, v162
	ds_write_b16_d16_hi v65, v162 offset:128
	ds_write_b16 v65, v163 offset:256
	ds_write_b16_d16_hi v65, v163 offset:384
	ds_write_b16 v65, v164 offset:512
	ds_write_b16_d16_hi v65, v164 offset:640
	ds_write_b16 v65, v165 offset:768
	ds_write_b16_d16_hi v65, v165 offset:896
	ds_write_b16 v65, v166 offset:1024
	ds_write_b16_d16_hi v65, v166 offset:1152
	ds_write_b16 v65, v167 offset:1280
	ds_write_b16_d16_hi v65, v167 offset:1408
	ds_write_b16 v65, v168 offset:1536
	ds_write_b16_d16_hi v65, v168 offset:1664
	ds_write_b16 v65, v169 offset:1792
	ds_write_b16_d16_hi v65, v169 offset:1920
	ds_read_b64 v[202:203], v154
	ds_read_b64 v[204:205], v154 offset:512
	ds_read_b64 v[206:207], v154 offset:1024
	ds_read_b64 v[208:209], v154 offset:1536
	v_and_b32_e32 v78, 0xffff, v25
	v_lshrrev_b32_e32 v79, 16, v25
	v_lshl_add_u32 v78, v78, 7, v150
	v_lshl_add_u32 v79, v79, 7, v151
	s_mov_b32 m0, s99
	s_add_i32 s43, s99, 0x400
	global_load_lds_dwordx4 v78, s[50:51]
	s_mov_b32 m0, s43
	s_nop 0
	global_load_lds_dwordx4 v79, s[50:51]
	s_waitcnt vmcnt(8)
	v_add_u32_e32 v54, s77, v59
	v_add_u32_e32 v55, s77, v60
	v_add_u32_e32 v56, s77, v61
	v_add_u32_e32 v57, s77, v62
	ds_read_b64_tr_b4 v[50:51], v160 offset:384
	ds_read_b64_tr_b4 v[52:53], v160 offset:1408
	ds_read_b64_tr_b4 v[130:131], v54
	ds_read_b64_tr_b4 v[132:133], v55
	ds_read_b64_tr_b4 v[134:135], v56
	ds_read_b64_tr_b4 v[136:137], v57
	s_waitcnt lgkmcnt(15)
	v_dot8c_i32_i4_e32 v38, v122, v48
	v_dot8c_i32_i4_e32 v39, v122, v46
	v_dot8c_i32_i4_e32 v40, v124, v48
	v_dot8c_i32_i4_e32 v41, v124, v46
	v_dot8c_i32_i4_e32 v42, v126, v48
	v_dot8c_i32_i4_e32 v43, v126, v46
	v_dot8c_i32_i4_e32 v44, v128, v48
	v_dot8c_i32_i4_e32 v45, v128, v46
	v_dot8c_i32_i4_e32 v38, v123, v49
	v_dot8c_i32_i4_e32 v39, v123, v47
	v_dot8c_i32_i4_e32 v40, v125, v49
	v_dot8c_i32_i4_e32 v41, v125, v47
	v_dot8c_i32_i4_e32 v42, v127, v49
	v_dot8c_i32_i4_e32 v43, v127, v47
	v_dot8c_i32_i4_e32 v44, v129, v49
	v_dot8c_i32_i4_e32 v45, v129, v47
	s_waitcnt lgkmcnt(15)
	v_and_b32_e32 v78, 0xffff, v26
	v_lshrrev_b32_e32 v79, 16, v26
	v_lshl_add_u32 v78, v78, 7, v150
	v_lshl_add_u32 v79, v79, 7, v151
	s_mov_b32 m0, s76
	s_add_i32 s43, s76, 0x400
	global_load_lds_dwordx4 v78, s[50:51]
	s_mov_b32 m0, s43
	s_nop 0
	global_load_lds_dwordx4 v79, s[50:51]
	s_waitcnt vmcnt(8)
	v_add_u32_e32 v54, s78, v59
	v_add_u32_e32 v55, s78, v60
	v_add_u32_e32 v56, s78, v61
	v_add_u32_e32 v57, s78, v62
	ds_read_b64_tr_b4 v[46:47], v160 offset:512
	ds_read_b64_tr_b4 v[48:49], v160 offset:1536
	ds_read_b64_tr_b4 v[122:123], v54
	ds_read_b64_tr_b4 v[124:125], v55
	ds_read_b64_tr_b4 v[126:127], v56
	ds_read_b64_tr_b4 v[128:129], v57
	s_waitcnt lgkmcnt(6)
	v_dot8c_i32_i4_e32 v38, v130, v52
	v_dot8c_i32_i4_e32 v39, v130, v50
	v_dot8c_i32_i4_e32 v40, v132, v52
	v_dot8c_i32_i4_e32 v41, v132, v50
	v_dot8c_i32_i4_e32 v42, v134, v52
	v_dot8c_i32_i4_e32 v43, v134, v50
	v_dot8c_i32_i4_e32 v44, v136, v52
	v_dot8c_i32_i4_e32 v45, v136, v50
	v_dot8c_i32_i4_e32 v38, v131, v53
	v_dot8c_i32_i4_e32 v39, v131, v51
	v_dot8c_i32_i4_e32 v40, v133, v53
	v_dot8c_i32_i4_e32 v41, v133, v51
	v_dot8c_i32_i4_e32 v42, v135, v53
	v_dot8c_i32_i4_e32 v43, v135, v51
	v_dot8c_i32_i4_e32 v44, v137, v53
	v_dot8c_i32_i4_e32 v45, v137, v51
	v_and_b32_e32 v78, 0xffff, v27
	v_lshrrev_b32_e32 v79, 16, v27
	v_lshl_add_u32 v78, v78, 7, v150
	v_lshl_add_u32 v79, v79, 7, v151
	s_mov_b32 m0, s77
	s_add_i32 s43, s77, 0x400
	global_load_lds_dwordx4 v78, s[50:51]
	s_mov_b32 m0, s43
	s_nop 0
	global_load_lds_dwordx4 v79, s[50:51]
	s_waitcnt vmcnt(8)
; #define LAS __attribute__((address_space(3)))
; #define TR4(p_) __builtin_amdgcn_ds_read_tr4_b64_v2i32((LAS v2i*)(p_))
; __device__ __forceinline__ void peer_v_tokens(int j, const LAS unsigned short* EL, const LAS unsigned char* AL  , const LAS float* ASC  , const LAS int* SAL  , ...
;     ...
;         for (int m = 0; m < 2; ++m) {
;             const int idx = lane + 64 * m, tau = idx >> 4, sr = idx & 15, k = 16 * (sr & 7) + 2 * tau + (sr >> 3);
;             const int aq = (int)*(const LAS signed char*)(AL + tl * 128 + k); const int tq = aq + 8;
;             const unsigned lo = (((unsigned)tq & 15u) ^ 8u) * 0x11111111u, hi = ((unsigned)(tq >> 4) & 15u) * 0x11111111u;
;             typedef unsigned u2v __attribute__((ext_vector_type(2)));
;             u2v l2; l2.x = lo; l2.y = lo; u2v h2; h2.x = hi; h2.y = hi;
;             *(LAS u2v*)(ATL + 8 * idx) = l2; *(LAS u2v*)(ATL + 1024 + 8 * idx) = h2;
;         }
;     ...
;         for (int st = 0; st < 16; ++st) {
;             const int p = st >> 2, q = st & 3;
;             if (st < 14) VDMA(st + 2, (st + 2) % 3);
;             if (st < 14) asm volatile("s_waitcnt vmcnt(8)" ::: "memory");
;             else if (st == 14) asm volatile("s_waitcnt vmcnt(4)" ::: "memory");
;             else asm volatile("s_waitcnt vmcnt(0)" ::: "memory");
;             if (q == 0) {
; #pragma unroll
;                 for (int r = 0; r < 4; ++r) { accH[r] = 0; accL[r] = 0; } }
; #pragma unroll
;             for (int tp = 0; tp < 2; ++tp) {
;                 const v2i ao = TR4(ATL + (2 * q + tp) * 128 + 8 * s16), ah = TR4(ATL + 1024 + (2 * q + tp) * 128 + 8 * s16);
; #pragma unroll
;                 for (int r = 0; r < 4; ++r) {
;                     const v2i d = TR4(ldsb + BUF[st % 3] + 2048 * tp + roff[r]);
;                     accH[r] = __builtin_amdgcn_sdot8(d.x, ah.x, accH[r], false); accH[r] = __builtin_amdgcn_sdot8(d.y, ah.y, accH[r], false);
;                     accL[r] = __builtin_amdgcn_sdot8(d.x, ao.x, accL[r], false); accL[r] = __builtin_amdgcn_sdot8(d.y, ao.y, accL[r], false);
;                 }
;             }
;             asm volatile("s_waitcnt lgkmcnt(0)" ::: "memory");
	v_add_u32_e32 v54, s79, v59
	v_add_u32_e32 v55, s79, v60
	v_add_u32_e32 v56, s79, v61
	v_add_u32_e32 v57, s79, v62
	ds_read_b64_tr_b4 v[50:51], v160 offset:640
	ds_read_b64_tr_b4 v[52:53], v160 offset:1664
	ds_read_b64_tr_b4 v[130:131], v54
	ds_read_b64_tr_b4 v[132:133], v55
	ds_read_b64_tr_b4 v[134:135], v56
	ds_read_b64_tr_b4 v[136:137], v57
	s_waitcnt lgkmcnt(6)
	v_dot8c_i32_i4_e32 v38, v122, v48
	v_dot8c_i32_i4_e32 v39, v122, v46
	v_dot8c_i32_i4_e32 v40, v124, v48
	v_dot8c_i32_i4_e32 v41, v124, v46
	v_dot8c_i32_i4_e32 v42, v126, v48
	v_dot8c_i32_i4_e32 v43, v126, v46
	v_dot8c_i32_i4_e32 v44, v128, v48
	v_dot8c_i32_i4_e32 v45, v128, v46
	v_dot8c_i32_i4_e32 v38, v123, v49
	v_dot8c_i32_i4_e32 v39, v123, v47
	v_dot8c_i32_i4_e32 v40, v125, v49
	v_dot8c_i32_i4_e32 v41, v125, v47
	v_dot8c_i32_i4_e32 v42, v127, v49
	v_dot8c_i32_i4_e32 v43, v127, v47
	v_dot8c_i32_i4_e32 v44, v129, v49
	v_dot8c_i32_i4_e32 v45, v129, v47
	s_waitcnt lgkmcnt(15)
	v_add_u32_e32 v143, 8, v139
	v_and_b32_e32 v142, 15, v143
	v_xor_b32_e32 v142, 8, v142
	v_bfe_u32 v144, v143, 4, 4
	v_mul_lo_u32 v142, v142, s92
	v_mul_lo_u32 v144, v144, s92
	v_mov_b32_e32 v143, v142
	v_mov_b32_e32 v145, v144
	ds_write2st64_b64 v159, v[142:143], v[144:145] offset1:2
	v_and_b32_e32 v78, 0xffff, v28
	v_lshrrev_b32_e32 v79, 16, v28
	v_lshl_add_u32 v78, v78, 7, v150
	v_lshl_add_u32 v79, v79, 7, v151
	s_mov_b32 m0, s78
	s_add_i32 s43, s78, 0x400
	global_load_lds_dwordx4 v78, s[50:51]
	s_mov_b32 m0, s43
	s_nop 0
	global_load_lds_dwordx4 v79, s[50:51]
	s_waitcnt vmcnt(8)
	v_add_u32_e32 v54, s98, v59
	v_add_u32_e32 v55, s98, v60
	v_add_u32_e32 v56, s98, v61
	v_add_u32_e32 v57, s98, v62
	ds_read_b64_tr_b4 v[46:47], v160 offset:768
	ds_read_b64_tr_b4 v[48:49], v160 offset:1792
	ds_read_b64_tr_b4 v[122:123], v54
	ds_read_b64_tr_b4 v[124:125], v55
	ds_read_b64_tr_b4 v[126:127], v56
	ds_read_b64_tr_b4 v[128:129], v57
	s_waitcnt lgkmcnt(7)
	v_dot8c_i32_i4_e32 v38, v130, v52
	v_dot8c_i32_i4_e32 v39, v130, v50
	v_dot8c_i32_i4_e32 v40, v132, v52
	v_dot8c_i32_i4_e32 v41, v132, v50
	v_dot8c_i32_i4_e32 v42, v134, v52
	v_dot8c_i32_i4_e32 v43, v134, v50
	v_dot8c_i32_i4_e32 v44, v136, v52
	v_dot8c_i32_i4_e32 v45, v136, v50
	v_dot8c_i32_i4_e32 v38, v131, v53
	v_dot8c_i32_i4_e32 v39, v131, v51
	v_dot8c_i32_i4_e32 v40, v133, v53
	v_dot8c_i32_i4_e32 v41, v133, v51
	v_dot8c_i32_i4_e32 v42, v135, v53
	v_dot8c_i32_i4_e32 v43, v135, v51
	v_dot8c_i32_i4_e32 v44, v137, v53
	v_dot8c_i32_i4_e32 v45, v137, v51
	v_and_b32_e32 v78, 0xffff, v29
	v_lshrrev_b32_e32 v79, 16, v29
	v_lshl_add_u32 v78, v78, 7, v150
	v_lshl_add_u32 v79, v79, 7, v151
	s_mov_b32 m0, s79
	s_add_i32 s43, s79, 0x400
	global_load_lds_dwordx4 v78, s[50:51]
	s_mov_b32 m0, s43
	s_nop 0
	global_load_lds_dwordx4 v79, s[50:51]
	s_waitcnt vmcnt(8)
	v_add_u32_e32 v54, s99, v59
	v_add_u32_e32 v55, s99, v60
	v_add_u32_e32 v56, s99, v61
	v_add_u32_e32 v57, s99, v62
	ds_read_b64_tr_b4 v[50:51], v160 offset:896
	ds_read_b64_tr_b4 v[52:53], v160 offset:1920
	ds_read_b64_tr_b4 v[130:131], v54
	ds_read_b64_tr_b4 v[132:133], v55
	ds_read_b64_tr_b4 v[134:135], v56
	ds_read_b64_tr_b4 v[136:137], v57
	s_waitcnt lgkmcnt(6)
	v_dot8c_i32_i4_e32 v38, v122, v48
	v_dot8c_i32_i4_e32 v39, v122, v46
	v_dot8c_i32_i4_e32 v40, v124, v48
	v_dot8c_i32_i4_e32 v41, v124, v46
	v_dot8c_i32_i4_e32 v42, v126, v48
	v_dot8c_i32_i4_e32 v43, v126, v46
	v_dot8c_i32_i4_e32 v44, v128, v48
	v_dot8c_i32_i4_e32 v45, v128, v46
	v_dot8c_i32_i4_e32 v38, v123, v49
	v_dot8c_i32_i4_e32 v39, v123, v47
	v_dot8c_i32_i4_e32 v40, v125, v49
	v_dot8c_i32_i4_e32 v41, v125, v47
	v_dot8c_i32_i4_e32 v42, v127, v49
	v_dot8c_i32_i4_e32 v43, v127, v47
	v_dot8c_i32_i4_e32 v44, v129, v49
	v_dot8c_i32_i4_e32 v45, v129, v47
	v_and_b32_e32 v78, 0xffff, v30
	v_lshrrev_b32_e32 v79, 16, v30
	v_lshl_add_u32 v78, v78, 7, v150
	v_lshl_add_u32 v79, v79, 7, v151
	s_mov_b32 m0, s98
	s_add_i32 s43, s98, 0x400
	global_load_lds_dwordx4 v78, s[50:51]
	s_mov_b32 m0, s43
	s_nop 0
	global_load_lds_dwordx4 v79, s[50:51]
	s_waitcnt vmcnt(8)
	v_add_u32_e32 v54, s76, v59
	v_add_u32_e32 v55, s76, v60
	v_add_u32_e32 v56, s76, v61
	v_add_u32_e32 v57, s76, v62
	ds_read_b64_tr_b4 v[46:47], v160
	ds_read_b64_tr_b4 v[48:49], v160 offset:1024
	ds_read_b64_tr_b4 v[122:123], v54
	ds_read_b64_tr_b4 v[124:125], v55
	ds_read_b64_tr_b4 v[126:127], v56
	ds_read_b64_tr_b4 v[128:129], v57
	s_waitcnt lgkmcnt(6)
	v_dot8c_i32_i4_e32 v38, v130, v52
	v_dot8c_i32_i4_e32 v39, v130, v50
	v_dot8c_i32_i4_e32 v40, v132, v52
	v_dot8c_i32_i4_e32 v41, v132, v50
	v_dot8c_i32_i4_e32 v42, v134, v52
	v_dot8c_i32_i4_e32 v43, v134, v50
	v_dot8c_i32_i4_e32 v44, v136, v52
	v_dot8c_i32_i4_e32 v45, v136, v50
	v_dot8c_i32_i4_e32 v38, v131, v53
	v_dot8c_i32_i4_e32 v39, v131, v51
	v_dot8c_i32_i4_e32 v40, v133, v53
	v_dot8c_i32_i4_e32 v41, v133, v51
	v_dot8c_i32_i4_e32 v42, v135, v53
	v_dot8c_i32_i4_e32 v43, v135, v51
	v_dot8c_i32_i4_e32 v44, v137, v53
	v_dot8c_i32_i4_e32 v45, v137, v51
	s_nop 3
	s_waitcnt lgkmcnt(15)
; #define LAS __attribute__((address_space(3)))
; __device__ __forceinline__ bf16 f2bf(float f) { return (bf16)f2bfu(f); }
; __device__ __forceinline__ void peer_v_tokens(int j, const LAS unsigned short* EL, const LAS unsigned char* AL  , const LAS float* ASC  , const LAS int* SAL  , ...
;     ...
;             if (q == 3) {
; #pragma unroll
;                 for (int r = 0; r < 4; ++r) STASH[256 * p + 16 * (grp + 4 * r) + pc] = f2bf(asc * (float)(2 * ((accH[r] << 4) + accL[r]) + sa));
;             }
;     ...
;         {
;             float4 v[4]; float ss = 0.f;
; #pragma unroll
;             for (int jq = 0; jq < 4; ++jq) { typedef unsigned u2v __attribute__((ext_vector_type(2))); const u2v pw = *(const LAS u2v*)(STASH + 4 * lane + 256 * jq); const uint2 hw = hv[jq];
;                 v[jq] = make_float4(__uint_as_float(hw.x << 16) + __uint_as_float(pw.x << 16), __uint_as_float(hw.x & 0xffff0000u) + __uint_as_float(pw.x & 0xffff0000u),
;                                     __uint_as_float(hw.y << 16) + __uint_as_float(pw.y << 16), __uint_as_float(hw.y & 0xffff0000u) + __uint_as_float(pw.y & 0xffff0000u));
;                 ss += v[jq].x * v[jq].x + v[jq].y * v[jq].y + v[jq].z * v[jq].z + v[jq].w * v[jq].w; }
;             ss = wave_sum(ss);
;             const float r3 = rsqrtf(ss * (1.f / D) + EPS);
	v_lshlrev_b32_e32 v38, 5, v38
	v_lshlrev_b32_e32 v39, 1, v39
	v_add3_u32 v38, v39, v229, v38
	v_cvt_f32_i32_e32 v38, v38
	v_mul_f32_e32 v38, v228, v38
	v_lshlrev_b32_e32 v40, 5, v40
	v_lshlrev_b32_e32 v41, 1, v41
	v_add3_u32 v40, v41, v229, v40
	v_cvt_f32_i32_e32 v40, v40
	v_mul_f32_e32 v40, v228, v40
	v_lshlrev_b32_e32 v42, 5, v42
	v_lshlrev_b32_e32 v43, 1, v43
	v_add3_u32 v42, v43, v229, v42
	v_cvt_f32_i32_e32 v42, v42
	v_mul_f32_e32 v42, v228, v42
	v_lshlrev_b32_e32 v44, 5, v44
	v_lshlrev_b32_e32 v45, 1, v45
	v_add3_u32 v44, v45, v229, v44
	v_cvt_f32_i32_e32 v44, v44
	v_mul_f32_e32 v44, v228, v44
	v_cvt_pk_bf16_f32 v178, v38, v40
	v_cvt_pk_bf16_f32 v179, v42, v44
	v_add_u32_e32 v147, 8, v140
	v_and_b32_e32 v146, 15, v147
	v_xor_b32_e32 v146, 8, v146
	v_bfe_u32 v148, v147, 4, 4
	v_mul_lo_u32 v146, v146, s92
	v_mul_lo_u32 v148, v148, s92
	v_mov_b32_e32 v147, v146
	v_mov_b32_e32 v149, v148
	ds_write2st64_b64 v77, v[146:147], v[148:149] offset1:2
	v_add_u32_e32 v138, 0x800, v74
	ds_read_u8 v139, v138
	v_add_u32_e32 v141, 0x800, v73
	ds_read_u8 v140, v141
	s_add_i32 s43, s67, 96
	v_mov_b32_e32 v138, s43
	ds_read2st64_b32 v[228:229], v138 offset1:1
	ds_read_b128 v[18:21], v227 offset:4096
	ds_read_b128 v[22:25], v227 offset:4112
	v_add_u32_e32 v152, 0x200000, v63
	v_add_u32_e32 v153, 0x200000, v64
	v_mov_b32_e32 v38, 0
	v_mov_b32_e32 v39, 0
	v_mov_b32_e32 v40, 0
	v_mov_b32_e32 v41, 0
	v_mov_b32_e32 v42, 0
	v_mov_b32_e32 v43, 0
	v_mov_b32_e32 v44, 0
	v_mov_b32_e32 v45, 0
	v_and_b32_e32 v78, 0xffff, v31
	v_lshrrev_b32_e32 v79, 16, v31
	v_lshl_add_u32 v78, v78, 7, v150
	v_lshl_add_u32 v79, v79, 7, v151
	s_mov_b32 m0, s99
	s_add_i32 s43, s99, 0x400
	global_load_lds_dwordx4 v78, s[50:51]
	s_mov_b32 m0, s43
	s_nop 0
	global_load_lds_dwordx4 v79, s[50:51]
	s_waitcnt vmcnt(8)
	v_add_u32_e32 v54, s77, v59
	v_add_u32_e32 v55, s77, v60
	v_add_u32_e32 v56, s77, v61
	v_add_u32_e32 v57, s77, v62
	ds_read_b64_tr_b4 v[50:51], v160 offset:128
	ds_read_b64_tr_b4 v[52:53], v160 offset:1152
	ds_read_b64_tr_b4 v[130:131], v54
	ds_read_b64_tr_b4 v[132:133], v55
	ds_read_b64_tr_b4 v[134:135], v56
	ds_read_b64_tr_b4 v[136:137], v57
	s_waitcnt lgkmcnt(12)
	s_waitcnt vmcnt(34) lgkmcnt(15)
	v_lshlrev_b32_e32 v210, 16, v194
	v_and_b32_e32 v211, 0xffff0000, v194
	v_lshlrev_b32_e32 v142, 16, v202
	v_and_b32_e32 v143, 0xffff0000, v202
	v_add_f32_e32 v210, v210, v142
	v_add_f32_e32 v211, v211, v143
	v_lshlrev_b32_e32 v212, 16, v195
	v_and_b32_e32 v213, 0xffff0000, v195
	v_lshlrev_b32_e32 v142, 16, v203
	v_and_b32_e32 v143, 0xffff0000, v203
	v_add_f32_e32 v212, v212, v142
	v_add_f32_e32 v213, v213, v143
	v_lshlrev_b32_e32 v214, 16, v196
	v_and_b32_e32 v215, 0xffff0000, v196
	v_lshlrev_b32_e32 v142, 16, v204
	v_and_b32_e32 v143, 0xffff0000, v204
	v_add_f32_e32 v214, v214, v142
	v_add_f32_e32 v215, v215, v143
	v_lshlrev_b32_e32 v216, 16, v197
	v_and_b32_e32 v217, 0xffff0000, v197
	v_lshlrev_b32_e32 v142, 16, v205
	v_and_b32_e32 v143, 0xffff0000, v205
	v_add_f32_e32 v216, v216, v142
	v_add_f32_e32 v217, v217, v143
	v_lshlrev_b32_e32 v218, 16, v198
	v_and_b32_e32 v219, 0xffff0000, v198
	v_lshlrev_b32_e32 v142, 16, v206
	v_and_b32_e32 v143, 0xffff0000, v206
	v_add_f32_e32 v218, v218, v142
	v_add_f32_e32 v219, v219, v143
	v_lshlrev_b32_e32 v220, 16, v199
	v_and_b32_e32 v221, 0xffff0000, v199
	v_lshlrev_b32_e32 v142, 16, v207
	v_and_b32_e32 v143, 0xffff0000, v207
	v_add_f32_e32 v220, v220, v142
	v_add_f32_e32 v221, v221, v143
	v_lshlrev_b32_e32 v222, 16, v200
	v_and_b32_e32 v223, 0xffff0000, v200
	v_lshlrev_b32_e32 v142, 16, v208
	v_and_b32_e32 v143, 0xffff0000, v208
	v_add_f32_e32 v222, v222, v142
	v_add_f32_e32 v223, v223, v143
	v_lshlrev_b32_e32 v224, 16, v201
	v_and_b32_e32 v225, 0xffff0000, v201
	v_lshlrev_b32_e32 v142, 16, v209
	v_and_b32_e32 v143, 0xffff0000, v209
	v_add_f32_e32 v224, v224, v142
	v_add_f32_e32 v225, v225, v143
	v_mov_b32_e32 v144, 0
	v_mul_f32_e32 v145, v210, v210
	v_fmac_f32_e32 v145, v211, v211
	v_fmac_f32_e32 v145, v212, v212
	v_fmac_f32_e32 v145, v213, v213
	v_add_f32_e32 v144, v144, v145
	v_mul_f32_e32 v145, v214, v214
	v_fmac_f32_e32 v145, v215, v215
	v_fmac_f32_e32 v145, v216, v216
	v_fmac_f32_e32 v145, v217, v217
	v_add_f32_e32 v144, v144, v145
	v_mul_f32_e32 v145, v218, v218
	v_fmac_f32_e32 v145, v219, v219
	v_fmac_f32_e32 v145, v220, v220
	v_fmac_f32_e32 v145, v221, v221
	v_add_f32_e32 v144, v144, v145
	v_mul_f32_e32 v145, v222, v222
	v_fmac_f32_e32 v145, v223, v223
	v_fmac_f32_e32 v145, v224, v224
	v_fmac_f32_e32 v145, v225, v225
	v_add_f32_e32 v144, v144, v145
	s_nop 1
	v_add_f32_dpp v144, v144, v144 quad_perm:[1,0,3,2] row_mask:0xf bank_mask:0xf bound_ctrl:1
	s_nop 1
	v_add_f32_dpp v144, v144, v144 quad_perm:[2,3,0,1] row_mask:0xf bank_mask:0xf bound_ctrl:1
	s_nop 1
	v_add_f32_dpp v144, v144, v144 row_half_mirror row_mask:0xf bank_mask:0xf bound_ctrl:1
	s_nop 1
	v_add_f32_dpp v144, v144, v144 row_mirror row_mask:0xf bank_mask:0xf bound_ctrl:1
	s_nop 1
	v_readlane_b32 s10, v144, 0
	v_readlane_b32 s11, v144, 16
	v_readlane_b32 s14, v144, 32
	v_readlane_b32 s15, v144, 48
	s_nop 3
	v_mov_b32_e32 v144, s11
	v_mov_b32_e32 v145, s15
	v_add_f32_e32 v144, s10, v144
	v_add_f32_e32 v145, s14, v145
	v_add_f32_e32 v144, v144, v145
	v_fmamk_f32 v144, v144, 0x3a800000, v111
	v_rsq_f32_e32 v144, v144
	s_nop 0
	v_mul_f32_e32 v210, v210, v144
	v_mul_f32_e32 v211, v211, v144
	v_mul_f32_e32 v212, v212, v144
	v_mul_f32_e32 v213, v213, v144
	v_mul_f32_e32 v214, v214, v144
	v_mul_f32_e32 v215, v215, v144
	v_mul_f32_e32 v216, v216, v144
	v_mul_f32_e32 v217, v217, v144
	v_mul_f32_e32 v218, v218, v144
	v_mul_f32_e32 v219, v219, v144
	v_mul_f32_e32 v220, v220, v144
	v_mul_f32_e32 v221, v221, v144
	v_mul_f32_e32 v222, v222, v144
	v_mul_f32_e32 v223, v223, v144
	v_mul_f32_e32 v224, v224, v144
	v_mul_f32_e32 v225, v225, v144
	v_dot8c_i32_i4_e32 v38, v122, v48
	v_dot8c_i32_i4_e32 v39, v122, v46
	v_dot8c_i32_i4_e32 v40, v124, v48
	v_dot8c_i32_i4_e32 v41, v124, v46
	v_dot8c_i32_i4_e32 v42, v126, v48
	v_dot8c_i32_i4_e32 v43, v126, v46
	v_dot8c_i32_i4_e32 v44, v128, v48
	v_dot8c_i32_i4_e32 v45, v128, v46
	v_dot8c_i32_i4_e32 v38, v123, v49
	v_dot8c_i32_i4_e32 v39, v123, v47
	v_dot8c_i32_i4_e32 v40, v125, v49
	v_dot8c_i32_i4_e32 v41, v125, v47
	v_dot8c_i32_i4_e32 v42, v127, v49
	v_dot8c_i32_i4_e32 v43, v127, v47
	v_dot8c_i32_i4_e32 v44, v129, v49
	v_dot8c_i32_i4_e32 v45, v129, v47
	v_and_b32_e32 v78, 0xffff, v32
	v_lshrrev_b32_e32 v79, 16, v32
	v_lshl_add_u32 v78, v78, 7, v150
	v_lshl_add_u32 v79, v79, 7, v151
	s_mov_b32 m0, s76
	s_add_i32 s43, s76, 0x400
	global_load_lds_dwordx4 v78, s[50:51]
	s_mov_b32 m0, s43
	s_nop 0
	global_load_lds_dwordx4 v79, s[50:51]
	s_waitcnt vmcnt(8)
; #define TR4(p_) __builtin_amdgcn_ds_read_tr4_b64_v2i32((LAS v2i*)(p_))
; #define VDMA(st_, k_) do { _Pragma("unroll") for (int i_ = 0; i_ < 4; ++i_) { \
;         const unsigned off_ = (unsigned)((st_) >> 2) * (16384u * 128u) + (PE_ID(E, 4 * ((st_) & 3) + i_) << 7) + ((i_ & 1) ? cx1 : cx0); \
;         __builtin_amdgcn_global_load_lds((const unsigned*)(V4 + off_), (LAS unsigned*)(ldsb + BUF[k_] + 1024 * i_), 16, 0, 0); } } while (0)
; __device__ __forceinline__ void peer_v_tokens(int j, const LAS unsigned short* EL, const LAS unsigned char* AL  , const LAS float* ASC  , const LAS int* SAL  , ...
;     ...
;         for (int st = 0; st < 16; ++st) {
;             const int p = st >> 2, q = st & 3;
;             if (st < 14) VDMA(st + 2, (st + 2) % 3);
;             if (st < 14) asm volatile("s_waitcnt vmcnt(8)" ::: "memory");
;             else if (st == 14) asm volatile("s_waitcnt vmcnt(4)" ::: "memory");
;             else asm volatile("s_waitcnt vmcnt(0)" ::: "memory");
;             if (q == 0) {
; #pragma unroll
;                 for (int r = 0; r < 4; ++r) { accH[r] = 0; accL[r] = 0; } }
; #pragma unroll
;             for (int tp = 0; tp < 2; ++tp) {
;                 const v2i ao = TR4(ATL + (2 * q + tp) * 128 + 8 * s16), ah = TR4(ATL + 1024 + (2 * q + tp) * 128 + 8 * s16);
; #pragma unroll
;                 for (int r = 0; r < 4; ++r) {
;                     const v2i d = TR4(ldsb + BUF[st % 3] + 2048 * tp + roff[r]);
;                     accH[r] = __builtin_amdgcn_sdot8(d.x, ah.x, accH[r], false); accH[r] = __builtin_amdgcn_sdot8(d.y, ah.y, accH[r], false);
;                     accL[r] = __builtin_amdgcn_sdot8(d.x, ao.x, accL[r], false); accL[r] = __builtin_amdgcn_sdot8(d.y, ao.y, accL[r], false);
;                 }
;             }
;             asm volatile("s_waitcnt lgkmcnt(0)" ::: "memory");
	v_add_u32_e32 v54, s78, v59
	v_add_u32_e32 v55, s78, v60
	v_add_u32_e32 v56, s78, v61
	v_add_u32_e32 v57, s78, v62
	ds_read_b64_tr_b4 v[46:47], v160 offset:256
	ds_read_b64_tr_b4 v[48:49], v160 offset:1280
	ds_read_b64_tr_b4 v[122:123], v54
	ds_read_b64_tr_b4 v[124:125], v55
	ds_read_b64_tr_b4 v[126:127], v56
	ds_read_b64_tr_b4 v[128:129], v57
	s_waitcnt lgkmcnt(6)
	v_dot8c_i32_i4_e32 v38, v130, v52
	v_dot8c_i32_i4_e32 v39, v130, v50
	v_dot8c_i32_i4_e32 v40, v132, v52
	v_dot8c_i32_i4_e32 v41, v132, v50
	v_dot8c_i32_i4_e32 v42, v134, v52
	v_dot8c_i32_i4_e32 v43, v134, v50
	v_dot8c_i32_i4_e32 v44, v136, v52
	v_dot8c_i32_i4_e32 v45, v136, v50
	v_dot8c_i32_i4_e32 v38, v131, v53
	v_dot8c_i32_i4_e32 v39, v131, v51
	v_dot8c_i32_i4_e32 v40, v133, v53
	v_dot8c_i32_i4_e32 v41, v133, v51
	v_dot8c_i32_i4_e32 v42, v135, v53
	v_dot8c_i32_i4_e32 v43, v135, v51
	v_dot8c_i32_i4_e32 v44, v137, v53
	v_dot8c_i32_i4_e32 v45, v137, v51
	v_and_b32_e32 v78, 0xffff, v33
	v_lshrrev_b32_e32 v79, 16, v33
	v_lshl_add_u32 v78, v78, 7, v150
	v_lshl_add_u32 v79, v79, 7, v151
	s_mov_b32 m0, s77
	s_add_i32 s43, s77, 0x400
	global_load_lds_dwordx4 v78, s[50:51]
	s_mov_b32 m0, s43
	s_nop 0
	global_load_lds_dwordx4 v79, s[50:51]
	s_waitcnt vmcnt(8)
	v_add_u32_e32 v54, s79, v59
	v_add_u32_e32 v55, s79, v60
	v_add_u32_e32 v56, s79, v61
	v_add_u32_e32 v57, s79, v62
	ds_read_b64_tr_b4 v[50:51], v160 offset:384
	ds_read_b64_tr_b4 v[52:53], v160 offset:1408
	ds_read_b64_tr_b4 v[130:131], v54
	ds_read_b64_tr_b4 v[132:133], v55
	ds_read_b64_tr_b4 v[134:135], v56
	ds_read_b64_tr_b4 v[136:137], v57
	s_waitcnt lgkmcnt(6)
	v_dot8c_i32_i4_e32 v38, v122, v48
	v_dot8c_i32_i4_e32 v39, v122, v46
	v_dot8c_i32_i4_e32 v40, v124, v48
	v_dot8c_i32_i4_e32 v41, v124, v46
	v_dot8c_i32_i4_e32 v42, v126, v48
	v_dot8c_i32_i4_e32 v43, v126, v46
	v_dot8c_i32_i4_e32 v44, v128, v48
	v_dot8c_i32_i4_e32 v45, v128, v46
	v_dot8c_i32_i4_e32 v38, v123, v49
	v_dot8c_i32_i4_e32 v39, v123, v47
	v_dot8c_i32_i4_e32 v40, v125, v49
	v_dot8c_i32_i4_e32 v41, v125, v47
	v_dot8c_i32_i4_e32 v42, v127, v49
	v_dot8c_i32_i4_e32 v43, v127, v47
	v_dot8c_i32_i4_e32 v44, v129, v49
	v_dot8c_i32_i4_e32 v45, v129, v47
	s_waitcnt lgkmcnt(15)
	v_and_b32_e32 v78, 0xffff, v18
	v_lshrrev_b32_e32 v79, 16, v18
	v_lshl_add_u32 v78, v78, 7, v152
	v_lshl_add_u32 v79, v79, 7, v153
	s_mov_b32 m0, s78
	s_add_i32 s43, s78, 0x400
	global_load_lds_dwordx4 v78, s[50:51]
	s_mov_b32 m0, s43
	s_nop 0
	global_load_lds_dwordx4 v79, s[50:51]
	s_waitcnt vmcnt(8)
	v_add_u32_e32 v54, s98, v59
	v_add_u32_e32 v55, s98, v60
	v_add_u32_e32 v56, s98, v61
	v_add_u32_e32 v57, s98, v62
	ds_read_b64_tr_b4 v[46:47], v160 offset:512
	ds_read_b64_tr_b4 v[48:49], v160 offset:1536
	ds_read_b64_tr_b4 v[122:123], v54
	ds_read_b64_tr_b4 v[124:125], v55
	ds_read_b64_tr_b4 v[126:127], v56
	ds_read_b64_tr_b4 v[128:129], v57
	s_waitcnt lgkmcnt(6)
	v_dot8c_i32_i4_e32 v38, v130, v52
	v_dot8c_i32_i4_e32 v39, v130, v50
	v_dot8c_i32_i4_e32 v40, v132, v52
	v_dot8c_i32_i4_e32 v41, v132, v50
	v_dot8c_i32_i4_e32 v42, v134, v52
	v_dot8c_i32_i4_e32 v43, v134, v50
	v_dot8c_i32_i4_e32 v44, v136, v52
	v_dot8c_i32_i4_e32 v45, v136, v50
	v_dot8c_i32_i4_e32 v38, v131, v53
	v_dot8c_i32_i4_e32 v39, v131, v51
	v_dot8c_i32_i4_e32 v40, v133, v53
	v_dot8c_i32_i4_e32 v41, v133, v51
	v_dot8c_i32_i4_e32 v42, v135, v53
	v_dot8c_i32_i4_e32 v43, v135, v51
	v_dot8c_i32_i4_e32 v44, v137, v53
	v_dot8c_i32_i4_e32 v45, v137, v51
	v_and_b32_e32 v78, 0xffff, v19
	v_lshrrev_b32_e32 v79, 16, v19
	v_lshl_add_u32 v78, v78, 7, v152
	v_lshl_add_u32 v79, v79, 7, v153
	s_mov_b32 m0, s79
	s_add_i32 s43, s79, 0x400
	global_load_lds_dwordx4 v78, s[50:51]
	s_mov_b32 m0, s43
	s_nop 0
	global_load_lds_dwordx4 v79, s[50:51]
	s_waitcnt vmcnt(8)
	v_add_u32_e32 v54, s99, v59
	v_add_u32_e32 v55, s99, v60
	v_add_u32_e32 v56, s99, v61
	v_add_u32_e32 v57, s99, v62
	ds_read_b64_tr_b4 v[50:51], v160 offset:640
	ds_read_b64_tr_b4 v[52:53], v160 offset:1664
	ds_read_b64_tr_b4 v[130:131], v54
	ds_read_b64_tr_b4 v[132:133], v55
	ds_read_b64_tr_b4 v[134:135], v56
	ds_read_b64_tr_b4 v[136:137], v57
	s_waitcnt lgkmcnt(6)
	v_dot8c_i32_i4_e32 v38, v122, v48
	v_dot8c_i32_i4_e32 v39, v122, v46
	v_dot8c_i32_i4_e32 v40, v124, v48
	v_dot8c_i32_i4_e32 v41, v124, v46
	v_dot8c_i32_i4_e32 v42, v126, v48
	v_dot8c_i32_i4_e32 v43, v126, v46
	v_dot8c_i32_i4_e32 v44, v128, v48
	v_dot8c_i32_i4_e32 v45, v128, v46
	v_dot8c_i32_i4_e32 v38, v123, v49
	v_dot8c_i32_i4_e32 v39, v123, v47
	v_dot8c_i32_i4_e32 v40, v125, v49
	v_dot8c_i32_i4_e32 v41, v125, v47
	v_dot8c_i32_i4_e32 v42, v127, v49
	v_dot8c_i32_i4_e32 v43, v127, v47
	v_dot8c_i32_i4_e32 v44, v129, v49
	v_dot8c_i32_i4_e32 v45, v129, v47
	s_waitcnt lgkmcnt(15)
	v_add_u32_e32 v143, 8, v139
	v_and_b32_e32 v142, 15, v143
	v_xor_b32_e32 v142, 8, v142
	v_bfe_u32 v144, v143, 4, 4
	v_mul_lo_u32 v142, v142, s92
	v_mul_lo_u32 v144, v144, s92
	v_mov_b32_e32 v143, v142
	v_mov_b32_e32 v145, v144
	ds_write2st64_b64 v159, v[142:143], v[144:145] offset1:2
	v_and_b32_e32 v78, 0xffff, v20
	v_lshrrev_b32_e32 v79, 16, v20
	v_lshl_add_u32 v78, v78, 7, v152
	v_lshl_add_u32 v79, v79, 7, v153
	s_mov_b32 m0, s98
	s_add_i32 s43, s98, 0x400
	global_load_lds_dwordx4 v78, s[50:51]
	s_mov_b32 m0, s43
	s_nop 0
	global_load_lds_dwordx4 v79, s[50:51]
	s_waitcnt vmcnt(8)
	v_add_u32_e32 v54, s76, v59
	v_add_u32_e32 v55, s76, v60
	v_add_u32_e32 v56, s76, v61
	v_add_u32_e32 v57, s76, v62
	ds_read_b64_tr_b4 v[46:47], v160 offset:768
	ds_read_b64_tr_b4 v[48:49], v160 offset:1792
	ds_read_b64_tr_b4 v[122:123], v54
	ds_read_b64_tr_b4 v[124:125], v55
	ds_read_b64_tr_b4 v[126:127], v56
	ds_read_b64_tr_b4 v[128:129], v57
	s_waitcnt lgkmcnt(7)
; #define LAS __attribute__((address_space(3)))
; __device__ __forceinline__ bf16 f2bf(float f) { return (bf16)f2bfu(f); }
; #define CFENCE() asm volatile("" ::: "memory")
; __device__ __forceinline__ void peer_v_tokens(int j, const LAS unsigned short* EL, const LAS unsigned char* AL  , const LAS float* ASC  , const LAS int* SAL  , ...
;     ...
;             if (q == 3) {
; #pragma unroll
;                 for (int r = 0; r < 4; ++r) STASH[256 * p + 16 * (grp + 4 * r) + pc] = f2bf(asc * (float)(2 * ((accH[r] << 4) + accL[r]) + sa));
;             }
;         }
;         CFENCE();
;         {
;             float4 v[4]; float ss = 0.f;
; #pragma unroll
;             for (int jq = 0; jq < 4; ++jq) { typedef unsigned u2v __attribute__((ext_vector_type(2))); const u2v pw = *(const LAS u2v*)(STASH + 4 * lane + 256 * jq); const uint2 hw = hv[jq];
;                 v[jq] = make_float4(__uint_as_float(hw.x << 16) + __uint_as_float(pw.x << 16), __uint_as_float(hw.x & 0xffff0000u) + __uint_as_float(pw.x & 0xffff0000u),
;                                     __uint_as_float(hw.y << 16) + __uint_as_float(pw.y << 16), __uint_as_float(hw.y & 0xffff0000u) + __uint_as_float(pw.y & 0xffff0000u));
;                 ss += v[jq].x * v[jq].x + v[jq].y * v[jq].y + v[jq].z * v[jq].z + v[jq].w * v[jq].w; }
;             ss = wave_sum(ss);
;             const float r3 = rsqrtf(ss * (1.f / D) + EPS);
;             float4* op = (float4*)(outp + (size_t)t * D) + lane;
; #pragma unroll
;             for (int jq = 0; jq < 4; ++jq) { typedef float f4v __attribute__((ext_vector_type(4))); f4v o4; o4.x = v[jq].x * r3 * gv[jq].x; o4.y = v[jq].y * r3 * gv[jq].y; o4.z = v[jq].z * r3 * gv[jq].z; o4.w = v[jq].w * r3 * gv[jq].w;
;                 __builtin_nontemporal_store(o4, (f4v*)op + 64 * jq); }
;         }
	v_dot8c_i32_i4_e32 v38, v130, v52
	v_dot8c_i32_i4_e32 v39, v130, v50
	v_dot8c_i32_i4_e32 v40, v132, v52
	v_dot8c_i32_i4_e32 v41, v132, v50
	v_dot8c_i32_i4_e32 v42, v134, v52
	v_dot8c_i32_i4_e32 v43, v134, v50
	v_dot8c_i32_i4_e32 v44, v136, v52
	v_dot8c_i32_i4_e32 v45, v136, v50
	v_dot8c_i32_i4_e32 v38, v131, v53
	v_dot8c_i32_i4_e32 v39, v131, v51
	v_dot8c_i32_i4_e32 v40, v133, v53
	v_dot8c_i32_i4_e32 v41, v133, v51
	v_dot8c_i32_i4_e32 v42, v135, v53
	v_dot8c_i32_i4_e32 v43, v135, v51
	v_dot8c_i32_i4_e32 v44, v137, v53
	v_dot8c_i32_i4_e32 v45, v137, v51
	v_and_b32_e32 v78, 0xffff, v21
	v_lshrrev_b32_e32 v79, 16, v21
	v_lshl_add_u32 v78, v78, 7, v152
	v_lshl_add_u32 v79, v79, 7, v153
	s_mov_b32 m0, s99
	s_add_i32 s43, s99, 0x400
	global_load_lds_dwordx4 v78, s[50:51]
	s_mov_b32 m0, s43
	s_nop 0
	global_load_lds_dwordx4 v79, s[50:51]
	s_waitcnt vmcnt(8)
	v_add_u32_e32 v54, s77, v59
	v_add_u32_e32 v55, s77, v60
	v_add_u32_e32 v56, s77, v61
	v_add_u32_e32 v57, s77, v62
	ds_read_b64_tr_b4 v[50:51], v160 offset:896
	ds_read_b64_tr_b4 v[52:53], v160 offset:1920
	ds_read_b64_tr_b4 v[130:131], v54
	ds_read_b64_tr_b4 v[132:133], v55
	ds_read_b64_tr_b4 v[134:135], v56
	ds_read_b64_tr_b4 v[136:137], v57
	s_waitcnt lgkmcnt(6)
	v_dot8c_i32_i4_e32 v38, v122, v48
	v_dot8c_i32_i4_e32 v39, v122, v46
	v_dot8c_i32_i4_e32 v40, v124, v48
	v_dot8c_i32_i4_e32 v41, v124, v46
	v_dot8c_i32_i4_e32 v42, v126, v48
	v_dot8c_i32_i4_e32 v43, v126, v46
	v_dot8c_i32_i4_e32 v44, v128, v48
	v_dot8c_i32_i4_e32 v45, v128, v46
	v_dot8c_i32_i4_e32 v38, v123, v49
	v_dot8c_i32_i4_e32 v39, v123, v47
	v_dot8c_i32_i4_e32 v40, v125, v49
	v_dot8c_i32_i4_e32 v41, v125, v47
	v_dot8c_i32_i4_e32 v42, v127, v49
	v_dot8c_i32_i4_e32 v43, v127, v47
	v_dot8c_i32_i4_e32 v44, v129, v49
	v_dot8c_i32_i4_e32 v45, v129, v47
	v_and_b32_e32 v78, 0xffff, v22
	v_lshrrev_b32_e32 v79, 16, v22
	v_lshl_add_u32 v78, v78, 7, v152
	v_lshl_add_u32 v79, v79, 7, v153
	s_mov_b32 m0, s76
	s_add_i32 s43, s76, 0x400
	global_load_lds_dwordx4 v78, s[50:51]
	s_mov_b32 m0, s43
	s_nop 0
	global_load_lds_dwordx4 v79, s[50:51]
	s_waitcnt vmcnt(8)
	v_add_u32_e32 v54, s78, v59
	v_add_u32_e32 v55, s78, v60
	v_add_u32_e32 v56, s78, v61
	v_add_u32_e32 v57, s78, v62
	ds_read_b64_tr_b4 v[46:47], v160
	ds_read_b64_tr_b4 v[48:49], v160 offset:1024
	ds_read_b64_tr_b4 v[122:123], v54
	ds_read_b64_tr_b4 v[124:125], v55
	ds_read_b64_tr_b4 v[126:127], v56
	ds_read_b64_tr_b4 v[128:129], v57
	s_waitcnt lgkmcnt(6)
	v_dot8c_i32_i4_e32 v38, v130, v52
	v_dot8c_i32_i4_e32 v39, v130, v50
	v_dot8c_i32_i4_e32 v40, v132, v52
	v_dot8c_i32_i4_e32 v41, v132, v50
	v_dot8c_i32_i4_e32 v42, v134, v52
	v_dot8c_i32_i4_e32 v43, v134, v50
	v_dot8c_i32_i4_e32 v44, v136, v52
	v_dot8c_i32_i4_e32 v45, v136, v50
	v_dot8c_i32_i4_e32 v38, v131, v53
	v_dot8c_i32_i4_e32 v39, v131, v51
	v_dot8c_i32_i4_e32 v40, v133, v53
	v_dot8c_i32_i4_e32 v41, v133, v51
	v_dot8c_i32_i4_e32 v42, v135, v53
	v_dot8c_i32_i4_e32 v43, v135, v51
	v_dot8c_i32_i4_e32 v44, v137, v53
	v_dot8c_i32_i4_e32 v45, v137, v51
	s_nop 3
	s_waitcnt lgkmcnt(15)
	v_lshlrev_b32_e32 v38, 5, v38
	v_lshlrev_b32_e32 v39, 1, v39
	v_add3_u32 v38, v39, v229, v38
	v_cvt_f32_i32_e32 v38, v38
	v_mul_f32_e32 v38, v228, v38
	v_lshlrev_b32_e32 v40, 5, v40
	v_lshlrev_b32_e32 v41, 1, v41
	v_add3_u32 v40, v41, v229, v40
	v_cvt_f32_i32_e32 v40, v40
	v_mul_f32_e32 v40, v228, v40
	v_lshlrev_b32_e32 v42, 5, v42
	v_lshlrev_b32_e32 v43, 1, v43
	v_add3_u32 v42, v43, v229, v42
	v_cvt_f32_i32_e32 v42, v42
	v_mul_f32_e32 v42, v228, v42
	v_lshlrev_b32_e32 v44, 5, v44
	v_lshlrev_b32_e32 v45, 1, v45
	v_add3_u32 v44, v45, v229, v44
	v_cvt_f32_i32_e32 v44, v44
	v_mul_f32_e32 v44, v228, v44
	v_cvt_pk_bf16_f32 v186, v38, v40
	v_cvt_pk_bf16_f32 v187, v42, v44
	ds_read_b128 v[252:255], v155
	s_add_i32 s44, s40, 0
	s_ashr_i32 s45, s44, 31
	s_lshl_b64 s[44:45], s[44:45], 12
	v_lshl_add_u64 v[80:81], v[36:37], 0, s[44:45]
	s_waitcnt lgkmcnt(0)
	v_mul_f32_e32 v210, v210, v252
	v_mul_f32_e32 v211, v211, v253
	v_mul_f32_e32 v212, v212, v254
	v_mul_f32_e32 v213, v213, v255
	global_store_dwordx4 v[80:81], v[210:213], off nt
	s_add_i32 s43, s40, 8
	s_lshl_b32 s43, s43, 11
	v_add_u32_e32 v138, s43, v66
	global_load_dwordx2 v[194:195], v138, s[70:71]
	global_load_dwordx2 v[196:197], v138, s[70:71] offset:512
	global_load_dwordx2 v[198:199], v138, s[70:71] offset:1024
	global_load_dwordx2 v[200:201], v138, s[70:71] offset:1536
	v_add_u32_e32 v147, 8, v140
	v_and_b32_e32 v146, 15, v147
	v_xor_b32_e32 v146, 8, v146
	v_bfe_u32 v148, v147, 4, 4
	v_mul_lo_u32 v146, v146, s92
	v_mul_lo_u32 v148, v148, s92
	v_mov_b32_e32 v147, v146
	v_mov_b32_e32 v149, v148
	ds_write2st64_b64 v77, v[146:147], v[148:149] offset1:2
	v_add_u32_e32 v138, 0xc00, v74
	ds_read_u8 v139, v138
	v_add_u32_e32 v141, 0xc00, v73
	ds_read_u8 v140, v141
	s_add_i32 s43, s67, 64
	v_mov_b32_e32 v138, s43
	ds_read2st64_b32 v[228:229], v138 offset1:1
	ds_read_b128 v[26:29], v227 offset:6144
	ds_read_b128 v[30:33], v227 offset:6160
	v_mov_b32_e32 v38, 0
	v_mov_b32_e32 v39, 0
	v_mov_b32_e32 v40, 0
	v_mov_b32_e32 v41, 0
	v_mov_b32_e32 v42, 0
	v_mov_b32_e32 v43, 0
	v_mov_b32_e32 v44, 0
	v_mov_b32_e32 v45, 0
	v_and_b32_e32 v78, 0xffff, v23
	v_lshrrev_b32_e32 v79, 16, v23
	v_lshl_add_u32 v78, v78, 7, v152
	v_lshl_add_u32 v79, v79, 7, v153
	s_mov_b32 m0, s77
	s_add_i32 s43, s77, 0x400
	global_load_lds_dwordx4 v78, s[50:51]
	s_mov_b32 m0, s43
	s_nop 0
	global_load_lds_dwordx4 v79, s[50:51]
	s_waitcnt vmcnt(13)
	v_add_u32_e32 v54, s79, v59
	v_add_u32_e32 v55, s79, v60
	v_add_u32_e32 v56, s79, v61
	v_add_u32_e32 v57, s79, v62
	ds_read_b64_tr_b4 v[50:51], v160 offset:128
	ds_read_b64_tr_b4 v[52:53], v160 offset:1152
	ds_read_b64_tr_b4 v[130:131], v54
	ds_read_b64_tr_b4 v[132:133], v55
	ds_read_b64_tr_b4 v[134:135], v56
	ds_read_b64_tr_b4 v[136:137], v57
	s_waitcnt lgkmcnt(13)
; #define TR4(p_) __builtin_amdgcn_ds_read_tr4_b64_v2i32((LAS v2i*)(p_))
; #define VDMA(st_, k_) do { _Pragma("unroll") for (int i_ = 0; i_ < 4; ++i_) { \
;         const unsigned off_ = (unsigned)((st_) >> 2) * (16384u * 128u) + (PE_ID(E, 4 * ((st_) & 3) + i_) << 7) + ((i_ & 1) ? cx1 : cx0); \
;         __builtin_amdgcn_global_load_lds((const unsigned*)(V4 + off_), (LAS unsigned*)(ldsb + BUF[k_] + 1024 * i_), 16, 0, 0); } } while (0)
; __device__ __forceinline__ void peer_v_tokens(int j, const LAS unsigned short* EL, const LAS unsigned char* AL  , const LAS float* ASC  , const LAS int* SAL  , ...
;     ...
;         for (int st = 0; st < 16; ++st) {
;             const int p = st >> 2, q = st & 3;
;             if (st < 14) VDMA(st + 2, (st + 2) % 3);
;             if (st < 14) asm volatile("s_waitcnt vmcnt(8)" ::: "memory");
;             else if (st == 14) asm volatile("s_waitcnt vmcnt(4)" ::: "memory");
;             else asm volatile("s_waitcnt vmcnt(0)" ::: "memory");
;             if (q == 0) {
; #pragma unroll
;                 for (int r = 0; r < 4; ++r) { accH[r] = 0; accL[r] = 0; } }
; #pragma unroll
;             for (int tp = 0; tp < 2; ++tp) {
;                 const v2i ao = TR4(ATL + (2 * q + tp) * 128 + 8 * s16), ah = TR4(ATL + 1024 + (2 * q + tp) * 128 + 8 * s16);
; #pragma unroll
;                 for (int r = 0; r < 4; ++r) {
;                     const v2i d = TR4(ldsb + BUF[st % 3] + 2048 * tp + roff[r]);
;                     accH[r] = __builtin_amdgcn_sdot8(d.x, ah.x, accH[r], false); accH[r] = __builtin_amdgcn_sdot8(d.y, ah.y, accH[r], false);
;                     accL[r] = __builtin_amdgcn_sdot8(d.x, ao.x, accL[r], false); accL[r] = __builtin_amdgcn_sdot8(d.y, ao.y, accL[r], false);
;                 }
;             }
;             asm volatile("s_waitcnt lgkmcnt(0)" ::: "memory");
	v_dot8c_i32_i4_e32 v38, v122, v48
	v_dot8c_i32_i4_e32 v39, v122, v46
	v_dot8c_i32_i4_e32 v40, v124, v48
	v_dot8c_i32_i4_e32 v41, v124, v46
	v_dot8c_i32_i4_e32 v42, v126, v48
	v_dot8c_i32_i4_e32 v43, v126, v46
	v_dot8c_i32_i4_e32 v44, v128, v48
	v_dot8c_i32_i4_e32 v45, v128, v46
	v_dot8c_i32_i4_e32 v38, v123, v49
	v_dot8c_i32_i4_e32 v39, v123, v47
	v_dot8c_i32_i4_e32 v40, v125, v49
	v_dot8c_i32_i4_e32 v41, v125, v47
	v_dot8c_i32_i4_e32 v42, v127, v49
	v_dot8c_i32_i4_e32 v43, v127, v47
	v_dot8c_i32_i4_e32 v44, v129, v49
	v_dot8c_i32_i4_e32 v45, v129, v47
	v_and_b32_e32 v78, 0xffff, v24
	v_lshrrev_b32_e32 v79, 16, v24
	v_lshl_add_u32 v78, v78, 7, v152
	v_lshl_add_u32 v79, v79, 7, v153
	s_mov_b32 m0, s78
	s_add_i32 s43, s78, 0x400
	global_load_lds_dwordx4 v78, s[50:51]
	s_mov_b32 m0, s43
	s_nop 0
	global_load_lds_dwordx4 v79, s[50:51]
	s_waitcnt vmcnt(13)
	v_add_u32_e32 v54, s98, v59
	v_add_u32_e32 v55, s98, v60
	v_add_u32_e32 v56, s98, v61
	v_add_u32_e32 v57, s98, v62
	ds_read_b64_tr_b4 v[46:47], v160 offset:256
	ds_read_b64_tr_b4 v[48:49], v160 offset:1280
	ds_read_b64_tr_b4 v[122:123], v54
	ds_read_b64_tr_b4 v[124:125], v55
	ds_read_b64_tr_b4 v[126:127], v56
	ds_read_b64_tr_b4 v[128:129], v57
	s_waitcnt lgkmcnt(6)
	v_dot8c_i32_i4_e32 v38, v130, v52
	v_dot8c_i32_i4_e32 v39, v130, v50
	v_dot8c_i32_i4_e32 v40, v132, v52
	v_dot8c_i32_i4_e32 v41, v132, v50
	v_dot8c_i32_i4_e32 v42, v134, v52
	v_dot8c_i32_i4_e32 v43, v134, v50
	v_dot8c_i32_i4_e32 v44, v136, v52
	v_dot8c_i32_i4_e32 v45, v136, v50
	v_dot8c_i32_i4_e32 v38, v131, v53
	v_dot8c_i32_i4_e32 v39, v131, v51
	v_dot8c_i32_i4_e32 v40, v133, v53
	v_dot8c_i32_i4_e32 v41, v133, v51
	v_dot8c_i32_i4_e32 v42, v135, v53
	v_dot8c_i32_i4_e32 v43, v135, v51
	v_dot8c_i32_i4_e32 v44, v137, v53
	v_dot8c_i32_i4_e32 v45, v137, v51
	v_and_b32_e32 v78, 0xffff, v25
	v_lshrrev_b32_e32 v79, 16, v25
	v_lshl_add_u32 v78, v78, 7, v152
	v_lshl_add_u32 v79, v79, 7, v153
	s_mov_b32 m0, s79
	s_add_i32 s43, s79, 0x400
	global_load_lds_dwordx4 v78, s[50:51]
	s_mov_b32 m0, s43
	s_nop 0
	global_load_lds_dwordx4 v79, s[50:51]
	s_waitcnt vmcnt(13)
	v_add_u32_e32 v54, s99, v59
	v_add_u32_e32 v55, s99, v60
	v_add_u32_e32 v56, s99, v61
	v_add_u32_e32 v57, s99, v62
	ds_read_b64_tr_b4 v[50:51], v160 offset:384
	ds_read_b64_tr_b4 v[52:53], v160 offset:1408
	ds_read_b64_tr_b4 v[130:131], v54
	ds_read_b64_tr_b4 v[132:133], v55
	ds_read_b64_tr_b4 v[134:135], v56
	ds_read_b64_tr_b4 v[136:137], v57
	s_waitcnt lgkmcnt(6)
	v_dot8c_i32_i4_e32 v38, v122, v48
	v_dot8c_i32_i4_e32 v39, v122, v46
	v_dot8c_i32_i4_e32 v40, v124, v48
	v_dot8c_i32_i4_e32 v41, v124, v46
	v_dot8c_i32_i4_e32 v42, v126, v48
	v_dot8c_i32_i4_e32 v43, v126, v46
	v_dot8c_i32_i4_e32 v44, v128, v48
	v_dot8c_i32_i4_e32 v45, v128, v46
	v_dot8c_i32_i4_e32 v38, v123, v49
	v_dot8c_i32_i4_e32 v39, v123, v47
	v_dot8c_i32_i4_e32 v40, v125, v49
	v_dot8c_i32_i4_e32 v41, v125, v47
	v_dot8c_i32_i4_e32 v42, v127, v49
	v_dot8c_i32_i4_e32 v43, v127, v47
	v_dot8c_i32_i4_e32 v44, v129, v49
	v_dot8c_i32_i4_e32 v45, v129, v47
	s_waitcnt lgkmcnt(15)
	v_and_b32_e32 v78, 0xffff, v26
	v_lshrrev_b32_e32 v79, 16, v26
	v_lshl_add_u32 v78, v78, 7, v152
	v_lshl_add_u32 v79, v79, 7, v153
	s_mov_b32 m0, s98
	s_add_i32 s43, s98, 0x400
	global_load_lds_dwordx4 v78, s[50:51]
	s_mov_b32 m0, s43
	s_nop 0
	global_load_lds_dwordx4 v79, s[50:51]
	s_waitcnt vmcnt(13)
	v_add_u32_e32 v54, s76, v59
	v_add_u32_e32 v55, s76, v60
	v_add_u32_e32 v56, s76, v61
	v_add_u32_e32 v57, s76, v62
	ds_read_b64_tr_b4 v[46:47], v160 offset:512
	ds_read_b64_tr_b4 v[48:49], v160 offset:1536
	ds_read_b64_tr_b4 v[122:123], v54
	ds_read_b64_tr_b4 v[124:125], v55
	ds_read_b64_tr_b4 v[126:127], v56
	ds_read_b64_tr_b4 v[128:129], v57
	s_waitcnt lgkmcnt(6)
	v_dot8c_i32_i4_e32 v38, v130, v52
	v_dot8c_i32_i4_e32 v39, v130, v50
	v_dot8c_i32_i4_e32 v40, v132, v52
	v_dot8c_i32_i4_e32 v41, v132, v50
	v_dot8c_i32_i4_e32 v42, v134, v52
	v_dot8c_i32_i4_e32 v43, v134, v50
	v_dot8c_i32_i4_e32 v44, v136, v52
	v_dot8c_i32_i4_e32 v45, v136, v50
	v_dot8c_i32_i4_e32 v38, v131, v53
	v_dot8c_i32_i4_e32 v39, v131, v51
	v_dot8c_i32_i4_e32 v40, v133, v53
	v_dot8c_i32_i4_e32 v41, v133, v51
	v_dot8c_i32_i4_e32 v42, v135, v53
	v_dot8c_i32_i4_e32 v43, v135, v51
	v_dot8c_i32_i4_e32 v44, v137, v53
	v_dot8c_i32_i4_e32 v45, v137, v51
	v_and_b32_e32 v78, 0xffff, v27
	v_lshrrev_b32_e32 v79, 16, v27
	v_lshl_add_u32 v78, v78, 7, v152
	v_lshl_add_u32 v79, v79, 7, v153
	s_mov_b32 m0, s99
	s_add_i32 s43, s99, 0x400
	global_load_lds_dwordx4 v78, s[50:51]
	s_mov_b32 m0, s43
	s_nop 0
	global_load_lds_dwordx4 v79, s[50:51]
	s_waitcnt vmcnt(8)
	v_add_u32_e32 v54, s77, v59
	v_add_u32_e32 v55, s77, v60
	v_add_u32_e32 v56, s77, v61
	v_add_u32_e32 v57, s77, v62
	ds_read_b64_tr_b4 v[50:51], v160 offset:640
	ds_read_b64_tr_b4 v[52:53], v160 offset:1664
	ds_read_b64_tr_b4 v[130:131], v54
	ds_read_b64_tr_b4 v[132:133], v55
	ds_read_b64_tr_b4 v[134:135], v56
	ds_read_b64_tr_b4 v[136:137], v57
	s_waitcnt lgkmcnt(6)
	v_dot8c_i32_i4_e32 v38, v122, v48
	v_dot8c_i32_i4_e32 v39, v122, v46
	v_dot8c_i32_i4_e32 v40, v124, v48
	v_dot8c_i32_i4_e32 v41, v124, v46
	v_dot8c_i32_i4_e32 v42, v126, v48
	v_dot8c_i32_i4_e32 v43, v126, v46
	v_dot8c_i32_i4_e32 v44, v128, v48
	v_dot8c_i32_i4_e32 v45, v128, v46
	v_dot8c_i32_i4_e32 v38, v123, v49
	v_dot8c_i32_i4_e32 v39, v123, v47
	v_dot8c_i32_i4_e32 v40, v125, v49
	v_dot8c_i32_i4_e32 v41, v125, v47
	v_dot8c_i32_i4_e32 v42, v127, v49
	v_dot8c_i32_i4_e32 v43, v127, v47
	v_dot8c_i32_i4_e32 v44, v129, v49
	v_dot8c_i32_i4_e32 v45, v129, v47
	s_waitcnt lgkmcnt(15)
; __device__ __forceinline__ void peer_v_tokens(int j, const LAS unsigned short* EL, const LAS unsigned char* AL  , const LAS float* ASC  , const LAS int* SAL  , ...
;     ...
;         for (int st = 0; st < 16; ++st) {
;             const int p = st >> 2, q = st & 3;
;             if (st < 14) VDMA(st + 2, (st + 2) % 3);
;             if (st < 14) asm volatile("s_waitcnt vmcnt(8)" ::: "memory");
;             else if (st == 14) asm volatile("s_waitcnt vmcnt(4)" ::: "memory");
;             else asm volatile("s_waitcnt vmcnt(0)" ::: "memory");
;             if (q == 0) {
; #pragma unroll
;                 for (int r = 0; r < 4; ++r) { accH[r] = 0; accL[r] = 0; } }
; #pragma unroll
;             for (int tp = 0; tp < 2; ++tp) {
;                 const v2i ao = TR4(ATL + (2 * q + tp) * 128 + 8 * s16), ah = TR4(ATL + 1024 + (2 * q + tp) * 128 + 8 * s16);
; #pragma unroll
;                 for (int r = 0; r < 4; ++r) {
;                     const v2i d = TR4(ldsb + BUF[st % 3] + 2048 * tp + roff[r]);
;                     accH[r] = __builtin_amdgcn_sdot8(d.x, ah.x, accH[r], false); accH[r] = __builtin_amdgcn_sdot8(d.y, ah.y, accH[r], false);
;                     accL[r] = __builtin_amdgcn_sdot8(d.x, ao.x, accL[r], false); accL[r] = __builtin_amdgcn_sdot8(d.y, ao.y, accL[r], false);
;                 }
;             }
;             asm volatile("s_waitcnt lgkmcnt(0)" ::: "memory");
;             if (q == 3) {
; #pragma unroll
;                 for (int r = 0; r < 4; ++r) STASH[256 * p + 16 * (grp + 4 * r) + pc] = f2bf(asc * (float)(2 * ((accH[r] << 4) + accL[r]) + sa));
;             }
;         }
;         CFENCE();
;         {
;             float4 v[4]; float ss = 0.f;
; #pragma unroll
;             for (int jq = 0; jq < 4; ++jq) { typedef unsigned u2v __attribute__((ext_vector_type(2))); const u2v pw = *(const LAS u2v*)(STASH + 4 * lane + 256 * jq); const uint2 hw = hv[jq];
;                 v[jq] = make_float4(__uint_as_float(hw.x << 16) + __uint_as_float(pw.x << 16), __uint_as_float(hw.x & 0xffff0000u) + __uint_as_float(pw.x & 0xffff0000u),
;                                     __uint_as_float(hw.y << 16) + __uint_as_float(pw.y << 16), __uint_as_float(hw.y & 0xffff0000u) + __uint_as_float(pw.y & 0xffff0000u));
;                 ss += v[jq].x * v[jq].x + v[jq].y * v[jq].y + v[jq].z * v[jq].z + v[jq].w * v[jq].w; }
;             ss = wave_sum(ss);
	v_add_u32_e32 v143, 8, v139
	v_and_b32_e32 v142, 15, v143
	v_xor_b32_e32 v142, 8, v142
	v_bfe_u32 v144, v143, 4, 4
	v_mul_lo_u32 v142, v142, s92
	v_mul_lo_u32 v144, v144, s92
	v_mov_b32_e32 v143, v142
	v_mov_b32_e32 v145, v144
	ds_write2st64_b64 v159, v[142:143], v[144:145] offset1:2
	v_and_b32_e32 v78, 0xffff, v28
	v_lshrrev_b32_e32 v79, 16, v28
	v_lshl_add_u32 v78, v78, 7, v152
	v_lshl_add_u32 v79, v79, 7, v153
	s_mov_b32 m0, s76
	s_add_i32 s43, s76, 0x400
	global_load_lds_dwordx4 v78, s[50:51]
	s_mov_b32 m0, s43
	s_nop 0
	global_load_lds_dwordx4 v79, s[50:51]
	s_waitcnt vmcnt(8)
	v_add_u32_e32 v54, s78, v59
	v_add_u32_e32 v55, s78, v60
	v_add_u32_e32 v56, s78, v61
	v_add_u32_e32 v57, s78, v62
	ds_read_b64_tr_b4 v[46:47], v160 offset:768
	ds_read_b64_tr_b4 v[48:49], v160 offset:1792
	ds_read_b64_tr_b4 v[122:123], v54
	ds_read_b64_tr_b4 v[124:125], v55
	ds_read_b64_tr_b4 v[126:127], v56
	ds_read_b64_tr_b4 v[128:129], v57
	s_waitcnt lgkmcnt(7)
	v_dot8c_i32_i4_e32 v38, v130, v52
	v_dot8c_i32_i4_e32 v39, v130, v50
	v_dot8c_i32_i4_e32 v40, v132, v52
	v_dot8c_i32_i4_e32 v41, v132, v50
	v_dot8c_i32_i4_e32 v42, v134, v52
	v_dot8c_i32_i4_e32 v43, v134, v50
	v_dot8c_i32_i4_e32 v44, v136, v52
	v_dot8c_i32_i4_e32 v45, v136, v50
	v_dot8c_i32_i4_e32 v38, v131, v53
	v_dot8c_i32_i4_e32 v39, v131, v51
	v_dot8c_i32_i4_e32 v40, v133, v53
	v_dot8c_i32_i4_e32 v41, v133, v51
	v_dot8c_i32_i4_e32 v42, v135, v53
	v_dot8c_i32_i4_e32 v43, v135, v51
	v_dot8c_i32_i4_e32 v44, v137, v53
	v_dot8c_i32_i4_e32 v45, v137, v51
	v_and_b32_e32 v78, 0xffff, v29
	v_lshrrev_b32_e32 v79, 16, v29
	v_lshl_add_u32 v78, v78, 7, v152
	v_lshl_add_u32 v79, v79, 7, v153
	s_mov_b32 m0, s77
	s_add_i32 s43, s77, 0x400
	global_load_lds_dwordx4 v78, s[50:51]
	s_mov_b32 m0, s43
	s_nop 0
	global_load_lds_dwordx4 v79, s[50:51]
	s_waitcnt vmcnt(8)
	v_add_u32_e32 v54, s79, v59
	v_add_u32_e32 v55, s79, v60
	v_add_u32_e32 v56, s79, v61
	v_add_u32_e32 v57, s79, v62
	ds_read_b64_tr_b4 v[50:51], v160 offset:896
	ds_read_b64_tr_b4 v[52:53], v160 offset:1920
	ds_read_b64_tr_b4 v[130:131], v54
	ds_read_b64_tr_b4 v[132:133], v55
	ds_read_b64_tr_b4 v[134:135], v56
	ds_read_b64_tr_b4 v[136:137], v57
	s_waitcnt lgkmcnt(6)
	v_dot8c_i32_i4_e32 v38, v122, v48
	v_dot8c_i32_i4_e32 v39, v122, v46
	v_dot8c_i32_i4_e32 v40, v124, v48
	v_dot8c_i32_i4_e32 v41, v124, v46
	v_dot8c_i32_i4_e32 v42, v126, v48
	v_dot8c_i32_i4_e32 v43, v126, v46
	v_dot8c_i32_i4_e32 v44, v128, v48
	v_dot8c_i32_i4_e32 v45, v128, v46
	v_dot8c_i32_i4_e32 v38, v123, v49
	v_dot8c_i32_i4_e32 v39, v123, v47
	v_dot8c_i32_i4_e32 v40, v125, v49
	v_dot8c_i32_i4_e32 v41, v125, v47
	v_dot8c_i32_i4_e32 v42, v127, v49
	v_dot8c_i32_i4_e32 v43, v127, v47
	v_dot8c_i32_i4_e32 v44, v129, v49
	v_dot8c_i32_i4_e32 v45, v129, v47
	v_and_b32_e32 v78, 0xffff, v30
	v_lshrrev_b32_e32 v79, 16, v30
	v_lshl_add_u32 v78, v78, 7, v152
	v_lshl_add_u32 v79, v79, 7, v153
	s_mov_b32 m0, s78
	s_add_i32 s43, s78, 0x400
	global_load_lds_dwordx4 v78, s[50:51]
	s_mov_b32 m0, s43
	s_nop 0
	global_load_lds_dwordx4 v79, s[50:51]
	s_waitcnt vmcnt(8)
	v_add_u32_e32 v54, s98, v59
	v_add_u32_e32 v55, s98, v60
	v_add_u32_e32 v56, s98, v61
	v_add_u32_e32 v57, s98, v62
	ds_read_b64_tr_b4 v[46:47], v160
	ds_read_b64_tr_b4 v[48:49], v160 offset:1024
	ds_read_b64_tr_b4 v[122:123], v54
	ds_read_b64_tr_b4 v[124:125], v55
	ds_read_b64_tr_b4 v[126:127], v56
	ds_read_b64_tr_b4 v[128:129], v57
	s_waitcnt lgkmcnt(6)
	v_dot8c_i32_i4_e32 v38, v130, v52
	v_dot8c_i32_i4_e32 v39, v130, v50
	v_dot8c_i32_i4_e32 v40, v132, v52
	v_dot8c_i32_i4_e32 v41, v132, v50
	v_dot8c_i32_i4_e32 v42, v134, v52
	v_dot8c_i32_i4_e32 v43, v134, v50
	v_dot8c_i32_i4_e32 v44, v136, v52
	v_dot8c_i32_i4_e32 v45, v136, v50
	v_dot8c_i32_i4_e32 v38, v131, v53
	v_dot8c_i32_i4_e32 v39, v131, v51
	v_dot8c_i32_i4_e32 v40, v133, v53
	v_dot8c_i32_i4_e32 v41, v133, v51
	v_dot8c_i32_i4_e32 v42, v135, v53
	v_dot8c_i32_i4_e32 v43, v135, v51
	v_dot8c_i32_i4_e32 v44, v137, v53
	v_dot8c_i32_i4_e32 v45, v137, v51
	s_nop 3
	s_waitcnt lgkmcnt(15)
	v_lshlrev_b32_e32 v38, 5, v38
	v_lshlrev_b32_e32 v39, 1, v39
	v_add3_u32 v38, v39, v229, v38
	v_cvt_f32_i32_e32 v38, v38
	v_mul_f32_e32 v38, v228, v38
	v_lshlrev_b32_e32 v40, 5, v40
	v_lshlrev_b32_e32 v41, 1, v41
	v_add3_u32 v40, v41, v229, v40
	v_cvt_f32_i32_e32 v40, v40
	v_mul_f32_e32 v40, v228, v40
	v_lshlrev_b32_e32 v42, 5, v42
	v_lshlrev_b32_e32 v43, 1, v43
	v_add3_u32 v42, v43, v229, v42
	v_cvt_f32_i32_e32 v42, v42
	v_mul_f32_e32 v42, v228, v42
	v_lshlrev_b32_e32 v44, 5, v44
	v_lshlrev_b32_e32 v45, 1, v45
	v_add3_u32 v44, v45, v229, v44
	v_cvt_f32_i32_e32 v44, v44
	v_mul_f32_e32 v44, v228, v44
	v_cvt_pk_bf16_f32 v180, v38, v40
	v_cvt_pk_bf16_f32 v181, v42, v44
	ds_read_b128 v[252:255], v155 offset:1024
	s_add_i32 s44, s40, 0
	s_ashr_i32 s45, s44, 31
	s_lshl_b64 s[44:45], s[44:45], 12
	v_lshl_add_u64 v[80:81], v[36:37], 0, s[44:45]
	s_waitcnt lgkmcnt(0)
	v_mul_f32_e32 v214, v214, v252
	v_mul_f32_e32 v215, v215, v253
	v_mul_f32_e32 v216, v216, v254
	v_mul_f32_e32 v217, v217, v255
	global_store_dwordx4 v[80:81], v[214:217], off offset:1024 nt
	v_add_u32_e32 v147, 8, v140
	v_and_b32_e32 v146, 15, v147
	v_xor_b32_e32 v146, 8, v146
	v_bfe_u32 v148, v147, 4, 4
	v_mul_lo_u32 v146, v146, s92
	v_mul_lo_u32 v148, v148, s92
	v_mov_b32_e32 v147, v146
	v_mov_b32_e32 v149, v148
	ds_write2st64_b64 v77, v[146:147], v[148:149] offset1:2
	v_add_u32_e32 v138, 0x800, v74
	ds_read_u8 v139, v138
	v_add_u32_e32 v141, 0x800, v73
	ds_read_u8 v140, v141
	s_add_i32 s43, s67, 96
	v_mov_b32_e32 v138, s43
	ds_read2st64_b32 v[228:229], v138 offset1:1
	ds_read_b128 v[18:21], v227 offset:4096
	ds_read_b128 v[22:25], v227 offset:4112
	v_add_u32_e32 v150, 0x400000, v63
	v_add_u32_e32 v151, 0x400000, v64
	v_mov_b32_e32 v38, 0
	v_mov_b32_e32 v39, 0
	v_mov_b32_e32 v40, 0
	v_mov_b32_e32 v41, 0
	v_mov_b32_e32 v42, 0
	v_mov_b32_e32 v43, 0
	v_mov_b32_e32 v44, 0
	v_mov_b32_e32 v45, 0
	v_and_b32_e32 v78, 0xffff, v31
	v_lshrrev_b32_e32 v79, 16, v31
	v_lshl_add_u32 v78, v78, 7, v152
	v_lshl_add_u32 v79, v79, 7, v153
	s_mov_b32 m0, s79
	s_add_i32 s43, s79, 0x400
	global_load_lds_dwordx4 v78, s[50:51]
	s_mov_b32 m0, s43
	s_nop 0
	global_load_lds_dwordx4 v79, s[50:51]
	s_waitcnt vmcnt(9)
; #define LAS __attribute__((address_space(3)))
; __device__ __forceinline__ bf16 f2bf(float f) { return (bf16)f2bfu(f); }
; #define TR4(p_) __builtin_amdgcn_ds_read_tr4_b64_v2i32((LAS v2i*)(p_))
; #define VDMA(st_, k_) do { _Pragma("unroll") for (int i_ = 0; i_ < 4; ++i_) { \
;         const unsigned off_ = (unsigned)((st_) >> 2) * (16384u * 128u) + (PE_ID(E, 4 * ((st_) & 3) + i_) << 7) + ((i_ & 1) ? cx1 : cx0); \
;         __builtin_amdgcn_global_load_lds((const unsigned*)(V4 + off_), (LAS unsigned*)(ldsb + BUF[k_] + 1024 * i_), 16, 0, 0); } } while (0)
; __device__ __forceinline__ void peer_v_tokens(int j, const LAS unsigned short* EL, const LAS unsigned char* AL  , const LAS float* ASC  , const LAS int* SAL  , ...
;     ...
;         for (int st = 0; st < 16; ++st) {
;             const int p = st >> 2, q = st & 3;
;             if (st < 14) VDMA(st + 2, (st + 2) % 3);
;             if (st < 14) asm volatile("s_waitcnt vmcnt(8)" ::: "memory");
;             else if (st == 14) asm volatile("s_waitcnt vmcnt(4)" ::: "memory");
;             else asm volatile("s_waitcnt vmcnt(0)" ::: "memory");
;             if (q == 0) {
; #pragma unroll
;                 for (int r = 0; r < 4; ++r) { accH[r] = 0; accL[r] = 0; } }
; #pragma unroll
;             for (int tp = 0; tp < 2; ++tp) {
;                 const v2i ao = TR4(ATL + (2 * q + tp) * 128 + 8 * s16), ah = TR4(ATL + 1024 + (2 * q + tp) * 128 + 8 * s16);
; #pragma unroll
;                 for (int r = 0; r < 4; ++r) {
;                     const v2i d = TR4(ldsb + BUF[st % 3] + 2048 * tp + roff[r]);
;                     accH[r] = __builtin_amdgcn_sdot8(d.x, ah.x, accH[r], false); accH[r] = __builtin_amdgcn_sdot8(d.y, ah.y, accH[r], false);
;                     accL[r] = __builtin_amdgcn_sdot8(d.x, ao.x, accL[r], false); accL[r] = __builtin_amdgcn_sdot8(d.y, ao.y, accL[r], false);
;                 }
;             }
;             asm volatile("s_waitcnt lgkmcnt(0)" ::: "memory");
;             if (q == 3) {
; #pragma unroll
;                 for (int r = 0; r < 4; ++r) STASH[256 * p + 16 * (grp + 4 * r) + pc] = f2bf(asc * (float)(2 * ((accH[r] << 4) + accL[r]) + sa));
;     ...
;             for (int jq = 0; jq < 4; ++jq) { typedef unsigned u2v __attribute__((ext_vector_type(2))); const u2v pw = *(const LAS u2v*)(STASH + 4 * lane + 256 * jq); const uint2 hw = hv[jq];
	v_add_u32_e32 v54, s99, v59
	v_add_u32_e32 v55, s99, v60
	v_add_u32_e32 v56, s99, v61
	v_add_u32_e32 v57, s99, v62
	ds_read_b64_tr_b4 v[50:51], v160 offset:128
	ds_read_b64_tr_b4 v[52:53], v160 offset:1152
	ds_read_b64_tr_b4 v[130:131], v54
	ds_read_b64_tr_b4 v[132:133], v55
	ds_read_b64_tr_b4 v[134:135], v56
	ds_read_b64_tr_b4 v[136:137], v57
	s_waitcnt lgkmcnt(13)
	v_dot8c_i32_i4_e32 v38, v122, v48
	v_dot8c_i32_i4_e32 v39, v122, v46
	v_dot8c_i32_i4_e32 v40, v124, v48
	v_dot8c_i32_i4_e32 v41, v124, v46
	v_dot8c_i32_i4_e32 v42, v126, v48
	v_dot8c_i32_i4_e32 v43, v126, v46
	v_dot8c_i32_i4_e32 v44, v128, v48
	v_dot8c_i32_i4_e32 v45, v128, v46
	v_dot8c_i32_i4_e32 v38, v123, v49
	v_dot8c_i32_i4_e32 v39, v123, v47
	v_dot8c_i32_i4_e32 v40, v125, v49
	v_dot8c_i32_i4_e32 v41, v125, v47
	v_dot8c_i32_i4_e32 v42, v127, v49
	v_dot8c_i32_i4_e32 v43, v127, v47
	v_dot8c_i32_i4_e32 v44, v129, v49
	v_dot8c_i32_i4_e32 v45, v129, v47
	v_and_b32_e32 v78, 0xffff, v32
	v_lshrrev_b32_e32 v79, 16, v32
	v_lshl_add_u32 v78, v78, 7, v152
	v_lshl_add_u32 v79, v79, 7, v153
	s_mov_b32 m0, s98
	s_add_i32 s43, s98, 0x400
	global_load_lds_dwordx4 v78, s[50:51]
	s_mov_b32 m0, s43
	s_nop 0
	global_load_lds_dwordx4 v79, s[50:51]
	s_waitcnt vmcnt(9)
	v_add_u32_e32 v54, s76, v59
	v_add_u32_e32 v55, s76, v60
	v_add_u32_e32 v56, s76, v61
	v_add_u32_e32 v57, s76, v62
	ds_read_b64_tr_b4 v[46:47], v160 offset:256
	ds_read_b64_tr_b4 v[48:49], v160 offset:1280
	ds_read_b64_tr_b4 v[122:123], v54
	ds_read_b64_tr_b4 v[124:125], v55
	ds_read_b64_tr_b4 v[126:127], v56
	ds_read_b64_tr_b4 v[128:129], v57
	s_waitcnt lgkmcnt(6)
	v_dot8c_i32_i4_e32 v38, v130, v52
	v_dot8c_i32_i4_e32 v39, v130, v50
	v_dot8c_i32_i4_e32 v40, v132, v52
	v_dot8c_i32_i4_e32 v41, v132, v50
	v_dot8c_i32_i4_e32 v42, v134, v52
	v_dot8c_i32_i4_e32 v43, v134, v50
	v_dot8c_i32_i4_e32 v44, v136, v52
	v_dot8c_i32_i4_e32 v45, v136, v50
	v_dot8c_i32_i4_e32 v38, v131, v53
	v_dot8c_i32_i4_e32 v39, v131, v51
	v_dot8c_i32_i4_e32 v40, v133, v53
	v_dot8c_i32_i4_e32 v41, v133, v51
	v_dot8c_i32_i4_e32 v42, v135, v53
	v_dot8c_i32_i4_e32 v43, v135, v51
	v_dot8c_i32_i4_e32 v44, v137, v53
	v_dot8c_i32_i4_e32 v45, v137, v51
	ds_write_b16 v65, v170
	ds_write_b16_d16_hi v65, v170 offset:128
	ds_write_b16 v65, v171 offset:256
	ds_write_b16_d16_hi v65, v171 offset:384
	ds_write_b16 v65, v172 offset:512
	ds_write_b16_d16_hi v65, v172 offset:640
	ds_write_b16 v65, v173 offset:768
	ds_write_b16_d16_hi v65, v173 offset:896
	ds_write_b16 v65, v174 offset:1024
	ds_write_b16_d16_hi v65, v174 offset:1152
	ds_write_b16 v65, v175 offset:1280
	ds_write_b16_d16_hi v65, v175 offset:1408
	ds_write_b16 v65, v176 offset:1536
	ds_write_b16_d16_hi v65, v176 offset:1664
	ds_write_b16 v65, v177 offset:1792
	ds_write_b16_d16_hi v65, v177 offset:1920
	ds_read_b64 v[202:203], v154
	ds_read_b64 v[204:205], v154 offset:512
	ds_read_b64 v[206:207], v154 offset:1024
	ds_read_b64 v[208:209], v154 offset:1536
	v_and_b32_e32 v78, 0xffff, v33
	v_lshrrev_b32_e32 v79, 16, v33
	v_lshl_add_u32 v78, v78, 7, v152
	v_lshl_add_u32 v79, v79, 7, v153
	s_mov_b32 m0, s99
	s_add_i32 s43, s99, 0x400
	global_load_lds_dwordx4 v78, s[50:51]
	s_mov_b32 m0, s43
	s_nop 0
	global_load_lds_dwordx4 v79, s[50:51]
	s_waitcnt vmcnt(9)
	v_add_u32_e32 v54, s77, v59
	v_add_u32_e32 v55, s77, v60
	v_add_u32_e32 v56, s77, v61
	v_add_u32_e32 v57, s77, v62
	ds_read_b64_tr_b4 v[50:51], v160 offset:384
	ds_read_b64_tr_b4 v[52:53], v160 offset:1408
	ds_read_b64_tr_b4 v[130:131], v54
	ds_read_b64_tr_b4 v[132:133], v55
	ds_read_b64_tr_b4 v[134:135], v56
	ds_read_b64_tr_b4 v[136:137], v57
	s_waitcnt lgkmcnt(15)
	v_dot8c_i32_i4_e32 v38, v122, v48
	v_dot8c_i32_i4_e32 v39, v122, v46
	v_dot8c_i32_i4_e32 v40, v124, v48
	v_dot8c_i32_i4_e32 v41, v124, v46
	v_dot8c_i32_i4_e32 v42, v126, v48
	v_dot8c_i32_i4_e32 v43, v126, v46
	v_dot8c_i32_i4_e32 v44, v128, v48
	v_dot8c_i32_i4_e32 v45, v128, v46
	v_dot8c_i32_i4_e32 v38, v123, v49
	v_dot8c_i32_i4_e32 v39, v123, v47
	v_dot8c_i32_i4_e32 v40, v125, v49
	v_dot8c_i32_i4_e32 v41, v125, v47
	v_dot8c_i32_i4_e32 v42, v127, v49
	v_dot8c_i32_i4_e32 v43, v127, v47
	v_dot8c_i32_i4_e32 v44, v129, v49
	v_dot8c_i32_i4_e32 v45, v129, v47
	s_waitcnt lgkmcnt(15)
	v_and_b32_e32 v78, 0xffff, v18
	v_lshrrev_b32_e32 v79, 16, v18
	v_lshl_add_u32 v78, v78, 7, v150
	v_lshl_add_u32 v79, v79, 7, v151
	s_mov_b32 m0, s76
	s_add_i32 s43, s76, 0x400
	global_load_lds_dwordx4 v78, s[50:51]
	s_mov_b32 m0, s43
	s_nop 0
	global_load_lds_dwordx4 v79, s[50:51]
	s_waitcnt vmcnt(9)
	v_add_u32_e32 v54, s78, v59
	v_add_u32_e32 v55, s78, v60
	v_add_u32_e32 v56, s78, v61
	v_add_u32_e32 v57, s78, v62
	ds_read_b64_tr_b4 v[46:47], v160 offset:512
	ds_read_b64_tr_b4 v[48:49], v160 offset:1536
	ds_read_b64_tr_b4 v[122:123], v54
	ds_read_b64_tr_b4 v[124:125], v55
	ds_read_b64_tr_b4 v[126:127], v56
	ds_read_b64_tr_b4 v[128:129], v57
	s_waitcnt lgkmcnt(6)
	v_dot8c_i32_i4_e32 v38, v130, v52
	v_dot8c_i32_i4_e32 v39, v130, v50
	v_dot8c_i32_i4_e32 v40, v132, v52
	v_dot8c_i32_i4_e32 v41, v132, v50
	v_dot8c_i32_i4_e32 v42, v134, v52
	v_dot8c_i32_i4_e32 v43, v134, v50
	v_dot8c_i32_i4_e32 v44, v136, v52
	v_dot8c_i32_i4_e32 v45, v136, v50
	v_dot8c_i32_i4_e32 v38, v131, v53
	v_dot8c_i32_i4_e32 v39, v131, v51
	v_dot8c_i32_i4_e32 v40, v133, v53
	v_dot8c_i32_i4_e32 v41, v133, v51
	v_dot8c_i32_i4_e32 v42, v135, v53
	v_dot8c_i32_i4_e32 v43, v135, v51
	v_dot8c_i32_i4_e32 v44, v137, v53
	v_dot8c_i32_i4_e32 v45, v137, v51
	v_and_b32_e32 v78, 0xffff, v19
	v_lshrrev_b32_e32 v79, 16, v19
	v_lshl_add_u32 v78, v78, 7, v150
	v_lshl_add_u32 v79, v79, 7, v151
	s_mov_b32 m0, s77
	s_add_i32 s43, s77, 0x400
	global_load_lds_dwordx4 v78, s[50:51]
	s_mov_b32 m0, s43
	s_nop 0
	global_load_lds_dwordx4 v79, s[50:51]
	s_waitcnt vmcnt(8)
; __device__ __forceinline__ bf16 f2bf(float f) { return (bf16)f2bfu(f); }
; #define TR4(p_) __builtin_amdgcn_ds_read_tr4_b64_v2i32((LAS v2i*)(p_))
; #define VDMA(st_, k_) do { _Pragma("unroll") for (int i_ = 0; i_ < 4; ++i_) { \
;         const unsigned off_ = (unsigned)((st_) >> 2) * (16384u * 128u) + (PE_ID(E, 4 * ((st_) & 3) + i_) << 7) + ((i_ & 1) ? cx1 : cx0); \
;         __builtin_amdgcn_global_load_lds((const unsigned*)(V4 + off_), (LAS unsigned*)(ldsb + BUF[k_] + 1024 * i_), 16, 0, 0); } } while (0)
; __device__ __forceinline__ void peer_v_tokens(int j, const LAS unsigned short* EL, const LAS unsigned char* AL  , const LAS float* ASC  , const LAS int* SAL  , ...
;     ...
;         for (int st = 0; st < 16; ++st) {
;             const int p = st >> 2, q = st & 3;
;             if (st < 14) VDMA(st + 2, (st + 2) % 3);
;             if (st < 14) asm volatile("s_waitcnt vmcnt(8)" ::: "memory");
;             else if (st == 14) asm volatile("s_waitcnt vmcnt(4)" ::: "memory");
;             else asm volatile("s_waitcnt vmcnt(0)" ::: "memory");
;             if (q == 0) {
; #pragma unroll
;                 for (int r = 0; r < 4; ++r) { accH[r] = 0; accL[r] = 0; } }
; #pragma unroll
;             for (int tp = 0; tp < 2; ++tp) {
;                 const v2i ao = TR4(ATL + (2 * q + tp) * 128 + 8 * s16), ah = TR4(ATL + 1024 + (2 * q + tp) * 128 + 8 * s16);
; #pragma unroll
;                 for (int r = 0; r < 4; ++r) {
;                     const v2i d = TR4(ldsb + BUF[st % 3] + 2048 * tp + roff[r]);
;                     accH[r] = __builtin_amdgcn_sdot8(d.x, ah.x, accH[r], false); accH[r] = __builtin_amdgcn_sdot8(d.y, ah.y, accH[r], false);
;                     accL[r] = __builtin_amdgcn_sdot8(d.x, ao.x, accL[r], false); accL[r] = __builtin_amdgcn_sdot8(d.y, ao.y, accL[r], false);
;                 }
;             }
;             asm volatile("s_waitcnt lgkmcnt(0)" ::: "memory");
;             if (q == 3) {
; #pragma unroll
;                 for (int r = 0; r < 4; ++r) STASH[256 * p + 16 * (grp + 4 * r) + pc] = f2bf(asc * (float)(2 * ((accH[r] << 4) + accL[r]) + sa));
;             }
	v_add_u32_e32 v54, s79, v59
	v_add_u32_e32 v55, s79, v60
	v_add_u32_e32 v56, s79, v61
	v_add_u32_e32 v57, s79, v62
	ds_read_b64_tr_b4 v[50:51], v160 offset:640
	ds_read_b64_tr_b4 v[52:53], v160 offset:1664
	ds_read_b64_tr_b4 v[130:131], v54
	ds_read_b64_tr_b4 v[132:133], v55
	ds_read_b64_tr_b4 v[134:135], v56
	ds_read_b64_tr_b4 v[136:137], v57
	s_waitcnt lgkmcnt(6)
	v_dot8c_i32_i4_e32 v38, v122, v48
	v_dot8c_i32_i4_e32 v39, v122, v46
	v_dot8c_i32_i4_e32 v40, v124, v48
	v_dot8c_i32_i4_e32 v41, v124, v46
	v_dot8c_i32_i4_e32 v42, v126, v48
	v_dot8c_i32_i4_e32 v43, v126, v46
	v_dot8c_i32_i4_e32 v44, v128, v48
	v_dot8c_i32_i4_e32 v45, v128, v46
	v_dot8c_i32_i4_e32 v38, v123, v49
	v_dot8c_i32_i4_e32 v39, v123, v47
	v_dot8c_i32_i4_e32 v40, v125, v49
	v_dot8c_i32_i4_e32 v41, v125, v47
	v_dot8c_i32_i4_e32 v42, v127, v49
	v_dot8c_i32_i4_e32 v43, v127, v47
	v_dot8c_i32_i4_e32 v44, v129, v49
	v_dot8c_i32_i4_e32 v45, v129, v47
	s_waitcnt lgkmcnt(15)
	v_add_u32_e32 v143, 8, v139
	v_and_b32_e32 v142, 15, v143
	v_xor_b32_e32 v142, 8, v142
	v_bfe_u32 v144, v143, 4, 4
	v_mul_lo_u32 v142, v142, s92
	v_mul_lo_u32 v144, v144, s92
	v_mov_b32_e32 v143, v142
	v_mov_b32_e32 v145, v144
	ds_write2st64_b64 v159, v[142:143], v[144:145] offset1:2
	v_and_b32_e32 v78, 0xffff, v20
	v_lshrrev_b32_e32 v79, 16, v20
	v_lshl_add_u32 v78, v78, 7, v150
	v_lshl_add_u32 v79, v79, 7, v151
	s_mov_b32 m0, s78
	s_add_i32 s43, s78, 0x400
	global_load_lds_dwordx4 v78, s[50:51]
	s_mov_b32 m0, s43
	s_nop 0
	global_load_lds_dwordx4 v79, s[50:51]
	s_waitcnt vmcnt(8)
	v_add_u32_e32 v54, s98, v59
	v_add_u32_e32 v55, s98, v60
	v_add_u32_e32 v56, s98, v61
	v_add_u32_e32 v57, s98, v62
	ds_read_b64_tr_b4 v[46:47], v160 offset:768
	ds_read_b64_tr_b4 v[48:49], v160 offset:1792
	ds_read_b64_tr_b4 v[122:123], v54
	ds_read_b64_tr_b4 v[124:125], v55
	ds_read_b64_tr_b4 v[126:127], v56
	ds_read_b64_tr_b4 v[128:129], v57
	s_waitcnt lgkmcnt(7)
	v_dot8c_i32_i4_e32 v38, v130, v52
	v_dot8c_i32_i4_e32 v39, v130, v50
	v_dot8c_i32_i4_e32 v40, v132, v52
	v_dot8c_i32_i4_e32 v41, v132, v50
	v_dot8c_i32_i4_e32 v42, v134, v52
	v_dot8c_i32_i4_e32 v43, v134, v50
	v_dot8c_i32_i4_e32 v44, v136, v52
	v_dot8c_i32_i4_e32 v45, v136, v50
	v_dot8c_i32_i4_e32 v38, v131, v53
	v_dot8c_i32_i4_e32 v39, v131, v51
	v_dot8c_i32_i4_e32 v40, v133, v53
	v_dot8c_i32_i4_e32 v41, v133, v51
	v_dot8c_i32_i4_e32 v42, v135, v53
	v_dot8c_i32_i4_e32 v43, v135, v51
	v_dot8c_i32_i4_e32 v44, v137, v53
	v_dot8c_i32_i4_e32 v45, v137, v51
	v_and_b32_e32 v78, 0xffff, v21
	v_lshrrev_b32_e32 v79, 16, v21
	v_lshl_add_u32 v78, v78, 7, v150
	v_lshl_add_u32 v79, v79, 7, v151
	s_mov_b32 m0, s79
	s_add_i32 s43, s79, 0x400
	global_load_lds_dwordx4 v78, s[50:51]
	s_mov_b32 m0, s43
	s_nop 0
	global_load_lds_dwordx4 v79, s[50:51]
	s_waitcnt vmcnt(8)
	v_add_u32_e32 v54, s99, v59
	v_add_u32_e32 v55, s99, v60
	v_add_u32_e32 v56, s99, v61
	v_add_u32_e32 v57, s99, v62
	ds_read_b64_tr_b4 v[50:51], v160 offset:896
	ds_read_b64_tr_b4 v[52:53], v160 offset:1920
	ds_read_b64_tr_b4 v[130:131], v54
	ds_read_b64_tr_b4 v[132:133], v55
	ds_read_b64_tr_b4 v[134:135], v56
	ds_read_b64_tr_b4 v[136:137], v57
	s_waitcnt lgkmcnt(6)
	v_dot8c_i32_i4_e32 v38, v122, v48
	v_dot8c_i32_i4_e32 v39, v122, v46
	v_dot8c_i32_i4_e32 v40, v124, v48
	v_dot8c_i32_i4_e32 v41, v124, v46
	v_dot8c_i32_i4_e32 v42, v126, v48
	v_dot8c_i32_i4_e32 v43, v126, v46
	v_dot8c_i32_i4_e32 v44, v128, v48
	v_dot8c_i32_i4_e32 v45, v128, v46
	v_dot8c_i32_i4_e32 v38, v123, v49
	v_dot8c_i32_i4_e32 v39, v123, v47
	v_dot8c_i32_i4_e32 v40, v125, v49
	v_dot8c_i32_i4_e32 v41, v125, v47
	v_dot8c_i32_i4_e32 v42, v127, v49
	v_dot8c_i32_i4_e32 v43, v127, v47
	v_dot8c_i32_i4_e32 v44, v129, v49
	v_dot8c_i32_i4_e32 v45, v129, v47
	v_and_b32_e32 v78, 0xffff, v22
	v_lshrrev_b32_e32 v79, 16, v22
	v_lshl_add_u32 v78, v78, 7, v150
	v_lshl_add_u32 v79, v79, 7, v151
	s_mov_b32 m0, s98
	s_add_i32 s43, s98, 0x400
	global_load_lds_dwordx4 v78, s[50:51]
	s_mov_b32 m0, s43
	s_nop 0
	global_load_lds_dwordx4 v79, s[50:51]
	s_waitcnt vmcnt(8)
	v_add_u32_e32 v54, s76, v59
	v_add_u32_e32 v55, s76, v60
	v_add_u32_e32 v56, s76, v61
	v_add_u32_e32 v57, s76, v62
	ds_read_b64_tr_b4 v[46:47], v160
	ds_read_b64_tr_b4 v[48:49], v160 offset:1024
	ds_read_b64_tr_b4 v[122:123], v54
	ds_read_b64_tr_b4 v[124:125], v55
	ds_read_b64_tr_b4 v[126:127], v56
	ds_read_b64_tr_b4 v[128:129], v57
	s_waitcnt lgkmcnt(6)
	v_dot8c_i32_i4_e32 v38, v130, v52
	v_dot8c_i32_i4_e32 v39, v130, v50
	v_dot8c_i32_i4_e32 v40, v132, v52
	v_dot8c_i32_i4_e32 v41, v132, v50
	v_dot8c_i32_i4_e32 v42, v134, v52
	v_dot8c_i32_i4_e32 v43, v134, v50
	v_dot8c_i32_i4_e32 v44, v136, v52
	v_dot8c_i32_i4_e32 v45, v136, v50
	v_dot8c_i32_i4_e32 v38, v131, v53
	v_dot8c_i32_i4_e32 v39, v131, v51
	v_dot8c_i32_i4_e32 v40, v133, v53
	v_dot8c_i32_i4_e32 v41, v133, v51
	v_dot8c_i32_i4_e32 v42, v135, v53
	v_dot8c_i32_i4_e32 v43, v135, v51
	v_dot8c_i32_i4_e32 v44, v137, v53
	v_dot8c_i32_i4_e32 v45, v137, v51
	s_nop 3
	s_waitcnt lgkmcnt(15)
	v_lshlrev_b32_e32 v38, 5, v38
	v_lshlrev_b32_e32 v39, 1, v39
	v_add3_u32 v38, v39, v229, v38
	v_cvt_f32_i32_e32 v38, v38
	v_mul_f32_e32 v38, v228, v38
	v_lshlrev_b32_e32 v40, 5, v40
	v_lshlrev_b32_e32 v41, 1, v41
	v_add3_u32 v40, v41, v229, v40
	v_cvt_f32_i32_e32 v40, v40
	v_mul_f32_e32 v40, v228, v40
	v_lshlrev_b32_e32 v42, 5, v42
	v_lshlrev_b32_e32 v43, 1, v43
	v_add3_u32 v42, v43, v229, v42
	v_cvt_f32_i32_e32 v42, v42
	v_mul_f32_e32 v42, v228, v42
	v_lshlrev_b32_e32 v44, 5, v44
	v_lshlrev_b32_e32 v45, 1, v45
	v_add3_u32 v44, v45, v229, v44
	v_cvt_f32_i32_e32 v44, v44
	v_mul_f32_e32 v44, v228, v44
	v_cvt_pk_bf16_f32 v188, v38, v40
	v_cvt_pk_bf16_f32 v189, v42, v44
	ds_read_b128 v[252:255], v156
	s_add_i32 s44, s40, 0
	s_ashr_i32 s45, s44, 31
	s_lshl_b64 s[44:45], s[44:45], 12
	v_lshl_add_u64 v[80:81], v[36:37], 0, s[44:45]
	s_waitcnt lgkmcnt(0)
; #define LAS __attribute__((address_space(3)))
; __device__ __forceinline__ void peer_v_tokens(int j, const LAS unsigned short* EL, const LAS unsigned char* AL  , const LAS float* ASC  , const LAS int* SAL  , ...
;     ...
;         {
;             float4 v[4]; float ss = 0.f;
; #pragma unroll
;             for (int jq = 0; jq < 4; ++jq) { typedef unsigned u2v __attribute__((ext_vector_type(2))); const u2v pw = *(const LAS u2v*)(STASH + 4 * lane + 256 * jq); const uint2 hw = hv[jq];
;                 v[jq] = make_float4(__uint_as_float(hw.x << 16) + __uint_as_float(pw.x << 16), __uint_as_float(hw.x & 0xffff0000u) + __uint_as_float(pw.x & 0xffff0000u),
;                                     __uint_as_float(hw.y << 16) + __uint_as_float(pw.y << 16), __uint_as_float(hw.y & 0xffff0000u) + __uint_as_float(pw.y & 0xffff0000u));
;                 ss += v[jq].x * v[jq].x + v[jq].y * v[jq].y + v[jq].z * v[jq].z + v[jq].w * v[jq].w; }
;             ss = wave_sum(ss);
;             const float r3 = rsqrtf(ss * (1.f / D) + EPS);
;             float4* op = (float4*)(outp + (size_t)t * D) + lane;
; #pragma unroll
;             for (int jq = 0; jq < 4; ++jq) { typedef float f4v __attribute__((ext_vector_type(4))); f4v o4; o4.x = v[jq].x * r3 * gv[jq].x; o4.y = v[jq].y * r3 * gv[jq].y; o4.z = v[jq].z * r3 * gv[jq].z; o4.w = v[jq].w * r3 * gv[jq].w;
;                 __builtin_nontemporal_store(o4, (f4v*)op + 64 * jq); }
;         }
	v_mul_f32_e32 v218, v218, v252
	v_mul_f32_e32 v219, v219, v253
	v_mul_f32_e32 v220, v220, v254
	v_mul_f32_e32 v221, v221, v255
	global_store_dwordx4 v[80:81], v[218:221], off offset:2048 nt
	v_add_u32_e32 v147, 8, v140
	v_and_b32_e32 v146, 15, v147
	v_xor_b32_e32 v146, 8, v146
	v_bfe_u32 v148, v147, 4, 4
	v_mul_lo_u32 v146, v146, s92
	v_mul_lo_u32 v148, v148, s92
	v_mov_b32_e32 v147, v146
	v_mov_b32_e32 v149, v148
	ds_write2st64_b64 v77, v[146:147], v[148:149] offset1:2
	v_add_u32_e32 v138, 0xc00, v74
	ds_read_u8 v139, v138
	v_add_u32_e32 v141, 0xc00, v73
	ds_read_u8 v140, v141
	s_add_i32 s43, s67, 64
	v_mov_b32_e32 v138, s43
	ds_read2st64_b32 v[228:229], v138 offset1:1
	ds_read_b128 v[26:29], v227 offset:6144
	ds_read_b128 v[30:33], v227 offset:6160
	v_mov_b32_e32 v38, 0
	v_mov_b32_e32 v39, 0
	v_mov_b32_e32 v40, 0
	v_mov_b32_e32 v41, 0
	v_mov_b32_e32 v42, 0
	v_mov_b32_e32 v43, 0
	v_mov_b32_e32 v44, 0
	v_mov_b32_e32 v45, 0
	v_and_b32_e32 v78, 0xffff, v23
	v_lshrrev_b32_e32 v79, 16, v23
	v_lshl_add_u32 v78, v78, 7, v150
	v_lshl_add_u32 v79, v79, 7, v151
	s_mov_b32 m0, s99
	s_add_i32 s43, s99, 0x400
	global_load_lds_dwordx4 v78, s[50:51]
	s_mov_b32 m0, s43
	s_nop 0
	global_load_lds_dwordx4 v79, s[50:51]
	s_waitcnt vmcnt(9)
	v_add_u32_e32 v54, s77, v59
	v_add_u32_e32 v55, s77, v60
	v_add_u32_e32 v56, s77, v61
	v_add_u32_e32 v57, s77, v62
	ds_read_b64_tr_b4 v[50:51], v160 offset:128
	ds_read_b64_tr_b4 v[52:53], v160 offset:1152
	ds_read_b64_tr_b4 v[130:131], v54
	ds_read_b64_tr_b4 v[132:133], v55
	ds_read_b64_tr_b4 v[134:135], v56
	ds_read_b64_tr_b4 v[136:137], v57
	s_waitcnt lgkmcnt(13)
	s_waitcnt vmcnt(36) lgkmcnt(15)
	v_lshlrev_b32_e32 v236, 16, v194
	v_and_b32_e32 v237, 0xffff0000, v194
	v_lshlrev_b32_e32 v142, 16, v202
	v_and_b32_e32 v143, 0xffff0000, v202
	v_add_f32_e32 v236, v236, v142
	v_add_f32_e32 v237, v237, v143
	v_lshlrev_b32_e32 v238, 16, v195
	v_and_b32_e32 v239, 0xffff0000, v195
	v_lshlrev_b32_e32 v142, 16, v203
	v_and_b32_e32 v143, 0xffff0000, v203
	v_add_f32_e32 v238, v238, v142
	v_add_f32_e32 v239, v239, v143
	v_lshlrev_b32_e32 v240, 16, v196
	v_and_b32_e32 v241, 0xffff0000, v196
	v_lshlrev_b32_e32 v142, 16, v204
	v_and_b32_e32 v143, 0xffff0000, v204
	v_add_f32_e32 v240, v240, v142
	v_add_f32_e32 v241, v241, v143
	v_lshlrev_b32_e32 v242, 16, v197
	v_and_b32_e32 v243, 0xffff0000, v197
	v_lshlrev_b32_e32 v142, 16, v205
	v_and_b32_e32 v143, 0xffff0000, v205
	v_add_f32_e32 v242, v242, v142
	v_add_f32_e32 v243, v243, v143
	v_lshlrev_b32_e32 v244, 16, v198
	v_and_b32_e32 v245, 0xffff0000, v198
	v_lshlrev_b32_e32 v142, 16, v206
	v_and_b32_e32 v143, 0xffff0000, v206
	v_add_f32_e32 v244, v244, v142
	v_add_f32_e32 v245, v245, v143
	v_lshlrev_b32_e32 v246, 16, v199
	v_and_b32_e32 v247, 0xffff0000, v199
	v_lshlrev_b32_e32 v142, 16, v207
	v_and_b32_e32 v143, 0xffff0000, v207
	v_add_f32_e32 v246, v246, v142
	v_add_f32_e32 v247, v247, v143
	v_lshlrev_b32_e32 v248, 16, v200
	v_and_b32_e32 v249, 0xffff0000, v200
	v_lshlrev_b32_e32 v142, 16, v208
	v_and_b32_e32 v143, 0xffff0000, v208
	v_add_f32_e32 v248, v248, v142
	v_add_f32_e32 v249, v249, v143
	v_lshlrev_b32_e32 v250, 16, v201
	v_and_b32_e32 v251, 0xffff0000, v201
	v_lshlrev_b32_e32 v142, 16, v209
	v_and_b32_e32 v143, 0xffff0000, v209
	v_add_f32_e32 v250, v250, v142
	v_add_f32_e32 v251, v251, v143
	v_mov_b32_e32 v144, 0
	v_mul_f32_e32 v145, v236, v236
	v_fmac_f32_e32 v145, v237, v237
	v_fmac_f32_e32 v145, v238, v238
	v_fmac_f32_e32 v145, v239, v239
	v_add_f32_e32 v144, v144, v145
	v_mul_f32_e32 v145, v240, v240
	v_fmac_f32_e32 v145, v241, v241
	v_fmac_f32_e32 v145, v242, v242
	v_fmac_f32_e32 v145, v243, v243
	v_add_f32_e32 v144, v144, v145
	v_mul_f32_e32 v145, v244, v244
	v_fmac_f32_e32 v145, v245, v245
	v_fmac_f32_e32 v145, v246, v246
	v_fmac_f32_e32 v145, v247, v247
	v_add_f32_e32 v144, v144, v145
	v_mul_f32_e32 v145, v248, v248
	v_fmac_f32_e32 v145, v249, v249
	v_fmac_f32_e32 v145, v250, v250
	v_fmac_f32_e32 v145, v251, v251
	v_add_f32_e32 v144, v144, v145
	s_nop 1
	v_add_f32_dpp v144, v144, v144 quad_perm:[1,0,3,2] row_mask:0xf bank_mask:0xf bound_ctrl:1
	s_nop 1
	v_add_f32_dpp v144, v144, v144 quad_perm:[2,3,0,1] row_mask:0xf bank_mask:0xf bound_ctrl:1
	s_nop 1
	v_add_f32_dpp v144, v144, v144 row_half_mirror row_mask:0xf bank_mask:0xf bound_ctrl:1
	s_nop 1
	v_add_f32_dpp v144, v144, v144 row_mirror row_mask:0xf bank_mask:0xf bound_ctrl:1
	s_nop 1
	v_readlane_b32 s10, v144, 0
	v_readlane_b32 s11, v144, 16
	v_readlane_b32 s14, v144, 32
	v_readlane_b32 s15, v144, 48
	s_nop 3
	v_mov_b32_e32 v144, s11
	v_mov_b32_e32 v145, s15
	v_add_f32_e32 v144, s10, v144
	v_add_f32_e32 v145, s14, v145
	v_add_f32_e32 v144, v144, v145
	v_fmamk_f32 v144, v144, 0x3a800000, v111
	v_rsq_f32_e32 v144, v144
	s_nop 0
	v_mul_f32_e32 v236, v236, v144
	v_mul_f32_e32 v237, v237, v144
	v_mul_f32_e32 v238, v238, v144
	v_mul_f32_e32 v239, v239, v144
	v_mul_f32_e32 v240, v240, v144
	v_mul_f32_e32 v241, v241, v144
	v_mul_f32_e32 v242, v242, v144
	v_mul_f32_e32 v243, v243, v144
	v_mul_f32_e32 v244, v244, v144
	v_mul_f32_e32 v245, v245, v144
	v_mul_f32_e32 v246, v246, v144
	v_mul_f32_e32 v247, v247, v144
	v_mul_f32_e32 v248, v248, v144
	v_mul_f32_e32 v249, v249, v144
	v_mul_f32_e32 v250, v250, v144
	v_mul_f32_e32 v251, v251, v144
	v_dot8c_i32_i4_e32 v38, v122, v48
	v_dot8c_i32_i4_e32 v39, v122, v46
	v_dot8c_i32_i4_e32 v40, v124, v48
	v_dot8c_i32_i4_e32 v41, v124, v46
	v_dot8c_i32_i4_e32 v42, v126, v48
	v_dot8c_i32_i4_e32 v43, v126, v46
	v_dot8c_i32_i4_e32 v44, v128, v48
	v_dot8c_i32_i4_e32 v45, v128, v46
	v_dot8c_i32_i4_e32 v38, v123, v49
	v_dot8c_i32_i4_e32 v39, v123, v47
	v_dot8c_i32_i4_e32 v40, v125, v49
	v_dot8c_i32_i4_e32 v41, v125, v47
	v_dot8c_i32_i4_e32 v42, v127, v49
	v_dot8c_i32_i4_e32 v43, v127, v47
	v_dot8c_i32_i4_e32 v44, v129, v49
	v_dot8c_i32_i4_e32 v45, v129, v47
	v_and_b32_e32 v78, 0xffff, v24
	v_lshrrev_b32_e32 v79, 16, v24
	v_lshl_add_u32 v78, v78, 7, v150
	v_lshl_add_u32 v79, v79, 7, v151
	s_mov_b32 m0, s76
	s_add_i32 s43, s76, 0x400
	global_load_lds_dwordx4 v78, s[50:51]
	s_mov_b32 m0, s43
	s_nop 0
	global_load_lds_dwordx4 v79, s[50:51]
	s_waitcnt vmcnt(9)
; #define TR4(p_) __builtin_amdgcn_ds_read_tr4_b64_v2i32((LAS v2i*)(p_))
; #define VDMA(st_, k_) do { _Pragma("unroll") for (int i_ = 0; i_ < 4; ++i_) { \
;         const unsigned off_ = (unsigned)((st_) >> 2) * (16384u * 128u) + (PE_ID(E, 4 * ((st_) & 3) + i_) << 7) + ((i_ & 1) ? cx1 : cx0); \
;         __builtin_amdgcn_global_load_lds((const unsigned*)(V4 + off_), (LAS unsigned*)(ldsb + BUF[k_] + 1024 * i_), 16, 0, 0); } } while (0)
; __device__ __forceinline__ void peer_v_tokens(int j, const LAS unsigned short* EL, const LAS unsigned char* AL  , const LAS float* ASC  , const LAS int* SAL  , ...
;     ...
;         for (int st = 0; st < 16; ++st) {
;             const int p = st >> 2, q = st & 3;
;             if (st < 14) VDMA(st + 2, (st + 2) % 3);
;             if (st < 14) asm volatile("s_waitcnt vmcnt(8)" ::: "memory");
;             else if (st == 14) asm volatile("s_waitcnt vmcnt(4)" ::: "memory");
;             else asm volatile("s_waitcnt vmcnt(0)" ::: "memory");
;             if (q == 0) {
; #pragma unroll
;                 for (int r = 0; r < 4; ++r) { accH[r] = 0; accL[r] = 0; } }
; #pragma unroll
;             for (int tp = 0; tp < 2; ++tp) {
;                 const v2i ao = TR4(ATL + (2 * q + tp) * 128 + 8 * s16), ah = TR4(ATL + 1024 + (2 * q + tp) * 128 + 8 * s16);
; #pragma unroll
;                 for (int r = 0; r < 4; ++r) {
;                     const v2i d = TR4(ldsb + BUF[st % 3] + 2048 * tp + roff[r]);
;                     accH[r] = __builtin_amdgcn_sdot8(d.x, ah.x, accH[r], false); accH[r] = __builtin_amdgcn_sdot8(d.y, ah.y, accH[r], false);
;                     accL[r] = __builtin_amdgcn_sdot8(d.x, ao.x, accL[r], false); accL[r] = __builtin_amdgcn_sdot8(d.y, ao.y, accL[r], false);
;                 }
;             }
;             asm volatile("s_waitcnt lgkmcnt(0)" ::: "memory");
	v_add_u32_e32 v54, s78, v59
	v_add_u32_e32 v55, s78, v60
	v_add_u32_e32 v56, s78, v61
	v_add_u32_e32 v57, s78, v62
	ds_read_b64_tr_b4 v[46:47], v160 offset:256
	ds_read_b64_tr_b4 v[48:49], v160 offset:1280
	ds_read_b64_tr_b4 v[122:123], v54
	ds_read_b64_tr_b4 v[124:125], v55
	ds_read_b64_tr_b4 v[126:127], v56
	ds_read_b64_tr_b4 v[128:129], v57
	s_waitcnt lgkmcnt(6)
	v_dot8c_i32_i4_e32 v38, v130, v52
	v_dot8c_i32_i4_e32 v39, v130, v50
	v_dot8c_i32_i4_e32 v40, v132, v52
	v_dot8c_i32_i4_e32 v41, v132, v50
	v_dot8c_i32_i4_e32 v42, v134, v52
	v_dot8c_i32_i4_e32 v43, v134, v50
	v_dot8c_i32_i4_e32 v44, v136, v52
	v_dot8c_i32_i4_e32 v45, v136, v50
	v_dot8c_i32_i4_e32 v38, v131, v53
	v_dot8c_i32_i4_e32 v39, v131, v51
	v_dot8c_i32_i4_e32 v40, v133, v53
	v_dot8c_i32_i4_e32 v41, v133, v51
	v_dot8c_i32_i4_e32 v42, v135, v53
	v_dot8c_i32_i4_e32 v43, v135, v51
	v_dot8c_i32_i4_e32 v44, v137, v53
	v_dot8c_i32_i4_e32 v45, v137, v51
	v_and_b32_e32 v78, 0xffff, v25
	v_lshrrev_b32_e32 v79, 16, v25
	v_lshl_add_u32 v78, v78, 7, v150
	v_lshl_add_u32 v79, v79, 7, v151
	s_mov_b32 m0, s77
	s_add_i32 s43, s77, 0x400
	global_load_lds_dwordx4 v78, s[50:51]
	s_mov_b32 m0, s43
	s_nop 0
	global_load_lds_dwordx4 v79, s[50:51]
	s_waitcnt vmcnt(9)
	v_add_u32_e32 v54, s79, v59
	v_add_u32_e32 v55, s79, v60
	v_add_u32_e32 v56, s79, v61
	v_add_u32_e32 v57, s79, v62
	ds_read_b64_tr_b4 v[50:51], v160 offset:384
	ds_read_b64_tr_b4 v[52:53], v160 offset:1408
	ds_read_b64_tr_b4 v[130:131], v54
	ds_read_b64_tr_b4 v[132:133], v55
	ds_read_b64_tr_b4 v[134:135], v56
	ds_read_b64_tr_b4 v[136:137], v57
	s_waitcnt lgkmcnt(6)
	v_dot8c_i32_i4_e32 v38, v122, v48
	v_dot8c_i32_i4_e32 v39, v122, v46
	v_dot8c_i32_i4_e32 v40, v124, v48
	v_dot8c_i32_i4_e32 v41, v124, v46
	v_dot8c_i32_i4_e32 v42, v126, v48
	v_dot8c_i32_i4_e32 v43, v126, v46
	v_dot8c_i32_i4_e32 v44, v128, v48
	v_dot8c_i32_i4_e32 v45, v128, v46
	v_dot8c_i32_i4_e32 v38, v123, v49
	v_dot8c_i32_i4_e32 v39, v123, v47
	v_dot8c_i32_i4_e32 v40, v125, v49
	v_dot8c_i32_i4_e32 v41, v125, v47
	v_dot8c_i32_i4_e32 v42, v127, v49
	v_dot8c_i32_i4_e32 v43, v127, v47
	v_dot8c_i32_i4_e32 v44, v129, v49
	v_dot8c_i32_i4_e32 v45, v129, v47
	s_waitcnt lgkmcnt(15)
	v_and_b32_e32 v78, 0xffff, v26
	v_lshrrev_b32_e32 v79, 16, v26
	v_lshl_add_u32 v78, v78, 7, v150
	v_lshl_add_u32 v79, v79, 7, v151
	s_mov_b32 m0, s78
	s_add_i32 s43, s78, 0x400
	global_load_lds_dwordx4 v78, s[50:51]
	s_mov_b32 m0, s43
	s_nop 0
	global_load_lds_dwordx4 v79, s[50:51]
	s_waitcnt vmcnt(9)
	v_add_u32_e32 v54, s98, v59
	v_add_u32_e32 v55, s98, v60
	v_add_u32_e32 v56, s98, v61
	v_add_u32_e32 v57, s98, v62
	ds_read_b64_tr_b4 v[46:47], v160 offset:512
	ds_read_b64_tr_b4 v[48:49], v160 offset:1536
	ds_read_b64_tr_b4 v[122:123], v54
	ds_read_b64_tr_b4 v[124:125], v55
	ds_read_b64_tr_b4 v[126:127], v56
	ds_read_b64_tr_b4 v[128:129], v57
	s_waitcnt lgkmcnt(6)
	v_dot8c_i32_i4_e32 v38, v130, v52
	v_dot8c_i32_i4_e32 v39, v130, v50
	v_dot8c_i32_i4_e32 v40, v132, v52
	v_dot8c_i32_i4_e32 v41, v132, v50
	v_dot8c_i32_i4_e32 v42, v134, v52
	v_dot8c_i32_i4_e32 v43, v134, v50
	v_dot8c_i32_i4_e32 v44, v136, v52
	v_dot8c_i32_i4_e32 v45, v136, v50
	v_dot8c_i32_i4_e32 v38, v131, v53
	v_dot8c_i32_i4_e32 v39, v131, v51
	v_dot8c_i32_i4_e32 v40, v133, v53
	v_dot8c_i32_i4_e32 v41, v133, v51
	v_dot8c_i32_i4_e32 v42, v135, v53
	v_dot8c_i32_i4_e32 v43, v135, v51
	v_dot8c_i32_i4_e32 v44, v137, v53
	v_dot8c_i32_i4_e32 v45, v137, v51
	v_and_b32_e32 v78, 0xffff, v27
	v_lshrrev_b32_e32 v79, 16, v27
	v_lshl_add_u32 v78, v78, 7, v150
	v_lshl_add_u32 v79, v79, 7, v151
	s_mov_b32 m0, s79
	s_add_i32 s43, s79, 0x400
	global_load_lds_dwordx4 v78, s[50:51]
	s_mov_b32 m0, s43
	s_nop 0
	global_load_lds_dwordx4 v79, s[50:51]
	s_waitcnt vmcnt(8)
	v_add_u32_e32 v54, s99, v59
	v_add_u32_e32 v55, s99, v60
	v_add_u32_e32 v56, s99, v61
	v_add_u32_e32 v57, s99, v62
	ds_read_b64_tr_b4 v[50:51], v160 offset:640
	ds_read_b64_tr_b4 v[52:53], v160 offset:1664
	ds_read_b64_tr_b4 v[130:131], v54
	ds_read_b64_tr_b4 v[132:133], v55
	ds_read_b64_tr_b4 v[134:135], v56
	ds_read_b64_tr_b4 v[136:137], v57
	s_waitcnt lgkmcnt(6)
	v_dot8c_i32_i4_e32 v38, v122, v48
	v_dot8c_i32_i4_e32 v39, v122, v46
	v_dot8c_i32_i4_e32 v40, v124, v48
	v_dot8c_i32_i4_e32 v41, v124, v46
	v_dot8c_i32_i4_e32 v42, v126, v48
	v_dot8c_i32_i4_e32 v43, v126, v46
	v_dot8c_i32_i4_e32 v44, v128, v48
	v_dot8c_i32_i4_e32 v45, v128, v46
	v_dot8c_i32_i4_e32 v38, v123, v49
	v_dot8c_i32_i4_e32 v39, v123, v47
	v_dot8c_i32_i4_e32 v40, v125, v49
	v_dot8c_i32_i4_e32 v41, v125, v47
	v_dot8c_i32_i4_e32 v42, v127, v49
	v_dot8c_i32_i4_e32 v43, v127, v47
	v_dot8c_i32_i4_e32 v44, v129, v49
	v_dot8c_i32_i4_e32 v45, v129, v47
	s_waitcnt lgkmcnt(15)
	v_add_u32_e32 v143, 8, v139
	v_and_b32_e32 v142, 15, v143
	v_xor_b32_e32 v142, 8, v142
	v_bfe_u32 v144, v143, 4, 4
	v_mul_lo_u32 v142, v142, s92
	v_mul_lo_u32 v144, v144, s92
	v_mov_b32_e32 v143, v142
	v_mov_b32_e32 v145, v144
	ds_write2st64_b64 v159, v[142:143], v[144:145] offset1:2
	v_and_b32_e32 v78, 0xffff, v28
	v_lshrrev_b32_e32 v79, 16, v28
	v_lshl_add_u32 v78, v78, 7, v150
	v_lshl_add_u32 v79, v79, 7, v151
	s_mov_b32 m0, s98
	s_add_i32 s43, s98, 0x400
	global_load_lds_dwordx4 v78, s[50:51]
	s_mov_b32 m0, s43
	s_nop 0
	global_load_lds_dwordx4 v79, s[50:51]
	s_waitcnt vmcnt(8)
	v_add_u32_e32 v54, s76, v59
	v_add_u32_e32 v55, s76, v60
	v_add_u32_e32 v56, s76, v61
	v_add_u32_e32 v57, s76, v62
	ds_read_b64_tr_b4 v[46:47], v160 offset:768
	ds_read_b64_tr_b4 v[48:49], v160 offset:1792
	ds_read_b64_tr_b4 v[122:123], v54
	ds_read_b64_tr_b4 v[124:125], v55
	ds_read_b64_tr_b4 v[126:127], v56
	ds_read_b64_tr_b4 v[128:129], v57
	s_waitcnt lgkmcnt(7)
; #define LAS __attribute__((address_space(3)))
; __device__ __forceinline__ bf16 f2bf(float f) { return (bf16)f2bfu(f); }
; #define CFENCE() asm volatile("" ::: "memory")
; __device__ __forceinline__ void peer_v_tokens(int j, const LAS unsigned short* EL, const LAS unsigned char* AL  , const LAS float* ASC  , const LAS int* SAL  , ...
;     ...
;             if (q == 3) {
; #pragma unroll
;                 for (int r = 0; r < 4; ++r) STASH[256 * p + 16 * (grp + 4 * r) + pc] = f2bf(asc * (float)(2 * ((accH[r] << 4) + accL[r]) + sa));
;             }
;         }
;         CFENCE();
;         {
;             float4 v[4]; float ss = 0.f;
; #pragma unroll
;             for (int jq = 0; jq < 4; ++jq) { typedef unsigned u2v __attribute__((ext_vector_type(2))); const u2v pw = *(const LAS u2v*)(STASH + 4 * lane + 256 * jq); const uint2 hw = hv[jq];
;                 v[jq] = make_float4(__uint_as_float(hw.x << 16) + __uint_as_float(pw.x << 16), __uint_as_float(hw.x & 0xffff0000u) + __uint_as_float(pw.x & 0xffff0000u),
;                                     __uint_as_float(hw.y << 16) + __uint_as_float(pw.y << 16), __uint_as_float(hw.y & 0xffff0000u) + __uint_as_float(pw.y & 0xffff0000u));
;                 ss += v[jq].x * v[jq].x + v[jq].y * v[jq].y + v[jq].z * v[jq].z + v[jq].w * v[jq].w; }
;             ss = wave_sum(ss);
;             const float r3 = rsqrtf(ss * (1.f / D) + EPS);
;             float4* op = (float4*)(outp + (size_t)t * D) + lane;
; #pragma unroll
;             for (int jq = 0; jq < 4; ++jq) { typedef float f4v __attribute__((ext_vector_type(4))); f4v o4; o4.x = v[jq].x * r3 * gv[jq].x; o4.y = v[jq].y * r3 * gv[jq].y; o4.z = v[jq].z * r3 * gv[jq].z; o4.w = v[jq].w * r3 * gv[jq].w;
;                 __builtin_nontemporal_store(o4, (f4v*)op + 64 * jq); }
;         }
	v_dot8c_i32_i4_e32 v38, v130, v52
	v_dot8c_i32_i4_e32 v39, v130, v50
	v_dot8c_i32_i4_e32 v40, v132, v52
	v_dot8c_i32_i4_e32 v41, v132, v50
	v_dot8c_i32_i4_e32 v42, v134, v52
	v_dot8c_i32_i4_e32 v43, v134, v50
	v_dot8c_i32_i4_e32 v44, v136, v52
	v_dot8c_i32_i4_e32 v45, v136, v50
	v_dot8c_i32_i4_e32 v38, v131, v53
	v_dot8c_i32_i4_e32 v39, v131, v51
	v_dot8c_i32_i4_e32 v40, v133, v53
	v_dot8c_i32_i4_e32 v41, v133, v51
	v_dot8c_i32_i4_e32 v42, v135, v53
	v_dot8c_i32_i4_e32 v43, v135, v51
	v_dot8c_i32_i4_e32 v44, v137, v53
	v_dot8c_i32_i4_e32 v45, v137, v51
	v_and_b32_e32 v78, 0xffff, v29
	v_lshrrev_b32_e32 v79, 16, v29
	v_lshl_add_u32 v78, v78, 7, v150
	v_lshl_add_u32 v79, v79, 7, v151
	s_mov_b32 m0, s99
	s_add_i32 s43, s99, 0x400
	global_load_lds_dwordx4 v78, s[50:51]
	s_mov_b32 m0, s43
	s_nop 0
	global_load_lds_dwordx4 v79, s[50:51]
	s_waitcnt vmcnt(8)
	v_add_u32_e32 v54, s77, v59
	v_add_u32_e32 v55, s77, v60
	v_add_u32_e32 v56, s77, v61
	v_add_u32_e32 v57, s77, v62
	ds_read_b64_tr_b4 v[50:51], v160 offset:896
	ds_read_b64_tr_b4 v[52:53], v160 offset:1920
	ds_read_b64_tr_b4 v[130:131], v54
	ds_read_b64_tr_b4 v[132:133], v55
	ds_read_b64_tr_b4 v[134:135], v56
	ds_read_b64_tr_b4 v[136:137], v57
	s_waitcnt lgkmcnt(6)
	v_dot8c_i32_i4_e32 v38, v122, v48
	v_dot8c_i32_i4_e32 v39, v122, v46
	v_dot8c_i32_i4_e32 v40, v124, v48
	v_dot8c_i32_i4_e32 v41, v124, v46
	v_dot8c_i32_i4_e32 v42, v126, v48
	v_dot8c_i32_i4_e32 v43, v126, v46
	v_dot8c_i32_i4_e32 v44, v128, v48
	v_dot8c_i32_i4_e32 v45, v128, v46
	v_dot8c_i32_i4_e32 v38, v123, v49
	v_dot8c_i32_i4_e32 v39, v123, v47
	v_dot8c_i32_i4_e32 v40, v125, v49
	v_dot8c_i32_i4_e32 v41, v125, v47
	v_dot8c_i32_i4_e32 v42, v127, v49
	v_dot8c_i32_i4_e32 v43, v127, v47
	v_dot8c_i32_i4_e32 v44, v129, v49
	v_dot8c_i32_i4_e32 v45, v129, v47
	v_and_b32_e32 v78, 0xffff, v30
	v_lshrrev_b32_e32 v79, 16, v30
	v_lshl_add_u32 v78, v78, 7, v150
	v_lshl_add_u32 v79, v79, 7, v151
	s_mov_b32 m0, s76
	s_add_i32 s43, s76, 0x400
	global_load_lds_dwordx4 v78, s[50:51]
	s_mov_b32 m0, s43
	s_nop 0
	global_load_lds_dwordx4 v79, s[50:51]
	s_waitcnt vmcnt(8)
	v_add_u32_e32 v54, s78, v59
	v_add_u32_e32 v55, s78, v60
	v_add_u32_e32 v56, s78, v61
	v_add_u32_e32 v57, s78, v62
	ds_read_b64_tr_b4 v[46:47], v160
	ds_read_b64_tr_b4 v[48:49], v160 offset:1024
	ds_read_b64_tr_b4 v[122:123], v54
	ds_read_b64_tr_b4 v[124:125], v55
	ds_read_b64_tr_b4 v[126:127], v56
	ds_read_b64_tr_b4 v[128:129], v57
	s_waitcnt lgkmcnt(6)
	v_dot8c_i32_i4_e32 v38, v130, v52
	v_dot8c_i32_i4_e32 v39, v130, v50
	v_dot8c_i32_i4_e32 v40, v132, v52
	v_dot8c_i32_i4_e32 v41, v132, v50
	v_dot8c_i32_i4_e32 v42, v134, v52
	v_dot8c_i32_i4_e32 v43, v134, v50
	v_dot8c_i32_i4_e32 v44, v136, v52
	v_dot8c_i32_i4_e32 v45, v136, v50
	v_dot8c_i32_i4_e32 v38, v131, v53
	v_dot8c_i32_i4_e32 v39, v131, v51
	v_dot8c_i32_i4_e32 v40, v133, v53
	v_dot8c_i32_i4_e32 v41, v133, v51
	v_dot8c_i32_i4_e32 v42, v135, v53
	v_dot8c_i32_i4_e32 v43, v135, v51
	v_dot8c_i32_i4_e32 v44, v137, v53
	v_dot8c_i32_i4_e32 v45, v137, v51
	s_nop 3
	s_waitcnt lgkmcnt(15)
	v_lshlrev_b32_e32 v38, 5, v38
	v_lshlrev_b32_e32 v39, 1, v39
	v_add3_u32 v38, v39, v229, v38
	v_cvt_f32_i32_e32 v38, v38
	v_mul_f32_e32 v38, v228, v38
	v_lshlrev_b32_e32 v40, 5, v40
	v_lshlrev_b32_e32 v41, 1, v41
	v_add3_u32 v40, v41, v229, v40
	v_cvt_f32_i32_e32 v40, v40
	v_mul_f32_e32 v40, v228, v40
	v_lshlrev_b32_e32 v42, 5, v42
	v_lshlrev_b32_e32 v43, 1, v43
	v_add3_u32 v42, v43, v229, v42
	v_cvt_f32_i32_e32 v42, v42
	v_mul_f32_e32 v42, v228, v42
	v_lshlrev_b32_e32 v44, 5, v44
	v_lshlrev_b32_e32 v45, 1, v45
	v_add3_u32 v44, v45, v229, v44
	v_cvt_f32_i32_e32 v44, v44
	v_mul_f32_e32 v44, v228, v44
	v_cvt_pk_bf16_f32 v182, v38, v40
	v_cvt_pk_bf16_f32 v183, v42, v44
	ds_read_b128 v[252:255], v156 offset:1024
	s_add_i32 s44, s40, 0
	s_ashr_i32 s45, s44, 31
	s_lshl_b64 s[44:45], s[44:45], 12
	v_lshl_add_u64 v[80:81], v[36:37], 0, s[44:45]
	s_waitcnt lgkmcnt(0)
	v_mul_f32_e32 v222, v222, v252
	v_mul_f32_e32 v223, v223, v253
	v_mul_f32_e32 v224, v224, v254
	v_mul_f32_e32 v225, v225, v255
	global_store_dwordx4 v[80:81], v[222:225], off offset:3072 nt
	ds_read_b128 v[252:255], v155
	s_add_i32 s44, s40, 8
	s_ashr_i32 s45, s44, 31
	s_lshl_b64 s[44:45], s[44:45], 12
	v_lshl_add_u64 v[80:81], v[36:37], 0, s[44:45]
	s_waitcnt lgkmcnt(0)
	v_mul_f32_e32 v236, v236, v252
	v_mul_f32_e32 v237, v237, v253
	v_mul_f32_e32 v238, v238, v254
	v_mul_f32_e32 v239, v239, v255
	global_store_dwordx4 v[80:81], v[236:239], off nt
	v_add_u32_e32 v147, 8, v140
	v_and_b32_e32 v146, 15, v147
	v_xor_b32_e32 v146, 8, v146
	v_bfe_u32 v148, v147, 4, 4
	v_mul_lo_u32 v146, v146, s92
	v_mul_lo_u32 v148, v148, s92
	v_mov_b32_e32 v147, v146
	v_mov_b32_e32 v149, v148
	ds_write2st64_b64 v77, v[146:147], v[148:149] offset1:2
	v_add_u32_e32 v138, 0x800, v74
	ds_read_u8 v139, v138
	v_add_u32_e32 v141, 0x800, v73
	ds_read_u8 v140, v141
	s_add_i32 s43, s67, 96
	v_mov_b32_e32 v138, s43
	ds_read2st64_b32 v[228:229], v138 offset1:1
	ds_read_b128 v[18:21], v227 offset:4096
	ds_read_b128 v[22:25], v227 offset:4112
	v_add_u32_e32 v152, 0x600000, v63
	v_add_u32_e32 v153, 0x600000, v64
	v_mov_b32_e32 v38, 0
	v_mov_b32_e32 v39, 0
	v_mov_b32_e32 v40, 0
	v_mov_b32_e32 v41, 0
	v_mov_b32_e32 v42, 0
	v_mov_b32_e32 v43, 0
	v_mov_b32_e32 v44, 0
	v_mov_b32_e32 v45, 0
	v_and_b32_e32 v78, 0xffff, v31
	v_lshrrev_b32_e32 v79, 16, v31
	v_lshl_add_u32 v78, v78, 7, v150
	v_lshl_add_u32 v79, v79, 7, v151
	s_mov_b32 m0, s77
	s_add_i32 s43, s77, 0x400
	global_load_lds_dwordx4 v78, s[50:51]
	s_mov_b32 m0, s43
	s_nop 0
	global_load_lds_dwordx4 v79, s[50:51]
	s_waitcnt vmcnt(10)
; #define TR4(p_) __builtin_amdgcn_ds_read_tr4_b64_v2i32((LAS v2i*)(p_))
; #define VDMA(st_, k_) do { _Pragma("unroll") for (int i_ = 0; i_ < 4; ++i_) { \
;         const unsigned off_ = (unsigned)((st_) >> 2) * (16384u * 128u) + (PE_ID(E, 4 * ((st_) & 3) + i_) << 7) + ((i_ & 1) ? cx1 : cx0); \
;         __builtin_amdgcn_global_load_lds((const unsigned*)(V4 + off_), (LAS unsigned*)(ldsb + BUF[k_] + 1024 * i_), 16, 0, 0); } } while (0)
; __device__ __forceinline__ void peer_v_tokens(int j, const LAS unsigned short* EL, const LAS unsigned char* AL  , const LAS float* ASC  , const LAS int* SAL  , ...
;     ...
;         for (int st = 0; st < 16; ++st) {
;             const int p = st >> 2, q = st & 3;
;             if (st < 14) VDMA(st + 2, (st + 2) % 3);
;             if (st < 14) asm volatile("s_waitcnt vmcnt(8)" ::: "memory");
;             else if (st == 14) asm volatile("s_waitcnt vmcnt(4)" ::: "memory");
;             else asm volatile("s_waitcnt vmcnt(0)" ::: "memory");
;             if (q == 0) {
; #pragma unroll
;                 for (int r = 0; r < 4; ++r) { accH[r] = 0; accL[r] = 0; } }
; #pragma unroll
;             for (int tp = 0; tp < 2; ++tp) {
;                 const v2i ao = TR4(ATL + (2 * q + tp) * 128 + 8 * s16), ah = TR4(ATL + 1024 + (2 * q + tp) * 128 + 8 * s16);
; #pragma unroll
;                 for (int r = 0; r < 4; ++r) {
;                     const v2i d = TR4(ldsb + BUF[st % 3] + 2048 * tp + roff[r]);
;                     accH[r] = __builtin_amdgcn_sdot8(d.x, ah.x, accH[r], false); accH[r] = __builtin_amdgcn_sdot8(d.y, ah.y, accH[r], false);
;                     accL[r] = __builtin_amdgcn_sdot8(d.x, ao.x, accL[r], false); accL[r] = __builtin_amdgcn_sdot8(d.y, ao.y, accL[r], false);
;                 }
;             }
;             asm volatile("s_waitcnt lgkmcnt(0)" ::: "memory");
	v_add_u32_e32 v54, s79, v59
	v_add_u32_e32 v55, s79, v60
	v_add_u32_e32 v56, s79, v61
	v_add_u32_e32 v57, s79, v62
	ds_read_b64_tr_b4 v[50:51], v160 offset:128
	ds_read_b64_tr_b4 v[52:53], v160 offset:1152
	ds_read_b64_tr_b4 v[130:131], v54
	ds_read_b64_tr_b4 v[132:133], v55
	ds_read_b64_tr_b4 v[134:135], v56
	ds_read_b64_tr_b4 v[136:137], v57
	s_waitcnt lgkmcnt(14)
	v_dot8c_i32_i4_e32 v38, v122, v48
	v_dot8c_i32_i4_e32 v39, v122, v46
	v_dot8c_i32_i4_e32 v40, v124, v48
	v_dot8c_i32_i4_e32 v41, v124, v46
	v_dot8c_i32_i4_e32 v42, v126, v48
	v_dot8c_i32_i4_e32 v43, v126, v46
	v_dot8c_i32_i4_e32 v44, v128, v48
	v_dot8c_i32_i4_e32 v45, v128, v46
	v_dot8c_i32_i4_e32 v38, v123, v49
	v_dot8c_i32_i4_e32 v39, v123, v47
	v_dot8c_i32_i4_e32 v40, v125, v49
	v_dot8c_i32_i4_e32 v41, v125, v47
	v_dot8c_i32_i4_e32 v42, v127, v49
	v_dot8c_i32_i4_e32 v43, v127, v47
	v_dot8c_i32_i4_e32 v44, v129, v49
	v_dot8c_i32_i4_e32 v45, v129, v47
	v_and_b32_e32 v78, 0xffff, v32
	v_lshrrev_b32_e32 v79, 16, v32
	v_lshl_add_u32 v78, v78, 7, v150
	v_lshl_add_u32 v79, v79, 7, v151
	s_mov_b32 m0, s78
	s_add_i32 s43, s78, 0x400
	global_load_lds_dwordx4 v78, s[50:51]
	s_mov_b32 m0, s43
	s_nop 0
	global_load_lds_dwordx4 v79, s[50:51]
	s_waitcnt vmcnt(10)
	v_add_u32_e32 v54, s98, v59
	v_add_u32_e32 v55, s98, v60
	v_add_u32_e32 v56, s98, v61
	v_add_u32_e32 v57, s98, v62
	ds_read_b64_tr_b4 v[46:47], v160 offset:256
	ds_read_b64_tr_b4 v[48:49], v160 offset:1280
	ds_read_b64_tr_b4 v[122:123], v54
	ds_read_b64_tr_b4 v[124:125], v55
	ds_read_b64_tr_b4 v[126:127], v56
	ds_read_b64_tr_b4 v[128:129], v57
	s_waitcnt lgkmcnt(6)
	v_dot8c_i32_i4_e32 v38, v130, v52
	v_dot8c_i32_i4_e32 v39, v130, v50
	v_dot8c_i32_i4_e32 v40, v132, v52
	v_dot8c_i32_i4_e32 v41, v132, v50
	v_dot8c_i32_i4_e32 v42, v134, v52
	v_dot8c_i32_i4_e32 v43, v134, v50
	v_dot8c_i32_i4_e32 v44, v136, v52
	v_dot8c_i32_i4_e32 v45, v136, v50
	v_dot8c_i32_i4_e32 v38, v131, v53
	v_dot8c_i32_i4_e32 v39, v131, v51
	v_dot8c_i32_i4_e32 v40, v133, v53
	v_dot8c_i32_i4_e32 v41, v133, v51
	v_dot8c_i32_i4_e32 v42, v135, v53
	v_dot8c_i32_i4_e32 v43, v135, v51
	v_dot8c_i32_i4_e32 v44, v137, v53
	v_dot8c_i32_i4_e32 v45, v137, v51
	v_and_b32_e32 v78, 0xffff, v33
	v_lshrrev_b32_e32 v79, 16, v33
	v_lshl_add_u32 v78, v78, 7, v150
	v_lshl_add_u32 v79, v79, 7, v151
	s_mov_b32 m0, s79
	s_add_i32 s43, s79, 0x400
	global_load_lds_dwordx4 v78, s[50:51]
	s_mov_b32 m0, s43
	s_nop 0
	global_load_lds_dwordx4 v79, s[50:51]
	s_waitcnt vmcnt(10)
	v_add_u32_e32 v54, s99, v59
	v_add_u32_e32 v55, s99, v60
	v_add_u32_e32 v56, s99, v61
	v_add_u32_e32 v57, s99, v62
	ds_read_b64_tr_b4 v[50:51], v160 offset:384
	ds_read_b64_tr_b4 v[52:53], v160 offset:1408
	ds_read_b64_tr_b4 v[130:131], v54
	ds_read_b64_tr_b4 v[132:133], v55
	ds_read_b64_tr_b4 v[134:135], v56
	ds_read_b64_tr_b4 v[136:137], v57
	s_waitcnt lgkmcnt(6)
	v_dot8c_i32_i4_e32 v38, v122, v48
	v_dot8c_i32_i4_e32 v39, v122, v46
	v_dot8c_i32_i4_e32 v40, v124, v48
	v_dot8c_i32_i4_e32 v41, v124, v46
	v_dot8c_i32_i4_e32 v42, v126, v48
	v_dot8c_i32_i4_e32 v43, v126, v46
	v_dot8c_i32_i4_e32 v44, v128, v48
	v_dot8c_i32_i4_e32 v45, v128, v46
	v_dot8c_i32_i4_e32 v38, v123, v49
	v_dot8c_i32_i4_e32 v39, v123, v47
	v_dot8c_i32_i4_e32 v40, v125, v49
	v_dot8c_i32_i4_e32 v41, v125, v47
	v_dot8c_i32_i4_e32 v42, v127, v49
	v_dot8c_i32_i4_e32 v43, v127, v47
	v_dot8c_i32_i4_e32 v44, v129, v49
	v_dot8c_i32_i4_e32 v45, v129, v47
	s_waitcnt lgkmcnt(15)
	v_and_b32_e32 v78, 0xffff, v18
	v_lshrrev_b32_e32 v79, 16, v18
	v_lshl_add_u32 v78, v78, 7, v152
	v_lshl_add_u32 v79, v79, 7, v153
	s_mov_b32 m0, s98
	s_add_i32 s43, s98, 0x400
	global_load_lds_dwordx4 v78, s[50:51]
	s_mov_b32 m0, s43
	s_nop 0
	global_load_lds_dwordx4 v79, s[50:51]
	s_waitcnt vmcnt(10)
	v_add_u32_e32 v54, s76, v59
	v_add_u32_e32 v55, s76, v60
	v_add_u32_e32 v56, s76, v61
	v_add_u32_e32 v57, s76, v62
	ds_read_b64_tr_b4 v[46:47], v160 offset:512
	ds_read_b64_tr_b4 v[48:49], v160 offset:1536
	ds_read_b64_tr_b4 v[122:123], v54
	ds_read_b64_tr_b4 v[124:125], v55
	ds_read_b64_tr_b4 v[126:127], v56
	ds_read_b64_tr_b4 v[128:129], v57
	s_waitcnt lgkmcnt(6)
	v_dot8c_i32_i4_e32 v38, v130, v52
	v_dot8c_i32_i4_e32 v39, v130, v50
	v_dot8c_i32_i4_e32 v40, v132, v52
	v_dot8c_i32_i4_e32 v41, v132, v50
	v_dot8c_i32_i4_e32 v42, v134, v52
	v_dot8c_i32_i4_e32 v43, v134, v50
	v_dot8c_i32_i4_e32 v44, v136, v52
	v_dot8c_i32_i4_e32 v45, v136, v50
	v_dot8c_i32_i4_e32 v38, v131, v53
	v_dot8c_i32_i4_e32 v39, v131, v51
	v_dot8c_i32_i4_e32 v40, v133, v53
	v_dot8c_i32_i4_e32 v41, v133, v51
	v_dot8c_i32_i4_e32 v42, v135, v53
	v_dot8c_i32_i4_e32 v43, v135, v51
	v_dot8c_i32_i4_e32 v44, v137, v53
	v_dot8c_i32_i4_e32 v45, v137, v51
	v_and_b32_e32 v78, 0xffff, v19
	v_lshrrev_b32_e32 v79, 16, v19
	v_lshl_add_u32 v78, v78, 7, v152
	v_lshl_add_u32 v79, v79, 7, v153
	s_mov_b32 m0, s99
	s_add_i32 s43, s99, 0x400
	global_load_lds_dwordx4 v78, s[50:51]
	s_mov_b32 m0, s43
	s_nop 0
	global_load_lds_dwordx4 v79, s[50:51]
	s_waitcnt vmcnt(8)
	v_add_u32_e32 v54, s77, v59
	v_add_u32_e32 v55, s77, v60
	v_add_u32_e32 v56, s77, v61
	v_add_u32_e32 v57, s77, v62
	ds_read_b64_tr_b4 v[50:51], v160 offset:640
	ds_read_b64_tr_b4 v[52:53], v160 offset:1664
	ds_read_b64_tr_b4 v[130:131], v54
	ds_read_b64_tr_b4 v[132:133], v55
	ds_read_b64_tr_b4 v[134:135], v56
	ds_read_b64_tr_b4 v[136:137], v57
	s_waitcnt lgkmcnt(6)
	v_dot8c_i32_i4_e32 v38, v122, v48
	v_dot8c_i32_i4_e32 v39, v122, v46
	v_dot8c_i32_i4_e32 v40, v124, v48
	v_dot8c_i32_i4_e32 v41, v124, v46
	v_dot8c_i32_i4_e32 v42, v126, v48
	v_dot8c_i32_i4_e32 v43, v126, v46
	v_dot8c_i32_i4_e32 v44, v128, v48
	v_dot8c_i32_i4_e32 v45, v128, v46
	v_dot8c_i32_i4_e32 v38, v123, v49
	v_dot8c_i32_i4_e32 v39, v123, v47
	v_dot8c_i32_i4_e32 v40, v125, v49
	v_dot8c_i32_i4_e32 v41, v125, v47
	v_dot8c_i32_i4_e32 v42, v127, v49
	v_dot8c_i32_i4_e32 v43, v127, v47
	v_dot8c_i32_i4_e32 v44, v129, v49
	v_dot8c_i32_i4_e32 v45, v129, v47
	s_waitcnt lgkmcnt(15)
; __device__ __forceinline__ void peer_v_tokens(int j, const LAS unsigned short* EL, const LAS unsigned char* AL  , const LAS float* ASC  , const LAS int* SAL  , ...
;     ...
;         for (int st = 0; st < 16; ++st) {
;             const int p = st >> 2, q = st & 3;
;             if (st < 14) VDMA(st + 2, (st + 2) % 3);
;             if (st < 14) asm volatile("s_waitcnt vmcnt(8)" ::: "memory");
;             else if (st == 14) asm volatile("s_waitcnt vmcnt(4)" ::: "memory");
;             else asm volatile("s_waitcnt vmcnt(0)" ::: "memory");
;             if (q == 0) {
; #pragma unroll
;                 for (int r = 0; r < 4; ++r) { accH[r] = 0; accL[r] = 0; } }
; #pragma unroll
;             for (int tp = 0; tp < 2; ++tp) {
;                 const v2i ao = TR4(ATL + (2 * q + tp) * 128 + 8 * s16), ah = TR4(ATL + 1024 + (2 * q + tp) * 128 + 8 * s16);
; #pragma unroll
;                 for (int r = 0; r < 4; ++r) {
;                     const v2i d = TR4(ldsb + BUF[st % 3] + 2048 * tp + roff[r]);
;                     accH[r] = __builtin_amdgcn_sdot8(d.x, ah.x, accH[r], false); accH[r] = __builtin_amdgcn_sdot8(d.y, ah.y, accH[r], false);
;                     accL[r] = __builtin_amdgcn_sdot8(d.x, ao.x, accL[r], false); accL[r] = __builtin_amdgcn_sdot8(d.y, ao.y, accL[r], false);
;                 }
;             }
;             asm volatile("s_waitcnt lgkmcnt(0)" ::: "memory");
;             if (q == 3) {
; #pragma unroll
;                 for (int r = 0; r < 4; ++r) STASH[256 * p + 16 * (grp + 4 * r) + pc] = f2bf(asc * (float)(2 * ((accH[r] << 4) + accL[r]) + sa));
;             }
;         }
;         CFENCE();
;         {
;             float4 v[4]; float ss = 0.f;
; #pragma unroll
;             for (int jq = 0; jq < 4; ++jq) { typedef unsigned u2v __attribute__((ext_vector_type(2))); const u2v pw = *(const LAS u2v*)(STASH + 4 * lane + 256 * jq); const uint2 hw = hv[jq];
;                 v[jq] = make_float4(__uint_as_float(hw.x << 16) + __uint_as_float(pw.x << 16), __uint_as_float(hw.x & 0xffff0000u) + __uint_as_float(pw.x & 0xffff0000u),
;                                     __uint_as_float(hw.y << 16) + __uint_as_float(pw.y << 16), __uint_as_float(hw.y & 0xffff0000u) + __uint_as_float(pw.y & 0xffff0000u));
;                 ss += v[jq].x * v[jq].x + v[jq].y * v[jq].y + v[jq].z * v[jq].z + v[jq].w * v[jq].w; }
;             ss = wave_sum(ss);
	v_add_u32_e32 v143, 8, v139
	v_and_b32_e32 v142, 15, v143
	v_xor_b32_e32 v142, 8, v142
	v_bfe_u32 v144, v143, 4, 4
	v_mul_lo_u32 v142, v142, s92
	v_mul_lo_u32 v144, v144, s92
	v_mov_b32_e32 v143, v142
	v_mov_b32_e32 v145, v144
	ds_write2st64_b64 v159, v[142:143], v[144:145] offset1:2
	v_and_b32_e32 v78, 0xffff, v20
	v_lshrrev_b32_e32 v79, 16, v20
	v_lshl_add_u32 v78, v78, 7, v152
	v_lshl_add_u32 v79, v79, 7, v153
	s_mov_b32 m0, s76
	s_add_i32 s43, s76, 0x400
	global_load_lds_dwordx4 v78, s[50:51]
	s_mov_b32 m0, s43
	s_nop 0
	global_load_lds_dwordx4 v79, s[50:51]
	s_waitcnt vmcnt(8)
	v_add_u32_e32 v54, s78, v59
	v_add_u32_e32 v55, s78, v60
	v_add_u32_e32 v56, s78, v61
	v_add_u32_e32 v57, s78, v62
	ds_read_b64_tr_b4 v[46:47], v160 offset:768
	ds_read_b64_tr_b4 v[48:49], v160 offset:1792
	ds_read_b64_tr_b4 v[122:123], v54
	ds_read_b64_tr_b4 v[124:125], v55
	ds_read_b64_tr_b4 v[126:127], v56
	ds_read_b64_tr_b4 v[128:129], v57
	s_waitcnt lgkmcnt(7)
	v_dot8c_i32_i4_e32 v38, v130, v52
	v_dot8c_i32_i4_e32 v39, v130, v50
	v_dot8c_i32_i4_e32 v40, v132, v52
	v_dot8c_i32_i4_e32 v41, v132, v50
	v_dot8c_i32_i4_e32 v42, v134, v52
	v_dot8c_i32_i4_e32 v43, v134, v50
	v_dot8c_i32_i4_e32 v44, v136, v52
	v_dot8c_i32_i4_e32 v45, v136, v50
	v_dot8c_i32_i4_e32 v38, v131, v53
	v_dot8c_i32_i4_e32 v39, v131, v51
	v_dot8c_i32_i4_e32 v40, v133, v53
	v_dot8c_i32_i4_e32 v41, v133, v51
	v_dot8c_i32_i4_e32 v42, v135, v53
	v_dot8c_i32_i4_e32 v43, v135, v51
	v_dot8c_i32_i4_e32 v44, v137, v53
	v_dot8c_i32_i4_e32 v45, v137, v51
	v_and_b32_e32 v78, 0xffff, v21
	v_lshrrev_b32_e32 v79, 16, v21
	v_lshl_add_u32 v78, v78, 7, v152
	v_lshl_add_u32 v79, v79, 7, v153
	s_mov_b32 m0, s77
	s_add_i32 s43, s77, 0x400
	global_load_lds_dwordx4 v78, s[50:51]
	s_mov_b32 m0, s43
	s_nop 0
	global_load_lds_dwordx4 v79, s[50:51]
	s_waitcnt vmcnt(8)
	v_add_u32_e32 v54, s79, v59
	v_add_u32_e32 v55, s79, v60
	v_add_u32_e32 v56, s79, v61
	v_add_u32_e32 v57, s79, v62
	ds_read_b64_tr_b4 v[50:51], v160 offset:896
	ds_read_b64_tr_b4 v[52:53], v160 offset:1920
	ds_read_b64_tr_b4 v[130:131], v54
	ds_read_b64_tr_b4 v[132:133], v55
	ds_read_b64_tr_b4 v[134:135], v56
	ds_read_b64_tr_b4 v[136:137], v57
	s_waitcnt lgkmcnt(6)
	v_dot8c_i32_i4_e32 v38, v122, v48
	v_dot8c_i32_i4_e32 v39, v122, v46
	v_dot8c_i32_i4_e32 v40, v124, v48
	v_dot8c_i32_i4_e32 v41, v124, v46
	v_dot8c_i32_i4_e32 v42, v126, v48
	v_dot8c_i32_i4_e32 v43, v126, v46
	v_dot8c_i32_i4_e32 v44, v128, v48
	v_dot8c_i32_i4_e32 v45, v128, v46
	v_dot8c_i32_i4_e32 v38, v123, v49
	v_dot8c_i32_i4_e32 v39, v123, v47
	v_dot8c_i32_i4_e32 v40, v125, v49
	v_dot8c_i32_i4_e32 v41, v125, v47
	v_dot8c_i32_i4_e32 v42, v127, v49
	v_dot8c_i32_i4_e32 v43, v127, v47
	v_dot8c_i32_i4_e32 v44, v129, v49
	v_dot8c_i32_i4_e32 v45, v129, v47
	v_and_b32_e32 v78, 0xffff, v22
	v_lshrrev_b32_e32 v79, 16, v22
	v_lshl_add_u32 v78, v78, 7, v152
	v_lshl_add_u32 v79, v79, 7, v153
	s_mov_b32 m0, s78
	s_add_i32 s43, s78, 0x400
	global_load_lds_dwordx4 v78, s[50:51]
	s_mov_b32 m0, s43
	s_nop 0
	global_load_lds_dwordx4 v79, s[50:51]
	s_waitcnt vmcnt(8)
	v_add_u32_e32 v54, s98, v59
	v_add_u32_e32 v55, s98, v60
	v_add_u32_e32 v56, s98, v61
	v_add_u32_e32 v57, s98, v62
	ds_read_b64_tr_b4 v[46:47], v160
	ds_read_b64_tr_b4 v[48:49], v160 offset:1024
	ds_read_b64_tr_b4 v[122:123], v54
	ds_read_b64_tr_b4 v[124:125], v55
	ds_read_b64_tr_b4 v[126:127], v56
	ds_read_b64_tr_b4 v[128:129], v57
	s_waitcnt lgkmcnt(6)
	v_dot8c_i32_i4_e32 v38, v130, v52
	v_dot8c_i32_i4_e32 v39, v130, v50
	v_dot8c_i32_i4_e32 v40, v132, v52
	v_dot8c_i32_i4_e32 v41, v132, v50
	v_dot8c_i32_i4_e32 v42, v134, v52
	v_dot8c_i32_i4_e32 v43, v134, v50
	v_dot8c_i32_i4_e32 v44, v136, v52
	v_dot8c_i32_i4_e32 v45, v136, v50
	v_dot8c_i32_i4_e32 v38, v131, v53
	v_dot8c_i32_i4_e32 v39, v131, v51
	v_dot8c_i32_i4_e32 v40, v133, v53
	v_dot8c_i32_i4_e32 v41, v133, v51
	v_dot8c_i32_i4_e32 v42, v135, v53
	v_dot8c_i32_i4_e32 v43, v135, v51
	v_dot8c_i32_i4_e32 v44, v137, v53
	v_dot8c_i32_i4_e32 v45, v137, v51
	s_nop 3
	s_waitcnt lgkmcnt(15)
	v_lshlrev_b32_e32 v38, 5, v38
	v_lshlrev_b32_e32 v39, 1, v39
	v_add3_u32 v38, v39, v229, v38
	v_cvt_f32_i32_e32 v38, v38
	v_mul_f32_e32 v38, v228, v38
	v_lshlrev_b32_e32 v40, 5, v40
	v_lshlrev_b32_e32 v41, 1, v41
	v_add3_u32 v40, v41, v229, v40
	v_cvt_f32_i32_e32 v40, v40
	v_mul_f32_e32 v40, v228, v40
	v_lshlrev_b32_e32 v42, 5, v42
	v_lshlrev_b32_e32 v43, 1, v43
	v_add3_u32 v42, v43, v229, v42
	v_cvt_f32_i32_e32 v42, v42
	v_mul_f32_e32 v42, v228, v42
	v_lshlrev_b32_e32 v44, 5, v44
	v_lshlrev_b32_e32 v45, 1, v45
	v_add3_u32 v44, v45, v229, v44
	v_cvt_f32_i32_e32 v44, v44
	v_mul_f32_e32 v44, v228, v44
	v_cvt_pk_bf16_f32 v190, v38, v40
	v_cvt_pk_bf16_f32 v191, v42, v44
	ds_read_b128 v[252:255], v155 offset:1024
	s_add_i32 s44, s40, 8
	s_ashr_i32 s45, s44, 31
	s_lshl_b64 s[44:45], s[44:45], 12
	v_lshl_add_u64 v[80:81], v[36:37], 0, s[44:45]
	s_waitcnt lgkmcnt(0)
	v_mul_f32_e32 v240, v240, v252
	v_mul_f32_e32 v241, v241, v253
	v_mul_f32_e32 v242, v242, v254
	v_mul_f32_e32 v243, v243, v255
	global_store_dwordx4 v[80:81], v[240:243], off offset:1024 nt
	v_add_u32_e32 v147, 8, v140
	v_and_b32_e32 v146, 15, v147
	v_xor_b32_e32 v146, 8, v146
	v_bfe_u32 v148, v147, 4, 4
	v_mul_lo_u32 v146, v146, s92
	v_mul_lo_u32 v148, v148, s92
	v_mov_b32_e32 v147, v146
	v_mov_b32_e32 v149, v148
	ds_write2st64_b64 v77, v[146:147], v[148:149] offset1:2
	v_add_u32_e32 v138, 0xc00, v74
	ds_read_u8 v139, v138
	v_add_u32_e32 v141, 0xc00, v73
	ds_read_u8 v140, v141
	s_add_i32 s43, s67, 64
	v_mov_b32_e32 v138, s43
	ds_read2st64_b32 v[228:229], v138 offset1:1
	ds_read_b128 v[26:29], v227 offset:6144
	ds_read_b128 v[30:33], v227 offset:6160
	v_mov_b32_e32 v38, 0
	v_mov_b32_e32 v39, 0
	v_mov_b32_e32 v40, 0
	v_mov_b32_e32 v41, 0
	v_mov_b32_e32 v42, 0
	v_mov_b32_e32 v43, 0
	v_mov_b32_e32 v44, 0
	v_mov_b32_e32 v45, 0
	v_and_b32_e32 v78, 0xffff, v23
	v_lshrrev_b32_e32 v79, 16, v23
	v_lshl_add_u32 v78, v78, 7, v152
	v_lshl_add_u32 v79, v79, 7, v153
	s_mov_b32 m0, s79
	s_add_i32 s43, s79, 0x400
	global_load_lds_dwordx4 v78, s[50:51]
	s_mov_b32 m0, s43
	s_nop 0
	global_load_lds_dwordx4 v79, s[50:51]
	s_waitcnt vmcnt(9)
; #define TR4(p_) __builtin_amdgcn_ds_read_tr4_b64_v2i32((LAS v2i*)(p_))
; #define VDMA(st_, k_) do { _Pragma("unroll") for (int i_ = 0; i_ < 4; ++i_) { \
;         const unsigned off_ = (unsigned)((st_) >> 2) * (16384u * 128u) + (PE_ID(E, 4 * ((st_) & 3) + i_) << 7) + ((i_ & 1) ? cx1 : cx0); \
;         __builtin_amdgcn_global_load_lds((const unsigned*)(V4 + off_), (LAS unsigned*)(ldsb + BUF[k_] + 1024 * i_), 16, 0, 0); } } while (0)
; __device__ __forceinline__ void peer_v_tokens(int j, const LAS unsigned short* EL, const LAS unsigned char* AL  , const LAS float* ASC  , const LAS int* SAL  , ...
;     ...
;         for (int st = 0; st < 16; ++st) {
;             const int p = st >> 2, q = st & 3;
;             if (st < 14) VDMA(st + 2, (st + 2) % 3);
;             if (st < 14) asm volatile("s_waitcnt vmcnt(8)" ::: "memory");
;             else if (st == 14) asm volatile("s_waitcnt vmcnt(4)" ::: "memory");
;             else asm volatile("s_waitcnt vmcnt(0)" ::: "memory");
;             if (q == 0) {
; #pragma unroll
;                 for (int r = 0; r < 4; ++r) { accH[r] = 0; accL[r] = 0; } }
; #pragma unroll
;             for (int tp = 0; tp < 2; ++tp) {
;                 const v2i ao = TR4(ATL + (2 * q + tp) * 128 + 8 * s16), ah = TR4(ATL + 1024 + (2 * q + tp) * 128 + 8 * s16);
; #pragma unroll
;                 for (int r = 0; r < 4; ++r) {
;                     const v2i d = TR4(ldsb + BUF[st % 3] + 2048 * tp + roff[r]);
;                     accH[r] = __builtin_amdgcn_sdot8(d.x, ah.x, accH[r], false); accH[r] = __builtin_amdgcn_sdot8(d.y, ah.y, accH[r], false);
;                     accL[r] = __builtin_amdgcn_sdot8(d.x, ao.x, accL[r], false); accL[r] = __builtin_amdgcn_sdot8(d.y, ao.y, accL[r], false);
;                 }
;             }
;             asm volatile("s_waitcnt lgkmcnt(0)" ::: "memory");
	v_add_u32_e32 v54, s99, v59
	v_add_u32_e32 v55, s99, v60
	v_add_u32_e32 v56, s99, v61
	v_add_u32_e32 v57, s99, v62
	ds_read_b64_tr_b4 v[50:51], v160 offset:128
	ds_read_b64_tr_b4 v[52:53], v160 offset:1152
	ds_read_b64_tr_b4 v[130:131], v54
	ds_read_b64_tr_b4 v[132:133], v55
	ds_read_b64_tr_b4 v[134:135], v56
	ds_read_b64_tr_b4 v[136:137], v57
	s_waitcnt lgkmcnt(13)
	v_dot8c_i32_i4_e32 v38, v122, v48
	v_dot8c_i32_i4_e32 v39, v122, v46
	v_dot8c_i32_i4_e32 v40, v124, v48
	v_dot8c_i32_i4_e32 v41, v124, v46
	v_dot8c_i32_i4_e32 v42, v126, v48
	v_dot8c_i32_i4_e32 v43, v126, v46
	v_dot8c_i32_i4_e32 v44, v128, v48
	v_dot8c_i32_i4_e32 v45, v128, v46
	v_dot8c_i32_i4_e32 v38, v123, v49
	v_dot8c_i32_i4_e32 v39, v123, v47
	v_dot8c_i32_i4_e32 v40, v125, v49
	v_dot8c_i32_i4_e32 v41, v125, v47
	v_dot8c_i32_i4_e32 v42, v127, v49
	v_dot8c_i32_i4_e32 v43, v127, v47
	v_dot8c_i32_i4_e32 v44, v129, v49
	v_dot8c_i32_i4_e32 v45, v129, v47
	v_and_b32_e32 v78, 0xffff, v24
	v_lshrrev_b32_e32 v79, 16, v24
	v_lshl_add_u32 v78, v78, 7, v152
	v_lshl_add_u32 v79, v79, 7, v153
	s_mov_b32 m0, s98
	s_add_i32 s43, s98, 0x400
	global_load_lds_dwordx4 v78, s[50:51]
	s_mov_b32 m0, s43
	s_nop 0
	global_load_lds_dwordx4 v79, s[50:51]
	s_waitcnt vmcnt(9)
	v_add_u32_e32 v54, s76, v59
	v_add_u32_e32 v55, s76, v60
	v_add_u32_e32 v56, s76, v61
	v_add_u32_e32 v57, s76, v62
	ds_read_b64_tr_b4 v[46:47], v160 offset:256
	ds_read_b64_tr_b4 v[48:49], v160 offset:1280
	ds_read_b64_tr_b4 v[122:123], v54
	ds_read_b64_tr_b4 v[124:125], v55
	ds_read_b64_tr_b4 v[126:127], v56
	ds_read_b64_tr_b4 v[128:129], v57
	s_waitcnt lgkmcnt(6)
	v_dot8c_i32_i4_e32 v38, v130, v52
	v_dot8c_i32_i4_e32 v39, v130, v50
	v_dot8c_i32_i4_e32 v40, v132, v52
	v_dot8c_i32_i4_e32 v41, v132, v50
	v_dot8c_i32_i4_e32 v42, v134, v52
	v_dot8c_i32_i4_e32 v43, v134, v50
	v_dot8c_i32_i4_e32 v44, v136, v52
	v_dot8c_i32_i4_e32 v45, v136, v50
	v_dot8c_i32_i4_e32 v38, v131, v53
	v_dot8c_i32_i4_e32 v39, v131, v51
	v_dot8c_i32_i4_e32 v40, v133, v53
	v_dot8c_i32_i4_e32 v41, v133, v51
	v_dot8c_i32_i4_e32 v42, v135, v53
	v_dot8c_i32_i4_e32 v43, v135, v51
	v_dot8c_i32_i4_e32 v44, v137, v53
	v_dot8c_i32_i4_e32 v45, v137, v51
	v_and_b32_e32 v78, 0xffff, v25
	v_lshrrev_b32_e32 v79, 16, v25
	v_lshl_add_u32 v78, v78, 7, v152
	v_lshl_add_u32 v79, v79, 7, v153
	s_mov_b32 m0, s99
	s_add_i32 s43, s99, 0x400
	global_load_lds_dwordx4 v78, s[50:51]
	s_mov_b32 m0, s43
	s_nop 0
	global_load_lds_dwordx4 v79, s[50:51]
	s_waitcnt vmcnt(9)
	v_add_u32_e32 v54, s77, v59
	v_add_u32_e32 v55, s77, v60
	v_add_u32_e32 v56, s77, v61
	v_add_u32_e32 v57, s77, v62
	ds_read_b64_tr_b4 v[50:51], v160 offset:384
	ds_read_b64_tr_b4 v[52:53], v160 offset:1408
	ds_read_b64_tr_b4 v[130:131], v54
	ds_read_b64_tr_b4 v[132:133], v55
	ds_read_b64_tr_b4 v[134:135], v56
	ds_read_b64_tr_b4 v[136:137], v57
	s_waitcnt lgkmcnt(6)
	v_dot8c_i32_i4_e32 v38, v122, v48
	v_dot8c_i32_i4_e32 v39, v122, v46
	v_dot8c_i32_i4_e32 v40, v124, v48
	v_dot8c_i32_i4_e32 v41, v124, v46
	v_dot8c_i32_i4_e32 v42, v126, v48
	v_dot8c_i32_i4_e32 v43, v126, v46
	v_dot8c_i32_i4_e32 v44, v128, v48
	v_dot8c_i32_i4_e32 v45, v128, v46
	v_dot8c_i32_i4_e32 v38, v123, v49
	v_dot8c_i32_i4_e32 v39, v123, v47
	v_dot8c_i32_i4_e32 v40, v125, v49
	v_dot8c_i32_i4_e32 v41, v125, v47
	v_dot8c_i32_i4_e32 v42, v127, v49
	v_dot8c_i32_i4_e32 v43, v127, v47
	v_dot8c_i32_i4_e32 v44, v129, v49
	v_dot8c_i32_i4_e32 v45, v129, v47
	s_waitcnt lgkmcnt(15)
	v_and_b32_e32 v78, 0xffff, v26
	v_lshrrev_b32_e32 v79, 16, v26
	v_lshl_add_u32 v78, v78, 7, v152
	v_lshl_add_u32 v79, v79, 7, v153
	s_mov_b32 m0, s76
	s_add_i32 s43, s76, 0x400
	global_load_lds_dwordx4 v78, s[50:51]
	s_mov_b32 m0, s43
	s_nop 0
	global_load_lds_dwordx4 v79, s[50:51]
	s_waitcnt vmcnt(9)
	v_add_u32_e32 v54, s78, v59
	v_add_u32_e32 v55, s78, v60
	v_add_u32_e32 v56, s78, v61
	v_add_u32_e32 v57, s78, v62
	ds_read_b64_tr_b4 v[46:47], v160 offset:512
	ds_read_b64_tr_b4 v[48:49], v160 offset:1536
	ds_read_b64_tr_b4 v[122:123], v54
	ds_read_b64_tr_b4 v[124:125], v55
	ds_read_b64_tr_b4 v[126:127], v56
	ds_read_b64_tr_b4 v[128:129], v57
	s_waitcnt lgkmcnt(6)
	v_dot8c_i32_i4_e32 v38, v130, v52
	v_dot8c_i32_i4_e32 v39, v130, v50
	v_dot8c_i32_i4_e32 v40, v132, v52
	v_dot8c_i32_i4_e32 v41, v132, v50
	v_dot8c_i32_i4_e32 v42, v134, v52
	v_dot8c_i32_i4_e32 v43, v134, v50
	v_dot8c_i32_i4_e32 v44, v136, v52
	v_dot8c_i32_i4_e32 v45, v136, v50
	v_dot8c_i32_i4_e32 v38, v131, v53
	v_dot8c_i32_i4_e32 v39, v131, v51
	v_dot8c_i32_i4_e32 v40, v133, v53
	v_dot8c_i32_i4_e32 v41, v133, v51
	v_dot8c_i32_i4_e32 v42, v135, v53
	v_dot8c_i32_i4_e32 v43, v135, v51
	v_dot8c_i32_i4_e32 v44, v137, v53
	v_dot8c_i32_i4_e32 v45, v137, v51
	v_and_b32_e32 v78, 0xffff, v27
	v_lshrrev_b32_e32 v79, 16, v27
	v_lshl_add_u32 v78, v78, 7, v152
	v_lshl_add_u32 v79, v79, 7, v153
	s_mov_b32 m0, s77
	s_add_i32 s43, s77, 0x400
	global_load_lds_dwordx4 v78, s[50:51]
	s_mov_b32 m0, s43
	s_nop 0
	global_load_lds_dwordx4 v79, s[50:51]
	s_waitcnt vmcnt(8)
	v_add_u32_e32 v54, s79, v59
	v_add_u32_e32 v55, s79, v60
	v_add_u32_e32 v56, s79, v61
	v_add_u32_e32 v57, s79, v62
	ds_read_b64_tr_b4 v[50:51], v160 offset:640
	ds_read_b64_tr_b4 v[52:53], v160 offset:1664
	ds_read_b64_tr_b4 v[130:131], v54
	ds_read_b64_tr_b4 v[132:133], v55
	ds_read_b64_tr_b4 v[134:135], v56
	ds_read_b64_tr_b4 v[136:137], v57
	s_waitcnt lgkmcnt(6)
	v_dot8c_i32_i4_e32 v38, v122, v48
	v_dot8c_i32_i4_e32 v39, v122, v46
	v_dot8c_i32_i4_e32 v40, v124, v48
	v_dot8c_i32_i4_e32 v41, v124, v46
	v_dot8c_i32_i4_e32 v42, v126, v48
	v_dot8c_i32_i4_e32 v43, v126, v46
	v_dot8c_i32_i4_e32 v44, v128, v48
	v_dot8c_i32_i4_e32 v45, v128, v46
	v_dot8c_i32_i4_e32 v38, v123, v49
	v_dot8c_i32_i4_e32 v39, v123, v47
	v_dot8c_i32_i4_e32 v40, v125, v49
	v_dot8c_i32_i4_e32 v41, v125, v47
	v_dot8c_i32_i4_e32 v42, v127, v49
	v_dot8c_i32_i4_e32 v43, v127, v47
	v_dot8c_i32_i4_e32 v44, v129, v49
	v_dot8c_i32_i4_e32 v45, v129, v47
	s_waitcnt lgkmcnt(15)
; __device__ __forceinline__ bf16 f2bf(float f) { return (bf16)f2bfu(f); }
; #define TR4(p_) __builtin_amdgcn_ds_read_tr4_b64_v2i32((LAS v2i*)(p_))
; #define VDMA(st_, k_) do { _Pragma("unroll") for (int i_ = 0; i_ < 4; ++i_) { \
;         const unsigned off_ = (unsigned)((st_) >> 2) * (16384u * 128u) + (PE_ID(E, 4 * ((st_) & 3) + i_) << 7) + ((i_ & 1) ? cx1 : cx0); \
;         __builtin_amdgcn_global_load_lds((const unsigned*)(V4 + off_), (LAS unsigned*)(ldsb + BUF[k_] + 1024 * i_), 16, 0, 0); } } while (0)
; __device__ __forceinline__ void peer_v_tokens(int j, const LAS unsigned short* EL, const LAS unsigned char* AL  , const LAS float* ASC  , const LAS int* SAL  , ...
;     ...
;         for (int st = 0; st < 16; ++st) {
;             const int p = st >> 2, q = st & 3;
;             if (st < 14) VDMA(st + 2, (st + 2) % 3);
;             if (st < 14) asm volatile("s_waitcnt vmcnt(8)" ::: "memory");
;             else if (st == 14) asm volatile("s_waitcnt vmcnt(4)" ::: "memory");
;             else asm volatile("s_waitcnt vmcnt(0)" ::: "memory");
;             if (q == 0) {
; #pragma unroll
;                 for (int r = 0; r < 4; ++r) { accH[r] = 0; accL[r] = 0; } }
; #pragma unroll
;             for (int tp = 0; tp < 2; ++tp) {
;                 const v2i ao = TR4(ATL + (2 * q + tp) * 128 + 8 * s16), ah = TR4(ATL + 1024 + (2 * q + tp) * 128 + 8 * s16);
; #pragma unroll
;                 for (int r = 0; r < 4; ++r) {
;                     const v2i d = TR4(ldsb + BUF[st % 3] + 2048 * tp + roff[r]);
;                     accH[r] = __builtin_amdgcn_sdot8(d.x, ah.x, accH[r], false); accH[r] = __builtin_amdgcn_sdot8(d.y, ah.y, accH[r], false);
;                     accL[r] = __builtin_amdgcn_sdot8(d.x, ao.x, accL[r], false); accL[r] = __builtin_amdgcn_sdot8(d.y, ao.y, accL[r], false);
;                 }
;             }
;             asm volatile("s_waitcnt lgkmcnt(0)" ::: "memory");
;             if (q == 3) {
; #pragma unroll
;                 for (int r = 0; r < 4; ++r) STASH[256 * p + 16 * (grp + 4 * r) + pc] = f2bf(asc * (float)(2 * ((accH[r] << 4) + accL[r]) + sa));
;             }
	v_add_u32_e32 v143, 8, v139
	v_and_b32_e32 v142, 15, v143
	v_xor_b32_e32 v142, 8, v142
	v_bfe_u32 v144, v143, 4, 4
	v_mul_lo_u32 v142, v142, s92
	v_mul_lo_u32 v144, v144, s92
	v_mov_b32_e32 v143, v142
	v_mov_b32_e32 v145, v144
	ds_write2st64_b64 v159, v[142:143], v[144:145] offset1:2
	v_and_b32_e32 v78, 0xffff, v28
	v_lshrrev_b32_e32 v79, 16, v28
	v_lshl_add_u32 v78, v78, 7, v152
	v_lshl_add_u32 v79, v79, 7, v153
	s_mov_b32 m0, s78
	s_add_i32 s43, s78, 0x400
	global_load_lds_dwordx4 v78, s[50:51]
	s_mov_b32 m0, s43
	s_nop 0
	global_load_lds_dwordx4 v79, s[50:51]
	s_waitcnt vmcnt(8)
	v_add_u32_e32 v54, s98, v59
	v_add_u32_e32 v55, s98, v60
	v_add_u32_e32 v56, s98, v61
	v_add_u32_e32 v57, s98, v62
	ds_read_b64_tr_b4 v[46:47], v160 offset:768
	ds_read_b64_tr_b4 v[48:49], v160 offset:1792
	ds_read_b64_tr_b4 v[122:123], v54
	ds_read_b64_tr_b4 v[124:125], v55
	ds_read_b64_tr_b4 v[126:127], v56
	ds_read_b64_tr_b4 v[128:129], v57
	s_waitcnt lgkmcnt(7)
	v_dot8c_i32_i4_e32 v38, v130, v52
	v_dot8c_i32_i4_e32 v39, v130, v50
	v_dot8c_i32_i4_e32 v40, v132, v52
	v_dot8c_i32_i4_e32 v41, v132, v50
	v_dot8c_i32_i4_e32 v42, v134, v52
	v_dot8c_i32_i4_e32 v43, v134, v50
	v_dot8c_i32_i4_e32 v44, v136, v52
	v_dot8c_i32_i4_e32 v45, v136, v50
	v_dot8c_i32_i4_e32 v38, v131, v53
	v_dot8c_i32_i4_e32 v39, v131, v51
	v_dot8c_i32_i4_e32 v40, v133, v53
	v_dot8c_i32_i4_e32 v41, v133, v51
	v_dot8c_i32_i4_e32 v42, v135, v53
	v_dot8c_i32_i4_e32 v43, v135, v51
	v_dot8c_i32_i4_e32 v44, v137, v53
	v_dot8c_i32_i4_e32 v45, v137, v51
	v_and_b32_e32 v78, 0xffff, v29
	v_lshrrev_b32_e32 v79, 16, v29
	v_lshl_add_u32 v78, v78, 7, v152
	v_lshl_add_u32 v79, v79, 7, v153
	s_mov_b32 m0, s79
	s_add_i32 s43, s79, 0x400
	global_load_lds_dwordx4 v78, s[50:51]
	s_mov_b32 m0, s43
	s_nop 0
	global_load_lds_dwordx4 v79, s[50:51]
	s_waitcnt vmcnt(8)
	v_add_u32_e32 v54, s99, v59
	v_add_u32_e32 v55, s99, v60
	v_add_u32_e32 v56, s99, v61
	v_add_u32_e32 v57, s99, v62
	ds_read_b64_tr_b4 v[50:51], v160 offset:896
	ds_read_b64_tr_b4 v[52:53], v160 offset:1920
	ds_read_b64_tr_b4 v[130:131], v54
	ds_read_b64_tr_b4 v[132:133], v55
	ds_read_b64_tr_b4 v[134:135], v56
	ds_read_b64_tr_b4 v[136:137], v57
	s_waitcnt lgkmcnt(6)
	v_dot8c_i32_i4_e32 v38, v122, v48
	v_dot8c_i32_i4_e32 v39, v122, v46
	v_dot8c_i32_i4_e32 v40, v124, v48
	v_dot8c_i32_i4_e32 v41, v124, v46
	v_dot8c_i32_i4_e32 v42, v126, v48
	v_dot8c_i32_i4_e32 v43, v126, v46
	v_dot8c_i32_i4_e32 v44, v128, v48
	v_dot8c_i32_i4_e32 v45, v128, v46
	v_dot8c_i32_i4_e32 v38, v123, v49
	v_dot8c_i32_i4_e32 v39, v123, v47
	v_dot8c_i32_i4_e32 v40, v125, v49
	v_dot8c_i32_i4_e32 v41, v125, v47
	v_dot8c_i32_i4_e32 v42, v127, v49
	v_dot8c_i32_i4_e32 v43, v127, v47
	v_dot8c_i32_i4_e32 v44, v129, v49
	v_dot8c_i32_i4_e32 v45, v129, v47
	v_and_b32_e32 v78, 0xffff, v30
	v_lshrrev_b32_e32 v79, 16, v30
	v_lshl_add_u32 v78, v78, 7, v152
	v_lshl_add_u32 v79, v79, 7, v153
	s_mov_b32 m0, s98
	s_add_i32 s43, s98, 0x400
	global_load_lds_dwordx4 v78, s[50:51]
	s_mov_b32 m0, s43
	s_nop 0
	global_load_lds_dwordx4 v79, s[50:51]
	s_waitcnt vmcnt(8)
	v_add_u32_e32 v54, s76, v59
	v_add_u32_e32 v55, s76, v60
	v_add_u32_e32 v56, s76, v61
	v_add_u32_e32 v57, s76, v62
	ds_read_b64_tr_b4 v[46:47], v160
	ds_read_b64_tr_b4 v[48:49], v160 offset:1024
	ds_read_b64_tr_b4 v[122:123], v54
	ds_read_b64_tr_b4 v[124:125], v55
	ds_read_b64_tr_b4 v[126:127], v56
	ds_read_b64_tr_b4 v[128:129], v57
	s_waitcnt lgkmcnt(6)
	v_dot8c_i32_i4_e32 v38, v130, v52
	v_dot8c_i32_i4_e32 v39, v130, v50
	v_dot8c_i32_i4_e32 v40, v132, v52
	v_dot8c_i32_i4_e32 v41, v132, v50
	v_dot8c_i32_i4_e32 v42, v134, v52
	v_dot8c_i32_i4_e32 v43, v134, v50
	v_dot8c_i32_i4_e32 v44, v136, v52
	v_dot8c_i32_i4_e32 v45, v136, v50
	v_dot8c_i32_i4_e32 v38, v131, v53
	v_dot8c_i32_i4_e32 v39, v131, v51
	v_dot8c_i32_i4_e32 v40, v133, v53
	v_dot8c_i32_i4_e32 v41, v133, v51
	v_dot8c_i32_i4_e32 v42, v135, v53
	v_dot8c_i32_i4_e32 v43, v135, v51
	v_dot8c_i32_i4_e32 v44, v137, v53
	v_dot8c_i32_i4_e32 v45, v137, v51
	s_nop 3
	s_waitcnt lgkmcnt(15)
	v_lshlrev_b32_e32 v38, 5, v38
	v_lshlrev_b32_e32 v39, 1, v39
	v_add3_u32 v38, v39, v229, v38
	v_cvt_f32_i32_e32 v38, v38
	v_mul_f32_e32 v38, v228, v38
	v_lshlrev_b32_e32 v40, 5, v40
	v_lshlrev_b32_e32 v41, 1, v41
	v_add3_u32 v40, v41, v229, v40
	v_cvt_f32_i32_e32 v40, v40
	v_mul_f32_e32 v40, v228, v40
	v_lshlrev_b32_e32 v42, 5, v42
	v_lshlrev_b32_e32 v43, 1, v43
	v_add3_u32 v42, v43, v229, v42
	v_cvt_f32_i32_e32 v42, v42
	v_mul_f32_e32 v42, v228, v42
	v_lshlrev_b32_e32 v44, 5, v44
	v_lshlrev_b32_e32 v45, 1, v45
	v_add3_u32 v44, v45, v229, v44
	v_cvt_f32_i32_e32 v44, v44
	v_mul_f32_e32 v44, v228, v44
	v_cvt_pk_bf16_f32 v184, v38, v40
	v_cvt_pk_bf16_f32 v185, v42, v44
	ds_read_b128 v[252:255], v156
	s_add_i32 s44, s40, 8
	s_ashr_i32 s45, s44, 31
	s_lshl_b64 s[44:45], s[44:45], 12
	v_lshl_add_u64 v[80:81], v[36:37], 0, s[44:45]
	s_waitcnt lgkmcnt(0)
; #define LAS __attribute__((address_space(3)))
; __device__ __forceinline__ void peer_v_tokens(int j, const LAS unsigned short* EL, const LAS unsigned char* AL  , const LAS float* ASC  , const LAS int* SAL  , ...
;     ...
;         {
;             float4 v[4]; float ss = 0.f;
; #pragma unroll
;             for (int jq = 0; jq < 4; ++jq) { typedef unsigned u2v __attribute__((ext_vector_type(2))); const u2v pw = *(const LAS u2v*)(STASH + 4 * lane + 256 * jq); const uint2 hw = hv[jq];
;                 v[jq] = make_float4(__uint_as_float(hw.x << 16) + __uint_as_float(pw.x << 16), __uint_as_float(hw.x & 0xffff0000u) + __uint_as_float(pw.x & 0xffff0000u),
;                                     __uint_as_float(hw.y << 16) + __uint_as_float(pw.y << 16), __uint_as_float(hw.y & 0xffff0000u) + __uint_as_float(pw.y & 0xffff0000u));
;                 ss += v[jq].x * v[jq].x + v[jq].y * v[jq].y + v[jq].z * v[jq].z + v[jq].w * v[jq].w; }
;             ss = wave_sum(ss);
;             const float r3 = rsqrtf(ss * (1.f / D) + EPS);
;             float4* op = (float4*)(outp + (size_t)t * D) + lane;
; #pragma unroll
;             for (int jq = 0; jq < 4; ++jq) { typedef float f4v __attribute__((ext_vector_type(4))); f4v o4; o4.x = v[jq].x * r3 * gv[jq].x; o4.y = v[jq].y * r3 * gv[jq].y; o4.z = v[jq].z * r3 * gv[jq].z; o4.w = v[jq].w * r3 * gv[jq].w;
;                 __builtin_nontemporal_store(o4, (f4v*)op + 64 * jq); }
;         }
	v_mul_f32_e32 v244, v244, v252
	v_mul_f32_e32 v245, v245, v253
	v_mul_f32_e32 v246, v246, v254
	v_mul_f32_e32 v247, v247, v255
	global_store_dwordx4 v[80:81], v[244:247], off offset:2048 nt
	s_add_i32 s43, s40, 16
	s_lshl_b32 s43, s43, 11
	v_add_u32_e32 v138, s43, v66
	global_load_dwordx2 v[194:195], v138, s[70:71]
	global_load_dwordx2 v[196:197], v138, s[70:71] offset:512
	global_load_dwordx2 v[198:199], v138, s[70:71] offset:1024
	global_load_dwordx2 v[200:201], v138, s[70:71] offset:1536
	v_add_u32_e32 v147, 8, v140
	v_and_b32_e32 v146, 15, v147
	v_xor_b32_e32 v146, 8, v146
	v_bfe_u32 v148, v147, 4, 4
	v_mul_lo_u32 v146, v146, s92
	v_mul_lo_u32 v148, v148, s92
	v_mov_b32_e32 v147, v146
	v_mov_b32_e32 v149, v148
	ds_write2st64_b64 v77, v[146:147], v[148:149] offset1:2
	v_add_u32_e32 v138, 0x1000, v74
	ds_read_u8 v139, v138
	v_add_u32_e32 v141, 0x1000, v73
	ds_read_u8 v140, v141
	s_add_i32 s43, s67, 96
	v_mov_b32_e32 v138, s43
	ds_read2st64_b32 v[228:229], v138 offset1:1
	ds_read_b128 v[18:21], v227 offset:8192
	ds_read_b128 v[22:25], v227 offset:8208
	v_mov_b32_e32 v150, v63
	v_mov_b32_e32 v151, v64
	v_mov_b32_e32 v38, 0
	v_mov_b32_e32 v39, 0
	v_mov_b32_e32 v40, 0
	v_mov_b32_e32 v41, 0
	v_mov_b32_e32 v42, 0
	v_mov_b32_e32 v43, 0
	v_mov_b32_e32 v44, 0
	v_mov_b32_e32 v45, 0
	v_and_b32_e32 v78, 0xffff, v31
	v_lshrrev_b32_e32 v79, 16, v31
	v_lshl_add_u32 v78, v78, 7, v152
	v_lshl_add_u32 v79, v79, 7, v153
	s_mov_b32 m0, s99
	s_add_i32 s43, s99, 0x400
	global_load_lds_dwordx4 v78, s[50:51]
	s_mov_b32 m0, s43
	s_nop 0
	global_load_lds_dwordx4 v79, s[50:51]
	s_waitcnt vmcnt(13)
	v_add_u32_e32 v54, s77, v59
	v_add_u32_e32 v55, s77, v60
	v_add_u32_e32 v56, s77, v61
	v_add_u32_e32 v57, s77, v62
	ds_read_b64_tr_b4 v[50:51], v160 offset:128
	ds_read_b64_tr_b4 v[52:53], v160 offset:1152
	ds_read_b64_tr_b4 v[130:131], v54
	ds_read_b64_tr_b4 v[132:133], v55
	ds_read_b64_tr_b4 v[134:135], v56
	ds_read_b64_tr_b4 v[136:137], v57
	s_waitcnt lgkmcnt(13)
	v_dot8c_i32_i4_e32 v38, v122, v48
	v_dot8c_i32_i4_e32 v39, v122, v46
	v_dot8c_i32_i4_e32 v40, v124, v48
	v_dot8c_i32_i4_e32 v41, v124, v46
	v_dot8c_i32_i4_e32 v42, v126, v48
	v_dot8c_i32_i4_e32 v43, v126, v46
	v_dot8c_i32_i4_e32 v44, v128, v48
	v_dot8c_i32_i4_e32 v45, v128, v46
	v_dot8c_i32_i4_e32 v38, v123, v49
	v_dot8c_i32_i4_e32 v39, v123, v47
	v_dot8c_i32_i4_e32 v40, v125, v49
	v_dot8c_i32_i4_e32 v41, v125, v47
	v_dot8c_i32_i4_e32 v42, v127, v49
	v_dot8c_i32_i4_e32 v43, v127, v47
	v_dot8c_i32_i4_e32 v44, v129, v49
	v_dot8c_i32_i4_e32 v45, v129, v47
	v_and_b32_e32 v78, 0xffff, v32
	v_lshrrev_b32_e32 v79, 16, v32
	v_lshl_add_u32 v78, v78, 7, v152
	v_lshl_add_u32 v79, v79, 7, v153
	s_mov_b32 m0, s76
	s_add_i32 s43, s76, 0x400
	global_load_lds_dwordx4 v78, s[50:51]
	s_mov_b32 m0, s43
	s_nop 0
	global_load_lds_dwordx4 v79, s[50:51]
	s_waitcnt vmcnt(13)
	v_add_u32_e32 v54, s78, v59
	v_add_u32_e32 v55, s78, v60
	v_add_u32_e32 v56, s78, v61
	v_add_u32_e32 v57, s78, v62
	ds_read_b64_tr_b4 v[46:47], v160 offset:256
	ds_read_b64_tr_b4 v[48:49], v160 offset:1280
	ds_read_b64_tr_b4 v[122:123], v54
	ds_read_b64_tr_b4 v[124:125], v55
	ds_read_b64_tr_b4 v[126:127], v56
	ds_read_b64_tr_b4 v[128:129], v57
	s_waitcnt lgkmcnt(6)
	v_dot8c_i32_i4_e32 v38, v130, v52
	v_dot8c_i32_i4_e32 v39, v130, v50
	v_dot8c_i32_i4_e32 v40, v132, v52
	v_dot8c_i32_i4_e32 v41, v132, v50
	v_dot8c_i32_i4_e32 v42, v134, v52
	v_dot8c_i32_i4_e32 v43, v134, v50
	v_dot8c_i32_i4_e32 v44, v136, v52
	v_dot8c_i32_i4_e32 v45, v136, v50
	v_dot8c_i32_i4_e32 v38, v131, v53
	v_dot8c_i32_i4_e32 v39, v131, v51
	v_dot8c_i32_i4_e32 v40, v133, v53
	v_dot8c_i32_i4_e32 v41, v133, v51
	v_dot8c_i32_i4_e32 v42, v135, v53
	v_dot8c_i32_i4_e32 v43, v135, v51
	v_dot8c_i32_i4_e32 v44, v137, v53
	v_dot8c_i32_i4_e32 v45, v137, v51
	v_and_b32_e32 v78, 0xffff, v33
	v_lshrrev_b32_e32 v79, 16, v33
	v_lshl_add_u32 v78, v78, 7, v152
	v_lshl_add_u32 v79, v79, 7, v153
	s_mov_b32 m0, s77
	s_add_i32 s43, s77, 0x400
	global_load_lds_dwordx4 v78, s[50:51]
	s_mov_b32 m0, s43
	s_nop 0
	global_load_lds_dwordx4 v79, s[50:51]
	s_waitcnt vmcnt(13)
	v_add_u32_e32 v54, s79, v59
	v_add_u32_e32 v55, s79, v60
	v_add_u32_e32 v56, s79, v61
	v_add_u32_e32 v57, s79, v62
	ds_read_b64_tr_b4 v[50:51], v160 offset:384
	ds_read_b64_tr_b4 v[52:53], v160 offset:1408
	ds_read_b64_tr_b4 v[130:131], v54
	ds_read_b64_tr_b4 v[132:133], v55
	ds_read_b64_tr_b4 v[134:135], v56
	ds_read_b64_tr_b4 v[136:137], v57
	s_waitcnt lgkmcnt(6)
	v_dot8c_i32_i4_e32 v38, v122, v48
	v_dot8c_i32_i4_e32 v39, v122, v46
	v_dot8c_i32_i4_e32 v40, v124, v48
	v_dot8c_i32_i4_e32 v41, v124, v46
	v_dot8c_i32_i4_e32 v42, v126, v48
	v_dot8c_i32_i4_e32 v43, v126, v46
	v_dot8c_i32_i4_e32 v44, v128, v48
	v_dot8c_i32_i4_e32 v45, v128, v46
	v_dot8c_i32_i4_e32 v38, v123, v49
	v_dot8c_i32_i4_e32 v39, v123, v47
	v_dot8c_i32_i4_e32 v40, v125, v49
	v_dot8c_i32_i4_e32 v41, v125, v47
	v_dot8c_i32_i4_e32 v42, v127, v49
	v_dot8c_i32_i4_e32 v43, v127, v47
	v_dot8c_i32_i4_e32 v44, v129, v49
	v_dot8c_i32_i4_e32 v45, v129, v47
	s_waitcnt lgkmcnt(15)
	v_and_b32_e32 v78, 0xffff, v18
	v_lshrrev_b32_e32 v79, 16, v18
	v_lshl_add_u32 v78, v78, 7, v150
	v_lshl_add_u32 v79, v79, 7, v151
	s_mov_b32 m0, s78
	s_add_i32 s43, s78, 0x400
	global_load_lds_dwordx4 v78, s[50:51]
	s_mov_b32 m0, s43
	s_nop 0
	global_load_lds_dwordx4 v79, s[50:51]
	s_waitcnt vmcnt(13)
	v_add_u32_e32 v54, s98, v59
	v_add_u32_e32 v55, s98, v60
	v_add_u32_e32 v56, s98, v61
	v_add_u32_e32 v57, s98, v62
	ds_read_b64_tr_b4 v[46:47], v160 offset:512
	ds_read_b64_tr_b4 v[48:49], v160 offset:1536
	ds_read_b64_tr_b4 v[122:123], v54
	ds_read_b64_tr_b4 v[124:125], v55
	ds_read_b64_tr_b4 v[126:127], v56
	ds_read_b64_tr_b4 v[128:129], v57
	s_waitcnt lgkmcnt(6)
; #define TR4(p_) __builtin_amdgcn_ds_read_tr4_b64_v2i32((LAS v2i*)(p_))
; #define VDMA(st_, k_) do { _Pragma("unroll") for (int i_ = 0; i_ < 4; ++i_) { \
;         const unsigned off_ = (unsigned)((st_) >> 2) * (16384u * 128u) + (PE_ID(E, 4 * ((st_) & 3) + i_) << 7) + ((i_ & 1) ? cx1 : cx0); \
;         __builtin_amdgcn_global_load_lds((const unsigned*)(V4 + off_), (LAS unsigned*)(ldsb + BUF[k_] + 1024 * i_), 16, 0, 0); } } while (0)
; __device__ __forceinline__ void peer_v_tokens(int j, const LAS unsigned short* EL, const LAS unsigned char* AL  , const LAS float* ASC  , const LAS int* SAL  , ...
;     ...
;         for (int st = 0; st < 16; ++st) {
;             const int p = st >> 2, q = st & 3;
;             if (st < 14) VDMA(st + 2, (st + 2) % 3);
;             if (st < 14) asm volatile("s_waitcnt vmcnt(8)" ::: "memory");
;             else if (st == 14) asm volatile("s_waitcnt vmcnt(4)" ::: "memory");
;             else asm volatile("s_waitcnt vmcnt(0)" ::: "memory");
;             if (q == 0) {
; #pragma unroll
;                 for (int r = 0; r < 4; ++r) { accH[r] = 0; accL[r] = 0; } }
; #pragma unroll
;             for (int tp = 0; tp < 2; ++tp) {
;                 const v2i ao = TR4(ATL + (2 * q + tp) * 128 + 8 * s16), ah = TR4(ATL + 1024 + (2 * q + tp) * 128 + 8 * s16);
; #pragma unroll
;                 for (int r = 0; r < 4; ++r) {
;                     const v2i d = TR4(ldsb + BUF[st % 3] + 2048 * tp + roff[r]);
;                     accH[r] = __builtin_amdgcn_sdot8(d.x, ah.x, accH[r], false); accH[r] = __builtin_amdgcn_sdot8(d.y, ah.y, accH[r], false);
;                     accL[r] = __builtin_amdgcn_sdot8(d.x, ao.x, accL[r], false); accL[r] = __builtin_amdgcn_sdot8(d.y, ao.y, accL[r], false);
;                 }
;             }
;             asm volatile("s_waitcnt lgkmcnt(0)" ::: "memory");
	v_dot8c_i32_i4_e32 v38, v130, v52
	v_dot8c_i32_i4_e32 v39, v130, v50
	v_dot8c_i32_i4_e32 v40, v132, v52
	v_dot8c_i32_i4_e32 v41, v132, v50
	v_dot8c_i32_i4_e32 v42, v134, v52
	v_dot8c_i32_i4_e32 v43, v134, v50
	v_dot8c_i32_i4_e32 v44, v136, v52
	v_dot8c_i32_i4_e32 v45, v136, v50
	v_dot8c_i32_i4_e32 v38, v131, v53
	v_dot8c_i32_i4_e32 v39, v131, v51
	v_dot8c_i32_i4_e32 v40, v133, v53
	v_dot8c_i32_i4_e32 v41, v133, v51
	v_dot8c_i32_i4_e32 v42, v135, v53
	v_dot8c_i32_i4_e32 v43, v135, v51
	v_dot8c_i32_i4_e32 v44, v137, v53
	v_dot8c_i32_i4_e32 v45, v137, v51
	v_and_b32_e32 v78, 0xffff, v19
	v_lshrrev_b32_e32 v79, 16, v19
	v_lshl_add_u32 v78, v78, 7, v150
	v_lshl_add_u32 v79, v79, 7, v151
	s_mov_b32 m0, s79
	s_add_i32 s43, s79, 0x400
	global_load_lds_dwordx4 v78, s[50:51]
	s_mov_b32 m0, s43
	s_nop 0
	global_load_lds_dwordx4 v79, s[50:51]
	s_waitcnt vmcnt(8)
	v_add_u32_e32 v54, s99, v59
	v_add_u32_e32 v55, s99, v60
	v_add_u32_e32 v56, s99, v61
	v_add_u32_e32 v57, s99, v62
	ds_read_b64_tr_b4 v[50:51], v160 offset:640
	ds_read_b64_tr_b4 v[52:53], v160 offset:1664
	ds_read_b64_tr_b4 v[130:131], v54
	ds_read_b64_tr_b4 v[132:133], v55
	ds_read_b64_tr_b4 v[134:135], v56
	ds_read_b64_tr_b4 v[136:137], v57
	s_waitcnt lgkmcnt(6)
	v_dot8c_i32_i4_e32 v38, v122, v48
	v_dot8c_i32_i4_e32 v39, v122, v46
	v_dot8c_i32_i4_e32 v40, v124, v48
	v_dot8c_i32_i4_e32 v41, v124, v46
	v_dot8c_i32_i4_e32 v42, v126, v48
	v_dot8c_i32_i4_e32 v43, v126, v46
	v_dot8c_i32_i4_e32 v44, v128, v48
	v_dot8c_i32_i4_e32 v45, v128, v46
	v_dot8c_i32_i4_e32 v38, v123, v49
	v_dot8c_i32_i4_e32 v39, v123, v47
	v_dot8c_i32_i4_e32 v40, v125, v49
	v_dot8c_i32_i4_e32 v41, v125, v47
	v_dot8c_i32_i4_e32 v42, v127, v49
	v_dot8c_i32_i4_e32 v43, v127, v47
	v_dot8c_i32_i4_e32 v44, v129, v49
	v_dot8c_i32_i4_e32 v45, v129, v47
	s_waitcnt lgkmcnt(15)
	v_add_u32_e32 v143, 8, v139
	v_and_b32_e32 v142, 15, v143
	v_xor_b32_e32 v142, 8, v142
	v_bfe_u32 v144, v143, 4, 4
	v_mul_lo_u32 v142, v142, s92
	v_mul_lo_u32 v144, v144, s92
	v_mov_b32_e32 v143, v142
	v_mov_b32_e32 v145, v144
	ds_write2st64_b64 v159, v[142:143], v[144:145] offset1:2
	v_and_b32_e32 v78, 0xffff, v20
	v_lshrrev_b32_e32 v79, 16, v20
	v_lshl_add_u32 v78, v78, 7, v150
	v_lshl_add_u32 v79, v79, 7, v151
	s_mov_b32 m0, s98
	s_add_i32 s43, s98, 0x400
	global_load_lds_dwordx4 v78, s[50:51]
	s_mov_b32 m0, s43
	s_nop 0
	global_load_lds_dwordx4 v79, s[50:51]
	s_waitcnt vmcnt(8)
	v_add_u32_e32 v54, s76, v59
	v_add_u32_e32 v55, s76, v60
	v_add_u32_e32 v56, s76, v61
	v_add_u32_e32 v57, s76, v62
	ds_read_b64_tr_b4 v[46:47], v160 offset:768
	ds_read_b64_tr_b4 v[48:49], v160 offset:1792
	ds_read_b64_tr_b4 v[122:123], v54
	ds_read_b64_tr_b4 v[124:125], v55
	ds_read_b64_tr_b4 v[126:127], v56
	ds_read_b64_tr_b4 v[128:129], v57
	s_waitcnt lgkmcnt(7)
	v_dot8c_i32_i4_e32 v38, v130, v52
	v_dot8c_i32_i4_e32 v39, v130, v50
	v_dot8c_i32_i4_e32 v40, v132, v52
	v_dot8c_i32_i4_e32 v41, v132, v50
	v_dot8c_i32_i4_e32 v42, v134, v52
	v_dot8c_i32_i4_e32 v43, v134, v50
	v_dot8c_i32_i4_e32 v44, v136, v52
	v_dot8c_i32_i4_e32 v45, v136, v50
	v_dot8c_i32_i4_e32 v38, v131, v53
	v_dot8c_i32_i4_e32 v39, v131, v51
	v_dot8c_i32_i4_e32 v40, v133, v53
	v_dot8c_i32_i4_e32 v41, v133, v51
	v_dot8c_i32_i4_e32 v42, v135, v53
	v_dot8c_i32_i4_e32 v43, v135, v51
	v_dot8c_i32_i4_e32 v44, v137, v53
	v_dot8c_i32_i4_e32 v45, v137, v51
	v_and_b32_e32 v78, 0xffff, v21
	v_lshrrev_b32_e32 v79, 16, v21
	v_lshl_add_u32 v78, v78, 7, v150
	v_lshl_add_u32 v79, v79, 7, v151
	s_mov_b32 m0, s99
	s_add_i32 s43, s99, 0x400
	global_load_lds_dwordx4 v78, s[50:51]
	s_mov_b32 m0, s43
	s_nop 0
	global_load_lds_dwordx4 v79, s[50:51]
	s_waitcnt vmcnt(8)
	v_add_u32_e32 v54, s77, v59
	v_add_u32_e32 v55, s77, v60
	v_add_u32_e32 v56, s77, v61
	v_add_u32_e32 v57, s77, v62
	ds_read_b64_tr_b4 v[50:51], v160 offset:896
	ds_read_b64_tr_b4 v[52:53], v160 offset:1920
	ds_read_b64_tr_b4 v[130:131], v54
	ds_read_b64_tr_b4 v[132:133], v55
	ds_read_b64_tr_b4 v[134:135], v56
	ds_read_b64_tr_b4 v[136:137], v57
	s_waitcnt lgkmcnt(6)
	v_dot8c_i32_i4_e32 v38, v122, v48
	v_dot8c_i32_i4_e32 v39, v122, v46
	v_dot8c_i32_i4_e32 v40, v124, v48
	v_dot8c_i32_i4_e32 v41, v124, v46
	v_dot8c_i32_i4_e32 v42, v126, v48
	v_dot8c_i32_i4_e32 v43, v126, v46
	v_dot8c_i32_i4_e32 v44, v128, v48
	v_dot8c_i32_i4_e32 v45, v128, v46
	v_dot8c_i32_i4_e32 v38, v123, v49
	v_dot8c_i32_i4_e32 v39, v123, v47
	v_dot8c_i32_i4_e32 v40, v125, v49
	v_dot8c_i32_i4_e32 v41, v125, v47
	v_dot8c_i32_i4_e32 v42, v127, v49
	v_dot8c_i32_i4_e32 v43, v127, v47
	v_dot8c_i32_i4_e32 v44, v129, v49
	v_dot8c_i32_i4_e32 v45, v129, v47
	v_and_b32_e32 v78, 0xffff, v22
	v_lshrrev_b32_e32 v79, 16, v22
	v_lshl_add_u32 v78, v78, 7, v150
	v_lshl_add_u32 v79, v79, 7, v151
	s_mov_b32 m0, s76
	s_add_i32 s43, s76, 0x400
	global_load_lds_dwordx4 v78, s[50:51]
	s_mov_b32 m0, s43
	s_nop 0
	global_load_lds_dwordx4 v79, s[50:51]
	s_waitcnt vmcnt(8)
	v_add_u32_e32 v54, s78, v59
	v_add_u32_e32 v55, s78, v60
	v_add_u32_e32 v56, s78, v61
	v_add_u32_e32 v57, s78, v62
	ds_read_b64_tr_b4 v[46:47], v160
	ds_read_b64_tr_b4 v[48:49], v160 offset:1024
	ds_read_b64_tr_b4 v[122:123], v54
	ds_read_b64_tr_b4 v[124:125], v55
	ds_read_b64_tr_b4 v[126:127], v56
	ds_read_b64_tr_b4 v[128:129], v57
	s_waitcnt lgkmcnt(6)
	v_dot8c_i32_i4_e32 v38, v130, v52
	v_dot8c_i32_i4_e32 v39, v130, v50
	v_dot8c_i32_i4_e32 v40, v132, v52
	v_dot8c_i32_i4_e32 v41, v132, v50
	v_dot8c_i32_i4_e32 v42, v134, v52
	v_dot8c_i32_i4_e32 v43, v134, v50
	v_dot8c_i32_i4_e32 v44, v136, v52
	v_dot8c_i32_i4_e32 v45, v136, v50
	v_dot8c_i32_i4_e32 v38, v131, v53
	v_dot8c_i32_i4_e32 v39, v131, v51
	v_dot8c_i32_i4_e32 v40, v133, v53
	v_dot8c_i32_i4_e32 v41, v133, v51
	v_dot8c_i32_i4_e32 v42, v135, v53
	v_dot8c_i32_i4_e32 v43, v135, v51
	v_dot8c_i32_i4_e32 v44, v137, v53
	v_dot8c_i32_i4_e32 v45, v137, v51
	s_nop 3
	s_waitcnt lgkmcnt(15)
; #define LAS __attribute__((address_space(3)))
; __device__ __forceinline__ bf16 f2bf(float f) { return (bf16)f2bfu(f); }
; #define CFENCE() asm volatile("" ::: "memory")
; __device__ __forceinline__ void peer_v_tokens(int j, const LAS unsigned short* EL, const LAS unsigned char* AL  , const LAS float* ASC  , const LAS int* SAL  , ...
;     ...
;             if (q == 3) {
; #pragma unroll
;                 for (int r = 0; r < 4; ++r) STASH[256 * p + 16 * (grp + 4 * r) + pc] = f2bf(asc * (float)(2 * ((accH[r] << 4) + accL[r]) + sa));
;             }
;         }
;         CFENCE();
;         {
;             float4 v[4]; float ss = 0.f;
; #pragma unroll
;             for (int jq = 0; jq < 4; ++jq) { typedef unsigned u2v __attribute__((ext_vector_type(2))); const u2v pw = *(const LAS u2v*)(STASH + 4 * lane + 256 * jq); const uint2 hw = hv[jq];
;                 v[jq] = make_float4(__uint_as_float(hw.x << 16) + __uint_as_float(pw.x << 16), __uint_as_float(hw.x & 0xffff0000u) + __uint_as_float(pw.x & 0xffff0000u),
;                                     __uint_as_float(hw.y << 16) + __uint_as_float(pw.y << 16), __uint_as_float(hw.y & 0xffff0000u) + __uint_as_float(pw.y & 0xffff0000u));
;                 ss += v[jq].x * v[jq].x + v[jq].y * v[jq].y + v[jq].z * v[jq].z + v[jq].w * v[jq].w; }
;             ss = wave_sum(ss);
;             const float r3 = rsqrtf(ss * (1.f / D) + EPS);
;             float4* op = (float4*)(outp + (size_t)t * D) + lane;
; #pragma unroll
;             for (int jq = 0; jq < 4; ++jq) { typedef float f4v __attribute__((ext_vector_type(4))); f4v o4; o4.x = v[jq].x * r3 * gv[jq].x; o4.y = v[jq].y * r3 * gv[jq].y; o4.z = v[jq].z * r3 * gv[jq].z; o4.w = v[jq].w * r3 * gv[jq].w;
;                 __builtin_nontemporal_store(o4, (f4v*)op + 64 * jq); }
;         }
	v_lshlrev_b32_e32 v38, 5, v38
	v_lshlrev_b32_e32 v39, 1, v39
	v_add3_u32 v38, v39, v229, v38
	v_cvt_f32_i32_e32 v38, v38
	v_mul_f32_e32 v38, v228, v38
	v_lshlrev_b32_e32 v40, 5, v40
	v_lshlrev_b32_e32 v41, 1, v41
	v_add3_u32 v40, v41, v229, v40
	v_cvt_f32_i32_e32 v40, v40
	v_mul_f32_e32 v40, v228, v40
	v_lshlrev_b32_e32 v42, 5, v42
	v_lshlrev_b32_e32 v43, 1, v43
	v_add3_u32 v42, v43, v229, v42
	v_cvt_f32_i32_e32 v42, v42
	v_mul_f32_e32 v42, v228, v42
	v_lshlrev_b32_e32 v44, 5, v44
	v_lshlrev_b32_e32 v45, 1, v45
	v_add3_u32 v44, v45, v229, v44
	v_cvt_f32_i32_e32 v44, v44
	v_mul_f32_e32 v44, v228, v44
	v_cvt_pk_bf16_f32 v192, v38, v40
	v_cvt_pk_bf16_f32 v193, v42, v44
	ds_read_b128 v[252:255], v156 offset:1024
	s_add_i32 s44, s40, 8
	s_ashr_i32 s45, s44, 31
	s_lshl_b64 s[44:45], s[44:45], 12
	v_lshl_add_u64 v[80:81], v[36:37], 0, s[44:45]
	s_waitcnt lgkmcnt(0)
	v_mul_f32_e32 v248, v248, v252
	v_mul_f32_e32 v249, v249, v253
	v_mul_f32_e32 v250, v250, v254
	v_mul_f32_e32 v251, v251, v255
	global_store_dwordx4 v[80:81], v[248:251], off offset:3072 nt
	v_add_u32_e32 v147, 8, v140
	v_and_b32_e32 v146, 15, v147
	v_xor_b32_e32 v146, 8, v146
	v_bfe_u32 v148, v147, 4, 4
	v_mul_lo_u32 v146, v146, s92
	v_mul_lo_u32 v148, v148, s92
	v_mov_b32_e32 v147, v146
	v_mov_b32_e32 v149, v148
	ds_write2st64_b64 v77, v[146:147], v[148:149] offset1:2
	v_add_u32_e32 v138, 0x1400, v74
	ds_read_u8 v139, v138
	v_add_u32_e32 v141, 0x1400, v73
	ds_read_u8 v140, v141
	s_add_i32 s43, s67, 128
	v_mov_b32_e32 v138, s43
	ds_read2st64_b32 v[228:229], v138 offset1:1
	ds_read_b128 v[26:29], v227 offset:10240
	ds_read_b128 v[30:33], v227 offset:10256
	v_mov_b32_e32 v38, 0
	v_mov_b32_e32 v39, 0
	v_mov_b32_e32 v40, 0
	v_mov_b32_e32 v41, 0
	v_mov_b32_e32 v42, 0
	v_mov_b32_e32 v43, 0
	v_mov_b32_e32 v44, 0
	v_mov_b32_e32 v45, 0
	v_and_b32_e32 v78, 0xffff, v23
	v_lshrrev_b32_e32 v79, 16, v23
	v_lshl_add_u32 v78, v78, 7, v150
	v_lshl_add_u32 v79, v79, 7, v151
	s_mov_b32 m0, s77
	s_add_i32 s43, s77, 0x400
	global_load_lds_dwordx4 v78, s[50:51]
	s_mov_b32 m0, s43
	s_nop 0
	global_load_lds_dwordx4 v79, s[50:51]
	s_waitcnt vmcnt(9)
	v_add_u32_e32 v54, s79, v59
	v_add_u32_e32 v55, s79, v60
	v_add_u32_e32 v56, s79, v61
	v_add_u32_e32 v57, s79, v62
	ds_read_b64_tr_b4 v[50:51], v160 offset:128
	ds_read_b64_tr_b4 v[52:53], v160 offset:1152
	ds_read_b64_tr_b4 v[130:131], v54
	ds_read_b64_tr_b4 v[132:133], v55
	ds_read_b64_tr_b4 v[134:135], v56
	ds_read_b64_tr_b4 v[136:137], v57
	s_waitcnt lgkmcnt(13)
	v_dot8c_i32_i4_e32 v38, v122, v48
	v_dot8c_i32_i4_e32 v39, v122, v46
	v_dot8c_i32_i4_e32 v40, v124, v48
	v_dot8c_i32_i4_e32 v41, v124, v46
	v_dot8c_i32_i4_e32 v42, v126, v48
	v_dot8c_i32_i4_e32 v43, v126, v46
	v_dot8c_i32_i4_e32 v44, v128, v48
	v_dot8c_i32_i4_e32 v45, v128, v46
	v_dot8c_i32_i4_e32 v38, v123, v49
	v_dot8c_i32_i4_e32 v39, v123, v47
	v_dot8c_i32_i4_e32 v40, v125, v49
	v_dot8c_i32_i4_e32 v41, v125, v47
	v_dot8c_i32_i4_e32 v42, v127, v49
	v_dot8c_i32_i4_e32 v43, v127, v47
	v_dot8c_i32_i4_e32 v44, v129, v49
	v_dot8c_i32_i4_e32 v45, v129, v47
	v_and_b32_e32 v78, 0xffff, v24
	v_lshrrev_b32_e32 v79, 16, v24
	v_lshl_add_u32 v78, v78, 7, v150
	v_lshl_add_u32 v79, v79, 7, v151
	s_mov_b32 m0, s78
	s_add_i32 s43, s78, 0x400
	global_load_lds_dwordx4 v78, s[50:51]
	s_mov_b32 m0, s43
	s_nop 0
	global_load_lds_dwordx4 v79, s[50:51]
	s_waitcnt vmcnt(9)
	v_add_u32_e32 v54, s98, v59
	v_add_u32_e32 v55, s98, v60
	v_add_u32_e32 v56, s98, v61
	v_add_u32_e32 v57, s98, v62
	ds_read_b64_tr_b4 v[46:47], v160 offset:256
	ds_read_b64_tr_b4 v[48:49], v160 offset:1280
	ds_read_b64_tr_b4 v[122:123], v54
	ds_read_b64_tr_b4 v[124:125], v55
	ds_read_b64_tr_b4 v[126:127], v56
	ds_read_b64_tr_b4 v[128:129], v57
	s_waitcnt lgkmcnt(6)
	v_dot8c_i32_i4_e32 v38, v130, v52
	v_dot8c_i32_i4_e32 v39, v130, v50
	v_dot8c_i32_i4_e32 v40, v132, v52
	v_dot8c_i32_i4_e32 v41, v132, v50
	v_dot8c_i32_i4_e32 v42, v134, v52
	v_dot8c_i32_i4_e32 v43, v134, v50
	v_dot8c_i32_i4_e32 v44, v136, v52
	v_dot8c_i32_i4_e32 v45, v136, v50
	v_dot8c_i32_i4_e32 v38, v131, v53
	v_dot8c_i32_i4_e32 v39, v131, v51
	v_dot8c_i32_i4_e32 v40, v133, v53
	v_dot8c_i32_i4_e32 v41, v133, v51
	v_dot8c_i32_i4_e32 v42, v135, v53
	v_dot8c_i32_i4_e32 v43, v135, v51
	v_dot8c_i32_i4_e32 v44, v137, v53
	v_dot8c_i32_i4_e32 v45, v137, v51
	ds_write_b16 v65, v178
	ds_write_b16_d16_hi v65, v178 offset:128
	ds_write_b16 v65, v179 offset:256
	ds_write_b16_d16_hi v65, v179 offset:384
	ds_write_b16 v65, v180 offset:512
	ds_write_b16_d16_hi v65, v180 offset:640
	ds_write_b16 v65, v181 offset:768
	ds_write_b16_d16_hi v65, v181 offset:896
	ds_write_b16 v65, v182 offset:1024
	ds_write_b16_d16_hi v65, v182 offset:1152
	ds_write_b16 v65, v183 offset:1280
	ds_write_b16_d16_hi v65, v183 offset:1408
	ds_write_b16 v65, v184 offset:1536
	ds_write_b16_d16_hi v65, v184 offset:1664
	ds_write_b16 v65, v185 offset:1792
	ds_write_b16_d16_hi v65, v185 offset:1920
	ds_read_b64 v[202:203], v154
	ds_read_b64 v[204:205], v154 offset:512
	ds_read_b64 v[206:207], v154 offset:1024
	ds_read_b64 v[208:209], v154 offset:1536
	v_and_b32_e32 v78, 0xffff, v25
	v_lshrrev_b32_e32 v79, 16, v25
	v_lshl_add_u32 v78, v78, 7, v150
	v_lshl_add_u32 v79, v79, 7, v151
	s_mov_b32 m0, s79
	s_add_i32 s43, s79, 0x400
	global_load_lds_dwordx4 v78, s[50:51]
	s_mov_b32 m0, s43
	s_nop 0
	global_load_lds_dwordx4 v79, s[50:51]
	s_waitcnt vmcnt(9)
	v_add_u32_e32 v54, s99, v59
	v_add_u32_e32 v55, s99, v60
	v_add_u32_e32 v56, s99, v61
	v_add_u32_e32 v57, s99, v62
	ds_read_b64_tr_b4 v[50:51], v160 offset:384
	ds_read_b64_tr_b4 v[52:53], v160 offset:1408
	ds_read_b64_tr_b4 v[130:131], v54
	ds_read_b64_tr_b4 v[132:133], v55
	ds_read_b64_tr_b4 v[134:135], v56
	ds_read_b64_tr_b4 v[136:137], v57
	s_waitcnt lgkmcnt(15)
; #define TR4(p_) __builtin_amdgcn_ds_read_tr4_b64_v2i32((LAS v2i*)(p_))
; #define VDMA(st_, k_) do { _Pragma("unroll") for (int i_ = 0; i_ < 4; ++i_) { \
;         const unsigned off_ = (unsigned)((st_) >> 2) * (16384u * 128u) + (PE_ID(E, 4 * ((st_) & 3) + i_) << 7) + ((i_ & 1) ? cx1 : cx0); \
;         __builtin_amdgcn_global_load_lds((const unsigned*)(V4 + off_), (LAS unsigned*)(ldsb + BUF[k_] + 1024 * i_), 16, 0, 0); } } while (0)
; __device__ __forceinline__ void peer_v_tokens(int j, const LAS unsigned short* EL, const LAS unsigned char* AL  , const LAS float* ASC  , const LAS int* SAL  , ...
;     ...
;         for (int st = 0; st < 16; ++st) {
;             const int p = st >> 2, q = st & 3;
;             if (st < 14) VDMA(st + 2, (st + 2) % 3);
;             if (st < 14) asm volatile("s_waitcnt vmcnt(8)" ::: "memory");
;             else if (st == 14) asm volatile("s_waitcnt vmcnt(4)" ::: "memory");
;             else asm volatile("s_waitcnt vmcnt(0)" ::: "memory");
;             if (q == 0) {
; #pragma unroll
;                 for (int r = 0; r < 4; ++r) { accH[r] = 0; accL[r] = 0; } }
; #pragma unroll
;             for (int tp = 0; tp < 2; ++tp) {
;                 const v2i ao = TR4(ATL + (2 * q + tp) * 128 + 8 * s16), ah = TR4(ATL + 1024 + (2 * q + tp) * 128 + 8 * s16);
; #pragma unroll
;                 for (int r = 0; r < 4; ++r) {
;                     const v2i d = TR4(ldsb + BUF[st % 3] + 2048 * tp + roff[r]);
;                     accH[r] = __builtin_amdgcn_sdot8(d.x, ah.x, accH[r], false); accH[r] = __builtin_amdgcn_sdot8(d.y, ah.y, accH[r], false);
;                     accL[r] = __builtin_amdgcn_sdot8(d.x, ao.x, accL[r], false); accL[r] = __builtin_amdgcn_sdot8(d.y, ao.y, accL[r], false);
;                 }
;             }
;             asm volatile("s_waitcnt lgkmcnt(0)" ::: "memory");
	v_dot8c_i32_i4_e32 v38, v122, v48
	v_dot8c_i32_i4_e32 v39, v122, v46
	v_dot8c_i32_i4_e32 v40, v124, v48
	v_dot8c_i32_i4_e32 v41, v124, v46
	v_dot8c_i32_i4_e32 v42, v126, v48
	v_dot8c_i32_i4_e32 v43, v126, v46
	v_dot8c_i32_i4_e32 v44, v128, v48
	v_dot8c_i32_i4_e32 v45, v128, v46
	v_dot8c_i32_i4_e32 v38, v123, v49
	v_dot8c_i32_i4_e32 v39, v123, v47
	v_dot8c_i32_i4_e32 v40, v125, v49
	v_dot8c_i32_i4_e32 v41, v125, v47
	v_dot8c_i32_i4_e32 v42, v127, v49
	v_dot8c_i32_i4_e32 v43, v127, v47
	v_dot8c_i32_i4_e32 v44, v129, v49
	v_dot8c_i32_i4_e32 v45, v129, v47
	s_waitcnt lgkmcnt(15)
	v_and_b32_e32 v78, 0xffff, v26
	v_lshrrev_b32_e32 v79, 16, v26
	v_lshl_add_u32 v78, v78, 7, v150
	v_lshl_add_u32 v79, v79, 7, v151
	s_mov_b32 m0, s98
	s_add_i32 s43, s98, 0x400
	global_load_lds_dwordx4 v78, s[50:51]
	s_mov_b32 m0, s43
	s_nop 0
	global_load_lds_dwordx4 v79, s[50:51]
	s_waitcnt vmcnt(9)
	v_add_u32_e32 v54, s76, v59
	v_add_u32_e32 v55, s76, v60
	v_add_u32_e32 v56, s76, v61
	v_add_u32_e32 v57, s76, v62
	ds_read_b64_tr_b4 v[46:47], v160 offset:512
	ds_read_b64_tr_b4 v[48:49], v160 offset:1536
	ds_read_b64_tr_b4 v[122:123], v54
	ds_read_b64_tr_b4 v[124:125], v55
	ds_read_b64_tr_b4 v[126:127], v56
	ds_read_b64_tr_b4 v[128:129], v57
	s_waitcnt lgkmcnt(6)
	v_dot8c_i32_i4_e32 v38, v130, v52
	v_dot8c_i32_i4_e32 v39, v130, v50
	v_dot8c_i32_i4_e32 v40, v132, v52
	v_dot8c_i32_i4_e32 v41, v132, v50
	v_dot8c_i32_i4_e32 v42, v134, v52
	v_dot8c_i32_i4_e32 v43, v134, v50
	v_dot8c_i32_i4_e32 v44, v136, v52
	v_dot8c_i32_i4_e32 v45, v136, v50
	v_dot8c_i32_i4_e32 v38, v131, v53
	v_dot8c_i32_i4_e32 v39, v131, v51
	v_dot8c_i32_i4_e32 v40, v133, v53
	v_dot8c_i32_i4_e32 v41, v133, v51
	v_dot8c_i32_i4_e32 v42, v135, v53
	v_dot8c_i32_i4_e32 v43, v135, v51
	v_dot8c_i32_i4_e32 v44, v137, v53
	v_dot8c_i32_i4_e32 v45, v137, v51
	v_and_b32_e32 v78, 0xffff, v27
	v_lshrrev_b32_e32 v79, 16, v27
	v_lshl_add_u32 v78, v78, 7, v150
	v_lshl_add_u32 v79, v79, 7, v151
	s_mov_b32 m0, s99
	s_add_i32 s43, s99, 0x400
	global_load_lds_dwordx4 v78, s[50:51]
	s_mov_b32 m0, s43
	s_nop 0
	global_load_lds_dwordx4 v79, s[50:51]
	s_waitcnt vmcnt(8)
	v_add_u32_e32 v54, s77, v59
	v_add_u32_e32 v55, s77, v60
	v_add_u32_e32 v56, s77, v61
	v_add_u32_e32 v57, s77, v62
	ds_read_b64_tr_b4 v[50:51], v160 offset:640
	ds_read_b64_tr_b4 v[52:53], v160 offset:1664
	ds_read_b64_tr_b4 v[130:131], v54
	ds_read_b64_tr_b4 v[132:133], v55
	ds_read_b64_tr_b4 v[134:135], v56
	ds_read_b64_tr_b4 v[136:137], v57
	s_waitcnt lgkmcnt(6)
	v_dot8c_i32_i4_e32 v38, v122, v48
	v_dot8c_i32_i4_e32 v39, v122, v46
	v_dot8c_i32_i4_e32 v40, v124, v48
	v_dot8c_i32_i4_e32 v41, v124, v46
	v_dot8c_i32_i4_e32 v42, v126, v48
	v_dot8c_i32_i4_e32 v43, v126, v46
	v_dot8c_i32_i4_e32 v44, v128, v48
	v_dot8c_i32_i4_e32 v45, v128, v46
	v_dot8c_i32_i4_e32 v38, v123, v49
	v_dot8c_i32_i4_e32 v39, v123, v47
	v_dot8c_i32_i4_e32 v40, v125, v49
	v_dot8c_i32_i4_e32 v41, v125, v47
	v_dot8c_i32_i4_e32 v42, v127, v49
	v_dot8c_i32_i4_e32 v43, v127, v47
	v_dot8c_i32_i4_e32 v44, v129, v49
	v_dot8c_i32_i4_e32 v45, v129, v47
	s_waitcnt lgkmcnt(15)
	v_add_u32_e32 v143, 8, v139
	v_and_b32_e32 v142, 15, v143
	v_xor_b32_e32 v142, 8, v142
	v_bfe_u32 v144, v143, 4, 4
	v_mul_lo_u32 v142, v142, s92
	v_mul_lo_u32 v144, v144, s92
	v_mov_b32_e32 v143, v142
	v_mov_b32_e32 v145, v144
	ds_write2st64_b64 v159, v[142:143], v[144:145] offset1:2
	v_and_b32_e32 v78, 0xffff, v28
	v_lshrrev_b32_e32 v79, 16, v28
	v_lshl_add_u32 v78, v78, 7, v150
	v_lshl_add_u32 v79, v79, 7, v151
	s_mov_b32 m0, s76
	s_add_i32 s43, s76, 0x400
	global_load_lds_dwordx4 v78, s[50:51]
	s_mov_b32 m0, s43
	s_nop 0
	global_load_lds_dwordx4 v79, s[50:51]
	s_waitcnt vmcnt(8)
	v_add_u32_e32 v54, s78, v59
	v_add_u32_e32 v55, s78, v60
	v_add_u32_e32 v56, s78, v61
	v_add_u32_e32 v57, s78, v62
	ds_read_b64_tr_b4 v[46:47], v160 offset:768
	ds_read_b64_tr_b4 v[48:49], v160 offset:1792
	ds_read_b64_tr_b4 v[122:123], v54
	ds_read_b64_tr_b4 v[124:125], v55
	ds_read_b64_tr_b4 v[126:127], v56
	ds_read_b64_tr_b4 v[128:129], v57
	s_waitcnt lgkmcnt(7)
	v_dot8c_i32_i4_e32 v38, v130, v52
	v_dot8c_i32_i4_e32 v39, v130, v50
	v_dot8c_i32_i4_e32 v40, v132, v52
	v_dot8c_i32_i4_e32 v41, v132, v50
	v_dot8c_i32_i4_e32 v42, v134, v52
	v_dot8c_i32_i4_e32 v43, v134, v50
	v_dot8c_i32_i4_e32 v44, v136, v52
	v_dot8c_i32_i4_e32 v45, v136, v50
	v_dot8c_i32_i4_e32 v38, v131, v53
	v_dot8c_i32_i4_e32 v39, v131, v51
	v_dot8c_i32_i4_e32 v40, v133, v53
	v_dot8c_i32_i4_e32 v41, v133, v51
	v_dot8c_i32_i4_e32 v42, v135, v53
	v_dot8c_i32_i4_e32 v43, v135, v51
	v_dot8c_i32_i4_e32 v44, v137, v53
	v_dot8c_i32_i4_e32 v45, v137, v51
	v_and_b32_e32 v78, 0xffff, v29
	v_lshrrev_b32_e32 v79, 16, v29
	v_lshl_add_u32 v78, v78, 7, v150
	v_lshl_add_u32 v79, v79, 7, v151
	s_mov_b32 m0, s77
	s_add_i32 s43, s77, 0x400
	global_load_lds_dwordx4 v78, s[50:51]
	s_mov_b32 m0, s43
	s_nop 0
	global_load_lds_dwordx4 v79, s[50:51]
	s_waitcnt vmcnt(8)
	v_add_u32_e32 v54, s79, v59
	v_add_u32_e32 v55, s79, v60
	v_add_u32_e32 v56, s79, v61
	v_add_u32_e32 v57, s79, v62
	ds_read_b64_tr_b4 v[50:51], v160 offset:896
	ds_read_b64_tr_b4 v[52:53], v160 offset:1920
	ds_read_b64_tr_b4 v[130:131], v54
	ds_read_b64_tr_b4 v[132:133], v55
	ds_read_b64_tr_b4 v[134:135], v56
	ds_read_b64_tr_b4 v[136:137], v57
	s_waitcnt lgkmcnt(6)
; #define LAS __attribute__((address_space(3)))
; __device__ __forceinline__ bf16 f2bf(float f) { return (bf16)f2bfu(f); }
; #define CFENCE() asm volatile("" ::: "memory")
; __device__ __forceinline__ void peer_v_tokens(int j, const LAS unsigned short* EL, const LAS unsigned char* AL  , const LAS float* ASC  , const LAS int* SAL  , ...
;     ...
;             if (q == 3) {
; #pragma unroll
;                 for (int r = 0; r < 4; ++r) STASH[256 * p + 16 * (grp + 4 * r) + pc] = f2bf(asc * (float)(2 * ((accH[r] << 4) + accL[r]) + sa));
;             }
;         }
;         CFENCE();
;         {
;             float4 v[4]; float ss = 0.f;
; #pragma unroll
;             for (int jq = 0; jq < 4; ++jq) { typedef unsigned u2v __attribute__((ext_vector_type(2))); const u2v pw = *(const LAS u2v*)(STASH + 4 * lane + 256 * jq); const uint2 hw = hv[jq];
;                 v[jq] = make_float4(__uint_as_float(hw.x << 16) + __uint_as_float(pw.x << 16), __uint_as_float(hw.x & 0xffff0000u) + __uint_as_float(pw.x & 0xffff0000u),
;                                     __uint_as_float(hw.y << 16) + __uint_as_float(pw.y << 16), __uint_as_float(hw.y & 0xffff0000u) + __uint_as_float(pw.y & 0xffff0000u));
;                 ss += v[jq].x * v[jq].x + v[jq].y * v[jq].y + v[jq].z * v[jq].z + v[jq].w * v[jq].w; }
;             ss = wave_sum(ss);
;             const float r3 = rsqrtf(ss * (1.f / D) + EPS);
	v_dot8c_i32_i4_e32 v38, v122, v48
	v_dot8c_i32_i4_e32 v39, v122, v46
	v_dot8c_i32_i4_e32 v40, v124, v48
	v_dot8c_i32_i4_e32 v41, v124, v46
	v_dot8c_i32_i4_e32 v42, v126, v48
	v_dot8c_i32_i4_e32 v43, v126, v46
	v_dot8c_i32_i4_e32 v44, v128, v48
	v_dot8c_i32_i4_e32 v45, v128, v46
	v_dot8c_i32_i4_e32 v38, v123, v49
	v_dot8c_i32_i4_e32 v39, v123, v47
	v_dot8c_i32_i4_e32 v40, v125, v49
	v_dot8c_i32_i4_e32 v41, v125, v47
	v_dot8c_i32_i4_e32 v42, v127, v49
	v_dot8c_i32_i4_e32 v43, v127, v47
	v_dot8c_i32_i4_e32 v44, v129, v49
	v_dot8c_i32_i4_e32 v45, v129, v47
	v_and_b32_e32 v78, 0xffff, v30
	v_lshrrev_b32_e32 v79, 16, v30
	v_lshl_add_u32 v78, v78, 7, v150
	v_lshl_add_u32 v79, v79, 7, v151
	s_mov_b32 m0, s78
	s_add_i32 s43, s78, 0x400
	global_load_lds_dwordx4 v78, s[50:51]
	s_mov_b32 m0, s43
	s_nop 0
	global_load_lds_dwordx4 v79, s[50:51]
	s_waitcnt vmcnt(8)
	v_add_u32_e32 v54, s98, v59
	v_add_u32_e32 v55, s98, v60
	v_add_u32_e32 v56, s98, v61
	v_add_u32_e32 v57, s98, v62
	ds_read_b64_tr_b4 v[46:47], v160
	ds_read_b64_tr_b4 v[48:49], v160 offset:1024
	ds_read_b64_tr_b4 v[122:123], v54
	ds_read_b64_tr_b4 v[124:125], v55
	ds_read_b64_tr_b4 v[126:127], v56
	ds_read_b64_tr_b4 v[128:129], v57
	s_waitcnt lgkmcnt(6)
	v_dot8c_i32_i4_e32 v38, v130, v52
	v_dot8c_i32_i4_e32 v39, v130, v50
	v_dot8c_i32_i4_e32 v40, v132, v52
	v_dot8c_i32_i4_e32 v41, v132, v50
	v_dot8c_i32_i4_e32 v42, v134, v52
	v_dot8c_i32_i4_e32 v43, v134, v50
	v_dot8c_i32_i4_e32 v44, v136, v52
	v_dot8c_i32_i4_e32 v45, v136, v50
	v_dot8c_i32_i4_e32 v38, v131, v53
	v_dot8c_i32_i4_e32 v39, v131, v51
	v_dot8c_i32_i4_e32 v40, v133, v53
	v_dot8c_i32_i4_e32 v41, v133, v51
	v_dot8c_i32_i4_e32 v42, v135, v53
	v_dot8c_i32_i4_e32 v43, v135, v51
	v_dot8c_i32_i4_e32 v44, v137, v53
	v_dot8c_i32_i4_e32 v45, v137, v51
	s_nop 3
	s_waitcnt lgkmcnt(15)
	v_lshlrev_b32_e32 v38, 5, v38
	v_lshlrev_b32_e32 v39, 1, v39
	v_add3_u32 v38, v39, v229, v38
	v_cvt_f32_i32_e32 v38, v38
	v_mul_f32_e32 v38, v228, v38
	v_lshlrev_b32_e32 v40, 5, v40
	v_lshlrev_b32_e32 v41, 1, v41
	v_add3_u32 v40, v41, v229, v40
	v_cvt_f32_i32_e32 v40, v40
	v_mul_f32_e32 v40, v228, v40
	v_lshlrev_b32_e32 v42, 5, v42
	v_lshlrev_b32_e32 v43, 1, v43
	v_add3_u32 v42, v43, v229, v42
	v_cvt_f32_i32_e32 v42, v42
	v_mul_f32_e32 v42, v228, v42
	v_lshlrev_b32_e32 v44, 5, v44
	v_lshlrev_b32_e32 v45, 1, v45
	v_add3_u32 v44, v45, v229, v44
	v_cvt_f32_i32_e32 v44, v44
	v_mul_f32_e32 v44, v228, v44
	v_cvt_pk_bf16_f32 v162, v38, v40
	v_cvt_pk_bf16_f32 v163, v42, v44
	v_add_u32_e32 v147, 8, v140
	v_and_b32_e32 v146, 15, v147
	v_xor_b32_e32 v146, 8, v146
	v_bfe_u32 v148, v147, 4, 4
	v_mul_lo_u32 v146, v146, s92
	v_mul_lo_u32 v148, v148, s92
	v_mov_b32_e32 v147, v146
	v_mov_b32_e32 v149, v148
	ds_write2st64_b64 v77, v[146:147], v[148:149] offset1:2
	v_add_u32_e32 v138, 0x1000, v74
	ds_read_u8 v139, v138
	v_add_u32_e32 v141, 0x1000, v73
	ds_read_u8 v140, v141
	s_add_i32 s43, s67, 160
	v_mov_b32_e32 v138, s43
	ds_read2st64_b32 v[228:229], v138 offset1:1
	ds_read_b128 v[18:21], v227 offset:8192
	ds_read_b128 v[22:25], v227 offset:8208
	v_add_u32_e32 v152, 0x200000, v63
	v_add_u32_e32 v153, 0x200000, v64
	v_mov_b32_e32 v38, 0
	v_mov_b32_e32 v39, 0
	v_mov_b32_e32 v40, 0
	v_mov_b32_e32 v41, 0
	v_mov_b32_e32 v42, 0
	v_mov_b32_e32 v43, 0
	v_mov_b32_e32 v44, 0
	v_mov_b32_e32 v45, 0
	v_and_b32_e32 v78, 0xffff, v31
	v_lshrrev_b32_e32 v79, 16, v31
	v_lshl_add_u32 v78, v78, 7, v150
	v_lshl_add_u32 v79, v79, 7, v151
	s_mov_b32 m0, s79
	s_add_i32 s43, s79, 0x400
	global_load_lds_dwordx4 v78, s[50:51]
	s_mov_b32 m0, s43
	s_nop 0
	global_load_lds_dwordx4 v79, s[50:51]
	s_waitcnt vmcnt(8)
	v_add_u32_e32 v54, s99, v59
	v_add_u32_e32 v55, s99, v60
	v_add_u32_e32 v56, s99, v61
	v_add_u32_e32 v57, s99, v62
	ds_read_b64_tr_b4 v[50:51], v160 offset:128
	ds_read_b64_tr_b4 v[52:53], v160 offset:1152
	ds_read_b64_tr_b4 v[130:131], v54
	ds_read_b64_tr_b4 v[132:133], v55
	ds_read_b64_tr_b4 v[134:135], v56
	ds_read_b64_tr_b4 v[136:137], v57
	s_waitcnt lgkmcnt(12)
	s_waitcnt vmcnt(35) lgkmcnt(15)
	v_lshlrev_b32_e32 v210, 16, v194
	v_and_b32_e32 v211, 0xffff0000, v194
	v_lshlrev_b32_e32 v142, 16, v202
	v_and_b32_e32 v143, 0xffff0000, v202
	v_add_f32_e32 v210, v210, v142
	v_add_f32_e32 v211, v211, v143
	v_lshlrev_b32_e32 v212, 16, v195
	v_and_b32_e32 v213, 0xffff0000, v195
	v_lshlrev_b32_e32 v142, 16, v203
	v_and_b32_e32 v143, 0xffff0000, v203
	v_add_f32_e32 v212, v212, v142
	v_add_f32_e32 v213, v213, v143
	v_lshlrev_b32_e32 v214, 16, v196
	v_and_b32_e32 v215, 0xffff0000, v196
	v_lshlrev_b32_e32 v142, 16, v204
	v_and_b32_e32 v143, 0xffff0000, v204
	v_add_f32_e32 v214, v214, v142
	v_add_f32_e32 v215, v215, v143
	v_lshlrev_b32_e32 v216, 16, v197
	v_and_b32_e32 v217, 0xffff0000, v197
	v_lshlrev_b32_e32 v142, 16, v205
	v_and_b32_e32 v143, 0xffff0000, v205
	v_add_f32_e32 v216, v216, v142
	v_add_f32_e32 v217, v217, v143
	v_lshlrev_b32_e32 v218, 16, v198
	v_and_b32_e32 v219, 0xffff0000, v198
	v_lshlrev_b32_e32 v142, 16, v206
	v_and_b32_e32 v143, 0xffff0000, v206
	v_add_f32_e32 v218, v218, v142
	v_add_f32_e32 v219, v219, v143
	v_lshlrev_b32_e32 v220, 16, v199
	v_and_b32_e32 v221, 0xffff0000, v199
	v_lshlrev_b32_e32 v142, 16, v207
	v_and_b32_e32 v143, 0xffff0000, v207
	v_add_f32_e32 v220, v220, v142
	v_add_f32_e32 v221, v221, v143
	v_lshlrev_b32_e32 v222, 16, v200
	v_and_b32_e32 v223, 0xffff0000, v200
	v_lshlrev_b32_e32 v142, 16, v208
	v_and_b32_e32 v143, 0xffff0000, v208
	v_add_f32_e32 v222, v222, v142
	v_add_f32_e32 v223, v223, v143
	v_lshlrev_b32_e32 v224, 16, v201
	v_and_b32_e32 v225, 0xffff0000, v201
	v_lshlrev_b32_e32 v142, 16, v209
	v_and_b32_e32 v143, 0xffff0000, v209
	v_add_f32_e32 v224, v224, v142
; #define TR4(p_) __builtin_amdgcn_ds_read_tr4_b64_v2i32((LAS v2i*)(p_))
; #define VDMA(st_, k_) do { _Pragma("unroll") for (int i_ = 0; i_ < 4; ++i_) { \
;         const unsigned off_ = (unsigned)((st_) >> 2) * (16384u * 128u) + (PE_ID(E, 4 * ((st_) & 3) + i_) << 7) + ((i_ & 1) ? cx1 : cx0); \
;         __builtin_amdgcn_global_load_lds((const unsigned*)(V4 + off_), (LAS unsigned*)(ldsb + BUF[k_] + 1024 * i_), 16, 0, 0); } } while (0)
; __device__ __forceinline__ void peer_v_tokens(int j, const LAS unsigned short* EL, const LAS unsigned char* AL  , const LAS float* ASC  , const LAS int* SAL  , ...
;     ...
;         for (int st = 0; st < 16; ++st) {
;             const int p = st >> 2, q = st & 3;
;             if (st < 14) VDMA(st + 2, (st + 2) % 3);
;             if (st < 14) asm volatile("s_waitcnt vmcnt(8)" ::: "memory");
;             else if (st == 14) asm volatile("s_waitcnt vmcnt(4)" ::: "memory");
;             else asm volatile("s_waitcnt vmcnt(0)" ::: "memory");
;             if (q == 0) {
; #pragma unroll
;                 for (int r = 0; r < 4; ++r) { accH[r] = 0; accL[r] = 0; } }
; #pragma unroll
;             for (int tp = 0; tp < 2; ++tp) {
;                 const v2i ao = TR4(ATL + (2 * q + tp) * 128 + 8 * s16), ah = TR4(ATL + 1024 + (2 * q + tp) * 128 + 8 * s16);
; #pragma unroll
;                 for (int r = 0; r < 4; ++r) {
;                     const v2i d = TR4(ldsb + BUF[st % 3] + 2048 * tp + roff[r]);
;                     accH[r] = __builtin_amdgcn_sdot8(d.x, ah.x, accH[r], false); accH[r] = __builtin_amdgcn_sdot8(d.y, ah.y, accH[r], false);
;                     accL[r] = __builtin_amdgcn_sdot8(d.x, ao.x, accL[r], false); accL[r] = __builtin_amdgcn_sdot8(d.y, ao.y, accL[r], false);
;                 }
;             }
;             asm volatile("s_waitcnt lgkmcnt(0)" ::: "memory");
;     ...
;                 ss += v[jq].x * v[jq].x + v[jq].y * v[jq].y + v[jq].z * v[jq].z + v[jq].w * v[jq].w; }
;             ss = wave_sum(ss);
;             const float r3 = rsqrtf(ss * (1.f / D) + EPS);
	v_add_f32_e32 v225, v225, v143
	v_mov_b32_e32 v144, 0
	v_mul_f32_e32 v145, v210, v210
	v_fmac_f32_e32 v145, v211, v211
	v_fmac_f32_e32 v145, v212, v212
	v_fmac_f32_e32 v145, v213, v213
	v_add_f32_e32 v144, v144, v145
	v_mul_f32_e32 v145, v214, v214
	v_fmac_f32_e32 v145, v215, v215
	v_fmac_f32_e32 v145, v216, v216
	v_fmac_f32_e32 v145, v217, v217
	v_add_f32_e32 v144, v144, v145
	v_mul_f32_e32 v145, v218, v218
	v_fmac_f32_e32 v145, v219, v219
	v_fmac_f32_e32 v145, v220, v220
	v_fmac_f32_e32 v145, v221, v221
	v_add_f32_e32 v144, v144, v145
	v_mul_f32_e32 v145, v222, v222
	v_fmac_f32_e32 v145, v223, v223
	v_fmac_f32_e32 v145, v224, v224
	v_fmac_f32_e32 v145, v225, v225
	v_add_f32_e32 v144, v144, v145
	s_nop 1
	v_add_f32_dpp v144, v144, v144 quad_perm:[1,0,3,2] row_mask:0xf bank_mask:0xf bound_ctrl:1
	s_nop 1
	v_add_f32_dpp v144, v144, v144 quad_perm:[2,3,0,1] row_mask:0xf bank_mask:0xf bound_ctrl:1
	s_nop 1
	v_add_f32_dpp v144, v144, v144 row_half_mirror row_mask:0xf bank_mask:0xf bound_ctrl:1
	s_nop 1
	v_add_f32_dpp v144, v144, v144 row_mirror row_mask:0xf bank_mask:0xf bound_ctrl:1
	s_nop 1
	v_readlane_b32 s10, v144, 0
	v_readlane_b32 s11, v144, 16
	v_readlane_b32 s14, v144, 32
	v_readlane_b32 s15, v144, 48
	s_nop 3
	v_mov_b32_e32 v144, s11
	v_mov_b32_e32 v145, s15
	v_add_f32_e32 v144, s10, v144
	v_add_f32_e32 v145, s14, v145
	v_add_f32_e32 v144, v144, v145
	v_fmamk_f32 v144, v144, 0x3a800000, v111
	v_rsq_f32_e32 v144, v144
	s_nop 0
	v_mul_f32_e32 v210, v210, v144
	v_mul_f32_e32 v211, v211, v144
	v_mul_f32_e32 v212, v212, v144
	v_mul_f32_e32 v213, v213, v144
	v_mul_f32_e32 v214, v214, v144
	v_mul_f32_e32 v215, v215, v144
	v_mul_f32_e32 v216, v216, v144
	v_mul_f32_e32 v217, v217, v144
	v_mul_f32_e32 v218, v218, v144
	v_mul_f32_e32 v219, v219, v144
	v_mul_f32_e32 v220, v220, v144
	v_mul_f32_e32 v221, v221, v144
	v_mul_f32_e32 v222, v222, v144
	v_mul_f32_e32 v223, v223, v144
	v_mul_f32_e32 v224, v224, v144
	v_mul_f32_e32 v225, v225, v144
	v_dot8c_i32_i4_e32 v38, v122, v48
	v_dot8c_i32_i4_e32 v39, v122, v46
	v_dot8c_i32_i4_e32 v40, v124, v48
	v_dot8c_i32_i4_e32 v41, v124, v46
	v_dot8c_i32_i4_e32 v42, v126, v48
	v_dot8c_i32_i4_e32 v43, v126, v46
	v_dot8c_i32_i4_e32 v44, v128, v48
	v_dot8c_i32_i4_e32 v45, v128, v46
	v_dot8c_i32_i4_e32 v38, v123, v49
	v_dot8c_i32_i4_e32 v39, v123, v47
	v_dot8c_i32_i4_e32 v40, v125, v49
	v_dot8c_i32_i4_e32 v41, v125, v47
	v_dot8c_i32_i4_e32 v42, v127, v49
	v_dot8c_i32_i4_e32 v43, v127, v47
	v_dot8c_i32_i4_e32 v44, v129, v49
	v_dot8c_i32_i4_e32 v45, v129, v47
	v_and_b32_e32 v78, 0xffff, v32
	v_lshrrev_b32_e32 v79, 16, v32
	v_lshl_add_u32 v78, v78, 7, v150
	v_lshl_add_u32 v79, v79, 7, v151
	s_mov_b32 m0, s98
	s_add_i32 s43, s98, 0x400
	global_load_lds_dwordx4 v78, s[50:51]
	s_mov_b32 m0, s43
	s_nop 0
	global_load_lds_dwordx4 v79, s[50:51]
	s_waitcnt vmcnt(8)
	v_add_u32_e32 v54, s76, v59
	v_add_u32_e32 v55, s76, v60
	v_add_u32_e32 v56, s76, v61
	v_add_u32_e32 v57, s76, v62
	ds_read_b64_tr_b4 v[46:47], v160 offset:256
	ds_read_b64_tr_b4 v[48:49], v160 offset:1280
	ds_read_b64_tr_b4 v[122:123], v54
	ds_read_b64_tr_b4 v[124:125], v55
	ds_read_b64_tr_b4 v[126:127], v56
	ds_read_b64_tr_b4 v[128:129], v57
	s_waitcnt lgkmcnt(6)
	v_dot8c_i32_i4_e32 v38, v130, v52
	v_dot8c_i32_i4_e32 v39, v130, v50
	v_dot8c_i32_i4_e32 v40, v132, v52
	v_dot8c_i32_i4_e32 v41, v132, v50
	v_dot8c_i32_i4_e32 v42, v134, v52
	v_dot8c_i32_i4_e32 v43, v134, v50
	v_dot8c_i32_i4_e32 v44, v136, v52
	v_dot8c_i32_i4_e32 v45, v136, v50
	v_dot8c_i32_i4_e32 v38, v131, v53
	v_dot8c_i32_i4_e32 v39, v131, v51
	v_dot8c_i32_i4_e32 v40, v133, v53
	v_dot8c_i32_i4_e32 v41, v133, v51
	v_dot8c_i32_i4_e32 v42, v135, v53
	v_dot8c_i32_i4_e32 v43, v135, v51
	v_dot8c_i32_i4_e32 v44, v137, v53
	v_dot8c_i32_i4_e32 v45, v137, v51
	v_and_b32_e32 v78, 0xffff, v33
	v_lshrrev_b32_e32 v79, 16, v33
	v_lshl_add_u32 v78, v78, 7, v150
	v_lshl_add_u32 v79, v79, 7, v151
	s_mov_b32 m0, s99
	s_add_i32 s43, s99, 0x400
	global_load_lds_dwordx4 v78, s[50:51]
	s_mov_b32 m0, s43
	s_nop 0
	global_load_lds_dwordx4 v79, s[50:51]
	s_waitcnt vmcnt(8)
	v_add_u32_e32 v54, s77, v59
	v_add_u32_e32 v55, s77, v60
	v_add_u32_e32 v56, s77, v61
	v_add_u32_e32 v57, s77, v62
	ds_read_b64_tr_b4 v[50:51], v160 offset:384
	ds_read_b64_tr_b4 v[52:53], v160 offset:1408
	ds_read_b64_tr_b4 v[130:131], v54
	ds_read_b64_tr_b4 v[132:133], v55
	ds_read_b64_tr_b4 v[134:135], v56
	ds_read_b64_tr_b4 v[136:137], v57
	s_waitcnt lgkmcnt(6)
	v_dot8c_i32_i4_e32 v38, v122, v48
	v_dot8c_i32_i4_e32 v39, v122, v46
	v_dot8c_i32_i4_e32 v40, v124, v48
	v_dot8c_i32_i4_e32 v41, v124, v46
	v_dot8c_i32_i4_e32 v42, v126, v48
	v_dot8c_i32_i4_e32 v43, v126, v46
	v_dot8c_i32_i4_e32 v44, v128, v48
	v_dot8c_i32_i4_e32 v45, v128, v46
	v_dot8c_i32_i4_e32 v38, v123, v49
	v_dot8c_i32_i4_e32 v39, v123, v47
	v_dot8c_i32_i4_e32 v40, v125, v49
	v_dot8c_i32_i4_e32 v41, v125, v47
	v_dot8c_i32_i4_e32 v42, v127, v49
	v_dot8c_i32_i4_e32 v43, v127, v47
	v_dot8c_i32_i4_e32 v44, v129, v49
	v_dot8c_i32_i4_e32 v45, v129, v47
	s_waitcnt lgkmcnt(15)
	v_and_b32_e32 v78, 0xffff, v18
	v_lshrrev_b32_e32 v79, 16, v18
	v_lshl_add_u32 v78, v78, 7, v152
	v_lshl_add_u32 v79, v79, 7, v153
	s_mov_b32 m0, s76
	s_add_i32 s43, s76, 0x400
	global_load_lds_dwordx4 v78, s[50:51]
	s_mov_b32 m0, s43
	s_nop 0
	global_load_lds_dwordx4 v79, s[50:51]
	s_waitcnt vmcnt(8)
	v_add_u32_e32 v54, s78, v59
	v_add_u32_e32 v55, s78, v60
	v_add_u32_e32 v56, s78, v61
	v_add_u32_e32 v57, s78, v62
	ds_read_b64_tr_b4 v[46:47], v160 offset:512
	ds_read_b64_tr_b4 v[48:49], v160 offset:1536
	ds_read_b64_tr_b4 v[122:123], v54
	ds_read_b64_tr_b4 v[124:125], v55
	ds_read_b64_tr_b4 v[126:127], v56
	ds_read_b64_tr_b4 v[128:129], v57
	s_waitcnt lgkmcnt(6)
; #define LAS __attribute__((address_space(3)))
; #define TR4(p_) __builtin_amdgcn_ds_read_tr4_b64_v2i32((LAS v2i*)(p_))
; __device__ __forceinline__ void peer_v_tokens(int j, const LAS unsigned short* EL, const LAS unsigned char* AL  , const LAS float* ASC  , const LAS int* SAL  , ...
;     ...
; #pragma unroll
;         for (int m = 0; m < 2; ++m) {
;             const int idx = lane + 64 * m, tau = idx >> 4, sr = idx & 15, k = 16 * (sr & 7) + 2 * tau + (sr >> 3);
;             const int aq = (int)*(const LAS signed char*)(AL + tl * 128 + k); const int tq = aq + 8;
;             const unsigned lo = (((unsigned)tq & 15u) ^ 8u) * 0x11111111u, hi = ((unsigned)(tq >> 4) & 15u) * 0x11111111u;
;             typedef unsigned u2v __attribute__((ext_vector_type(2)));
;             u2v l2; l2.x = lo; l2.y = lo; u2v h2; h2.x = hi; h2.y = hi;
;             *(LAS u2v*)(ATL + 8 * idx) = l2; *(LAS u2v*)(ATL + 1024 + 8 * idx) = h2;
;         }
;     ...
;         for (int st = 0; st < 16; ++st) {
;             const int p = st >> 2, q = st & 3;
;             if (st < 14) VDMA(st + 2, (st + 2) % 3);
;             if (st < 14) asm volatile("s_waitcnt vmcnt(8)" ::: "memory");
;             else if (st == 14) asm volatile("s_waitcnt vmcnt(4)" ::: "memory");
;             else asm volatile("s_waitcnt vmcnt(0)" ::: "memory");
;             if (q == 0) {
; #pragma unroll
;                 for (int r = 0; r < 4; ++r) { accH[r] = 0; accL[r] = 0; } }
; #pragma unroll
;             for (int tp = 0; tp < 2; ++tp) {
;                 const v2i ao = TR4(ATL + (2 * q + tp) * 128 + 8 * s16), ah = TR4(ATL + 1024 + (2 * q + tp) * 128 + 8 * s16);
; #pragma unroll
;                 for (int r = 0; r < 4; ++r) {
;                     const v2i d = TR4(ldsb + BUF[st % 3] + 2048 * tp + roff[r]);
;                     accH[r] = __builtin_amdgcn_sdot8(d.x, ah.x, accH[r], false); accH[r] = __builtin_amdgcn_sdot8(d.y, ah.y, accH[r], false);
;                     accL[r] = __builtin_amdgcn_sdot8(d.x, ao.x, accL[r], false); accL[r] = __builtin_amdgcn_sdot8(d.y, ao.y, accL[r], false);
;                 }
;             }
;             asm volatile("s_waitcnt lgkmcnt(0)" ::: "memory");
	v_dot8c_i32_i4_e32 v38, v130, v52
	v_dot8c_i32_i4_e32 v39, v130, v50
	v_dot8c_i32_i4_e32 v40, v132, v52
	v_dot8c_i32_i4_e32 v41, v132, v50
	v_dot8c_i32_i4_e32 v42, v134, v52
	v_dot8c_i32_i4_e32 v43, v134, v50
	v_dot8c_i32_i4_e32 v44, v136, v52
	v_dot8c_i32_i4_e32 v45, v136, v50
	v_dot8c_i32_i4_e32 v38, v131, v53
	v_dot8c_i32_i4_e32 v39, v131, v51
	v_dot8c_i32_i4_e32 v40, v133, v53
	v_dot8c_i32_i4_e32 v41, v133, v51
	v_dot8c_i32_i4_e32 v42, v135, v53
	v_dot8c_i32_i4_e32 v43, v135, v51
	v_dot8c_i32_i4_e32 v44, v137, v53
	v_dot8c_i32_i4_e32 v45, v137, v51
	v_and_b32_e32 v78, 0xffff, v19
	v_lshrrev_b32_e32 v79, 16, v19
	v_lshl_add_u32 v78, v78, 7, v152
	v_lshl_add_u32 v79, v79, 7, v153
	s_mov_b32 m0, s77
	s_add_i32 s43, s77, 0x400
	global_load_lds_dwordx4 v78, s[50:51]
	s_mov_b32 m0, s43
	s_nop 0
	global_load_lds_dwordx4 v79, s[50:51]
	s_waitcnt vmcnt(8)
	v_add_u32_e32 v54, s79, v59
	v_add_u32_e32 v55, s79, v60
	v_add_u32_e32 v56, s79, v61
	v_add_u32_e32 v57, s79, v62
	ds_read_b64_tr_b4 v[50:51], v160 offset:640
	ds_read_b64_tr_b4 v[52:53], v160 offset:1664
	ds_read_b64_tr_b4 v[130:131], v54
	ds_read_b64_tr_b4 v[132:133], v55
	ds_read_b64_tr_b4 v[134:135], v56
	ds_read_b64_tr_b4 v[136:137], v57
	s_waitcnt lgkmcnt(6)
	v_dot8c_i32_i4_e32 v38, v122, v48
	v_dot8c_i32_i4_e32 v39, v122, v46
	v_dot8c_i32_i4_e32 v40, v124, v48
	v_dot8c_i32_i4_e32 v41, v124, v46
	v_dot8c_i32_i4_e32 v42, v126, v48
	v_dot8c_i32_i4_e32 v43, v126, v46
	v_dot8c_i32_i4_e32 v44, v128, v48
	v_dot8c_i32_i4_e32 v45, v128, v46
	v_dot8c_i32_i4_e32 v38, v123, v49
	v_dot8c_i32_i4_e32 v39, v123, v47
	v_dot8c_i32_i4_e32 v40, v125, v49
	v_dot8c_i32_i4_e32 v41, v125, v47
	v_dot8c_i32_i4_e32 v42, v127, v49
	v_dot8c_i32_i4_e32 v43, v127, v47
	v_dot8c_i32_i4_e32 v44, v129, v49
	v_dot8c_i32_i4_e32 v45, v129, v47
	s_waitcnt lgkmcnt(15)
	v_add_u32_e32 v143, 8, v139
	v_and_b32_e32 v142, 15, v143
	v_xor_b32_e32 v142, 8, v142
	v_bfe_u32 v144, v143, 4, 4
	v_mul_lo_u32 v142, v142, s92
	v_mul_lo_u32 v144, v144, s92
	v_mov_b32_e32 v143, v142
	v_mov_b32_e32 v145, v144
	ds_write2st64_b64 v159, v[142:143], v[144:145] offset1:2
	v_and_b32_e32 v78, 0xffff, v20
	v_lshrrev_b32_e32 v79, 16, v20
	v_lshl_add_u32 v78, v78, 7, v152
	v_lshl_add_u32 v79, v79, 7, v153
	s_mov_b32 m0, s78
	s_add_i32 s43, s78, 0x400
	global_load_lds_dwordx4 v78, s[50:51]
	s_mov_b32 m0, s43
	s_nop 0
	global_load_lds_dwordx4 v79, s[50:51]
	s_waitcnt vmcnt(8)
	v_add_u32_e32 v54, s98, v59
	v_add_u32_e32 v55, s98, v60
	v_add_u32_e32 v56, s98, v61
	v_add_u32_e32 v57, s98, v62
	ds_read_b64_tr_b4 v[46:47], v160 offset:768
	ds_read_b64_tr_b4 v[48:49], v160 offset:1792
	ds_read_b64_tr_b4 v[122:123], v54
	ds_read_b64_tr_b4 v[124:125], v55
	ds_read_b64_tr_b4 v[126:127], v56
	ds_read_b64_tr_b4 v[128:129], v57
	s_waitcnt lgkmcnt(7)
	v_dot8c_i32_i4_e32 v38, v130, v52
	v_dot8c_i32_i4_e32 v39, v130, v50
	v_dot8c_i32_i4_e32 v40, v132, v52
	v_dot8c_i32_i4_e32 v41, v132, v50
	v_dot8c_i32_i4_e32 v42, v134, v52
	v_dot8c_i32_i4_e32 v43, v134, v50
	v_dot8c_i32_i4_e32 v44, v136, v52
	v_dot8c_i32_i4_e32 v45, v136, v50
	v_dot8c_i32_i4_e32 v38, v131, v53
	v_dot8c_i32_i4_e32 v39, v131, v51
	v_dot8c_i32_i4_e32 v40, v133, v53
	v_dot8c_i32_i4_e32 v41, v133, v51
	v_dot8c_i32_i4_e32 v42, v135, v53
	v_dot8c_i32_i4_e32 v43, v135, v51
	v_dot8c_i32_i4_e32 v44, v137, v53
	v_dot8c_i32_i4_e32 v45, v137, v51
	v_and_b32_e32 v78, 0xffff, v21
	v_lshrrev_b32_e32 v79, 16, v21
	v_lshl_add_u32 v78, v78, 7, v152
	v_lshl_add_u32 v79, v79, 7, v153
	s_mov_b32 m0, s79
	s_add_i32 s43, s79, 0x400
	global_load_lds_dwordx4 v78, s[50:51]
	s_mov_b32 m0, s43
	s_nop 0
	global_load_lds_dwordx4 v79, s[50:51]
	s_waitcnt vmcnt(8)
	v_add_u32_e32 v54, s99, v59
	v_add_u32_e32 v55, s99, v60
	v_add_u32_e32 v56, s99, v61
	v_add_u32_e32 v57, s99, v62
	ds_read_b64_tr_b4 v[50:51], v160 offset:896
	ds_read_b64_tr_b4 v[52:53], v160 offset:1920
	ds_read_b64_tr_b4 v[130:131], v54
	ds_read_b64_tr_b4 v[132:133], v55
	ds_read_b64_tr_b4 v[134:135], v56
	ds_read_b64_tr_b4 v[136:137], v57
	s_waitcnt lgkmcnt(6)
	v_dot8c_i32_i4_e32 v38, v122, v48
	v_dot8c_i32_i4_e32 v39, v122, v46
	v_dot8c_i32_i4_e32 v40, v124, v48
	v_dot8c_i32_i4_e32 v41, v124, v46
	v_dot8c_i32_i4_e32 v42, v126, v48
	v_dot8c_i32_i4_e32 v43, v126, v46
	v_dot8c_i32_i4_e32 v44, v128, v48
	v_dot8c_i32_i4_e32 v45, v128, v46
	v_dot8c_i32_i4_e32 v38, v123, v49
	v_dot8c_i32_i4_e32 v39, v123, v47
	v_dot8c_i32_i4_e32 v40, v125, v49
	v_dot8c_i32_i4_e32 v41, v125, v47
	v_dot8c_i32_i4_e32 v42, v127, v49
	v_dot8c_i32_i4_e32 v43, v127, v47
	v_dot8c_i32_i4_e32 v44, v129, v49
	v_dot8c_i32_i4_e32 v45, v129, v47
	v_and_b32_e32 v78, 0xffff, v22
	v_lshrrev_b32_e32 v79, 16, v22
	v_lshl_add_u32 v78, v78, 7, v152
	v_lshl_add_u32 v79, v79, 7, v153
	s_mov_b32 m0, s98
	s_add_i32 s43, s98, 0x400
	global_load_lds_dwordx4 v78, s[50:51]
	s_mov_b32 m0, s43
	s_nop 0
	global_load_lds_dwordx4 v79, s[50:51]
	s_waitcnt vmcnt(8)
	v_add_u32_e32 v54, s76, v59
	v_add_u32_e32 v55, s76, v60
	v_add_u32_e32 v56, s76, v61
	v_add_u32_e32 v57, s76, v62
	ds_read_b64_tr_b4 v[46:47], v160
	ds_read_b64_tr_b4 v[48:49], v160 offset:1024
	ds_read_b64_tr_b4 v[122:123], v54
	ds_read_b64_tr_b4 v[124:125], v55
	ds_read_b64_tr_b4 v[126:127], v56
	ds_read_b64_tr_b4 v[128:129], v57
	s_waitcnt lgkmcnt(6)
	v_dot8c_i32_i4_e32 v38, v130, v52
	v_dot8c_i32_i4_e32 v39, v130, v50
	v_dot8c_i32_i4_e32 v40, v132, v52
	v_dot8c_i32_i4_e32 v41, v132, v50
	v_dot8c_i32_i4_e32 v42, v134, v52
	v_dot8c_i32_i4_e32 v43, v134, v50
	v_dot8c_i32_i4_e32 v44, v136, v52
	v_dot8c_i32_i4_e32 v45, v136, v50
	v_dot8c_i32_i4_e32 v38, v131, v53
	v_dot8c_i32_i4_e32 v39, v131, v51
	v_dot8c_i32_i4_e32 v40, v133, v53
	v_dot8c_i32_i4_e32 v41, v133, v51
	v_dot8c_i32_i4_e32 v42, v135, v53
	v_dot8c_i32_i4_e32 v43, v135, v51
	v_dot8c_i32_i4_e32 v44, v137, v53
	v_dot8c_i32_i4_e32 v45, v137, v51
	s_nop 3
	s_waitcnt lgkmcnt(15)
; __device__ __forceinline__ void peer_v_tokens(int j, const LAS unsigned short* EL, const LAS unsigned char* AL  , const LAS float* ASC  , const LAS int* SAL  , ...
;     ...
;     for (int it = 0; it < 8; ++it) {
;         const int tl = it * 8 + wave, t = j * 64 + tl;
;         unsigned E[8];
;         { const LAS v4u* ep = (const LAS v4u*)(EL + tl * 128 + 16 * g); const v4u e0 = ep[0], e1 = ep[1];
;           E[0] = e0.x; E[1] = e0.y; E[2] = e0.z; E[3] = e0.w; E[4] = e1.x; E[5] = e1.y; E[6] = e1.z; E[7] = e1.w; }
;         uint2 hv[4]; float4 gv[4];
;         { unsigned ho = (unsigned)t * (D / 4) + (unsigned)lane; asm volatile("" : "+v"(ho)); const uint2* hp = (const uint2*)HB + ho; const float4* gp = (const float4*)fng + lane;
; #pragma unroll
;           for (int jq = 0; jq < 4; ++jq) { hv[jq] = hp[64 * jq]; gv[jq] = gp[64 * jq]; } }
;         VDMA(0, 0); VDMA(1, 1);
; #pragma unroll
;         for (int m = 0; m < 2; ++m) {
;     ...
;         for (int st = 0; st < 16; ++st) {
;             const int p = st >> 2, q = st & 3;
;             if (st < 14) VDMA(st + 2, (st + 2) % 3);
;             if (st < 14) asm volatile("s_waitcnt vmcnt(8)" ::: "memory");
;             else if (st == 14) asm volatile("s_waitcnt vmcnt(4)" ::: "memory");
;             else asm volatile("s_waitcnt vmcnt(0)" ::: "memory");
;             if (q == 0) {
; #pragma unroll
;                 for (int r = 0; r < 4; ++r) { accH[r] = 0; accL[r] = 0; } }
; #pragma unroll
;             for (int tp = 0; tp < 2; ++tp) {
;                 const v2i ao = TR4(ATL + (2 * q + tp) * 128 + 8 * s16), ah = TR4(ATL + 1024 + (2 * q + tp) * 128 + 8 * s16);
; #pragma unroll
;                 for (int r = 0; r < 4; ++r) {
;                     const v2i d = TR4(ldsb + BUF[st % 3] + 2048 * tp + roff[r]);
;                     accH[r] = __builtin_amdgcn_sdot8(d.x, ah.x, accH[r], false); accH[r] = __builtin_amdgcn_sdot8(d.y, ah.y, accH[r], false);
;                     accL[r] = __builtin_amdgcn_sdot8(d.x, ao.x, accL[r], false); accL[r] = __builtin_amdgcn_sdot8(d.y, ao.y, accL[r], false);
;                 }
;             }
;             asm volatile("s_waitcnt lgkmcnt(0)" ::: "memory");
;             if (q == 3) {
; #pragma unroll
;                 for (int r = 0; r < 4; ++r) STASH[256 * p + 16 * (grp + 4 * r) + pc] = f2bf(asc * (float)(2 * ((accH[r] << 4) + accL[r]) + sa));
;             }
;         }
	v_lshlrev_b32_e32 v38, 5, v38
	v_lshlrev_b32_e32 v39, 1, v39
	v_add3_u32 v38, v39, v229, v38
	v_cvt_f32_i32_e32 v38, v38
	v_mul_f32_e32 v38, v228, v38
	v_lshlrev_b32_e32 v40, 5, v40
	v_lshlrev_b32_e32 v41, 1, v41
	v_add3_u32 v40, v41, v229, v40
	v_cvt_f32_i32_e32 v40, v40
	v_mul_f32_e32 v40, v228, v40
	v_lshlrev_b32_e32 v42, 5, v42
	v_lshlrev_b32_e32 v43, 1, v43
	v_add3_u32 v42, v43, v229, v42
	v_cvt_f32_i32_e32 v42, v42
	v_mul_f32_e32 v42, v228, v42
	v_lshlrev_b32_e32 v44, 5, v44
	v_lshlrev_b32_e32 v45, 1, v45
	v_add3_u32 v44, v45, v229, v44
	v_cvt_f32_i32_e32 v44, v44
	v_mul_f32_e32 v44, v228, v44
	v_cvt_pk_bf16_f32 v170, v38, v40
	v_cvt_pk_bf16_f32 v171, v42, v44
	ds_read_b128 v[252:255], v155
	s_add_i32 s44, s40, 16
	s_ashr_i32 s45, s44, 31
	s_lshl_b64 s[44:45], s[44:45], 12
	v_lshl_add_u64 v[80:81], v[36:37], 0, s[44:45]
	s_waitcnt lgkmcnt(0)
	v_mul_f32_e32 v210, v210, v252
	v_mul_f32_e32 v211, v211, v253
	v_mul_f32_e32 v212, v212, v254
	v_mul_f32_e32 v213, v213, v255
	global_store_dwordx4 v[80:81], v[210:213], off nt
	s_add_i32 s43, s40, 24
	s_lshl_b32 s43, s43, 11
	v_add_u32_e32 v138, s43, v66
	global_load_dwordx2 v[194:195], v138, s[70:71]
	global_load_dwordx2 v[196:197], v138, s[70:71] offset:512
	global_load_dwordx2 v[198:199], v138, s[70:71] offset:1024
	global_load_dwordx2 v[200:201], v138, s[70:71] offset:1536
	v_add_u32_e32 v147, 8, v140
	v_and_b32_e32 v146, 15, v147
	v_xor_b32_e32 v146, 8, v146
	v_bfe_u32 v148, v147, 4, 4
	v_mul_lo_u32 v146, v146, s92
	v_mul_lo_u32 v148, v148, s92
	v_mov_b32_e32 v147, v146
	v_mov_b32_e32 v149, v148
	ds_write2st64_b64 v77, v[146:147], v[148:149] offset1:2
	v_add_u32_e32 v138, 0x1400, v74
	ds_read_u8 v139, v138
	v_add_u32_e32 v141, 0x1400, v73
	ds_read_u8 v140, v141
	s_add_i32 s43, s67, 128
	v_mov_b32_e32 v138, s43
	ds_read2st64_b32 v[228:229], v138 offset1:1
	ds_read_b128 v[26:29], v227 offset:10240
	ds_read_b128 v[30:33], v227 offset:10256
	v_mov_b32_e32 v38, 0
	v_mov_b32_e32 v39, 0
	v_mov_b32_e32 v40, 0
	v_mov_b32_e32 v41, 0
	v_mov_b32_e32 v42, 0
	v_mov_b32_e32 v43, 0
	v_mov_b32_e32 v44, 0
	v_mov_b32_e32 v45, 0
	v_and_b32_e32 v78, 0xffff, v23
	v_lshrrev_b32_e32 v79, 16, v23
	v_lshl_add_u32 v78, v78, 7, v152
	v_lshl_add_u32 v79, v79, 7, v153
	s_mov_b32 m0, s99
	s_add_i32 s43, s99, 0x400
	global_load_lds_dwordx4 v78, s[50:51]
	s_mov_b32 m0, s43
	s_nop 0
	global_load_lds_dwordx4 v79, s[50:51]
	s_waitcnt vmcnt(13)
	v_add_u32_e32 v54, s77, v59
	v_add_u32_e32 v55, s77, v60
	v_add_u32_e32 v56, s77, v61
	v_add_u32_e32 v57, s77, v62
	ds_read_b64_tr_b4 v[50:51], v160 offset:128
	ds_read_b64_tr_b4 v[52:53], v160 offset:1152
	ds_read_b64_tr_b4 v[130:131], v54
	ds_read_b64_tr_b4 v[132:133], v55
	ds_read_b64_tr_b4 v[134:135], v56
	ds_read_b64_tr_b4 v[136:137], v57
	s_waitcnt lgkmcnt(13)
	v_dot8c_i32_i4_e32 v38, v122, v48
	v_dot8c_i32_i4_e32 v39, v122, v46
	v_dot8c_i32_i4_e32 v40, v124, v48
	v_dot8c_i32_i4_e32 v41, v124, v46
	v_dot8c_i32_i4_e32 v42, v126, v48
	v_dot8c_i32_i4_e32 v43, v126, v46
	v_dot8c_i32_i4_e32 v44, v128, v48
	v_dot8c_i32_i4_e32 v45, v128, v46
	v_dot8c_i32_i4_e32 v38, v123, v49
	v_dot8c_i32_i4_e32 v39, v123, v47
	v_dot8c_i32_i4_e32 v40, v125, v49
	v_dot8c_i32_i4_e32 v41, v125, v47
	v_dot8c_i32_i4_e32 v42, v127, v49
	v_dot8c_i32_i4_e32 v43, v127, v47
	v_dot8c_i32_i4_e32 v44, v129, v49
	v_dot8c_i32_i4_e32 v45, v129, v47
	v_and_b32_e32 v78, 0xffff, v24
	v_lshrrev_b32_e32 v79, 16, v24
	v_lshl_add_u32 v78, v78, 7, v152
	v_lshl_add_u32 v79, v79, 7, v153
	s_mov_b32 m0, s76
	s_add_i32 s43, s76, 0x400
	global_load_lds_dwordx4 v78, s[50:51]
	s_mov_b32 m0, s43
	s_nop 0
	global_load_lds_dwordx4 v79, s[50:51]
	s_waitcnt vmcnt(13)
	v_add_u32_e32 v54, s78, v59
	v_add_u32_e32 v55, s78, v60
	v_add_u32_e32 v56, s78, v61
	v_add_u32_e32 v57, s78, v62
	ds_read_b64_tr_b4 v[46:47], v160 offset:256
	ds_read_b64_tr_b4 v[48:49], v160 offset:1280
	ds_read_b64_tr_b4 v[122:123], v54
	ds_read_b64_tr_b4 v[124:125], v55
	ds_read_b64_tr_b4 v[126:127], v56
	ds_read_b64_tr_b4 v[128:129], v57
	s_waitcnt lgkmcnt(6)
	v_dot8c_i32_i4_e32 v38, v130, v52
	v_dot8c_i32_i4_e32 v39, v130, v50
	v_dot8c_i32_i4_e32 v40, v132, v52
	v_dot8c_i32_i4_e32 v41, v132, v50
	v_dot8c_i32_i4_e32 v42, v134, v52
	v_dot8c_i32_i4_e32 v43, v134, v50
	v_dot8c_i32_i4_e32 v44, v136, v52
	v_dot8c_i32_i4_e32 v45, v136, v50
	v_dot8c_i32_i4_e32 v38, v131, v53
	v_dot8c_i32_i4_e32 v39, v131, v51
	v_dot8c_i32_i4_e32 v40, v133, v53
	v_dot8c_i32_i4_e32 v41, v133, v51
	v_dot8c_i32_i4_e32 v42, v135, v53
	v_dot8c_i32_i4_e32 v43, v135, v51
	v_dot8c_i32_i4_e32 v44, v137, v53
	v_dot8c_i32_i4_e32 v45, v137, v51
	v_and_b32_e32 v78, 0xffff, v25
	v_lshrrev_b32_e32 v79, 16, v25
	v_lshl_add_u32 v78, v78, 7, v152
	v_lshl_add_u32 v79, v79, 7, v153
	s_mov_b32 m0, s77
	s_add_i32 s43, s77, 0x400
	global_load_lds_dwordx4 v78, s[50:51]
	s_mov_b32 m0, s43
	s_nop 0
	global_load_lds_dwordx4 v79, s[50:51]
	s_waitcnt vmcnt(13)
	v_add_u32_e32 v54, s79, v59
	v_add_u32_e32 v55, s79, v60
	v_add_u32_e32 v56, s79, v61
	v_add_u32_e32 v57, s79, v62
	ds_read_b64_tr_b4 v[50:51], v160 offset:384
	ds_read_b64_tr_b4 v[52:53], v160 offset:1408
	ds_read_b64_tr_b4 v[130:131], v54
	ds_read_b64_tr_b4 v[132:133], v55
	ds_read_b64_tr_b4 v[134:135], v56
	ds_read_b64_tr_b4 v[136:137], v57
	s_waitcnt lgkmcnt(6)
	v_dot8c_i32_i4_e32 v38, v122, v48
	v_dot8c_i32_i4_e32 v39, v122, v46
	v_dot8c_i32_i4_e32 v40, v124, v48
	v_dot8c_i32_i4_e32 v41, v124, v46
	v_dot8c_i32_i4_e32 v42, v126, v48
	v_dot8c_i32_i4_e32 v43, v126, v46
	v_dot8c_i32_i4_e32 v44, v128, v48
	v_dot8c_i32_i4_e32 v45, v128, v46
	v_dot8c_i32_i4_e32 v38, v123, v49
	v_dot8c_i32_i4_e32 v39, v123, v47
	v_dot8c_i32_i4_e32 v40, v125, v49
	v_dot8c_i32_i4_e32 v41, v125, v47
	v_dot8c_i32_i4_e32 v42, v127, v49
	v_dot8c_i32_i4_e32 v43, v127, v47
	v_dot8c_i32_i4_e32 v44, v129, v49
	v_dot8c_i32_i4_e32 v45, v129, v47
	s_waitcnt lgkmcnt(15)
; #define TR4(p_) __builtin_amdgcn_ds_read_tr4_b64_v2i32((LAS v2i*)(p_))
; #define VDMA(st_, k_) do { _Pragma("unroll") for (int i_ = 0; i_ < 4; ++i_) { \
;         const unsigned off_ = (unsigned)((st_) >> 2) * (16384u * 128u) + (PE_ID(E, 4 * ((st_) & 3) + i_) << 7) + ((i_ & 1) ? cx1 : cx0); \
;         __builtin_amdgcn_global_load_lds((const unsigned*)(V4 + off_), (LAS unsigned*)(ldsb + BUF[k_] + 1024 * i_), 16, 0, 0); } } while (0)
; __device__ __forceinline__ void peer_v_tokens(int j, const LAS unsigned short* EL, const LAS unsigned char* AL  , const LAS float* ASC  , const LAS int* SAL  , ...
;     ...
;         for (int st = 0; st < 16; ++st) {
;             const int p = st >> 2, q = st & 3;
;             if (st < 14) VDMA(st + 2, (st + 2) % 3);
;             if (st < 14) asm volatile("s_waitcnt vmcnt(8)" ::: "memory");
;             else if (st == 14) asm volatile("s_waitcnt vmcnt(4)" ::: "memory");
;             else asm volatile("s_waitcnt vmcnt(0)" ::: "memory");
;             if (q == 0) {
; #pragma unroll
;                 for (int r = 0; r < 4; ++r) { accH[r] = 0; accL[r] = 0; } }
; #pragma unroll
;             for (int tp = 0; tp < 2; ++tp) {
;                 const v2i ao = TR4(ATL + (2 * q + tp) * 128 + 8 * s16), ah = TR4(ATL + 1024 + (2 * q + tp) * 128 + 8 * s16);
; #pragma unroll
;                 for (int r = 0; r < 4; ++r) {
;                     const v2i d = TR4(ldsb + BUF[st % 3] + 2048 * tp + roff[r]);
;                     accH[r] = __builtin_amdgcn_sdot8(d.x, ah.x, accH[r], false); accH[r] = __builtin_amdgcn_sdot8(d.y, ah.y, accH[r], false);
;                     accL[r] = __builtin_amdgcn_sdot8(d.x, ao.x, accL[r], false); accL[r] = __builtin_amdgcn_sdot8(d.y, ao.y, accL[r], false);
;                 }
;             }
;             asm volatile("s_waitcnt lgkmcnt(0)" ::: "memory");
	v_and_b32_e32 v78, 0xffff, v26
	v_lshrrev_b32_e32 v79, 16, v26
	v_lshl_add_u32 v78, v78, 7, v152
	v_lshl_add_u32 v79, v79, 7, v153
	s_mov_b32 m0, s78
	s_add_i32 s43, s78, 0x400
	global_load_lds_dwordx4 v78, s[50:51]
	s_mov_b32 m0, s43
	s_nop 0
	global_load_lds_dwordx4 v79, s[50:51]
	s_waitcnt vmcnt(13)
	v_add_u32_e32 v54, s98, v59
	v_add_u32_e32 v55, s98, v60
	v_add_u32_e32 v56, s98, v61
	v_add_u32_e32 v57, s98, v62
	ds_read_b64_tr_b4 v[46:47], v160 offset:512
	ds_read_b64_tr_b4 v[48:49], v160 offset:1536
	ds_read_b64_tr_b4 v[122:123], v54
	ds_read_b64_tr_b4 v[124:125], v55
	ds_read_b64_tr_b4 v[126:127], v56
	ds_read_b64_tr_b4 v[128:129], v57
	s_waitcnt lgkmcnt(6)
	v_dot8c_i32_i4_e32 v38, v130, v52
	v_dot8c_i32_i4_e32 v39, v130, v50
	v_dot8c_i32_i4_e32 v40, v132, v52
	v_dot8c_i32_i4_e32 v41, v132, v50
	v_dot8c_i32_i4_e32 v42, v134, v52
	v_dot8c_i32_i4_e32 v43, v134, v50
	v_dot8c_i32_i4_e32 v44, v136, v52
	v_dot8c_i32_i4_e32 v45, v136, v50
	v_dot8c_i32_i4_e32 v38, v131, v53
	v_dot8c_i32_i4_e32 v39, v131, v51
	v_dot8c_i32_i4_e32 v40, v133, v53
	v_dot8c_i32_i4_e32 v41, v133, v51
	v_dot8c_i32_i4_e32 v42, v135, v53
	v_dot8c_i32_i4_e32 v43, v135, v51
	v_dot8c_i32_i4_e32 v44, v137, v53
	v_dot8c_i32_i4_e32 v45, v137, v51
	v_and_b32_e32 v78, 0xffff, v27
	v_lshrrev_b32_e32 v79, 16, v27
	v_lshl_add_u32 v78, v78, 7, v152
	v_lshl_add_u32 v79, v79, 7, v153
	s_mov_b32 m0, s79
	s_add_i32 s43, s79, 0x400
	global_load_lds_dwordx4 v78, s[50:51]
	s_mov_b32 m0, s43
	s_nop 0
	global_load_lds_dwordx4 v79, s[50:51]
	s_waitcnt vmcnt(8)
	v_add_u32_e32 v54, s99, v59
	v_add_u32_e32 v55, s99, v60
	v_add_u32_e32 v56, s99, v61
	v_add_u32_e32 v57, s99, v62
	ds_read_b64_tr_b4 v[50:51], v160 offset:640
	ds_read_b64_tr_b4 v[52:53], v160 offset:1664
	ds_read_b64_tr_b4 v[130:131], v54
	ds_read_b64_tr_b4 v[132:133], v55
	ds_read_b64_tr_b4 v[134:135], v56
	ds_read_b64_tr_b4 v[136:137], v57
	s_waitcnt lgkmcnt(6)
	v_dot8c_i32_i4_e32 v38, v122, v48
	v_dot8c_i32_i4_e32 v39, v122, v46
	v_dot8c_i32_i4_e32 v40, v124, v48
	v_dot8c_i32_i4_e32 v41, v124, v46
	v_dot8c_i32_i4_e32 v42, v126, v48
	v_dot8c_i32_i4_e32 v43, v126, v46
	v_dot8c_i32_i4_e32 v44, v128, v48
	v_dot8c_i32_i4_e32 v45, v128, v46
	v_dot8c_i32_i4_e32 v38, v123, v49
	v_dot8c_i32_i4_e32 v39, v123, v47
	v_dot8c_i32_i4_e32 v40, v125, v49
	v_dot8c_i32_i4_e32 v41, v125, v47
	v_dot8c_i32_i4_e32 v42, v127, v49
	v_dot8c_i32_i4_e32 v43, v127, v47
	v_dot8c_i32_i4_e32 v44, v129, v49
	v_dot8c_i32_i4_e32 v45, v129, v47
	s_waitcnt lgkmcnt(15)
	v_add_u32_e32 v143, 8, v139
	v_and_b32_e32 v142, 15, v143
	v_xor_b32_e32 v142, 8, v142
	v_bfe_u32 v144, v143, 4, 4
	v_mul_lo_u32 v142, v142, s92
	v_mul_lo_u32 v144, v144, s92
	v_mov_b32_e32 v143, v142
	v_mov_b32_e32 v145, v144
	ds_write2st64_b64 v159, v[142:143], v[144:145] offset1:2
	v_and_b32_e32 v78, 0xffff, v28
	v_lshrrev_b32_e32 v79, 16, v28
	v_lshl_add_u32 v78, v78, 7, v152
	v_lshl_add_u32 v79, v79, 7, v153
	s_mov_b32 m0, s98
	s_add_i32 s43, s98, 0x400
	global_load_lds_dwordx4 v78, s[50:51]
	s_mov_b32 m0, s43
	s_nop 0
	global_load_lds_dwordx4 v79, s[50:51]
	s_waitcnt vmcnt(8)
	v_add_u32_e32 v54, s76, v59
	v_add_u32_e32 v55, s76, v60
	v_add_u32_e32 v56, s76, v61
	v_add_u32_e32 v57, s76, v62
	ds_read_b64_tr_b4 v[46:47], v160 offset:768
	ds_read_b64_tr_b4 v[48:49], v160 offset:1792
	ds_read_b64_tr_b4 v[122:123], v54
	ds_read_b64_tr_b4 v[124:125], v55
	ds_read_b64_tr_b4 v[126:127], v56
	ds_read_b64_tr_b4 v[128:129], v57
	s_waitcnt lgkmcnt(7)
	v_dot8c_i32_i4_e32 v38, v130, v52
	v_dot8c_i32_i4_e32 v39, v130, v50
	v_dot8c_i32_i4_e32 v40, v132, v52
	v_dot8c_i32_i4_e32 v41, v132, v50
	v_dot8c_i32_i4_e32 v42, v134, v52
	v_dot8c_i32_i4_e32 v43, v134, v50
	v_dot8c_i32_i4_e32 v44, v136, v52
	v_dot8c_i32_i4_e32 v45, v136, v50
	v_dot8c_i32_i4_e32 v38, v131, v53
	v_dot8c_i32_i4_e32 v39, v131, v51
	v_dot8c_i32_i4_e32 v40, v133, v53
	v_dot8c_i32_i4_e32 v41, v133, v51
	v_dot8c_i32_i4_e32 v42, v135, v53
	v_dot8c_i32_i4_e32 v43, v135, v51
	v_dot8c_i32_i4_e32 v44, v137, v53
	v_dot8c_i32_i4_e32 v45, v137, v51
	v_and_b32_e32 v78, 0xffff, v29
	v_lshrrev_b32_e32 v79, 16, v29
	v_lshl_add_u32 v78, v78, 7, v152
	v_lshl_add_u32 v79, v79, 7, v153
	s_mov_b32 m0, s99
	s_add_i32 s43, s99, 0x400
	global_load_lds_dwordx4 v78, s[50:51]
	s_mov_b32 m0, s43
	s_nop 0
	global_load_lds_dwordx4 v79, s[50:51]
	s_waitcnt vmcnt(8)
	v_add_u32_e32 v54, s77, v59
	v_add_u32_e32 v55, s77, v60
	v_add_u32_e32 v56, s77, v61
	v_add_u32_e32 v57, s77, v62
	ds_read_b64_tr_b4 v[50:51], v160 offset:896
	ds_read_b64_tr_b4 v[52:53], v160 offset:1920
	ds_read_b64_tr_b4 v[130:131], v54
	ds_read_b64_tr_b4 v[132:133], v55
	ds_read_b64_tr_b4 v[134:135], v56
	ds_read_b64_tr_b4 v[136:137], v57
	s_waitcnt lgkmcnt(6)
	v_dot8c_i32_i4_e32 v38, v122, v48
	v_dot8c_i32_i4_e32 v39, v122, v46
	v_dot8c_i32_i4_e32 v40, v124, v48
	v_dot8c_i32_i4_e32 v41, v124, v46
	v_dot8c_i32_i4_e32 v42, v126, v48
	v_dot8c_i32_i4_e32 v43, v126, v46
	v_dot8c_i32_i4_e32 v44, v128, v48
	v_dot8c_i32_i4_e32 v45, v128, v46
	v_dot8c_i32_i4_e32 v38, v123, v49
	v_dot8c_i32_i4_e32 v39, v123, v47
	v_dot8c_i32_i4_e32 v40, v125, v49
	v_dot8c_i32_i4_e32 v41, v125, v47
	v_dot8c_i32_i4_e32 v42, v127, v49
	v_dot8c_i32_i4_e32 v43, v127, v47
	v_dot8c_i32_i4_e32 v44, v129, v49
	v_dot8c_i32_i4_e32 v45, v129, v47
	v_and_b32_e32 v78, 0xffff, v30
	v_lshrrev_b32_e32 v79, 16, v30
	v_lshl_add_u32 v78, v78, 7, v152
	v_lshl_add_u32 v79, v79, 7, v153
	s_mov_b32 m0, s76
	s_add_i32 s43, s76, 0x400
	global_load_lds_dwordx4 v78, s[50:51]
	s_mov_b32 m0, s43
	s_nop 0
	global_load_lds_dwordx4 v79, s[50:51]
	s_waitcnt vmcnt(8)
; #define LAS __attribute__((address_space(3)))
; __device__ __forceinline__ bf16 f2bf(float f) { return (bf16)f2bfu(f); }
; __device__ __forceinline__ void peer_v_tokens(int j, const LAS unsigned short* EL, const LAS unsigned char* AL  , const LAS float* ASC  , const LAS int* SAL  , ...
;     ...
;         for (int st = 0; st < 16; ++st) {
;             const int p = st >> 2, q = st & 3;
;             if (st < 14) VDMA(st + 2, (st + 2) % 3);
;             if (st < 14) asm volatile("s_waitcnt vmcnt(8)" ::: "memory");
;             else if (st == 14) asm volatile("s_waitcnt vmcnt(4)" ::: "memory");
;             else asm volatile("s_waitcnt vmcnt(0)" ::: "memory");
;             if (q == 0) {
; #pragma unroll
;                 for (int r = 0; r < 4; ++r) { accH[r] = 0; accL[r] = 0; } }
; #pragma unroll
;             for (int tp = 0; tp < 2; ++tp) {
;                 const v2i ao = TR4(ATL + (2 * q + tp) * 128 + 8 * s16), ah = TR4(ATL + 1024 + (2 * q + tp) * 128 + 8 * s16);
; #pragma unroll
;                 for (int r = 0; r < 4; ++r) {
;                     const v2i d = TR4(ldsb + BUF[st % 3] + 2048 * tp + roff[r]);
;                     accH[r] = __builtin_amdgcn_sdot8(d.x, ah.x, accH[r], false); accH[r] = __builtin_amdgcn_sdot8(d.y, ah.y, accH[r], false);
;                     accL[r] = __builtin_amdgcn_sdot8(d.x, ao.x, accL[r], false); accL[r] = __builtin_amdgcn_sdot8(d.y, ao.y, accL[r], false);
;                 }
;             }
;             asm volatile("s_waitcnt lgkmcnt(0)" ::: "memory");
;             if (q == 3) {
; #pragma unroll
;                 for (int r = 0; r < 4; ++r) STASH[256 * p + 16 * (grp + 4 * r) + pc] = f2bf(asc * (float)(2 * ((accH[r] << 4) + accL[r]) + sa));
;             }
;         }
;     ...
;             for (int jq = 0; jq < 4; ++jq) { typedef unsigned u2v __attribute__((ext_vector_type(2))); const u2v pw = *(const LAS u2v*)(STASH + 4 * lane + 256 * jq); const uint2 hw = hv[jq];
;                 v[jq] = make_float4(__uint_as_float(hw.x << 16) + __uint_as_float(pw.x << 16), __uint_as_float(hw.x & 0xffff0000u) + __uint_as_float(pw.x & 0xffff0000u),
;                                     __uint_as_float(hw.y << 16) + __uint_as_float(pw.y << 16), __uint_as_float(hw.y & 0xffff0000u) + __uint_as_float(pw.y & 0xffff0000u));
;                 ss += v[jq].x * v[jq].x + v[jq].y * v[jq].y + v[jq].z * v[jq].z + v[jq].w * v[jq].w; }
	v_add_u32_e32 v54, s78, v59
	v_add_u32_e32 v55, s78, v60
	v_add_u32_e32 v56, s78, v61
	v_add_u32_e32 v57, s78, v62
	ds_read_b64_tr_b4 v[46:47], v160
	ds_read_b64_tr_b4 v[48:49], v160 offset:1024
	ds_read_b64_tr_b4 v[122:123], v54
	ds_read_b64_tr_b4 v[124:125], v55
	ds_read_b64_tr_b4 v[126:127], v56
	ds_read_b64_tr_b4 v[128:129], v57
	s_waitcnt lgkmcnt(6)
	v_dot8c_i32_i4_e32 v38, v130, v52
	v_dot8c_i32_i4_e32 v39, v130, v50
	v_dot8c_i32_i4_e32 v40, v132, v52
	v_dot8c_i32_i4_e32 v41, v132, v50
	v_dot8c_i32_i4_e32 v42, v134, v52
	v_dot8c_i32_i4_e32 v43, v134, v50
	v_dot8c_i32_i4_e32 v44, v136, v52
	v_dot8c_i32_i4_e32 v45, v136, v50
	v_dot8c_i32_i4_e32 v38, v131, v53
	v_dot8c_i32_i4_e32 v39, v131, v51
	v_dot8c_i32_i4_e32 v40, v133, v53
	v_dot8c_i32_i4_e32 v41, v133, v51
	v_dot8c_i32_i4_e32 v42, v135, v53
	v_dot8c_i32_i4_e32 v43, v135, v51
	v_dot8c_i32_i4_e32 v44, v137, v53
	v_dot8c_i32_i4_e32 v45, v137, v51
	s_nop 3
	s_waitcnt lgkmcnt(15)
	v_lshlrev_b32_e32 v38, 5, v38
	v_lshlrev_b32_e32 v39, 1, v39
	v_add3_u32 v38, v39, v229, v38
	v_cvt_f32_i32_e32 v38, v38
	v_mul_f32_e32 v38, v228, v38
	v_lshlrev_b32_e32 v40, 5, v40
	v_lshlrev_b32_e32 v41, 1, v41
	v_add3_u32 v40, v41, v229, v40
	v_cvt_f32_i32_e32 v40, v40
	v_mul_f32_e32 v40, v228, v40
	v_lshlrev_b32_e32 v42, 5, v42
	v_lshlrev_b32_e32 v43, 1, v43
	v_add3_u32 v42, v43, v229, v42
	v_cvt_f32_i32_e32 v42, v42
	v_mul_f32_e32 v42, v228, v42
	v_lshlrev_b32_e32 v44, 5, v44
	v_lshlrev_b32_e32 v45, 1, v45
	v_add3_u32 v44, v45, v229, v44
	v_cvt_f32_i32_e32 v44, v44
	v_mul_f32_e32 v44, v228, v44
	v_cvt_pk_bf16_f32 v164, v38, v40
	v_cvt_pk_bf16_f32 v165, v42, v44
	ds_read_b128 v[252:255], v155 offset:1024
	s_add_i32 s44, s40, 16
	s_ashr_i32 s45, s44, 31
	s_lshl_b64 s[44:45], s[44:45], 12
	v_lshl_add_u64 v[80:81], v[36:37], 0, s[44:45]
	s_waitcnt lgkmcnt(0)
	v_mul_f32_e32 v214, v214, v252
	v_mul_f32_e32 v215, v215, v253
	v_mul_f32_e32 v216, v216, v254
	v_mul_f32_e32 v217, v217, v255
	global_store_dwordx4 v[80:81], v[214:217], off offset:1024 nt
	v_add_u32_e32 v147, 8, v140
	v_and_b32_e32 v146, 15, v147
	v_xor_b32_e32 v146, 8, v146
	v_bfe_u32 v148, v147, 4, 4
	v_mul_lo_u32 v146, v146, s92
	v_mul_lo_u32 v148, v148, s92
	v_mov_b32_e32 v147, v146
	v_mov_b32_e32 v149, v148
	ds_write2st64_b64 v77, v[146:147], v[148:149] offset1:2
	v_add_u32_e32 v138, 0x1000, v74
	ds_read_u8 v139, v138
	v_add_u32_e32 v141, 0x1000, v73
	ds_read_u8 v140, v141
	s_add_i32 s43, s67, 160
	v_mov_b32_e32 v138, s43
	ds_read2st64_b32 v[228:229], v138 offset1:1
	ds_read_b128 v[18:21], v227 offset:8192
	ds_read_b128 v[22:25], v227 offset:8208
	v_add_u32_e32 v150, 0x400000, v63
	v_add_u32_e32 v151, 0x400000, v64
	v_mov_b32_e32 v38, 0
	v_mov_b32_e32 v39, 0
	v_mov_b32_e32 v40, 0
	v_mov_b32_e32 v41, 0
	v_mov_b32_e32 v42, 0
	v_mov_b32_e32 v43, 0
	v_mov_b32_e32 v44, 0
	v_mov_b32_e32 v45, 0
	v_and_b32_e32 v78, 0xffff, v31
	v_lshrrev_b32_e32 v79, 16, v31
	v_lshl_add_u32 v78, v78, 7, v152
	v_lshl_add_u32 v79, v79, 7, v153
	s_mov_b32 m0, s77
	s_add_i32 s43, s77, 0x400
	global_load_lds_dwordx4 v78, s[50:51]
	s_mov_b32 m0, s43
	s_nop 0
	global_load_lds_dwordx4 v79, s[50:51]
	s_waitcnt vmcnt(9)
	v_add_u32_e32 v54, s79, v59
	v_add_u32_e32 v55, s79, v60
	v_add_u32_e32 v56, s79, v61
	v_add_u32_e32 v57, s79, v62
	ds_read_b64_tr_b4 v[50:51], v160 offset:128
	ds_read_b64_tr_b4 v[52:53], v160 offset:1152
	ds_read_b64_tr_b4 v[130:131], v54
	ds_read_b64_tr_b4 v[132:133], v55
	ds_read_b64_tr_b4 v[134:135], v56
	ds_read_b64_tr_b4 v[136:137], v57
	s_waitcnt lgkmcnt(13)
	v_dot8c_i32_i4_e32 v38, v122, v48
	v_dot8c_i32_i4_e32 v39, v122, v46
	v_dot8c_i32_i4_e32 v40, v124, v48
	v_dot8c_i32_i4_e32 v41, v124, v46
	v_dot8c_i32_i4_e32 v42, v126, v48
	v_dot8c_i32_i4_e32 v43, v126, v46
	v_dot8c_i32_i4_e32 v44, v128, v48
	v_dot8c_i32_i4_e32 v45, v128, v46
	v_dot8c_i32_i4_e32 v38, v123, v49
	v_dot8c_i32_i4_e32 v39, v123, v47
	v_dot8c_i32_i4_e32 v40, v125, v49
	v_dot8c_i32_i4_e32 v41, v125, v47
	v_dot8c_i32_i4_e32 v42, v127, v49
	v_dot8c_i32_i4_e32 v43, v127, v47
	v_dot8c_i32_i4_e32 v44, v129, v49
	v_dot8c_i32_i4_e32 v45, v129, v47
	v_and_b32_e32 v78, 0xffff, v32
	v_lshrrev_b32_e32 v79, 16, v32
	v_lshl_add_u32 v78, v78, 7, v152
	v_lshl_add_u32 v79, v79, 7, v153
	s_mov_b32 m0, s78
	s_add_i32 s43, s78, 0x400
	global_load_lds_dwordx4 v78, s[50:51]
	s_mov_b32 m0, s43
	s_nop 0
	global_load_lds_dwordx4 v79, s[50:51]
	s_waitcnt vmcnt(9)
	v_add_u32_e32 v54, s98, v59
	v_add_u32_e32 v55, s98, v60
	v_add_u32_e32 v56, s98, v61
	v_add_u32_e32 v57, s98, v62
	ds_read_b64_tr_b4 v[46:47], v160 offset:256
	ds_read_b64_tr_b4 v[48:49], v160 offset:1280
	ds_read_b64_tr_b4 v[122:123], v54
	ds_read_b64_tr_b4 v[124:125], v55
	ds_read_b64_tr_b4 v[126:127], v56
	ds_read_b64_tr_b4 v[128:129], v57
	s_waitcnt lgkmcnt(6)
	v_dot8c_i32_i4_e32 v38, v130, v52
	v_dot8c_i32_i4_e32 v39, v130, v50
	v_dot8c_i32_i4_e32 v40, v132, v52
	v_dot8c_i32_i4_e32 v41, v132, v50
	v_dot8c_i32_i4_e32 v42, v134, v52
	v_dot8c_i32_i4_e32 v43, v134, v50
	v_dot8c_i32_i4_e32 v44, v136, v52
	v_dot8c_i32_i4_e32 v45, v136, v50
	v_dot8c_i32_i4_e32 v38, v131, v53
	v_dot8c_i32_i4_e32 v39, v131, v51
	v_dot8c_i32_i4_e32 v40, v133, v53
	v_dot8c_i32_i4_e32 v41, v133, v51
	v_dot8c_i32_i4_e32 v42, v135, v53
	v_dot8c_i32_i4_e32 v43, v135, v51
	v_dot8c_i32_i4_e32 v44, v137, v53
	v_dot8c_i32_i4_e32 v45, v137, v51
	ds_write_b16 v65, v186
	ds_write_b16_d16_hi v65, v186 offset:128
	ds_write_b16 v65, v187 offset:256
	ds_write_b16_d16_hi v65, v187 offset:384
	ds_write_b16 v65, v188 offset:512
	ds_write_b16_d16_hi v65, v188 offset:640
	ds_write_b16 v65, v189 offset:768
	ds_write_b16_d16_hi v65, v189 offset:896
	ds_write_b16 v65, v190 offset:1024
	ds_write_b16_d16_hi v65, v190 offset:1152
	ds_write_b16 v65, v191 offset:1280
	ds_write_b16_d16_hi v65, v191 offset:1408
	ds_write_b16 v65, v192 offset:1536
	ds_write_b16_d16_hi v65, v192 offset:1664
	ds_write_b16 v65, v193 offset:1792
	ds_write_b16_d16_hi v65, v193 offset:1920
	ds_read_b64 v[202:203], v154
	ds_read_b64 v[204:205], v154 offset:512
	ds_read_b64 v[206:207], v154 offset:1024
	ds_read_b64 v[208:209], v154 offset:1536
	v_and_b32_e32 v78, 0xffff, v33
	v_lshrrev_b32_e32 v79, 16, v33
	v_lshl_add_u32 v78, v78, 7, v152
	v_lshl_add_u32 v79, v79, 7, v153
	s_mov_b32 m0, s79
	s_add_i32 s43, s79, 0x400
	global_load_lds_dwordx4 v78, s[50:51]
	s_mov_b32 m0, s43
	s_nop 0
	global_load_lds_dwordx4 v79, s[50:51]
	s_waitcnt vmcnt(9)
; #define TR4(p_) __builtin_amdgcn_ds_read_tr4_b64_v2i32((LAS v2i*)(p_))
; #define VDMA(st_, k_) do { _Pragma("unroll") for (int i_ = 0; i_ < 4; ++i_) { \
;         const unsigned off_ = (unsigned)((st_) >> 2) * (16384u * 128u) + (PE_ID(E, 4 * ((st_) & 3) + i_) << 7) + ((i_ & 1) ? cx1 : cx0); \
;         __builtin_amdgcn_global_load_lds((const unsigned*)(V4 + off_), (LAS unsigned*)(ldsb + BUF[k_] + 1024 * i_), 16, 0, 0); } } while (0)
; __device__ __forceinline__ void peer_v_tokens(int j, const LAS unsigned short* EL, const LAS unsigned char* AL  , const LAS float* ASC  , const LAS int* SAL  , ...
;     ...
;         for (int st = 0; st < 16; ++st) {
;             const int p = st >> 2, q = st & 3;
;             if (st < 14) VDMA(st + 2, (st + 2) % 3);
;             if (st < 14) asm volatile("s_waitcnt vmcnt(8)" ::: "memory");
;             else if (st == 14) asm volatile("s_waitcnt vmcnt(4)" ::: "memory");
;             else asm volatile("s_waitcnt vmcnt(0)" ::: "memory");
;             if (q == 0) {
; #pragma unroll
;                 for (int r = 0; r < 4; ++r) { accH[r] = 0; accL[r] = 0; } }
; #pragma unroll
;             for (int tp = 0; tp < 2; ++tp) {
;                 const v2i ao = TR4(ATL + (2 * q + tp) * 128 + 8 * s16), ah = TR4(ATL + 1024 + (2 * q + tp) * 128 + 8 * s16);
; #pragma unroll
;                 for (int r = 0; r < 4; ++r) {
;                     const v2i d = TR4(ldsb + BUF[st % 3] + 2048 * tp + roff[r]);
;                     accH[r] = __builtin_amdgcn_sdot8(d.x, ah.x, accH[r], false); accH[r] = __builtin_amdgcn_sdot8(d.y, ah.y, accH[r], false);
;                     accL[r] = __builtin_amdgcn_sdot8(d.x, ao.x, accL[r], false); accL[r] = __builtin_amdgcn_sdot8(d.y, ao.y, accL[r], false);
;                 }
;             }
;             asm volatile("s_waitcnt lgkmcnt(0)" ::: "memory");
	v_add_u32_e32 v54, s99, v59
	v_add_u32_e32 v55, s99, v60
	v_add_u32_e32 v56, s99, v61
	v_add_u32_e32 v57, s99, v62
	ds_read_b64_tr_b4 v[50:51], v160 offset:384
	ds_read_b64_tr_b4 v[52:53], v160 offset:1408
	ds_read_b64_tr_b4 v[130:131], v54
	ds_read_b64_tr_b4 v[132:133], v55
	ds_read_b64_tr_b4 v[134:135], v56
	ds_read_b64_tr_b4 v[136:137], v57
	s_waitcnt lgkmcnt(15)
	v_dot8c_i32_i4_e32 v38, v122, v48
	v_dot8c_i32_i4_e32 v39, v122, v46
	v_dot8c_i32_i4_e32 v40, v124, v48
	v_dot8c_i32_i4_e32 v41, v124, v46
	v_dot8c_i32_i4_e32 v42, v126, v48
	v_dot8c_i32_i4_e32 v43, v126, v46
	v_dot8c_i32_i4_e32 v44, v128, v48
	v_dot8c_i32_i4_e32 v45, v128, v46
	v_dot8c_i32_i4_e32 v38, v123, v49
	v_dot8c_i32_i4_e32 v39, v123, v47
	v_dot8c_i32_i4_e32 v40, v125, v49
	v_dot8c_i32_i4_e32 v41, v125, v47
	v_dot8c_i32_i4_e32 v42, v127, v49
	v_dot8c_i32_i4_e32 v43, v127, v47
	v_dot8c_i32_i4_e32 v44, v129, v49
	v_dot8c_i32_i4_e32 v45, v129, v47
	s_waitcnt lgkmcnt(15)
	v_and_b32_e32 v78, 0xffff, v18
	v_lshrrev_b32_e32 v79, 16, v18
	v_lshl_add_u32 v78, v78, 7, v150
	v_lshl_add_u32 v79, v79, 7, v151
	s_mov_b32 m0, s98
	s_add_i32 s43, s98, 0x400
	global_load_lds_dwordx4 v78, s[50:51]
	s_mov_b32 m0, s43
	s_nop 0
	global_load_lds_dwordx4 v79, s[50:51]
	s_waitcnt vmcnt(9)
	v_add_u32_e32 v54, s76, v59
	v_add_u32_e32 v55, s76, v60
	v_add_u32_e32 v56, s76, v61
	v_add_u32_e32 v57, s76, v62
	ds_read_b64_tr_b4 v[46:47], v160 offset:512
	ds_read_b64_tr_b4 v[48:49], v160 offset:1536
	ds_read_b64_tr_b4 v[122:123], v54
	ds_read_b64_tr_b4 v[124:125], v55
	ds_read_b64_tr_b4 v[126:127], v56
	ds_read_b64_tr_b4 v[128:129], v57
	s_waitcnt lgkmcnt(6)
	v_dot8c_i32_i4_e32 v38, v130, v52
	v_dot8c_i32_i4_e32 v39, v130, v50
	v_dot8c_i32_i4_e32 v40, v132, v52
	v_dot8c_i32_i4_e32 v41, v132, v50
	v_dot8c_i32_i4_e32 v42, v134, v52
	v_dot8c_i32_i4_e32 v43, v134, v50
	v_dot8c_i32_i4_e32 v44, v136, v52
	v_dot8c_i32_i4_e32 v45, v136, v50
	v_dot8c_i32_i4_e32 v38, v131, v53
	v_dot8c_i32_i4_e32 v39, v131, v51
	v_dot8c_i32_i4_e32 v40, v133, v53
	v_dot8c_i32_i4_e32 v41, v133, v51
	v_dot8c_i32_i4_e32 v42, v135, v53
	v_dot8c_i32_i4_e32 v43, v135, v51
	v_dot8c_i32_i4_e32 v44, v137, v53
	v_dot8c_i32_i4_e32 v45, v137, v51
	v_and_b32_e32 v78, 0xffff, v19
	v_lshrrev_b32_e32 v79, 16, v19
	v_lshl_add_u32 v78, v78, 7, v150
	v_lshl_add_u32 v79, v79, 7, v151
	s_mov_b32 m0, s99
	s_add_i32 s43, s99, 0x400
	global_load_lds_dwordx4 v78, s[50:51]
	s_mov_b32 m0, s43
	s_nop 0
	global_load_lds_dwordx4 v79, s[50:51]
	s_waitcnt vmcnt(8)
	v_add_u32_e32 v54, s77, v59
	v_add_u32_e32 v55, s77, v60
	v_add_u32_e32 v56, s77, v61
	v_add_u32_e32 v57, s77, v62
	ds_read_b64_tr_b4 v[50:51], v160 offset:640
	ds_read_b64_tr_b4 v[52:53], v160 offset:1664
	ds_read_b64_tr_b4 v[130:131], v54
	ds_read_b64_tr_b4 v[132:133], v55
	ds_read_b64_tr_b4 v[134:135], v56
	ds_read_b64_tr_b4 v[136:137], v57
	s_waitcnt lgkmcnt(6)
	v_dot8c_i32_i4_e32 v38, v122, v48
	v_dot8c_i32_i4_e32 v39, v122, v46
	v_dot8c_i32_i4_e32 v40, v124, v48
	v_dot8c_i32_i4_e32 v41, v124, v46
	v_dot8c_i32_i4_e32 v42, v126, v48
	v_dot8c_i32_i4_e32 v43, v126, v46
	v_dot8c_i32_i4_e32 v44, v128, v48
	v_dot8c_i32_i4_e32 v45, v128, v46
	v_dot8c_i32_i4_e32 v38, v123, v49
	v_dot8c_i32_i4_e32 v39, v123, v47
	v_dot8c_i32_i4_e32 v40, v125, v49
	v_dot8c_i32_i4_e32 v41, v125, v47
	v_dot8c_i32_i4_e32 v42, v127, v49
	v_dot8c_i32_i4_e32 v43, v127, v47
	v_dot8c_i32_i4_e32 v44, v129, v49
	v_dot8c_i32_i4_e32 v45, v129, v47
	s_waitcnt lgkmcnt(15)
	v_add_u32_e32 v143, 8, v139
	v_and_b32_e32 v142, 15, v143
	v_xor_b32_e32 v142, 8, v142
	v_bfe_u32 v144, v143, 4, 4
	v_mul_lo_u32 v142, v142, s92
	v_mul_lo_u32 v144, v144, s92
	v_mov_b32_e32 v143, v142
	v_mov_b32_e32 v145, v144
	ds_write2st64_b64 v159, v[142:143], v[144:145] offset1:2
	v_and_b32_e32 v78, 0xffff, v20
	v_lshrrev_b32_e32 v79, 16, v20
	v_lshl_add_u32 v78, v78, 7, v150
	v_lshl_add_u32 v79, v79, 7, v151
	s_mov_b32 m0, s76
	s_add_i32 s43, s76, 0x400
	global_load_lds_dwordx4 v78, s[50:51]
	s_mov_b32 m0, s43
	s_nop 0
	global_load_lds_dwordx4 v79, s[50:51]
	s_waitcnt vmcnt(8)
	v_add_u32_e32 v54, s78, v59
	v_add_u32_e32 v55, s78, v60
	v_add_u32_e32 v56, s78, v61
	v_add_u32_e32 v57, s78, v62
	ds_read_b64_tr_b4 v[46:47], v160 offset:768
	ds_read_b64_tr_b4 v[48:49], v160 offset:1792
	ds_read_b64_tr_b4 v[122:123], v54
	ds_read_b64_tr_b4 v[124:125], v55
	ds_read_b64_tr_b4 v[126:127], v56
	ds_read_b64_tr_b4 v[128:129], v57
	s_waitcnt lgkmcnt(7)
	v_dot8c_i32_i4_e32 v38, v130, v52
	v_dot8c_i32_i4_e32 v39, v130, v50
	v_dot8c_i32_i4_e32 v40, v132, v52
	v_dot8c_i32_i4_e32 v41, v132, v50
	v_dot8c_i32_i4_e32 v42, v134, v52
	v_dot8c_i32_i4_e32 v43, v134, v50
	v_dot8c_i32_i4_e32 v44, v136, v52
	v_dot8c_i32_i4_e32 v45, v136, v50
	v_dot8c_i32_i4_e32 v38, v131, v53
	v_dot8c_i32_i4_e32 v39, v131, v51
	v_dot8c_i32_i4_e32 v40, v133, v53
	v_dot8c_i32_i4_e32 v41, v133, v51
	v_dot8c_i32_i4_e32 v42, v135, v53
	v_dot8c_i32_i4_e32 v43, v135, v51
	v_dot8c_i32_i4_e32 v44, v137, v53
	v_dot8c_i32_i4_e32 v45, v137, v51
	v_and_b32_e32 v78, 0xffff, v21
	v_lshrrev_b32_e32 v79, 16, v21
	v_lshl_add_u32 v78, v78, 7, v150
	v_lshl_add_u32 v79, v79, 7, v151
	s_mov_b32 m0, s77
	s_add_i32 s43, s77, 0x400
	global_load_lds_dwordx4 v78, s[50:51]
	s_mov_b32 m0, s43
	s_nop 0
	global_load_lds_dwordx4 v79, s[50:51]
	s_waitcnt vmcnt(8)
	v_add_u32_e32 v54, s79, v59
	v_add_u32_e32 v55, s79, v60
	v_add_u32_e32 v56, s79, v61
	v_add_u32_e32 v57, s79, v62
	ds_read_b64_tr_b4 v[50:51], v160 offset:896
	ds_read_b64_tr_b4 v[52:53], v160 offset:1920
	ds_read_b64_tr_b4 v[130:131], v54
	ds_read_b64_tr_b4 v[132:133], v55
	ds_read_b64_tr_b4 v[134:135], v56
	ds_read_b64_tr_b4 v[136:137], v57
	s_waitcnt lgkmcnt(6)
; __device__ __forceinline__ bf16 f2bf(float f) { return (bf16)f2bfu(f); }
; #define TR4(p_) __builtin_amdgcn_ds_read_tr4_b64_v2i32((LAS v2i*)(p_))
; #define VDMA(st_, k_) do { _Pragma("unroll") for (int i_ = 0; i_ < 4; ++i_) { \
;         const unsigned off_ = (unsigned)((st_) >> 2) * (16384u * 128u) + (PE_ID(E, 4 * ((st_) & 3) + i_) << 7) + ((i_ & 1) ? cx1 : cx0); \
;         __builtin_amdgcn_global_load_lds((const unsigned*)(V4 + off_), (LAS unsigned*)(ldsb + BUF[k_] + 1024 * i_), 16, 0, 0); } } while (0)
; __device__ __forceinline__ void peer_v_tokens(int j, const LAS unsigned short* EL, const LAS unsigned char* AL  , const LAS float* ASC  , const LAS int* SAL  , ...
;     ...
;         for (int st = 0; st < 16; ++st) {
;             const int p = st >> 2, q = st & 3;
;             if (st < 14) VDMA(st + 2, (st + 2) % 3);
;             if (st < 14) asm volatile("s_waitcnt vmcnt(8)" ::: "memory");
;             else if (st == 14) asm volatile("s_waitcnt vmcnt(4)" ::: "memory");
;             else asm volatile("s_waitcnt vmcnt(0)" ::: "memory");
;             if (q == 0) {
; #pragma unroll
;                 for (int r = 0; r < 4; ++r) { accH[r] = 0; accL[r] = 0; } }
; #pragma unroll
;             for (int tp = 0; tp < 2; ++tp) {
;                 const v2i ao = TR4(ATL + (2 * q + tp) * 128 + 8 * s16), ah = TR4(ATL + 1024 + (2 * q + tp) * 128 + 8 * s16);
; #pragma unroll
;                 for (int r = 0; r < 4; ++r) {
;                     const v2i d = TR4(ldsb + BUF[st % 3] + 2048 * tp + roff[r]);
;                     accH[r] = __builtin_amdgcn_sdot8(d.x, ah.x, accH[r], false); accH[r] = __builtin_amdgcn_sdot8(d.y, ah.y, accH[r], false);
;                     accL[r] = __builtin_amdgcn_sdot8(d.x, ao.x, accL[r], false); accL[r] = __builtin_amdgcn_sdot8(d.y, ao.y, accL[r], false);
;                 }
;             }
;             asm volatile("s_waitcnt lgkmcnt(0)" ::: "memory");
;             if (q == 3) {
; #pragma unroll
;                 for (int r = 0; r < 4; ++r) STASH[256 * p + 16 * (grp + 4 * r) + pc] = f2bf(asc * (float)(2 * ((accH[r] << 4) + accL[r]) + sa));
;             }
;         }
;     ...
;         {
;             float4 v[4]; float ss = 0.f;
; #pragma unroll
	v_dot8c_i32_i4_e32 v38, v122, v48
	v_dot8c_i32_i4_e32 v39, v122, v46
	v_dot8c_i32_i4_e32 v40, v124, v48
	v_dot8c_i32_i4_e32 v41, v124, v46
	v_dot8c_i32_i4_e32 v42, v126, v48
	v_dot8c_i32_i4_e32 v43, v126, v46
	v_dot8c_i32_i4_e32 v44, v128, v48
	v_dot8c_i32_i4_e32 v45, v128, v46
	v_dot8c_i32_i4_e32 v38, v123, v49
	v_dot8c_i32_i4_e32 v39, v123, v47
	v_dot8c_i32_i4_e32 v40, v125, v49
	v_dot8c_i32_i4_e32 v41, v125, v47
	v_dot8c_i32_i4_e32 v42, v127, v49
	v_dot8c_i32_i4_e32 v43, v127, v47
	v_dot8c_i32_i4_e32 v44, v129, v49
	v_dot8c_i32_i4_e32 v45, v129, v47
	v_and_b32_e32 v78, 0xffff, v22
	v_lshrrev_b32_e32 v79, 16, v22
	v_lshl_add_u32 v78, v78, 7, v150
	v_lshl_add_u32 v79, v79, 7, v151
	s_mov_b32 m0, s78
	s_add_i32 s43, s78, 0x400
	global_load_lds_dwordx4 v78, s[50:51]
	s_mov_b32 m0, s43
	s_nop 0
	global_load_lds_dwordx4 v79, s[50:51]
	s_waitcnt vmcnt(8)
	v_add_u32_e32 v54, s98, v59
	v_add_u32_e32 v55, s98, v60
	v_add_u32_e32 v56, s98, v61
	v_add_u32_e32 v57, s98, v62
	ds_read_b64_tr_b4 v[46:47], v160
	ds_read_b64_tr_b4 v[48:49], v160 offset:1024
	ds_read_b64_tr_b4 v[122:123], v54
	ds_read_b64_tr_b4 v[124:125], v55
	ds_read_b64_tr_b4 v[126:127], v56
	ds_read_b64_tr_b4 v[128:129], v57
	s_waitcnt lgkmcnt(6)
	v_dot8c_i32_i4_e32 v38, v130, v52
	v_dot8c_i32_i4_e32 v39, v130, v50
	v_dot8c_i32_i4_e32 v40, v132, v52
	v_dot8c_i32_i4_e32 v41, v132, v50
	v_dot8c_i32_i4_e32 v42, v134, v52
	v_dot8c_i32_i4_e32 v43, v134, v50
	v_dot8c_i32_i4_e32 v44, v136, v52
	v_dot8c_i32_i4_e32 v45, v136, v50
	v_dot8c_i32_i4_e32 v38, v131, v53
	v_dot8c_i32_i4_e32 v39, v131, v51
	v_dot8c_i32_i4_e32 v40, v133, v53
	v_dot8c_i32_i4_e32 v41, v133, v51
	v_dot8c_i32_i4_e32 v42, v135, v53
	v_dot8c_i32_i4_e32 v43, v135, v51
	v_dot8c_i32_i4_e32 v44, v137, v53
	v_dot8c_i32_i4_e32 v45, v137, v51
	s_nop 3
	s_waitcnt lgkmcnt(15)
	v_lshlrev_b32_e32 v38, 5, v38
	v_lshlrev_b32_e32 v39, 1, v39
	v_add3_u32 v38, v39, v229, v38
	v_cvt_f32_i32_e32 v38, v38
	v_mul_f32_e32 v38, v228, v38
	v_lshlrev_b32_e32 v40, 5, v40
	v_lshlrev_b32_e32 v41, 1, v41
	v_add3_u32 v40, v41, v229, v40
	v_cvt_f32_i32_e32 v40, v40
	v_mul_f32_e32 v40, v228, v40
	v_lshlrev_b32_e32 v42, 5, v42
	v_lshlrev_b32_e32 v43, 1, v43
	v_add3_u32 v42, v43, v229, v42
	v_cvt_f32_i32_e32 v42, v42
	v_mul_f32_e32 v42, v228, v42
	v_lshlrev_b32_e32 v44, 5, v44
	v_lshlrev_b32_e32 v45, 1, v45
	v_add3_u32 v44, v45, v229, v44
	v_cvt_f32_i32_e32 v44, v44
	v_mul_f32_e32 v44, v228, v44
	v_cvt_pk_bf16_f32 v172, v38, v40
	v_cvt_pk_bf16_f32 v173, v42, v44
	ds_read_b128 v[252:255], v156
	s_add_i32 s44, s40, 16
	s_ashr_i32 s45, s44, 31
	s_lshl_b64 s[44:45], s[44:45], 12
	v_lshl_add_u64 v[80:81], v[36:37], 0, s[44:45]
	s_waitcnt lgkmcnt(0)
	v_mul_f32_e32 v218, v218, v252
	v_mul_f32_e32 v219, v219, v253
	v_mul_f32_e32 v220, v220, v254
	v_mul_f32_e32 v221, v221, v255
	global_store_dwordx4 v[80:81], v[218:221], off offset:2048 nt
	v_add_u32_e32 v147, 8, v140
	v_and_b32_e32 v146, 15, v147
	v_xor_b32_e32 v146, 8, v146
	v_bfe_u32 v148, v147, 4, 4
	v_mul_lo_u32 v146, v146, s92
	v_mul_lo_u32 v148, v148, s92
	v_mov_b32_e32 v147, v146
	v_mov_b32_e32 v149, v148
	ds_write2st64_b64 v77, v[146:147], v[148:149] offset1:2
	v_add_u32_e32 v138, 0x1400, v74
	ds_read_u8 v139, v138
	v_add_u32_e32 v141, 0x1400, v73
	ds_read_u8 v140, v141
	s_add_i32 s43, s67, 128
	v_mov_b32_e32 v138, s43
	ds_read2st64_b32 v[228:229], v138 offset1:1
	ds_read_b128 v[26:29], v227 offset:10240
	ds_read_b128 v[30:33], v227 offset:10256
	v_mov_b32_e32 v38, 0
	v_mov_b32_e32 v39, 0
	v_mov_b32_e32 v40, 0
	v_mov_b32_e32 v41, 0
	v_mov_b32_e32 v42, 0
	v_mov_b32_e32 v43, 0
	v_mov_b32_e32 v44, 0
	v_mov_b32_e32 v45, 0
	v_and_b32_e32 v78, 0xffff, v23
	v_lshrrev_b32_e32 v79, 16, v23
	v_lshl_add_u32 v78, v78, 7, v150
	v_lshl_add_u32 v79, v79, 7, v151
	s_mov_b32 m0, s79
	s_add_i32 s43, s79, 0x400
	global_load_lds_dwordx4 v78, s[50:51]
	s_mov_b32 m0, s43
	s_nop 0
	global_load_lds_dwordx4 v79, s[50:51]
	s_waitcnt vmcnt(9)
	v_add_u32_e32 v54, s99, v59
	v_add_u32_e32 v55, s99, v60
	v_add_u32_e32 v56, s99, v61
	v_add_u32_e32 v57, s99, v62
	ds_read_b64_tr_b4 v[50:51], v160 offset:128
	ds_read_b64_tr_b4 v[52:53], v160 offset:1152
	ds_read_b64_tr_b4 v[130:131], v54
	ds_read_b64_tr_b4 v[132:133], v55
	ds_read_b64_tr_b4 v[134:135], v56
	ds_read_b64_tr_b4 v[136:137], v57
	s_waitcnt lgkmcnt(13)
	s_waitcnt vmcnt(36) lgkmcnt(15)
; #define LAS __attribute__((address_space(3)))
; #define TR4(p_) __builtin_amdgcn_ds_read_tr4_b64_v2i32((LAS v2i*)(p_))
; __device__ __forceinline__ void peer_v_tokens(int j, const LAS unsigned short* EL, const LAS unsigned char* AL  , const LAS float* ASC  , const LAS int* SAL  , ...
;     ...
;             for (int tp = 0; tp < 2; ++tp) {
;                 const v2i ao = TR4(ATL + (2 * q + tp) * 128 + 8 * s16), ah = TR4(ATL + 1024 + (2 * q + tp) * 128 + 8 * s16);
; #pragma unroll
;                 for (int r = 0; r < 4; ++r) {
;                     const v2i d = TR4(ldsb + BUF[st % 3] + 2048 * tp + roff[r]);
;                     accH[r] = __builtin_amdgcn_sdot8(d.x, ah.x, accH[r], false); accH[r] = __builtin_amdgcn_sdot8(d.y, ah.y, accH[r], false);
;                     accL[r] = __builtin_amdgcn_sdot8(d.x, ao.x, accL[r], false); accL[r] = __builtin_amdgcn_sdot8(d.y, ao.y, accL[r], false);
;                 }
;             }
;     ...
;         {
;             float4 v[4]; float ss = 0.f;
; #pragma unroll
;             for (int jq = 0; jq < 4; ++jq) { typedef unsigned u2v __attribute__((ext_vector_type(2))); const u2v pw = *(const LAS u2v*)(STASH + 4 * lane + 256 * jq); const uint2 hw = hv[jq];
;                 v[jq] = make_float4(__uint_as_float(hw.x << 16) + __uint_as_float(pw.x << 16), __uint_as_float(hw.x & 0xffff0000u) + __uint_as_float(pw.x & 0xffff0000u),
;                                     __uint_as_float(hw.y << 16) + __uint_as_float(pw.y << 16), __uint_as_float(hw.y & 0xffff0000u) + __uint_as_float(pw.y & 0xffff0000u));
;                 ss += v[jq].x * v[jq].x + v[jq].y * v[jq].y + v[jq].z * v[jq].z + v[jq].w * v[jq].w; }
;             ss = wave_sum(ss);
;             const float r3 = rsqrtf(ss * (1.f / D) + EPS);
	v_lshlrev_b32_e32 v236, 16, v194
	v_and_b32_e32 v237, 0xffff0000, v194
	v_lshlrev_b32_e32 v142, 16, v202
	v_and_b32_e32 v143, 0xffff0000, v202
	v_add_f32_e32 v236, v236, v142
	v_add_f32_e32 v237, v237, v143
	v_lshlrev_b32_e32 v238, 16, v195
	v_and_b32_e32 v239, 0xffff0000, v195
	v_lshlrev_b32_e32 v142, 16, v203
	v_and_b32_e32 v143, 0xffff0000, v203
	v_add_f32_e32 v238, v238, v142
	v_add_f32_e32 v239, v239, v143
	v_lshlrev_b32_e32 v240, 16, v196
	v_and_b32_e32 v241, 0xffff0000, v196
	v_lshlrev_b32_e32 v142, 16, v204
	v_and_b32_e32 v143, 0xffff0000, v204
	v_add_f32_e32 v240, v240, v142
	v_add_f32_e32 v241, v241, v143
	v_lshlrev_b32_e32 v242, 16, v197
	v_and_b32_e32 v243, 0xffff0000, v197
	v_lshlrev_b32_e32 v142, 16, v205
	v_and_b32_e32 v143, 0xffff0000, v205
	v_add_f32_e32 v242, v242, v142
	v_add_f32_e32 v243, v243, v143
	v_lshlrev_b32_e32 v244, 16, v198
	v_and_b32_e32 v245, 0xffff0000, v198
	v_lshlrev_b32_e32 v142, 16, v206
	v_and_b32_e32 v143, 0xffff0000, v206
	v_add_f32_e32 v244, v244, v142
	v_add_f32_e32 v245, v245, v143
	v_lshlrev_b32_e32 v246, 16, v199
	v_and_b32_e32 v247, 0xffff0000, v199
	v_lshlrev_b32_e32 v142, 16, v207
	v_and_b32_e32 v143, 0xffff0000, v207
	v_add_f32_e32 v246, v246, v142
	v_add_f32_e32 v247, v247, v143
	v_lshlrev_b32_e32 v248, 16, v200
	v_and_b32_e32 v249, 0xffff0000, v200
	v_lshlrev_b32_e32 v142, 16, v208
	v_and_b32_e32 v143, 0xffff0000, v208
	v_add_f32_e32 v248, v248, v142
	v_add_f32_e32 v249, v249, v143
	v_lshlrev_b32_e32 v250, 16, v201
	v_and_b32_e32 v251, 0xffff0000, v201
	v_lshlrev_b32_e32 v142, 16, v209
	v_and_b32_e32 v143, 0xffff0000, v209
	v_add_f32_e32 v250, v250, v142
	v_add_f32_e32 v251, v251, v143
	v_mov_b32_e32 v144, 0
	v_mul_f32_e32 v145, v236, v236
	v_fmac_f32_e32 v145, v237, v237
	v_fmac_f32_e32 v145, v238, v238
	v_fmac_f32_e32 v145, v239, v239
	v_add_f32_e32 v144, v144, v145
	v_mul_f32_e32 v145, v240, v240
	v_fmac_f32_e32 v145, v241, v241
	v_fmac_f32_e32 v145, v242, v242
	v_fmac_f32_e32 v145, v243, v243
	v_add_f32_e32 v144, v144, v145
	v_mul_f32_e32 v145, v244, v244
	v_fmac_f32_e32 v145, v245, v245
	v_fmac_f32_e32 v145, v246, v246
	v_fmac_f32_e32 v145, v247, v247
	v_add_f32_e32 v144, v144, v145
	v_mul_f32_e32 v145, v248, v248
	v_fmac_f32_e32 v145, v249, v249
	v_fmac_f32_e32 v145, v250, v250
	v_fmac_f32_e32 v145, v251, v251
	v_add_f32_e32 v144, v144, v145
	s_nop 1
	v_add_f32_dpp v144, v144, v144 quad_perm:[1,0,3,2] row_mask:0xf bank_mask:0xf bound_ctrl:1
	s_nop 1
	v_add_f32_dpp v144, v144, v144 quad_perm:[2,3,0,1] row_mask:0xf bank_mask:0xf bound_ctrl:1
	s_nop 1
	v_add_f32_dpp v144, v144, v144 row_half_mirror row_mask:0xf bank_mask:0xf bound_ctrl:1
	s_nop 1
	v_add_f32_dpp v144, v144, v144 row_mirror row_mask:0xf bank_mask:0xf bound_ctrl:1
	s_nop 1
	v_readlane_b32 s10, v144, 0
	v_readlane_b32 s11, v144, 16
	v_readlane_b32 s14, v144, 32
	v_readlane_b32 s15, v144, 48
	s_nop 3
	v_mov_b32_e32 v144, s11
	v_mov_b32_e32 v145, s15
	v_add_f32_e32 v144, s10, v144
	v_add_f32_e32 v145, s14, v145
	v_add_f32_e32 v144, v144, v145
	v_fmamk_f32 v144, v144, 0x3a800000, v111
	v_rsq_f32_e32 v144, v144
	s_nop 0
	v_mul_f32_e32 v236, v236, v144
	v_mul_f32_e32 v237, v237, v144
	v_mul_f32_e32 v238, v238, v144
	v_mul_f32_e32 v239, v239, v144
	v_mul_f32_e32 v240, v240, v144
	v_mul_f32_e32 v241, v241, v144
	v_mul_f32_e32 v242, v242, v144
	v_mul_f32_e32 v243, v243, v144
	v_mul_f32_e32 v244, v244, v144
	v_mul_f32_e32 v245, v245, v144
	v_mul_f32_e32 v246, v246, v144
	v_mul_f32_e32 v247, v247, v144
	v_mul_f32_e32 v248, v248, v144
	v_mul_f32_e32 v249, v249, v144
	v_mul_f32_e32 v250, v250, v144
	v_mul_f32_e32 v251, v251, v144
	v_dot8c_i32_i4_e32 v38, v122, v48
	v_dot8c_i32_i4_e32 v39, v122, v46
	v_dot8c_i32_i4_e32 v40, v124, v48
	v_dot8c_i32_i4_e32 v41, v124, v46
	v_dot8c_i32_i4_e32 v42, v126, v48
	v_dot8c_i32_i4_e32 v43, v126, v46
	v_dot8c_i32_i4_e32 v44, v128, v48
	v_dot8c_i32_i4_e32 v45, v128, v46
	v_dot8c_i32_i4_e32 v38, v123, v49
	v_dot8c_i32_i4_e32 v39, v123, v47
	v_dot8c_i32_i4_e32 v40, v125, v49
	v_dot8c_i32_i4_e32 v41, v125, v47
	v_dot8c_i32_i4_e32 v42, v127, v49
	v_dot8c_i32_i4_e32 v43, v127, v47
	v_dot8c_i32_i4_e32 v44, v129, v49
	v_dot8c_i32_i4_e32 v45, v129, v47
	v_and_b32_e32 v78, 0xffff, v24
	v_lshrrev_b32_e32 v79, 16, v24
	v_lshl_add_u32 v78, v78, 7, v150
	v_lshl_add_u32 v79, v79, 7, v151
	s_mov_b32 m0, s98
	s_add_i32 s43, s98, 0x400
	global_load_lds_dwordx4 v78, s[50:51]
	s_mov_b32 m0, s43
	s_nop 0
	global_load_lds_dwordx4 v79, s[50:51]
	s_waitcnt vmcnt(9)
	v_add_u32_e32 v54, s76, v59
	v_add_u32_e32 v55, s76, v60
	v_add_u32_e32 v56, s76, v61
	v_add_u32_e32 v57, s76, v62
	ds_read_b64_tr_b4 v[46:47], v160 offset:256
	ds_read_b64_tr_b4 v[48:49], v160 offset:1280
	ds_read_b64_tr_b4 v[122:123], v54
	ds_read_b64_tr_b4 v[124:125], v55
	ds_read_b64_tr_b4 v[126:127], v56
	ds_read_b64_tr_b4 v[128:129], v57
	s_waitcnt lgkmcnt(6)
	v_dot8c_i32_i4_e32 v38, v130, v52
	v_dot8c_i32_i4_e32 v39, v130, v50
	v_dot8c_i32_i4_e32 v40, v132, v52
	v_dot8c_i32_i4_e32 v41, v132, v50
	v_dot8c_i32_i4_e32 v42, v134, v52
	v_dot8c_i32_i4_e32 v43, v134, v50
	v_dot8c_i32_i4_e32 v44, v136, v52
	v_dot8c_i32_i4_e32 v45, v136, v50
	v_dot8c_i32_i4_e32 v38, v131, v53
	v_dot8c_i32_i4_e32 v39, v131, v51
	v_dot8c_i32_i4_e32 v40, v133, v53
	v_dot8c_i32_i4_e32 v41, v133, v51
	v_dot8c_i32_i4_e32 v42, v135, v53
	v_dot8c_i32_i4_e32 v43, v135, v51
	v_dot8c_i32_i4_e32 v44, v137, v53
	v_dot8c_i32_i4_e32 v45, v137, v51
	v_and_b32_e32 v78, 0xffff, v25
	v_lshrrev_b32_e32 v79, 16, v25
	v_lshl_add_u32 v78, v78, 7, v150
	v_lshl_add_u32 v79, v79, 7, v151
	s_mov_b32 m0, s99
	s_add_i32 s43, s99, 0x400
	global_load_lds_dwordx4 v78, s[50:51]
	s_mov_b32 m0, s43
	s_nop 0
	global_load_lds_dwordx4 v79, s[50:51]
	s_waitcnt vmcnt(9)
; #define LAS __attribute__((address_space(3)))
; #define TR4(p_) __builtin_amdgcn_ds_read_tr4_b64_v2i32((LAS v2i*)(p_))
; __device__ __forceinline__ void peer_v_tokens(int j, const LAS unsigned short* EL, const LAS unsigned char* AL  , const LAS float* ASC  , const LAS int* SAL  , ...
;     ...
; #pragma unroll
;         for (int m = 0; m < 2; ++m) {
;             const int idx = lane + 64 * m, tau = idx >> 4, sr = idx & 15, k = 16 * (sr & 7) + 2 * tau + (sr >> 3);
;             const int aq = (int)*(const LAS signed char*)(AL + tl * 128 + k); const int tq = aq + 8;
;             const unsigned lo = (((unsigned)tq & 15u) ^ 8u) * 0x11111111u, hi = ((unsigned)(tq >> 4) & 15u) * 0x11111111u;
;             typedef unsigned u2v __attribute__((ext_vector_type(2)));
;             u2v l2; l2.x = lo; l2.y = lo; u2v h2; h2.x = hi; h2.y = hi;
;             *(LAS u2v*)(ATL + 8 * idx) = l2; *(LAS u2v*)(ATL + 1024 + 8 * idx) = h2;
;         }
;     ...
;         for (int st = 0; st < 16; ++st) {
;             const int p = st >> 2, q = st & 3;
;             if (st < 14) VDMA(st + 2, (st + 2) % 3);
;             if (st < 14) asm volatile("s_waitcnt vmcnt(8)" ::: "memory");
;             else if (st == 14) asm volatile("s_waitcnt vmcnt(4)" ::: "memory");
;             else asm volatile("s_waitcnt vmcnt(0)" ::: "memory");
;             if (q == 0) {
; #pragma unroll
;                 for (int r = 0; r < 4; ++r) { accH[r] = 0; accL[r] = 0; } }
; #pragma unroll
;             for (int tp = 0; tp < 2; ++tp) {
;                 const v2i ao = TR4(ATL + (2 * q + tp) * 128 + 8 * s16), ah = TR4(ATL + 1024 + (2 * q + tp) * 128 + 8 * s16);
; #pragma unroll
;                 for (int r = 0; r < 4; ++r) {
;                     const v2i d = TR4(ldsb + BUF[st % 3] + 2048 * tp + roff[r]);
;                     accH[r] = __builtin_amdgcn_sdot8(d.x, ah.x, accH[r], false); accH[r] = __builtin_amdgcn_sdot8(d.y, ah.y, accH[r], false);
;                     accL[r] = __builtin_amdgcn_sdot8(d.x, ao.x, accL[r], false); accL[r] = __builtin_amdgcn_sdot8(d.y, ao.y, accL[r], false);
;                 }
;             }
;             asm volatile("s_waitcnt lgkmcnt(0)" ::: "memory");
	v_add_u32_e32 v54, s77, v59
	v_add_u32_e32 v55, s77, v60
	v_add_u32_e32 v56, s77, v61
	v_add_u32_e32 v57, s77, v62
	ds_read_b64_tr_b4 v[50:51], v160 offset:384
	ds_read_b64_tr_b4 v[52:53], v160 offset:1408
	ds_read_b64_tr_b4 v[130:131], v54
	ds_read_b64_tr_b4 v[132:133], v55
	ds_read_b64_tr_b4 v[134:135], v56
	ds_read_b64_tr_b4 v[136:137], v57
	s_waitcnt lgkmcnt(6)
	v_dot8c_i32_i4_e32 v38, v122, v48
	v_dot8c_i32_i4_e32 v39, v122, v46
	v_dot8c_i32_i4_e32 v40, v124, v48
	v_dot8c_i32_i4_e32 v41, v124, v46
	v_dot8c_i32_i4_e32 v42, v126, v48
	v_dot8c_i32_i4_e32 v43, v126, v46
	v_dot8c_i32_i4_e32 v44, v128, v48
	v_dot8c_i32_i4_e32 v45, v128, v46
	v_dot8c_i32_i4_e32 v38, v123, v49
	v_dot8c_i32_i4_e32 v39, v123, v47
	v_dot8c_i32_i4_e32 v40, v125, v49
	v_dot8c_i32_i4_e32 v41, v125, v47
	v_dot8c_i32_i4_e32 v42, v127, v49
	v_dot8c_i32_i4_e32 v43, v127, v47
	v_dot8c_i32_i4_e32 v44, v129, v49
	v_dot8c_i32_i4_e32 v45, v129, v47
	s_waitcnt lgkmcnt(15)
	v_and_b32_e32 v78, 0xffff, v26
	v_lshrrev_b32_e32 v79, 16, v26
	v_lshl_add_u32 v78, v78, 7, v150
	v_lshl_add_u32 v79, v79, 7, v151
	s_mov_b32 m0, s76
	s_add_i32 s43, s76, 0x400
	global_load_lds_dwordx4 v78, s[50:51]
	s_mov_b32 m0, s43
	s_nop 0
	global_load_lds_dwordx4 v79, s[50:51]
	s_waitcnt vmcnt(9)
	v_add_u32_e32 v54, s78, v59
	v_add_u32_e32 v55, s78, v60
	v_add_u32_e32 v56, s78, v61
	v_add_u32_e32 v57, s78, v62
	ds_read_b64_tr_b4 v[46:47], v160 offset:512
	ds_read_b64_tr_b4 v[48:49], v160 offset:1536
	ds_read_b64_tr_b4 v[122:123], v54
	ds_read_b64_tr_b4 v[124:125], v55
	ds_read_b64_tr_b4 v[126:127], v56
	ds_read_b64_tr_b4 v[128:129], v57
	s_waitcnt lgkmcnt(6)
	v_dot8c_i32_i4_e32 v38, v130, v52
	v_dot8c_i32_i4_e32 v39, v130, v50
	v_dot8c_i32_i4_e32 v40, v132, v52
	v_dot8c_i32_i4_e32 v41, v132, v50
	v_dot8c_i32_i4_e32 v42, v134, v52
	v_dot8c_i32_i4_e32 v43, v134, v50
	v_dot8c_i32_i4_e32 v44, v136, v52
	v_dot8c_i32_i4_e32 v45, v136, v50
	v_dot8c_i32_i4_e32 v38, v131, v53
	v_dot8c_i32_i4_e32 v39, v131, v51
	v_dot8c_i32_i4_e32 v40, v133, v53
	v_dot8c_i32_i4_e32 v41, v133, v51
	v_dot8c_i32_i4_e32 v42, v135, v53
	v_dot8c_i32_i4_e32 v43, v135, v51
	v_dot8c_i32_i4_e32 v44, v137, v53
	v_dot8c_i32_i4_e32 v45, v137, v51
	v_and_b32_e32 v78, 0xffff, v27
	v_lshrrev_b32_e32 v79, 16, v27
	v_lshl_add_u32 v78, v78, 7, v150
	v_lshl_add_u32 v79, v79, 7, v151
	s_mov_b32 m0, s77
	s_add_i32 s43, s77, 0x400
	global_load_lds_dwordx4 v78, s[50:51]
	s_mov_b32 m0, s43
	s_nop 0
	global_load_lds_dwordx4 v79, s[50:51]
	s_waitcnt vmcnt(8)
	v_add_u32_e32 v54, s79, v59
	v_add_u32_e32 v55, s79, v60
	v_add_u32_e32 v56, s79, v61
	v_add_u32_e32 v57, s79, v62
	ds_read_b64_tr_b4 v[50:51], v160 offset:640
	ds_read_b64_tr_b4 v[52:53], v160 offset:1664
	ds_read_b64_tr_b4 v[130:131], v54
	ds_read_b64_tr_b4 v[132:133], v55
	ds_read_b64_tr_b4 v[134:135], v56
	ds_read_b64_tr_b4 v[136:137], v57
	s_waitcnt lgkmcnt(6)
	v_dot8c_i32_i4_e32 v38, v122, v48
	v_dot8c_i32_i4_e32 v39, v122, v46
	v_dot8c_i32_i4_e32 v40, v124, v48
	v_dot8c_i32_i4_e32 v41, v124, v46
	v_dot8c_i32_i4_e32 v42, v126, v48
	v_dot8c_i32_i4_e32 v43, v126, v46
	v_dot8c_i32_i4_e32 v44, v128, v48
	v_dot8c_i32_i4_e32 v45, v128, v46
	v_dot8c_i32_i4_e32 v38, v123, v49
	v_dot8c_i32_i4_e32 v39, v123, v47
	v_dot8c_i32_i4_e32 v40, v125, v49
	v_dot8c_i32_i4_e32 v41, v125, v47
	v_dot8c_i32_i4_e32 v42, v127, v49
	v_dot8c_i32_i4_e32 v43, v127, v47
	v_dot8c_i32_i4_e32 v44, v129, v49
	v_dot8c_i32_i4_e32 v45, v129, v47
	s_waitcnt lgkmcnt(15)
	v_add_u32_e32 v143, 8, v139
	v_and_b32_e32 v142, 15, v143
	v_xor_b32_e32 v142, 8, v142
	v_bfe_u32 v144, v143, 4, 4
	v_mul_lo_u32 v142, v142, s92
	v_mul_lo_u32 v144, v144, s92
	v_mov_b32_e32 v143, v142
	v_mov_b32_e32 v145, v144
	ds_write2st64_b64 v159, v[142:143], v[144:145] offset1:2
	v_and_b32_e32 v78, 0xffff, v28
	v_lshrrev_b32_e32 v79, 16, v28
	v_lshl_add_u32 v78, v78, 7, v150
	v_lshl_add_u32 v79, v79, 7, v151
	s_mov_b32 m0, s78
	s_add_i32 s43, s78, 0x400
	global_load_lds_dwordx4 v78, s[50:51]
	s_mov_b32 m0, s43
	s_nop 0
	global_load_lds_dwordx4 v79, s[50:51]
	s_waitcnt vmcnt(8)
	v_add_u32_e32 v54, s98, v59
	v_add_u32_e32 v55, s98, v60
	v_add_u32_e32 v56, s98, v61
	v_add_u32_e32 v57, s98, v62
	ds_read_b64_tr_b4 v[46:47], v160 offset:768
	ds_read_b64_tr_b4 v[48:49], v160 offset:1792
	ds_read_b64_tr_b4 v[122:123], v54
	ds_read_b64_tr_b4 v[124:125], v55
	ds_read_b64_tr_b4 v[126:127], v56
	ds_read_b64_tr_b4 v[128:129], v57
	s_waitcnt lgkmcnt(7)
	v_dot8c_i32_i4_e32 v38, v130, v52
	v_dot8c_i32_i4_e32 v39, v130, v50
	v_dot8c_i32_i4_e32 v40, v132, v52
	v_dot8c_i32_i4_e32 v41, v132, v50
	v_dot8c_i32_i4_e32 v42, v134, v52
	v_dot8c_i32_i4_e32 v43, v134, v50
	v_dot8c_i32_i4_e32 v44, v136, v52
	v_dot8c_i32_i4_e32 v45, v136, v50
	v_dot8c_i32_i4_e32 v38, v131, v53
	v_dot8c_i32_i4_e32 v39, v131, v51
	v_dot8c_i32_i4_e32 v40, v133, v53
	v_dot8c_i32_i4_e32 v41, v133, v51
	v_dot8c_i32_i4_e32 v42, v135, v53
	v_dot8c_i32_i4_e32 v43, v135, v51
	v_dot8c_i32_i4_e32 v44, v137, v53
	v_dot8c_i32_i4_e32 v45, v137, v51
	v_and_b32_e32 v78, 0xffff, v29
	v_lshrrev_b32_e32 v79, 16, v29
	v_lshl_add_u32 v78, v78, 7, v150
	v_lshl_add_u32 v79, v79, 7, v151
	s_mov_b32 m0, s79
	s_add_i32 s43, s79, 0x400
	global_load_lds_dwordx4 v78, s[50:51]
	s_mov_b32 m0, s43
	s_nop 0
	global_load_lds_dwordx4 v79, s[50:51]
	s_waitcnt vmcnt(8)
	v_add_u32_e32 v54, s99, v59
	v_add_u32_e32 v55, s99, v60
	v_add_u32_e32 v56, s99, v61
	v_add_u32_e32 v57, s99, v62
	ds_read_b64_tr_b4 v[50:51], v160 offset:896
	ds_read_b64_tr_b4 v[52:53], v160 offset:1920
	ds_read_b64_tr_b4 v[130:131], v54
	ds_read_b64_tr_b4 v[132:133], v55
	ds_read_b64_tr_b4 v[134:135], v56
	ds_read_b64_tr_b4 v[136:137], v57
	s_waitcnt lgkmcnt(6)
; __device__ __forceinline__ bf16 f2bf(float f) { return (bf16)f2bfu(f); }
; #define TR4(p_) __builtin_amdgcn_ds_read_tr4_b64_v2i32((LAS v2i*)(p_))
; __device__ __forceinline__ void peer_v_tokens(int j, const LAS unsigned short* EL, const LAS unsigned char* AL  , const LAS float* ASC  , const LAS int* SAL  , ...
;     ...
;         for (int st = 0; st < 16; ++st) {
;             const int p = st >> 2, q = st & 3;
;             if (st < 14) VDMA(st + 2, (st + 2) % 3);
;             if (st < 14) asm volatile("s_waitcnt vmcnt(8)" ::: "memory");
;             else if (st == 14) asm volatile("s_waitcnt vmcnt(4)" ::: "memory");
;             else asm volatile("s_waitcnt vmcnt(0)" ::: "memory");
;             if (q == 0) {
; #pragma unroll
;                 for (int r = 0; r < 4; ++r) { accH[r] = 0; accL[r] = 0; } }
; #pragma unroll
;             for (int tp = 0; tp < 2; ++tp) {
;                 const v2i ao = TR4(ATL + (2 * q + tp) * 128 + 8 * s16), ah = TR4(ATL + 1024 + (2 * q + tp) * 128 + 8 * s16);
; #pragma unroll
;                 for (int r = 0; r < 4; ++r) {
;                     const v2i d = TR4(ldsb + BUF[st % 3] + 2048 * tp + roff[r]);
;                     accH[r] = __builtin_amdgcn_sdot8(d.x, ah.x, accH[r], false); accH[r] = __builtin_amdgcn_sdot8(d.y, ah.y, accH[r], false);
;                     accL[r] = __builtin_amdgcn_sdot8(d.x, ao.x, accL[r], false); accL[r] = __builtin_amdgcn_sdot8(d.y, ao.y, accL[r], false);
;                 }
;             }
;             asm volatile("s_waitcnt lgkmcnt(0)" ::: "memory");
;             if (q == 3) {
; #pragma unroll
;                 for (int r = 0; r < 4; ++r) STASH[256 * p + 16 * (grp + 4 * r) + pc] = f2bf(asc * (float)(2 * ((accH[r] << 4) + accL[r]) + sa));
;             }
;         }
;     ...
;             float4* op = (float4*)(outp + (size_t)t * D) + lane;
; #pragma unroll
;             for (int jq = 0; jq < 4; ++jq) { typedef float f4v __attribute__((ext_vector_type(4))); f4v o4; o4.x = v[jq].x * r3 * gv[jq].x; o4.y = v[jq].y * r3 * gv[jq].y; o4.z = v[jq].z * r3 * gv[jq].z; o4.w = v[jq].w * r3 * gv[jq].w;
;                 __builtin_nontemporal_store(o4, (f4v*)op + 64 * jq); }
	v_dot8c_i32_i4_e32 v38, v122, v48
	v_dot8c_i32_i4_e32 v39, v122, v46
	v_dot8c_i32_i4_e32 v40, v124, v48
	v_dot8c_i32_i4_e32 v41, v124, v46
	v_dot8c_i32_i4_e32 v42, v126, v48
	v_dot8c_i32_i4_e32 v43, v126, v46
	v_dot8c_i32_i4_e32 v44, v128, v48
	v_dot8c_i32_i4_e32 v45, v128, v46
	v_dot8c_i32_i4_e32 v38, v123, v49
	v_dot8c_i32_i4_e32 v39, v123, v47
	v_dot8c_i32_i4_e32 v40, v125, v49
	v_dot8c_i32_i4_e32 v41, v125, v47
	v_dot8c_i32_i4_e32 v42, v127, v49
	v_dot8c_i32_i4_e32 v43, v127, v47
	v_dot8c_i32_i4_e32 v44, v129, v49
	v_dot8c_i32_i4_e32 v45, v129, v47
	v_and_b32_e32 v78, 0xffff, v30
	v_lshrrev_b32_e32 v79, 16, v30
	v_lshl_add_u32 v78, v78, 7, v150
	v_lshl_add_u32 v79, v79, 7, v151
	s_mov_b32 m0, s98
	s_add_i32 s43, s98, 0x400
	global_load_lds_dwordx4 v78, s[50:51]
	s_mov_b32 m0, s43
	s_nop 0
	global_load_lds_dwordx4 v79, s[50:51]
	s_waitcnt vmcnt(8)
	v_add_u32_e32 v54, s76, v59
	v_add_u32_e32 v55, s76, v60
	v_add_u32_e32 v56, s76, v61
	v_add_u32_e32 v57, s76, v62
	ds_read_b64_tr_b4 v[46:47], v160
	ds_read_b64_tr_b4 v[48:49], v160 offset:1024
	ds_read_b64_tr_b4 v[122:123], v54
	ds_read_b64_tr_b4 v[124:125], v55
	ds_read_b64_tr_b4 v[126:127], v56
	ds_read_b64_tr_b4 v[128:129], v57
	s_waitcnt lgkmcnt(6)
	v_dot8c_i32_i4_e32 v38, v130, v52
	v_dot8c_i32_i4_e32 v39, v130, v50
	v_dot8c_i32_i4_e32 v40, v132, v52
	v_dot8c_i32_i4_e32 v41, v132, v50
	v_dot8c_i32_i4_e32 v42, v134, v52
	v_dot8c_i32_i4_e32 v43, v134, v50
	v_dot8c_i32_i4_e32 v44, v136, v52
	v_dot8c_i32_i4_e32 v45, v136, v50
	v_dot8c_i32_i4_e32 v38, v131, v53
	v_dot8c_i32_i4_e32 v39, v131, v51
	v_dot8c_i32_i4_e32 v40, v133, v53
	v_dot8c_i32_i4_e32 v41, v133, v51
	v_dot8c_i32_i4_e32 v42, v135, v53
	v_dot8c_i32_i4_e32 v43, v135, v51
	v_dot8c_i32_i4_e32 v44, v137, v53
	v_dot8c_i32_i4_e32 v45, v137, v51
	s_nop 3
	s_waitcnt lgkmcnt(15)
	v_lshlrev_b32_e32 v38, 5, v38
	v_lshlrev_b32_e32 v39, 1, v39
	v_add3_u32 v38, v39, v229, v38
	v_cvt_f32_i32_e32 v38, v38
	v_mul_f32_e32 v38, v228, v38
	v_lshlrev_b32_e32 v40, 5, v40
	v_lshlrev_b32_e32 v41, 1, v41
	v_add3_u32 v40, v41, v229, v40
	v_cvt_f32_i32_e32 v40, v40
	v_mul_f32_e32 v40, v228, v40
	v_lshlrev_b32_e32 v42, 5, v42
	v_lshlrev_b32_e32 v43, 1, v43
	v_add3_u32 v42, v43, v229, v42
	v_cvt_f32_i32_e32 v42, v42
	v_mul_f32_e32 v42, v228, v42
	v_lshlrev_b32_e32 v44, 5, v44
	v_lshlrev_b32_e32 v45, 1, v45
	v_add3_u32 v44, v45, v229, v44
	v_cvt_f32_i32_e32 v44, v44
	v_mul_f32_e32 v44, v228, v44
	v_cvt_pk_bf16_f32 v166, v38, v40
	v_cvt_pk_bf16_f32 v167, v42, v44
	ds_read_b128 v[252:255], v156 offset:1024
	s_add_i32 s44, s40, 16
	s_ashr_i32 s45, s44, 31
	s_lshl_b64 s[44:45], s[44:45], 12
	v_lshl_add_u64 v[80:81], v[36:37], 0, s[44:45]
	s_waitcnt lgkmcnt(0)
	v_mul_f32_e32 v222, v222, v252
	v_mul_f32_e32 v223, v223, v253
	v_mul_f32_e32 v224, v224, v254
	v_mul_f32_e32 v225, v225, v255
	global_store_dwordx4 v[80:81], v[222:225], off offset:3072 nt
	ds_read_b128 v[252:255], v155
	s_add_i32 s44, s40, 24
	s_ashr_i32 s45, s44, 31
	s_lshl_b64 s[44:45], s[44:45], 12
	v_lshl_add_u64 v[80:81], v[36:37], 0, s[44:45]
	s_waitcnt lgkmcnt(0)
	v_mul_f32_e32 v236, v236, v252
	v_mul_f32_e32 v237, v237, v253
	v_mul_f32_e32 v238, v238, v254
	v_mul_f32_e32 v239, v239, v255
	global_store_dwordx4 v[80:81], v[236:239], off nt
	v_add_u32_e32 v147, 8, v140
	v_and_b32_e32 v146, 15, v147
	v_xor_b32_e32 v146, 8, v146
	v_bfe_u32 v148, v147, 4, 4
	v_mul_lo_u32 v146, v146, s92
	v_mul_lo_u32 v148, v148, s92
	v_mov_b32_e32 v147, v146
	v_mov_b32_e32 v149, v148
	ds_write2st64_b64 v77, v[146:147], v[148:149] offset1:2
	v_add_u32_e32 v138, 0x1000, v74
	ds_read_u8 v139, v138
	v_add_u32_e32 v141, 0x1000, v73
	ds_read_u8 v140, v141
	s_add_i32 s43, s67, 160
	v_mov_b32_e32 v138, s43
	ds_read2st64_b32 v[228:229], v138 offset1:1
	ds_read_b128 v[18:21], v227 offset:8192
	ds_read_b128 v[22:25], v227 offset:8208
	v_add_u32_e32 v152, 0x600000, v63
	v_add_u32_e32 v153, 0x600000, v64
	v_mov_b32_e32 v38, 0
	v_mov_b32_e32 v39, 0
	v_mov_b32_e32 v40, 0
	v_mov_b32_e32 v41, 0
	v_mov_b32_e32 v42, 0
	v_mov_b32_e32 v43, 0
	v_mov_b32_e32 v44, 0
	v_mov_b32_e32 v45, 0
	v_and_b32_e32 v78, 0xffff, v31
	v_lshrrev_b32_e32 v79, 16, v31
	v_lshl_add_u32 v78, v78, 7, v150
	v_lshl_add_u32 v79, v79, 7, v151
	s_mov_b32 m0, s99
	s_add_i32 s43, s99, 0x400
	global_load_lds_dwordx4 v78, s[50:51]
	s_mov_b32 m0, s43
	s_nop 0
	global_load_lds_dwordx4 v79, s[50:51]
	s_waitcnt vmcnt(10)
	v_add_u32_e32 v54, s77, v59
	v_add_u32_e32 v55, s77, v60
	v_add_u32_e32 v56, s77, v61
	v_add_u32_e32 v57, s77, v62
	ds_read_b64_tr_b4 v[50:51], v160 offset:128
	ds_read_b64_tr_b4 v[52:53], v160 offset:1152
	ds_read_b64_tr_b4 v[130:131], v54
	ds_read_b64_tr_b4 v[132:133], v55
	ds_read_b64_tr_b4 v[134:135], v56
	ds_read_b64_tr_b4 v[136:137], v57
	s_waitcnt lgkmcnt(14)
	v_dot8c_i32_i4_e32 v38, v122, v48
	v_dot8c_i32_i4_e32 v39, v122, v46
	v_dot8c_i32_i4_e32 v40, v124, v48
	v_dot8c_i32_i4_e32 v41, v124, v46
	v_dot8c_i32_i4_e32 v42, v126, v48
	v_dot8c_i32_i4_e32 v43, v126, v46
	v_dot8c_i32_i4_e32 v44, v128, v48
	v_dot8c_i32_i4_e32 v45, v128, v46
	v_dot8c_i32_i4_e32 v38, v123, v49
	v_dot8c_i32_i4_e32 v39, v123, v47
	v_dot8c_i32_i4_e32 v40, v125, v49
	v_dot8c_i32_i4_e32 v41, v125, v47
	v_dot8c_i32_i4_e32 v42, v127, v49
	v_dot8c_i32_i4_e32 v43, v127, v47
	v_dot8c_i32_i4_e32 v44, v129, v49
	v_dot8c_i32_i4_e32 v45, v129, v47
	v_and_b32_e32 v78, 0xffff, v32
	v_lshrrev_b32_e32 v79, 16, v32
	v_lshl_add_u32 v78, v78, 7, v150
	v_lshl_add_u32 v79, v79, 7, v151
	s_mov_b32 m0, s76
	s_add_i32 s43, s76, 0x400
	global_load_lds_dwordx4 v78, s[50:51]
	s_mov_b32 m0, s43
	s_nop 0
	global_load_lds_dwordx4 v79, s[50:51]
	s_waitcnt vmcnt(10)
; #define TR4(p_) __builtin_amdgcn_ds_read_tr4_b64_v2i32((LAS v2i*)(p_))
; #define VDMA(st_, k_) do { _Pragma("unroll") for (int i_ = 0; i_ < 4; ++i_) { \
;         const unsigned off_ = (unsigned)((st_) >> 2) * (16384u * 128u) + (PE_ID(E, 4 * ((st_) & 3) + i_) << 7) + ((i_ & 1) ? cx1 : cx0); \
;         __builtin_amdgcn_global_load_lds((const unsigned*)(V4 + off_), (LAS unsigned*)(ldsb + BUF[k_] + 1024 * i_), 16, 0, 0); } } while (0)
; __device__ __forceinline__ void peer_v_tokens(int j, const LAS unsigned short* EL, const LAS unsigned char* AL  , const LAS float* ASC  , const LAS int* SAL  , ...
;     ...
;         for (int st = 0; st < 16; ++st) {
;             const int p = st >> 2, q = st & 3;
;             if (st < 14) VDMA(st + 2, (st + 2) % 3);
;             if (st < 14) asm volatile("s_waitcnt vmcnt(8)" ::: "memory");
;             else if (st == 14) asm volatile("s_waitcnt vmcnt(4)" ::: "memory");
;             else asm volatile("s_waitcnt vmcnt(0)" ::: "memory");
;             if (q == 0) {
; #pragma unroll
;                 for (int r = 0; r < 4; ++r) { accH[r] = 0; accL[r] = 0; } }
; #pragma unroll
;             for (int tp = 0; tp < 2; ++tp) {
;                 const v2i ao = TR4(ATL + (2 * q + tp) * 128 + 8 * s16), ah = TR4(ATL + 1024 + (2 * q + tp) * 128 + 8 * s16);
; #pragma unroll
;                 for (int r = 0; r < 4; ++r) {
;                     const v2i d = TR4(ldsb + BUF[st % 3] + 2048 * tp + roff[r]);
;                     accH[r] = __builtin_amdgcn_sdot8(d.x, ah.x, accH[r], false); accH[r] = __builtin_amdgcn_sdot8(d.y, ah.y, accH[r], false);
;                     accL[r] = __builtin_amdgcn_sdot8(d.x, ao.x, accL[r], false); accL[r] = __builtin_amdgcn_sdot8(d.y, ao.y, accL[r], false);
;                 }
;             }
;             asm volatile("s_waitcnt lgkmcnt(0)" ::: "memory");
	v_add_u32_e32 v54, s78, v59
	v_add_u32_e32 v55, s78, v60
	v_add_u32_e32 v56, s78, v61
	v_add_u32_e32 v57, s78, v62
	ds_read_b64_tr_b4 v[46:47], v160 offset:256
	ds_read_b64_tr_b4 v[48:49], v160 offset:1280
	ds_read_b64_tr_b4 v[122:123], v54
	ds_read_b64_tr_b4 v[124:125], v55
	ds_read_b64_tr_b4 v[126:127], v56
	ds_read_b64_tr_b4 v[128:129], v57
	s_waitcnt lgkmcnt(6)
	v_dot8c_i32_i4_e32 v38, v130, v52
	v_dot8c_i32_i4_e32 v39, v130, v50
	v_dot8c_i32_i4_e32 v40, v132, v52
	v_dot8c_i32_i4_e32 v41, v132, v50
	v_dot8c_i32_i4_e32 v42, v134, v52
	v_dot8c_i32_i4_e32 v43, v134, v50
	v_dot8c_i32_i4_e32 v44, v136, v52
	v_dot8c_i32_i4_e32 v45, v136, v50
	v_dot8c_i32_i4_e32 v38, v131, v53
	v_dot8c_i32_i4_e32 v39, v131, v51
	v_dot8c_i32_i4_e32 v40, v133, v53
	v_dot8c_i32_i4_e32 v41, v133, v51
	v_dot8c_i32_i4_e32 v42, v135, v53
	v_dot8c_i32_i4_e32 v43, v135, v51
	v_dot8c_i32_i4_e32 v44, v137, v53
	v_dot8c_i32_i4_e32 v45, v137, v51
	v_and_b32_e32 v78, 0xffff, v33
	v_lshrrev_b32_e32 v79, 16, v33
	v_lshl_add_u32 v78, v78, 7, v150
	v_lshl_add_u32 v79, v79, 7, v151
	s_mov_b32 m0, s77
	s_add_i32 s43, s77, 0x400
	global_load_lds_dwordx4 v78, s[50:51]
	s_mov_b32 m0, s43
	s_nop 0
	global_load_lds_dwordx4 v79, s[50:51]
	s_waitcnt vmcnt(10)
	v_add_u32_e32 v54, s79, v59
	v_add_u32_e32 v55, s79, v60
	v_add_u32_e32 v56, s79, v61
	v_add_u32_e32 v57, s79, v62
	ds_read_b64_tr_b4 v[50:51], v160 offset:384
	ds_read_b64_tr_b4 v[52:53], v160 offset:1408
	ds_read_b64_tr_b4 v[130:131], v54
	ds_read_b64_tr_b4 v[132:133], v55
	ds_read_b64_tr_b4 v[134:135], v56
	ds_read_b64_tr_b4 v[136:137], v57
	s_waitcnt lgkmcnt(6)
	v_dot8c_i32_i4_e32 v38, v122, v48
	v_dot8c_i32_i4_e32 v39, v122, v46
	v_dot8c_i32_i4_e32 v40, v124, v48
	v_dot8c_i32_i4_e32 v41, v124, v46
	v_dot8c_i32_i4_e32 v42, v126, v48
	v_dot8c_i32_i4_e32 v43, v126, v46
	v_dot8c_i32_i4_e32 v44, v128, v48
	v_dot8c_i32_i4_e32 v45, v128, v46
	v_dot8c_i32_i4_e32 v38, v123, v49
	v_dot8c_i32_i4_e32 v39, v123, v47
	v_dot8c_i32_i4_e32 v40, v125, v49
	v_dot8c_i32_i4_e32 v41, v125, v47
	v_dot8c_i32_i4_e32 v42, v127, v49
	v_dot8c_i32_i4_e32 v43, v127, v47
	v_dot8c_i32_i4_e32 v44, v129, v49
	v_dot8c_i32_i4_e32 v45, v129, v47
	s_waitcnt lgkmcnt(15)
	v_and_b32_e32 v78, 0xffff, v18
	v_lshrrev_b32_e32 v79, 16, v18
	v_lshl_add_u32 v78, v78, 7, v152
	v_lshl_add_u32 v79, v79, 7, v153
	s_mov_b32 m0, s78
	s_add_i32 s43, s78, 0x400
	global_load_lds_dwordx4 v78, s[50:51]
	s_mov_b32 m0, s43
	s_nop 0
	global_load_lds_dwordx4 v79, s[50:51]
	s_waitcnt vmcnt(10)
	v_add_u32_e32 v54, s98, v59
	v_add_u32_e32 v55, s98, v60
	v_add_u32_e32 v56, s98, v61
	v_add_u32_e32 v57, s98, v62
	ds_read_b64_tr_b4 v[46:47], v160 offset:512
	ds_read_b64_tr_b4 v[48:49], v160 offset:1536
	ds_read_b64_tr_b4 v[122:123], v54
	ds_read_b64_tr_b4 v[124:125], v55
	ds_read_b64_tr_b4 v[126:127], v56
	ds_read_b64_tr_b4 v[128:129], v57
	s_waitcnt lgkmcnt(6)
	v_dot8c_i32_i4_e32 v38, v130, v52
	v_dot8c_i32_i4_e32 v39, v130, v50
	v_dot8c_i32_i4_e32 v40, v132, v52
	v_dot8c_i32_i4_e32 v41, v132, v50
	v_dot8c_i32_i4_e32 v42, v134, v52
	v_dot8c_i32_i4_e32 v43, v134, v50
	v_dot8c_i32_i4_e32 v44, v136, v52
	v_dot8c_i32_i4_e32 v45, v136, v50
	v_dot8c_i32_i4_e32 v38, v131, v53
	v_dot8c_i32_i4_e32 v39, v131, v51
	v_dot8c_i32_i4_e32 v40, v133, v53
	v_dot8c_i32_i4_e32 v41, v133, v51
	v_dot8c_i32_i4_e32 v42, v135, v53
	v_dot8c_i32_i4_e32 v43, v135, v51
	v_dot8c_i32_i4_e32 v44, v137, v53
	v_dot8c_i32_i4_e32 v45, v137, v51
	v_and_b32_e32 v78, 0xffff, v19
	v_lshrrev_b32_e32 v79, 16, v19
	v_lshl_add_u32 v78, v78, 7, v152
	v_lshl_add_u32 v79, v79, 7, v153
	s_mov_b32 m0, s79
	s_add_i32 s43, s79, 0x400
	global_load_lds_dwordx4 v78, s[50:51]
	s_mov_b32 m0, s43
	s_nop 0
	global_load_lds_dwordx4 v79, s[50:51]
	s_waitcnt vmcnt(8)
	v_add_u32_e32 v54, s99, v59
	v_add_u32_e32 v55, s99, v60
	v_add_u32_e32 v56, s99, v61
	v_add_u32_e32 v57, s99, v62
	ds_read_b64_tr_b4 v[50:51], v160 offset:640
	ds_read_b64_tr_b4 v[52:53], v160 offset:1664
	ds_read_b64_tr_b4 v[130:131], v54
	ds_read_b64_tr_b4 v[132:133], v55
	ds_read_b64_tr_b4 v[134:135], v56
	ds_read_b64_tr_b4 v[136:137], v57
	s_waitcnt lgkmcnt(6)
	v_dot8c_i32_i4_e32 v38, v122, v48
	v_dot8c_i32_i4_e32 v39, v122, v46
	v_dot8c_i32_i4_e32 v40, v124, v48
	v_dot8c_i32_i4_e32 v41, v124, v46
	v_dot8c_i32_i4_e32 v42, v126, v48
	v_dot8c_i32_i4_e32 v43, v126, v46
	v_dot8c_i32_i4_e32 v44, v128, v48
	v_dot8c_i32_i4_e32 v45, v128, v46
	v_dot8c_i32_i4_e32 v38, v123, v49
	v_dot8c_i32_i4_e32 v39, v123, v47
	v_dot8c_i32_i4_e32 v40, v125, v49
	v_dot8c_i32_i4_e32 v41, v125, v47
	v_dot8c_i32_i4_e32 v42, v127, v49
	v_dot8c_i32_i4_e32 v43, v127, v47
	v_dot8c_i32_i4_e32 v44, v129, v49
	v_dot8c_i32_i4_e32 v45, v129, v47
	s_waitcnt lgkmcnt(15)
	v_add_u32_e32 v143, 8, v139
	v_and_b32_e32 v142, 15, v143
	v_xor_b32_e32 v142, 8, v142
	v_bfe_u32 v144, v143, 4, 4
	v_mul_lo_u32 v142, v142, s92
	v_mul_lo_u32 v144, v144, s92
	v_mov_b32_e32 v143, v142
	v_mov_b32_e32 v145, v144
	ds_write2st64_b64 v159, v[142:143], v[144:145] offset1:2
	v_and_b32_e32 v78, 0xffff, v20
	v_lshrrev_b32_e32 v79, 16, v20
	v_lshl_add_u32 v78, v78, 7, v152
	v_lshl_add_u32 v79, v79, 7, v153
	s_mov_b32 m0, s98
	s_add_i32 s43, s98, 0x400
	global_load_lds_dwordx4 v78, s[50:51]
	s_mov_b32 m0, s43
	s_nop 0
	global_load_lds_dwordx4 v79, s[50:51]
	s_waitcnt vmcnt(8)
	v_add_u32_e32 v54, s76, v59
	v_add_u32_e32 v55, s76, v60
	v_add_u32_e32 v56, s76, v61
	v_add_u32_e32 v57, s76, v62
	ds_read_b64_tr_b4 v[46:47], v160 offset:768
	ds_read_b64_tr_b4 v[48:49], v160 offset:1792
	ds_read_b64_tr_b4 v[122:123], v54
	ds_read_b64_tr_b4 v[124:125], v55
	ds_read_b64_tr_b4 v[126:127], v56
	ds_read_b64_tr_b4 v[128:129], v57
	s_waitcnt lgkmcnt(7)
; __device__ __forceinline__ void peer_v_tokens(int j, const LAS unsigned short* EL, const LAS unsigned char* AL  , const LAS float* ASC  , const LAS int* SAL  , ...
;     ...
;     for (int it = 0; it < 8; ++it) {
;         const int tl = it * 8 + wave, t = j * 64 + tl;
;         unsigned E[8];
;         { const LAS v4u* ep = (const LAS v4u*)(EL + tl * 128 + 16 * g); const v4u e0 = ep[0], e1 = ep[1];
;           E[0] = e0.x; E[1] = e0.y; E[2] = e0.z; E[3] = e0.w; E[4] = e1.x; E[5] = e1.y; E[6] = e1.z; E[7] = e1.w; }
;         uint2 hv[4]; float4 gv[4];
;         { unsigned ho = (unsigned)t * (D / 4) + (unsigned)lane; asm volatile("" : "+v"(ho)); const uint2* hp = (const uint2*)HB + ho; const float4* gp = (const float4*)fng + lane;
; #pragma unroll
;           for (int jq = 0; jq < 4; ++jq) { hv[jq] = hp[64 * jq]; gv[jq] = gp[64 * jq]; } }
;         VDMA(0, 0); VDMA(1, 1);
; #pragma unroll
;         for (int m = 0; m < 2; ++m) {
;     ...
;         for (int st = 0; st < 16; ++st) {
;             const int p = st >> 2, q = st & 3;
;             if (st < 14) VDMA(st + 2, (st + 2) % 3);
;             if (st < 14) asm volatile("s_waitcnt vmcnt(8)" ::: "memory");
;             else if (st == 14) asm volatile("s_waitcnt vmcnt(4)" ::: "memory");
;             else asm volatile("s_waitcnt vmcnt(0)" ::: "memory");
;             if (q == 0) {
; #pragma unroll
;                 for (int r = 0; r < 4; ++r) { accH[r] = 0; accL[r] = 0; } }
; #pragma unroll
;             for (int tp = 0; tp < 2; ++tp) {
;                 const v2i ao = TR4(ATL + (2 * q + tp) * 128 + 8 * s16), ah = TR4(ATL + 1024 + (2 * q + tp) * 128 + 8 * s16);
; #pragma unroll
;                 for (int r = 0; r < 4; ++r) {
;                     const v2i d = TR4(ldsb + BUF[st % 3] + 2048 * tp + roff[r]);
;                     accH[r] = __builtin_amdgcn_sdot8(d.x, ah.x, accH[r], false); accH[r] = __builtin_amdgcn_sdot8(d.y, ah.y, accH[r], false);
;                     accL[r] = __builtin_amdgcn_sdot8(d.x, ao.x, accL[r], false); accL[r] = __builtin_amdgcn_sdot8(d.y, ao.y, accL[r], false);
;                 }
;             }
;             asm volatile("s_waitcnt lgkmcnt(0)" ::: "memory");
;             if (q == 3) {
; #pragma unroll
;                 for (int r = 0; r < 4; ++r) STASH[256 * p + 16 * (grp + 4 * r) + pc] = f2bf(asc * (float)(2 * ((accH[r] << 4) + accL[r]) + sa));
;             }
;         }
	v_dot8c_i32_i4_e32 v38, v130, v52
	v_dot8c_i32_i4_e32 v39, v130, v50
	v_dot8c_i32_i4_e32 v40, v132, v52
	v_dot8c_i32_i4_e32 v41, v132, v50
	v_dot8c_i32_i4_e32 v42, v134, v52
	v_dot8c_i32_i4_e32 v43, v134, v50
	v_dot8c_i32_i4_e32 v44, v136, v52
	v_dot8c_i32_i4_e32 v45, v136, v50
	v_dot8c_i32_i4_e32 v38, v131, v53
	v_dot8c_i32_i4_e32 v39, v131, v51
	v_dot8c_i32_i4_e32 v40, v133, v53
	v_dot8c_i32_i4_e32 v41, v133, v51
	v_dot8c_i32_i4_e32 v42, v135, v53
	v_dot8c_i32_i4_e32 v43, v135, v51
	v_dot8c_i32_i4_e32 v44, v137, v53
	v_dot8c_i32_i4_e32 v45, v137, v51
	v_and_b32_e32 v78, 0xffff, v21
	v_lshrrev_b32_e32 v79, 16, v21
	v_lshl_add_u32 v78, v78, 7, v152
	v_lshl_add_u32 v79, v79, 7, v153
	s_mov_b32 m0, s99
	s_add_i32 s43, s99, 0x400
	global_load_lds_dwordx4 v78, s[50:51]
	s_mov_b32 m0, s43
	s_nop 0
	global_load_lds_dwordx4 v79, s[50:51]
	s_waitcnt vmcnt(8)
	v_add_u32_e32 v54, s77, v59
	v_add_u32_e32 v55, s77, v60
	v_add_u32_e32 v56, s77, v61
	v_add_u32_e32 v57, s77, v62
	ds_read_b64_tr_b4 v[50:51], v160 offset:896
	ds_read_b64_tr_b4 v[52:53], v160 offset:1920
	ds_read_b64_tr_b4 v[130:131], v54
	ds_read_b64_tr_b4 v[132:133], v55
	ds_read_b64_tr_b4 v[134:135], v56
	ds_read_b64_tr_b4 v[136:137], v57
	s_waitcnt lgkmcnt(6)
	v_dot8c_i32_i4_e32 v38, v122, v48
	v_dot8c_i32_i4_e32 v39, v122, v46
	v_dot8c_i32_i4_e32 v40, v124, v48
	v_dot8c_i32_i4_e32 v41, v124, v46
	v_dot8c_i32_i4_e32 v42, v126, v48
	v_dot8c_i32_i4_e32 v43, v126, v46
	v_dot8c_i32_i4_e32 v44, v128, v48
	v_dot8c_i32_i4_e32 v45, v128, v46
	v_dot8c_i32_i4_e32 v38, v123, v49
	v_dot8c_i32_i4_e32 v39, v123, v47
	v_dot8c_i32_i4_e32 v40, v125, v49
	v_dot8c_i32_i4_e32 v41, v125, v47
	v_dot8c_i32_i4_e32 v42, v127, v49
	v_dot8c_i32_i4_e32 v43, v127, v47
	v_dot8c_i32_i4_e32 v44, v129, v49
	v_dot8c_i32_i4_e32 v45, v129, v47
	v_and_b32_e32 v78, 0xffff, v22
	v_lshrrev_b32_e32 v79, 16, v22
	v_lshl_add_u32 v78, v78, 7, v152
	v_lshl_add_u32 v79, v79, 7, v153
	s_mov_b32 m0, s76
	s_add_i32 s43, s76, 0x400
	global_load_lds_dwordx4 v78, s[50:51]
	s_mov_b32 m0, s43
	s_nop 0
	global_load_lds_dwordx4 v79, s[50:51]
	s_waitcnt vmcnt(8)
	v_add_u32_e32 v54, s78, v59
	v_add_u32_e32 v55, s78, v60
	v_add_u32_e32 v56, s78, v61
	v_add_u32_e32 v57, s78, v62
	ds_read_b64_tr_b4 v[46:47], v160
	ds_read_b64_tr_b4 v[48:49], v160 offset:1024
	ds_read_b64_tr_b4 v[122:123], v54
	ds_read_b64_tr_b4 v[124:125], v55
	ds_read_b64_tr_b4 v[126:127], v56
	ds_read_b64_tr_b4 v[128:129], v57
	s_waitcnt lgkmcnt(6)
	v_dot8c_i32_i4_e32 v38, v130, v52
	v_dot8c_i32_i4_e32 v39, v130, v50
	v_dot8c_i32_i4_e32 v40, v132, v52
	v_dot8c_i32_i4_e32 v41, v132, v50
	v_dot8c_i32_i4_e32 v42, v134, v52
	v_dot8c_i32_i4_e32 v43, v134, v50
	v_dot8c_i32_i4_e32 v44, v136, v52
	v_dot8c_i32_i4_e32 v45, v136, v50
	v_dot8c_i32_i4_e32 v38, v131, v53
	v_dot8c_i32_i4_e32 v39, v131, v51
	v_dot8c_i32_i4_e32 v40, v133, v53
	v_dot8c_i32_i4_e32 v41, v133, v51
	v_dot8c_i32_i4_e32 v42, v135, v53
	v_dot8c_i32_i4_e32 v43, v135, v51
	v_dot8c_i32_i4_e32 v44, v137, v53
	v_dot8c_i32_i4_e32 v45, v137, v51
	s_nop 3
	s_waitcnt lgkmcnt(15)
	v_lshlrev_b32_e32 v38, 5, v38
	v_lshlrev_b32_e32 v39, 1, v39
	v_add3_u32 v38, v39, v229, v38
	v_cvt_f32_i32_e32 v38, v38
	v_mul_f32_e32 v38, v228, v38
	v_lshlrev_b32_e32 v40, 5, v40
	v_lshlrev_b32_e32 v41, 1, v41
	v_add3_u32 v40, v41, v229, v40
	v_cvt_f32_i32_e32 v40, v40
	v_mul_f32_e32 v40, v228, v40
	v_lshlrev_b32_e32 v42, 5, v42
	v_lshlrev_b32_e32 v43, 1, v43
	v_add3_u32 v42, v43, v229, v42
	v_cvt_f32_i32_e32 v42, v42
	v_mul_f32_e32 v42, v228, v42
	v_lshlrev_b32_e32 v44, 5, v44
	v_lshlrev_b32_e32 v45, 1, v45
	v_add3_u32 v44, v45, v229, v44
	v_cvt_f32_i32_e32 v44, v44
	v_mul_f32_e32 v44, v228, v44
	v_cvt_pk_bf16_f32 v174, v38, v40
	v_cvt_pk_bf16_f32 v175, v42, v44
	ds_read_b128 v[252:255], v155 offset:1024
	s_add_i32 s44, s40, 24
	s_ashr_i32 s45, s44, 31
	s_lshl_b64 s[44:45], s[44:45], 12
	v_lshl_add_u64 v[80:81], v[36:37], 0, s[44:45]
	s_waitcnt lgkmcnt(0)
	v_mul_f32_e32 v240, v240, v252
	v_mul_f32_e32 v241, v241, v253
	v_mul_f32_e32 v242, v242, v254
	v_mul_f32_e32 v243, v243, v255
	global_store_dwordx4 v[80:81], v[240:243], off offset:1024 nt
	v_add_u32_e32 v147, 8, v140
	v_and_b32_e32 v146, 15, v147
	v_xor_b32_e32 v146, 8, v146
	v_bfe_u32 v148, v147, 4, 4
	v_mul_lo_u32 v146, v146, s92
	v_mul_lo_u32 v148, v148, s92
	v_mov_b32_e32 v147, v146
	v_mov_b32_e32 v149, v148
	ds_write2st64_b64 v77, v[146:147], v[148:149] offset1:2
	v_add_u32_e32 v138, 0x1400, v74
	ds_read_u8 v139, v138
	v_add_u32_e32 v141, 0x1400, v73
	ds_read_u8 v140, v141
	s_add_i32 s43, s67, 128
	v_mov_b32_e32 v138, s43
	ds_read2st64_b32 v[228:229], v138 offset1:1
	ds_read_b128 v[26:29], v227 offset:10240
	ds_read_b128 v[30:33], v227 offset:10256
	v_mov_b32_e32 v38, 0
	v_mov_b32_e32 v39, 0
	v_mov_b32_e32 v40, 0
	v_mov_b32_e32 v41, 0
	v_mov_b32_e32 v42, 0
	v_mov_b32_e32 v43, 0
	v_mov_b32_e32 v44, 0
	v_mov_b32_e32 v45, 0
	v_and_b32_e32 v78, 0xffff, v23
	v_lshrrev_b32_e32 v79, 16, v23
	v_lshl_add_u32 v78, v78, 7, v152
	v_lshl_add_u32 v79, v79, 7, v153
	s_mov_b32 m0, s77
	s_add_i32 s43, s77, 0x400
	global_load_lds_dwordx4 v78, s[50:51]
	s_mov_b32 m0, s43
	s_nop 0
	global_load_lds_dwordx4 v79, s[50:51]
	s_waitcnt vmcnt(9)
	v_add_u32_e32 v54, s79, v59
	v_add_u32_e32 v55, s79, v60
	v_add_u32_e32 v56, s79, v61
	v_add_u32_e32 v57, s79, v62
	ds_read_b64_tr_b4 v[50:51], v160 offset:128
	ds_read_b64_tr_b4 v[52:53], v160 offset:1152
	ds_read_b64_tr_b4 v[130:131], v54
	ds_read_b64_tr_b4 v[132:133], v55
	ds_read_b64_tr_b4 v[134:135], v56
	ds_read_b64_tr_b4 v[136:137], v57
	s_waitcnt lgkmcnt(13)
; #define TR4(p_) __builtin_amdgcn_ds_read_tr4_b64_v2i32((LAS v2i*)(p_))
; #define VDMA(st_, k_) do { _Pragma("unroll") for (int i_ = 0; i_ < 4; ++i_) { \
;         const unsigned off_ = (unsigned)((st_) >> 2) * (16384u * 128u) + (PE_ID(E, 4 * ((st_) & 3) + i_) << 7) + ((i_ & 1) ? cx1 : cx0); \
;         __builtin_amdgcn_global_load_lds((const unsigned*)(V4 + off_), (LAS unsigned*)(ldsb + BUF[k_] + 1024 * i_), 16, 0, 0); } } while (0)
; __device__ __forceinline__ void peer_v_tokens(int j, const LAS unsigned short* EL, const LAS unsigned char* AL  , const LAS float* ASC  , const LAS int* SAL  , ...
;     ...
;         for (int st = 0; st < 16; ++st) {
;             const int p = st >> 2, q = st & 3;
;             if (st < 14) VDMA(st + 2, (st + 2) % 3);
;             if (st < 14) asm volatile("s_waitcnt vmcnt(8)" ::: "memory");
;             else if (st == 14) asm volatile("s_waitcnt vmcnt(4)" ::: "memory");
;             else asm volatile("s_waitcnt vmcnt(0)" ::: "memory");
;             if (q == 0) {
; #pragma unroll
;                 for (int r = 0; r < 4; ++r) { accH[r] = 0; accL[r] = 0; } }
; #pragma unroll
;             for (int tp = 0; tp < 2; ++tp) {
;                 const v2i ao = TR4(ATL + (2 * q + tp) * 128 + 8 * s16), ah = TR4(ATL + 1024 + (2 * q + tp) * 128 + 8 * s16);
; #pragma unroll
;                 for (int r = 0; r < 4; ++r) {
;                     const v2i d = TR4(ldsb + BUF[st % 3] + 2048 * tp + roff[r]);
;                     accH[r] = __builtin_amdgcn_sdot8(d.x, ah.x, accH[r], false); accH[r] = __builtin_amdgcn_sdot8(d.y, ah.y, accH[r], false);
;                     accL[r] = __builtin_amdgcn_sdot8(d.x, ao.x, accL[r], false); accL[r] = __builtin_amdgcn_sdot8(d.y, ao.y, accL[r], false);
;                 }
;             }
;             asm volatile("s_waitcnt lgkmcnt(0)" ::: "memory");
	v_dot8c_i32_i4_e32 v38, v122, v48
	v_dot8c_i32_i4_e32 v39, v122, v46
	v_dot8c_i32_i4_e32 v40, v124, v48
	v_dot8c_i32_i4_e32 v41, v124, v46
	v_dot8c_i32_i4_e32 v42, v126, v48
	v_dot8c_i32_i4_e32 v43, v126, v46
	v_dot8c_i32_i4_e32 v44, v128, v48
	v_dot8c_i32_i4_e32 v45, v128, v46
	v_dot8c_i32_i4_e32 v38, v123, v49
	v_dot8c_i32_i4_e32 v39, v123, v47
	v_dot8c_i32_i4_e32 v40, v125, v49
	v_dot8c_i32_i4_e32 v41, v125, v47
	v_dot8c_i32_i4_e32 v42, v127, v49
	v_dot8c_i32_i4_e32 v43, v127, v47
	v_dot8c_i32_i4_e32 v44, v129, v49
	v_dot8c_i32_i4_e32 v45, v129, v47
	v_and_b32_e32 v78, 0xffff, v24
	v_lshrrev_b32_e32 v79, 16, v24
	v_lshl_add_u32 v78, v78, 7, v152
	v_lshl_add_u32 v79, v79, 7, v153
	s_mov_b32 m0, s78
	s_add_i32 s43, s78, 0x400
	global_load_lds_dwordx4 v78, s[50:51]
	s_mov_b32 m0, s43
	s_nop 0
	global_load_lds_dwordx4 v79, s[50:51]
	s_waitcnt vmcnt(9)
	v_add_u32_e32 v54, s98, v59
	v_add_u32_e32 v55, s98, v60
	v_add_u32_e32 v56, s98, v61
	v_add_u32_e32 v57, s98, v62
	ds_read_b64_tr_b4 v[46:47], v160 offset:256
	ds_read_b64_tr_b4 v[48:49], v160 offset:1280
	ds_read_b64_tr_b4 v[122:123], v54
	ds_read_b64_tr_b4 v[124:125], v55
	ds_read_b64_tr_b4 v[126:127], v56
	ds_read_b64_tr_b4 v[128:129], v57
	s_waitcnt lgkmcnt(6)
	v_dot8c_i32_i4_e32 v38, v130, v52
	v_dot8c_i32_i4_e32 v39, v130, v50
	v_dot8c_i32_i4_e32 v40, v132, v52
	v_dot8c_i32_i4_e32 v41, v132, v50
	v_dot8c_i32_i4_e32 v42, v134, v52
	v_dot8c_i32_i4_e32 v43, v134, v50
	v_dot8c_i32_i4_e32 v44, v136, v52
	v_dot8c_i32_i4_e32 v45, v136, v50
	v_dot8c_i32_i4_e32 v38, v131, v53
	v_dot8c_i32_i4_e32 v39, v131, v51
	v_dot8c_i32_i4_e32 v40, v133, v53
	v_dot8c_i32_i4_e32 v41, v133, v51
	v_dot8c_i32_i4_e32 v42, v135, v53
	v_dot8c_i32_i4_e32 v43, v135, v51
	v_dot8c_i32_i4_e32 v44, v137, v53
	v_dot8c_i32_i4_e32 v45, v137, v51
	v_and_b32_e32 v78, 0xffff, v25
	v_lshrrev_b32_e32 v79, 16, v25
	v_lshl_add_u32 v78, v78, 7, v152
	v_lshl_add_u32 v79, v79, 7, v153
	s_mov_b32 m0, s79
	s_add_i32 s43, s79, 0x400
	global_load_lds_dwordx4 v78, s[50:51]
	s_mov_b32 m0, s43
	s_nop 0
	global_load_lds_dwordx4 v79, s[50:51]
	s_waitcnt vmcnt(9)
	v_add_u32_e32 v54, s99, v59
	v_add_u32_e32 v55, s99, v60
	v_add_u32_e32 v56, s99, v61
	v_add_u32_e32 v57, s99, v62
	ds_read_b64_tr_b4 v[50:51], v160 offset:384
	ds_read_b64_tr_b4 v[52:53], v160 offset:1408
	ds_read_b64_tr_b4 v[130:131], v54
	ds_read_b64_tr_b4 v[132:133], v55
	ds_read_b64_tr_b4 v[134:135], v56
	ds_read_b64_tr_b4 v[136:137], v57
	s_waitcnt lgkmcnt(6)
	v_dot8c_i32_i4_e32 v38, v122, v48
	v_dot8c_i32_i4_e32 v39, v122, v46
	v_dot8c_i32_i4_e32 v40, v124, v48
	v_dot8c_i32_i4_e32 v41, v124, v46
	v_dot8c_i32_i4_e32 v42, v126, v48
	v_dot8c_i32_i4_e32 v43, v126, v46
	v_dot8c_i32_i4_e32 v44, v128, v48
	v_dot8c_i32_i4_e32 v45, v128, v46
	v_dot8c_i32_i4_e32 v38, v123, v49
	v_dot8c_i32_i4_e32 v39, v123, v47
	v_dot8c_i32_i4_e32 v40, v125, v49
	v_dot8c_i32_i4_e32 v41, v125, v47
	v_dot8c_i32_i4_e32 v42, v127, v49
	v_dot8c_i32_i4_e32 v43, v127, v47
	v_dot8c_i32_i4_e32 v44, v129, v49
	v_dot8c_i32_i4_e32 v45, v129, v47
	s_waitcnt lgkmcnt(15)
	v_and_b32_e32 v78, 0xffff, v26
	v_lshrrev_b32_e32 v79, 16, v26
	v_lshl_add_u32 v78, v78, 7, v152
	v_lshl_add_u32 v79, v79, 7, v153
	s_mov_b32 m0, s98
	s_add_i32 s43, s98, 0x400
	global_load_lds_dwordx4 v78, s[50:51]
	s_mov_b32 m0, s43
	s_nop 0
	global_load_lds_dwordx4 v79, s[50:51]
	s_waitcnt vmcnt(9)
	v_add_u32_e32 v54, s76, v59
	v_add_u32_e32 v55, s76, v60
	v_add_u32_e32 v56, s76, v61
	v_add_u32_e32 v57, s76, v62
	ds_read_b64_tr_b4 v[46:47], v160 offset:512
	ds_read_b64_tr_b4 v[48:49], v160 offset:1536
	ds_read_b64_tr_b4 v[122:123], v54
	ds_read_b64_tr_b4 v[124:125], v55
	ds_read_b64_tr_b4 v[126:127], v56
	ds_read_b64_tr_b4 v[128:129], v57
	s_waitcnt lgkmcnt(6)
	v_dot8c_i32_i4_e32 v38, v130, v52
	v_dot8c_i32_i4_e32 v39, v130, v50
	v_dot8c_i32_i4_e32 v40, v132, v52
	v_dot8c_i32_i4_e32 v41, v132, v50
	v_dot8c_i32_i4_e32 v42, v134, v52
	v_dot8c_i32_i4_e32 v43, v134, v50
	v_dot8c_i32_i4_e32 v44, v136, v52
	v_dot8c_i32_i4_e32 v45, v136, v50
	v_dot8c_i32_i4_e32 v38, v131, v53
	v_dot8c_i32_i4_e32 v39, v131, v51
	v_dot8c_i32_i4_e32 v40, v133, v53
	v_dot8c_i32_i4_e32 v41, v133, v51
	v_dot8c_i32_i4_e32 v42, v135, v53
	v_dot8c_i32_i4_e32 v43, v135, v51
	v_dot8c_i32_i4_e32 v44, v137, v53
	v_dot8c_i32_i4_e32 v45, v137, v51
	v_and_b32_e32 v78, 0xffff, v27
	v_lshrrev_b32_e32 v79, 16, v27
	v_lshl_add_u32 v78, v78, 7, v152
	v_lshl_add_u32 v79, v79, 7, v153
	s_mov_b32 m0, s99
	s_add_i32 s43, s99, 0x400
	global_load_lds_dwordx4 v78, s[50:51]
	s_mov_b32 m0, s43
	s_nop 0
	global_load_lds_dwordx4 v79, s[50:51]
	s_waitcnt vmcnt(8)
	v_add_u32_e32 v54, s77, v59
	v_add_u32_e32 v55, s77, v60
	v_add_u32_e32 v56, s77, v61
	v_add_u32_e32 v57, s77, v62
	ds_read_b64_tr_b4 v[50:51], v160 offset:640
	ds_read_b64_tr_b4 v[52:53], v160 offset:1664
	ds_read_b64_tr_b4 v[130:131], v54
	ds_read_b64_tr_b4 v[132:133], v55
	ds_read_b64_tr_b4 v[134:135], v56
	ds_read_b64_tr_b4 v[136:137], v57
	s_waitcnt lgkmcnt(6)
	v_dot8c_i32_i4_e32 v38, v122, v48
	v_dot8c_i32_i4_e32 v39, v122, v46
	v_dot8c_i32_i4_e32 v40, v124, v48
	v_dot8c_i32_i4_e32 v41, v124, v46
	v_dot8c_i32_i4_e32 v42, v126, v48
	v_dot8c_i32_i4_e32 v43, v126, v46
	v_dot8c_i32_i4_e32 v44, v128, v48
	v_dot8c_i32_i4_e32 v45, v128, v46
	v_dot8c_i32_i4_e32 v38, v123, v49
	v_dot8c_i32_i4_e32 v39, v123, v47
	v_dot8c_i32_i4_e32 v40, v125, v49
	v_dot8c_i32_i4_e32 v41, v125, v47
	v_dot8c_i32_i4_e32 v42, v127, v49
	v_dot8c_i32_i4_e32 v43, v127, v47
	v_dot8c_i32_i4_e32 v44, v129, v49
	v_dot8c_i32_i4_e32 v45, v129, v47
	s_waitcnt lgkmcnt(15)
; #define LAS __attribute__((address_space(3)))
; __device__ __forceinline__ bf16 f2bf(float f) { return (bf16)f2bfu(f); }
; __device__ __forceinline__ void peer_v_tokens(int j, const LAS unsigned short* EL, const LAS unsigned char* AL  , const LAS float* ASC  , const LAS int* SAL  , ...
;     ...
; #pragma unroll
;         for (int m = 0; m < 2; ++m) {
;             const int idx = lane + 64 * m, tau = idx >> 4, sr = idx & 15, k = 16 * (sr & 7) + 2 * tau + (sr >> 3);
;             const int aq = (int)*(const LAS signed char*)(AL + tl * 128 + k); const int tq = aq + 8;
;             const unsigned lo = (((unsigned)tq & 15u) ^ 8u) * 0x11111111u, hi = ((unsigned)(tq >> 4) & 15u) * 0x11111111u;
;             typedef unsigned u2v __attribute__((ext_vector_type(2)));
;             u2v l2; l2.x = lo; l2.y = lo; u2v h2; h2.x = hi; h2.y = hi;
;             *(LAS u2v*)(ATL + 8 * idx) = l2; *(LAS u2v*)(ATL + 1024 + 8 * idx) = h2;
;         }
;     ...
;         for (int st = 0; st < 16; ++st) {
;             const int p = st >> 2, q = st & 3;
;             if (st < 14) VDMA(st + 2, (st + 2) % 3);
;             if (st < 14) asm volatile("s_waitcnt vmcnt(8)" ::: "memory");
;             else if (st == 14) asm volatile("s_waitcnt vmcnt(4)" ::: "memory");
;             else asm volatile("s_waitcnt vmcnt(0)" ::: "memory");
;             if (q == 0) {
; #pragma unroll
;                 for (int r = 0; r < 4; ++r) { accH[r] = 0; accL[r] = 0; } }
; #pragma unroll
;             for (int tp = 0; tp < 2; ++tp) {
;                 const v2i ao = TR4(ATL + (2 * q + tp) * 128 + 8 * s16), ah = TR4(ATL + 1024 + (2 * q + tp) * 128 + 8 * s16);
; #pragma unroll
;                 for (int r = 0; r < 4; ++r) {
;                     const v2i d = TR4(ldsb + BUF[st % 3] + 2048 * tp + roff[r]);
;                     accH[r] = __builtin_amdgcn_sdot8(d.x, ah.x, accH[r], false); accH[r] = __builtin_amdgcn_sdot8(d.y, ah.y, accH[r], false);
;                     accL[r] = __builtin_amdgcn_sdot8(d.x, ao.x, accL[r], false); accL[r] = __builtin_amdgcn_sdot8(d.y, ao.y, accL[r], false);
;                 }
;             }
;             asm volatile("s_waitcnt lgkmcnt(0)" ::: "memory");
;             if (q == 3) {
; #pragma unroll
;                 for (int r = 0; r < 4; ++r) STASH[256 * p + 16 * (grp + 4 * r) + pc] = f2bf(asc * (float)(2 * ((accH[r] << 4) + accL[r]) + sa));
;             }
;         }
	v_add_u32_e32 v143, 8, v139
	v_and_b32_e32 v142, 15, v143
	v_xor_b32_e32 v142, 8, v142
	v_bfe_u32 v144, v143, 4, 4
	v_mul_lo_u32 v142, v142, s92
	v_mul_lo_u32 v144, v144, s92
	v_mov_b32_e32 v143, v142
	v_mov_b32_e32 v145, v144
	ds_write2st64_b64 v159, v[142:143], v[144:145] offset1:2
	v_and_b32_e32 v78, 0xffff, v28
	v_lshrrev_b32_e32 v79, 16, v28
	v_lshl_add_u32 v78, v78, 7, v152
	v_lshl_add_u32 v79, v79, 7, v153
	s_mov_b32 m0, s76
	s_add_i32 s43, s76, 0x400
	global_load_lds_dwordx4 v78, s[50:51]
	s_mov_b32 m0, s43
	s_nop 0
	global_load_lds_dwordx4 v79, s[50:51]
	s_waitcnt vmcnt(8)
	v_add_u32_e32 v54, s78, v59
	v_add_u32_e32 v55, s78, v60
	v_add_u32_e32 v56, s78, v61
	v_add_u32_e32 v57, s78, v62
	ds_read_b64_tr_b4 v[46:47], v160 offset:768
	ds_read_b64_tr_b4 v[48:49], v160 offset:1792
	ds_read_b64_tr_b4 v[122:123], v54
	ds_read_b64_tr_b4 v[124:125], v55
	ds_read_b64_tr_b4 v[126:127], v56
	ds_read_b64_tr_b4 v[128:129], v57
	s_waitcnt lgkmcnt(7)
	v_dot8c_i32_i4_e32 v38, v130, v52
	v_dot8c_i32_i4_e32 v39, v130, v50
	v_dot8c_i32_i4_e32 v40, v132, v52
	v_dot8c_i32_i4_e32 v41, v132, v50
	v_dot8c_i32_i4_e32 v42, v134, v52
	v_dot8c_i32_i4_e32 v43, v134, v50
	v_dot8c_i32_i4_e32 v44, v136, v52
	v_dot8c_i32_i4_e32 v45, v136, v50
	v_dot8c_i32_i4_e32 v38, v131, v53
	v_dot8c_i32_i4_e32 v39, v131, v51
	v_dot8c_i32_i4_e32 v40, v133, v53
	v_dot8c_i32_i4_e32 v41, v133, v51
	v_dot8c_i32_i4_e32 v42, v135, v53
	v_dot8c_i32_i4_e32 v43, v135, v51
	v_dot8c_i32_i4_e32 v44, v137, v53
	v_dot8c_i32_i4_e32 v45, v137, v51
	v_and_b32_e32 v78, 0xffff, v29
	v_lshrrev_b32_e32 v79, 16, v29
	v_lshl_add_u32 v78, v78, 7, v152
	v_lshl_add_u32 v79, v79, 7, v153
	s_mov_b32 m0, s77
	s_add_i32 s43, s77, 0x400
	global_load_lds_dwordx4 v78, s[50:51]
	s_mov_b32 m0, s43
	s_nop 0
	global_load_lds_dwordx4 v79, s[50:51]
	s_waitcnt vmcnt(8)
	v_add_u32_e32 v54, s79, v59
	v_add_u32_e32 v55, s79, v60
	v_add_u32_e32 v56, s79, v61
	v_add_u32_e32 v57, s79, v62
	ds_read_b64_tr_b4 v[50:51], v160 offset:896
	ds_read_b64_tr_b4 v[52:53], v160 offset:1920
	ds_read_b64_tr_b4 v[130:131], v54
	ds_read_b64_tr_b4 v[132:133], v55
	ds_read_b64_tr_b4 v[134:135], v56
	ds_read_b64_tr_b4 v[136:137], v57
	s_waitcnt lgkmcnt(6)
	v_dot8c_i32_i4_e32 v38, v122, v48
	v_dot8c_i32_i4_e32 v39, v122, v46
	v_dot8c_i32_i4_e32 v40, v124, v48
	v_dot8c_i32_i4_e32 v41, v124, v46
	v_dot8c_i32_i4_e32 v42, v126, v48
	v_dot8c_i32_i4_e32 v43, v126, v46
	v_dot8c_i32_i4_e32 v44, v128, v48
	v_dot8c_i32_i4_e32 v45, v128, v46
	v_dot8c_i32_i4_e32 v38, v123, v49
	v_dot8c_i32_i4_e32 v39, v123, v47
	v_dot8c_i32_i4_e32 v40, v125, v49
	v_dot8c_i32_i4_e32 v41, v125, v47
	v_dot8c_i32_i4_e32 v42, v127, v49
	v_dot8c_i32_i4_e32 v43, v127, v47
	v_dot8c_i32_i4_e32 v44, v129, v49
	v_dot8c_i32_i4_e32 v45, v129, v47
	v_and_b32_e32 v78, 0xffff, v30
	v_lshrrev_b32_e32 v79, 16, v30
	v_lshl_add_u32 v78, v78, 7, v152
	v_lshl_add_u32 v79, v79, 7, v153
	s_mov_b32 m0, s78
	s_add_i32 s43, s78, 0x400
	global_load_lds_dwordx4 v78, s[50:51]
	s_mov_b32 m0, s43
	s_nop 0
	global_load_lds_dwordx4 v79, s[50:51]
	s_waitcnt vmcnt(8)
	v_add_u32_e32 v54, s98, v59
	v_add_u32_e32 v55, s98, v60
	v_add_u32_e32 v56, s98, v61
	v_add_u32_e32 v57, s98, v62
	ds_read_b64_tr_b4 v[46:47], v160
	ds_read_b64_tr_b4 v[48:49], v160 offset:1024
	ds_read_b64_tr_b4 v[122:123], v54
	ds_read_b64_tr_b4 v[124:125], v55
	ds_read_b64_tr_b4 v[126:127], v56
	ds_read_b64_tr_b4 v[128:129], v57
	s_waitcnt lgkmcnt(6)
	v_dot8c_i32_i4_e32 v38, v130, v52
	v_dot8c_i32_i4_e32 v39, v130, v50
	v_dot8c_i32_i4_e32 v40, v132, v52
	v_dot8c_i32_i4_e32 v41, v132, v50
	v_dot8c_i32_i4_e32 v42, v134, v52
	v_dot8c_i32_i4_e32 v43, v134, v50
	v_dot8c_i32_i4_e32 v44, v136, v52
	v_dot8c_i32_i4_e32 v45, v136, v50
	v_dot8c_i32_i4_e32 v38, v131, v53
	v_dot8c_i32_i4_e32 v39, v131, v51
	v_dot8c_i32_i4_e32 v40, v133, v53
	v_dot8c_i32_i4_e32 v41, v133, v51
	v_dot8c_i32_i4_e32 v42, v135, v53
	v_dot8c_i32_i4_e32 v43, v135, v51
	v_dot8c_i32_i4_e32 v44, v137, v53
	v_dot8c_i32_i4_e32 v45, v137, v51
	s_nop 3
	s_waitcnt lgkmcnt(15)
	v_lshlrev_b32_e32 v38, 5, v38
	v_lshlrev_b32_e32 v39, 1, v39
	v_add3_u32 v38, v39, v229, v38
	v_cvt_f32_i32_e32 v38, v38
	v_mul_f32_e32 v38, v228, v38
	v_lshlrev_b32_e32 v40, 5, v40
	v_lshlrev_b32_e32 v41, 1, v41
	v_add3_u32 v40, v41, v229, v40
	v_cvt_f32_i32_e32 v40, v40
	v_mul_f32_e32 v40, v228, v40
	v_lshlrev_b32_e32 v42, 5, v42
	v_lshlrev_b32_e32 v43, 1, v43
	v_add3_u32 v42, v43, v229, v42
	v_cvt_f32_i32_e32 v42, v42
	v_mul_f32_e32 v42, v228, v42
	v_lshlrev_b32_e32 v44, 5, v44
	v_lshlrev_b32_e32 v45, 1, v45
	v_add3_u32 v44, v45, v229, v44
	v_cvt_f32_i32_e32 v44, v44
	v_mul_f32_e32 v44, v228, v44
	v_cvt_pk_bf16_f32 v168, v38, v40
	v_cvt_pk_bf16_f32 v169, v42, v44
	ds_read_b128 v[252:255], v156
	s_add_i32 s44, s40, 24
	s_ashr_i32 s45, s44, 31
	s_lshl_b64 s[44:45], s[44:45], 12
	v_lshl_add_u64 v[80:81], v[36:37], 0, s[44:45]
	s_waitcnt lgkmcnt(0)
; #define TR4(p_) __builtin_amdgcn_ds_read_tr4_b64_v2i32((LAS v2i*)(p_))
; __device__ __forceinline__ void peer_v_tokens(int j, const LAS unsigned short* EL, const LAS unsigned char* AL  , const LAS float* ASC  , const LAS int* SAL  , ...
;     ...
;         { unsigned ho = (unsigned)t * (D / 4) + (unsigned)lane; asm volatile("" : "+v"(ho)); const uint2* hp = (const uint2*)HB + ho; const float4* gp = (const float4*)fng + lane;
; #pragma unroll
;           for (int jq = 0; jq < 4; ++jq) { hv[jq] = hp[64 * jq]; gv[jq] = gp[64 * jq]; } }
;     ...
;         for (int st = 0; st < 16; ++st) {
;             const int p = st >> 2, q = st & 3;
;             if (st < 14) VDMA(st + 2, (st + 2) % 3);
;             if (st < 14) asm volatile("s_waitcnt vmcnt(8)" ::: "memory");
;             else if (st == 14) asm volatile("s_waitcnt vmcnt(4)" ::: "memory");
;             else asm volatile("s_waitcnt vmcnt(0)" ::: "memory");
;             if (q == 0) {
; #pragma unroll
;                 for (int r = 0; r < 4; ++r) { accH[r] = 0; accL[r] = 0; } }
; #pragma unroll
;             for (int tp = 0; tp < 2; ++tp) {
;                 const v2i ao = TR4(ATL + (2 * q + tp) * 128 + 8 * s16), ah = TR4(ATL + 1024 + (2 * q + tp) * 128 + 8 * s16);
; #pragma unroll
;                 for (int r = 0; r < 4; ++r) {
;                     const v2i d = TR4(ldsb + BUF[st % 3] + 2048 * tp + roff[r]);
;                     accH[r] = __builtin_amdgcn_sdot8(d.x, ah.x, accH[r], false); accH[r] = __builtin_amdgcn_sdot8(d.y, ah.y, accH[r], false);
;                     accL[r] = __builtin_amdgcn_sdot8(d.x, ao.x, accL[r], false); accL[r] = __builtin_amdgcn_sdot8(d.y, ao.y, accL[r], false);
;                 }
;             }
;             asm volatile("s_waitcnt lgkmcnt(0)" ::: "memory");
;     ...
;             float4* op = (float4*)(outp + (size_t)t * D) + lane;
; #pragma unroll
;             for (int jq = 0; jq < 4; ++jq) { typedef float f4v __attribute__((ext_vector_type(4))); f4v o4; o4.x = v[jq].x * r3 * gv[jq].x; o4.y = v[jq].y * r3 * gv[jq].y; o4.z = v[jq].z * r3 * gv[jq].z; o4.w = v[jq].w * r3 * gv[jq].w;
;                 __builtin_nontemporal_store(o4, (f4v*)op + 64 * jq); }
	v_mul_f32_e32 v244, v244, v252
	v_mul_f32_e32 v245, v245, v253
	v_mul_f32_e32 v246, v246, v254
	v_mul_f32_e32 v247, v247, v255
	global_store_dwordx4 v[80:81], v[244:247], off offset:2048 nt
	s_add_i32 s43, s40, 32
	s_lshl_b32 s43, s43, 11
	v_add_u32_e32 v138, s43, v66
	global_load_dwordx2 v[194:195], v138, s[70:71]
	global_load_dwordx2 v[196:197], v138, s[70:71] offset:512
	global_load_dwordx2 v[198:199], v138, s[70:71] offset:1024
	global_load_dwordx2 v[200:201], v138, s[70:71] offset:1536
	v_add_u32_e32 v147, 8, v140
	v_and_b32_e32 v146, 15, v147
	v_xor_b32_e32 v146, 8, v146
	v_bfe_u32 v148, v147, 4, 4
	v_mul_lo_u32 v146, v146, s92
	v_mul_lo_u32 v148, v148, s92
	v_mov_b32_e32 v147, v146
	v_mov_b32_e32 v149, v148
	ds_write2st64_b64 v77, v[146:147], v[148:149] offset1:2
	v_add_u32_e32 v138, 0x1800, v74
	ds_read_u8 v139, v138
	v_add_u32_e32 v141, 0x1800, v73
	ds_read_u8 v140, v141
	s_add_i32 s43, s67, 160
	v_mov_b32_e32 v138, s43
	ds_read2st64_b32 v[228:229], v138 offset1:1
	ds_read_b128 v[18:21], v227 offset:12288
	ds_read_b128 v[22:25], v227 offset:12304
	v_mov_b32_e32 v150, v63
	v_mov_b32_e32 v151, v64
	v_mov_b32_e32 v38, 0
	v_mov_b32_e32 v39, 0
	v_mov_b32_e32 v40, 0
	v_mov_b32_e32 v41, 0
	v_mov_b32_e32 v42, 0
	v_mov_b32_e32 v43, 0
	v_mov_b32_e32 v44, 0
	v_mov_b32_e32 v45, 0
	v_and_b32_e32 v78, 0xffff, v31
	v_lshrrev_b32_e32 v79, 16, v31
	v_lshl_add_u32 v78, v78, 7, v152
	v_lshl_add_u32 v79, v79, 7, v153
	s_mov_b32 m0, s79
	s_add_i32 s43, s79, 0x400
	global_load_lds_dwordx4 v78, s[50:51]
	s_mov_b32 m0, s43
	s_nop 0
	global_load_lds_dwordx4 v79, s[50:51]
	s_waitcnt vmcnt(13)
	v_add_u32_e32 v54, s99, v59
	v_add_u32_e32 v55, s99, v60
	v_add_u32_e32 v56, s99, v61
	v_add_u32_e32 v57, s99, v62
	ds_read_b64_tr_b4 v[50:51], v160 offset:128
	ds_read_b64_tr_b4 v[52:53], v160 offset:1152
	ds_read_b64_tr_b4 v[130:131], v54
	ds_read_b64_tr_b4 v[132:133], v55
	ds_read_b64_tr_b4 v[134:135], v56
	ds_read_b64_tr_b4 v[136:137], v57
	s_waitcnt lgkmcnt(13)
	v_dot8c_i32_i4_e32 v38, v122, v48
	v_dot8c_i32_i4_e32 v39, v122, v46
	v_dot8c_i32_i4_e32 v40, v124, v48
	v_dot8c_i32_i4_e32 v41, v124, v46
	v_dot8c_i32_i4_e32 v42, v126, v48
	v_dot8c_i32_i4_e32 v43, v126, v46
	v_dot8c_i32_i4_e32 v44, v128, v48
	v_dot8c_i32_i4_e32 v45, v128, v46
	v_dot8c_i32_i4_e32 v38, v123, v49
	v_dot8c_i32_i4_e32 v39, v123, v47
	v_dot8c_i32_i4_e32 v40, v125, v49
	v_dot8c_i32_i4_e32 v41, v125, v47
	v_dot8c_i32_i4_e32 v42, v127, v49
	v_dot8c_i32_i4_e32 v43, v127, v47
	v_dot8c_i32_i4_e32 v44, v129, v49
	v_dot8c_i32_i4_e32 v45, v129, v47
	v_and_b32_e32 v78, 0xffff, v32
	v_lshrrev_b32_e32 v79, 16, v32
	v_lshl_add_u32 v78, v78, 7, v152
	v_lshl_add_u32 v79, v79, 7, v153
	s_mov_b32 m0, s98
	s_add_i32 s43, s98, 0x400
	global_load_lds_dwordx4 v78, s[50:51]
	s_mov_b32 m0, s43
	s_nop 0
	global_load_lds_dwordx4 v79, s[50:51]
	s_waitcnt vmcnt(13)
	v_add_u32_e32 v54, s76, v59
	v_add_u32_e32 v55, s76, v60
	v_add_u32_e32 v56, s76, v61
	v_add_u32_e32 v57, s76, v62
	ds_read_b64_tr_b4 v[46:47], v160 offset:256
	ds_read_b64_tr_b4 v[48:49], v160 offset:1280
	ds_read_b64_tr_b4 v[122:123], v54
	ds_read_b64_tr_b4 v[124:125], v55
	ds_read_b64_tr_b4 v[126:127], v56
	ds_read_b64_tr_b4 v[128:129], v57
	s_waitcnt lgkmcnt(6)
	v_dot8c_i32_i4_e32 v38, v130, v52
	v_dot8c_i32_i4_e32 v39, v130, v50
	v_dot8c_i32_i4_e32 v40, v132, v52
	v_dot8c_i32_i4_e32 v41, v132, v50
	v_dot8c_i32_i4_e32 v42, v134, v52
	v_dot8c_i32_i4_e32 v43, v134, v50
	v_dot8c_i32_i4_e32 v44, v136, v52
	v_dot8c_i32_i4_e32 v45, v136, v50
	v_dot8c_i32_i4_e32 v38, v131, v53
	v_dot8c_i32_i4_e32 v39, v131, v51
	v_dot8c_i32_i4_e32 v40, v133, v53
	v_dot8c_i32_i4_e32 v41, v133, v51
	v_dot8c_i32_i4_e32 v42, v135, v53
	v_dot8c_i32_i4_e32 v43, v135, v51
	v_dot8c_i32_i4_e32 v44, v137, v53
	v_dot8c_i32_i4_e32 v45, v137, v51
	v_and_b32_e32 v78, 0xffff, v33
	v_lshrrev_b32_e32 v79, 16, v33
	v_lshl_add_u32 v78, v78, 7, v152
	v_lshl_add_u32 v79, v79, 7, v153
	s_mov_b32 m0, s99
	s_add_i32 s43, s99, 0x400
	global_load_lds_dwordx4 v78, s[50:51]
	s_mov_b32 m0, s43
	s_nop 0
	global_load_lds_dwordx4 v79, s[50:51]
	s_waitcnt vmcnt(13)
	v_add_u32_e32 v54, s77, v59
	v_add_u32_e32 v55, s77, v60
	v_add_u32_e32 v56, s77, v61
	v_add_u32_e32 v57, s77, v62
	ds_read_b64_tr_b4 v[50:51], v160 offset:384
	ds_read_b64_tr_b4 v[52:53], v160 offset:1408
	ds_read_b64_tr_b4 v[130:131], v54
	ds_read_b64_tr_b4 v[132:133], v55
	ds_read_b64_tr_b4 v[134:135], v56
	ds_read_b64_tr_b4 v[136:137], v57
	s_waitcnt lgkmcnt(6)
	v_dot8c_i32_i4_e32 v38, v122, v48
	v_dot8c_i32_i4_e32 v39, v122, v46
	v_dot8c_i32_i4_e32 v40, v124, v48
	v_dot8c_i32_i4_e32 v41, v124, v46
	v_dot8c_i32_i4_e32 v42, v126, v48
	v_dot8c_i32_i4_e32 v43, v126, v46
	v_dot8c_i32_i4_e32 v44, v128, v48
	v_dot8c_i32_i4_e32 v45, v128, v46
	v_dot8c_i32_i4_e32 v38, v123, v49
	v_dot8c_i32_i4_e32 v39, v123, v47
	v_dot8c_i32_i4_e32 v40, v125, v49
	v_dot8c_i32_i4_e32 v41, v125, v47
	v_dot8c_i32_i4_e32 v42, v127, v49
	v_dot8c_i32_i4_e32 v43, v127, v47
	v_dot8c_i32_i4_e32 v44, v129, v49
	v_dot8c_i32_i4_e32 v45, v129, v47
	s_waitcnt lgkmcnt(15)
	v_and_b32_e32 v78, 0xffff, v18
	v_lshrrev_b32_e32 v79, 16, v18
	v_lshl_add_u32 v78, v78, 7, v150
	v_lshl_add_u32 v79, v79, 7, v151
	s_mov_b32 m0, s76
	s_add_i32 s43, s76, 0x400
	global_load_lds_dwordx4 v78, s[50:51]
	s_mov_b32 m0, s43
	s_nop 0
	global_load_lds_dwordx4 v79, s[50:51]
	s_waitcnt vmcnt(13)
	v_add_u32_e32 v54, s78, v59
	v_add_u32_e32 v55, s78, v60
	v_add_u32_e32 v56, s78, v61
	v_add_u32_e32 v57, s78, v62
	ds_read_b64_tr_b4 v[46:47], v160 offset:512
	ds_read_b64_tr_b4 v[48:49], v160 offset:1536
	ds_read_b64_tr_b4 v[122:123], v54
	ds_read_b64_tr_b4 v[124:125], v55
	ds_read_b64_tr_b4 v[126:127], v56
	ds_read_b64_tr_b4 v[128:129], v57
	s_waitcnt lgkmcnt(6)
; #define TR4(p_) __builtin_amdgcn_ds_read_tr4_b64_v2i32((LAS v2i*)(p_))
; #define VDMA(st_, k_) do { _Pragma("unroll") for (int i_ = 0; i_ < 4; ++i_) { \
;         const unsigned off_ = (unsigned)((st_) >> 2) * (16384u * 128u) + (PE_ID(E, 4 * ((st_) & 3) + i_) << 7) + ((i_ & 1) ? cx1 : cx0); \
;         __builtin_amdgcn_global_load_lds((const unsigned*)(V4 + off_), (LAS unsigned*)(ldsb + BUF[k_] + 1024 * i_), 16, 0, 0); } } while (0)
; __device__ __forceinline__ void peer_v_tokens(int j, const LAS unsigned short* EL, const LAS unsigned char* AL  , const LAS float* ASC  , const LAS int* SAL  , ...
;     ...
;         for (int st = 0; st < 16; ++st) {
;             const int p = st >> 2, q = st & 3;
;             if (st < 14) VDMA(st + 2, (st + 2) % 3);
;             if (st < 14) asm volatile("s_waitcnt vmcnt(8)" ::: "memory");
;             else if (st == 14) asm volatile("s_waitcnt vmcnt(4)" ::: "memory");
;             else asm volatile("s_waitcnt vmcnt(0)" ::: "memory");
;             if (q == 0) {
; #pragma unroll
;                 for (int r = 0; r < 4; ++r) { accH[r] = 0; accL[r] = 0; } }
; #pragma unroll
;             for (int tp = 0; tp < 2; ++tp) {
;                 const v2i ao = TR4(ATL + (2 * q + tp) * 128 + 8 * s16), ah = TR4(ATL + 1024 + (2 * q + tp) * 128 + 8 * s16);
; #pragma unroll
;                 for (int r = 0; r < 4; ++r) {
;                     const v2i d = TR4(ldsb + BUF[st % 3] + 2048 * tp + roff[r]);
;                     accH[r] = __builtin_amdgcn_sdot8(d.x, ah.x, accH[r], false); accH[r] = __builtin_amdgcn_sdot8(d.y, ah.y, accH[r], false);
;                     accL[r] = __builtin_amdgcn_sdot8(d.x, ao.x, accL[r], false); accL[r] = __builtin_amdgcn_sdot8(d.y, ao.y, accL[r], false);
;                 }
;             }
;             asm volatile("s_waitcnt lgkmcnt(0)" ::: "memory");
	v_dot8c_i32_i4_e32 v38, v130, v52
	v_dot8c_i32_i4_e32 v39, v130, v50
	v_dot8c_i32_i4_e32 v40, v132, v52
	v_dot8c_i32_i4_e32 v41, v132, v50
	v_dot8c_i32_i4_e32 v42, v134, v52
	v_dot8c_i32_i4_e32 v43, v134, v50
	v_dot8c_i32_i4_e32 v44, v136, v52
	v_dot8c_i32_i4_e32 v45, v136, v50
	v_dot8c_i32_i4_e32 v38, v131, v53
	v_dot8c_i32_i4_e32 v39, v131, v51
	v_dot8c_i32_i4_e32 v40, v133, v53
	v_dot8c_i32_i4_e32 v41, v133, v51
	v_dot8c_i32_i4_e32 v42, v135, v53
	v_dot8c_i32_i4_e32 v43, v135, v51
	v_dot8c_i32_i4_e32 v44, v137, v53
	v_dot8c_i32_i4_e32 v45, v137, v51
	v_and_b32_e32 v78, 0xffff, v19
	v_lshrrev_b32_e32 v79, 16, v19
	v_lshl_add_u32 v78, v78, 7, v150
	v_lshl_add_u32 v79, v79, 7, v151
	s_mov_b32 m0, s77
	s_add_i32 s43, s77, 0x400
	global_load_lds_dwordx4 v78, s[50:51]
	s_mov_b32 m0, s43
	s_nop 0
	global_load_lds_dwordx4 v79, s[50:51]
	s_waitcnt vmcnt(8)
	v_add_u32_e32 v54, s79, v59
	v_add_u32_e32 v55, s79, v60
	v_add_u32_e32 v56, s79, v61
	v_add_u32_e32 v57, s79, v62
	ds_read_b64_tr_b4 v[50:51], v160 offset:640
	ds_read_b64_tr_b4 v[52:53], v160 offset:1664
	ds_read_b64_tr_b4 v[130:131], v54
	ds_read_b64_tr_b4 v[132:133], v55
	ds_read_b64_tr_b4 v[134:135], v56
	ds_read_b64_tr_b4 v[136:137], v57
	s_waitcnt lgkmcnt(6)
	v_dot8c_i32_i4_e32 v38, v122, v48
	v_dot8c_i32_i4_e32 v39, v122, v46
	v_dot8c_i32_i4_e32 v40, v124, v48
	v_dot8c_i32_i4_e32 v41, v124, v46
	v_dot8c_i32_i4_e32 v42, v126, v48
	v_dot8c_i32_i4_e32 v43, v126, v46
	v_dot8c_i32_i4_e32 v44, v128, v48
	v_dot8c_i32_i4_e32 v45, v128, v46
	v_dot8c_i32_i4_e32 v38, v123, v49
	v_dot8c_i32_i4_e32 v39, v123, v47
	v_dot8c_i32_i4_e32 v40, v125, v49
	v_dot8c_i32_i4_e32 v41, v125, v47
	v_dot8c_i32_i4_e32 v42, v127, v49
	v_dot8c_i32_i4_e32 v43, v127, v47
	v_dot8c_i32_i4_e32 v44, v129, v49
	v_dot8c_i32_i4_e32 v45, v129, v47
	s_waitcnt lgkmcnt(15)
	v_add_u32_e32 v143, 8, v139
	v_and_b32_e32 v142, 15, v143
	v_xor_b32_e32 v142, 8, v142
	v_bfe_u32 v144, v143, 4, 4
	v_mul_lo_u32 v142, v142, s92
	v_mul_lo_u32 v144, v144, s92
	v_mov_b32_e32 v143, v142
	v_mov_b32_e32 v145, v144
	ds_write2st64_b64 v159, v[142:143], v[144:145] offset1:2
	v_and_b32_e32 v78, 0xffff, v20
	v_lshrrev_b32_e32 v79, 16, v20
	v_lshl_add_u32 v78, v78, 7, v150
	v_lshl_add_u32 v79, v79, 7, v151
	s_mov_b32 m0, s78
	s_add_i32 s43, s78, 0x400
	global_load_lds_dwordx4 v78, s[50:51]
	s_mov_b32 m0, s43
	s_nop 0
	global_load_lds_dwordx4 v79, s[50:51]
	s_waitcnt vmcnt(8)
	v_add_u32_e32 v54, s98, v59
	v_add_u32_e32 v55, s98, v60
	v_add_u32_e32 v56, s98, v61
	v_add_u32_e32 v57, s98, v62
	ds_read_b64_tr_b4 v[46:47], v160 offset:768
	ds_read_b64_tr_b4 v[48:49], v160 offset:1792
	ds_read_b64_tr_b4 v[122:123], v54
	ds_read_b64_tr_b4 v[124:125], v55
	ds_read_b64_tr_b4 v[126:127], v56
	ds_read_b64_tr_b4 v[128:129], v57
	s_waitcnt lgkmcnt(7)
	v_dot8c_i32_i4_e32 v38, v130, v52
	v_dot8c_i32_i4_e32 v39, v130, v50
	v_dot8c_i32_i4_e32 v40, v132, v52
	v_dot8c_i32_i4_e32 v41, v132, v50
	v_dot8c_i32_i4_e32 v42, v134, v52
	v_dot8c_i32_i4_e32 v43, v134, v50
	v_dot8c_i32_i4_e32 v44, v136, v52
	v_dot8c_i32_i4_e32 v45, v136, v50
	v_dot8c_i32_i4_e32 v38, v131, v53
	v_dot8c_i32_i4_e32 v39, v131, v51
	v_dot8c_i32_i4_e32 v40, v133, v53
	v_dot8c_i32_i4_e32 v41, v133, v51
	v_dot8c_i32_i4_e32 v42, v135, v53
	v_dot8c_i32_i4_e32 v43, v135, v51
	v_dot8c_i32_i4_e32 v44, v137, v53
	v_dot8c_i32_i4_e32 v45, v137, v51
	v_and_b32_e32 v78, 0xffff, v21
	v_lshrrev_b32_e32 v79, 16, v21
	v_lshl_add_u32 v78, v78, 7, v150
	v_lshl_add_u32 v79, v79, 7, v151
	s_mov_b32 m0, s79
	s_add_i32 s43, s79, 0x400
	global_load_lds_dwordx4 v78, s[50:51]
	s_mov_b32 m0, s43
	s_nop 0
	global_load_lds_dwordx4 v79, s[50:51]
	s_waitcnt vmcnt(8)
	v_add_u32_e32 v54, s99, v59
	v_add_u32_e32 v55, s99, v60
	v_add_u32_e32 v56, s99, v61
	v_add_u32_e32 v57, s99, v62
	ds_read_b64_tr_b4 v[50:51], v160 offset:896
	ds_read_b64_tr_b4 v[52:53], v160 offset:1920
	ds_read_b64_tr_b4 v[130:131], v54
	ds_read_b64_tr_b4 v[132:133], v55
	ds_read_b64_tr_b4 v[134:135], v56
	ds_read_b64_tr_b4 v[136:137], v57
	s_waitcnt lgkmcnt(6)
	v_dot8c_i32_i4_e32 v38, v122, v48
	v_dot8c_i32_i4_e32 v39, v122, v46
	v_dot8c_i32_i4_e32 v40, v124, v48
	v_dot8c_i32_i4_e32 v41, v124, v46
	v_dot8c_i32_i4_e32 v42, v126, v48
	v_dot8c_i32_i4_e32 v43, v126, v46
	v_dot8c_i32_i4_e32 v44, v128, v48
	v_dot8c_i32_i4_e32 v45, v128, v46
	v_dot8c_i32_i4_e32 v38, v123, v49
	v_dot8c_i32_i4_e32 v39, v123, v47
	v_dot8c_i32_i4_e32 v40, v125, v49
	v_dot8c_i32_i4_e32 v41, v125, v47
	v_dot8c_i32_i4_e32 v42, v127, v49
	v_dot8c_i32_i4_e32 v43, v127, v47
	v_dot8c_i32_i4_e32 v44, v129, v49
	v_dot8c_i32_i4_e32 v45, v129, v47
	v_and_b32_e32 v78, 0xffff, v22
	v_lshrrev_b32_e32 v79, 16, v22
	v_lshl_add_u32 v78, v78, 7, v150
	v_lshl_add_u32 v79, v79, 7, v151
	s_mov_b32 m0, s98
	s_add_i32 s43, s98, 0x400
	global_load_lds_dwordx4 v78, s[50:51]
	s_mov_b32 m0, s43
	s_nop 0
	global_load_lds_dwordx4 v79, s[50:51]
	s_waitcnt vmcnt(8)
	v_add_u32_e32 v54, s76, v59
	v_add_u32_e32 v55, s76, v60
	v_add_u32_e32 v56, s76, v61
	v_add_u32_e32 v57, s76, v62
	ds_read_b64_tr_b4 v[46:47], v160
	ds_read_b64_tr_b4 v[48:49], v160 offset:1024
	ds_read_b64_tr_b4 v[122:123], v54
	ds_read_b64_tr_b4 v[124:125], v55
	ds_read_b64_tr_b4 v[126:127], v56
	ds_read_b64_tr_b4 v[128:129], v57
	s_waitcnt lgkmcnt(6)
	v_dot8c_i32_i4_e32 v38, v130, v52
	v_dot8c_i32_i4_e32 v39, v130, v50
	v_dot8c_i32_i4_e32 v40, v132, v52
	v_dot8c_i32_i4_e32 v41, v132, v50
	v_dot8c_i32_i4_e32 v42, v134, v52
	v_dot8c_i32_i4_e32 v43, v134, v50
	v_dot8c_i32_i4_e32 v44, v136, v52
	v_dot8c_i32_i4_e32 v45, v136, v50
	v_dot8c_i32_i4_e32 v38, v131, v53
	v_dot8c_i32_i4_e32 v39, v131, v51
	v_dot8c_i32_i4_e32 v40, v133, v53
	v_dot8c_i32_i4_e32 v41, v133, v51
	v_dot8c_i32_i4_e32 v42, v135, v53
	v_dot8c_i32_i4_e32 v43, v135, v51
	v_dot8c_i32_i4_e32 v44, v137, v53
	v_dot8c_i32_i4_e32 v45, v137, v51
	s_nop 3
	s_waitcnt lgkmcnt(15)
; #define LAS __attribute__((address_space(3)))
; __device__ __forceinline__ bf16 f2bf(float f) { return (bf16)f2bfu(f); }
; #define TR4(p_) __builtin_amdgcn_ds_read_tr4_b64_v2i32((LAS v2i*)(p_))
; #define VDMA(st_, k_) do { _Pragma("unroll") for (int i_ = 0; i_ < 4; ++i_) { \
;         const unsigned off_ = (unsigned)((st_) >> 2) * (16384u * 128u) + (PE_ID(E, 4 * ((st_) & 3) + i_) << 7) + ((i_ & 1) ? cx1 : cx0); \
;         __builtin_amdgcn_global_load_lds((const unsigned*)(V4 + off_), (LAS unsigned*)(ldsb + BUF[k_] + 1024 * i_), 16, 0, 0); } } while (0)
; __device__ __forceinline__ void peer_v_tokens(int j, const LAS unsigned short* EL, const LAS unsigned char* AL  , const LAS float* ASC  , const LAS int* SAL  , ...
;     ...
;         for (int st = 0; st < 16; ++st) {
;             const int p = st >> 2, q = st & 3;
;             if (st < 14) VDMA(st + 2, (st + 2) % 3);
;             if (st < 14) asm volatile("s_waitcnt vmcnt(8)" ::: "memory");
;             else if (st == 14) asm volatile("s_waitcnt vmcnt(4)" ::: "memory");
;             else asm volatile("s_waitcnt vmcnt(0)" ::: "memory");
;             if (q == 0) {
; #pragma unroll
;                 for (int r = 0; r < 4; ++r) { accH[r] = 0; accL[r] = 0; } }
; #pragma unroll
;             for (int tp = 0; tp < 2; ++tp) {
;                 const v2i ao = TR4(ATL + (2 * q + tp) * 128 + 8 * s16), ah = TR4(ATL + 1024 + (2 * q + tp) * 128 + 8 * s16);
; #pragma unroll
;                 for (int r = 0; r < 4; ++r) {
;                     const v2i d = TR4(ldsb + BUF[st % 3] + 2048 * tp + roff[r]);
;                     accH[r] = __builtin_amdgcn_sdot8(d.x, ah.x, accH[r], false); accH[r] = __builtin_amdgcn_sdot8(d.y, ah.y, accH[r], false);
;                     accL[r] = __builtin_amdgcn_sdot8(d.x, ao.x, accL[r], false); accL[r] = __builtin_amdgcn_sdot8(d.y, ao.y, accL[r], false);
;                 }
;             }
;             asm volatile("s_waitcnt lgkmcnt(0)" ::: "memory");
;     ...
;                 for (int r = 0; r < 4; ++r) STASH[256 * p + 16 * (grp + 4 * r) + pc] = f2bf(asc * (float)(2 * ((accH[r] << 4) + accL[r]) + sa));
;             }
;         }
;     ...
;             for (int jq = 0; jq < 4; ++jq) { typedef unsigned u2v __attribute__((ext_vector_type(2))); const u2v pw = *(const LAS u2v*)(STASH + 4 * lane + 256 * jq); const uint2 hw = hv[jq];
	v_lshlrev_b32_e32 v38, 5, v38
	v_lshlrev_b32_e32 v39, 1, v39
	v_add3_u32 v38, v39, v229, v38
	v_cvt_f32_i32_e32 v38, v38
	v_mul_f32_e32 v38, v228, v38
	v_lshlrev_b32_e32 v40, 5, v40
	v_lshlrev_b32_e32 v41, 1, v41
	v_add3_u32 v40, v41, v229, v40
	v_cvt_f32_i32_e32 v40, v40
	v_mul_f32_e32 v40, v228, v40
	v_lshlrev_b32_e32 v42, 5, v42
	v_lshlrev_b32_e32 v43, 1, v43
	v_add3_u32 v42, v43, v229, v42
	v_cvt_f32_i32_e32 v42, v42
	v_mul_f32_e32 v42, v228, v42
	v_lshlrev_b32_e32 v44, 5, v44
	v_lshlrev_b32_e32 v45, 1, v45
	v_add3_u32 v44, v45, v229, v44
	v_cvt_f32_i32_e32 v44, v44
	v_mul_f32_e32 v44, v228, v44
	v_cvt_pk_bf16_f32 v176, v38, v40
	v_cvt_pk_bf16_f32 v177, v42, v44
	ds_read_b128 v[252:255], v156 offset:1024
	s_add_i32 s44, s40, 24
	s_ashr_i32 s45, s44, 31
	s_lshl_b64 s[44:45], s[44:45], 12
	v_lshl_add_u64 v[80:81], v[36:37], 0, s[44:45]
	s_waitcnt lgkmcnt(0)
	v_mul_f32_e32 v248, v248, v252
	v_mul_f32_e32 v249, v249, v253
	v_mul_f32_e32 v250, v250, v254
	v_mul_f32_e32 v251, v251, v255
	global_store_dwordx4 v[80:81], v[248:251], off offset:3072 nt
	v_add_u32_e32 v147, 8, v140
	v_and_b32_e32 v146, 15, v147
	v_xor_b32_e32 v146, 8, v146
	v_bfe_u32 v148, v147, 4, 4
	v_mul_lo_u32 v146, v146, s92
	v_mul_lo_u32 v148, v148, s92
	v_mov_b32_e32 v147, v146
	v_mov_b32_e32 v149, v148
	ds_write2st64_b64 v77, v[146:147], v[148:149] offset1:2
	v_add_u32_e32 v138, 0x1c00, v74
	ds_read_u8 v139, v138
	v_add_u32_e32 v141, 0x1c00, v73
	ds_read_u8 v140, v141
	s_add_i32 s43, s67, 192
	v_mov_b32_e32 v138, s43
	ds_read2st64_b32 v[228:229], v138 offset1:1
	ds_read_b128 v[26:29], v227 offset:14336
	ds_read_b128 v[30:33], v227 offset:14352
	v_mov_b32_e32 v38, 0
	v_mov_b32_e32 v39, 0
	v_mov_b32_e32 v40, 0
	v_mov_b32_e32 v41, 0
	v_mov_b32_e32 v42, 0
	v_mov_b32_e32 v43, 0
	v_mov_b32_e32 v44, 0
	v_mov_b32_e32 v45, 0
	v_and_b32_e32 v78, 0xffff, v23
	v_lshrrev_b32_e32 v79, 16, v23
	v_lshl_add_u32 v78, v78, 7, v150
	v_lshl_add_u32 v79, v79, 7, v151
	s_mov_b32 m0, s99
	s_add_i32 s43, s99, 0x400
	global_load_lds_dwordx4 v78, s[50:51]
	s_mov_b32 m0, s43
	s_nop 0
	global_load_lds_dwordx4 v79, s[50:51]
	s_waitcnt vmcnt(9)
	v_add_u32_e32 v54, s77, v59
	v_add_u32_e32 v55, s77, v60
	v_add_u32_e32 v56, s77, v61
	v_add_u32_e32 v57, s77, v62
	ds_read_b64_tr_b4 v[50:51], v160 offset:128
	ds_read_b64_tr_b4 v[52:53], v160 offset:1152
	ds_read_b64_tr_b4 v[130:131], v54
	ds_read_b64_tr_b4 v[132:133], v55
	ds_read_b64_tr_b4 v[134:135], v56
	ds_read_b64_tr_b4 v[136:137], v57
	s_waitcnt lgkmcnt(13)
	v_dot8c_i32_i4_e32 v38, v122, v48
	v_dot8c_i32_i4_e32 v39, v122, v46
	v_dot8c_i32_i4_e32 v40, v124, v48
	v_dot8c_i32_i4_e32 v41, v124, v46
	v_dot8c_i32_i4_e32 v42, v126, v48
	v_dot8c_i32_i4_e32 v43, v126, v46
	v_dot8c_i32_i4_e32 v44, v128, v48
	v_dot8c_i32_i4_e32 v45, v128, v46
	v_dot8c_i32_i4_e32 v38, v123, v49
	v_dot8c_i32_i4_e32 v39, v123, v47
	v_dot8c_i32_i4_e32 v40, v125, v49
	v_dot8c_i32_i4_e32 v41, v125, v47
	v_dot8c_i32_i4_e32 v42, v127, v49
	v_dot8c_i32_i4_e32 v43, v127, v47
	v_dot8c_i32_i4_e32 v44, v129, v49
	v_dot8c_i32_i4_e32 v45, v129, v47
	v_and_b32_e32 v78, 0xffff, v24
	v_lshrrev_b32_e32 v79, 16, v24
	v_lshl_add_u32 v78, v78, 7, v150
	v_lshl_add_u32 v79, v79, 7, v151
	s_mov_b32 m0, s76
	s_add_i32 s43, s76, 0x400
	global_load_lds_dwordx4 v78, s[50:51]
	s_mov_b32 m0, s43
	s_nop 0
	global_load_lds_dwordx4 v79, s[50:51]
	s_waitcnt vmcnt(9)
	v_add_u32_e32 v54, s78, v59
	v_add_u32_e32 v55, s78, v60
	v_add_u32_e32 v56, s78, v61
	v_add_u32_e32 v57, s78, v62
	ds_read_b64_tr_b4 v[46:47], v160 offset:256
	ds_read_b64_tr_b4 v[48:49], v160 offset:1280
	ds_read_b64_tr_b4 v[122:123], v54
	ds_read_b64_tr_b4 v[124:125], v55
	ds_read_b64_tr_b4 v[126:127], v56
	ds_read_b64_tr_b4 v[128:129], v57
	s_waitcnt lgkmcnt(6)
	v_dot8c_i32_i4_e32 v38, v130, v52
	v_dot8c_i32_i4_e32 v39, v130, v50
	v_dot8c_i32_i4_e32 v40, v132, v52
	v_dot8c_i32_i4_e32 v41, v132, v50
	v_dot8c_i32_i4_e32 v42, v134, v52
	v_dot8c_i32_i4_e32 v43, v134, v50
	v_dot8c_i32_i4_e32 v44, v136, v52
	v_dot8c_i32_i4_e32 v45, v136, v50
	v_dot8c_i32_i4_e32 v38, v131, v53
	v_dot8c_i32_i4_e32 v39, v131, v51
	v_dot8c_i32_i4_e32 v40, v133, v53
	v_dot8c_i32_i4_e32 v41, v133, v51
	v_dot8c_i32_i4_e32 v42, v135, v53
	v_dot8c_i32_i4_e32 v43, v135, v51
	v_dot8c_i32_i4_e32 v44, v137, v53
	v_dot8c_i32_i4_e32 v45, v137, v51
	ds_write_b16 v65, v162
	ds_write_b16_d16_hi v65, v162 offset:128
	ds_write_b16 v65, v163 offset:256
	ds_write_b16_d16_hi v65, v163 offset:384
	ds_write_b16 v65, v164 offset:512
	ds_write_b16_d16_hi v65, v164 offset:640
	ds_write_b16 v65, v165 offset:768
	ds_write_b16_d16_hi v65, v165 offset:896
	ds_write_b16 v65, v166 offset:1024
	ds_write_b16_d16_hi v65, v166 offset:1152
	ds_write_b16 v65, v167 offset:1280
	ds_write_b16_d16_hi v65, v167 offset:1408
	ds_write_b16 v65, v168 offset:1536
	ds_write_b16_d16_hi v65, v168 offset:1664
	ds_write_b16 v65, v169 offset:1792
	ds_write_b16_d16_hi v65, v169 offset:1920
	ds_read_b64 v[202:203], v154
	ds_read_b64 v[204:205], v154 offset:512
	ds_read_b64 v[206:207], v154 offset:1024
	ds_read_b64 v[208:209], v154 offset:1536
	v_and_b32_e32 v78, 0xffff, v25
	v_lshrrev_b32_e32 v79, 16, v25
	v_lshl_add_u32 v78, v78, 7, v150
	v_lshl_add_u32 v79, v79, 7, v151
	s_mov_b32 m0, s77
	s_add_i32 s43, s77, 0x400
	global_load_lds_dwordx4 v78, s[50:51]
	s_mov_b32 m0, s43
	s_nop 0
	global_load_lds_dwordx4 v79, s[50:51]
	s_waitcnt vmcnt(9)
	v_add_u32_e32 v54, s79, v59
	v_add_u32_e32 v55, s79, v60
	v_add_u32_e32 v56, s79, v61
	v_add_u32_e32 v57, s79, v62
	ds_read_b64_tr_b4 v[50:51], v160 offset:384
	ds_read_b64_tr_b4 v[52:53], v160 offset:1408
	ds_read_b64_tr_b4 v[130:131], v54
	ds_read_b64_tr_b4 v[132:133], v55
	ds_read_b64_tr_b4 v[134:135], v56
	ds_read_b64_tr_b4 v[136:137], v57
	s_waitcnt lgkmcnt(15)
; #define LAS __attribute__((address_space(3)))
; #define TR4(p_) __builtin_amdgcn_ds_read_tr4_b64_v2i32((LAS v2i*)(p_))
; __device__ __forceinline__ void peer_v_tokens(int j, const LAS unsigned short* EL, const LAS unsigned char* AL  , const LAS float* ASC  , const LAS int* SAL  , ...
;     ...
; #pragma unroll
;         for (int m = 0; m < 2; ++m) {
;             const int idx = lane + 64 * m, tau = idx >> 4, sr = idx & 15, k = 16 * (sr & 7) + 2 * tau + (sr >> 3);
;             const int aq = (int)*(const LAS signed char*)(AL + tl * 128 + k); const int tq = aq + 8;
;             const unsigned lo = (((unsigned)tq & 15u) ^ 8u) * 0x11111111u, hi = ((unsigned)(tq >> 4) & 15u) * 0x11111111u;
;             typedef unsigned u2v __attribute__((ext_vector_type(2)));
;             u2v l2; l2.x = lo; l2.y = lo; u2v h2; h2.x = hi; h2.y = hi;
;             *(LAS u2v*)(ATL + 8 * idx) = l2; *(LAS u2v*)(ATL + 1024 + 8 * idx) = h2;
;         }
;     ...
;         for (int st = 0; st < 16; ++st) {
;             const int p = st >> 2, q = st & 3;
;             if (st < 14) VDMA(st + 2, (st + 2) % 3);
;             if (st < 14) asm volatile("s_waitcnt vmcnt(8)" ::: "memory");
;             else if (st == 14) asm volatile("s_waitcnt vmcnt(4)" ::: "memory");
;             else asm volatile("s_waitcnt vmcnt(0)" ::: "memory");
;             if (q == 0) {
; #pragma unroll
;                 for (int r = 0; r < 4; ++r) { accH[r] = 0; accL[r] = 0; } }
; #pragma unroll
;             for (int tp = 0; tp < 2; ++tp) {
;                 const v2i ao = TR4(ATL + (2 * q + tp) * 128 + 8 * s16), ah = TR4(ATL + 1024 + (2 * q + tp) * 128 + 8 * s16);
; #pragma unroll
;                 for (int r = 0; r < 4; ++r) {
;                     const v2i d = TR4(ldsb + BUF[st % 3] + 2048 * tp + roff[r]);
;                     accH[r] = __builtin_amdgcn_sdot8(d.x, ah.x, accH[r], false); accH[r] = __builtin_amdgcn_sdot8(d.y, ah.y, accH[r], false);
;                     accL[r] = __builtin_amdgcn_sdot8(d.x, ao.x, accL[r], false); accL[r] = __builtin_amdgcn_sdot8(d.y, ao.y, accL[r], false);
;                 }
;             }
;             asm volatile("s_waitcnt lgkmcnt(0)" ::: "memory");
	v_dot8c_i32_i4_e32 v38, v122, v48
	v_dot8c_i32_i4_e32 v39, v122, v46
	v_dot8c_i32_i4_e32 v40, v124, v48
	v_dot8c_i32_i4_e32 v41, v124, v46
	v_dot8c_i32_i4_e32 v42, v126, v48
	v_dot8c_i32_i4_e32 v43, v126, v46
	v_dot8c_i32_i4_e32 v44, v128, v48
	v_dot8c_i32_i4_e32 v45, v128, v46
	v_dot8c_i32_i4_e32 v38, v123, v49
	v_dot8c_i32_i4_e32 v39, v123, v47
	v_dot8c_i32_i4_e32 v40, v125, v49
	v_dot8c_i32_i4_e32 v41, v125, v47
	v_dot8c_i32_i4_e32 v42, v127, v49
	v_dot8c_i32_i4_e32 v43, v127, v47
	v_dot8c_i32_i4_e32 v44, v129, v49
	v_dot8c_i32_i4_e32 v45, v129, v47
	s_waitcnt lgkmcnt(15)
	v_and_b32_e32 v78, 0xffff, v26
	v_lshrrev_b32_e32 v79, 16, v26
	v_lshl_add_u32 v78, v78, 7, v150
	v_lshl_add_u32 v79, v79, 7, v151
	s_mov_b32 m0, s78
	s_add_i32 s43, s78, 0x400
	global_load_lds_dwordx4 v78, s[50:51]
	s_mov_b32 m0, s43
	s_nop 0
	global_load_lds_dwordx4 v79, s[50:51]
	s_waitcnt vmcnt(9)
	v_add_u32_e32 v54, s98, v59
	v_add_u32_e32 v55, s98, v60
	v_add_u32_e32 v56, s98, v61
	v_add_u32_e32 v57, s98, v62
	ds_read_b64_tr_b4 v[46:47], v160 offset:512
	ds_read_b64_tr_b4 v[48:49], v160 offset:1536
	ds_read_b64_tr_b4 v[122:123], v54
	ds_read_b64_tr_b4 v[124:125], v55
	ds_read_b64_tr_b4 v[126:127], v56
	ds_read_b64_tr_b4 v[128:129], v57
	s_waitcnt lgkmcnt(6)
	v_dot8c_i32_i4_e32 v38, v130, v52
	v_dot8c_i32_i4_e32 v39, v130, v50
	v_dot8c_i32_i4_e32 v40, v132, v52
	v_dot8c_i32_i4_e32 v41, v132, v50
	v_dot8c_i32_i4_e32 v42, v134, v52
	v_dot8c_i32_i4_e32 v43, v134, v50
	v_dot8c_i32_i4_e32 v44, v136, v52
	v_dot8c_i32_i4_e32 v45, v136, v50
	v_dot8c_i32_i4_e32 v38, v131, v53
	v_dot8c_i32_i4_e32 v39, v131, v51
	v_dot8c_i32_i4_e32 v40, v133, v53
	v_dot8c_i32_i4_e32 v41, v133, v51
	v_dot8c_i32_i4_e32 v42, v135, v53
	v_dot8c_i32_i4_e32 v43, v135, v51
	v_dot8c_i32_i4_e32 v44, v137, v53
	v_dot8c_i32_i4_e32 v45, v137, v51
	v_and_b32_e32 v78, 0xffff, v27
	v_lshrrev_b32_e32 v79, 16, v27
	v_lshl_add_u32 v78, v78, 7, v150
	v_lshl_add_u32 v79, v79, 7, v151
	s_mov_b32 m0, s79
	s_add_i32 s43, s79, 0x400
	global_load_lds_dwordx4 v78, s[50:51]
	s_mov_b32 m0, s43
	s_nop 0
	global_load_lds_dwordx4 v79, s[50:51]
	s_waitcnt vmcnt(8)
	v_add_u32_e32 v54, s99, v59
	v_add_u32_e32 v55, s99, v60
	v_add_u32_e32 v56, s99, v61
	v_add_u32_e32 v57, s99, v62
	ds_read_b64_tr_b4 v[50:51], v160 offset:640
	ds_read_b64_tr_b4 v[52:53], v160 offset:1664
	ds_read_b64_tr_b4 v[130:131], v54
	ds_read_b64_tr_b4 v[132:133], v55
	ds_read_b64_tr_b4 v[134:135], v56
	ds_read_b64_tr_b4 v[136:137], v57
	s_waitcnt lgkmcnt(6)
	v_dot8c_i32_i4_e32 v38, v122, v48
	v_dot8c_i32_i4_e32 v39, v122, v46
	v_dot8c_i32_i4_e32 v40, v124, v48
	v_dot8c_i32_i4_e32 v41, v124, v46
	v_dot8c_i32_i4_e32 v42, v126, v48
	v_dot8c_i32_i4_e32 v43, v126, v46
	v_dot8c_i32_i4_e32 v44, v128, v48
	v_dot8c_i32_i4_e32 v45, v128, v46
	v_dot8c_i32_i4_e32 v38, v123, v49
	v_dot8c_i32_i4_e32 v39, v123, v47
	v_dot8c_i32_i4_e32 v40, v125, v49
	v_dot8c_i32_i4_e32 v41, v125, v47
	v_dot8c_i32_i4_e32 v42, v127, v49
	v_dot8c_i32_i4_e32 v43, v127, v47
	v_dot8c_i32_i4_e32 v44, v129, v49
	v_dot8c_i32_i4_e32 v45, v129, v47
	s_waitcnt lgkmcnt(15)
	v_add_u32_e32 v143, 8, v139
	v_and_b32_e32 v142, 15, v143
	v_xor_b32_e32 v142, 8, v142
	v_bfe_u32 v144, v143, 4, 4
	v_mul_lo_u32 v142, v142, s92
	v_mul_lo_u32 v144, v144, s92
	v_mov_b32_e32 v143, v142
	v_mov_b32_e32 v145, v144
	ds_write2st64_b64 v159, v[142:143], v[144:145] offset1:2
	v_and_b32_e32 v78, 0xffff, v28
	v_lshrrev_b32_e32 v79, 16, v28
	v_lshl_add_u32 v78, v78, 7, v150
	v_lshl_add_u32 v79, v79, 7, v151
	s_mov_b32 m0, s98
	s_add_i32 s43, s98, 0x400
	global_load_lds_dwordx4 v78, s[50:51]
	s_mov_b32 m0, s43
	s_nop 0
	global_load_lds_dwordx4 v79, s[50:51]
	s_waitcnt vmcnt(8)
	v_add_u32_e32 v54, s76, v59
	v_add_u32_e32 v55, s76, v60
	v_add_u32_e32 v56, s76, v61
	v_add_u32_e32 v57, s76, v62
	ds_read_b64_tr_b4 v[46:47], v160 offset:768
	ds_read_b64_tr_b4 v[48:49], v160 offset:1792
	ds_read_b64_tr_b4 v[122:123], v54
	ds_read_b64_tr_b4 v[124:125], v55
	ds_read_b64_tr_b4 v[126:127], v56
	ds_read_b64_tr_b4 v[128:129], v57
	s_waitcnt lgkmcnt(7)
	v_dot8c_i32_i4_e32 v38, v130, v52
	v_dot8c_i32_i4_e32 v39, v130, v50
	v_dot8c_i32_i4_e32 v40, v132, v52
	v_dot8c_i32_i4_e32 v41, v132, v50
	v_dot8c_i32_i4_e32 v42, v134, v52
	v_dot8c_i32_i4_e32 v43, v134, v50
	v_dot8c_i32_i4_e32 v44, v136, v52
	v_dot8c_i32_i4_e32 v45, v136, v50
	v_dot8c_i32_i4_e32 v38, v131, v53
	v_dot8c_i32_i4_e32 v39, v131, v51
	v_dot8c_i32_i4_e32 v40, v133, v53
	v_dot8c_i32_i4_e32 v41, v133, v51
	v_dot8c_i32_i4_e32 v42, v135, v53
	v_dot8c_i32_i4_e32 v43, v135, v51
	v_dot8c_i32_i4_e32 v44, v137, v53
	v_dot8c_i32_i4_e32 v45, v137, v51
	v_and_b32_e32 v78, 0xffff, v29
	v_lshrrev_b32_e32 v79, 16, v29
	v_lshl_add_u32 v78, v78, 7, v150
	v_lshl_add_u32 v79, v79, 7, v151
	s_mov_b32 m0, s99
	s_add_i32 s43, s99, 0x400
	global_load_lds_dwordx4 v78, s[50:51]
	s_mov_b32 m0, s43
	s_nop 0
	global_load_lds_dwordx4 v79, s[50:51]
	s_waitcnt vmcnt(8)
	v_add_u32_e32 v54, s77, v59
	v_add_u32_e32 v55, s77, v60
	v_add_u32_e32 v56, s77, v61
	v_add_u32_e32 v57, s77, v62
	ds_read_b64_tr_b4 v[50:51], v160 offset:896
	ds_read_b64_tr_b4 v[52:53], v160 offset:1920
	ds_read_b64_tr_b4 v[130:131], v54
	ds_read_b64_tr_b4 v[132:133], v55
	ds_read_b64_tr_b4 v[134:135], v56
	ds_read_b64_tr_b4 v[136:137], v57
	s_waitcnt lgkmcnt(6)
; #define LAS __attribute__((address_space(3)))
; __device__ __forceinline__ void peer_v_tokens(int j, const LAS unsigned short* EL, const LAS unsigned char* AL  , const LAS float* ASC  , const LAS int* SAL  , ...
;     ...
;         for (int st = 0; st < 16; ++st) {
;             const int p = st >> 2, q = st & 3;
;             if (st < 14) VDMA(st + 2, (st + 2) % 3);
;             if (st < 14) asm volatile("s_waitcnt vmcnt(8)" ::: "memory");
;             else if (st == 14) asm volatile("s_waitcnt vmcnt(4)" ::: "memory");
;             else asm volatile("s_waitcnt vmcnt(0)" ::: "memory");
;             if (q == 0) {
; #pragma unroll
;                 for (int r = 0; r < 4; ++r) { accH[r] = 0; accL[r] = 0; } }
; #pragma unroll
;             for (int tp = 0; tp < 2; ++tp) {
;                 const v2i ao = TR4(ATL + (2 * q + tp) * 128 + 8 * s16), ah = TR4(ATL + 1024 + (2 * q + tp) * 128 + 8 * s16);
; #pragma unroll
;                 for (int r = 0; r < 4; ++r) {
;                     const v2i d = TR4(ldsb + BUF[st % 3] + 2048 * tp + roff[r]);
;                     accH[r] = __builtin_amdgcn_sdot8(d.x, ah.x, accH[r], false); accH[r] = __builtin_amdgcn_sdot8(d.y, ah.y, accH[r], false);
;                     accL[r] = __builtin_amdgcn_sdot8(d.x, ao.x, accL[r], false); accL[r] = __builtin_amdgcn_sdot8(d.y, ao.y, accL[r], false);
;                 }
;             }
;             asm volatile("s_waitcnt lgkmcnt(0)" ::: "memory");
;             if (q == 3) {
; #pragma unroll
;                 for (int r = 0; r < 4; ++r) STASH[256 * p + 16 * (grp + 4 * r) + pc] = f2bf(asc * (float)(2 * ((accH[r] << 4) + accL[r]) + sa));
;             }
;         }
;     ...
;         {
;             float4 v[4]; float ss = 0.f;
; #pragma unroll
;             for (int jq = 0; jq < 4; ++jq) { typedef unsigned u2v __attribute__((ext_vector_type(2))); const u2v pw = *(const LAS u2v*)(STASH + 4 * lane + 256 * jq); const uint2 hw = hv[jq];
;                 v[jq] = make_float4(__uint_as_float(hw.x << 16) + __uint_as_float(pw.x << 16), __uint_as_float(hw.x & 0xffff0000u) + __uint_as_float(pw.x & 0xffff0000u),
;                                     __uint_as_float(hw.y << 16) + __uint_as_float(pw.y << 16), __uint_as_float(hw.y & 0xffff0000u) + __uint_as_float(pw.y & 0xffff0000u));
;                 ss += v[jq].x * v[jq].x + v[jq].y * v[jq].y + v[jq].z * v[jq].z + v[jq].w * v[jq].w; }
	v_dot8c_i32_i4_e32 v38, v122, v48
	v_dot8c_i32_i4_e32 v39, v122, v46
	v_dot8c_i32_i4_e32 v40, v124, v48
	v_dot8c_i32_i4_e32 v41, v124, v46
	v_dot8c_i32_i4_e32 v42, v126, v48
	v_dot8c_i32_i4_e32 v43, v126, v46
	v_dot8c_i32_i4_e32 v44, v128, v48
	v_dot8c_i32_i4_e32 v45, v128, v46
	v_dot8c_i32_i4_e32 v38, v123, v49
	v_dot8c_i32_i4_e32 v39, v123, v47
	v_dot8c_i32_i4_e32 v40, v125, v49
	v_dot8c_i32_i4_e32 v41, v125, v47
	v_dot8c_i32_i4_e32 v42, v127, v49
	v_dot8c_i32_i4_e32 v43, v127, v47
	v_dot8c_i32_i4_e32 v44, v129, v49
	v_dot8c_i32_i4_e32 v45, v129, v47
	v_and_b32_e32 v78, 0xffff, v30
	v_lshrrev_b32_e32 v79, 16, v30
	v_lshl_add_u32 v78, v78, 7, v150
	v_lshl_add_u32 v79, v79, 7, v151
	s_mov_b32 m0, s76
	s_add_i32 s43, s76, 0x400
	global_load_lds_dwordx4 v78, s[50:51]
	s_mov_b32 m0, s43
	s_nop 0
	global_load_lds_dwordx4 v79, s[50:51]
	s_waitcnt vmcnt(8)
	v_add_u32_e32 v54, s78, v59
	v_add_u32_e32 v55, s78, v60
	v_add_u32_e32 v56, s78, v61
	v_add_u32_e32 v57, s78, v62
	ds_read_b64_tr_b4 v[46:47], v160
	ds_read_b64_tr_b4 v[48:49], v160 offset:1024
	ds_read_b64_tr_b4 v[122:123], v54
	ds_read_b64_tr_b4 v[124:125], v55
	ds_read_b64_tr_b4 v[126:127], v56
	ds_read_b64_tr_b4 v[128:129], v57
	s_waitcnt lgkmcnt(6)
	v_dot8c_i32_i4_e32 v38, v130, v52
	v_dot8c_i32_i4_e32 v39, v130, v50
	v_dot8c_i32_i4_e32 v40, v132, v52
	v_dot8c_i32_i4_e32 v41, v132, v50
	v_dot8c_i32_i4_e32 v42, v134, v52
	v_dot8c_i32_i4_e32 v43, v134, v50
	v_dot8c_i32_i4_e32 v44, v136, v52
	v_dot8c_i32_i4_e32 v45, v136, v50
	v_dot8c_i32_i4_e32 v38, v131, v53
	v_dot8c_i32_i4_e32 v39, v131, v51
	v_dot8c_i32_i4_e32 v40, v133, v53
	v_dot8c_i32_i4_e32 v41, v133, v51
	v_dot8c_i32_i4_e32 v42, v135, v53
	v_dot8c_i32_i4_e32 v43, v135, v51
	v_dot8c_i32_i4_e32 v44, v137, v53
	v_dot8c_i32_i4_e32 v45, v137, v51
	s_nop 3
	s_waitcnt lgkmcnt(15)
	v_lshlrev_b32_e32 v38, 5, v38
	v_lshlrev_b32_e32 v39, 1, v39
	v_add3_u32 v38, v39, v229, v38
	v_cvt_f32_i32_e32 v38, v38
	v_mul_f32_e32 v38, v228, v38
	v_lshlrev_b32_e32 v40, 5, v40
	v_lshlrev_b32_e32 v41, 1, v41
	v_add3_u32 v40, v41, v229, v40
	v_cvt_f32_i32_e32 v40, v40
	v_mul_f32_e32 v40, v228, v40
	v_lshlrev_b32_e32 v42, 5, v42
	v_lshlrev_b32_e32 v43, 1, v43
	v_add3_u32 v42, v43, v229, v42
	v_cvt_f32_i32_e32 v42, v42
	v_mul_f32_e32 v42, v228, v42
	v_lshlrev_b32_e32 v44, 5, v44
	v_lshlrev_b32_e32 v45, 1, v45
	v_add3_u32 v44, v45, v229, v44
	v_cvt_f32_i32_e32 v44, v44
	v_mul_f32_e32 v44, v228, v44
	v_cvt_pk_bf16_f32 v178, v38, v40
	v_cvt_pk_bf16_f32 v179, v42, v44
	v_add_u32_e32 v147, 8, v140
	v_and_b32_e32 v146, 15, v147
	v_xor_b32_e32 v146, 8, v146
	v_bfe_u32 v148, v147, 4, 4
	v_mul_lo_u32 v146, v146, s92
	v_mul_lo_u32 v148, v148, s92
	v_mov_b32_e32 v147, v146
	v_mov_b32_e32 v149, v148
	ds_write2st64_b64 v77, v[146:147], v[148:149] offset1:2
	v_add_u32_e32 v138, 0x1800, v74
	ds_read_u8 v139, v138
	v_add_u32_e32 v141, 0x1800, v73
	ds_read_u8 v140, v141
	s_add_i32 s43, s67, 224
	v_mov_b32_e32 v138, s43
	ds_read2st64_b32 v[228:229], v138 offset1:1
	ds_read_b128 v[18:21], v227 offset:12288
	ds_read_b128 v[22:25], v227 offset:12304
	v_add_u32_e32 v152, 0x200000, v63
	v_add_u32_e32 v153, 0x200000, v64
	v_mov_b32_e32 v38, 0
	v_mov_b32_e32 v39, 0
	v_mov_b32_e32 v40, 0
	v_mov_b32_e32 v41, 0
	v_mov_b32_e32 v42, 0
	v_mov_b32_e32 v43, 0
	v_mov_b32_e32 v44, 0
	v_mov_b32_e32 v45, 0
	v_and_b32_e32 v78, 0xffff, v31
	v_lshrrev_b32_e32 v79, 16, v31
	v_lshl_add_u32 v78, v78, 7, v150
	v_lshl_add_u32 v79, v79, 7, v151
	s_mov_b32 m0, s77
	s_add_i32 s43, s77, 0x400
	global_load_lds_dwordx4 v78, s[50:51]
	s_mov_b32 m0, s43
	s_nop 0
	global_load_lds_dwordx4 v79, s[50:51]
	s_waitcnt vmcnt(8)
	v_add_u32_e32 v54, s79, v59
	v_add_u32_e32 v55, s79, v60
	v_add_u32_e32 v56, s79, v61
	v_add_u32_e32 v57, s79, v62
	ds_read_b64_tr_b4 v[50:51], v160 offset:128
	ds_read_b64_tr_b4 v[52:53], v160 offset:1152
	ds_read_b64_tr_b4 v[130:131], v54
	ds_read_b64_tr_b4 v[132:133], v55
	ds_read_b64_tr_b4 v[134:135], v56
	ds_read_b64_tr_b4 v[136:137], v57
	s_waitcnt lgkmcnt(12)
	s_waitcnt vmcnt(35) lgkmcnt(15)
	v_lshlrev_b32_e32 v210, 16, v194
	v_and_b32_e32 v211, 0xffff0000, v194
	v_lshlrev_b32_e32 v142, 16, v202
	v_and_b32_e32 v143, 0xffff0000, v202
	v_add_f32_e32 v210, v210, v142
	v_add_f32_e32 v211, v211, v143
	v_lshlrev_b32_e32 v212, 16, v195
	v_and_b32_e32 v213, 0xffff0000, v195
	v_lshlrev_b32_e32 v142, 16, v203
	v_and_b32_e32 v143, 0xffff0000, v203
	v_add_f32_e32 v212, v212, v142
	v_add_f32_e32 v213, v213, v143
	v_lshlrev_b32_e32 v214, 16, v196
	v_and_b32_e32 v215, 0xffff0000, v196
	v_lshlrev_b32_e32 v142, 16, v204
	v_and_b32_e32 v143, 0xffff0000, v204
	v_add_f32_e32 v214, v214, v142
	v_add_f32_e32 v215, v215, v143
	v_lshlrev_b32_e32 v216, 16, v197
	v_and_b32_e32 v217, 0xffff0000, v197
	v_lshlrev_b32_e32 v142, 16, v205
	v_and_b32_e32 v143, 0xffff0000, v205
	v_add_f32_e32 v216, v216, v142
	v_add_f32_e32 v217, v217, v143
	v_lshlrev_b32_e32 v218, 16, v198
	v_and_b32_e32 v219, 0xffff0000, v198
	v_lshlrev_b32_e32 v142, 16, v206
	v_and_b32_e32 v143, 0xffff0000, v206
	v_add_f32_e32 v218, v218, v142
	v_add_f32_e32 v219, v219, v143
	v_lshlrev_b32_e32 v220, 16, v199
	v_and_b32_e32 v221, 0xffff0000, v199
	v_lshlrev_b32_e32 v142, 16, v207
	v_and_b32_e32 v143, 0xffff0000, v207
	v_add_f32_e32 v220, v220, v142
	v_add_f32_e32 v221, v221, v143
	v_lshlrev_b32_e32 v222, 16, v200
	v_and_b32_e32 v223, 0xffff0000, v200
	v_lshlrev_b32_e32 v142, 16, v208
	v_and_b32_e32 v143, 0xffff0000, v208
	v_add_f32_e32 v222, v222, v142
	v_add_f32_e32 v223, v223, v143
	v_lshlrev_b32_e32 v224, 16, v201
	v_and_b32_e32 v225, 0xffff0000, v201
	v_lshlrev_b32_e32 v142, 16, v209
	v_and_b32_e32 v143, 0xffff0000, v209
	v_add_f32_e32 v224, v224, v142
; #define TR4(p_) __builtin_amdgcn_ds_read_tr4_b64_v2i32((LAS v2i*)(p_))
; #define VDMA(st_, k_) do { _Pragma("unroll") for (int i_ = 0; i_ < 4; ++i_) { \
;         const unsigned off_ = (unsigned)((st_) >> 2) * (16384u * 128u) + (PE_ID(E, 4 * ((st_) & 3) + i_) << 7) + ((i_ & 1) ? cx1 : cx0); \
;         __builtin_amdgcn_global_load_lds((const unsigned*)(V4 + off_), (LAS unsigned*)(ldsb + BUF[k_] + 1024 * i_), 16, 0, 0); } } while (0)
; __device__ __forceinline__ void peer_v_tokens(int j, const LAS unsigned short* EL, const LAS unsigned char* AL  , const LAS float* ASC  , const LAS int* SAL  , ...
;     ...
;         for (int st = 0; st < 16; ++st) {
;             const int p = st >> 2, q = st & 3;
;             if (st < 14) VDMA(st + 2, (st + 2) % 3);
;             if (st < 14) asm volatile("s_waitcnt vmcnt(8)" ::: "memory");
;             else if (st == 14) asm volatile("s_waitcnt vmcnt(4)" ::: "memory");
;             else asm volatile("s_waitcnt vmcnt(0)" ::: "memory");
;             if (q == 0) {
; #pragma unroll
;                 for (int r = 0; r < 4; ++r) { accH[r] = 0; accL[r] = 0; } }
; #pragma unroll
;             for (int tp = 0; tp < 2; ++tp) {
;                 const v2i ao = TR4(ATL + (2 * q + tp) * 128 + 8 * s16), ah = TR4(ATL + 1024 + (2 * q + tp) * 128 + 8 * s16);
; #pragma unroll
;                 for (int r = 0; r < 4; ++r) {
;                     const v2i d = TR4(ldsb + BUF[st % 3] + 2048 * tp + roff[r]);
;                     accH[r] = __builtin_amdgcn_sdot8(d.x, ah.x, accH[r], false); accH[r] = __builtin_amdgcn_sdot8(d.y, ah.y, accH[r], false);
;                     accL[r] = __builtin_amdgcn_sdot8(d.x, ao.x, accL[r], false); accL[r] = __builtin_amdgcn_sdot8(d.y, ao.y, accL[r], false);
;                 }
;             }
;     ...
;                                     __uint_as_float(hw.y << 16) + __uint_as_float(pw.y << 16), __uint_as_float(hw.y & 0xffff0000u) + __uint_as_float(pw.y & 0xffff0000u));
;                 ss += v[jq].x * v[jq].x + v[jq].y * v[jq].y + v[jq].z * v[jq].z + v[jq].w * v[jq].w; }
;             ss = wave_sum(ss);
;             const float r3 = rsqrtf(ss * (1.f / D) + EPS);
	v_add_f32_e32 v225, v225, v143
	v_mov_b32_e32 v144, 0
	v_mul_f32_e32 v145, v210, v210
	v_fmac_f32_e32 v145, v211, v211
	v_fmac_f32_e32 v145, v212, v212
	v_fmac_f32_e32 v145, v213, v213
	v_add_f32_e32 v144, v144, v145
	v_mul_f32_e32 v145, v214, v214
	v_fmac_f32_e32 v145, v215, v215
	v_fmac_f32_e32 v145, v216, v216
	v_fmac_f32_e32 v145, v217, v217
	v_add_f32_e32 v144, v144, v145
	v_mul_f32_e32 v145, v218, v218
	v_fmac_f32_e32 v145, v219, v219
	v_fmac_f32_e32 v145, v220, v220
	v_fmac_f32_e32 v145, v221, v221
	v_add_f32_e32 v144, v144, v145
	v_mul_f32_e32 v145, v222, v222
	v_fmac_f32_e32 v145, v223, v223
	v_fmac_f32_e32 v145, v224, v224
	v_fmac_f32_e32 v145, v225, v225
	v_add_f32_e32 v144, v144, v145
	s_nop 1
	v_add_f32_dpp v144, v144, v144 quad_perm:[1,0,3,2] row_mask:0xf bank_mask:0xf bound_ctrl:1
	s_nop 1
	v_add_f32_dpp v144, v144, v144 quad_perm:[2,3,0,1] row_mask:0xf bank_mask:0xf bound_ctrl:1
	s_nop 1
	v_add_f32_dpp v144, v144, v144 row_half_mirror row_mask:0xf bank_mask:0xf bound_ctrl:1
	s_nop 1
	v_add_f32_dpp v144, v144, v144 row_mirror row_mask:0xf bank_mask:0xf bound_ctrl:1
	s_nop 1
	v_readlane_b32 s10, v144, 0
	v_readlane_b32 s11, v144, 16
	v_readlane_b32 s14, v144, 32
	v_readlane_b32 s15, v144, 48
	s_nop 3
	v_mov_b32_e32 v144, s11
	v_mov_b32_e32 v145, s15
	v_add_f32_e32 v144, s10, v144
	v_add_f32_e32 v145, s14, v145
	v_add_f32_e32 v144, v144, v145
	v_fmamk_f32 v144, v144, 0x3a800000, v111
	v_rsq_f32_e32 v144, v144
	s_nop 0
	v_mul_f32_e32 v210, v210, v144
	v_mul_f32_e32 v211, v211, v144
	v_mul_f32_e32 v212, v212, v144
	v_mul_f32_e32 v213, v213, v144
	v_mul_f32_e32 v214, v214, v144
	v_mul_f32_e32 v215, v215, v144
	v_mul_f32_e32 v216, v216, v144
	v_mul_f32_e32 v217, v217, v144
	v_mul_f32_e32 v218, v218, v144
	v_mul_f32_e32 v219, v219, v144
	v_mul_f32_e32 v220, v220, v144
	v_mul_f32_e32 v221, v221, v144
	v_mul_f32_e32 v222, v222, v144
	v_mul_f32_e32 v223, v223, v144
	v_mul_f32_e32 v224, v224, v144
	v_mul_f32_e32 v225, v225, v144
	v_dot8c_i32_i4_e32 v38, v122, v48
	v_dot8c_i32_i4_e32 v39, v122, v46
	v_dot8c_i32_i4_e32 v40, v124, v48
	v_dot8c_i32_i4_e32 v41, v124, v46
	v_dot8c_i32_i4_e32 v42, v126, v48
	v_dot8c_i32_i4_e32 v43, v126, v46
	v_dot8c_i32_i4_e32 v44, v128, v48
	v_dot8c_i32_i4_e32 v45, v128, v46
	v_dot8c_i32_i4_e32 v38, v123, v49
	v_dot8c_i32_i4_e32 v39, v123, v47
	v_dot8c_i32_i4_e32 v40, v125, v49
	v_dot8c_i32_i4_e32 v41, v125, v47
	v_dot8c_i32_i4_e32 v42, v127, v49
	v_dot8c_i32_i4_e32 v43, v127, v47
	v_dot8c_i32_i4_e32 v44, v129, v49
	v_dot8c_i32_i4_e32 v45, v129, v47
	v_and_b32_e32 v78, 0xffff, v32
	v_lshrrev_b32_e32 v79, 16, v32
	v_lshl_add_u32 v78, v78, 7, v150
	v_lshl_add_u32 v79, v79, 7, v151
	s_mov_b32 m0, s78
	s_add_i32 s43, s78, 0x400
	global_load_lds_dwordx4 v78, s[50:51]
	s_mov_b32 m0, s43
	s_nop 0
	global_load_lds_dwordx4 v79, s[50:51]
	s_waitcnt vmcnt(8)
	v_add_u32_e32 v54, s98, v59
	v_add_u32_e32 v55, s98, v60
	v_add_u32_e32 v56, s98, v61
	v_add_u32_e32 v57, s98, v62
	ds_read_b64_tr_b4 v[46:47], v160 offset:256
	ds_read_b64_tr_b4 v[48:49], v160 offset:1280
	ds_read_b64_tr_b4 v[122:123], v54
	ds_read_b64_tr_b4 v[124:125], v55
	ds_read_b64_tr_b4 v[126:127], v56
	ds_read_b64_tr_b4 v[128:129], v57
	s_waitcnt lgkmcnt(6)
	v_dot8c_i32_i4_e32 v38, v130, v52
	v_dot8c_i32_i4_e32 v39, v130, v50
	v_dot8c_i32_i4_e32 v40, v132, v52
	v_dot8c_i32_i4_e32 v41, v132, v50
	v_dot8c_i32_i4_e32 v42, v134, v52
	v_dot8c_i32_i4_e32 v43, v134, v50
	v_dot8c_i32_i4_e32 v44, v136, v52
	v_dot8c_i32_i4_e32 v45, v136, v50
	v_dot8c_i32_i4_e32 v38, v131, v53
	v_dot8c_i32_i4_e32 v39, v131, v51
	v_dot8c_i32_i4_e32 v40, v133, v53
	v_dot8c_i32_i4_e32 v41, v133, v51
	v_dot8c_i32_i4_e32 v42, v135, v53
	v_dot8c_i32_i4_e32 v43, v135, v51
	v_dot8c_i32_i4_e32 v44, v137, v53
	v_dot8c_i32_i4_e32 v45, v137, v51
	v_and_b32_e32 v78, 0xffff, v33
	v_lshrrev_b32_e32 v79, 16, v33
	v_lshl_add_u32 v78, v78, 7, v150
	v_lshl_add_u32 v79, v79, 7, v151
	s_mov_b32 m0, s79
	s_add_i32 s43, s79, 0x400
	global_load_lds_dwordx4 v78, s[50:51]
	s_mov_b32 m0, s43
	s_nop 0
	global_load_lds_dwordx4 v79, s[50:51]
	s_waitcnt vmcnt(8)
	v_add_u32_e32 v54, s99, v59
	v_add_u32_e32 v55, s99, v60
	v_add_u32_e32 v56, s99, v61
	v_add_u32_e32 v57, s99, v62
	ds_read_b64_tr_b4 v[50:51], v160 offset:384
	ds_read_b64_tr_b4 v[52:53], v160 offset:1408
	ds_read_b64_tr_b4 v[130:131], v54
	ds_read_b64_tr_b4 v[132:133], v55
	ds_read_b64_tr_b4 v[134:135], v56
	ds_read_b64_tr_b4 v[136:137], v57
	s_waitcnt lgkmcnt(6)
	v_dot8c_i32_i4_e32 v38, v122, v48
	v_dot8c_i32_i4_e32 v39, v122, v46
	v_dot8c_i32_i4_e32 v40, v124, v48
	v_dot8c_i32_i4_e32 v41, v124, v46
	v_dot8c_i32_i4_e32 v42, v126, v48
	v_dot8c_i32_i4_e32 v43, v126, v46
	v_dot8c_i32_i4_e32 v44, v128, v48
	v_dot8c_i32_i4_e32 v45, v128, v46
	v_dot8c_i32_i4_e32 v38, v123, v49
	v_dot8c_i32_i4_e32 v39, v123, v47
	v_dot8c_i32_i4_e32 v40, v125, v49
	v_dot8c_i32_i4_e32 v41, v125, v47
	v_dot8c_i32_i4_e32 v42, v127, v49
	v_dot8c_i32_i4_e32 v43, v127, v47
	v_dot8c_i32_i4_e32 v44, v129, v49
	v_dot8c_i32_i4_e32 v45, v129, v47
	s_waitcnt lgkmcnt(15)
	v_and_b32_e32 v78, 0xffff, v18
	v_lshrrev_b32_e32 v79, 16, v18
	v_lshl_add_u32 v78, v78, 7, v152
	v_lshl_add_u32 v79, v79, 7, v153
	s_mov_b32 m0, s98
	s_add_i32 s43, s98, 0x400
	global_load_lds_dwordx4 v78, s[50:51]
	s_mov_b32 m0, s43
	s_nop 0
	global_load_lds_dwordx4 v79, s[50:51]
	s_waitcnt vmcnt(8)
	v_add_u32_e32 v54, s76, v59
	v_add_u32_e32 v55, s76, v60
	v_add_u32_e32 v56, s76, v61
	v_add_u32_e32 v57, s76, v62
	ds_read_b64_tr_b4 v[46:47], v160 offset:512
	ds_read_b64_tr_b4 v[48:49], v160 offset:1536
	ds_read_b64_tr_b4 v[122:123], v54
	ds_read_b64_tr_b4 v[124:125], v55
	ds_read_b64_tr_b4 v[126:127], v56
	ds_read_b64_tr_b4 v[128:129], v57
	s_waitcnt lgkmcnt(6)
; #define TR4(p_) __builtin_amdgcn_ds_read_tr4_b64_v2i32((LAS v2i*)(p_))
; #define VDMA(st_, k_) do { _Pragma("unroll") for (int i_ = 0; i_ < 4; ++i_) { \
;         const unsigned off_ = (unsigned)((st_) >> 2) * (16384u * 128u) + (PE_ID(E, 4 * ((st_) & 3) + i_) << 7) + ((i_ & 1) ? cx1 : cx0); \
;         __builtin_amdgcn_global_load_lds((const unsigned*)(V4 + off_), (LAS unsigned*)(ldsb + BUF[k_] + 1024 * i_), 16, 0, 0); } } while (0)
; __device__ __forceinline__ void peer_v_tokens(int j, const LAS unsigned short* EL, const LAS unsigned char* AL  , const LAS float* ASC  , const LAS int* SAL  , ...
;     ...
;         for (int st = 0; st < 16; ++st) {
;             const int p = st >> 2, q = st & 3;
;             if (st < 14) VDMA(st + 2, (st + 2) % 3);
;             if (st < 14) asm volatile("s_waitcnt vmcnt(8)" ::: "memory");
;             else if (st == 14) asm volatile("s_waitcnt vmcnt(4)" ::: "memory");
;             else asm volatile("s_waitcnt vmcnt(0)" ::: "memory");
;             if (q == 0) {
; #pragma unroll
;                 for (int r = 0; r < 4; ++r) { accH[r] = 0; accL[r] = 0; } }
; #pragma unroll
;             for (int tp = 0; tp < 2; ++tp) {
;                 const v2i ao = TR4(ATL + (2 * q + tp) * 128 + 8 * s16), ah = TR4(ATL + 1024 + (2 * q + tp) * 128 + 8 * s16);
; #pragma unroll
;                 for (int r = 0; r < 4; ++r) {
;                     const v2i d = TR4(ldsb + BUF[st % 3] + 2048 * tp + roff[r]);
;                     accH[r] = __builtin_amdgcn_sdot8(d.x, ah.x, accH[r], false); accH[r] = __builtin_amdgcn_sdot8(d.y, ah.y, accH[r], false);
;                     accL[r] = __builtin_amdgcn_sdot8(d.x, ao.x, accL[r], false); accL[r] = __builtin_amdgcn_sdot8(d.y, ao.y, accL[r], false);
;                 }
;             }
;             asm volatile("s_waitcnt lgkmcnt(0)" ::: "memory");
	v_dot8c_i32_i4_e32 v38, v130, v52
	v_dot8c_i32_i4_e32 v39, v130, v50
	v_dot8c_i32_i4_e32 v40, v132, v52
	v_dot8c_i32_i4_e32 v41, v132, v50
	v_dot8c_i32_i4_e32 v42, v134, v52
	v_dot8c_i32_i4_e32 v43, v134, v50
	v_dot8c_i32_i4_e32 v44, v136, v52
	v_dot8c_i32_i4_e32 v45, v136, v50
	v_dot8c_i32_i4_e32 v38, v131, v53
	v_dot8c_i32_i4_e32 v39, v131, v51
	v_dot8c_i32_i4_e32 v40, v133, v53
	v_dot8c_i32_i4_e32 v41, v133, v51
	v_dot8c_i32_i4_e32 v42, v135, v53
	v_dot8c_i32_i4_e32 v43, v135, v51
	v_dot8c_i32_i4_e32 v44, v137, v53
	v_dot8c_i32_i4_e32 v45, v137, v51
	v_and_b32_e32 v78, 0xffff, v19
	v_lshrrev_b32_e32 v79, 16, v19
	v_lshl_add_u32 v78, v78, 7, v152
	v_lshl_add_u32 v79, v79, 7, v153
	s_mov_b32 m0, s99
	s_add_i32 s43, s99, 0x400
	global_load_lds_dwordx4 v78, s[50:51]
	s_mov_b32 m0, s43
	s_nop 0
	global_load_lds_dwordx4 v79, s[50:51]
	s_waitcnt vmcnt(8)
	v_add_u32_e32 v54, s77, v59
	v_add_u32_e32 v55, s77, v60
	v_add_u32_e32 v56, s77, v61
	v_add_u32_e32 v57, s77, v62
	ds_read_b64_tr_b4 v[50:51], v160 offset:640
	ds_read_b64_tr_b4 v[52:53], v160 offset:1664
	ds_read_b64_tr_b4 v[130:131], v54
	ds_read_b64_tr_b4 v[132:133], v55
	ds_read_b64_tr_b4 v[134:135], v56
	ds_read_b64_tr_b4 v[136:137], v57
	s_waitcnt lgkmcnt(6)
	v_dot8c_i32_i4_e32 v38, v122, v48
	v_dot8c_i32_i4_e32 v39, v122, v46
	v_dot8c_i32_i4_e32 v40, v124, v48
	v_dot8c_i32_i4_e32 v41, v124, v46
	v_dot8c_i32_i4_e32 v42, v126, v48
	v_dot8c_i32_i4_e32 v43, v126, v46
	v_dot8c_i32_i4_e32 v44, v128, v48
	v_dot8c_i32_i4_e32 v45, v128, v46
	v_dot8c_i32_i4_e32 v38, v123, v49
	v_dot8c_i32_i4_e32 v39, v123, v47
	v_dot8c_i32_i4_e32 v40, v125, v49
	v_dot8c_i32_i4_e32 v41, v125, v47
	v_dot8c_i32_i4_e32 v42, v127, v49
	v_dot8c_i32_i4_e32 v43, v127, v47
	v_dot8c_i32_i4_e32 v44, v129, v49
	v_dot8c_i32_i4_e32 v45, v129, v47
	s_waitcnt lgkmcnt(15)
	v_add_u32_e32 v143, 8, v139
	v_and_b32_e32 v142, 15, v143
	v_xor_b32_e32 v142, 8, v142
	v_bfe_u32 v144, v143, 4, 4
	v_mul_lo_u32 v142, v142, s92
	v_mul_lo_u32 v144, v144, s92
	v_mov_b32_e32 v143, v142
	v_mov_b32_e32 v145, v144
	ds_write2st64_b64 v159, v[142:143], v[144:145] offset1:2
	v_and_b32_e32 v78, 0xffff, v20
	v_lshrrev_b32_e32 v79, 16, v20
	v_lshl_add_u32 v78, v78, 7, v152
	v_lshl_add_u32 v79, v79, 7, v153
	s_mov_b32 m0, s76
	s_add_i32 s43, s76, 0x400
	global_load_lds_dwordx4 v78, s[50:51]
	s_mov_b32 m0, s43
	s_nop 0
	global_load_lds_dwordx4 v79, s[50:51]
	s_waitcnt vmcnt(8)
	v_add_u32_e32 v54, s78, v59
	v_add_u32_e32 v55, s78, v60
	v_add_u32_e32 v56, s78, v61
	v_add_u32_e32 v57, s78, v62
	ds_read_b64_tr_b4 v[46:47], v160 offset:768
	ds_read_b64_tr_b4 v[48:49], v160 offset:1792
	ds_read_b64_tr_b4 v[122:123], v54
	ds_read_b64_tr_b4 v[124:125], v55
	ds_read_b64_tr_b4 v[126:127], v56
	ds_read_b64_tr_b4 v[128:129], v57
	s_waitcnt lgkmcnt(7)
	v_dot8c_i32_i4_e32 v38, v130, v52
	v_dot8c_i32_i4_e32 v39, v130, v50
	v_dot8c_i32_i4_e32 v40, v132, v52
	v_dot8c_i32_i4_e32 v41, v132, v50
	v_dot8c_i32_i4_e32 v42, v134, v52
	v_dot8c_i32_i4_e32 v43, v134, v50
	v_dot8c_i32_i4_e32 v44, v136, v52
	v_dot8c_i32_i4_e32 v45, v136, v50
	v_dot8c_i32_i4_e32 v38, v131, v53
	v_dot8c_i32_i4_e32 v39, v131, v51
	v_dot8c_i32_i4_e32 v40, v133, v53
	v_dot8c_i32_i4_e32 v41, v133, v51
	v_dot8c_i32_i4_e32 v42, v135, v53
	v_dot8c_i32_i4_e32 v43, v135, v51
	v_dot8c_i32_i4_e32 v44, v137, v53
	v_dot8c_i32_i4_e32 v45, v137, v51
	v_and_b32_e32 v78, 0xffff, v21
	v_lshrrev_b32_e32 v79, 16, v21
	v_lshl_add_u32 v78, v78, 7, v152
	v_lshl_add_u32 v79, v79, 7, v153
	s_mov_b32 m0, s77
	s_add_i32 s43, s77, 0x400
	global_load_lds_dwordx4 v78, s[50:51]
	s_mov_b32 m0, s43
	s_nop 0
	global_load_lds_dwordx4 v79, s[50:51]
	s_waitcnt vmcnt(8)
	v_add_u32_e32 v54, s79, v59
	v_add_u32_e32 v55, s79, v60
	v_add_u32_e32 v56, s79, v61
	v_add_u32_e32 v57, s79, v62
	ds_read_b64_tr_b4 v[50:51], v160 offset:896
	ds_read_b64_tr_b4 v[52:53], v160 offset:1920
	ds_read_b64_tr_b4 v[130:131], v54
	ds_read_b64_tr_b4 v[132:133], v55
	ds_read_b64_tr_b4 v[134:135], v56
	ds_read_b64_tr_b4 v[136:137], v57
	s_waitcnt lgkmcnt(6)
	v_dot8c_i32_i4_e32 v38, v122, v48
	v_dot8c_i32_i4_e32 v39, v122, v46
	v_dot8c_i32_i4_e32 v40, v124, v48
	v_dot8c_i32_i4_e32 v41, v124, v46
	v_dot8c_i32_i4_e32 v42, v126, v48
	v_dot8c_i32_i4_e32 v43, v126, v46
	v_dot8c_i32_i4_e32 v44, v128, v48
	v_dot8c_i32_i4_e32 v45, v128, v46
	v_dot8c_i32_i4_e32 v38, v123, v49
	v_dot8c_i32_i4_e32 v39, v123, v47
	v_dot8c_i32_i4_e32 v40, v125, v49
	v_dot8c_i32_i4_e32 v41, v125, v47
	v_dot8c_i32_i4_e32 v42, v127, v49
	v_dot8c_i32_i4_e32 v43, v127, v47
	v_dot8c_i32_i4_e32 v44, v129, v49
	v_dot8c_i32_i4_e32 v45, v129, v47
	v_and_b32_e32 v78, 0xffff, v22
	v_lshrrev_b32_e32 v79, 16, v22
	v_lshl_add_u32 v78, v78, 7, v152
	v_lshl_add_u32 v79, v79, 7, v153
	s_mov_b32 m0, s78
	s_add_i32 s43, s78, 0x400
	global_load_lds_dwordx4 v78, s[50:51]
	s_mov_b32 m0, s43
	s_nop 0
	global_load_lds_dwordx4 v79, s[50:51]
	s_waitcnt vmcnt(8)
	v_add_u32_e32 v54, s98, v59
	v_add_u32_e32 v55, s98, v60
	v_add_u32_e32 v56, s98, v61
	v_add_u32_e32 v57, s98, v62
	ds_read_b64_tr_b4 v[46:47], v160
	ds_read_b64_tr_b4 v[48:49], v160 offset:1024
	ds_read_b64_tr_b4 v[122:123], v54
	ds_read_b64_tr_b4 v[124:125], v55
	ds_read_b64_tr_b4 v[126:127], v56
	ds_read_b64_tr_b4 v[128:129], v57
	s_waitcnt lgkmcnt(6)
	v_dot8c_i32_i4_e32 v38, v130, v52
	v_dot8c_i32_i4_e32 v39, v130, v50
	v_dot8c_i32_i4_e32 v40, v132, v52
	v_dot8c_i32_i4_e32 v41, v132, v50
	v_dot8c_i32_i4_e32 v42, v134, v52
	v_dot8c_i32_i4_e32 v43, v134, v50
	v_dot8c_i32_i4_e32 v44, v136, v52
	v_dot8c_i32_i4_e32 v45, v136, v50
	v_dot8c_i32_i4_e32 v38, v131, v53
	v_dot8c_i32_i4_e32 v39, v131, v51
	v_dot8c_i32_i4_e32 v40, v133, v53
	v_dot8c_i32_i4_e32 v41, v133, v51
	v_dot8c_i32_i4_e32 v42, v135, v53
	v_dot8c_i32_i4_e32 v43, v135, v51
	v_dot8c_i32_i4_e32 v44, v137, v53
	v_dot8c_i32_i4_e32 v45, v137, v51
	s_nop 3
	s_waitcnt lgkmcnt(15)
; __device__ __forceinline__ bf16 f2bf(float f) { return (bf16)f2bfu(f); }
; __device__ __forceinline__ void peer_v_tokens(int j, const LAS unsigned short* EL, const LAS unsigned char* AL  , const LAS float* ASC  , const LAS int* SAL  , ...
;     ...
;         { unsigned ho = (unsigned)t * (D / 4) + (unsigned)lane; asm volatile("" : "+v"(ho)); const uint2* hp = (const uint2*)HB + ho; const float4* gp = (const float4*)fng + lane;
; #pragma unroll
;           for (int jq = 0; jq < 4; ++jq) { hv[jq] = hp[64 * jq]; gv[jq] = gp[64 * jq]; } }
;     ...
;                 for (int r = 0; r < 4; ++r) STASH[256 * p + 16 * (grp + 4 * r) + pc] = f2bf(asc * (float)(2 * ((accH[r] << 4) + accL[r]) + sa));
;             }
;         }
;     ...
;             float4* op = (float4*)(outp + (size_t)t * D) + lane;
; #pragma unroll
;             for (int jq = 0; jq < 4; ++jq) { typedef float f4v __attribute__((ext_vector_type(4))); f4v o4; o4.x = v[jq].x * r3 * gv[jq].x; o4.y = v[jq].y * r3 * gv[jq].y; o4.z = v[jq].z * r3 * gv[jq].z; o4.w = v[jq].w * r3 * gv[jq].w;
;                 __builtin_nontemporal_store(o4, (f4v*)op + 64 * jq); }
	v_lshlrev_b32_e32 v38, 5, v38
	v_lshlrev_b32_e32 v39, 1, v39
	v_add3_u32 v38, v39, v229, v38
	v_cvt_f32_i32_e32 v38, v38
	v_mul_f32_e32 v38, v228, v38
	v_lshlrev_b32_e32 v40, 5, v40
	v_lshlrev_b32_e32 v41, 1, v41
	v_add3_u32 v40, v41, v229, v40
	v_cvt_f32_i32_e32 v40, v40
	v_mul_f32_e32 v40, v228, v40
	v_lshlrev_b32_e32 v42, 5, v42
	v_lshlrev_b32_e32 v43, 1, v43
	v_add3_u32 v42, v43, v229, v42
	v_cvt_f32_i32_e32 v42, v42
	v_mul_f32_e32 v42, v228, v42
	v_lshlrev_b32_e32 v44, 5, v44
	v_lshlrev_b32_e32 v45, 1, v45
	v_add3_u32 v44, v45, v229, v44
	v_cvt_f32_i32_e32 v44, v44
	v_mul_f32_e32 v44, v228, v44
	v_cvt_pk_bf16_f32 v186, v38, v40
	v_cvt_pk_bf16_f32 v187, v42, v44
	ds_read_b128 v[252:255], v155
	s_add_i32 s44, s40, 32
	s_ashr_i32 s45, s44, 31
	s_lshl_b64 s[44:45], s[44:45], 12
	v_lshl_add_u64 v[80:81], v[36:37], 0, s[44:45]
	s_waitcnt lgkmcnt(0)
	v_mul_f32_e32 v210, v210, v252
	v_mul_f32_e32 v211, v211, v253
	v_mul_f32_e32 v212, v212, v254
	v_mul_f32_e32 v213, v213, v255
	global_store_dwordx4 v[80:81], v[210:213], off nt
	s_add_i32 s43, s40, 40
	s_lshl_b32 s43, s43, 11
	v_add_u32_e32 v138, s43, v66
	global_load_dwordx2 v[194:195], v138, s[70:71]
	global_load_dwordx2 v[196:197], v138, s[70:71] offset:512
	global_load_dwordx2 v[198:199], v138, s[70:71] offset:1024
	global_load_dwordx2 v[200:201], v138, s[70:71] offset:1536
	v_add_u32_e32 v147, 8, v140
	v_and_b32_e32 v146, 15, v147
	v_xor_b32_e32 v146, 8, v146
	v_bfe_u32 v148, v147, 4, 4
	v_mul_lo_u32 v146, v146, s92
	v_mul_lo_u32 v148, v148, s92
	v_mov_b32_e32 v147, v146
	v_mov_b32_e32 v149, v148
	ds_write2st64_b64 v77, v[146:147], v[148:149] offset1:2
	v_add_u32_e32 v138, 0x1c00, v74
	ds_read_u8 v139, v138
	v_add_u32_e32 v141, 0x1c00, v73
	ds_read_u8 v140, v141
	s_add_i32 s43, s67, 192
	v_mov_b32_e32 v138, s43
	ds_read2st64_b32 v[228:229], v138 offset1:1
	ds_read_b128 v[26:29], v227 offset:14336
	ds_read_b128 v[30:33], v227 offset:14352
	v_mov_b32_e32 v38, 0
	v_mov_b32_e32 v39, 0
	v_mov_b32_e32 v40, 0
	v_mov_b32_e32 v41, 0
	v_mov_b32_e32 v42, 0
	v_mov_b32_e32 v43, 0
	v_mov_b32_e32 v44, 0
	v_mov_b32_e32 v45, 0
	v_and_b32_e32 v78, 0xffff, v23
	v_lshrrev_b32_e32 v79, 16, v23
	v_lshl_add_u32 v78, v78, 7, v152
	v_lshl_add_u32 v79, v79, 7, v153
	s_mov_b32 m0, s79
	s_add_i32 s43, s79, 0x400
	global_load_lds_dwordx4 v78, s[50:51]
	s_mov_b32 m0, s43
	s_nop 0
	global_load_lds_dwordx4 v79, s[50:51]
	s_waitcnt vmcnt(13)
	v_add_u32_e32 v54, s99, v59
	v_add_u32_e32 v55, s99, v60
	v_add_u32_e32 v56, s99, v61
	v_add_u32_e32 v57, s99, v62
	ds_read_b64_tr_b4 v[50:51], v160 offset:128
	ds_read_b64_tr_b4 v[52:53], v160 offset:1152
	ds_read_b64_tr_b4 v[130:131], v54
	ds_read_b64_tr_b4 v[132:133], v55
	ds_read_b64_tr_b4 v[134:135], v56
	ds_read_b64_tr_b4 v[136:137], v57
	s_waitcnt lgkmcnt(13)
	v_dot8c_i32_i4_e32 v38, v122, v48
	v_dot8c_i32_i4_e32 v39, v122, v46
	v_dot8c_i32_i4_e32 v40, v124, v48
	v_dot8c_i32_i4_e32 v41, v124, v46
	v_dot8c_i32_i4_e32 v42, v126, v48
	v_dot8c_i32_i4_e32 v43, v126, v46
	v_dot8c_i32_i4_e32 v44, v128, v48
	v_dot8c_i32_i4_e32 v45, v128, v46
	v_dot8c_i32_i4_e32 v38, v123, v49
	v_dot8c_i32_i4_e32 v39, v123, v47
	v_dot8c_i32_i4_e32 v40, v125, v49
	v_dot8c_i32_i4_e32 v41, v125, v47
	v_dot8c_i32_i4_e32 v42, v127, v49
	v_dot8c_i32_i4_e32 v43, v127, v47
	v_dot8c_i32_i4_e32 v44, v129, v49
	v_dot8c_i32_i4_e32 v45, v129, v47
	v_and_b32_e32 v78, 0xffff, v24
	v_lshrrev_b32_e32 v79, 16, v24
	v_lshl_add_u32 v78, v78, 7, v152
	v_lshl_add_u32 v79, v79, 7, v153
	s_mov_b32 m0, s98
	s_add_i32 s43, s98, 0x400
	global_load_lds_dwordx4 v78, s[50:51]
	s_mov_b32 m0, s43
	s_nop 0
	global_load_lds_dwordx4 v79, s[50:51]
	s_waitcnt vmcnt(13)
	v_add_u32_e32 v54, s76, v59
	v_add_u32_e32 v55, s76, v60
	v_add_u32_e32 v56, s76, v61
	v_add_u32_e32 v57, s76, v62
	ds_read_b64_tr_b4 v[46:47], v160 offset:256
	ds_read_b64_tr_b4 v[48:49], v160 offset:1280
	ds_read_b64_tr_b4 v[122:123], v54
	ds_read_b64_tr_b4 v[124:125], v55
	ds_read_b64_tr_b4 v[126:127], v56
	ds_read_b64_tr_b4 v[128:129], v57
	s_waitcnt lgkmcnt(6)
	v_dot8c_i32_i4_e32 v38, v130, v52
	v_dot8c_i32_i4_e32 v39, v130, v50
	v_dot8c_i32_i4_e32 v40, v132, v52
	v_dot8c_i32_i4_e32 v41, v132, v50
	v_dot8c_i32_i4_e32 v42, v134, v52
	v_dot8c_i32_i4_e32 v43, v134, v50
	v_dot8c_i32_i4_e32 v44, v136, v52
	v_dot8c_i32_i4_e32 v45, v136, v50
	v_dot8c_i32_i4_e32 v38, v131, v53
	v_dot8c_i32_i4_e32 v39, v131, v51
	v_dot8c_i32_i4_e32 v40, v133, v53
	v_dot8c_i32_i4_e32 v41, v133, v51
	v_dot8c_i32_i4_e32 v42, v135, v53
	v_dot8c_i32_i4_e32 v43, v135, v51
	v_dot8c_i32_i4_e32 v44, v137, v53
	v_dot8c_i32_i4_e32 v45, v137, v51
	v_and_b32_e32 v78, 0xffff, v25
	v_lshrrev_b32_e32 v79, 16, v25
	v_lshl_add_u32 v78, v78, 7, v152
	v_lshl_add_u32 v79, v79, 7, v153
	s_mov_b32 m0, s99
	s_add_i32 s43, s99, 0x400
	global_load_lds_dwordx4 v78, s[50:51]
	s_mov_b32 m0, s43
	s_nop 0
	global_load_lds_dwordx4 v79, s[50:51]
	s_waitcnt vmcnt(13)
	v_add_u32_e32 v54, s77, v59
	v_add_u32_e32 v55, s77, v60
	v_add_u32_e32 v56, s77, v61
	v_add_u32_e32 v57, s77, v62
	ds_read_b64_tr_b4 v[50:51], v160 offset:384
	ds_read_b64_tr_b4 v[52:53], v160 offset:1408
	ds_read_b64_tr_b4 v[130:131], v54
	ds_read_b64_tr_b4 v[132:133], v55
	ds_read_b64_tr_b4 v[134:135], v56
	ds_read_b64_tr_b4 v[136:137], v57
	s_waitcnt lgkmcnt(6)
	v_dot8c_i32_i4_e32 v38, v122, v48
	v_dot8c_i32_i4_e32 v39, v122, v46
	v_dot8c_i32_i4_e32 v40, v124, v48
	v_dot8c_i32_i4_e32 v41, v124, v46
	v_dot8c_i32_i4_e32 v42, v126, v48
	v_dot8c_i32_i4_e32 v43, v126, v46
	v_dot8c_i32_i4_e32 v44, v128, v48
	v_dot8c_i32_i4_e32 v45, v128, v46
	v_dot8c_i32_i4_e32 v38, v123, v49
	v_dot8c_i32_i4_e32 v39, v123, v47
	v_dot8c_i32_i4_e32 v40, v125, v49
	v_dot8c_i32_i4_e32 v41, v125, v47
	v_dot8c_i32_i4_e32 v42, v127, v49
	v_dot8c_i32_i4_e32 v43, v127, v47
	v_dot8c_i32_i4_e32 v44, v129, v49
	v_dot8c_i32_i4_e32 v45, v129, v47
	s_waitcnt lgkmcnt(15)
; #define LAS __attribute__((address_space(3)))
; #define TR4(p_) __builtin_amdgcn_ds_read_tr4_b64_v2i32((LAS v2i*)(p_))
; __device__ __forceinline__ void peer_v_tokens(int j, const LAS unsigned short* EL, const LAS unsigned char* AL  , const LAS float* ASC  , const LAS int* SAL  , ...
;     ...
; #pragma unroll
;         for (int m = 0; m < 2; ++m) {
;             const int idx = lane + 64 * m, tau = idx >> 4, sr = idx & 15, k = 16 * (sr & 7) + 2 * tau + (sr >> 3);
;             const int aq = (int)*(const LAS signed char*)(AL + tl * 128 + k); const int tq = aq + 8;
;             const unsigned lo = (((unsigned)tq & 15u) ^ 8u) * 0x11111111u, hi = ((unsigned)(tq >> 4) & 15u) * 0x11111111u;
;             typedef unsigned u2v __attribute__((ext_vector_type(2)));
;             u2v l2; l2.x = lo; l2.y = lo; u2v h2; h2.x = hi; h2.y = hi;
;             *(LAS u2v*)(ATL + 8 * idx) = l2; *(LAS u2v*)(ATL + 1024 + 8 * idx) = h2;
;         }
;     ...
;         for (int st = 0; st < 16; ++st) {
;             const int p = st >> 2, q = st & 3;
;             if (st < 14) VDMA(st + 2, (st + 2) % 3);
;             if (st < 14) asm volatile("s_waitcnt vmcnt(8)" ::: "memory");
;             else if (st == 14) asm volatile("s_waitcnt vmcnt(4)" ::: "memory");
;             else asm volatile("s_waitcnt vmcnt(0)" ::: "memory");
;             if (q == 0) {
; #pragma unroll
;                 for (int r = 0; r < 4; ++r) { accH[r] = 0; accL[r] = 0; } }
; #pragma unroll
;             for (int tp = 0; tp < 2; ++tp) {
;                 const v2i ao = TR4(ATL + (2 * q + tp) * 128 + 8 * s16), ah = TR4(ATL + 1024 + (2 * q + tp) * 128 + 8 * s16);
; #pragma unroll
;                 for (int r = 0; r < 4; ++r) {
;                     const v2i d = TR4(ldsb + BUF[st % 3] + 2048 * tp + roff[r]);
;                     accH[r] = __builtin_amdgcn_sdot8(d.x, ah.x, accH[r], false); accH[r] = __builtin_amdgcn_sdot8(d.y, ah.y, accH[r], false);
;                     accL[r] = __builtin_amdgcn_sdot8(d.x, ao.x, accL[r], false); accL[r] = __builtin_amdgcn_sdot8(d.y, ao.y, accL[r], false);
;                 }
;             }
;             asm volatile("s_waitcnt lgkmcnt(0)" ::: "memory");
	v_and_b32_e32 v78, 0xffff, v26
	v_lshrrev_b32_e32 v79, 16, v26
	v_lshl_add_u32 v78, v78, 7, v152
	v_lshl_add_u32 v79, v79, 7, v153
	s_mov_b32 m0, s76
	s_add_i32 s43, s76, 0x400
	global_load_lds_dwordx4 v78, s[50:51]
	s_mov_b32 m0, s43
	s_nop 0
	global_load_lds_dwordx4 v79, s[50:51]
	s_waitcnt vmcnt(13)
	v_add_u32_e32 v54, s78, v59
	v_add_u32_e32 v55, s78, v60
	v_add_u32_e32 v56, s78, v61
	v_add_u32_e32 v57, s78, v62
	ds_read_b64_tr_b4 v[46:47], v160 offset:512
	ds_read_b64_tr_b4 v[48:49], v160 offset:1536
	ds_read_b64_tr_b4 v[122:123], v54
	ds_read_b64_tr_b4 v[124:125], v55
	ds_read_b64_tr_b4 v[126:127], v56
	ds_read_b64_tr_b4 v[128:129], v57
	s_waitcnt lgkmcnt(6)
	v_dot8c_i32_i4_e32 v38, v130, v52
	v_dot8c_i32_i4_e32 v39, v130, v50
	v_dot8c_i32_i4_e32 v40, v132, v52
	v_dot8c_i32_i4_e32 v41, v132, v50
	v_dot8c_i32_i4_e32 v42, v134, v52
	v_dot8c_i32_i4_e32 v43, v134, v50
	v_dot8c_i32_i4_e32 v44, v136, v52
	v_dot8c_i32_i4_e32 v45, v136, v50
	v_dot8c_i32_i4_e32 v38, v131, v53
	v_dot8c_i32_i4_e32 v39, v131, v51
	v_dot8c_i32_i4_e32 v40, v133, v53
	v_dot8c_i32_i4_e32 v41, v133, v51
	v_dot8c_i32_i4_e32 v42, v135, v53
	v_dot8c_i32_i4_e32 v43, v135, v51
	v_dot8c_i32_i4_e32 v44, v137, v53
	v_dot8c_i32_i4_e32 v45, v137, v51
	v_and_b32_e32 v78, 0xffff, v27
	v_lshrrev_b32_e32 v79, 16, v27
	v_lshl_add_u32 v78, v78, 7, v152
	v_lshl_add_u32 v79, v79, 7, v153
	s_mov_b32 m0, s77
	s_add_i32 s43, s77, 0x400
	global_load_lds_dwordx4 v78, s[50:51]
	s_mov_b32 m0, s43
	s_nop 0
	global_load_lds_dwordx4 v79, s[50:51]
	s_waitcnt vmcnt(8)
	v_add_u32_e32 v54, s79, v59
	v_add_u32_e32 v55, s79, v60
	v_add_u32_e32 v56, s79, v61
	v_add_u32_e32 v57, s79, v62
	ds_read_b64_tr_b4 v[50:51], v160 offset:640
	ds_read_b64_tr_b4 v[52:53], v160 offset:1664
	ds_read_b64_tr_b4 v[130:131], v54
	ds_read_b64_tr_b4 v[132:133], v55
	ds_read_b64_tr_b4 v[134:135], v56
	ds_read_b64_tr_b4 v[136:137], v57
	s_waitcnt lgkmcnt(6)
	v_dot8c_i32_i4_e32 v38, v122, v48
	v_dot8c_i32_i4_e32 v39, v122, v46
	v_dot8c_i32_i4_e32 v40, v124, v48
	v_dot8c_i32_i4_e32 v41, v124, v46
	v_dot8c_i32_i4_e32 v42, v126, v48
	v_dot8c_i32_i4_e32 v43, v126, v46
	v_dot8c_i32_i4_e32 v44, v128, v48
	v_dot8c_i32_i4_e32 v45, v128, v46
	v_dot8c_i32_i4_e32 v38, v123, v49
	v_dot8c_i32_i4_e32 v39, v123, v47
	v_dot8c_i32_i4_e32 v40, v125, v49
	v_dot8c_i32_i4_e32 v41, v125, v47
	v_dot8c_i32_i4_e32 v42, v127, v49
	v_dot8c_i32_i4_e32 v43, v127, v47
	v_dot8c_i32_i4_e32 v44, v129, v49
	v_dot8c_i32_i4_e32 v45, v129, v47
	s_waitcnt lgkmcnt(15)
	v_add_u32_e32 v143, 8, v139
	v_and_b32_e32 v142, 15, v143
	v_xor_b32_e32 v142, 8, v142
	v_bfe_u32 v144, v143, 4, 4
	v_mul_lo_u32 v142, v142, s92
	v_mul_lo_u32 v144, v144, s92
	v_mov_b32_e32 v143, v142
	v_mov_b32_e32 v145, v144
	ds_write2st64_b64 v159, v[142:143], v[144:145] offset1:2
	v_and_b32_e32 v78, 0xffff, v28
	v_lshrrev_b32_e32 v79, 16, v28
	v_lshl_add_u32 v78, v78, 7, v152
	v_lshl_add_u32 v79, v79, 7, v153
	s_mov_b32 m0, s78
	s_add_i32 s43, s78, 0x400
	global_load_lds_dwordx4 v78, s[50:51]
	s_mov_b32 m0, s43
	s_nop 0
	global_load_lds_dwordx4 v79, s[50:51]
	s_waitcnt vmcnt(8)
	v_add_u32_e32 v54, s98, v59
	v_add_u32_e32 v55, s98, v60
	v_add_u32_e32 v56, s98, v61
	v_add_u32_e32 v57, s98, v62
	ds_read_b64_tr_b4 v[46:47], v160 offset:768
	ds_read_b64_tr_b4 v[48:49], v160 offset:1792
	ds_read_b64_tr_b4 v[122:123], v54
	ds_read_b64_tr_b4 v[124:125], v55
	ds_read_b64_tr_b4 v[126:127], v56
	ds_read_b64_tr_b4 v[128:129], v57
	s_waitcnt lgkmcnt(7)
	v_dot8c_i32_i4_e32 v38, v130, v52
	v_dot8c_i32_i4_e32 v39, v130, v50
	v_dot8c_i32_i4_e32 v40, v132, v52
	v_dot8c_i32_i4_e32 v41, v132, v50
	v_dot8c_i32_i4_e32 v42, v134, v52
	v_dot8c_i32_i4_e32 v43, v134, v50
	v_dot8c_i32_i4_e32 v44, v136, v52
	v_dot8c_i32_i4_e32 v45, v136, v50
	v_dot8c_i32_i4_e32 v38, v131, v53
	v_dot8c_i32_i4_e32 v39, v131, v51
	v_dot8c_i32_i4_e32 v40, v133, v53
	v_dot8c_i32_i4_e32 v41, v133, v51
	v_dot8c_i32_i4_e32 v42, v135, v53
	v_dot8c_i32_i4_e32 v43, v135, v51
	v_dot8c_i32_i4_e32 v44, v137, v53
	v_dot8c_i32_i4_e32 v45, v137, v51
	v_and_b32_e32 v78, 0xffff, v29
	v_lshrrev_b32_e32 v79, 16, v29
	v_lshl_add_u32 v78, v78, 7, v152
	v_lshl_add_u32 v79, v79, 7, v153
	s_mov_b32 m0, s79
	s_add_i32 s43, s79, 0x400
	global_load_lds_dwordx4 v78, s[50:51]
	s_mov_b32 m0, s43
	s_nop 0
	global_load_lds_dwordx4 v79, s[50:51]
	s_waitcnt vmcnt(8)
	v_add_u32_e32 v54, s99, v59
	v_add_u32_e32 v55, s99, v60
	v_add_u32_e32 v56, s99, v61
	v_add_u32_e32 v57, s99, v62
	ds_read_b64_tr_b4 v[50:51], v160 offset:896
	ds_read_b64_tr_b4 v[52:53], v160 offset:1920
	ds_read_b64_tr_b4 v[130:131], v54
	ds_read_b64_tr_b4 v[132:133], v55
	ds_read_b64_tr_b4 v[134:135], v56
	ds_read_b64_tr_b4 v[136:137], v57
	s_waitcnt lgkmcnt(6)
	v_dot8c_i32_i4_e32 v38, v122, v48
	v_dot8c_i32_i4_e32 v39, v122, v46
	v_dot8c_i32_i4_e32 v40, v124, v48
	v_dot8c_i32_i4_e32 v41, v124, v46
	v_dot8c_i32_i4_e32 v42, v126, v48
	v_dot8c_i32_i4_e32 v43, v126, v46
	v_dot8c_i32_i4_e32 v44, v128, v48
	v_dot8c_i32_i4_e32 v45, v128, v46
	v_dot8c_i32_i4_e32 v38, v123, v49
	v_dot8c_i32_i4_e32 v39, v123, v47
	v_dot8c_i32_i4_e32 v40, v125, v49
	v_dot8c_i32_i4_e32 v41, v125, v47
	v_dot8c_i32_i4_e32 v42, v127, v49
	v_dot8c_i32_i4_e32 v43, v127, v47
	v_dot8c_i32_i4_e32 v44, v129, v49
	v_dot8c_i32_i4_e32 v45, v129, v47
	v_and_b32_e32 v78, 0xffff, v30
	v_lshrrev_b32_e32 v79, 16, v30
	v_lshl_add_u32 v78, v78, 7, v152
	v_lshl_add_u32 v79, v79, 7, v153
	s_mov_b32 m0, s98
	s_add_i32 s43, s98, 0x400
	global_load_lds_dwordx4 v78, s[50:51]
	s_mov_b32 m0, s43
	s_nop 0
	global_load_lds_dwordx4 v79, s[50:51]
	s_waitcnt vmcnt(8)
; __device__ __forceinline__ void peer_v_tokens(int j, const LAS unsigned short* EL, const LAS unsigned char* AL  , const LAS float* ASC  , const LAS int* SAL  , ...
;     ...
;         for (int st = 0; st < 16; ++st) {
;             const int p = st >> 2, q = st & 3;
;             if (st < 14) VDMA(st + 2, (st + 2) % 3);
;             if (st < 14) asm volatile("s_waitcnt vmcnt(8)" ::: "memory");
;             else if (st == 14) asm volatile("s_waitcnt vmcnt(4)" ::: "memory");
;             else asm volatile("s_waitcnt vmcnt(0)" ::: "memory");
;             if (q == 0) {
; #pragma unroll
;                 for (int r = 0; r < 4; ++r) { accH[r] = 0; accL[r] = 0; } }
; #pragma unroll
;             for (int tp = 0; tp < 2; ++tp) {
;                 const v2i ao = TR4(ATL + (2 * q + tp) * 128 + 8 * s16), ah = TR4(ATL + 1024 + (2 * q + tp) * 128 + 8 * s16);
; #pragma unroll
;                 for (int r = 0; r < 4; ++r) {
;                     const v2i d = TR4(ldsb + BUF[st % 3] + 2048 * tp + roff[r]);
;                     accH[r] = __builtin_amdgcn_sdot8(d.x, ah.x, accH[r], false); accH[r] = __builtin_amdgcn_sdot8(d.y, ah.y, accH[r], false);
;                     accL[r] = __builtin_amdgcn_sdot8(d.x, ao.x, accL[r], false); accL[r] = __builtin_amdgcn_sdot8(d.y, ao.y, accL[r], false);
;                 }
;             }
;             asm volatile("s_waitcnt lgkmcnt(0)" ::: "memory");
;             if (q == 3) {
; #pragma unroll
;                 for (int r = 0; r < 4; ++r) STASH[256 * p + 16 * (grp + 4 * r) + pc] = f2bf(asc * (float)(2 * ((accH[r] << 4) + accL[r]) + sa));
;             }
;         }
;         CFENCE();
;         {
;             float4 v[4]; float ss = 0.f;
; #pragma unroll
;             for (int jq = 0; jq < 4; ++jq) { typedef unsigned u2v __attribute__((ext_vector_type(2))); const u2v pw = *(const LAS u2v*)(STASH + 4 * lane + 256 * jq); const uint2 hw = hv[jq];
;                 v[jq] = make_float4(__uint_as_float(hw.x << 16) + __uint_as_float(pw.x << 16), __uint_as_float(hw.x & 0xffff0000u) + __uint_as_float(pw.x & 0xffff0000u),
;                                     __uint_as_float(hw.y << 16) + __uint_as_float(pw.y << 16), __uint_as_float(hw.y & 0xffff0000u) + __uint_as_float(pw.y & 0xffff0000u));
;                 ss += v[jq].x * v[jq].x + v[jq].y * v[jq].y + v[jq].z * v[jq].z + v[jq].w * v[jq].w; }
;             ss = wave_sum(ss);
	v_add_u32_e32 v54, s76, v59
	v_add_u32_e32 v55, s76, v60
	v_add_u32_e32 v56, s76, v61
	v_add_u32_e32 v57, s76, v62
	ds_read_b64_tr_b4 v[46:47], v160
	ds_read_b64_tr_b4 v[48:49], v160 offset:1024
	ds_read_b64_tr_b4 v[122:123], v54
	ds_read_b64_tr_b4 v[124:125], v55
	ds_read_b64_tr_b4 v[126:127], v56
	ds_read_b64_tr_b4 v[128:129], v57
	s_waitcnt lgkmcnt(6)
	v_dot8c_i32_i4_e32 v38, v130, v52
	v_dot8c_i32_i4_e32 v39, v130, v50
	v_dot8c_i32_i4_e32 v40, v132, v52
	v_dot8c_i32_i4_e32 v41, v132, v50
	v_dot8c_i32_i4_e32 v42, v134, v52
	v_dot8c_i32_i4_e32 v43, v134, v50
	v_dot8c_i32_i4_e32 v44, v136, v52
	v_dot8c_i32_i4_e32 v45, v136, v50
	v_dot8c_i32_i4_e32 v38, v131, v53
	v_dot8c_i32_i4_e32 v39, v131, v51
	v_dot8c_i32_i4_e32 v40, v133, v53
	v_dot8c_i32_i4_e32 v41, v133, v51
	v_dot8c_i32_i4_e32 v42, v135, v53
	v_dot8c_i32_i4_e32 v43, v135, v51
	v_dot8c_i32_i4_e32 v44, v137, v53
	v_dot8c_i32_i4_e32 v45, v137, v51
	s_nop 3
	s_waitcnt lgkmcnt(15)
	v_lshlrev_b32_e32 v38, 5, v38
	v_lshlrev_b32_e32 v39, 1, v39
	v_add3_u32 v38, v39, v229, v38
	v_cvt_f32_i32_e32 v38, v38
	v_mul_f32_e32 v38, v228, v38
	v_lshlrev_b32_e32 v40, 5, v40
	v_lshlrev_b32_e32 v41, 1, v41
	v_add3_u32 v40, v41, v229, v40
	v_cvt_f32_i32_e32 v40, v40
	v_mul_f32_e32 v40, v228, v40
	v_lshlrev_b32_e32 v42, 5, v42
	v_lshlrev_b32_e32 v43, 1, v43
	v_add3_u32 v42, v43, v229, v42
	v_cvt_f32_i32_e32 v42, v42
	v_mul_f32_e32 v42, v228, v42
	v_lshlrev_b32_e32 v44, 5, v44
	v_lshlrev_b32_e32 v45, 1, v45
	v_add3_u32 v44, v45, v229, v44
	v_cvt_f32_i32_e32 v44, v44
	v_mul_f32_e32 v44, v228, v44
	v_cvt_pk_bf16_f32 v180, v38, v40
	v_cvt_pk_bf16_f32 v181, v42, v44
	ds_read_b128 v[252:255], v155 offset:1024
	s_add_i32 s44, s40, 32
	s_ashr_i32 s45, s44, 31
	s_lshl_b64 s[44:45], s[44:45], 12
	v_lshl_add_u64 v[80:81], v[36:37], 0, s[44:45]
	s_waitcnt lgkmcnt(0)
	v_mul_f32_e32 v214, v214, v252
	v_mul_f32_e32 v215, v215, v253
	v_mul_f32_e32 v216, v216, v254
	v_mul_f32_e32 v217, v217, v255
	global_store_dwordx4 v[80:81], v[214:217], off offset:1024 nt
	v_add_u32_e32 v147, 8, v140
	v_and_b32_e32 v146, 15, v147
	v_xor_b32_e32 v146, 8, v146
	v_bfe_u32 v148, v147, 4, 4
	v_mul_lo_u32 v146, v146, s92
	v_mul_lo_u32 v148, v148, s92
	v_mov_b32_e32 v147, v146
	v_mov_b32_e32 v149, v148
	ds_write2st64_b64 v77, v[146:147], v[148:149] offset1:2
	v_add_u32_e32 v138, 0x1800, v74
	ds_read_u8 v139, v138
	v_add_u32_e32 v141, 0x1800, v73
	ds_read_u8 v140, v141
	s_add_i32 s43, s67, 224
	v_mov_b32_e32 v138, s43
	ds_read2st64_b32 v[228:229], v138 offset1:1
	ds_read_b128 v[18:21], v227 offset:12288
	ds_read_b128 v[22:25], v227 offset:12304
	v_add_u32_e32 v150, 0x400000, v63
	v_add_u32_e32 v151, 0x400000, v64
	v_mov_b32_e32 v38, 0
	v_mov_b32_e32 v39, 0
	v_mov_b32_e32 v40, 0
	v_mov_b32_e32 v41, 0
	v_mov_b32_e32 v42, 0
	v_mov_b32_e32 v43, 0
	v_mov_b32_e32 v44, 0
	v_mov_b32_e32 v45, 0
	v_and_b32_e32 v78, 0xffff, v31
	v_lshrrev_b32_e32 v79, 16, v31
	v_lshl_add_u32 v78, v78, 7, v152
	v_lshl_add_u32 v79, v79, 7, v153
	s_mov_b32 m0, s99
	s_add_i32 s43, s99, 0x400
	global_load_lds_dwordx4 v78, s[50:51]
	s_mov_b32 m0, s43
	s_nop 0
	global_load_lds_dwordx4 v79, s[50:51]
	s_waitcnt vmcnt(9)
	v_add_u32_e32 v54, s77, v59
	v_add_u32_e32 v55, s77, v60
	v_add_u32_e32 v56, s77, v61
	v_add_u32_e32 v57, s77, v62
	ds_read_b64_tr_b4 v[50:51], v160 offset:128
	ds_read_b64_tr_b4 v[52:53], v160 offset:1152
	ds_read_b64_tr_b4 v[130:131], v54
	ds_read_b64_tr_b4 v[132:133], v55
	ds_read_b64_tr_b4 v[134:135], v56
	ds_read_b64_tr_b4 v[136:137], v57
	s_waitcnt lgkmcnt(13)
	v_dot8c_i32_i4_e32 v38, v122, v48
	v_dot8c_i32_i4_e32 v39, v122, v46
	v_dot8c_i32_i4_e32 v40, v124, v48
	v_dot8c_i32_i4_e32 v41, v124, v46
	v_dot8c_i32_i4_e32 v42, v126, v48
	v_dot8c_i32_i4_e32 v43, v126, v46
	v_dot8c_i32_i4_e32 v44, v128, v48
	v_dot8c_i32_i4_e32 v45, v128, v46
	v_dot8c_i32_i4_e32 v38, v123, v49
	v_dot8c_i32_i4_e32 v39, v123, v47
	v_dot8c_i32_i4_e32 v40, v125, v49
	v_dot8c_i32_i4_e32 v41, v125, v47
	v_dot8c_i32_i4_e32 v42, v127, v49
	v_dot8c_i32_i4_e32 v43, v127, v47
	v_dot8c_i32_i4_e32 v44, v129, v49
	v_dot8c_i32_i4_e32 v45, v129, v47
	v_and_b32_e32 v78, 0xffff, v32
	v_lshrrev_b32_e32 v79, 16, v32
	v_lshl_add_u32 v78, v78, 7, v152
	v_lshl_add_u32 v79, v79, 7, v153
	s_mov_b32 m0, s76
	s_add_i32 s43, s76, 0x400
	global_load_lds_dwordx4 v78, s[50:51]
	s_mov_b32 m0, s43
	s_nop 0
	global_load_lds_dwordx4 v79, s[50:51]
	s_waitcnt vmcnt(9)
	v_add_u32_e32 v54, s78, v59
	v_add_u32_e32 v55, s78, v60
	v_add_u32_e32 v56, s78, v61
	v_add_u32_e32 v57, s78, v62
	ds_read_b64_tr_b4 v[46:47], v160 offset:256
	ds_read_b64_tr_b4 v[48:49], v160 offset:1280
	ds_read_b64_tr_b4 v[122:123], v54
	ds_read_b64_tr_b4 v[124:125], v55
	ds_read_b64_tr_b4 v[126:127], v56
	ds_read_b64_tr_b4 v[128:129], v57
	s_waitcnt lgkmcnt(6)
	v_dot8c_i32_i4_e32 v38, v130, v52
	v_dot8c_i32_i4_e32 v39, v130, v50
	v_dot8c_i32_i4_e32 v40, v132, v52
	v_dot8c_i32_i4_e32 v41, v132, v50
	v_dot8c_i32_i4_e32 v42, v134, v52
	v_dot8c_i32_i4_e32 v43, v134, v50
	v_dot8c_i32_i4_e32 v44, v136, v52
	v_dot8c_i32_i4_e32 v45, v136, v50
	v_dot8c_i32_i4_e32 v38, v131, v53
	v_dot8c_i32_i4_e32 v39, v131, v51
	v_dot8c_i32_i4_e32 v40, v133, v53
	v_dot8c_i32_i4_e32 v41, v133, v51
	v_dot8c_i32_i4_e32 v42, v135, v53
	v_dot8c_i32_i4_e32 v43, v135, v51
	v_dot8c_i32_i4_e32 v44, v137, v53
	v_dot8c_i32_i4_e32 v45, v137, v51
	ds_write_b16 v65, v170
	ds_write_b16_d16_hi v65, v170 offset:128
	ds_write_b16 v65, v171 offset:256
	ds_write_b16_d16_hi v65, v171 offset:384
	ds_write_b16 v65, v172 offset:512
	ds_write_b16_d16_hi v65, v172 offset:640
	ds_write_b16 v65, v173 offset:768
	ds_write_b16_d16_hi v65, v173 offset:896
	ds_write_b16 v65, v174 offset:1024
	ds_write_b16_d16_hi v65, v174 offset:1152
	ds_write_b16 v65, v175 offset:1280
	ds_write_b16_d16_hi v65, v175 offset:1408
	ds_write_b16 v65, v176 offset:1536
	ds_write_b16_d16_hi v65, v176 offset:1664
	ds_write_b16 v65, v177 offset:1792
	ds_write_b16_d16_hi v65, v177 offset:1920
	ds_read_b64 v[202:203], v154
	ds_read_b64 v[204:205], v154 offset:512
	ds_read_b64 v[206:207], v154 offset:1024
	ds_read_b64 v[208:209], v154 offset:1536
	v_and_b32_e32 v78, 0xffff, v33
	v_lshrrev_b32_e32 v79, 16, v33
	v_lshl_add_u32 v78, v78, 7, v152
	v_lshl_add_u32 v79, v79, 7, v153
	s_mov_b32 m0, s77
	s_add_i32 s43, s77, 0x400
	global_load_lds_dwordx4 v78, s[50:51]
	s_mov_b32 m0, s43
	s_nop 0
	global_load_lds_dwordx4 v79, s[50:51]
	s_waitcnt vmcnt(9)
; __device__ __forceinline__ void peer_v_tokens(int j, const LAS unsigned short* EL, const LAS unsigned char* AL  , const LAS float* ASC  , const LAS int* SAL  , ...
;     ...
; #pragma unroll
;         for (int m = 0; m < 2; ++m) {
;             const int idx = lane + 64 * m, tau = idx >> 4, sr = idx & 15, k = 16 * (sr & 7) + 2 * tau + (sr >> 3);
;             const int aq = (int)*(const LAS signed char*)(AL + tl * 128 + k); const int tq = aq + 8;
;             const unsigned lo = (((unsigned)tq & 15u) ^ 8u) * 0x11111111u, hi = ((unsigned)(tq >> 4) & 15u) * 0x11111111u;
;             typedef unsigned u2v __attribute__((ext_vector_type(2)));
;             u2v l2; l2.x = lo; l2.y = lo; u2v h2; h2.x = hi; h2.y = hi;
;             *(LAS u2v*)(ATL + 8 * idx) = l2; *(LAS u2v*)(ATL + 1024 + 8 * idx) = h2;
;         }
;         const float asc = ASC[tl]; const int sa = SAL[tl];
;         CFENCE();
;         int accH[4], accL[4];
; #pragma unroll
;         for (int st = 0; st < 16; ++st) {
;             const int p = st >> 2, q = st & 3;
;             if (st < 14) VDMA(st + 2, (st + 2) % 3);
;             if (st < 14) asm volatile("s_waitcnt vmcnt(8)" ::: "memory");
;             else if (st == 14) asm volatile("s_waitcnt vmcnt(4)" ::: "memory");
;             else asm volatile("s_waitcnt vmcnt(0)" ::: "memory");
;             if (q == 0) {
; #pragma unroll
;                 for (int r = 0; r < 4; ++r) { accH[r] = 0; accL[r] = 0; } }
; #pragma unroll
;             for (int tp = 0; tp < 2; ++tp) {
;                 const v2i ao = TR4(ATL + (2 * q + tp) * 128 + 8 * s16), ah = TR4(ATL + 1024 + (2 * q + tp) * 128 + 8 * s16);
; #pragma unroll
;                 for (int r = 0; r < 4; ++r) {
;                     const v2i d = TR4(ldsb + BUF[st % 3] + 2048 * tp + roff[r]);
;                     accH[r] = __builtin_amdgcn_sdot8(d.x, ah.x, accH[r], false); accH[r] = __builtin_amdgcn_sdot8(d.y, ah.y, accH[r], false);
;                     accL[r] = __builtin_amdgcn_sdot8(d.x, ao.x, accL[r], false); accL[r] = __builtin_amdgcn_sdot8(d.y, ao.y, accL[r], false);
;                 }
;             }
;             asm volatile("s_waitcnt lgkmcnt(0)" ::: "memory");
;             if (q == 3) {
; #pragma unroll
;                 for (int r = 0; r < 4; ++r) STASH[256 * p + 16 * (grp + 4 * r) + pc] = f2bf(asc * (float)(2 * ((accH[r] << 4) + accL[r]) + sa));
;             }
	v_add_u32_e32 v54, s79, v59
	v_add_u32_e32 v55, s79, v60
	v_add_u32_e32 v56, s79, v61
	v_add_u32_e32 v57, s79, v62
	ds_read_b64_tr_b4 v[50:51], v160 offset:384
	ds_read_b64_tr_b4 v[52:53], v160 offset:1408
	ds_read_b64_tr_b4 v[130:131], v54
	ds_read_b64_tr_b4 v[132:133], v55
	ds_read_b64_tr_b4 v[134:135], v56
	ds_read_b64_tr_b4 v[136:137], v57
	s_waitcnt lgkmcnt(15)
	v_dot8c_i32_i4_e32 v38, v122, v48
	v_dot8c_i32_i4_e32 v39, v122, v46
	v_dot8c_i32_i4_e32 v40, v124, v48
	v_dot8c_i32_i4_e32 v41, v124, v46
	v_dot8c_i32_i4_e32 v42, v126, v48
	v_dot8c_i32_i4_e32 v43, v126, v46
	v_dot8c_i32_i4_e32 v44, v128, v48
	v_dot8c_i32_i4_e32 v45, v128, v46
	v_dot8c_i32_i4_e32 v38, v123, v49
	v_dot8c_i32_i4_e32 v39, v123, v47
	v_dot8c_i32_i4_e32 v40, v125, v49
	v_dot8c_i32_i4_e32 v41, v125, v47
	v_dot8c_i32_i4_e32 v42, v127, v49
	v_dot8c_i32_i4_e32 v43, v127, v47
	v_dot8c_i32_i4_e32 v44, v129, v49
	v_dot8c_i32_i4_e32 v45, v129, v47
	s_waitcnt lgkmcnt(15)
	v_and_b32_e32 v78, 0xffff, v18
	v_lshrrev_b32_e32 v79, 16, v18
	v_lshl_add_u32 v78, v78, 7, v150
	v_lshl_add_u32 v79, v79, 7, v151
	s_mov_b32 m0, s78
	s_add_i32 s43, s78, 0x400
	global_load_lds_dwordx4 v78, s[50:51]
	s_mov_b32 m0, s43
	s_nop 0
	global_load_lds_dwordx4 v79, s[50:51]
	s_waitcnt vmcnt(9)
	v_add_u32_e32 v54, s98, v59
	v_add_u32_e32 v55, s98, v60
	v_add_u32_e32 v56, s98, v61
	v_add_u32_e32 v57, s98, v62
	ds_read_b64_tr_b4 v[46:47], v160 offset:512
	ds_read_b64_tr_b4 v[48:49], v160 offset:1536
	ds_read_b64_tr_b4 v[122:123], v54
	ds_read_b64_tr_b4 v[124:125], v55
	ds_read_b64_tr_b4 v[126:127], v56
	ds_read_b64_tr_b4 v[128:129], v57
	s_waitcnt lgkmcnt(6)
	v_dot8c_i32_i4_e32 v38, v130, v52
	v_dot8c_i32_i4_e32 v39, v130, v50
	v_dot8c_i32_i4_e32 v40, v132, v52
	v_dot8c_i32_i4_e32 v41, v132, v50
	v_dot8c_i32_i4_e32 v42, v134, v52
	v_dot8c_i32_i4_e32 v43, v134, v50
	v_dot8c_i32_i4_e32 v44, v136, v52
	v_dot8c_i32_i4_e32 v45, v136, v50
	v_dot8c_i32_i4_e32 v38, v131, v53
	v_dot8c_i32_i4_e32 v39, v131, v51
	v_dot8c_i32_i4_e32 v40, v133, v53
	v_dot8c_i32_i4_e32 v41, v133, v51
	v_dot8c_i32_i4_e32 v42, v135, v53
	v_dot8c_i32_i4_e32 v43, v135, v51
	v_dot8c_i32_i4_e32 v44, v137, v53
	v_dot8c_i32_i4_e32 v45, v137, v51
	v_and_b32_e32 v78, 0xffff, v19
	v_lshrrev_b32_e32 v79, 16, v19
	v_lshl_add_u32 v78, v78, 7, v150
	v_lshl_add_u32 v79, v79, 7, v151
	s_mov_b32 m0, s79
	s_add_i32 s43, s79, 0x400
	global_load_lds_dwordx4 v78, s[50:51]
	s_mov_b32 m0, s43
	s_nop 0
	global_load_lds_dwordx4 v79, s[50:51]
	s_waitcnt vmcnt(8)
	v_add_u32_e32 v54, s99, v59
	v_add_u32_e32 v55, s99, v60
	v_add_u32_e32 v56, s99, v61
	v_add_u32_e32 v57, s99, v62
	ds_read_b64_tr_b4 v[50:51], v160 offset:640
	ds_read_b64_tr_b4 v[52:53], v160 offset:1664
	ds_read_b64_tr_b4 v[130:131], v54
	ds_read_b64_tr_b4 v[132:133], v55
	ds_read_b64_tr_b4 v[134:135], v56
	ds_read_b64_tr_b4 v[136:137], v57
	s_waitcnt lgkmcnt(6)
	v_dot8c_i32_i4_e32 v38, v122, v48
	v_dot8c_i32_i4_e32 v39, v122, v46
	v_dot8c_i32_i4_e32 v40, v124, v48
	v_dot8c_i32_i4_e32 v41, v124, v46
	v_dot8c_i32_i4_e32 v42, v126, v48
	v_dot8c_i32_i4_e32 v43, v126, v46
	v_dot8c_i32_i4_e32 v44, v128, v48
	v_dot8c_i32_i4_e32 v45, v128, v46
	v_dot8c_i32_i4_e32 v38, v123, v49
	v_dot8c_i32_i4_e32 v39, v123, v47
	v_dot8c_i32_i4_e32 v40, v125, v49
	v_dot8c_i32_i4_e32 v41, v125, v47
	v_dot8c_i32_i4_e32 v42, v127, v49
	v_dot8c_i32_i4_e32 v43, v127, v47
	v_dot8c_i32_i4_e32 v44, v129, v49
	v_dot8c_i32_i4_e32 v45, v129, v47
	s_waitcnt lgkmcnt(15)
	v_add_u32_e32 v143, 8, v139
	v_and_b32_e32 v142, 15, v143
	v_xor_b32_e32 v142, 8, v142
	v_bfe_u32 v144, v143, 4, 4
	v_mul_lo_u32 v142, v142, s92
	v_mul_lo_u32 v144, v144, s92
	v_mov_b32_e32 v143, v142
	v_mov_b32_e32 v145, v144
	ds_write2st64_b64 v159, v[142:143], v[144:145] offset1:2
	v_and_b32_e32 v78, 0xffff, v20
	v_lshrrev_b32_e32 v79, 16, v20
	v_lshl_add_u32 v78, v78, 7, v150
	v_lshl_add_u32 v79, v79, 7, v151
	s_mov_b32 m0, s98
	s_add_i32 s43, s98, 0x400
	global_load_lds_dwordx4 v78, s[50:51]
	s_mov_b32 m0, s43
	s_nop 0
	global_load_lds_dwordx4 v79, s[50:51]
	s_waitcnt vmcnt(8)
	v_add_u32_e32 v54, s76, v59
	v_add_u32_e32 v55, s76, v60
	v_add_u32_e32 v56, s76, v61
	v_add_u32_e32 v57, s76, v62
	ds_read_b64_tr_b4 v[46:47], v160 offset:768
	ds_read_b64_tr_b4 v[48:49], v160 offset:1792
	ds_read_b64_tr_b4 v[122:123], v54
	ds_read_b64_tr_b4 v[124:125], v55
	ds_read_b64_tr_b4 v[126:127], v56
	ds_read_b64_tr_b4 v[128:129], v57
	s_waitcnt lgkmcnt(7)
	v_dot8c_i32_i4_e32 v38, v130, v52
	v_dot8c_i32_i4_e32 v39, v130, v50
	v_dot8c_i32_i4_e32 v40, v132, v52
	v_dot8c_i32_i4_e32 v41, v132, v50
	v_dot8c_i32_i4_e32 v42, v134, v52
	v_dot8c_i32_i4_e32 v43, v134, v50
	v_dot8c_i32_i4_e32 v44, v136, v52
	v_dot8c_i32_i4_e32 v45, v136, v50
	v_dot8c_i32_i4_e32 v38, v131, v53
	v_dot8c_i32_i4_e32 v39, v131, v51
	v_dot8c_i32_i4_e32 v40, v133, v53
	v_dot8c_i32_i4_e32 v41, v133, v51
	v_dot8c_i32_i4_e32 v42, v135, v53
	v_dot8c_i32_i4_e32 v43, v135, v51
	v_dot8c_i32_i4_e32 v44, v137, v53
	v_dot8c_i32_i4_e32 v45, v137, v51
	v_and_b32_e32 v78, 0xffff, v21
	v_lshrrev_b32_e32 v79, 16, v21
	v_lshl_add_u32 v78, v78, 7, v150
	v_lshl_add_u32 v79, v79, 7, v151
	s_mov_b32 m0, s99
	s_add_i32 s43, s99, 0x400
	global_load_lds_dwordx4 v78, s[50:51]
	s_mov_b32 m0, s43
	s_nop 0
	global_load_lds_dwordx4 v79, s[50:51]
	s_waitcnt vmcnt(8)
	v_add_u32_e32 v54, s77, v59
	v_add_u32_e32 v55, s77, v60
	v_add_u32_e32 v56, s77, v61
	v_add_u32_e32 v57, s77, v62
	ds_read_b64_tr_b4 v[50:51], v160 offset:896
	ds_read_b64_tr_b4 v[52:53], v160 offset:1920
	ds_read_b64_tr_b4 v[130:131], v54
	ds_read_b64_tr_b4 v[132:133], v55
	ds_read_b64_tr_b4 v[134:135], v56
	ds_read_b64_tr_b4 v[136:137], v57
	s_waitcnt lgkmcnt(6)
; __device__ __forceinline__ void peer_v_tokens(int j, const LAS unsigned short* EL, const LAS unsigned char* AL  , const LAS float* ASC  , const LAS int* SAL  , ...
;     ...
;         for (int st = 0; st < 16; ++st) {
;             const int p = st >> 2, q = st & 3;
;             if (st < 14) VDMA(st + 2, (st + 2) % 3);
;             if (st < 14) asm volatile("s_waitcnt vmcnt(8)" ::: "memory");
;             else if (st == 14) asm volatile("s_waitcnt vmcnt(4)" ::: "memory");
;             else asm volatile("s_waitcnt vmcnt(0)" ::: "memory");
;             if (q == 0) {
; #pragma unroll
;                 for (int r = 0; r < 4; ++r) { accH[r] = 0; accL[r] = 0; } }
; #pragma unroll
;             for (int tp = 0; tp < 2; ++tp) {
;                 const v2i ao = TR4(ATL + (2 * q + tp) * 128 + 8 * s16), ah = TR4(ATL + 1024 + (2 * q + tp) * 128 + 8 * s16);
; #pragma unroll
;                 for (int r = 0; r < 4; ++r) {
;                     const v2i d = TR4(ldsb + BUF[st % 3] + 2048 * tp + roff[r]);
;                     accH[r] = __builtin_amdgcn_sdot8(d.x, ah.x, accH[r], false); accH[r] = __builtin_amdgcn_sdot8(d.y, ah.y, accH[r], false);
;                     accL[r] = __builtin_amdgcn_sdot8(d.x, ao.x, accL[r], false); accL[r] = __builtin_amdgcn_sdot8(d.y, ao.y, accL[r], false);
;                 }
;             }
;             asm volatile("s_waitcnt lgkmcnt(0)" ::: "memory");
;             if (q == 3) {
; #pragma unroll
;                 for (int r = 0; r < 4; ++r) STASH[256 * p + 16 * (grp + 4 * r) + pc] = f2bf(asc * (float)(2 * ((accH[r] << 4) + accL[r]) + sa));
;             }
;         }
;         CFENCE();
;         {
;             float4 v[4]; float ss = 0.f;
; #pragma unroll
;             for (int jq = 0; jq < 4; ++jq) { typedef unsigned u2v __attribute__((ext_vector_type(2))); const u2v pw = *(const LAS u2v*)(STASH + 4 * lane + 256 * jq); const uint2 hw = hv[jq];
;                 v[jq] = make_float4(__uint_as_float(hw.x << 16) + __uint_as_float(pw.x << 16), __uint_as_float(hw.x & 0xffff0000u) + __uint_as_float(pw.x & 0xffff0000u),
;                                     __uint_as_float(hw.y << 16) + __uint_as_float(pw.y << 16), __uint_as_float(hw.y & 0xffff0000u) + __uint_as_float(pw.y & 0xffff0000u));
;                 ss += v[jq].x * v[jq].x + v[jq].y * v[jq].y + v[jq].z * v[jq].z + v[jq].w * v[jq].w; }
;             ss = wave_sum(ss);
	v_dot8c_i32_i4_e32 v38, v122, v48
	v_dot8c_i32_i4_e32 v39, v122, v46
	v_dot8c_i32_i4_e32 v40, v124, v48
	v_dot8c_i32_i4_e32 v41, v124, v46
	v_dot8c_i32_i4_e32 v42, v126, v48
	v_dot8c_i32_i4_e32 v43, v126, v46
	v_dot8c_i32_i4_e32 v44, v128, v48
	v_dot8c_i32_i4_e32 v45, v128, v46
	v_dot8c_i32_i4_e32 v38, v123, v49
	v_dot8c_i32_i4_e32 v39, v123, v47
	v_dot8c_i32_i4_e32 v40, v125, v49
	v_dot8c_i32_i4_e32 v41, v125, v47
	v_dot8c_i32_i4_e32 v42, v127, v49
	v_dot8c_i32_i4_e32 v43, v127, v47
	v_dot8c_i32_i4_e32 v44, v129, v49
	v_dot8c_i32_i4_e32 v45, v129, v47
	v_and_b32_e32 v78, 0xffff, v22
	v_lshrrev_b32_e32 v79, 16, v22
	v_lshl_add_u32 v78, v78, 7, v150
	v_lshl_add_u32 v79, v79, 7, v151
	s_mov_b32 m0, s76
	s_add_i32 s43, s76, 0x400
	global_load_lds_dwordx4 v78, s[50:51]
	s_mov_b32 m0, s43
	s_nop 0
	global_load_lds_dwordx4 v79, s[50:51]
	s_waitcnt vmcnt(8)
	v_add_u32_e32 v54, s78, v59
	v_add_u32_e32 v55, s78, v60
	v_add_u32_e32 v56, s78, v61
	v_add_u32_e32 v57, s78, v62
	ds_read_b64_tr_b4 v[46:47], v160
	ds_read_b64_tr_b4 v[48:49], v160 offset:1024
	ds_read_b64_tr_b4 v[122:123], v54
	ds_read_b64_tr_b4 v[124:125], v55
	ds_read_b64_tr_b4 v[126:127], v56
	ds_read_b64_tr_b4 v[128:129], v57
	s_waitcnt lgkmcnt(6)
	v_dot8c_i32_i4_e32 v38, v130, v52
	v_dot8c_i32_i4_e32 v39, v130, v50
	v_dot8c_i32_i4_e32 v40, v132, v52
	v_dot8c_i32_i4_e32 v41, v132, v50
	v_dot8c_i32_i4_e32 v42, v134, v52
	v_dot8c_i32_i4_e32 v43, v134, v50
	v_dot8c_i32_i4_e32 v44, v136, v52
	v_dot8c_i32_i4_e32 v45, v136, v50
	v_dot8c_i32_i4_e32 v38, v131, v53
	v_dot8c_i32_i4_e32 v39, v131, v51
	v_dot8c_i32_i4_e32 v40, v133, v53
	v_dot8c_i32_i4_e32 v41, v133, v51
	v_dot8c_i32_i4_e32 v42, v135, v53
	v_dot8c_i32_i4_e32 v43, v135, v51
	v_dot8c_i32_i4_e32 v44, v137, v53
	v_dot8c_i32_i4_e32 v45, v137, v51
	s_nop 3
	s_waitcnt lgkmcnt(15)
	v_lshlrev_b32_e32 v38, 5, v38
	v_lshlrev_b32_e32 v39, 1, v39
	v_add3_u32 v38, v39, v229, v38
	v_cvt_f32_i32_e32 v38, v38
	v_mul_f32_e32 v38, v228, v38
	v_lshlrev_b32_e32 v40, 5, v40
	v_lshlrev_b32_e32 v41, 1, v41
	v_add3_u32 v40, v41, v229, v40
	v_cvt_f32_i32_e32 v40, v40
	v_mul_f32_e32 v40, v228, v40
	v_lshlrev_b32_e32 v42, 5, v42
	v_lshlrev_b32_e32 v43, 1, v43
	v_add3_u32 v42, v43, v229, v42
	v_cvt_f32_i32_e32 v42, v42
	v_mul_f32_e32 v42, v228, v42
	v_lshlrev_b32_e32 v44, 5, v44
	v_lshlrev_b32_e32 v45, 1, v45
	v_add3_u32 v44, v45, v229, v44
	v_cvt_f32_i32_e32 v44, v44
	v_mul_f32_e32 v44, v228, v44
	v_cvt_pk_bf16_f32 v188, v38, v40
	v_cvt_pk_bf16_f32 v189, v42, v44
	ds_read_b128 v[252:255], v156
	s_add_i32 s44, s40, 32
	s_ashr_i32 s45, s44, 31
	s_lshl_b64 s[44:45], s[44:45], 12
	v_lshl_add_u64 v[80:81], v[36:37], 0, s[44:45]
	s_waitcnt lgkmcnt(0)
	v_mul_f32_e32 v218, v218, v252
	v_mul_f32_e32 v219, v219, v253
	v_mul_f32_e32 v220, v220, v254
	v_mul_f32_e32 v221, v221, v255
	global_store_dwordx4 v[80:81], v[218:221], off offset:2048 nt
	v_add_u32_e32 v147, 8, v140
	v_and_b32_e32 v146, 15, v147
	v_xor_b32_e32 v146, 8, v146
	v_bfe_u32 v148, v147, 4, 4
	v_mul_lo_u32 v146, v146, s92
	v_mul_lo_u32 v148, v148, s92
	v_mov_b32_e32 v147, v146
	v_mov_b32_e32 v149, v148
	ds_write2st64_b64 v77, v[146:147], v[148:149] offset1:2
	v_add_u32_e32 v138, 0x1c00, v74
	ds_read_u8 v139, v138
	v_add_u32_e32 v141, 0x1c00, v73
	ds_read_u8 v140, v141
	s_add_i32 s43, s67, 192
	v_mov_b32_e32 v138, s43
	ds_read2st64_b32 v[228:229], v138 offset1:1
	ds_read_b128 v[26:29], v227 offset:14336
	ds_read_b128 v[30:33], v227 offset:14352
	v_mov_b32_e32 v38, 0
	v_mov_b32_e32 v39, 0
	v_mov_b32_e32 v40, 0
	v_mov_b32_e32 v41, 0
	v_mov_b32_e32 v42, 0
	v_mov_b32_e32 v43, 0
	v_mov_b32_e32 v44, 0
	v_mov_b32_e32 v45, 0
	v_and_b32_e32 v78, 0xffff, v23
	v_lshrrev_b32_e32 v79, 16, v23
	v_lshl_add_u32 v78, v78, 7, v150
	v_lshl_add_u32 v79, v79, 7, v151
	s_mov_b32 m0, s77
	s_add_i32 s43, s77, 0x400
	global_load_lds_dwordx4 v78, s[50:51]
	s_mov_b32 m0, s43
	s_nop 0
	global_load_lds_dwordx4 v79, s[50:51]
	s_waitcnt vmcnt(9)
	v_add_u32_e32 v54, s79, v59
	v_add_u32_e32 v55, s79, v60
	v_add_u32_e32 v56, s79, v61
	v_add_u32_e32 v57, s79, v62
	ds_read_b64_tr_b4 v[50:51], v160 offset:128
	ds_read_b64_tr_b4 v[52:53], v160 offset:1152
	ds_read_b64_tr_b4 v[130:131], v54
	ds_read_b64_tr_b4 v[132:133], v55
	ds_read_b64_tr_b4 v[134:135], v56
	ds_read_b64_tr_b4 v[136:137], v57
	s_waitcnt lgkmcnt(13)
	s_waitcnt vmcnt(36) lgkmcnt(15)
; #define LAS __attribute__((address_space(3)))
; #define TR4(p_) __builtin_amdgcn_ds_read_tr4_b64_v2i32((LAS v2i*)(p_))
; __device__ __forceinline__ void peer_v_tokens(int j, const LAS unsigned short* EL, const LAS unsigned char* AL  , const LAS float* ASC  , const LAS int* SAL  , ...
;     ...
;         for (int st = 0; st < 16; ++st) {
;             const int p = st >> 2, q = st & 3;
;             if (st < 14) VDMA(st + 2, (st + 2) % 3);
;             if (st < 14) asm volatile("s_waitcnt vmcnt(8)" ::: "memory");
;             else if (st == 14) asm volatile("s_waitcnt vmcnt(4)" ::: "memory");
;             else asm volatile("s_waitcnt vmcnt(0)" ::: "memory");
;             if (q == 0) {
; #pragma unroll
;                 for (int r = 0; r < 4; ++r) { accH[r] = 0; accL[r] = 0; } }
; #pragma unroll
;             for (int tp = 0; tp < 2; ++tp) {
;                 const v2i ao = TR4(ATL + (2 * q + tp) * 128 + 8 * s16), ah = TR4(ATL + 1024 + (2 * q + tp) * 128 + 8 * s16);
; #pragma unroll
;                 for (int r = 0; r < 4; ++r) {
;                     const v2i d = TR4(ldsb + BUF[st % 3] + 2048 * tp + roff[r]);
;                     accH[r] = __builtin_amdgcn_sdot8(d.x, ah.x, accH[r], false); accH[r] = __builtin_amdgcn_sdot8(d.y, ah.y, accH[r], false);
;                     accL[r] = __builtin_amdgcn_sdot8(d.x, ao.x, accL[r], false); accL[r] = __builtin_amdgcn_sdot8(d.y, ao.y, accL[r], false);
;                 }
;     ...
;         {
;             float4 v[4]; float ss = 0.f;
; #pragma unroll
;             for (int jq = 0; jq < 4; ++jq) { typedef unsigned u2v __attribute__((ext_vector_type(2))); const u2v pw = *(const LAS u2v*)(STASH + 4 * lane + 256 * jq); const uint2 hw = hv[jq];
;                 v[jq] = make_float4(__uint_as_float(hw.x << 16) + __uint_as_float(pw.x << 16), __uint_as_float(hw.x & 0xffff0000u) + __uint_as_float(pw.x & 0xffff0000u),
;                                     __uint_as_float(hw.y << 16) + __uint_as_float(pw.y << 16), __uint_as_float(hw.y & 0xffff0000u) + __uint_as_float(pw.y & 0xffff0000u));
;                 ss += v[jq].x * v[jq].x + v[jq].y * v[jq].y + v[jq].z * v[jq].z + v[jq].w * v[jq].w; }
;             ss = wave_sum(ss);
;             const float r3 = rsqrtf(ss * (1.f / D) + EPS);
	v_lshlrev_b32_e32 v236, 16, v194
	v_and_b32_e32 v237, 0xffff0000, v194
	v_lshlrev_b32_e32 v142, 16, v202
	v_and_b32_e32 v143, 0xffff0000, v202
	v_add_f32_e32 v236, v236, v142
	v_add_f32_e32 v237, v237, v143
	v_lshlrev_b32_e32 v238, 16, v195
	v_and_b32_e32 v239, 0xffff0000, v195
	v_lshlrev_b32_e32 v142, 16, v203
	v_and_b32_e32 v143, 0xffff0000, v203
	v_add_f32_e32 v238, v238, v142
	v_add_f32_e32 v239, v239, v143
	v_lshlrev_b32_e32 v240, 16, v196
	v_and_b32_e32 v241, 0xffff0000, v196
	v_lshlrev_b32_e32 v142, 16, v204
	v_and_b32_e32 v143, 0xffff0000, v204
	v_add_f32_e32 v240, v240, v142
	v_add_f32_e32 v241, v241, v143
	v_lshlrev_b32_e32 v242, 16, v197
	v_and_b32_e32 v243, 0xffff0000, v197
	v_lshlrev_b32_e32 v142, 16, v205
	v_and_b32_e32 v143, 0xffff0000, v205
	v_add_f32_e32 v242, v242, v142
	v_add_f32_e32 v243, v243, v143
	v_lshlrev_b32_e32 v244, 16, v198
	v_and_b32_e32 v245, 0xffff0000, v198
	v_lshlrev_b32_e32 v142, 16, v206
	v_and_b32_e32 v143, 0xffff0000, v206
	v_add_f32_e32 v244, v244, v142
	v_add_f32_e32 v245, v245, v143
	v_lshlrev_b32_e32 v246, 16, v199
	v_and_b32_e32 v247, 0xffff0000, v199
	v_lshlrev_b32_e32 v142, 16, v207
	v_and_b32_e32 v143, 0xffff0000, v207
	v_add_f32_e32 v246, v246, v142
	v_add_f32_e32 v247, v247, v143
	v_lshlrev_b32_e32 v248, 16, v200
	v_and_b32_e32 v249, 0xffff0000, v200
	v_lshlrev_b32_e32 v142, 16, v208
	v_and_b32_e32 v143, 0xffff0000, v208
	v_add_f32_e32 v248, v248, v142
	v_add_f32_e32 v249, v249, v143
	v_lshlrev_b32_e32 v250, 16, v201
	v_and_b32_e32 v251, 0xffff0000, v201
	v_lshlrev_b32_e32 v142, 16, v209
	v_and_b32_e32 v143, 0xffff0000, v209
	v_add_f32_e32 v250, v250, v142
	v_add_f32_e32 v251, v251, v143
	v_mov_b32_e32 v144, 0
	v_mul_f32_e32 v145, v236, v236
	v_fmac_f32_e32 v145, v237, v237
	v_fmac_f32_e32 v145, v238, v238
	v_fmac_f32_e32 v145, v239, v239
	v_add_f32_e32 v144, v144, v145
	v_mul_f32_e32 v145, v240, v240
	v_fmac_f32_e32 v145, v241, v241
	v_fmac_f32_e32 v145, v242, v242
	v_fmac_f32_e32 v145, v243, v243
	v_add_f32_e32 v144, v144, v145
	v_mul_f32_e32 v145, v244, v244
	v_fmac_f32_e32 v145, v245, v245
	v_fmac_f32_e32 v145, v246, v246
	v_fmac_f32_e32 v145, v247, v247
	v_add_f32_e32 v144, v144, v145
	v_mul_f32_e32 v145, v248, v248
	v_fmac_f32_e32 v145, v249, v249
	v_fmac_f32_e32 v145, v250, v250
	v_fmac_f32_e32 v145, v251, v251
	v_add_f32_e32 v144, v144, v145
	s_nop 1
	v_add_f32_dpp v144, v144, v144 quad_perm:[1,0,3,2] row_mask:0xf bank_mask:0xf bound_ctrl:1
	s_nop 1
	v_add_f32_dpp v144, v144, v144 quad_perm:[2,3,0,1] row_mask:0xf bank_mask:0xf bound_ctrl:1
	s_nop 1
	v_add_f32_dpp v144, v144, v144 row_half_mirror row_mask:0xf bank_mask:0xf bound_ctrl:1
	s_nop 1
	v_add_f32_dpp v144, v144, v144 row_mirror row_mask:0xf bank_mask:0xf bound_ctrl:1
	s_nop 1
	v_readlane_b32 s10, v144, 0
	v_readlane_b32 s11, v144, 16
	v_readlane_b32 s14, v144, 32
	v_readlane_b32 s15, v144, 48
	s_nop 3
	v_mov_b32_e32 v144, s11
	v_mov_b32_e32 v145, s15
	v_add_f32_e32 v144, s10, v144
	v_add_f32_e32 v145, s14, v145
	v_add_f32_e32 v144, v144, v145
	v_fmamk_f32 v144, v144, 0x3a800000, v111
	v_rsq_f32_e32 v144, v144
	s_nop 0
	v_mul_f32_e32 v236, v236, v144
	v_mul_f32_e32 v237, v237, v144
	v_mul_f32_e32 v238, v238, v144
	v_mul_f32_e32 v239, v239, v144
	v_mul_f32_e32 v240, v240, v144
	v_mul_f32_e32 v241, v241, v144
	v_mul_f32_e32 v242, v242, v144
	v_mul_f32_e32 v243, v243, v144
	v_mul_f32_e32 v244, v244, v144
	v_mul_f32_e32 v245, v245, v144
	v_mul_f32_e32 v246, v246, v144
	v_mul_f32_e32 v247, v247, v144
	v_mul_f32_e32 v248, v248, v144
	v_mul_f32_e32 v249, v249, v144
	v_mul_f32_e32 v250, v250, v144
	v_mul_f32_e32 v251, v251, v144
	v_dot8c_i32_i4_e32 v38, v122, v48
	v_dot8c_i32_i4_e32 v39, v122, v46
	v_dot8c_i32_i4_e32 v40, v124, v48
	v_dot8c_i32_i4_e32 v41, v124, v46
	v_dot8c_i32_i4_e32 v42, v126, v48
	v_dot8c_i32_i4_e32 v43, v126, v46
	v_dot8c_i32_i4_e32 v44, v128, v48
	v_dot8c_i32_i4_e32 v45, v128, v46
	v_dot8c_i32_i4_e32 v38, v123, v49
	v_dot8c_i32_i4_e32 v39, v123, v47
	v_dot8c_i32_i4_e32 v40, v125, v49
	v_dot8c_i32_i4_e32 v41, v125, v47
	v_dot8c_i32_i4_e32 v42, v127, v49
	v_dot8c_i32_i4_e32 v43, v127, v47
	v_dot8c_i32_i4_e32 v44, v129, v49
	v_dot8c_i32_i4_e32 v45, v129, v47
	v_and_b32_e32 v78, 0xffff, v24
	v_lshrrev_b32_e32 v79, 16, v24
	v_lshl_add_u32 v78, v78, 7, v150
	v_lshl_add_u32 v79, v79, 7, v151
	s_mov_b32 m0, s78
	s_add_i32 s43, s78, 0x400
	global_load_lds_dwordx4 v78, s[50:51]
	s_mov_b32 m0, s43
	s_nop 0
	global_load_lds_dwordx4 v79, s[50:51]
	s_waitcnt vmcnt(9)
	v_add_u32_e32 v54, s98, v59
	v_add_u32_e32 v55, s98, v60
	v_add_u32_e32 v56, s98, v61
	v_add_u32_e32 v57, s98, v62
	ds_read_b64_tr_b4 v[46:47], v160 offset:256
	ds_read_b64_tr_b4 v[48:49], v160 offset:1280
	ds_read_b64_tr_b4 v[122:123], v54
	ds_read_b64_tr_b4 v[124:125], v55
	ds_read_b64_tr_b4 v[126:127], v56
	ds_read_b64_tr_b4 v[128:129], v57
	s_waitcnt lgkmcnt(6)
	v_dot8c_i32_i4_e32 v38, v130, v52
	v_dot8c_i32_i4_e32 v39, v130, v50
	v_dot8c_i32_i4_e32 v40, v132, v52
	v_dot8c_i32_i4_e32 v41, v132, v50
	v_dot8c_i32_i4_e32 v42, v134, v52
	v_dot8c_i32_i4_e32 v43, v134, v50
	v_dot8c_i32_i4_e32 v44, v136, v52
	v_dot8c_i32_i4_e32 v45, v136, v50
	v_dot8c_i32_i4_e32 v38, v131, v53
	v_dot8c_i32_i4_e32 v39, v131, v51
	v_dot8c_i32_i4_e32 v40, v133, v53
	v_dot8c_i32_i4_e32 v41, v133, v51
	v_dot8c_i32_i4_e32 v42, v135, v53
	v_dot8c_i32_i4_e32 v43, v135, v51
	v_dot8c_i32_i4_e32 v44, v137, v53
	v_dot8c_i32_i4_e32 v45, v137, v51
	v_and_b32_e32 v78, 0xffff, v25
	v_lshrrev_b32_e32 v79, 16, v25
	v_lshl_add_u32 v78, v78, 7, v150
	v_lshl_add_u32 v79, v79, 7, v151
	s_mov_b32 m0, s79
	s_add_i32 s43, s79, 0x400
	global_load_lds_dwordx4 v78, s[50:51]
	s_mov_b32 m0, s43
	s_nop 0
	global_load_lds_dwordx4 v79, s[50:51]
	s_waitcnt vmcnt(9)
; #define LAS __attribute__((address_space(3)))
; #define TR4(p_) __builtin_amdgcn_ds_read_tr4_b64_v2i32((LAS v2i*)(p_))
; #define CFENCE() asm volatile("" ::: "memory")
; __device__ __forceinline__ void peer_v_tokens(int j, const LAS unsigned short* EL, const LAS unsigned char* AL  , const LAS float* ASC  , const LAS int* SAL  , ...
;     ...
; #pragma unroll
;         for (int m = 0; m < 2; ++m) {
;             const int idx = lane + 64 * m, tau = idx >> 4, sr = idx & 15, k = 16 * (sr & 7) + 2 * tau + (sr >> 3);
;             const int aq = (int)*(const LAS signed char*)(AL + tl * 128 + k); const int tq = aq + 8;
;             const unsigned lo = (((unsigned)tq & 15u) ^ 8u) * 0x11111111u, hi = ((unsigned)(tq >> 4) & 15u) * 0x11111111u;
;             typedef unsigned u2v __attribute__((ext_vector_type(2)));
;             u2v l2; l2.x = lo; l2.y = lo; u2v h2; h2.x = hi; h2.y = hi;
;             *(LAS u2v*)(ATL + 8 * idx) = l2; *(LAS u2v*)(ATL + 1024 + 8 * idx) = h2;
;         }
;         const float asc = ASC[tl]; const int sa = SAL[tl];
;         CFENCE();
;         int accH[4], accL[4];
; #pragma unroll
;         for (int st = 0; st < 16; ++st) {
;             const int p = st >> 2, q = st & 3;
;             if (st < 14) VDMA(st + 2, (st + 2) % 3);
;             if (st < 14) asm volatile("s_waitcnt vmcnt(8)" ::: "memory");
;             else if (st == 14) asm volatile("s_waitcnt vmcnt(4)" ::: "memory");
;             else asm volatile("s_waitcnt vmcnt(0)" ::: "memory");
;             if (q == 0) {
; #pragma unroll
;                 for (int r = 0; r < 4; ++r) { accH[r] = 0; accL[r] = 0; } }
; #pragma unroll
;             for (int tp = 0; tp < 2; ++tp) {
;                 const v2i ao = TR4(ATL + (2 * q + tp) * 128 + 8 * s16), ah = TR4(ATL + 1024 + (2 * q + tp) * 128 + 8 * s16);
; #pragma unroll
;                 for (int r = 0; r < 4; ++r) {
;                     const v2i d = TR4(ldsb + BUF[st % 3] + 2048 * tp + roff[r]);
;                     accH[r] = __builtin_amdgcn_sdot8(d.x, ah.x, accH[r], false); accH[r] = __builtin_amdgcn_sdot8(d.y, ah.y, accH[r], false);
;                     accL[r] = __builtin_amdgcn_sdot8(d.x, ao.x, accL[r], false); accL[r] = __builtin_amdgcn_sdot8(d.y, ao.y, accL[r], false);
;                 }
	v_add_u32_e32 v54, s99, v59
	v_add_u32_e32 v55, s99, v60
	v_add_u32_e32 v56, s99, v61
	v_add_u32_e32 v57, s99, v62
	ds_read_b64_tr_b4 v[50:51], v160 offset:384
	ds_read_b64_tr_b4 v[52:53], v160 offset:1408
	ds_read_b64_tr_b4 v[130:131], v54
	ds_read_b64_tr_b4 v[132:133], v55
	ds_read_b64_tr_b4 v[134:135], v56
	ds_read_b64_tr_b4 v[136:137], v57
	s_waitcnt lgkmcnt(6)
	v_dot8c_i32_i4_e32 v38, v122, v48
	v_dot8c_i32_i4_e32 v39, v122, v46
	v_dot8c_i32_i4_e32 v40, v124, v48
	v_dot8c_i32_i4_e32 v41, v124, v46
	v_dot8c_i32_i4_e32 v42, v126, v48
	v_dot8c_i32_i4_e32 v43, v126, v46
	v_dot8c_i32_i4_e32 v44, v128, v48
	v_dot8c_i32_i4_e32 v45, v128, v46
	v_dot8c_i32_i4_e32 v38, v123, v49
	v_dot8c_i32_i4_e32 v39, v123, v47
	v_dot8c_i32_i4_e32 v40, v125, v49
	v_dot8c_i32_i4_e32 v41, v125, v47
	v_dot8c_i32_i4_e32 v42, v127, v49
	v_dot8c_i32_i4_e32 v43, v127, v47
	v_dot8c_i32_i4_e32 v44, v129, v49
	v_dot8c_i32_i4_e32 v45, v129, v47
	s_waitcnt lgkmcnt(15)
	v_and_b32_e32 v78, 0xffff, v26
	v_lshrrev_b32_e32 v79, 16, v26
	v_lshl_add_u32 v78, v78, 7, v150
	v_lshl_add_u32 v79, v79, 7, v151
	s_mov_b32 m0, s98
	s_add_i32 s43, s98, 0x400
	global_load_lds_dwordx4 v78, s[50:51]
	s_mov_b32 m0, s43
	s_nop 0
	global_load_lds_dwordx4 v79, s[50:51]
	s_waitcnt vmcnt(9)
	v_add_u32_e32 v54, s76, v59
	v_add_u32_e32 v55, s76, v60
	v_add_u32_e32 v56, s76, v61
	v_add_u32_e32 v57, s76, v62
	ds_read_b64_tr_b4 v[46:47], v160 offset:512
	ds_read_b64_tr_b4 v[48:49], v160 offset:1536
	ds_read_b64_tr_b4 v[122:123], v54
	ds_read_b64_tr_b4 v[124:125], v55
	ds_read_b64_tr_b4 v[126:127], v56
	ds_read_b64_tr_b4 v[128:129], v57
	s_waitcnt lgkmcnt(6)
	v_dot8c_i32_i4_e32 v38, v130, v52
	v_dot8c_i32_i4_e32 v39, v130, v50
	v_dot8c_i32_i4_e32 v40, v132, v52
	v_dot8c_i32_i4_e32 v41, v132, v50
	v_dot8c_i32_i4_e32 v42, v134, v52
	v_dot8c_i32_i4_e32 v43, v134, v50
	v_dot8c_i32_i4_e32 v44, v136, v52
	v_dot8c_i32_i4_e32 v45, v136, v50
	v_dot8c_i32_i4_e32 v38, v131, v53
	v_dot8c_i32_i4_e32 v39, v131, v51
	v_dot8c_i32_i4_e32 v40, v133, v53
	v_dot8c_i32_i4_e32 v41, v133, v51
	v_dot8c_i32_i4_e32 v42, v135, v53
	v_dot8c_i32_i4_e32 v43, v135, v51
	v_dot8c_i32_i4_e32 v44, v137, v53
	v_dot8c_i32_i4_e32 v45, v137, v51
	v_and_b32_e32 v78, 0xffff, v27
	v_lshrrev_b32_e32 v79, 16, v27
	v_lshl_add_u32 v78, v78, 7, v150
	v_lshl_add_u32 v79, v79, 7, v151
	s_mov_b32 m0, s99
	s_add_i32 s43, s99, 0x400
	global_load_lds_dwordx4 v78, s[50:51]
	s_mov_b32 m0, s43
	s_nop 0
	global_load_lds_dwordx4 v79, s[50:51]
	s_waitcnt vmcnt(8)
	v_add_u32_e32 v54, s77, v59
	v_add_u32_e32 v55, s77, v60
	v_add_u32_e32 v56, s77, v61
	v_add_u32_e32 v57, s77, v62
	ds_read_b64_tr_b4 v[50:51], v160 offset:640
	ds_read_b64_tr_b4 v[52:53], v160 offset:1664
	ds_read_b64_tr_b4 v[130:131], v54
	ds_read_b64_tr_b4 v[132:133], v55
	ds_read_b64_tr_b4 v[134:135], v56
	ds_read_b64_tr_b4 v[136:137], v57
	s_waitcnt lgkmcnt(6)
	v_dot8c_i32_i4_e32 v38, v122, v48
	v_dot8c_i32_i4_e32 v39, v122, v46
	v_dot8c_i32_i4_e32 v40, v124, v48
	v_dot8c_i32_i4_e32 v41, v124, v46
	v_dot8c_i32_i4_e32 v42, v126, v48
	v_dot8c_i32_i4_e32 v43, v126, v46
	v_dot8c_i32_i4_e32 v44, v128, v48
	v_dot8c_i32_i4_e32 v45, v128, v46
	v_dot8c_i32_i4_e32 v38, v123, v49
	v_dot8c_i32_i4_e32 v39, v123, v47
	v_dot8c_i32_i4_e32 v40, v125, v49
	v_dot8c_i32_i4_e32 v41, v125, v47
	v_dot8c_i32_i4_e32 v42, v127, v49
	v_dot8c_i32_i4_e32 v43, v127, v47
	v_dot8c_i32_i4_e32 v44, v129, v49
	v_dot8c_i32_i4_e32 v45, v129, v47
	s_waitcnt lgkmcnt(15)
	v_add_u32_e32 v143, 8, v139
	v_and_b32_e32 v142, 15, v143
	v_xor_b32_e32 v142, 8, v142
	v_bfe_u32 v144, v143, 4, 4
	v_mul_lo_u32 v142, v142, s92
	v_mul_lo_u32 v144, v144, s92
	v_mov_b32_e32 v143, v142
	v_mov_b32_e32 v145, v144
	ds_write2st64_b64 v159, v[142:143], v[144:145] offset1:2
	v_and_b32_e32 v78, 0xffff, v28
	v_lshrrev_b32_e32 v79, 16, v28
	v_lshl_add_u32 v78, v78, 7, v150
	v_lshl_add_u32 v79, v79, 7, v151
	s_mov_b32 m0, s76
	s_add_i32 s43, s76, 0x400
	global_load_lds_dwordx4 v78, s[50:51]
	s_mov_b32 m0, s43
	s_nop 0
	global_load_lds_dwordx4 v79, s[50:51]
	s_waitcnt vmcnt(8)
	v_add_u32_e32 v54, s78, v59
	v_add_u32_e32 v55, s78, v60
	v_add_u32_e32 v56, s78, v61
	v_add_u32_e32 v57, s78, v62
	ds_read_b64_tr_b4 v[46:47], v160 offset:768
	ds_read_b64_tr_b4 v[48:49], v160 offset:1792
	ds_read_b64_tr_b4 v[122:123], v54
	ds_read_b64_tr_b4 v[124:125], v55
	ds_read_b64_tr_b4 v[126:127], v56
	ds_read_b64_tr_b4 v[128:129], v57
	s_waitcnt lgkmcnt(7)
	v_dot8c_i32_i4_e32 v38, v130, v52
	v_dot8c_i32_i4_e32 v39, v130, v50
	v_dot8c_i32_i4_e32 v40, v132, v52
	v_dot8c_i32_i4_e32 v41, v132, v50
	v_dot8c_i32_i4_e32 v42, v134, v52
	v_dot8c_i32_i4_e32 v43, v134, v50
	v_dot8c_i32_i4_e32 v44, v136, v52
	v_dot8c_i32_i4_e32 v45, v136, v50
	v_dot8c_i32_i4_e32 v38, v131, v53
	v_dot8c_i32_i4_e32 v39, v131, v51
	v_dot8c_i32_i4_e32 v40, v133, v53
	v_dot8c_i32_i4_e32 v41, v133, v51
	v_dot8c_i32_i4_e32 v42, v135, v53
	v_dot8c_i32_i4_e32 v43, v135, v51
	v_dot8c_i32_i4_e32 v44, v137, v53
	v_dot8c_i32_i4_e32 v45, v137, v51
	v_and_b32_e32 v78, 0xffff, v29
	v_lshrrev_b32_e32 v79, 16, v29
	v_lshl_add_u32 v78, v78, 7, v150
	v_lshl_add_u32 v79, v79, 7, v151
	s_mov_b32 m0, s77
	s_add_i32 s43, s77, 0x400
	global_load_lds_dwordx4 v78, s[50:51]
	s_mov_b32 m0, s43
	s_nop 0
	global_load_lds_dwordx4 v79, s[50:51]
	s_waitcnt vmcnt(8)
	v_add_u32_e32 v54, s79, v59
	v_add_u32_e32 v55, s79, v60
	v_add_u32_e32 v56, s79, v61
	v_add_u32_e32 v57, s79, v62
	ds_read_b64_tr_b4 v[50:51], v160 offset:896
	ds_read_b64_tr_b4 v[52:53], v160 offset:1920
	ds_read_b64_tr_b4 v[130:131], v54
	ds_read_b64_tr_b4 v[132:133], v55
	ds_read_b64_tr_b4 v[134:135], v56
	ds_read_b64_tr_b4 v[136:137], v57
	s_waitcnt lgkmcnt(6)
; __device__ __forceinline__ void peer_v_tokens(int j, const LAS unsigned short* EL, const LAS unsigned char* AL  , const LAS float* ASC  , const LAS int* SAL  , ...
;     ...
;         for (int st = 0; st < 16; ++st) {
;             const int p = st >> 2, q = st & 3;
;             if (st < 14) VDMA(st + 2, (st + 2) % 3);
;             if (st < 14) asm volatile("s_waitcnt vmcnt(8)" ::: "memory");
;             else if (st == 14) asm volatile("s_waitcnt vmcnt(4)" ::: "memory");
;             else asm volatile("s_waitcnt vmcnt(0)" ::: "memory");
;             if (q == 0) {
; #pragma unroll
;                 for (int r = 0; r < 4; ++r) { accH[r] = 0; accL[r] = 0; } }
; #pragma unroll
;             for (int tp = 0; tp < 2; ++tp) {
;                 const v2i ao = TR4(ATL + (2 * q + tp) * 128 + 8 * s16), ah = TR4(ATL + 1024 + (2 * q + tp) * 128 + 8 * s16);
; #pragma unroll
;                 for (int r = 0; r < 4; ++r) {
;                     const v2i d = TR4(ldsb + BUF[st % 3] + 2048 * tp + roff[r]);
;                     accH[r] = __builtin_amdgcn_sdot8(d.x, ah.x, accH[r], false); accH[r] = __builtin_amdgcn_sdot8(d.y, ah.y, accH[r], false);
;                     accL[r] = __builtin_amdgcn_sdot8(d.x, ao.x, accL[r], false); accL[r] = __builtin_amdgcn_sdot8(d.y, ao.y, accL[r], false);
;                 }
;             }
;             asm volatile("s_waitcnt lgkmcnt(0)" ::: "memory");
;             if (q == 3) {
; #pragma unroll
;                 for (int r = 0; r < 4; ++r) STASH[256 * p + 16 * (grp + 4 * r) + pc] = f2bf(asc * (float)(2 * ((accH[r] << 4) + accL[r]) + sa));
;             }
;         }
;         CFENCE();
;         {
;             float4 v[4]; float ss = 0.f;
; #pragma unroll
;             for (int jq = 0; jq < 4; ++jq) { typedef unsigned u2v __attribute__((ext_vector_type(2))); const u2v pw = *(const LAS u2v*)(STASH + 4 * lane + 256 * jq); const uint2 hw = hv[jq];
;                 v[jq] = make_float4(__uint_as_float(hw.x << 16) + __uint_as_float(pw.x << 16), __uint_as_float(hw.x & 0xffff0000u) + __uint_as_float(pw.x & 0xffff0000u),
;                                     __uint_as_float(hw.y << 16) + __uint_as_float(pw.y << 16), __uint_as_float(hw.y & 0xffff0000u) + __uint_as_float(pw.y & 0xffff0000u));
;                 ss += v[jq].x * v[jq].x + v[jq].y * v[jq].y + v[jq].z * v[jq].z + v[jq].w * v[jq].w; }
;             ss = wave_sum(ss);
	v_dot8c_i32_i4_e32 v38, v122, v48
	v_dot8c_i32_i4_e32 v39, v122, v46
	v_dot8c_i32_i4_e32 v40, v124, v48
	v_dot8c_i32_i4_e32 v41, v124, v46
	v_dot8c_i32_i4_e32 v42, v126, v48
	v_dot8c_i32_i4_e32 v43, v126, v46
	v_dot8c_i32_i4_e32 v44, v128, v48
	v_dot8c_i32_i4_e32 v45, v128, v46
	v_dot8c_i32_i4_e32 v38, v123, v49
	v_dot8c_i32_i4_e32 v39, v123, v47
	v_dot8c_i32_i4_e32 v40, v125, v49
	v_dot8c_i32_i4_e32 v41, v125, v47
	v_dot8c_i32_i4_e32 v42, v127, v49
	v_dot8c_i32_i4_e32 v43, v127, v47
	v_dot8c_i32_i4_e32 v44, v129, v49
	v_dot8c_i32_i4_e32 v45, v129, v47
	v_and_b32_e32 v78, 0xffff, v30
	v_lshrrev_b32_e32 v79, 16, v30
	v_lshl_add_u32 v78, v78, 7, v150
	v_lshl_add_u32 v79, v79, 7, v151
	s_mov_b32 m0, s78
	s_add_i32 s43, s78, 0x400
	global_load_lds_dwordx4 v78, s[50:51]
	s_mov_b32 m0, s43
	s_nop 0
	global_load_lds_dwordx4 v79, s[50:51]
	s_waitcnt vmcnt(8)
	v_add_u32_e32 v54, s98, v59
	v_add_u32_e32 v55, s98, v60
	v_add_u32_e32 v56, s98, v61
	v_add_u32_e32 v57, s98, v62
	ds_read_b64_tr_b4 v[46:47], v160
	ds_read_b64_tr_b4 v[48:49], v160 offset:1024
	ds_read_b64_tr_b4 v[122:123], v54
	ds_read_b64_tr_b4 v[124:125], v55
	ds_read_b64_tr_b4 v[126:127], v56
	ds_read_b64_tr_b4 v[128:129], v57
	s_waitcnt lgkmcnt(6)
	v_dot8c_i32_i4_e32 v38, v130, v52
	v_dot8c_i32_i4_e32 v39, v130, v50
	v_dot8c_i32_i4_e32 v40, v132, v52
	v_dot8c_i32_i4_e32 v41, v132, v50
	v_dot8c_i32_i4_e32 v42, v134, v52
	v_dot8c_i32_i4_e32 v43, v134, v50
	v_dot8c_i32_i4_e32 v44, v136, v52
	v_dot8c_i32_i4_e32 v45, v136, v50
	v_dot8c_i32_i4_e32 v38, v131, v53
	v_dot8c_i32_i4_e32 v39, v131, v51
	v_dot8c_i32_i4_e32 v40, v133, v53
	v_dot8c_i32_i4_e32 v41, v133, v51
	v_dot8c_i32_i4_e32 v42, v135, v53
	v_dot8c_i32_i4_e32 v43, v135, v51
	v_dot8c_i32_i4_e32 v44, v137, v53
	v_dot8c_i32_i4_e32 v45, v137, v51
	s_nop 3
	s_waitcnt lgkmcnt(15)
	v_lshlrev_b32_e32 v38, 5, v38
	v_lshlrev_b32_e32 v39, 1, v39
	v_add3_u32 v38, v39, v229, v38
	v_cvt_f32_i32_e32 v38, v38
	v_mul_f32_e32 v38, v228, v38
	v_lshlrev_b32_e32 v40, 5, v40
	v_lshlrev_b32_e32 v41, 1, v41
	v_add3_u32 v40, v41, v229, v40
	v_cvt_f32_i32_e32 v40, v40
	v_mul_f32_e32 v40, v228, v40
	v_lshlrev_b32_e32 v42, 5, v42
	v_lshlrev_b32_e32 v43, 1, v43
	v_add3_u32 v42, v43, v229, v42
	v_cvt_f32_i32_e32 v42, v42
	v_mul_f32_e32 v42, v228, v42
	v_lshlrev_b32_e32 v44, 5, v44
	v_lshlrev_b32_e32 v45, 1, v45
	v_add3_u32 v44, v45, v229, v44
	v_cvt_f32_i32_e32 v44, v44
	v_mul_f32_e32 v44, v228, v44
	v_cvt_pk_bf16_f32 v182, v38, v40
	v_cvt_pk_bf16_f32 v183, v42, v44
	ds_read_b128 v[252:255], v156 offset:1024
	s_add_i32 s44, s40, 32
	s_ashr_i32 s45, s44, 31
	s_lshl_b64 s[44:45], s[44:45], 12
	v_lshl_add_u64 v[80:81], v[36:37], 0, s[44:45]
	s_waitcnt lgkmcnt(0)
	v_mul_f32_e32 v222, v222, v252
	v_mul_f32_e32 v223, v223, v253
	v_mul_f32_e32 v224, v224, v254
	v_mul_f32_e32 v225, v225, v255
	global_store_dwordx4 v[80:81], v[222:225], off offset:3072 nt
	ds_read_b128 v[252:255], v155
	s_add_i32 s44, s40, 40
	s_ashr_i32 s45, s44, 31
	s_lshl_b64 s[44:45], s[44:45], 12
	v_lshl_add_u64 v[80:81], v[36:37], 0, s[44:45]
	s_waitcnt lgkmcnt(0)
	v_mul_f32_e32 v236, v236, v252
	v_mul_f32_e32 v237, v237, v253
	v_mul_f32_e32 v238, v238, v254
	v_mul_f32_e32 v239, v239, v255
	global_store_dwordx4 v[80:81], v[236:239], off nt
	v_add_u32_e32 v147, 8, v140
	v_and_b32_e32 v146, 15, v147
	v_xor_b32_e32 v146, 8, v146
	v_bfe_u32 v148, v147, 4, 4
	v_mul_lo_u32 v146, v146, s92
	v_mul_lo_u32 v148, v148, s92
	v_mov_b32_e32 v147, v146
	v_mov_b32_e32 v149, v148
	ds_write2st64_b64 v77, v[146:147], v[148:149] offset1:2
	v_add_u32_e32 v138, 0x1800, v74
	ds_read_u8 v139, v138
	v_add_u32_e32 v141, 0x1800, v73
	ds_read_u8 v140, v141
	s_add_i32 s43, s67, 224
	v_mov_b32_e32 v138, s43
	ds_read2st64_b32 v[228:229], v138 offset1:1
	ds_read_b128 v[18:21], v227 offset:12288
	ds_read_b128 v[22:25], v227 offset:12304
	v_add_u32_e32 v152, 0x600000, v63
	v_add_u32_e32 v153, 0x600000, v64
	v_mov_b32_e32 v38, 0
	v_mov_b32_e32 v39, 0
	v_mov_b32_e32 v40, 0
	v_mov_b32_e32 v41, 0
	v_mov_b32_e32 v42, 0
	v_mov_b32_e32 v43, 0
	v_mov_b32_e32 v44, 0
	v_mov_b32_e32 v45, 0
	v_and_b32_e32 v78, 0xffff, v31
	v_lshrrev_b32_e32 v79, 16, v31
	v_lshl_add_u32 v78, v78, 7, v150
	v_lshl_add_u32 v79, v79, 7, v151
	s_mov_b32 m0, s79
	s_add_i32 s43, s79, 0x400
	global_load_lds_dwordx4 v78, s[50:51]
	s_mov_b32 m0, s43
	s_nop 0
	global_load_lds_dwordx4 v79, s[50:51]
	s_waitcnt vmcnt(10)
	v_add_u32_e32 v54, s99, v59
	v_add_u32_e32 v55, s99, v60
	v_add_u32_e32 v56, s99, v61
	v_add_u32_e32 v57, s99, v62
	ds_read_b64_tr_b4 v[50:51], v160 offset:128
	ds_read_b64_tr_b4 v[52:53], v160 offset:1152
	ds_read_b64_tr_b4 v[130:131], v54
	ds_read_b64_tr_b4 v[132:133], v55
	ds_read_b64_tr_b4 v[134:135], v56
	ds_read_b64_tr_b4 v[136:137], v57
	s_waitcnt lgkmcnt(14)
	v_dot8c_i32_i4_e32 v38, v122, v48
	v_dot8c_i32_i4_e32 v39, v122, v46
	v_dot8c_i32_i4_e32 v40, v124, v48
	v_dot8c_i32_i4_e32 v41, v124, v46
	v_dot8c_i32_i4_e32 v42, v126, v48
	v_dot8c_i32_i4_e32 v43, v126, v46
	v_dot8c_i32_i4_e32 v44, v128, v48
	v_dot8c_i32_i4_e32 v45, v128, v46
	v_dot8c_i32_i4_e32 v38, v123, v49
	v_dot8c_i32_i4_e32 v39, v123, v47
	v_dot8c_i32_i4_e32 v40, v125, v49
	v_dot8c_i32_i4_e32 v41, v125, v47
	v_dot8c_i32_i4_e32 v42, v127, v49
	v_dot8c_i32_i4_e32 v43, v127, v47
	v_dot8c_i32_i4_e32 v44, v129, v49
	v_dot8c_i32_i4_e32 v45, v129, v47
	v_and_b32_e32 v78, 0xffff, v32
	v_lshrrev_b32_e32 v79, 16, v32
	v_lshl_add_u32 v78, v78, 7, v150
	v_lshl_add_u32 v79, v79, 7, v151
	s_mov_b32 m0, s98
	s_add_i32 s43, s98, 0x400
	global_load_lds_dwordx4 v78, s[50:51]
	s_mov_b32 m0, s43
	s_nop 0
	global_load_lds_dwordx4 v79, s[50:51]
	s_waitcnt vmcnt(10)
; #define LAS __attribute__((address_space(3)))
; #define TR4(p_) __builtin_amdgcn_ds_read_tr4_b64_v2i32((LAS v2i*)(p_))
; #define CFENCE() asm volatile("" ::: "memory")
; __device__ __forceinline__ void peer_v_tokens(int j, const LAS unsigned short* EL, const LAS unsigned char* AL  , const LAS float* ASC  , const LAS int* SAL  , ...
;     ...
; #pragma unroll
;         for (int m = 0; m < 2; ++m) {
;             const int idx = lane + 64 * m, tau = idx >> 4, sr = idx & 15, k = 16 * (sr & 7) + 2 * tau + (sr >> 3);
;             const int aq = (int)*(const LAS signed char*)(AL + tl * 128 + k); const int tq = aq + 8;
;             const unsigned lo = (((unsigned)tq & 15u) ^ 8u) * 0x11111111u, hi = ((unsigned)(tq >> 4) & 15u) * 0x11111111u;
;             typedef unsigned u2v __attribute__((ext_vector_type(2)));
;             u2v l2; l2.x = lo; l2.y = lo; u2v h2; h2.x = hi; h2.y = hi;
;             *(LAS u2v*)(ATL + 8 * idx) = l2; *(LAS u2v*)(ATL + 1024 + 8 * idx) = h2;
;         }
;         const float asc = ASC[tl]; const int sa = SAL[tl];
;         CFENCE();
;         int accH[4], accL[4];
; #pragma unroll
;         for (int st = 0; st < 16; ++st) {
;             const int p = st >> 2, q = st & 3;
;             if (st < 14) VDMA(st + 2, (st + 2) % 3);
;             if (st < 14) asm volatile("s_waitcnt vmcnt(8)" ::: "memory");
;             else if (st == 14) asm volatile("s_waitcnt vmcnt(4)" ::: "memory");
;             else asm volatile("s_waitcnt vmcnt(0)" ::: "memory");
;             if (q == 0) {
; #pragma unroll
;                 for (int r = 0; r < 4; ++r) { accH[r] = 0; accL[r] = 0; } }
; #pragma unroll
;             for (int tp = 0; tp < 2; ++tp) {
;                 const v2i ao = TR4(ATL + (2 * q + tp) * 128 + 8 * s16), ah = TR4(ATL + 1024 + (2 * q + tp) * 128 + 8 * s16);
; #pragma unroll
;                 for (int r = 0; r < 4; ++r) {
;                     const v2i d = TR4(ldsb + BUF[st % 3] + 2048 * tp + roff[r]);
;                     accH[r] = __builtin_amdgcn_sdot8(d.x, ah.x, accH[r], false); accH[r] = __builtin_amdgcn_sdot8(d.y, ah.y, accH[r], false);
;                     accL[r] = __builtin_amdgcn_sdot8(d.x, ao.x, accL[r], false); accL[r] = __builtin_amdgcn_sdot8(d.y, ao.y, accL[r], false);
;                 }
	v_add_u32_e32 v54, s76, v59
	v_add_u32_e32 v55, s76, v60
	v_add_u32_e32 v56, s76, v61
	v_add_u32_e32 v57, s76, v62
	ds_read_b64_tr_b4 v[46:47], v160 offset:256
	ds_read_b64_tr_b4 v[48:49], v160 offset:1280
	ds_read_b64_tr_b4 v[122:123], v54
	ds_read_b64_tr_b4 v[124:125], v55
	ds_read_b64_tr_b4 v[126:127], v56
	ds_read_b64_tr_b4 v[128:129], v57
	s_waitcnt lgkmcnt(6)
	v_dot8c_i32_i4_e32 v38, v130, v52
	v_dot8c_i32_i4_e32 v39, v130, v50
	v_dot8c_i32_i4_e32 v40, v132, v52
	v_dot8c_i32_i4_e32 v41, v132, v50
	v_dot8c_i32_i4_e32 v42, v134, v52
	v_dot8c_i32_i4_e32 v43, v134, v50
	v_dot8c_i32_i4_e32 v44, v136, v52
	v_dot8c_i32_i4_e32 v45, v136, v50
	v_dot8c_i32_i4_e32 v38, v131, v53
	v_dot8c_i32_i4_e32 v39, v131, v51
	v_dot8c_i32_i4_e32 v40, v133, v53
	v_dot8c_i32_i4_e32 v41, v133, v51
	v_dot8c_i32_i4_e32 v42, v135, v53
	v_dot8c_i32_i4_e32 v43, v135, v51
	v_dot8c_i32_i4_e32 v44, v137, v53
	v_dot8c_i32_i4_e32 v45, v137, v51
	v_and_b32_e32 v78, 0xffff, v33
	v_lshrrev_b32_e32 v79, 16, v33
	v_lshl_add_u32 v78, v78, 7, v150
	v_lshl_add_u32 v79, v79, 7, v151
	s_mov_b32 m0, s99
	s_add_i32 s43, s99, 0x400
	global_load_lds_dwordx4 v78, s[50:51]
	s_mov_b32 m0, s43
	s_nop 0
	global_load_lds_dwordx4 v79, s[50:51]
	s_waitcnt vmcnt(10)
	v_add_u32_e32 v54, s77, v59
	v_add_u32_e32 v55, s77, v60
	v_add_u32_e32 v56, s77, v61
	v_add_u32_e32 v57, s77, v62
	ds_read_b64_tr_b4 v[50:51], v160 offset:384
	ds_read_b64_tr_b4 v[52:53], v160 offset:1408
	ds_read_b64_tr_b4 v[130:131], v54
	ds_read_b64_tr_b4 v[132:133], v55
	ds_read_b64_tr_b4 v[134:135], v56
	ds_read_b64_tr_b4 v[136:137], v57
	s_waitcnt lgkmcnt(6)
	v_dot8c_i32_i4_e32 v38, v122, v48
	v_dot8c_i32_i4_e32 v39, v122, v46
	v_dot8c_i32_i4_e32 v40, v124, v48
	v_dot8c_i32_i4_e32 v41, v124, v46
	v_dot8c_i32_i4_e32 v42, v126, v48
	v_dot8c_i32_i4_e32 v43, v126, v46
	v_dot8c_i32_i4_e32 v44, v128, v48
	v_dot8c_i32_i4_e32 v45, v128, v46
	v_dot8c_i32_i4_e32 v38, v123, v49
	v_dot8c_i32_i4_e32 v39, v123, v47
	v_dot8c_i32_i4_e32 v40, v125, v49
	v_dot8c_i32_i4_e32 v41, v125, v47
	v_dot8c_i32_i4_e32 v42, v127, v49
	v_dot8c_i32_i4_e32 v43, v127, v47
	v_dot8c_i32_i4_e32 v44, v129, v49
	v_dot8c_i32_i4_e32 v45, v129, v47
	s_waitcnt lgkmcnt(15)
	v_and_b32_e32 v78, 0xffff, v18
	v_lshrrev_b32_e32 v79, 16, v18
	v_lshl_add_u32 v78, v78, 7, v152
	v_lshl_add_u32 v79, v79, 7, v153
	s_mov_b32 m0, s76
	s_add_i32 s43, s76, 0x400
	global_load_lds_dwordx4 v78, s[50:51]
	s_mov_b32 m0, s43
	s_nop 0
	global_load_lds_dwordx4 v79, s[50:51]
	s_waitcnt vmcnt(10)
	v_add_u32_e32 v54, s78, v59
	v_add_u32_e32 v55, s78, v60
	v_add_u32_e32 v56, s78, v61
	v_add_u32_e32 v57, s78, v62
	ds_read_b64_tr_b4 v[46:47], v160 offset:512
	ds_read_b64_tr_b4 v[48:49], v160 offset:1536
	ds_read_b64_tr_b4 v[122:123], v54
	ds_read_b64_tr_b4 v[124:125], v55
	ds_read_b64_tr_b4 v[126:127], v56
	ds_read_b64_tr_b4 v[128:129], v57
	s_waitcnt lgkmcnt(6)
	v_dot8c_i32_i4_e32 v38, v130, v52
	v_dot8c_i32_i4_e32 v39, v130, v50
	v_dot8c_i32_i4_e32 v40, v132, v52
	v_dot8c_i32_i4_e32 v41, v132, v50
	v_dot8c_i32_i4_e32 v42, v134, v52
	v_dot8c_i32_i4_e32 v43, v134, v50
	v_dot8c_i32_i4_e32 v44, v136, v52
	v_dot8c_i32_i4_e32 v45, v136, v50
	v_dot8c_i32_i4_e32 v38, v131, v53
	v_dot8c_i32_i4_e32 v39, v131, v51
	v_dot8c_i32_i4_e32 v40, v133, v53
	v_dot8c_i32_i4_e32 v41, v133, v51
	v_dot8c_i32_i4_e32 v42, v135, v53
	v_dot8c_i32_i4_e32 v43, v135, v51
	v_dot8c_i32_i4_e32 v44, v137, v53
	v_dot8c_i32_i4_e32 v45, v137, v51
	v_and_b32_e32 v78, 0xffff, v19
	v_lshrrev_b32_e32 v79, 16, v19
	v_lshl_add_u32 v78, v78, 7, v152
	v_lshl_add_u32 v79, v79, 7, v153
	s_mov_b32 m0, s77
	s_add_i32 s43, s77, 0x400
	global_load_lds_dwordx4 v78, s[50:51]
	s_mov_b32 m0, s43
	s_nop 0
	global_load_lds_dwordx4 v79, s[50:51]
	s_waitcnt vmcnt(8)
	v_add_u32_e32 v54, s79, v59
	v_add_u32_e32 v55, s79, v60
	v_add_u32_e32 v56, s79, v61
	v_add_u32_e32 v57, s79, v62
	ds_read_b64_tr_b4 v[50:51], v160 offset:640
	ds_read_b64_tr_b4 v[52:53], v160 offset:1664
	ds_read_b64_tr_b4 v[130:131], v54
	ds_read_b64_tr_b4 v[132:133], v55
	ds_read_b64_tr_b4 v[134:135], v56
	ds_read_b64_tr_b4 v[136:137], v57
	s_waitcnt lgkmcnt(6)
	v_dot8c_i32_i4_e32 v38, v122, v48
	v_dot8c_i32_i4_e32 v39, v122, v46
	v_dot8c_i32_i4_e32 v40, v124, v48
	v_dot8c_i32_i4_e32 v41, v124, v46
	v_dot8c_i32_i4_e32 v42, v126, v48
	v_dot8c_i32_i4_e32 v43, v126, v46
	v_dot8c_i32_i4_e32 v44, v128, v48
	v_dot8c_i32_i4_e32 v45, v128, v46
	v_dot8c_i32_i4_e32 v38, v123, v49
	v_dot8c_i32_i4_e32 v39, v123, v47
	v_dot8c_i32_i4_e32 v40, v125, v49
	v_dot8c_i32_i4_e32 v41, v125, v47
	v_dot8c_i32_i4_e32 v42, v127, v49
	v_dot8c_i32_i4_e32 v43, v127, v47
	v_dot8c_i32_i4_e32 v44, v129, v49
	v_dot8c_i32_i4_e32 v45, v129, v47
	s_waitcnt lgkmcnt(15)
	v_add_u32_e32 v143, 8, v139
	v_and_b32_e32 v142, 15, v143
	v_xor_b32_e32 v142, 8, v142
	v_bfe_u32 v144, v143, 4, 4
	v_mul_lo_u32 v142, v142, s92
	v_mul_lo_u32 v144, v144, s92
	v_mov_b32_e32 v143, v142
	v_mov_b32_e32 v145, v144
	ds_write2st64_b64 v159, v[142:143], v[144:145] offset1:2
	v_and_b32_e32 v78, 0xffff, v20
	v_lshrrev_b32_e32 v79, 16, v20
	v_lshl_add_u32 v78, v78, 7, v152
	v_lshl_add_u32 v79, v79, 7, v153
	s_mov_b32 m0, s78
	s_add_i32 s43, s78, 0x400
	global_load_lds_dwordx4 v78, s[50:51]
	s_mov_b32 m0, s43
	s_nop 0
	global_load_lds_dwordx4 v79, s[50:51]
	s_waitcnt vmcnt(8)
	v_add_u32_e32 v54, s98, v59
	v_add_u32_e32 v55, s98, v60
	v_add_u32_e32 v56, s98, v61
	v_add_u32_e32 v57, s98, v62
	ds_read_b64_tr_b4 v[46:47], v160 offset:768
	ds_read_b64_tr_b4 v[48:49], v160 offset:1792
	ds_read_b64_tr_b4 v[122:123], v54
	ds_read_b64_tr_b4 v[124:125], v55
	ds_read_b64_tr_b4 v[126:127], v56
	ds_read_b64_tr_b4 v[128:129], v57
	s_waitcnt lgkmcnt(7)
; __device__ __forceinline__ void peer_v_tokens(int j, const LAS unsigned short* EL, const LAS unsigned char* AL  , const LAS float* ASC  , const LAS int* SAL  , ...
;     ...
;         for (int st = 0; st < 16; ++st) {
;             const int p = st >> 2, q = st & 3;
;             if (st < 14) VDMA(st + 2, (st + 2) % 3);
;             if (st < 14) asm volatile("s_waitcnt vmcnt(8)" ::: "memory");
;             else if (st == 14) asm volatile("s_waitcnt vmcnt(4)" ::: "memory");
;             else asm volatile("s_waitcnt vmcnt(0)" ::: "memory");
;             if (q == 0) {
; #pragma unroll
;                 for (int r = 0; r < 4; ++r) { accH[r] = 0; accL[r] = 0; } }
; #pragma unroll
;             for (int tp = 0; tp < 2; ++tp) {
;                 const v2i ao = TR4(ATL + (2 * q + tp) * 128 + 8 * s16), ah = TR4(ATL + 1024 + (2 * q + tp) * 128 + 8 * s16);
; #pragma unroll
;                 for (int r = 0; r < 4; ++r) {
;                     const v2i d = TR4(ldsb + BUF[st % 3] + 2048 * tp + roff[r]);
;                     accH[r] = __builtin_amdgcn_sdot8(d.x, ah.x, accH[r], false); accH[r] = __builtin_amdgcn_sdot8(d.y, ah.y, accH[r], false);
;                     accL[r] = __builtin_amdgcn_sdot8(d.x, ao.x, accL[r], false); accL[r] = __builtin_amdgcn_sdot8(d.y, ao.y, accL[r], false);
;                 }
;             }
;             asm volatile("s_waitcnt lgkmcnt(0)" ::: "memory");
;             if (q == 3) {
; #pragma unroll
;                 for (int r = 0; r < 4; ++r) STASH[256 * p + 16 * (grp + 4 * r) + pc] = f2bf(asc * (float)(2 * ((accH[r] << 4) + accL[r]) + sa));
;             }
;         }
;         CFENCE();
;         {
;             float4 v[4]; float ss = 0.f;
; #pragma unroll
;             for (int jq = 0; jq < 4; ++jq) { typedef unsigned u2v __attribute__((ext_vector_type(2))); const u2v pw = *(const LAS u2v*)(STASH + 4 * lane + 256 * jq); const uint2 hw = hv[jq];
;                 v[jq] = make_float4(__uint_as_float(hw.x << 16) + __uint_as_float(pw.x << 16), __uint_as_float(hw.x & 0xffff0000u) + __uint_as_float(pw.x & 0xffff0000u),
;                                     __uint_as_float(hw.y << 16) + __uint_as_float(pw.y << 16), __uint_as_float(hw.y & 0xffff0000u) + __uint_as_float(pw.y & 0xffff0000u));
;                 ss += v[jq].x * v[jq].x + v[jq].y * v[jq].y + v[jq].z * v[jq].z + v[jq].w * v[jq].w; }
;             ss = wave_sum(ss);
	v_dot8c_i32_i4_e32 v38, v130, v52
	v_dot8c_i32_i4_e32 v39, v130, v50
	v_dot8c_i32_i4_e32 v40, v132, v52
	v_dot8c_i32_i4_e32 v41, v132, v50
	v_dot8c_i32_i4_e32 v42, v134, v52
	v_dot8c_i32_i4_e32 v43, v134, v50
	v_dot8c_i32_i4_e32 v44, v136, v52
	v_dot8c_i32_i4_e32 v45, v136, v50
	v_dot8c_i32_i4_e32 v38, v131, v53
	v_dot8c_i32_i4_e32 v39, v131, v51
	v_dot8c_i32_i4_e32 v40, v133, v53
	v_dot8c_i32_i4_e32 v41, v133, v51
	v_dot8c_i32_i4_e32 v42, v135, v53
	v_dot8c_i32_i4_e32 v43, v135, v51
	v_dot8c_i32_i4_e32 v44, v137, v53
	v_dot8c_i32_i4_e32 v45, v137, v51
	v_and_b32_e32 v78, 0xffff, v21
	v_lshrrev_b32_e32 v79, 16, v21
	v_lshl_add_u32 v78, v78, 7, v152
	v_lshl_add_u32 v79, v79, 7, v153
	s_mov_b32 m0, s79
	s_add_i32 s43, s79, 0x400
	global_load_lds_dwordx4 v78, s[50:51]
	s_mov_b32 m0, s43
	s_nop 0
	global_load_lds_dwordx4 v79, s[50:51]
	s_waitcnt vmcnt(8)
	v_add_u32_e32 v54, s99, v59
	v_add_u32_e32 v55, s99, v60
	v_add_u32_e32 v56, s99, v61
	v_add_u32_e32 v57, s99, v62
	ds_read_b64_tr_b4 v[50:51], v160 offset:896
	ds_read_b64_tr_b4 v[52:53], v160 offset:1920
	ds_read_b64_tr_b4 v[130:131], v54
	ds_read_b64_tr_b4 v[132:133], v55
	ds_read_b64_tr_b4 v[134:135], v56
	ds_read_b64_tr_b4 v[136:137], v57
	s_waitcnt lgkmcnt(6)
	v_dot8c_i32_i4_e32 v38, v122, v48
	v_dot8c_i32_i4_e32 v39, v122, v46
	v_dot8c_i32_i4_e32 v40, v124, v48
	v_dot8c_i32_i4_e32 v41, v124, v46
	v_dot8c_i32_i4_e32 v42, v126, v48
	v_dot8c_i32_i4_e32 v43, v126, v46
	v_dot8c_i32_i4_e32 v44, v128, v48
	v_dot8c_i32_i4_e32 v45, v128, v46
	v_dot8c_i32_i4_e32 v38, v123, v49
	v_dot8c_i32_i4_e32 v39, v123, v47
	v_dot8c_i32_i4_e32 v40, v125, v49
	v_dot8c_i32_i4_e32 v41, v125, v47
	v_dot8c_i32_i4_e32 v42, v127, v49
	v_dot8c_i32_i4_e32 v43, v127, v47
	v_dot8c_i32_i4_e32 v44, v129, v49
	v_dot8c_i32_i4_e32 v45, v129, v47
	v_and_b32_e32 v78, 0xffff, v22
	v_lshrrev_b32_e32 v79, 16, v22
	v_lshl_add_u32 v78, v78, 7, v152
	v_lshl_add_u32 v79, v79, 7, v153
	s_mov_b32 m0, s98
	s_add_i32 s43, s98, 0x400
	global_load_lds_dwordx4 v78, s[50:51]
	s_mov_b32 m0, s43
	s_nop 0
	global_load_lds_dwordx4 v79, s[50:51]
	s_waitcnt vmcnt(8)
	v_add_u32_e32 v54, s76, v59
	v_add_u32_e32 v55, s76, v60
	v_add_u32_e32 v56, s76, v61
	v_add_u32_e32 v57, s76, v62
	ds_read_b64_tr_b4 v[46:47], v160
	ds_read_b64_tr_b4 v[48:49], v160 offset:1024
	ds_read_b64_tr_b4 v[122:123], v54
	ds_read_b64_tr_b4 v[124:125], v55
	ds_read_b64_tr_b4 v[126:127], v56
	ds_read_b64_tr_b4 v[128:129], v57
	s_waitcnt lgkmcnt(6)
	v_dot8c_i32_i4_e32 v38, v130, v52
	v_dot8c_i32_i4_e32 v39, v130, v50
	v_dot8c_i32_i4_e32 v40, v132, v52
	v_dot8c_i32_i4_e32 v41, v132, v50
	v_dot8c_i32_i4_e32 v42, v134, v52
	v_dot8c_i32_i4_e32 v43, v134, v50
	v_dot8c_i32_i4_e32 v44, v136, v52
	v_dot8c_i32_i4_e32 v45, v136, v50
	v_dot8c_i32_i4_e32 v38, v131, v53
	v_dot8c_i32_i4_e32 v39, v131, v51
	v_dot8c_i32_i4_e32 v40, v133, v53
	v_dot8c_i32_i4_e32 v41, v133, v51
	v_dot8c_i32_i4_e32 v42, v135, v53
	v_dot8c_i32_i4_e32 v43, v135, v51
	v_dot8c_i32_i4_e32 v44, v137, v53
	v_dot8c_i32_i4_e32 v45, v137, v51
	s_nop 3
	s_waitcnt lgkmcnt(15)
	v_lshlrev_b32_e32 v38, 5, v38
	v_lshlrev_b32_e32 v39, 1, v39
	v_add3_u32 v38, v39, v229, v38
	v_cvt_f32_i32_e32 v38, v38
	v_mul_f32_e32 v38, v228, v38
	v_lshlrev_b32_e32 v40, 5, v40
	v_lshlrev_b32_e32 v41, 1, v41
	v_add3_u32 v40, v41, v229, v40
	v_cvt_f32_i32_e32 v40, v40
	v_mul_f32_e32 v40, v228, v40
	v_lshlrev_b32_e32 v42, 5, v42
	v_lshlrev_b32_e32 v43, 1, v43
	v_add3_u32 v42, v43, v229, v42
	v_cvt_f32_i32_e32 v42, v42
	v_mul_f32_e32 v42, v228, v42
	v_lshlrev_b32_e32 v44, 5, v44
	v_lshlrev_b32_e32 v45, 1, v45
	v_add3_u32 v44, v45, v229, v44
	v_cvt_f32_i32_e32 v44, v44
	v_mul_f32_e32 v44, v228, v44
	v_cvt_pk_bf16_f32 v190, v38, v40
	v_cvt_pk_bf16_f32 v191, v42, v44
	ds_read_b128 v[252:255], v155 offset:1024
	s_add_i32 s44, s40, 40
	s_ashr_i32 s45, s44, 31
	s_lshl_b64 s[44:45], s[44:45], 12
	v_lshl_add_u64 v[80:81], v[36:37], 0, s[44:45]
	s_waitcnt lgkmcnt(0)
	v_mul_f32_e32 v240, v240, v252
	v_mul_f32_e32 v241, v241, v253
	v_mul_f32_e32 v242, v242, v254
	v_mul_f32_e32 v243, v243, v255
	global_store_dwordx4 v[80:81], v[240:243], off offset:1024 nt
	v_add_u32_e32 v147, 8, v140
	v_and_b32_e32 v146, 15, v147
	v_xor_b32_e32 v146, 8, v146
	v_bfe_u32 v148, v147, 4, 4
	v_mul_lo_u32 v146, v146, s92
	v_mul_lo_u32 v148, v148, s92
	v_mov_b32_e32 v147, v146
	v_mov_b32_e32 v149, v148
	ds_write2st64_b64 v77, v[146:147], v[148:149] offset1:2
	v_add_u32_e32 v138, 0x1c00, v74
	ds_read_u8 v139, v138
	v_add_u32_e32 v141, 0x1c00, v73
	ds_read_u8 v140, v141
	s_add_i32 s43, s67, 192
	v_mov_b32_e32 v138, s43
	ds_read2st64_b32 v[228:229], v138 offset1:1
	ds_read_b128 v[26:29], v227 offset:14336
	ds_read_b128 v[30:33], v227 offset:14352
	v_mov_b32_e32 v38, 0
	v_mov_b32_e32 v39, 0
	v_mov_b32_e32 v40, 0
	v_mov_b32_e32 v41, 0
	v_mov_b32_e32 v42, 0
	v_mov_b32_e32 v43, 0
	v_mov_b32_e32 v44, 0
	v_mov_b32_e32 v45, 0
	v_and_b32_e32 v78, 0xffff, v23
	v_lshrrev_b32_e32 v79, 16, v23
	v_lshl_add_u32 v78, v78, 7, v152
	v_lshl_add_u32 v79, v79, 7, v153
	s_mov_b32 m0, s99
	s_add_i32 s43, s99, 0x400
	global_load_lds_dwordx4 v78, s[50:51]
	s_mov_b32 m0, s43
	s_nop 0
	global_load_lds_dwordx4 v79, s[50:51]
	s_waitcnt vmcnt(9)
	v_add_u32_e32 v54, s77, v59
	v_add_u32_e32 v55, s77, v60
	v_add_u32_e32 v56, s77, v61
	v_add_u32_e32 v57, s77, v62
	ds_read_b64_tr_b4 v[50:51], v160 offset:128
	ds_read_b64_tr_b4 v[52:53], v160 offset:1152
	ds_read_b64_tr_b4 v[130:131], v54
	ds_read_b64_tr_b4 v[132:133], v55
	ds_read_b64_tr_b4 v[134:135], v56
	ds_read_b64_tr_b4 v[136:137], v57
	s_waitcnt lgkmcnt(13)
; #define TR4(p_) __builtin_amdgcn_ds_read_tr4_b64_v2i32((LAS v2i*)(p_))
; #define VDMA(st_, k_) do { _Pragma("unroll") for (int i_ = 0; i_ < 4; ++i_) { \
;         const unsigned off_ = (unsigned)((st_) >> 2) * (16384u * 128u) + (PE_ID(E, 4 * ((st_) & 3) + i_) << 7) + ((i_ & 1) ? cx1 : cx0); \
;         __builtin_amdgcn_global_load_lds((const unsigned*)(V4 + off_), (LAS unsigned*)(ldsb + BUF[k_] + 1024 * i_), 16, 0, 0); } } while (0)
; __device__ __forceinline__ void peer_v_tokens(int j, const LAS unsigned short* EL, const LAS unsigned char* AL  , const LAS float* ASC  , const LAS int* SAL  , ...
;     ...
;         for (int st = 0; st < 16; ++st) {
;             const int p = st >> 2, q = st & 3;
;             if (st < 14) VDMA(st + 2, (st + 2) % 3);
;             if (st < 14) asm volatile("s_waitcnt vmcnt(8)" ::: "memory");
;             else if (st == 14) asm volatile("s_waitcnt vmcnt(4)" ::: "memory");
;             else asm volatile("s_waitcnt vmcnt(0)" ::: "memory");
;             if (q == 0) {
; #pragma unroll
;                 for (int r = 0; r < 4; ++r) { accH[r] = 0; accL[r] = 0; } }
; #pragma unroll
;             for (int tp = 0; tp < 2; ++tp) {
;                 const v2i ao = TR4(ATL + (2 * q + tp) * 128 + 8 * s16), ah = TR4(ATL + 1024 + (2 * q + tp) * 128 + 8 * s16);
; #pragma unroll
;                 for (int r = 0; r < 4; ++r) {
;                     const v2i d = TR4(ldsb + BUF[st % 3] + 2048 * tp + roff[r]);
;                     accH[r] = __builtin_amdgcn_sdot8(d.x, ah.x, accH[r], false); accH[r] = __builtin_amdgcn_sdot8(d.y, ah.y, accH[r], false);
;                     accL[r] = __builtin_amdgcn_sdot8(d.x, ao.x, accL[r], false); accL[r] = __builtin_amdgcn_sdot8(d.y, ao.y, accL[r], false);
;                 }
	v_dot8c_i32_i4_e32 v38, v122, v48
	v_dot8c_i32_i4_e32 v39, v122, v46
	v_dot8c_i32_i4_e32 v40, v124, v48
	v_dot8c_i32_i4_e32 v41, v124, v46
	v_dot8c_i32_i4_e32 v42, v126, v48
	v_dot8c_i32_i4_e32 v43, v126, v46
	v_dot8c_i32_i4_e32 v44, v128, v48
	v_dot8c_i32_i4_e32 v45, v128, v46
	v_dot8c_i32_i4_e32 v38, v123, v49
	v_dot8c_i32_i4_e32 v39, v123, v47
	v_dot8c_i32_i4_e32 v40, v125, v49
	v_dot8c_i32_i4_e32 v41, v125, v47
	v_dot8c_i32_i4_e32 v42, v127, v49
	v_dot8c_i32_i4_e32 v43, v127, v47
	v_dot8c_i32_i4_e32 v44, v129, v49
	v_dot8c_i32_i4_e32 v45, v129, v47
	v_and_b32_e32 v78, 0xffff, v24
	v_lshrrev_b32_e32 v79, 16, v24
	v_lshl_add_u32 v78, v78, 7, v152
	v_lshl_add_u32 v79, v79, 7, v153
	s_mov_b32 m0, s76
	s_add_i32 s43, s76, 0x400
	global_load_lds_dwordx4 v78, s[50:51]
	s_mov_b32 m0, s43
	s_nop 0
	global_load_lds_dwordx4 v79, s[50:51]
	s_waitcnt vmcnt(9)
	v_add_u32_e32 v54, s78, v59
	v_add_u32_e32 v55, s78, v60
	v_add_u32_e32 v56, s78, v61
	v_add_u32_e32 v57, s78, v62
	ds_read_b64_tr_b4 v[46:47], v160 offset:256
	ds_read_b64_tr_b4 v[48:49], v160 offset:1280
	ds_read_b64_tr_b4 v[122:123], v54
	ds_read_b64_tr_b4 v[124:125], v55
	ds_read_b64_tr_b4 v[126:127], v56
	ds_read_b64_tr_b4 v[128:129], v57
	s_waitcnt lgkmcnt(6)
	v_dot8c_i32_i4_e32 v38, v130, v52
	v_dot8c_i32_i4_e32 v39, v130, v50
	v_dot8c_i32_i4_e32 v40, v132, v52
	v_dot8c_i32_i4_e32 v41, v132, v50
	v_dot8c_i32_i4_e32 v42, v134, v52
	v_dot8c_i32_i4_e32 v43, v134, v50
	v_dot8c_i32_i4_e32 v44, v136, v52
	v_dot8c_i32_i4_e32 v45, v136, v50
	v_dot8c_i32_i4_e32 v38, v131, v53
	v_dot8c_i32_i4_e32 v39, v131, v51
	v_dot8c_i32_i4_e32 v40, v133, v53
	v_dot8c_i32_i4_e32 v41, v133, v51
	v_dot8c_i32_i4_e32 v42, v135, v53
	v_dot8c_i32_i4_e32 v43, v135, v51
	v_dot8c_i32_i4_e32 v44, v137, v53
	v_dot8c_i32_i4_e32 v45, v137, v51
	v_and_b32_e32 v78, 0xffff, v25
	v_lshrrev_b32_e32 v79, 16, v25
	v_lshl_add_u32 v78, v78, 7, v152
	v_lshl_add_u32 v79, v79, 7, v153
	s_mov_b32 m0, s77
	s_add_i32 s43, s77, 0x400
	global_load_lds_dwordx4 v78, s[50:51]
	s_mov_b32 m0, s43
	s_nop 0
	global_load_lds_dwordx4 v79, s[50:51]
	s_waitcnt vmcnt(9)
	v_add_u32_e32 v54, s79, v59
	v_add_u32_e32 v55, s79, v60
	v_add_u32_e32 v56, s79, v61
	v_add_u32_e32 v57, s79, v62
	ds_read_b64_tr_b4 v[50:51], v160 offset:384
	ds_read_b64_tr_b4 v[52:53], v160 offset:1408
	ds_read_b64_tr_b4 v[130:131], v54
	ds_read_b64_tr_b4 v[132:133], v55
	ds_read_b64_tr_b4 v[134:135], v56
	ds_read_b64_tr_b4 v[136:137], v57
	s_waitcnt lgkmcnt(6)
	v_dot8c_i32_i4_e32 v38, v122, v48
	v_dot8c_i32_i4_e32 v39, v122, v46
	v_dot8c_i32_i4_e32 v40, v124, v48
	v_dot8c_i32_i4_e32 v41, v124, v46
	v_dot8c_i32_i4_e32 v42, v126, v48
	v_dot8c_i32_i4_e32 v43, v126, v46
	v_dot8c_i32_i4_e32 v44, v128, v48
	v_dot8c_i32_i4_e32 v45, v128, v46
	v_dot8c_i32_i4_e32 v38, v123, v49
	v_dot8c_i32_i4_e32 v39, v123, v47
	v_dot8c_i32_i4_e32 v40, v125, v49
	v_dot8c_i32_i4_e32 v41, v125, v47
	v_dot8c_i32_i4_e32 v42, v127, v49
	v_dot8c_i32_i4_e32 v43, v127, v47
	v_dot8c_i32_i4_e32 v44, v129, v49
	v_dot8c_i32_i4_e32 v45, v129, v47
	s_waitcnt lgkmcnt(15)
	v_and_b32_e32 v78, 0xffff, v26
	v_lshrrev_b32_e32 v79, 16, v26
	v_lshl_add_u32 v78, v78, 7, v152
	v_lshl_add_u32 v79, v79, 7, v153
	s_mov_b32 m0, s78
	s_add_i32 s43, s78, 0x400
	global_load_lds_dwordx4 v78, s[50:51]
	s_mov_b32 m0, s43
	s_nop 0
	global_load_lds_dwordx4 v79, s[50:51]
	s_waitcnt vmcnt(9)
	v_add_u32_e32 v54, s98, v59
	v_add_u32_e32 v55, s98, v60
	v_add_u32_e32 v56, s98, v61
	v_add_u32_e32 v57, s98, v62
	ds_read_b64_tr_b4 v[46:47], v160 offset:512
	ds_read_b64_tr_b4 v[48:49], v160 offset:1536
	ds_read_b64_tr_b4 v[122:123], v54
	ds_read_b64_tr_b4 v[124:125], v55
	ds_read_b64_tr_b4 v[126:127], v56
	ds_read_b64_tr_b4 v[128:129], v57
	s_waitcnt lgkmcnt(6)
	v_dot8c_i32_i4_e32 v38, v130, v52
	v_dot8c_i32_i4_e32 v39, v130, v50
	v_dot8c_i32_i4_e32 v40, v132, v52
	v_dot8c_i32_i4_e32 v41, v132, v50
	v_dot8c_i32_i4_e32 v42, v134, v52
	v_dot8c_i32_i4_e32 v43, v134, v50
	v_dot8c_i32_i4_e32 v44, v136, v52
	v_dot8c_i32_i4_e32 v45, v136, v50
	v_dot8c_i32_i4_e32 v38, v131, v53
	v_dot8c_i32_i4_e32 v39, v131, v51
	v_dot8c_i32_i4_e32 v40, v133, v53
	v_dot8c_i32_i4_e32 v41, v133, v51
	v_dot8c_i32_i4_e32 v42, v135, v53
	v_dot8c_i32_i4_e32 v43, v135, v51
	v_dot8c_i32_i4_e32 v44, v137, v53
	v_dot8c_i32_i4_e32 v45, v137, v51
	v_and_b32_e32 v78, 0xffff, v27
	v_lshrrev_b32_e32 v79, 16, v27
	v_lshl_add_u32 v78, v78, 7, v152
	v_lshl_add_u32 v79, v79, 7, v153
	s_mov_b32 m0, s79
	s_add_i32 s43, s79, 0x400
	global_load_lds_dwordx4 v78, s[50:51]
	s_mov_b32 m0, s43
	s_nop 0
	global_load_lds_dwordx4 v79, s[50:51]
	s_waitcnt vmcnt(8)
	v_add_u32_e32 v54, s99, v59
	v_add_u32_e32 v55, s99, v60
	v_add_u32_e32 v56, s99, v61
	v_add_u32_e32 v57, s99, v62
	ds_read_b64_tr_b4 v[50:51], v160 offset:640
	ds_read_b64_tr_b4 v[52:53], v160 offset:1664
	ds_read_b64_tr_b4 v[130:131], v54
	ds_read_b64_tr_b4 v[132:133], v55
	ds_read_b64_tr_b4 v[134:135], v56
	ds_read_b64_tr_b4 v[136:137], v57
	s_waitcnt lgkmcnt(6)
	v_dot8c_i32_i4_e32 v38, v122, v48
	v_dot8c_i32_i4_e32 v39, v122, v46
	v_dot8c_i32_i4_e32 v40, v124, v48
	v_dot8c_i32_i4_e32 v41, v124, v46
	v_dot8c_i32_i4_e32 v42, v126, v48
	v_dot8c_i32_i4_e32 v43, v126, v46
	v_dot8c_i32_i4_e32 v44, v128, v48
	v_dot8c_i32_i4_e32 v45, v128, v46
	v_dot8c_i32_i4_e32 v38, v123, v49
	v_dot8c_i32_i4_e32 v39, v123, v47
	v_dot8c_i32_i4_e32 v40, v125, v49
	v_dot8c_i32_i4_e32 v41, v125, v47
	v_dot8c_i32_i4_e32 v42, v127, v49
	v_dot8c_i32_i4_e32 v43, v127, v47
	v_dot8c_i32_i4_e32 v44, v129, v49
	v_dot8c_i32_i4_e32 v45, v129, v47
	s_waitcnt lgkmcnt(15)
; __device__ __forceinline__ void peer_v_tokens(int j, const LAS unsigned short* EL, const LAS unsigned char* AL  , const LAS float* ASC  , const LAS int* SAL  , ...
;     ...
; #pragma unroll
;         for (int m = 0; m < 2; ++m) {
;             const int idx = lane + 64 * m, tau = idx >> 4, sr = idx & 15, k = 16 * (sr & 7) + 2 * tau + (sr >> 3);
;             const int aq = (int)*(const LAS signed char*)(AL + tl * 128 + k); const int tq = aq + 8;
;             const unsigned lo = (((unsigned)tq & 15u) ^ 8u) * 0x11111111u, hi = ((unsigned)(tq >> 4) & 15u) * 0x11111111u;
;             typedef unsigned u2v __attribute__((ext_vector_type(2)));
;             u2v l2; l2.x = lo; l2.y = lo; u2v h2; h2.x = hi; h2.y = hi;
;             *(LAS u2v*)(ATL + 8 * idx) = l2; *(LAS u2v*)(ATL + 1024 + 8 * idx) = h2;
;         }
;         const float asc = ASC[tl]; const int sa = SAL[tl];
;         CFENCE();
;         int accH[4], accL[4];
; #pragma unroll
;         for (int st = 0; st < 16; ++st) {
;             const int p = st >> 2, q = st & 3;
;             if (st < 14) VDMA(st + 2, (st + 2) % 3);
;             if (st < 14) asm volatile("s_waitcnt vmcnt(8)" ::: "memory");
;             else if (st == 14) asm volatile("s_waitcnt vmcnt(4)" ::: "memory");
;             else asm volatile("s_waitcnt vmcnt(0)" ::: "memory");
;             if (q == 0) {
; #pragma unroll
;                 for (int r = 0; r < 4; ++r) { accH[r] = 0; accL[r] = 0; } }
; #pragma unroll
;             for (int tp = 0; tp < 2; ++tp) {
;                 const v2i ao = TR4(ATL + (2 * q + tp) * 128 + 8 * s16), ah = TR4(ATL + 1024 + (2 * q + tp) * 128 + 8 * s16);
; #pragma unroll
;                 for (int r = 0; r < 4; ++r) {
;                     const v2i d = TR4(ldsb + BUF[st % 3] + 2048 * tp + roff[r]);
;                     accH[r] = __builtin_amdgcn_sdot8(d.x, ah.x, accH[r], false); accH[r] = __builtin_amdgcn_sdot8(d.y, ah.y, accH[r], false);
;                     accL[r] = __builtin_amdgcn_sdot8(d.x, ao.x, accL[r], false); accL[r] = __builtin_amdgcn_sdot8(d.y, ao.y, accL[r], false);
;                 }
;             }
;             asm volatile("s_waitcnt lgkmcnt(0)" ::: "memory");
;             if (q == 3) {
; #pragma unroll
;                 for (int r = 0; r < 4; ++r) STASH[256 * p + 16 * (grp + 4 * r) + pc] = f2bf(asc * (float)(2 * ((accH[r] << 4) + accL[r]) + sa));
;             }
	v_add_u32_e32 v143, 8, v139
	v_and_b32_e32 v142, 15, v143
	v_xor_b32_e32 v142, 8, v142
	v_bfe_u32 v144, v143, 4, 4
	v_mul_lo_u32 v142, v142, s92
	v_mul_lo_u32 v144, v144, s92
	v_mov_b32_e32 v143, v142
	v_mov_b32_e32 v145, v144
	ds_write2st64_b64 v159, v[142:143], v[144:145] offset1:2
	v_and_b32_e32 v78, 0xffff, v28
	v_lshrrev_b32_e32 v79, 16, v28
	v_lshl_add_u32 v78, v78, 7, v152
	v_lshl_add_u32 v79, v79, 7, v153
	s_mov_b32 m0, s98
	s_add_i32 s43, s98, 0x400
	global_load_lds_dwordx4 v78, s[50:51]
	s_mov_b32 m0, s43
	s_nop 0
	global_load_lds_dwordx4 v79, s[50:51]
	s_waitcnt vmcnt(8)
	v_add_u32_e32 v54, s76, v59
	v_add_u32_e32 v55, s76, v60
	v_add_u32_e32 v56, s76, v61
	v_add_u32_e32 v57, s76, v62
	ds_read_b64_tr_b4 v[46:47], v160 offset:768
	ds_read_b64_tr_b4 v[48:49], v160 offset:1792
	ds_read_b64_tr_b4 v[122:123], v54
	ds_read_b64_tr_b4 v[124:125], v55
	ds_read_b64_tr_b4 v[126:127], v56
	ds_read_b64_tr_b4 v[128:129], v57
	s_waitcnt lgkmcnt(7)
	v_dot8c_i32_i4_e32 v38, v130, v52
	v_dot8c_i32_i4_e32 v39, v130, v50
	v_dot8c_i32_i4_e32 v40, v132, v52
	v_dot8c_i32_i4_e32 v41, v132, v50
	v_dot8c_i32_i4_e32 v42, v134, v52
	v_dot8c_i32_i4_e32 v43, v134, v50
	v_dot8c_i32_i4_e32 v44, v136, v52
	v_dot8c_i32_i4_e32 v45, v136, v50
	v_dot8c_i32_i4_e32 v38, v131, v53
	v_dot8c_i32_i4_e32 v39, v131, v51
	v_dot8c_i32_i4_e32 v40, v133, v53
	v_dot8c_i32_i4_e32 v41, v133, v51
	v_dot8c_i32_i4_e32 v42, v135, v53
	v_dot8c_i32_i4_e32 v43, v135, v51
	v_dot8c_i32_i4_e32 v44, v137, v53
	v_dot8c_i32_i4_e32 v45, v137, v51
	v_and_b32_e32 v78, 0xffff, v29
	v_lshrrev_b32_e32 v79, 16, v29
	v_lshl_add_u32 v78, v78, 7, v152
	v_lshl_add_u32 v79, v79, 7, v153
	s_mov_b32 m0, s99
	s_add_i32 s43, s99, 0x400
	global_load_lds_dwordx4 v78, s[50:51]
	s_mov_b32 m0, s43
	s_nop 0
	global_load_lds_dwordx4 v79, s[50:51]
	s_waitcnt vmcnt(8)
	v_add_u32_e32 v54, s77, v59
	v_add_u32_e32 v55, s77, v60
	v_add_u32_e32 v56, s77, v61
	v_add_u32_e32 v57, s77, v62
	ds_read_b64_tr_b4 v[50:51], v160 offset:896
	ds_read_b64_tr_b4 v[52:53], v160 offset:1920
	ds_read_b64_tr_b4 v[130:131], v54
	ds_read_b64_tr_b4 v[132:133], v55
	ds_read_b64_tr_b4 v[134:135], v56
	ds_read_b64_tr_b4 v[136:137], v57
	s_waitcnt lgkmcnt(6)
	v_dot8c_i32_i4_e32 v38, v122, v48
	v_dot8c_i32_i4_e32 v39, v122, v46
	v_dot8c_i32_i4_e32 v40, v124, v48
	v_dot8c_i32_i4_e32 v41, v124, v46
	v_dot8c_i32_i4_e32 v42, v126, v48
	v_dot8c_i32_i4_e32 v43, v126, v46
	v_dot8c_i32_i4_e32 v44, v128, v48
	v_dot8c_i32_i4_e32 v45, v128, v46
	v_dot8c_i32_i4_e32 v38, v123, v49
	v_dot8c_i32_i4_e32 v39, v123, v47
	v_dot8c_i32_i4_e32 v40, v125, v49
	v_dot8c_i32_i4_e32 v41, v125, v47
	v_dot8c_i32_i4_e32 v42, v127, v49
	v_dot8c_i32_i4_e32 v43, v127, v47
	v_dot8c_i32_i4_e32 v44, v129, v49
	v_dot8c_i32_i4_e32 v45, v129, v47
	v_and_b32_e32 v78, 0xffff, v30
	v_lshrrev_b32_e32 v79, 16, v30
	v_lshl_add_u32 v78, v78, 7, v152
	v_lshl_add_u32 v79, v79, 7, v153
	s_mov_b32 m0, s76
	s_add_i32 s43, s76, 0x400
	global_load_lds_dwordx4 v78, s[50:51]
	s_mov_b32 m0, s43
	s_nop 0
	global_load_lds_dwordx4 v79, s[50:51]
	s_waitcnt vmcnt(8)
	v_add_u32_e32 v54, s78, v59
	v_add_u32_e32 v55, s78, v60
	v_add_u32_e32 v56, s78, v61
	v_add_u32_e32 v57, s78, v62
	ds_read_b64_tr_b4 v[46:47], v160
	ds_read_b64_tr_b4 v[48:49], v160 offset:1024
	ds_read_b64_tr_b4 v[122:123], v54
	ds_read_b64_tr_b4 v[124:125], v55
	ds_read_b64_tr_b4 v[126:127], v56
	ds_read_b64_tr_b4 v[128:129], v57
	s_waitcnt lgkmcnt(6)
	v_dot8c_i32_i4_e32 v38, v130, v52
	v_dot8c_i32_i4_e32 v39, v130, v50
	v_dot8c_i32_i4_e32 v40, v132, v52
	v_dot8c_i32_i4_e32 v41, v132, v50
	v_dot8c_i32_i4_e32 v42, v134, v52
	v_dot8c_i32_i4_e32 v43, v134, v50
	v_dot8c_i32_i4_e32 v44, v136, v52
	v_dot8c_i32_i4_e32 v45, v136, v50
	v_dot8c_i32_i4_e32 v38, v131, v53
	v_dot8c_i32_i4_e32 v39, v131, v51
	v_dot8c_i32_i4_e32 v40, v133, v53
	v_dot8c_i32_i4_e32 v41, v133, v51
	v_dot8c_i32_i4_e32 v42, v135, v53
	v_dot8c_i32_i4_e32 v43, v135, v51
	v_dot8c_i32_i4_e32 v44, v137, v53
	v_dot8c_i32_i4_e32 v45, v137, v51
	s_nop 3
	s_waitcnt lgkmcnt(15)
	v_lshlrev_b32_e32 v38, 5, v38
	v_lshlrev_b32_e32 v39, 1, v39
	v_add3_u32 v38, v39, v229, v38
	v_cvt_f32_i32_e32 v38, v38
	v_mul_f32_e32 v38, v228, v38
	v_lshlrev_b32_e32 v40, 5, v40
	v_lshlrev_b32_e32 v41, 1, v41
	v_add3_u32 v40, v41, v229, v40
	v_cvt_f32_i32_e32 v40, v40
	v_mul_f32_e32 v40, v228, v40
	v_lshlrev_b32_e32 v42, 5, v42
	v_lshlrev_b32_e32 v43, 1, v43
	v_add3_u32 v42, v43, v229, v42
	v_cvt_f32_i32_e32 v42, v42
	v_mul_f32_e32 v42, v228, v42
	v_lshlrev_b32_e32 v44, 5, v44
	v_lshlrev_b32_e32 v45, 1, v45
	v_add3_u32 v44, v45, v229, v44
	v_cvt_f32_i32_e32 v44, v44
	v_mul_f32_e32 v44, v228, v44
	v_cvt_pk_bf16_f32 v184, v38, v40
	v_cvt_pk_bf16_f32 v185, v42, v44
	ds_read_b128 v[252:255], v156
	s_add_i32 s44, s40, 40
	s_ashr_i32 s45, s44, 31
	s_lshl_b64 s[44:45], s[44:45], 12
	v_lshl_add_u64 v[80:81], v[36:37], 0, s[44:45]
	s_waitcnt lgkmcnt(0)
; __device__ __forceinline__ void peer_v_tokens(int j, const LAS unsigned short* EL, const LAS unsigned char* AL  , const LAS float* ASC  , const LAS int* SAL  , ...
;     ...
;         { unsigned ho = (unsigned)t * (D / 4) + (unsigned)lane; asm volatile("" : "+v"(ho)); const uint2* hp = (const uint2*)HB + ho; const float4* gp = (const float4*)fng + lane;
; #pragma unroll
;           for (int jq = 0; jq < 4; ++jq) { hv[jq] = hp[64 * jq]; gv[jq] = gp[64 * jq]; } }
;         VDMA(0, 0); VDMA(1, 1);
; #pragma unroll
;         for (int m = 0; m < 2; ++m) {
;             const int idx = lane + 64 * m, tau = idx >> 4, sr = idx & 15, k = 16 * (sr & 7) + 2 * tau + (sr >> 3);
;             const int aq = (int)*(const LAS signed char*)(AL + tl * 128 + k); const int tq = aq + 8;
;             const unsigned lo = (((unsigned)tq & 15u) ^ 8u) * 0x11111111u, hi = ((unsigned)(tq >> 4) & 15u) * 0x11111111u;
;             typedef unsigned u2v __attribute__((ext_vector_type(2)));
;             u2v l2; l2.x = lo; l2.y = lo; u2v h2; h2.x = hi; h2.y = hi;
;             *(LAS u2v*)(ATL + 8 * idx) = l2; *(LAS u2v*)(ATL + 1024 + 8 * idx) = h2;
;         }
;         const float asc = ASC[tl]; const int sa = SAL[tl];
;         CFENCE();
;         int accH[4], accL[4];
; #pragma unroll
;         for (int st = 0; st < 16; ++st) {
;             const int p = st >> 2, q = st & 3;
;             if (st < 14) VDMA(st + 2, (st + 2) % 3);
;             if (st < 14) asm volatile("s_waitcnt vmcnt(8)" ::: "memory");
;             else if (st == 14) asm volatile("s_waitcnt vmcnt(4)" ::: "memory");
;             else asm volatile("s_waitcnt vmcnt(0)" ::: "memory");
;             if (q == 0) {
; #pragma unroll
;                 for (int r = 0; r < 4; ++r) { accH[r] = 0; accL[r] = 0; } }
; #pragma unroll
;             for (int tp = 0; tp < 2; ++tp) {
;                 const v2i ao = TR4(ATL + (2 * q + tp) * 128 + 8 * s16), ah = TR4(ATL + 1024 + (2 * q + tp) * 128 + 8 * s16);
; #pragma unroll
;                 for (int r = 0; r < 4; ++r) {
;                     const v2i d = TR4(ldsb + BUF[st % 3] + 2048 * tp + roff[r]);
;                     accH[r] = __builtin_amdgcn_sdot8(d.x, ah.x, accH[r], false); accH[r] = __builtin_amdgcn_sdot8(d.y, ah.y, accH[r], false);
;                     accL[r] = __builtin_amdgcn_sdot8(d.x, ao.x, accL[r], false); accL[r] = __builtin_amdgcn_sdot8(d.y, ao.y, accL[r], false);
	v_mul_f32_e32 v244, v244, v252
	v_mul_f32_e32 v245, v245, v253
	v_mul_f32_e32 v246, v246, v254
	v_mul_f32_e32 v247, v247, v255
	global_store_dwordx4 v[80:81], v[244:247], off offset:2048 nt
	s_add_i32 s43, s40, 48
	s_lshl_b32 s43, s43, 11
	v_add_u32_e32 v138, s43, v66
	global_load_dwordx2 v[194:195], v138, s[70:71]
	global_load_dwordx2 v[196:197], v138, s[70:71] offset:512
	global_load_dwordx2 v[198:199], v138, s[70:71] offset:1024
	global_load_dwordx2 v[200:201], v138, s[70:71] offset:1536
	s_add_i32 s43, s40, 56
	s_lshl_b32 s43, s43, 11
	v_add_u32_e32 v138, s43, v66
	global_load_dwordx2 v[18:19], v138, s[70:71]
	global_load_dwordx2 v[20:21], v138, s[70:71] offset:512
	global_load_dwordx2 v[22:23], v138, s[70:71] offset:1024
	global_load_dwordx2 v[24:25], v138, s[70:71] offset:1536
	v_add_u32_e32 v147, 8, v140
	v_and_b32_e32 v146, 15, v147
	v_xor_b32_e32 v146, 8, v146
	v_bfe_u32 v148, v147, 4, 4
	v_mul_lo_u32 v146, v146, s92
	v_mul_lo_u32 v148, v148, s92
	v_mov_b32_e32 v147, v146
	v_mov_b32_e32 v149, v148
	ds_write2st64_b64 v77, v[146:147], v[148:149] offset1:2
	s_add_i32 s43, s67, 224
	v_mov_b32_e32 v138, s43
	ds_read2st64_b32 v[228:229], v138 offset1:1
	v_mov_b32_e32 v38, 0
	v_mov_b32_e32 v39, 0
	v_mov_b32_e32 v40, 0
	v_mov_b32_e32 v41, 0
	v_mov_b32_e32 v42, 0
	v_mov_b32_e32 v43, 0
	v_mov_b32_e32 v44, 0
	v_mov_b32_e32 v45, 0
	v_and_b32_e32 v78, 0xffff, v31
	v_lshrrev_b32_e32 v79, 16, v31
	v_lshl_add_u32 v78, v78, 7, v152
	v_lshl_add_u32 v79, v79, 7, v153
	s_mov_b32 m0, s77
	s_add_i32 s43, s77, 0x400
	global_load_lds_dwordx4 v78, s[50:51]
	s_mov_b32 m0, s43
	s_nop 0
	global_load_lds_dwordx4 v79, s[50:51]
	s_waitcnt vmcnt(17)
	v_add_u32_e32 v54, s79, v59
	v_add_u32_e32 v55, s79, v60
	v_add_u32_e32 v56, s79, v61
	v_add_u32_e32 v57, s79, v62
	ds_read_b64_tr_b4 v[50:51], v160 offset:128
	ds_read_b64_tr_b4 v[52:53], v160 offset:1152
	ds_read_b64_tr_b4 v[130:131], v54
	ds_read_b64_tr_b4 v[132:133], v55
	ds_read_b64_tr_b4 v[134:135], v56
	ds_read_b64_tr_b4 v[136:137], v57
	s_waitcnt lgkmcnt(9)
	v_dot8c_i32_i4_e32 v38, v122, v48
	v_dot8c_i32_i4_e32 v39, v122, v46
	v_dot8c_i32_i4_e32 v40, v124, v48
	v_dot8c_i32_i4_e32 v41, v124, v46
	v_dot8c_i32_i4_e32 v42, v126, v48
	v_dot8c_i32_i4_e32 v43, v126, v46
	v_dot8c_i32_i4_e32 v44, v128, v48
	v_dot8c_i32_i4_e32 v45, v128, v46
	v_dot8c_i32_i4_e32 v38, v123, v49
	v_dot8c_i32_i4_e32 v39, v123, v47
	v_dot8c_i32_i4_e32 v40, v125, v49
	v_dot8c_i32_i4_e32 v41, v125, v47
	v_dot8c_i32_i4_e32 v42, v127, v49
	v_dot8c_i32_i4_e32 v43, v127, v47
	v_dot8c_i32_i4_e32 v44, v129, v49
	v_dot8c_i32_i4_e32 v45, v129, v47
	v_and_b32_e32 v78, 0xffff, v32
	v_lshrrev_b32_e32 v79, 16, v32
	v_lshl_add_u32 v78, v78, 7, v152
	v_lshl_add_u32 v79, v79, 7, v153
	s_mov_b32 m0, s78
	s_add_i32 s43, s78, 0x400
	global_load_lds_dwordx4 v78, s[50:51]
	s_mov_b32 m0, s43
	s_nop 0
	global_load_lds_dwordx4 v79, s[50:51]
	s_waitcnt vmcnt(17)
	v_add_u32_e32 v54, s98, v59
	v_add_u32_e32 v55, s98, v60
	v_add_u32_e32 v56, s98, v61
	v_add_u32_e32 v57, s98, v62
	ds_read_b64_tr_b4 v[46:47], v160 offset:256
	ds_read_b64_tr_b4 v[48:49], v160 offset:1280
	ds_read_b64_tr_b4 v[122:123], v54
	ds_read_b64_tr_b4 v[124:125], v55
	ds_read_b64_tr_b4 v[126:127], v56
	ds_read_b64_tr_b4 v[128:129], v57
	s_waitcnt lgkmcnt(6)
	v_dot8c_i32_i4_e32 v38, v130, v52
	v_dot8c_i32_i4_e32 v39, v130, v50
	v_dot8c_i32_i4_e32 v40, v132, v52
	v_dot8c_i32_i4_e32 v41, v132, v50
	v_dot8c_i32_i4_e32 v42, v134, v52
	v_dot8c_i32_i4_e32 v43, v134, v50
	v_dot8c_i32_i4_e32 v44, v136, v52
	v_dot8c_i32_i4_e32 v45, v136, v50
	v_dot8c_i32_i4_e32 v38, v131, v53
	v_dot8c_i32_i4_e32 v39, v131, v51
	v_dot8c_i32_i4_e32 v40, v133, v53
	v_dot8c_i32_i4_e32 v41, v133, v51
	v_dot8c_i32_i4_e32 v42, v135, v53
	v_dot8c_i32_i4_e32 v43, v135, v51
	v_dot8c_i32_i4_e32 v44, v137, v53
	v_dot8c_i32_i4_e32 v45, v137, v51
	v_and_b32_e32 v78, 0xffff, v33
	v_lshrrev_b32_e32 v79, 16, v33
	v_lshl_add_u32 v78, v78, 7, v152
	v_lshl_add_u32 v79, v79, 7, v153
	s_mov_b32 m0, s79
	s_add_i32 s43, s79, 0x400
	global_load_lds_dwordx4 v78, s[50:51]
	s_mov_b32 m0, s43
	s_nop 0
	global_load_lds_dwordx4 v79, s[50:51]
	s_waitcnt vmcnt(17)
	v_add_u32_e32 v54, s99, v59
	v_add_u32_e32 v55, s99, v60
	v_add_u32_e32 v56, s99, v61
	v_add_u32_e32 v57, s99, v62
	ds_read_b64_tr_b4 v[50:51], v160 offset:384
	ds_read_b64_tr_b4 v[52:53], v160 offset:1408
	ds_read_b64_tr_b4 v[130:131], v54
	ds_read_b64_tr_b4 v[132:133], v55
	ds_read_b64_tr_b4 v[134:135], v56
	ds_read_b64_tr_b4 v[136:137], v57
	s_waitcnt lgkmcnt(6)
	v_dot8c_i32_i4_e32 v38, v122, v48
	v_dot8c_i32_i4_e32 v39, v122, v46
	v_dot8c_i32_i4_e32 v40, v124, v48
	v_dot8c_i32_i4_e32 v41, v124, v46
	v_dot8c_i32_i4_e32 v42, v126, v48
	v_dot8c_i32_i4_e32 v43, v126, v46
	v_dot8c_i32_i4_e32 v44, v128, v48
	v_dot8c_i32_i4_e32 v45, v128, v46
	v_dot8c_i32_i4_e32 v38, v123, v49
	v_dot8c_i32_i4_e32 v39, v123, v47
	v_dot8c_i32_i4_e32 v40, v125, v49
	v_dot8c_i32_i4_e32 v41, v125, v47
	v_dot8c_i32_i4_e32 v42, v127, v49
	v_dot8c_i32_i4_e32 v43, v127, v47
	v_dot8c_i32_i4_e32 v44, v129, v49
	v_dot8c_i32_i4_e32 v45, v129, v47
	s_waitcnt vmcnt(15)
	v_add_u32_e32 v54, s76, v59
	v_add_u32_e32 v55, s76, v60
	v_add_u32_e32 v56, s76, v61
	v_add_u32_e32 v57, s76, v62
	ds_read_b64_tr_b4 v[46:47], v160 offset:512
	ds_read_b64_tr_b4 v[48:49], v160 offset:1536
	ds_read_b64_tr_b4 v[122:123], v54
	ds_read_b64_tr_b4 v[124:125], v55
	ds_read_b64_tr_b4 v[126:127], v56
	ds_read_b64_tr_b4 v[128:129], v57
	s_waitcnt lgkmcnt(6)
; #define LAS __attribute__((address_space(3)))
; __device__ __forceinline__ bf16 f2bf(float f) { return (bf16)f2bfu(f); }
; #define TR4(p_) __builtin_amdgcn_ds_read_tr4_b64_v2i32((LAS v2i*)(p_))
; #define CFENCE() asm volatile("" ::: "memory")
; __device__ __forceinline__ void peer_v_tokens(int j, const LAS unsigned short* EL, const LAS unsigned char* AL  , const LAS float* ASC  , const LAS int* SAL  , ...
;     ...
;         for (int st = 0; st < 16; ++st) {
;             const int p = st >> 2, q = st & 3;
;             if (st < 14) VDMA(st + 2, (st + 2) % 3);
;             if (st < 14) asm volatile("s_waitcnt vmcnt(8)" ::: "memory");
;             else if (st == 14) asm volatile("s_waitcnt vmcnt(4)" ::: "memory");
;             else asm volatile("s_waitcnt vmcnt(0)" ::: "memory");
;             if (q == 0) {
; #pragma unroll
;                 for (int r = 0; r < 4; ++r) { accH[r] = 0; accL[r] = 0; } }
; #pragma unroll
;             for (int tp = 0; tp < 2; ++tp) {
;                 const v2i ao = TR4(ATL + (2 * q + tp) * 128 + 8 * s16), ah = TR4(ATL + 1024 + (2 * q + tp) * 128 + 8 * s16);
; #pragma unroll
;                 for (int r = 0; r < 4; ++r) {
;                     const v2i d = TR4(ldsb + BUF[st % 3] + 2048 * tp + roff[r]);
;                     accH[r] = __builtin_amdgcn_sdot8(d.x, ah.x, accH[r], false); accH[r] = __builtin_amdgcn_sdot8(d.y, ah.y, accH[r], false);
;                     accL[r] = __builtin_amdgcn_sdot8(d.x, ao.x, accL[r], false); accL[r] = __builtin_amdgcn_sdot8(d.y, ao.y, accL[r], false);
;                 }
;             }
;             asm volatile("s_waitcnt lgkmcnt(0)" ::: "memory");
;             if (q == 3) {
; #pragma unroll
;                 for (int r = 0; r < 4; ++r) STASH[256 * p + 16 * (grp + 4 * r) + pc] = f2bf(asc * (float)(2 * ((accH[r] << 4) + accL[r]) + sa));
;             }
;         }
;         CFENCE();
;         {
;             float4 v[4]; float ss = 0.f;
; #pragma unroll
;             for (int jq = 0; jq < 4; ++jq) { typedef unsigned u2v __attribute__((ext_vector_type(2))); const u2v pw = *(const LAS u2v*)(STASH + 4 * lane + 256 * jq); const uint2 hw = hv[jq];
	v_dot8c_i32_i4_e32 v38, v130, v52
	v_dot8c_i32_i4_e32 v39, v130, v50
	v_dot8c_i32_i4_e32 v40, v132, v52
	v_dot8c_i32_i4_e32 v41, v132, v50
	v_dot8c_i32_i4_e32 v42, v134, v52
	v_dot8c_i32_i4_e32 v43, v134, v50
	v_dot8c_i32_i4_e32 v44, v136, v52
	v_dot8c_i32_i4_e32 v45, v136, v50
	v_dot8c_i32_i4_e32 v38, v131, v53
	v_dot8c_i32_i4_e32 v39, v131, v51
	v_dot8c_i32_i4_e32 v40, v133, v53
	v_dot8c_i32_i4_e32 v41, v133, v51
	v_dot8c_i32_i4_e32 v42, v135, v53
	v_dot8c_i32_i4_e32 v43, v135, v51
	v_dot8c_i32_i4_e32 v44, v137, v53
	v_dot8c_i32_i4_e32 v45, v137, v51
	s_waitcnt vmcnt(4)
	v_add_u32_e32 v54, s77, v59
	v_add_u32_e32 v55, s77, v60
	v_add_u32_e32 v56, s77, v61
	v_add_u32_e32 v57, s77, v62
	ds_read_b64_tr_b4 v[50:51], v160 offset:640
	ds_read_b64_tr_b4 v[52:53], v160 offset:1664
	ds_read_b64_tr_b4 v[130:131], v54
	ds_read_b64_tr_b4 v[132:133], v55
	ds_read_b64_tr_b4 v[134:135], v56
	ds_read_b64_tr_b4 v[136:137], v57
	s_waitcnt lgkmcnt(6)
	v_dot8c_i32_i4_e32 v38, v122, v48
	v_dot8c_i32_i4_e32 v39, v122, v46
	v_dot8c_i32_i4_e32 v40, v124, v48
	v_dot8c_i32_i4_e32 v41, v124, v46
	v_dot8c_i32_i4_e32 v42, v126, v48
	v_dot8c_i32_i4_e32 v43, v126, v46
	v_dot8c_i32_i4_e32 v44, v128, v48
	v_dot8c_i32_i4_e32 v45, v128, v46
	v_dot8c_i32_i4_e32 v38, v123, v49
	v_dot8c_i32_i4_e32 v39, v123, v47
	v_dot8c_i32_i4_e32 v40, v125, v49
	v_dot8c_i32_i4_e32 v41, v125, v47
	v_dot8c_i32_i4_e32 v42, v127, v49
	v_dot8c_i32_i4_e32 v43, v127, v47
	v_dot8c_i32_i4_e32 v44, v129, v49
	v_dot8c_i32_i4_e32 v45, v129, v47
	s_waitcnt vmcnt(2)
	v_add_u32_e32 v54, s78, v59
	v_add_u32_e32 v55, s78, v60
	v_add_u32_e32 v56, s78, v61
	v_add_u32_e32 v57, s78, v62
	ds_read_b64_tr_b4 v[46:47], v160 offset:768
	ds_read_b64_tr_b4 v[48:49], v160 offset:1792
	ds_read_b64_tr_b4 v[122:123], v54
	ds_read_b64_tr_b4 v[124:125], v55
	ds_read_b64_tr_b4 v[126:127], v56
	ds_read_b64_tr_b4 v[128:129], v57
	s_waitcnt lgkmcnt(6)
	v_dot8c_i32_i4_e32 v38, v130, v52
	v_dot8c_i32_i4_e32 v39, v130, v50
	v_dot8c_i32_i4_e32 v40, v132, v52
	v_dot8c_i32_i4_e32 v41, v132, v50
	v_dot8c_i32_i4_e32 v42, v134, v52
	v_dot8c_i32_i4_e32 v43, v134, v50
	v_dot8c_i32_i4_e32 v44, v136, v52
	v_dot8c_i32_i4_e32 v45, v136, v50
	v_dot8c_i32_i4_e32 v38, v131, v53
	v_dot8c_i32_i4_e32 v39, v131, v51
	v_dot8c_i32_i4_e32 v40, v133, v53
	v_dot8c_i32_i4_e32 v41, v133, v51
	v_dot8c_i32_i4_e32 v42, v135, v53
	v_dot8c_i32_i4_e32 v43, v135, v51
	v_dot8c_i32_i4_e32 v44, v137, v53
	v_dot8c_i32_i4_e32 v45, v137, v51
	s_waitcnt vmcnt(0)
	v_add_u32_e32 v54, s79, v59
	v_add_u32_e32 v55, s79, v60
	v_add_u32_e32 v56, s79, v61
	v_add_u32_e32 v57, s79, v62
	ds_read_b64_tr_b4 v[50:51], v160 offset:896
	ds_read_b64_tr_b4 v[52:53], v160 offset:1920
	ds_read_b64_tr_b4 v[130:131], v54
	ds_read_b64_tr_b4 v[132:133], v55
	ds_read_b64_tr_b4 v[134:135], v56
	ds_read_b64_tr_b4 v[136:137], v57
	s_waitcnt lgkmcnt(6)
	v_dot8c_i32_i4_e32 v38, v122, v48
	v_dot8c_i32_i4_e32 v39, v122, v46
	v_dot8c_i32_i4_e32 v40, v124, v48
	v_dot8c_i32_i4_e32 v41, v124, v46
	v_dot8c_i32_i4_e32 v42, v126, v48
	v_dot8c_i32_i4_e32 v43, v126, v46
	v_dot8c_i32_i4_e32 v44, v128, v48
	v_dot8c_i32_i4_e32 v45, v128, v46
	v_dot8c_i32_i4_e32 v38, v123, v49
	v_dot8c_i32_i4_e32 v39, v123, v47
	v_dot8c_i32_i4_e32 v40, v125, v49
	v_dot8c_i32_i4_e32 v41, v125, v47
	v_dot8c_i32_i4_e32 v42, v127, v49
	v_dot8c_i32_i4_e32 v43, v127, v47
	v_dot8c_i32_i4_e32 v44, v129, v49
	v_dot8c_i32_i4_e32 v45, v129, v47
	s_waitcnt lgkmcnt(0)
	v_dot8c_i32_i4_e32 v38, v130, v52
	v_dot8c_i32_i4_e32 v39, v130, v50
	v_dot8c_i32_i4_e32 v40, v132, v52
	v_dot8c_i32_i4_e32 v41, v132, v50
	v_dot8c_i32_i4_e32 v42, v134, v52
	v_dot8c_i32_i4_e32 v43, v134, v50
	v_dot8c_i32_i4_e32 v44, v136, v52
	v_dot8c_i32_i4_e32 v45, v136, v50
	v_dot8c_i32_i4_e32 v38, v131, v53
	v_dot8c_i32_i4_e32 v39, v131, v51
	v_dot8c_i32_i4_e32 v40, v133, v53
	v_dot8c_i32_i4_e32 v41, v133, v51
	v_dot8c_i32_i4_e32 v42, v135, v53
	v_dot8c_i32_i4_e32 v43, v135, v51
	v_dot8c_i32_i4_e32 v44, v137, v53
	v_dot8c_i32_i4_e32 v45, v137, v51
	s_nop 3
	s_waitcnt lgkmcnt(15)
	v_lshlrev_b32_e32 v38, 5, v38
	v_lshlrev_b32_e32 v39, 1, v39
	v_add3_u32 v38, v39, v229, v38
	v_cvt_f32_i32_e32 v38, v38
	v_mul_f32_e32 v38, v228, v38
	v_lshlrev_b32_e32 v40, 5, v40
	v_lshlrev_b32_e32 v41, 1, v41
	v_add3_u32 v40, v41, v229, v40
	v_cvt_f32_i32_e32 v40, v40
	v_mul_f32_e32 v40, v228, v40
	v_lshlrev_b32_e32 v42, 5, v42
	v_lshlrev_b32_e32 v43, 1, v43
	v_add3_u32 v42, v43, v229, v42
	v_cvt_f32_i32_e32 v42, v42
	v_mul_f32_e32 v42, v228, v42
	v_lshlrev_b32_e32 v44, 5, v44
	v_lshlrev_b32_e32 v45, 1, v45
	v_add3_u32 v44, v45, v229, v44
	v_cvt_f32_i32_e32 v44, v44
	v_mul_f32_e32 v44, v228, v44
	v_cvt_pk_bf16_f32 v192, v38, v40
	v_cvt_pk_bf16_f32 v193, v42, v44
	ds_read_b128 v[252:255], v156 offset:1024
	s_add_i32 s44, s40, 40
	s_ashr_i32 s45, s44, 31
	s_lshl_b64 s[44:45], s[44:45], 12
	v_lshl_add_u64 v[80:81], v[36:37], 0, s[44:45]
	s_waitcnt lgkmcnt(0)
	v_mul_f32_e32 v248, v248, v252
	v_mul_f32_e32 v249, v249, v253
	v_mul_f32_e32 v250, v250, v254
	v_mul_f32_e32 v251, v251, v255
	global_store_dwordx4 v[80:81], v[248:251], off offset:3072 nt
	ds_write_b16 v65, v178
	ds_write_b16_d16_hi v65, v178 offset:128
	ds_write_b16 v65, v179 offset:256
	ds_write_b16_d16_hi v65, v179 offset:384
	ds_write_b16 v65, v180 offset:512
	ds_write_b16_d16_hi v65, v180 offset:640
	ds_write_b16 v65, v181 offset:768
	ds_write_b16_d16_hi v65, v181 offset:896
	ds_write_b16 v65, v182 offset:1024
	ds_write_b16_d16_hi v65, v182 offset:1152
	ds_write_b16 v65, v183 offset:1280
	ds_write_b16_d16_hi v65, v183 offset:1408
	ds_write_b16 v65, v184 offset:1536
	ds_write_b16_d16_hi v65, v184 offset:1664
	ds_write_b16 v65, v185 offset:1792
	ds_write_b16_d16_hi v65, v185 offset:1920
	ds_read_b64 v[202:203], v154
	ds_read_b64 v[204:205], v154 offset:512
	ds_read_b64 v[206:207], v154 offset:1024
	ds_read_b64 v[208:209], v154 offset:1536
	s_waitcnt vmcnt(11) lgkmcnt(0)
; #define LAS __attribute__((address_space(3)))
; __device__ __forceinline__ void peer_v_tokens(int j, const LAS unsigned short* EL, const LAS unsigned char* AL  , const LAS float* ASC  , const LAS int* SAL  , ...
;     ...
;         {
;             float4 v[4]; float ss = 0.f;
; #pragma unroll
;             for (int jq = 0; jq < 4; ++jq) { typedef unsigned u2v __attribute__((ext_vector_type(2))); const u2v pw = *(const LAS u2v*)(STASH + 4 * lane + 256 * jq); const uint2 hw = hv[jq];
;                 v[jq] = make_float4(__uint_as_float(hw.x << 16) + __uint_as_float(pw.x << 16), __uint_as_float(hw.x & 0xffff0000u) + __uint_as_float(pw.x & 0xffff0000u),
;                                     __uint_as_float(hw.y << 16) + __uint_as_float(pw.y << 16), __uint_as_float(hw.y & 0xffff0000u) + __uint_as_float(pw.y & 0xffff0000u));
;                 ss += v[jq].x * v[jq].x + v[jq].y * v[jq].y + v[jq].z * v[jq].z + v[jq].w * v[jq].w; }
;             ss = wave_sum(ss);
;             const float r3 = rsqrtf(ss * (1.f / D) + EPS);
;             float4* op = (float4*)(outp + (size_t)t * D) + lane;
; #pragma unroll
;             for (int jq = 0; jq < 4; ++jq) { typedef float f4v __attribute__((ext_vector_type(4))); f4v o4; o4.x = v[jq].x * r3 * gv[jq].x; o4.y = v[jq].y * r3 * gv[jq].y; o4.z = v[jq].z * r3 * gv[jq].z; o4.w = v[jq].w * r3 * gv[jq].w;
;                 __builtin_nontemporal_store(o4, (f4v*)op + 64 * jq); }
	v_lshlrev_b32_e32 v210, 16, v194
	v_and_b32_e32 v211, 0xffff0000, v194
	v_lshlrev_b32_e32 v142, 16, v202
	v_and_b32_e32 v143, 0xffff0000, v202
	v_add_f32_e32 v210, v210, v142
	v_add_f32_e32 v211, v211, v143
	v_lshlrev_b32_e32 v212, 16, v195
	v_and_b32_e32 v213, 0xffff0000, v195
	v_lshlrev_b32_e32 v142, 16, v203
	v_and_b32_e32 v143, 0xffff0000, v203
	v_add_f32_e32 v212, v212, v142
	v_add_f32_e32 v213, v213, v143
	v_lshlrev_b32_e32 v214, 16, v196
	v_and_b32_e32 v215, 0xffff0000, v196
	v_lshlrev_b32_e32 v142, 16, v204
	v_and_b32_e32 v143, 0xffff0000, v204
	v_add_f32_e32 v214, v214, v142
	v_add_f32_e32 v215, v215, v143
	v_lshlrev_b32_e32 v216, 16, v197
	v_and_b32_e32 v217, 0xffff0000, v197
	v_lshlrev_b32_e32 v142, 16, v205
	v_and_b32_e32 v143, 0xffff0000, v205
	v_add_f32_e32 v216, v216, v142
	v_add_f32_e32 v217, v217, v143
	v_lshlrev_b32_e32 v218, 16, v198
	v_and_b32_e32 v219, 0xffff0000, v198
	v_lshlrev_b32_e32 v142, 16, v206
	v_and_b32_e32 v143, 0xffff0000, v206
	v_add_f32_e32 v218, v218, v142
	v_add_f32_e32 v219, v219, v143
	v_lshlrev_b32_e32 v220, 16, v199
	v_and_b32_e32 v221, 0xffff0000, v199
	v_lshlrev_b32_e32 v142, 16, v207
	v_and_b32_e32 v143, 0xffff0000, v207
	v_add_f32_e32 v220, v220, v142
	v_add_f32_e32 v221, v221, v143
	v_lshlrev_b32_e32 v222, 16, v200
	v_and_b32_e32 v223, 0xffff0000, v200
	v_lshlrev_b32_e32 v142, 16, v208
	v_and_b32_e32 v143, 0xffff0000, v208
	v_add_f32_e32 v222, v222, v142
	v_add_f32_e32 v223, v223, v143
	v_lshlrev_b32_e32 v224, 16, v201
	v_and_b32_e32 v225, 0xffff0000, v201
	v_lshlrev_b32_e32 v142, 16, v209
	v_and_b32_e32 v143, 0xffff0000, v209
	v_add_f32_e32 v224, v224, v142
	v_add_f32_e32 v225, v225, v143
	v_mov_b32_e32 v144, 0
	v_mul_f32_e32 v145, v210, v210
	v_fmac_f32_e32 v145, v211, v211
	v_fmac_f32_e32 v145, v212, v212
	v_fmac_f32_e32 v145, v213, v213
	v_add_f32_e32 v144, v144, v145
	v_mul_f32_e32 v145, v214, v214
	v_fmac_f32_e32 v145, v215, v215
	v_fmac_f32_e32 v145, v216, v216
	v_fmac_f32_e32 v145, v217, v217
	v_add_f32_e32 v144, v144, v145
	v_mul_f32_e32 v145, v218, v218
	v_fmac_f32_e32 v145, v219, v219
	v_fmac_f32_e32 v145, v220, v220
	v_fmac_f32_e32 v145, v221, v221
	v_add_f32_e32 v144, v144, v145
	v_mul_f32_e32 v145, v222, v222
	v_fmac_f32_e32 v145, v223, v223
	v_fmac_f32_e32 v145, v224, v224
	v_fmac_f32_e32 v145, v225, v225
	v_add_f32_e32 v144, v144, v145
	s_nop 1
	v_add_f32_dpp v144, v144, v144 quad_perm:[1,0,3,2] row_mask:0xf bank_mask:0xf bound_ctrl:1
	s_nop 1
	v_add_f32_dpp v144, v144, v144 quad_perm:[2,3,0,1] row_mask:0xf bank_mask:0xf bound_ctrl:1
	s_nop 1
	v_add_f32_dpp v144, v144, v144 row_half_mirror row_mask:0xf bank_mask:0xf bound_ctrl:1
	s_nop 1
	v_add_f32_dpp v144, v144, v144 row_mirror row_mask:0xf bank_mask:0xf bound_ctrl:1
	s_nop 1
	v_readlane_b32 s10, v144, 0
	v_readlane_b32 s11, v144, 16
	v_readlane_b32 s14, v144, 32
	v_readlane_b32 s15, v144, 48
	s_nop 3
	v_mov_b32_e32 v144, s11
	v_mov_b32_e32 v145, s15
	v_add_f32_e32 v144, s10, v144
	v_add_f32_e32 v145, s14, v145
	v_add_f32_e32 v144, v144, v145
	v_fmamk_f32 v144, v144, 0x3a800000, v111
	v_rsq_f32_e32 v144, v144
	s_nop 0
	v_mul_f32_e32 v210, v210, v144
	v_mul_f32_e32 v211, v211, v144
	v_mul_f32_e32 v212, v212, v144
	v_mul_f32_e32 v213, v213, v144
	v_mul_f32_e32 v214, v214, v144
	v_mul_f32_e32 v215, v215, v144
	v_mul_f32_e32 v216, v216, v144
	v_mul_f32_e32 v217, v217, v144
	v_mul_f32_e32 v218, v218, v144
	v_mul_f32_e32 v219, v219, v144
	v_mul_f32_e32 v220, v220, v144
	v_mul_f32_e32 v221, v221, v144
	v_mul_f32_e32 v222, v222, v144
	v_mul_f32_e32 v223, v223, v144
	v_mul_f32_e32 v224, v224, v144
	v_mul_f32_e32 v225, v225, v144
	ds_read_b128 v[252:255], v155
	s_add_i32 s44, s40, 48
	s_ashr_i32 s45, s44, 31
	s_lshl_b64 s[44:45], s[44:45], 12
	v_lshl_add_u64 v[80:81], v[36:37], 0, s[44:45]
	s_waitcnt lgkmcnt(0)
	v_mul_f32_e32 v210, v210, v252
	v_mul_f32_e32 v211, v211, v253
	v_mul_f32_e32 v212, v212, v254
	v_mul_f32_e32 v213, v213, v255
	global_store_dwordx4 v[80:81], v[210:213], off nt
	ds_read_b128 v[252:255], v155 offset:1024
	s_add_i32 s44, s40, 48
	s_ashr_i32 s45, s44, 31
	s_lshl_b64 s[44:45], s[44:45], 12
	v_lshl_add_u64 v[80:81], v[36:37], 0, s[44:45]
	s_waitcnt lgkmcnt(0)
	v_mul_f32_e32 v214, v214, v252
	v_mul_f32_e32 v215, v215, v253
	v_mul_f32_e32 v216, v216, v254
	v_mul_f32_e32 v217, v217, v255
	global_store_dwordx4 v[80:81], v[214:217], off offset:1024 nt
	ds_read_b128 v[252:255], v156
	s_add_i32 s44, s40, 48
	s_ashr_i32 s45, s44, 31
	s_lshl_b64 s[44:45], s[44:45], 12
	v_lshl_add_u64 v[80:81], v[36:37], 0, s[44:45]
	s_waitcnt lgkmcnt(0)
	v_mul_f32_e32 v218, v218, v252
	v_mul_f32_e32 v219, v219, v253
	v_mul_f32_e32 v220, v220, v254
	v_mul_f32_e32 v221, v221, v255
	global_store_dwordx4 v[80:81], v[218:221], off offset:2048 nt
	ds_read_b128 v[252:255], v156 offset:1024
	s_add_i32 s44, s40, 48
	s_ashr_i32 s45, s44, 31
	s_lshl_b64 s[44:45], s[44:45], 12
	v_lshl_add_u64 v[80:81], v[36:37], 0, s[44:45]
	s_waitcnt lgkmcnt(0)
	v_mul_f32_e32 v222, v222, v252
	v_mul_f32_e32 v223, v223, v253
	v_mul_f32_e32 v224, v224, v254
	v_mul_f32_e32 v225, v225, v255
	global_store_dwordx4 v[80:81], v[222:225], off offset:3072 nt
	ds_write_b16 v65, v186
	ds_write_b16_d16_hi v65, v186 offset:128
	ds_write_b16 v65, v187 offset:256
	ds_write_b16_d16_hi v65, v187 offset:384
	ds_write_b16 v65, v188 offset:512
	ds_write_b16_d16_hi v65, v188 offset:640
	ds_write_b16 v65, v189 offset:768
	ds_write_b16_d16_hi v65, v189 offset:896
	ds_write_b16 v65, v190 offset:1024
	ds_write_b16_d16_hi v65, v190 offset:1152
	ds_write_b16 v65, v191 offset:1280
	ds_write_b16_d16_hi v65, v191 offset:1408
	ds_write_b16 v65, v192 offset:1536
	ds_write_b16_d16_hi v65, v192 offset:1664
	ds_write_b16 v65, v193 offset:1792
	ds_write_b16_d16_hi v65, v193 offset:1920
	ds_read_b64 v[202:203], v154
	ds_read_b64 v[204:205], v154 offset:512
	ds_read_b64 v[206:207], v154 offset:1024
	ds_read_b64 v[208:209], v154 offset:1536
	s_waitcnt vmcnt(11) lgkmcnt(0)
; #define LAS __attribute__((address_space(3)))
; __device__ __forceinline__ void peer_v_tokens(int j, const LAS unsigned short* EL, const LAS unsigned char* AL  , const LAS float* ASC  , const LAS int* SAL  , ...
;     ...
;         {
;             float4 v[4]; float ss = 0.f;
; #pragma unroll
;             for (int jq = 0; jq < 4; ++jq) { typedef unsigned u2v __attribute__((ext_vector_type(2))); const u2v pw = *(const LAS u2v*)(STASH + 4 * lane + 256 * jq); const uint2 hw = hv[jq];
;                 v[jq] = make_float4(__uint_as_float(hw.x << 16) + __uint_as_float(pw.x << 16), __uint_as_float(hw.x & 0xffff0000u) + __uint_as_float(pw.x & 0xffff0000u),
;                                     __uint_as_float(hw.y << 16) + __uint_as_float(pw.y << 16), __uint_as_float(hw.y & 0xffff0000u) + __uint_as_float(pw.y & 0xffff0000u));
;                 ss += v[jq].x * v[jq].x + v[jq].y * v[jq].y + v[jq].z * v[jq].z + v[jq].w * v[jq].w; }
;             ss = wave_sum(ss);
;             const float r3 = rsqrtf(ss * (1.f / D) + EPS);
;             float4* op = (float4*)(outp + (size_t)t * D) + lane;
; #pragma unroll
;             for (int jq = 0; jq < 4; ++jq) { typedef float f4v __attribute__((ext_vector_type(4))); f4v o4; o4.x = v[jq].x * r3 * gv[jq].x; o4.y = v[jq].y * r3 * gv[jq].y; o4.z = v[jq].z * r3 * gv[jq].z; o4.w = v[jq].w * r3 * gv[jq].w;
;                 __builtin_nontemporal_store(o4, (f4v*)op + 64 * jq); }
; __global__ void __launch_bounds__(NTHR, 2) k_main(Args a) {
;     ...
;         for (int j = bid; j < NCHUNK; j += nb) {
	v_lshlrev_b32_e32 v236, 16, v18
	v_and_b32_e32 v237, 0xffff0000, v18
	v_lshlrev_b32_e32 v142, 16, v202
	v_and_b32_e32 v143, 0xffff0000, v202
	v_add_f32_e32 v236, v236, v142
	v_add_f32_e32 v237, v237, v143
	v_lshlrev_b32_e32 v238, 16, v19
	v_and_b32_e32 v239, 0xffff0000, v19
	v_lshlrev_b32_e32 v142, 16, v203
	v_and_b32_e32 v143, 0xffff0000, v203
	v_add_f32_e32 v238, v238, v142
	v_add_f32_e32 v239, v239, v143
	v_lshlrev_b32_e32 v240, 16, v20
	v_and_b32_e32 v241, 0xffff0000, v20
	v_lshlrev_b32_e32 v142, 16, v204
	v_and_b32_e32 v143, 0xffff0000, v204
	v_add_f32_e32 v240, v240, v142
	v_add_f32_e32 v241, v241, v143
	v_lshlrev_b32_e32 v242, 16, v21
	v_and_b32_e32 v243, 0xffff0000, v21
	v_lshlrev_b32_e32 v142, 16, v205
	v_and_b32_e32 v143, 0xffff0000, v205
	v_add_f32_e32 v242, v242, v142
	v_add_f32_e32 v243, v243, v143
	v_lshlrev_b32_e32 v244, 16, v22
	v_and_b32_e32 v245, 0xffff0000, v22
	v_lshlrev_b32_e32 v142, 16, v206
	v_and_b32_e32 v143, 0xffff0000, v206
	v_add_f32_e32 v244, v244, v142
	v_add_f32_e32 v245, v245, v143
	v_lshlrev_b32_e32 v246, 16, v23
	v_and_b32_e32 v247, 0xffff0000, v23
	v_lshlrev_b32_e32 v142, 16, v207
	v_and_b32_e32 v143, 0xffff0000, v207
	v_add_f32_e32 v246, v246, v142
	v_add_f32_e32 v247, v247, v143
	v_lshlrev_b32_e32 v248, 16, v24
	v_and_b32_e32 v249, 0xffff0000, v24
	v_lshlrev_b32_e32 v142, 16, v208
	v_and_b32_e32 v143, 0xffff0000, v208
	v_add_f32_e32 v248, v248, v142
	v_add_f32_e32 v249, v249, v143
	v_lshlrev_b32_e32 v250, 16, v25
	v_and_b32_e32 v251, 0xffff0000, v25
	v_lshlrev_b32_e32 v142, 16, v209
	v_and_b32_e32 v143, 0xffff0000, v209
	v_add_f32_e32 v250, v250, v142
	v_add_f32_e32 v251, v251, v143
	v_mov_b32_e32 v144, 0
	v_mul_f32_e32 v145, v236, v236
	v_fmac_f32_e32 v145, v237, v237
	v_fmac_f32_e32 v145, v238, v238
	v_fmac_f32_e32 v145, v239, v239
	v_add_f32_e32 v144, v144, v145
	v_mul_f32_e32 v145, v240, v240
	v_fmac_f32_e32 v145, v241, v241
	v_fmac_f32_e32 v145, v242, v242
	v_fmac_f32_e32 v145, v243, v243
	v_add_f32_e32 v144, v144, v145
	v_mul_f32_e32 v145, v244, v244
	v_fmac_f32_e32 v145, v245, v245
	v_fmac_f32_e32 v145, v246, v246
	v_fmac_f32_e32 v145, v247, v247
	v_add_f32_e32 v144, v144, v145
	v_mul_f32_e32 v145, v248, v248
	v_fmac_f32_e32 v145, v249, v249
	v_fmac_f32_e32 v145, v250, v250
	v_fmac_f32_e32 v145, v251, v251
	v_add_f32_e32 v144, v144, v145
	s_nop 1
	v_add_f32_dpp v144, v144, v144 quad_perm:[1,0,3,2] row_mask:0xf bank_mask:0xf bound_ctrl:1
	s_nop 1
	v_add_f32_dpp v144, v144, v144 quad_perm:[2,3,0,1] row_mask:0xf bank_mask:0xf bound_ctrl:1
	s_nop 1
	v_add_f32_dpp v144, v144, v144 row_half_mirror row_mask:0xf bank_mask:0xf bound_ctrl:1
	s_nop 1
	v_add_f32_dpp v144, v144, v144 row_mirror row_mask:0xf bank_mask:0xf bound_ctrl:1
	s_nop 1
	v_readlane_b32 s10, v144, 0
	v_readlane_b32 s11, v144, 16
	v_readlane_b32 s14, v144, 32
	v_readlane_b32 s15, v144, 48
	s_nop 3
	v_mov_b32_e32 v144, s11
	v_mov_b32_e32 v145, s15
	v_add_f32_e32 v144, s10, v144
	v_add_f32_e32 v145, s14, v145
	v_add_f32_e32 v144, v144, v145
	v_fmamk_f32 v144, v144, 0x3a800000, v111
	v_rsq_f32_e32 v144, v144
	s_nop 0
	v_mul_f32_e32 v236, v236, v144
	v_mul_f32_e32 v237, v237, v144
	v_mul_f32_e32 v238, v238, v144
	v_mul_f32_e32 v239, v239, v144
	v_mul_f32_e32 v240, v240, v144
	v_mul_f32_e32 v241, v241, v144
	v_mul_f32_e32 v242, v242, v144
	v_mul_f32_e32 v243, v243, v144
	v_mul_f32_e32 v244, v244, v144
	v_mul_f32_e32 v245, v245, v144
	v_mul_f32_e32 v246, v246, v144
	v_mul_f32_e32 v247, v247, v144
	v_mul_f32_e32 v248, v248, v144
	v_mul_f32_e32 v249, v249, v144
	v_mul_f32_e32 v250, v250, v144
	v_mul_f32_e32 v251, v251, v144
	ds_read_b128 v[252:255], v155
	s_add_i32 s44, s40, 56
	s_ashr_i32 s45, s44, 31
	s_lshl_b64 s[44:45], s[44:45], 12
	v_lshl_add_u64 v[80:81], v[36:37], 0, s[44:45]
	s_waitcnt lgkmcnt(0)
	v_mul_f32_e32 v236, v236, v252
	v_mul_f32_e32 v237, v237, v253
	v_mul_f32_e32 v238, v238, v254
	v_mul_f32_e32 v239, v239, v255
	global_store_dwordx4 v[80:81], v[236:239], off nt
	ds_read_b128 v[252:255], v155 offset:1024
	s_add_i32 s44, s40, 56
	s_ashr_i32 s45, s44, 31
	s_lshl_b64 s[44:45], s[44:45], 12
	v_lshl_add_u64 v[80:81], v[36:37], 0, s[44:45]
	s_waitcnt lgkmcnt(0)
	v_mul_f32_e32 v240, v240, v252
	v_mul_f32_e32 v241, v241, v253
	v_mul_f32_e32 v242, v242, v254
	v_mul_f32_e32 v243, v243, v255
	global_store_dwordx4 v[80:81], v[240:243], off offset:1024 nt
	ds_read_b128 v[252:255], v156
	s_add_i32 s44, s40, 56
	s_ashr_i32 s45, s44, 31
	s_lshl_b64 s[44:45], s[44:45], 12
	v_lshl_add_u64 v[80:81], v[36:37], 0, s[44:45]
	s_waitcnt lgkmcnt(0)
	v_mul_f32_e32 v244, v244, v252
	v_mul_f32_e32 v245, v245, v253
	v_mul_f32_e32 v246, v246, v254
	v_mul_f32_e32 v247, v247, v255
	global_store_dwordx4 v[80:81], v[244:247], off offset:2048 nt
	ds_read_b128 v[252:255], v156 offset:1024
	s_add_i32 s44, s40, 56
	s_ashr_i32 s45, s44, 31
	s_lshl_b64 s[44:45], s[44:45], 12
	v_lshl_add_u64 v[80:81], v[36:37], 0, s[44:45]
	s_waitcnt lgkmcnt(0)
	v_mul_f32_e32 v248, v248, v252
	v_mul_f32_e32 v249, v249, v253
	v_mul_f32_e32 v250, v250, v254
	v_mul_f32_e32 v251, v251, v255
	global_store_dwordx4 v[80:81], v[248:251], off offset:3072 nt
	s_add_i32 s2, s2, s33
	s_add_i32 s40, s40, s63
	s_add_i32 s73, s73, s74
	s_cmpk_lt_i32 s2, 0x100
	s_cbranch_scc1 .LBB0_648
